# speedup vs baseline: 1.0066x; 1.0066x over previous
; DEVFI int opaque_tid(const int wv) { return (wv << 6) | lane_opaque(); }
; #define SBAR() __builtin_amdgcn_sched_barrier(0)
; #define WAIT_V0() asm volatile("s_waitcnt vmcnt(0)" ::: "memory")
; #define GLDS_STAGE(buf, kt) gemm_stage(t, (buf), (kt), shm, wid, lane)
; DEVFI void gemm_stage(const TileSrc& t, const int buf, const int kt, char* shm, const int wid, const int lane) {
;   int R, C; stage_rc<G_KS>(wid * 1024 + lane * 16, R, C);
;   const int oa = R * t.lda + C, ob = R * t.ldb + C;
; #pragma unroll
;   for (int i = 0; i < G_GL; ++i) {
;     __builtin_amdgcn_global_load_lds((const unsigned*)(t.A + (i * 64 * t.lda + kt * G_BK) + oa), (unsigned*)(shm + buf * G_STAGE_B + wid * 1024 + i * 8192), 16, 0, 0);
;     __builtin_amdgcn_global_load_lds((const unsigned*)(t.B + (i * 64 * t.ldb + kt * G_BK) + ob), (unsigned*)(shm + buf * G_STAGE_B + G_TILE_B + wid * 1024 + i * 8192), 16, 0, 0); }
; }
; DEVFI void gemm_issue0(const TileSrc& t, char* shm, const int wv) { const int tid = opaque_tid(wv); gemm_stage(t, 0, 0, shm, tid >> 6, tid & 63); }
; template <class Epi>
; DEVFI void gemm_main(const TileSrc t, const int K, char* shm, const bool pf, const TileSrc nx, const int wv, Epi epi) {
;   const int tid = opaque_tid(wv), wid = tid >> 6, lane = tid & 63, wr = wid >> 1, wc = wid & 1, fr = lane & 15, fq = lane >> 4;
;     ...
;   f32x4 acc[4][8] = {};
;   const int nt = K / G_BK;
;   const int sw = (fr * 64 + fq * 16) ^ ((fr >> 3) << 5);
;   const char* aBase = shm + wr * 8192 + sw;
;   const char* bBase = shm + G_TILE_B + wc * 16384 + sw;
;   WAIT_V0(); __syncthreads();
;   for (int t_ = 0; t_ < nt; ++t_) { const int cur = t_ & 1;
;     if (t_ + 1 < nt) GLDS_STAGE(cur ^ 1, t_ + 1);
; #pragma unroll
;     for (int ks = 0; ks < G_KS; ++ks) {
;       bf16x8 At[4], Bf[8];
; #pragma unroll
;       for (int n = 0; n < 8; ++n) Bf[n] = *(const bf16x8*)(bBase + cur * G_STAGE_B + (n * 2048 + ks * 1024));
;       SBAR();
;       At[0] = *(const bf16x8*)(aBase + cur * G_STAGE_B + (0 * 2048 + ks * 1024)); SBAR();
;       At[1] = *(const bf16x8*)(aBase + cur * G_STAGE_B + (1 * 2048 + ks * 1024)); SBAR();
;       At[2] = *(const bf16x8*)(aBase + cur * G_STAGE_B + (2 * 2048 + ks * 1024)); SBAR();
;       At[3] = *(const bf16x8*)(aBase + cur * G_STAGE_B + (3 * 2048 + ks * 1024));
.LBB0_138:
	s_mov_b32 s9, -1
	s_ashr_i32 s27, s33, 7
	v_mbcnt_lo_u32_b32 v0, s9, 0
	v_mbcnt_hi_u32_b32 v203, s9, v0
	v_or_b32_e32 v205, s33, v203
	v_ashrrev_i32_e32 v134, 6, v205
	v_and_b32_e32 v202, 15, v203
	v_and_b32_e32 v206, 1, v134
	v_and_b32_e32 v146, 48, v203
	v_lshlrev_b32_e32 v132, 2, v202
	v_lshl_or_b32 v0, v202, 6, v146
	v_and_b32_e32 v1, 32, v132
	s_lshl_b32 s9, s27, 13
	v_lshlrev_b32_e32 v2, 14, v206
	v_bitop3_b32 v138, s9, v0, v1 bitop3:0xf6
	v_bitop3_b32 v139, v2, v0, v1 bitop3:0xf6
	v_lshlrev_b32_e32 v0, 4, v203
	v_and_b32_e32 v1, 32, v203
	v_lshrrev_b32_e32 v2, 31, v134
	v_add_u32_e32 v2, v134, v2
	v_bitop3_b32 v0, v0, v1, 48 bitop3:0x6c
	v_ashrrev_i32_e32 v135, 1, v2
	v_lshrrev_b32_e32 v136, 1, v0
	v_lshlrev_b32_e32 v0, 8, v203
	v_and_b32_e32 v137, 0x3c00, v0
	v_mul_lo_u32 v0, v135, s66
	v_or_b32_e32 v0, v136, v0
	v_lshlrev_b32_e32 v1, 5, v134
	v_add3_u32 v0, v0, v137, v1
	v_ashrrev_i32_e32 v1, 31, v0
	s_waitcnt vmcnt(0)
	v_lshlrev_b64 v[0:1], 1, v[0:1]
	v_lshl_add_u64 v[128:129], s[6:7], 0, v[0:1]
	v_lshl_add_u64 v[130:131], s[2:3], 0, v[0:1]
	v_mov_b32_e32 v0, 0
	s_mov_b32 s8, 0
	v_and_b32_e32 v204, 63, v203
	v_lshlrev_b32_e32 v133, 10, v134
	s_mov_b64 s[6:7], 0
	v_mov_b32_e32 v1, v0
	v_mov_b32_e32 v2, v0
	v_mov_b32_e32 v3, v0
	v_mov_b32_e32 v4, v0
	v_mov_b32_e32 v5, v0
	v_mov_b32_e32 v6, v0
	v_mov_b32_e32 v7, v0
	v_mov_b32_e32 v8, v0
	v_mov_b32_e32 v9, v0
	v_mov_b32_e32 v10, v0
	v_mov_b32_e32 v11, v0
	v_mov_b32_e32 v12, v0
	v_mov_b32_e32 v13, v0
	v_mov_b32_e32 v14, v0
	v_mov_b32_e32 v15, v0
	v_mov_b32_e32 v16, v0
	v_mov_b32_e32 v17, v0
	v_mov_b32_e32 v18, v0
	v_mov_b32_e32 v19, v0
	v_mov_b32_e32 v20, v0
	v_mov_b32_e32 v21, v0
	v_mov_b32_e32 v22, v0
	v_mov_b32_e32 v23, v0
	v_mov_b32_e32 v24, v0
	v_mov_b32_e32 v25, v0
	v_mov_b32_e32 v26, v0
	v_mov_b32_e32 v27, v0
	v_mov_b32_e32 v28, v0
	v_mov_b32_e32 v29, v0
	v_mov_b32_e32 v30, v0
	v_mov_b32_e32 v31, v0
	v_mov_b32_e32 v32, v0
	v_mov_b32_e32 v33, v0
	v_mov_b32_e32 v34, v0
	v_mov_b32_e32 v35, v0
	v_mov_b32_e32 v36, v0
	v_mov_b32_e32 v37, v0
	v_mov_b32_e32 v38, v0
	v_mov_b32_e32 v39, v0
	v_mov_b32_e32 v40, v0
	v_mov_b32_e32 v41, v0
	v_mov_b32_e32 v42, v0
	v_mov_b32_e32 v43, v0
	v_mov_b32_e32 v44, v0
	v_mov_b32_e32 v45, v0
	v_mov_b32_e32 v46, v0
	v_mov_b32_e32 v47, v0
	v_mov_b32_e32 v48, v0
	v_mov_b32_e32 v49, v0
	v_mov_b32_e32 v50, v0
	v_mov_b32_e32 v51, v0
	v_mov_b32_e32 v52, v0
	v_mov_b32_e32 v53, v0
	v_mov_b32_e32 v54, v0
	v_mov_b32_e32 v55, v0
	v_mov_b32_e32 v56, v0
	v_mov_b32_e32 v57, v0
	v_mov_b32_e32 v58, v0
	v_mov_b32_e32 v59, v0
	v_mov_b32_e32 v60, v0
	v_mov_b32_e32 v61, v0
	v_mov_b32_e32 v62, v0
	v_mov_b32_e32 v63, v0
	v_mov_b32_e32 v64, v0
	v_mov_b32_e32 v65, v0
	v_mov_b32_e32 v66, v0
	v_mov_b32_e32 v67, v0
	v_mov_b32_e32 v68, v0
	v_mov_b32_e32 v69, v0
	v_mov_b32_e32 v70, v0
	v_mov_b32_e32 v71, v0
	v_mov_b32_e32 v72, v0
	v_mov_b32_e32 v73, v0
	v_mov_b32_e32 v74, v0
	v_mov_b32_e32 v75, v0
	v_mov_b32_e32 v76, v0
	v_mov_b32_e32 v77, v0
	v_mov_b32_e32 v78, v0
	v_mov_b32_e32 v79, v0
	v_mov_b32_e32 v80, v0
	v_mov_b32_e32 v81, v0
	v_mov_b32_e32 v82, v0
	v_mov_b32_e32 v83, v0
	v_mov_b32_e32 v84, v0
	v_mov_b32_e32 v85, v0
	v_mov_b32_e32 v86, v0
	v_mov_b32_e32 v87, v0
	v_mov_b32_e32 v88, v0
	v_mov_b32_e32 v89, v0
	v_mov_b32_e32 v90, v0
	v_mov_b32_e32 v91, v0
	v_mov_b32_e32 v92, v0
	v_mov_b32_e32 v93, v0
	v_mov_b32_e32 v94, v0
	v_mov_b32_e32 v95, v0
	v_mov_b32_e32 v96, v0
	v_mov_b32_e32 v97, v0
	v_mov_b32_e32 v98, v0
	v_mov_b32_e32 v99, v0
	v_mov_b32_e32 v100, v0
	v_mov_b32_e32 v101, v0
	v_mov_b32_e32 v102, v0
	v_mov_b32_e32 v103, v0
	v_mov_b32_e32 v104, v0
	v_mov_b32_e32 v105, v0
	v_mov_b32_e32 v106, v0
	v_mov_b32_e32 v107, v0
	v_mov_b32_e32 v108, v0
	v_mov_b32_e32 v109, v0
	v_mov_b32_e32 v110, v0
	v_mov_b32_e32 v111, v0
	v_mov_b32_e32 v112, v0
	v_mov_b32_e32 v113, v0
	v_mov_b32_e32 v114, v0
	v_mov_b32_e32 v115, v0
	v_mov_b32_e32 v116, v0
	v_mov_b32_e32 v117, v0
	v_mov_b32_e32 v118, v0
	v_mov_b32_e32 v119, v0
	v_mov_b32_e32 v120, v0
	v_mov_b32_e32 v121, v0
	v_mov_b32_e32 v122, v0
	v_mov_b32_e32 v123, v0
	v_mov_b32_e32 v124, v0
	v_mov_b32_e32 v125, v0
	v_mov_b32_e32 v126, v0
	v_mov_b32_e32 v127, v0
	s_waitcnt lgkmcnt(0)
	s_lshr_b32 s2, s33, 6
	s_lshr_b32 s3, s2, 1
	s_sub_u32 s3, s2, s3
	s_mov_b32 s6, 0x20000
	s_lshr_b32 s7, s6, 2
	s_mul_i32 s3, s3, s7
	s_and_b32 s7, s2, 1
	s_lshl_b32 s7, s7, 6
	s_sub_u32 s3, s3, s7
	s_add_u32 s3, s3, 0x80
	s_lshl_b32 s8, s6, 1
	s_lshl_b32 s2, s2, 11
	s_mov_b32 vcc_hi, 0
	s_mov_b32 vcc_lo, s3
	v_lshl_add_u64 v[130:131], v[130:131], 0, vcc
	v_lshl_add_u64 v[128:129], v[128:129], 0, vcc
	s_mov_b32 vcc_lo, s8
	v_lshl_add_u64 v[144:145], v[130:131], 0, vcc
	v_lshl_add_u64 v[200:201], v[128:129], 0, vcc
	v_add_u32_e32 v147, 0x10000, v138
	v_add_u32_e32 v207, 0x10000, v139
	s_nop 0
	v_readfirstlane_b32 s6, v130
	v_readfirstlane_b32 s7, v131
	v_readfirstlane_b32 vcc_lo, v128
	v_readfirstlane_b32 vcc_hi, v129
	s_nop 1
	v_subrev_u32_e32 v130, s6, v130
	v_subrev_u32_e32 v128, vcc_lo, v128
	v_add_u32_e32 v144, s8, v130
	v_add_u32_e32 v200, s8, v128
	s_nop 4
	s_add_u32 m0, s2, 0x10000
	s_nop 0
	global_load_lds_dwordx4 v130, s[6:7]
	s_add_u32 m0, s2, 0x14000
	s_nop 0
	global_load_lds_dwordx4 v144, s[6:7]
	s_add_u32 s6, s6, 64
	s_addc_u32 s7, s7, 0
	s_add_u32 m0, s2, 0x18000
	s_nop 0
	global_load_lds_dwordx4 v128, vcc
	s_add_u32 m0, s2, 0x1c000
	s_nop 0
	global_load_lds_dwordx4 v200, vcc
	s_add_u32 vcc_lo, vcc_lo, 64
	s_addc_u32 vcc_hi, vcc_hi, 0
	s_add_u32 m0, s2, 0x10400
	s_nop 0
	global_load_lds_dwordx4 v130, s[6:7]
	s_add_u32 m0, s2, 0x14400
	s_nop 0
	global_load_lds_dwordx4 v144, s[6:7]
	s_add_u32 s6, s6, 64
	s_addc_u32 s7, s7, 0
	s_add_u32 m0, s2, 0x18400
	s_nop 0
	global_load_lds_dwordx4 v128, vcc
	s_add_u32 m0, s2, 0x1c400
	s_nop 0
	global_load_lds_dwordx4 v200, vcc
	s_add_u32 vcc_lo, vcc_lo, 64
	s_addc_u32 vcc_hi, vcc_hi, 0
	s_waitcnt vmcnt(8)
	s_barrier
	ds_read_b128 v[140:143], v138
	ds_read_b128 v[148:151], v138 offset:2048
	ds_read_b128 v[152:155], v138 offset:4096
	ds_read_b128 v[156:159], v138 offset:6144
	ds_read_b128 v[178:181], v139 offset:32768
	ds_read_b128 v[184:187], v139 offset:34816
	ds_read_b128 v[188:191], v139 offset:36864
	ds_read_b128 v[192:195], v139 offset:38912
	ds_read_b128 v[196:199], v139 offset:40960
	ds_read_b128 v[208:211], v139 offset:43008
	ds_read_b128 v[218:221], v139 offset:45056
	ds_read_b128 v[228:231], v139 offset:47104
	s_mov_b32 s3, 7
; #define SBAR() __builtin_amdgcn_sched_barrier(0)
; #define WAIT_V0() asm volatile("s_waitcnt vmcnt(0)" ::: "memory")
; #define GLDS_STAGE(buf, kt) gemm_stage(t, (buf), (kt), shm, wid, lane)
; template <class Epi>
; DEVFI void gemm_main(const TileSrc t, const int K, char* shm, const bool pf, const TileSrc nx, const int wv, Epi epi) {
;     ...
;   for (int t_ = 0; t_ < nt; ++t_) { const int cur = t_ & 1;
;     if (t_ + 1 < nt) GLDS_STAGE(cur ^ 1, t_ + 1);
; #pragma unroll
;     for (int ks = 0; ks < G_KS; ++ks) {
;       bf16x8 At[4], Bf[8];
; #pragma unroll
;       for (int n = 0; n < 8; ++n) Bf[n] = *(const bf16x8*)(bBase + cur * G_STAGE_B + (n * 2048 + ks * 1024));
;       SBAR();
;       At[0] = *(const bf16x8*)(aBase + cur * G_STAGE_B + (0 * 2048 + ks * 1024)); SBAR();
;       At[1] = *(const bf16x8*)(aBase + cur * G_STAGE_B + (1 * 2048 + ks * 1024)); SBAR();
;       At[2] = *(const bf16x8*)(aBase + cur * G_STAGE_B + (2 * 2048 + ks * 1024)); SBAR();
;       At[3] = *(const bf16x8*)(aBase + cur * G_STAGE_B + (3 * 2048 + ks * 1024));
;       SBAR();
;       __builtin_amdgcn_s_setprio(1);
; #pragma unroll
;       for (int m = 0; m < 4; ++m)
; #pragma unroll
;         for (int n = 0; n < 8; ++n) acc[m][n] = __builtin_amdgcn_mfma_f32_16x16x32_bf16(At[m], Bf[n], acc[m][n], 0, 0, 0);
;       __builtin_amdgcn_s_setprio(0);
;       SBAR();
;     }
;     WAIT_V0(); __syncthreads();
.LgkA_loop:
	s_waitcnt lgkmcnt(0)
	s_waitcnt vmcnt(8)
	s_barrier
	v_mfma_f32_16x16x32_bf16 v[124:127], v[140:143], v[178:181], v[124:127]
	ds_read_b128 v[160:163], v138 offset:1024
	s_add_u32 m0, s2, 0x0
	v_mfma_f32_16x16x32_bf16 v[92:95], v[148:151], v[178:181], v[92:95]
	ds_read_b128 v[164:167], v138 offset:3072
	v_mfma_f32_16x16x32_bf16 v[60:63], v[152:155], v[178:181], v[60:63]
	ds_read_b128 v[168:171], v138 offset:5120
	global_load_lds_dwordx4 v130, s[6:7]
	v_mfma_f32_16x16x32_bf16 v[28:31], v[156:159], v[178:181], v[28:31]
	ds_read_b128 v[172:175], v138 offset:7168
	v_mfma_f32_16x16x32_bf16 v[120:123], v[140:143], v[184:187], v[120:123]
	ds_read_b128 v[224:227], v139 offset:46080
	v_mfma_f32_16x16x32_bf16 v[88:91], v[148:151], v[184:187], v[88:91]
	ds_read_b128 v[232:235], v139 offset:48128
	v_mfma_f32_16x16x32_bf16 v[56:59], v[152:155], v[184:187], v[56:59]
	ds_read_b128 v[178:181], v139 offset:33792
	v_mfma_f32_16x16x32_bf16 v[24:27], v[156:159], v[184:187], v[24:27]
	ds_read_b128 v[184:187], v139 offset:35840
	v_mfma_f32_16x16x32_bf16 v[108:111], v[140:143], v[188:191], v[108:111]
	s_add_u32 m0, s2, 0x4000
	v_mfma_f32_16x16x32_bf16 v[76:79], v[148:151], v[188:191], v[76:79]
	v_mfma_f32_16x16x32_bf16 v[44:47], v[152:155], v[188:191], v[44:47]
	global_load_lds_dwordx4 v144, s[6:7]
	v_mfma_f32_16x16x32_bf16 v[12:15], v[156:159], v[188:191], v[12:15]
	ds_read_b128 v[188:191], v139 offset:37888
	s_add_u32 s6, s6, 64
	s_addc_u32 s7, s7, 0
	v_mfma_f32_16x16x32_bf16 v[104:107], v[140:143], v[192:195], v[104:107]
	v_mfma_f32_16x16x32_bf16 v[72:75], v[148:151], v[192:195], v[72:75]
	v_mfma_f32_16x16x32_bf16 v[40:43], v[152:155], v[192:195], v[40:43]
	v_mfma_f32_16x16x32_bf16 v[8:11], v[156:159], v[192:195], v[8:11]
	ds_read_b128 v[192:195], v139 offset:39936
	v_mfma_f32_16x16x32_bf16 v[116:119], v[140:143], v[196:199], v[116:119]
	s_add_u32 m0, s2, 0x8000
	v_mfma_f32_16x16x32_bf16 v[84:87], v[148:151], v[196:199], v[84:87]
	v_mfma_f32_16x16x32_bf16 v[52:55], v[152:155], v[196:199], v[52:55]
	global_load_lds_dwordx4 v128, vcc
	v_mfma_f32_16x16x32_bf16 v[20:23], v[156:159], v[196:199], v[20:23]
	ds_read_b128 v[196:199], v139 offset:41984
	v_mfma_f32_16x16x32_bf16 v[112:115], v[140:143], v[208:211], v[112:115]
	v_mfma_f32_16x16x32_bf16 v[80:83], v[148:151], v[208:211], v[80:83]
	v_mfma_f32_16x16x32_bf16 v[48:51], v[152:155], v[208:211], v[48:51]
	v_mfma_f32_16x16x32_bf16 v[16:19], v[156:159], v[208:211], v[16:19]
	ds_read_b128 v[208:211], v139 offset:44032
	v_mfma_f32_16x16x32_bf16 v[100:103], v[140:143], v[218:221], v[100:103]
	s_add_u32 m0, s2, 0xc000
	v_mfma_f32_16x16x32_bf16 v[68:71], v[148:151], v[218:221], v[68:71]
	v_mfma_f32_16x16x32_bf16 v[36:39], v[152:155], v[218:221], v[36:39]
	global_load_lds_dwordx4 v200, vcc
	v_mfma_f32_16x16x32_bf16 v[4:7], v[156:159], v[218:221], v[4:7]
	s_add_u32 vcc_lo, vcc_lo, 64
	s_addc_u32 vcc_hi, vcc_hi, 0
	v_mfma_f32_16x16x32_bf16 v[96:99], v[140:143], v[228:231], v[96:99]
	v_mfma_f32_16x16x32_bf16 v[64:67], v[148:151], v[228:231], v[64:67]
	v_mfma_f32_16x16x32_bf16 v[32:35], v[152:155], v[228:231], v[32:35]
	v_mfma_f32_16x16x32_bf16 v[0:3], v[156:159], v[228:231], v[0:3]
	s_waitcnt lgkmcnt(0)
	s_waitcnt vmcnt(8)
	s_barrier
	v_mfma_f32_16x16x32_bf16 v[124:127], v[160:163], v[178:181], v[124:127]
	ds_read_b128 v[140:143], v147
	s_add_u32 m0, s2, 0x400
	v_mfma_f32_16x16x32_bf16 v[92:95], v[164:167], v[178:181], v[92:95]
	ds_read_b128 v[148:151], v147 offset:2048
	v_mfma_f32_16x16x32_bf16 v[60:63], v[168:171], v[178:181], v[60:63]
	ds_read_b128 v[152:155], v147 offset:4096
	global_load_lds_dwordx4 v130, s[6:7]
	v_mfma_f32_16x16x32_bf16 v[28:31], v[172:175], v[178:181], v[28:31]
	ds_read_b128 v[156:159], v147 offset:6144
	v_mfma_f32_16x16x32_bf16 v[120:123], v[160:163], v[184:187], v[120:123]
	ds_read_b128 v[218:221], v207 offset:45056
	v_mfma_f32_16x16x32_bf16 v[88:91], v[164:167], v[184:187], v[88:91]
	ds_read_b128 v[228:231], v207 offset:47104
	v_mfma_f32_16x16x32_bf16 v[56:59], v[168:171], v[184:187], v[56:59]
	ds_read_b128 v[178:181], v207 offset:32768
	v_mfma_f32_16x16x32_bf16 v[24:27], v[172:175], v[184:187], v[24:27]
	ds_read_b128 v[184:187], v207 offset:34816
	v_mfma_f32_16x16x32_bf16 v[108:111], v[160:163], v[188:191], v[108:111]
	s_add_u32 m0, s2, 0x4400
	v_mfma_f32_16x16x32_bf16 v[76:79], v[164:167], v[188:191], v[76:79]
	v_mfma_f32_16x16x32_bf16 v[44:47], v[168:171], v[188:191], v[44:47]
	global_load_lds_dwordx4 v144, s[6:7]
	v_mfma_f32_16x16x32_bf16 v[12:15], v[172:175], v[188:191], v[12:15]
	ds_read_b128 v[188:191], v207 offset:36864
	s_add_u32 s6, s6, 64
	s_addc_u32 s7, s7, 0
	v_mfma_f32_16x16x32_bf16 v[104:107], v[160:163], v[192:195], v[104:107]
	v_mfma_f32_16x16x32_bf16 v[72:75], v[164:167], v[192:195], v[72:75]
	v_mfma_f32_16x16x32_bf16 v[40:43], v[168:171], v[192:195], v[40:43]
	v_mfma_f32_16x16x32_bf16 v[8:11], v[172:175], v[192:195], v[8:11]
	ds_read_b128 v[192:195], v207 offset:38912
	v_mfma_f32_16x16x32_bf16 v[116:119], v[160:163], v[196:199], v[116:119]
	s_add_u32 m0, s2, 0x8400
	v_mfma_f32_16x16x32_bf16 v[84:87], v[164:167], v[196:199], v[84:87]
	v_mfma_f32_16x16x32_bf16 v[52:55], v[168:171], v[196:199], v[52:55]
	global_load_lds_dwordx4 v128, vcc
	v_mfma_f32_16x16x32_bf16 v[20:23], v[172:175], v[196:199], v[20:23]
	ds_read_b128 v[196:199], v207 offset:40960
	v_mfma_f32_16x16x32_bf16 v[112:115], v[160:163], v[208:211], v[112:115]
	v_mfma_f32_16x16x32_bf16 v[80:83], v[164:167], v[208:211], v[80:83]
	v_mfma_f32_16x16x32_bf16 v[48:51], v[168:171], v[208:211], v[48:51]
	v_mfma_f32_16x16x32_bf16 v[16:19], v[172:175], v[208:211], v[16:19]
	ds_read_b128 v[208:211], v207 offset:43008
	v_mfma_f32_16x16x32_bf16 v[100:103], v[160:163], v[224:227], v[100:103]
	s_add_u32 m0, s2, 0xc400
	v_mfma_f32_16x16x32_bf16 v[68:71], v[164:167], v[224:227], v[68:71]
	v_mfma_f32_16x16x32_bf16 v[36:39], v[168:171], v[224:227], v[36:39]
	global_load_lds_dwordx4 v200, vcc
	v_mfma_f32_16x16x32_bf16 v[4:7], v[172:175], v[224:227], v[4:7]
	s_add_u32 vcc_lo, vcc_lo, 64
	s_addc_u32 vcc_hi, vcc_hi, 0
	v_mfma_f32_16x16x32_bf16 v[96:99], v[160:163], v[232:235], v[96:99]
	v_mfma_f32_16x16x32_bf16 v[64:67], v[164:167], v[232:235], v[64:67]
	v_mfma_f32_16x16x32_bf16 v[32:35], v[168:171], v[232:235], v[32:35]
	v_mfma_f32_16x16x32_bf16 v[0:3], v[172:175], v[232:235], v[0:3]
	s_waitcnt lgkmcnt(0)
	s_waitcnt vmcnt(8)
	s_barrier
; #define SBAR() __builtin_amdgcn_sched_barrier(0)
; #define WAIT_V0() asm volatile("s_waitcnt vmcnt(0)" ::: "memory")
; #define GLDS_STAGE(buf, kt) gemm_stage(t, (buf), (kt), shm, wid, lane)
; template <class Epi>
; DEVFI void gemm_main(const TileSrc t, const int K, char* shm, const bool pf, const TileSrc nx, const int wv, Epi epi) {
;     ...
;   for (int t_ = 0; t_ < nt; ++t_) { const int cur = t_ & 1;
;     if (t_ + 1 < nt) GLDS_STAGE(cur ^ 1, t_ + 1);
; #pragma unroll
;     for (int ks = 0; ks < G_KS; ++ks) {
;       bf16x8 At[4], Bf[8];
; #pragma unroll
;       for (int n = 0; n < 8; ++n) Bf[n] = *(const bf16x8*)(bBase + cur * G_STAGE_B + (n * 2048 + ks * 1024));
;       SBAR();
;       At[0] = *(const bf16x8*)(aBase + cur * G_STAGE_B + (0 * 2048 + ks * 1024)); SBAR();
;       At[1] = *(const bf16x8*)(aBase + cur * G_STAGE_B + (1 * 2048 + ks * 1024)); SBAR();
;       At[2] = *(const bf16x8*)(aBase + cur * G_STAGE_B + (2 * 2048 + ks * 1024)); SBAR();
;       At[3] = *(const bf16x8*)(aBase + cur * G_STAGE_B + (3 * 2048 + ks * 1024));
;       SBAR();
;       __builtin_amdgcn_s_setprio(1);
; #pragma unroll
;       for (int m = 0; m < 4; ++m)
; #pragma unroll
;         for (int n = 0; n < 8; ++n) acc[m][n] = __builtin_amdgcn_mfma_f32_16x16x32_bf16(At[m], Bf[n], acc[m][n], 0, 0, 0);
;       __builtin_amdgcn_s_setprio(0);
;       SBAR();
;     }
;     WAIT_V0(); __syncthreads();
	v_mfma_f32_16x16x32_bf16 v[124:127], v[140:143], v[178:181], v[124:127]
	ds_read_b128 v[160:163], v147 offset:1024
	s_add_u32 m0, s2, 0x10000
	v_mfma_f32_16x16x32_bf16 v[92:95], v[148:151], v[178:181], v[92:95]
	ds_read_b128 v[164:167], v147 offset:3072
	v_mfma_f32_16x16x32_bf16 v[60:63], v[152:155], v[178:181], v[60:63]
	ds_read_b128 v[168:171], v147 offset:5120
	global_load_lds_dwordx4 v130, s[6:7]
	v_mfma_f32_16x16x32_bf16 v[28:31], v[156:159], v[178:181], v[28:31]
	ds_read_b128 v[172:175], v147 offset:7168
	v_mfma_f32_16x16x32_bf16 v[120:123], v[140:143], v[184:187], v[120:123]
	ds_read_b128 v[224:227], v207 offset:46080
	v_mfma_f32_16x16x32_bf16 v[88:91], v[148:151], v[184:187], v[88:91]
	ds_read_b128 v[232:235], v207 offset:48128
	v_mfma_f32_16x16x32_bf16 v[56:59], v[152:155], v[184:187], v[56:59]
	ds_read_b128 v[178:181], v207 offset:33792
	v_mfma_f32_16x16x32_bf16 v[24:27], v[156:159], v[184:187], v[24:27]
	ds_read_b128 v[184:187], v207 offset:35840
	v_mfma_f32_16x16x32_bf16 v[108:111], v[140:143], v[188:191], v[108:111]
	s_add_u32 m0, s2, 0x14000
	v_mfma_f32_16x16x32_bf16 v[76:79], v[148:151], v[188:191], v[76:79]
	v_mfma_f32_16x16x32_bf16 v[44:47], v[152:155], v[188:191], v[44:47]
	global_load_lds_dwordx4 v144, s[6:7]
	v_mfma_f32_16x16x32_bf16 v[12:15], v[156:159], v[188:191], v[12:15]
	ds_read_b128 v[188:191], v207 offset:37888
	s_add_u32 s6, s6, 64
	s_addc_u32 s7, s7, 0
	v_mfma_f32_16x16x32_bf16 v[104:107], v[140:143], v[192:195], v[104:107]
	v_mfma_f32_16x16x32_bf16 v[72:75], v[148:151], v[192:195], v[72:75]
	v_mfma_f32_16x16x32_bf16 v[40:43], v[152:155], v[192:195], v[40:43]
	v_mfma_f32_16x16x32_bf16 v[8:11], v[156:159], v[192:195], v[8:11]
	ds_read_b128 v[192:195], v207 offset:39936
	v_mfma_f32_16x16x32_bf16 v[116:119], v[140:143], v[196:199], v[116:119]
	s_add_u32 m0, s2, 0x18000
	v_mfma_f32_16x16x32_bf16 v[84:87], v[148:151], v[196:199], v[84:87]
	v_mfma_f32_16x16x32_bf16 v[52:55], v[152:155], v[196:199], v[52:55]
	global_load_lds_dwordx4 v128, vcc
	v_mfma_f32_16x16x32_bf16 v[20:23], v[156:159], v[196:199], v[20:23]
	ds_read_b128 v[196:199], v207 offset:41984
	v_mfma_f32_16x16x32_bf16 v[112:115], v[140:143], v[208:211], v[112:115]
	v_mfma_f32_16x16x32_bf16 v[80:83], v[148:151], v[208:211], v[80:83]
	v_mfma_f32_16x16x32_bf16 v[48:51], v[152:155], v[208:211], v[48:51]
	v_mfma_f32_16x16x32_bf16 v[16:19], v[156:159], v[208:211], v[16:19]
	ds_read_b128 v[208:211], v207 offset:44032
	v_mfma_f32_16x16x32_bf16 v[100:103], v[140:143], v[218:221], v[100:103]
	s_add_u32 m0, s2, 0x1c000
	v_mfma_f32_16x16x32_bf16 v[68:71], v[148:151], v[218:221], v[68:71]
	v_mfma_f32_16x16x32_bf16 v[36:39], v[152:155], v[218:221], v[36:39]
	global_load_lds_dwordx4 v200, vcc
	v_mfma_f32_16x16x32_bf16 v[4:7], v[156:159], v[218:221], v[4:7]
	s_add_u32 vcc_lo, vcc_lo, 64
	s_addc_u32 vcc_hi, vcc_hi, 0
	v_mfma_f32_16x16x32_bf16 v[96:99], v[140:143], v[228:231], v[96:99]
	v_mfma_f32_16x16x32_bf16 v[64:67], v[148:151], v[228:231], v[64:67]
	v_mfma_f32_16x16x32_bf16 v[32:35], v[152:155], v[228:231], v[32:35]
	v_mfma_f32_16x16x32_bf16 v[0:3], v[156:159], v[228:231], v[0:3]
	s_waitcnt lgkmcnt(0)
	s_waitcnt vmcnt(8)
	s_barrier
	v_mfma_f32_16x16x32_bf16 v[124:127], v[160:163], v[178:181], v[124:127]
	ds_read_b128 v[140:143], v138
	s_add_u32 m0, s2, 0x10400
	v_mfma_f32_16x16x32_bf16 v[92:95], v[164:167], v[178:181], v[92:95]
	ds_read_b128 v[148:151], v138 offset:2048
	v_mfma_f32_16x16x32_bf16 v[60:63], v[168:171], v[178:181], v[60:63]
	ds_read_b128 v[152:155], v138 offset:4096
	global_load_lds_dwordx4 v130, s[6:7]
	v_mfma_f32_16x16x32_bf16 v[28:31], v[172:175], v[178:181], v[28:31]
	ds_read_b128 v[156:159], v138 offset:6144
	v_mfma_f32_16x16x32_bf16 v[120:123], v[160:163], v[184:187], v[120:123]
	ds_read_b128 v[218:221], v139 offset:45056
	v_mfma_f32_16x16x32_bf16 v[88:91], v[164:167], v[184:187], v[88:91]
	ds_read_b128 v[228:231], v139 offset:47104
	v_mfma_f32_16x16x32_bf16 v[56:59], v[168:171], v[184:187], v[56:59]
	ds_read_b128 v[178:181], v139 offset:32768
	v_mfma_f32_16x16x32_bf16 v[24:27], v[172:175], v[184:187], v[24:27]
	ds_read_b128 v[184:187], v139 offset:34816
	v_mfma_f32_16x16x32_bf16 v[108:111], v[160:163], v[188:191], v[108:111]
	s_add_u32 m0, s2, 0x14400
	v_mfma_f32_16x16x32_bf16 v[76:79], v[164:167], v[188:191], v[76:79]
	v_mfma_f32_16x16x32_bf16 v[44:47], v[168:171], v[188:191], v[44:47]
	global_load_lds_dwordx4 v144, s[6:7]
	v_mfma_f32_16x16x32_bf16 v[12:15], v[172:175], v[188:191], v[12:15]
	ds_read_b128 v[188:191], v139 offset:36864
	s_add_u32 s6, s6, 64
	s_addc_u32 s7, s7, 0
	v_mfma_f32_16x16x32_bf16 v[104:107], v[160:163], v[192:195], v[104:107]
	v_mfma_f32_16x16x32_bf16 v[72:75], v[164:167], v[192:195], v[72:75]
	v_mfma_f32_16x16x32_bf16 v[40:43], v[168:171], v[192:195], v[40:43]
	v_mfma_f32_16x16x32_bf16 v[8:11], v[172:175], v[192:195], v[8:11]
	ds_read_b128 v[192:195], v139 offset:38912
	v_mfma_f32_16x16x32_bf16 v[116:119], v[160:163], v[196:199], v[116:119]
	s_add_u32 m0, s2, 0x18400
	v_mfma_f32_16x16x32_bf16 v[84:87], v[164:167], v[196:199], v[84:87]
	v_mfma_f32_16x16x32_bf16 v[52:55], v[168:171], v[196:199], v[52:55]
	global_load_lds_dwordx4 v128, vcc
	v_mfma_f32_16x16x32_bf16 v[20:23], v[172:175], v[196:199], v[20:23]
	ds_read_b128 v[196:199], v139 offset:40960
	v_mfma_f32_16x16x32_bf16 v[112:115], v[160:163], v[208:211], v[112:115]
	v_mfma_f32_16x16x32_bf16 v[80:83], v[164:167], v[208:211], v[80:83]
	v_mfma_f32_16x16x32_bf16 v[48:51], v[168:171], v[208:211], v[48:51]
	v_mfma_f32_16x16x32_bf16 v[16:19], v[172:175], v[208:211], v[16:19]
	ds_read_b128 v[208:211], v139 offset:43008
	v_mfma_f32_16x16x32_bf16 v[100:103], v[160:163], v[224:227], v[100:103]
	s_add_u32 m0, s2, 0x1c400
	v_mfma_f32_16x16x32_bf16 v[68:71], v[164:167], v[224:227], v[68:71]
	v_mfma_f32_16x16x32_bf16 v[36:39], v[168:171], v[224:227], v[36:39]
	global_load_lds_dwordx4 v200, vcc
	v_mfma_f32_16x16x32_bf16 v[4:7], v[172:175], v[224:227], v[4:7]
	s_add_u32 vcc_lo, vcc_lo, 64
	s_addc_u32 vcc_hi, vcc_hi, 0
	v_mfma_f32_16x16x32_bf16 v[96:99], v[160:163], v[232:235], v[96:99]
	v_mfma_f32_16x16x32_bf16 v[64:67], v[164:167], v[232:235], v[64:67]
	v_mfma_f32_16x16x32_bf16 v[32:35], v[168:171], v[232:235], v[32:35]
	v_mfma_f32_16x16x32_bf16 v[0:3], v[172:175], v[232:235], v[0:3]
	s_sub_u32 s3, s3, 1
	s_cmp_lg_u32 s3, 0
	s_cbranch_scc1 .LgkA_loop
; #define SBAR() __builtin_amdgcn_sched_barrier(0)
; #define WAIT_V0() asm volatile("s_waitcnt vmcnt(0)" ::: "memory")
; #define GLDS_STAGE(buf, kt) gemm_stage(t, (buf), (kt), shm, wid, lane)
; template <class Epi>
; DEVFI void gemm_main(const TileSrc t, const int K, char* shm, const bool pf, const TileSrc nx, const int wv, Epi epi) {
;     ...
;   for (int t_ = 0; t_ < nt; ++t_) { const int cur = t_ & 1;
;     if (t_ + 1 < nt) GLDS_STAGE(cur ^ 1, t_ + 1);
; #pragma unroll
;     for (int ks = 0; ks < G_KS; ++ks) {
;       bf16x8 At[4], Bf[8];
; #pragma unroll
;       for (int n = 0; n < 8; ++n) Bf[n] = *(const bf16x8*)(bBase + cur * G_STAGE_B + (n * 2048 + ks * 1024));
;       SBAR();
;       At[0] = *(const bf16x8*)(aBase + cur * G_STAGE_B + (0 * 2048 + ks * 1024)); SBAR();
;       At[1] = *(const bf16x8*)(aBase + cur * G_STAGE_B + (1 * 2048 + ks * 1024)); SBAR();
;       At[2] = *(const bf16x8*)(aBase + cur * G_STAGE_B + (2 * 2048 + ks * 1024)); SBAR();
;       At[3] = *(const bf16x8*)(aBase + cur * G_STAGE_B + (3 * 2048 + ks * 1024));
;       SBAR();
;       __builtin_amdgcn_s_setprio(1);
; #pragma unroll
;       for (int m = 0; m < 4; ++m)
; #pragma unroll
;         for (int n = 0; n < 8; ++n) acc[m][n] = __builtin_amdgcn_mfma_f32_16x16x32_bf16(At[m], Bf[n], acc[m][n], 0, 0, 0);
;       __builtin_amdgcn_s_setprio(0);
;       SBAR();
;     }
;     WAIT_V0(); __syncthreads();
	s_waitcnt lgkmcnt(0)
	s_waitcnt vmcnt(8)
	s_barrier
	v_mfma_f32_16x16x32_bf16 v[124:127], v[140:143], v[178:181], v[124:127]
	ds_read_b128 v[160:163], v138 offset:1024
	v_mfma_f32_16x16x32_bf16 v[92:95], v[148:151], v[178:181], v[92:95]
	ds_read_b128 v[164:167], v138 offset:3072
	v_mfma_f32_16x16x32_bf16 v[60:63], v[152:155], v[178:181], v[60:63]
	ds_read_b128 v[168:171], v138 offset:5120
	v_mfma_f32_16x16x32_bf16 v[28:31], v[156:159], v[178:181], v[28:31]
	ds_read_b128 v[172:175], v138 offset:7168
	v_mfma_f32_16x16x32_bf16 v[120:123], v[140:143], v[184:187], v[120:123]
	ds_read_b128 v[224:227], v139 offset:46080
	v_mfma_f32_16x16x32_bf16 v[88:91], v[148:151], v[184:187], v[88:91]
	ds_read_b128 v[232:235], v139 offset:48128
	v_mfma_f32_16x16x32_bf16 v[56:59], v[152:155], v[184:187], v[56:59]
	ds_read_b128 v[178:181], v139 offset:33792
	v_mfma_f32_16x16x32_bf16 v[24:27], v[156:159], v[184:187], v[24:27]
	ds_read_b128 v[184:187], v139 offset:35840
	v_mfma_f32_16x16x32_bf16 v[108:111], v[140:143], v[188:191], v[108:111]
	v_mfma_f32_16x16x32_bf16 v[76:79], v[148:151], v[188:191], v[76:79]
	v_mfma_f32_16x16x32_bf16 v[44:47], v[152:155], v[188:191], v[44:47]
	v_mfma_f32_16x16x32_bf16 v[12:15], v[156:159], v[188:191], v[12:15]
	ds_read_b128 v[188:191], v139 offset:37888
	v_mfma_f32_16x16x32_bf16 v[104:107], v[140:143], v[192:195], v[104:107]
	v_mfma_f32_16x16x32_bf16 v[72:75], v[148:151], v[192:195], v[72:75]
	v_mfma_f32_16x16x32_bf16 v[40:43], v[152:155], v[192:195], v[40:43]
	v_mfma_f32_16x16x32_bf16 v[8:11], v[156:159], v[192:195], v[8:11]
	ds_read_b128 v[192:195], v139 offset:39936
	v_mfma_f32_16x16x32_bf16 v[116:119], v[140:143], v[196:199], v[116:119]
	v_mfma_f32_16x16x32_bf16 v[84:87], v[148:151], v[196:199], v[84:87]
	v_mfma_f32_16x16x32_bf16 v[52:55], v[152:155], v[196:199], v[52:55]
	v_mfma_f32_16x16x32_bf16 v[20:23], v[156:159], v[196:199], v[20:23]
	ds_read_b128 v[196:199], v139 offset:41984
	v_mfma_f32_16x16x32_bf16 v[112:115], v[140:143], v[208:211], v[112:115]
	v_mfma_f32_16x16x32_bf16 v[80:83], v[148:151], v[208:211], v[80:83]
	v_mfma_f32_16x16x32_bf16 v[48:51], v[152:155], v[208:211], v[48:51]
	v_mfma_f32_16x16x32_bf16 v[16:19], v[156:159], v[208:211], v[16:19]
	ds_read_b128 v[208:211], v139 offset:44032
	v_mfma_f32_16x16x32_bf16 v[100:103], v[140:143], v[218:221], v[100:103]
	v_mfma_f32_16x16x32_bf16 v[68:71], v[148:151], v[218:221], v[68:71]
	v_mfma_f32_16x16x32_bf16 v[36:39], v[152:155], v[218:221], v[36:39]
	v_mfma_f32_16x16x32_bf16 v[4:7], v[156:159], v[218:221], v[4:7]
	v_mfma_f32_16x16x32_bf16 v[96:99], v[140:143], v[228:231], v[96:99]
	v_mfma_f32_16x16x32_bf16 v[64:67], v[148:151], v[228:231], v[64:67]
	v_mfma_f32_16x16x32_bf16 v[32:35], v[152:155], v[228:231], v[32:35]
	v_mfma_f32_16x16x32_bf16 v[0:3], v[156:159], v[228:231], v[0:3]
	s_waitcnt lgkmcnt(0)
	s_waitcnt vmcnt(4)
	s_barrier
	v_mfma_f32_16x16x32_bf16 v[124:127], v[160:163], v[178:181], v[124:127]
	ds_read_b128 v[140:143], v147
	v_mfma_f32_16x16x32_bf16 v[92:95], v[164:167], v[178:181], v[92:95]
	ds_read_b128 v[148:151], v147 offset:2048
	v_mfma_f32_16x16x32_bf16 v[60:63], v[168:171], v[178:181], v[60:63]
	ds_read_b128 v[152:155], v147 offset:4096
	v_mfma_f32_16x16x32_bf16 v[28:31], v[172:175], v[178:181], v[28:31]
	ds_read_b128 v[156:159], v147 offset:6144
	v_mfma_f32_16x16x32_bf16 v[120:123], v[160:163], v[184:187], v[120:123]
	ds_read_b128 v[218:221], v207 offset:45056
	v_mfma_f32_16x16x32_bf16 v[88:91], v[164:167], v[184:187], v[88:91]
	ds_read_b128 v[228:231], v207 offset:47104
	v_mfma_f32_16x16x32_bf16 v[56:59], v[168:171], v[184:187], v[56:59]
	ds_read_b128 v[178:181], v207 offset:32768
	v_mfma_f32_16x16x32_bf16 v[24:27], v[172:175], v[184:187], v[24:27]
	ds_read_b128 v[184:187], v207 offset:34816
	v_mfma_f32_16x16x32_bf16 v[108:111], v[160:163], v[188:191], v[108:111]
	v_mfma_f32_16x16x32_bf16 v[76:79], v[164:167], v[188:191], v[76:79]
	v_mfma_f32_16x16x32_bf16 v[44:47], v[168:171], v[188:191], v[44:47]
	v_mfma_f32_16x16x32_bf16 v[12:15], v[172:175], v[188:191], v[12:15]
	ds_read_b128 v[188:191], v207 offset:36864
	v_mfma_f32_16x16x32_bf16 v[104:107], v[160:163], v[192:195], v[104:107]
	v_mfma_f32_16x16x32_bf16 v[72:75], v[164:167], v[192:195], v[72:75]
	v_mfma_f32_16x16x32_bf16 v[40:43], v[168:171], v[192:195], v[40:43]
	v_mfma_f32_16x16x32_bf16 v[8:11], v[172:175], v[192:195], v[8:11]
	ds_read_b128 v[192:195], v207 offset:38912
	v_mfma_f32_16x16x32_bf16 v[116:119], v[160:163], v[196:199], v[116:119]
	v_mfma_f32_16x16x32_bf16 v[84:87], v[164:167], v[196:199], v[84:87]
	v_mfma_f32_16x16x32_bf16 v[52:55], v[168:171], v[196:199], v[52:55]
	v_mfma_f32_16x16x32_bf16 v[20:23], v[172:175], v[196:199], v[20:23]
	ds_read_b128 v[196:199], v207 offset:40960
	v_mfma_f32_16x16x32_bf16 v[112:115], v[160:163], v[208:211], v[112:115]
	v_mfma_f32_16x16x32_bf16 v[80:83], v[164:167], v[208:211], v[80:83]
	v_mfma_f32_16x16x32_bf16 v[48:51], v[168:171], v[208:211], v[48:51]
	v_mfma_f32_16x16x32_bf16 v[16:19], v[172:175], v[208:211], v[16:19]
	ds_read_b128 v[208:211], v207 offset:43008
	v_mfma_f32_16x16x32_bf16 v[100:103], v[160:163], v[224:227], v[100:103]
	v_mfma_f32_16x16x32_bf16 v[68:71], v[164:167], v[224:227], v[68:71]
	v_mfma_f32_16x16x32_bf16 v[36:39], v[168:171], v[224:227], v[36:39]
	v_mfma_f32_16x16x32_bf16 v[4:7], v[172:175], v[224:227], v[4:7]
	v_mfma_f32_16x16x32_bf16 v[96:99], v[160:163], v[232:235], v[96:99]
	v_mfma_f32_16x16x32_bf16 v[64:67], v[164:167], v[232:235], v[64:67]
	v_mfma_f32_16x16x32_bf16 v[32:35], v[168:171], v[232:235], v[32:35]
	v_mfma_f32_16x16x32_bf16 v[0:3], v[172:175], v[232:235], v[0:3]
	s_waitcnt lgkmcnt(0)
	s_waitcnt vmcnt(0)
	s_barrier
; #define SBAR() __builtin_amdgcn_sched_barrier(0)
; #define WAIT_V0() asm volatile("s_waitcnt vmcnt(0)" ::: "memory")
; DEVFI void gemm_stage(const TileSrc& t, const int buf, const int kt, char* shm, const int wid, const int lane) {
;   int R, C; stage_rc<G_KS>(wid * 1024 + lane * 16, R, C);
;   const int oa = R * t.lda + C, ob = R * t.ldb + C;
; #pragma unroll
;   for (int i = 0; i < G_GL; ++i) {
;     __builtin_amdgcn_global_load_lds((const unsigned*)(t.A + (i * 64 * t.lda + kt * G_BK) + oa), (unsigned*)(shm + buf * G_STAGE_B + wid * 1024 + i * 8192), 16, 0, 0);
;     __builtin_amdgcn_global_load_lds((const unsigned*)(t.B + (i * 64 * t.ldb + kt * G_BK) + ob), (unsigned*)(shm + buf * G_STAGE_B + G_TILE_B + wid * 1024 + i * 8192), 16, 0, 0); }
; }
; template <class Epi>
; DEVFI void gemm_main(const TileSrc t, const int K, char* shm, const bool pf, const TileSrc nx, const int wv, Epi epi) {
;     ...
; #pragma unroll
;     for (int ks = 0; ks < G_KS; ++ks) {
;       bf16x8 At[4], Bf[8];
; #pragma unroll
;       for (int n = 0; n < 8; ++n) Bf[n] = *(const bf16x8*)(bBase + cur * G_STAGE_B + (n * 2048 + ks * 1024));
;       SBAR();
;       At[0] = *(const bf16x8*)(aBase + cur * G_STAGE_B + (0 * 2048 + ks * 1024)); SBAR();
;       At[1] = *(const bf16x8*)(aBase + cur * G_STAGE_B + (1 * 2048 + ks * 1024)); SBAR();
;       At[2] = *(const bf16x8*)(aBase + cur * G_STAGE_B + (2 * 2048 + ks * 1024)); SBAR();
;       At[3] = *(const bf16x8*)(aBase + cur * G_STAGE_B + (3 * 2048 + ks * 1024));
;       SBAR();
;       __builtin_amdgcn_s_setprio(1);
; #pragma unroll
;       for (int m = 0; m < 4; ++m)
; #pragma unroll
;         for (int n = 0; n < 8; ++n) acc[m][n] = __builtin_amdgcn_mfma_f32_16x16x32_bf16(At[m], Bf[n], acc[m][n], 0, 0, 0);
;       __builtin_amdgcn_s_setprio(0);
;       SBAR();
;     }
;     WAIT_V0(); __syncthreads();
;   }
;     ...
;   if (pf) gemm_stage(nx, 0, 0, shm, wid, lane);
	v_mfma_f32_16x16x32_bf16 v[124:127], v[140:143], v[178:181], v[124:127]
	ds_read_b128 v[160:163], v147 offset:1024
	v_mfma_f32_16x16x32_bf16 v[92:95], v[148:151], v[178:181], v[92:95]
	ds_read_b128 v[164:167], v147 offset:3072
	v_mfma_f32_16x16x32_bf16 v[60:63], v[152:155], v[178:181], v[60:63]
	ds_read_b128 v[168:171], v147 offset:5120
	v_mfma_f32_16x16x32_bf16 v[28:31], v[156:159], v[178:181], v[28:31]
	ds_read_b128 v[172:175], v147 offset:7168
	v_mfma_f32_16x16x32_bf16 v[120:123], v[140:143], v[184:187], v[120:123]
	ds_read_b128 v[224:227], v207 offset:46080
	v_mfma_f32_16x16x32_bf16 v[88:91], v[148:151], v[184:187], v[88:91]
	ds_read_b128 v[232:235], v207 offset:48128
	v_mfma_f32_16x16x32_bf16 v[56:59], v[152:155], v[184:187], v[56:59]
	ds_read_b128 v[178:181], v207 offset:33792
	v_mfma_f32_16x16x32_bf16 v[24:27], v[156:159], v[184:187], v[24:27]
	ds_read_b128 v[184:187], v207 offset:35840
	v_mfma_f32_16x16x32_bf16 v[108:111], v[140:143], v[188:191], v[108:111]
	v_mfma_f32_16x16x32_bf16 v[76:79], v[148:151], v[188:191], v[76:79]
	v_mfma_f32_16x16x32_bf16 v[44:47], v[152:155], v[188:191], v[44:47]
	v_mfma_f32_16x16x32_bf16 v[12:15], v[156:159], v[188:191], v[12:15]
	ds_read_b128 v[188:191], v207 offset:37888
	v_mfma_f32_16x16x32_bf16 v[104:107], v[140:143], v[192:195], v[104:107]
	v_mfma_f32_16x16x32_bf16 v[72:75], v[148:151], v[192:195], v[72:75]
	v_mfma_f32_16x16x32_bf16 v[40:43], v[152:155], v[192:195], v[40:43]
	v_mfma_f32_16x16x32_bf16 v[8:11], v[156:159], v[192:195], v[8:11]
	ds_read_b128 v[192:195], v207 offset:39936
	v_mfma_f32_16x16x32_bf16 v[116:119], v[140:143], v[196:199], v[116:119]
	v_mfma_f32_16x16x32_bf16 v[84:87], v[148:151], v[196:199], v[84:87]
	v_mfma_f32_16x16x32_bf16 v[52:55], v[152:155], v[196:199], v[52:55]
	v_mfma_f32_16x16x32_bf16 v[20:23], v[156:159], v[196:199], v[20:23]
	ds_read_b128 v[196:199], v207 offset:41984
	v_mfma_f32_16x16x32_bf16 v[112:115], v[140:143], v[208:211], v[112:115]
	v_mfma_f32_16x16x32_bf16 v[80:83], v[148:151], v[208:211], v[80:83]
	v_mfma_f32_16x16x32_bf16 v[48:51], v[152:155], v[208:211], v[48:51]
	v_mfma_f32_16x16x32_bf16 v[16:19], v[156:159], v[208:211], v[16:19]
	ds_read_b128 v[208:211], v207 offset:44032
	v_mfma_f32_16x16x32_bf16 v[100:103], v[140:143], v[218:221], v[100:103]
	v_mfma_f32_16x16x32_bf16 v[68:71], v[148:151], v[218:221], v[68:71]
	v_mfma_f32_16x16x32_bf16 v[36:39], v[152:155], v[218:221], v[36:39]
	v_mfma_f32_16x16x32_bf16 v[4:7], v[156:159], v[218:221], v[4:7]
	v_mfma_f32_16x16x32_bf16 v[96:99], v[140:143], v[228:231], v[96:99]
	v_mfma_f32_16x16x32_bf16 v[64:67], v[148:151], v[228:231], v[64:67]
	v_mfma_f32_16x16x32_bf16 v[32:35], v[152:155], v[228:231], v[32:35]
	v_mfma_f32_16x16x32_bf16 v[0:3], v[156:159], v[228:231], v[0:3]
	s_waitcnt lgkmcnt(0)
	s_barrier
	v_mfma_f32_16x16x32_bf16 v[124:127], v[160:163], v[178:181], v[124:127]
	v_mfma_f32_16x16x32_bf16 v[92:95], v[164:167], v[178:181], v[92:95]
	v_mfma_f32_16x16x32_bf16 v[60:63], v[168:171], v[178:181], v[60:63]
	v_mfma_f32_16x16x32_bf16 v[28:31], v[172:175], v[178:181], v[28:31]
	v_mfma_f32_16x16x32_bf16 v[120:123], v[160:163], v[184:187], v[120:123]
	v_mfma_f32_16x16x32_bf16 v[88:91], v[164:167], v[184:187], v[88:91]
	v_mfma_f32_16x16x32_bf16 v[56:59], v[168:171], v[184:187], v[56:59]
	v_mfma_f32_16x16x32_bf16 v[24:27], v[172:175], v[184:187], v[24:27]
	v_mfma_f32_16x16x32_bf16 v[108:111], v[160:163], v[188:191], v[108:111]
	v_mfma_f32_16x16x32_bf16 v[76:79], v[164:167], v[188:191], v[76:79]
	v_mfma_f32_16x16x32_bf16 v[44:47], v[168:171], v[188:191], v[44:47]
	v_mfma_f32_16x16x32_bf16 v[12:15], v[172:175], v[188:191], v[12:15]
	v_mfma_f32_16x16x32_bf16 v[104:107], v[160:163], v[192:195], v[104:107]
	v_mfma_f32_16x16x32_bf16 v[72:75], v[164:167], v[192:195], v[72:75]
	v_mfma_f32_16x16x32_bf16 v[40:43], v[168:171], v[192:195], v[40:43]
	v_mfma_f32_16x16x32_bf16 v[8:11], v[172:175], v[192:195], v[8:11]
	v_mfma_f32_16x16x32_bf16 v[116:119], v[160:163], v[196:199], v[116:119]
	v_mfma_f32_16x16x32_bf16 v[84:87], v[164:167], v[196:199], v[84:87]
	v_mfma_f32_16x16x32_bf16 v[52:55], v[168:171], v[196:199], v[52:55]
	v_mfma_f32_16x16x32_bf16 v[20:23], v[172:175], v[196:199], v[20:23]
	v_mfma_f32_16x16x32_bf16 v[112:115], v[160:163], v[208:211], v[112:115]
	v_mfma_f32_16x16x32_bf16 v[80:83], v[164:167], v[208:211], v[80:83]
	v_mfma_f32_16x16x32_bf16 v[48:51], v[168:171], v[208:211], v[48:51]
	v_mfma_f32_16x16x32_bf16 v[16:19], v[172:175], v[208:211], v[16:19]
	v_mfma_f32_16x16x32_bf16 v[100:103], v[160:163], v[224:227], v[100:103]
	v_mfma_f32_16x16x32_bf16 v[68:71], v[164:167], v[224:227], v[68:71]
	v_mfma_f32_16x16x32_bf16 v[36:39], v[168:171], v[224:227], v[36:39]
	v_mfma_f32_16x16x32_bf16 v[4:7], v[172:175], v[224:227], v[4:7]
	v_mfma_f32_16x16x32_bf16 v[96:99], v[160:163], v[232:235], v[96:99]
	v_mfma_f32_16x16x32_bf16 v[64:67], v[164:167], v[232:235], v[64:67]
	v_mfma_f32_16x16x32_bf16 v[32:35], v[168:171], v[232:235], v[32:35]
	v_mfma_f32_16x16x32_bf16 v[0:3], v[172:175], v[232:235], v[0:3]
	s_nop 7
	s_nop 3
	s_mov_b64 s[6:7], 0x780
	s_mov_b32 s8, 0xf0000
	s_and_b64 vcc, exec, s[4:5]
	s_cbranch_vccz .LBB0_142
	v_lshlrev_b32_e32 v128, 1, v135
	v_sub_u32_e32 v128, v134, v128
	v_lshl_or_b32 v129, v135, 14, v137
	v_lshl_add_u32 v128, v128, 5, v129
	v_or_b32_e32 v128, v128, v136
	v_ashrrev_i32_e32 v129, 31, v128
	v_add_u32_e32 v134, 0x8000, v133
	v_lshlrev_b64 v[128:129], 1, v[128:129]
	v_readfirstlane_b32 s2, v133
	v_lshl_add_u64 v[130:131], s[20:21], 0, v[128:129]
	s_mov_b32 m0, s2
	v_readfirstlane_b32 s2, v134
	v_add_u32_e32 v136, 0x2000, v133
	global_load_lds_dwordx4 v[130:131], off
	v_lshl_add_u64 v[128:129], s[24:25], 0, v[128:129]
	s_mov_b32 m0, s2
	v_readfirstlane_b32 s2, v136
	v_add_u32_e32 v136, 0xa000, v133
	global_load_lds_dwordx4 v[128:129], off
	v_lshl_add_u64 v[134:135], v[130:131], 0, s[86:87]
	s_mov_b32 m0, s2
	v_readfirstlane_b32 s2, v136
	v_add_u32_e32 v136, 0x4000, v133
	global_load_lds_dwordx4 v[134:135], off
	v_lshl_add_u64 v[134:135], v[128:129], 0, s[86:87]
	s_mov_b32 m0, s2
	v_readfirstlane_b32 s2, v136
	v_add_u32_e32 v136, 0xc000, v133
	global_load_lds_dwordx4 v[134:135], off
	v_lshl_add_u64 v[134:135], v[130:131], 0, s[88:89]
	s_mov_b32 m0, s2
	v_readfirstlane_b32 s2, v136
	global_load_lds_dwordx4 v[134:135], off
	v_lshl_add_u64 v[134:135], v[128:129], 0, s[88:89]
	s_mov_b32 m0, s2
	v_lshl_add_u64 v[130:131], v[130:131], 0, s[90:91]
	global_load_lds_dwordx4 v[134:135], off
	v_add_u32_e32 v134, 0x6000, v133
	v_lshl_add_u64 v[128:129], v[128:129], 0, s[90:91]
	v_readfirstlane_b32 s2, v134
	s_mov_b32 m0, s2
	s_nop 0
	global_load_lds_dwordx4 v[130:131], off
	v_add_u32_e32 v130, 0xe000, v133
	s_nop 0
	v_readfirstlane_b32 s2, v130
	s_mov_b32 m0, s2
	s_nop 0
	global_load_lds_dwordx4 v[128:129], off

; DEVFI float dpp_xor1(float x) { return __int_as_float(__builtin_amdgcn_update_dpp(0, __float_as_int(x), 0xB1, 0xF, 0xF, true)); }
; #define XBF ((bfraw*)(kargs()->ws + O_XBF))
; DEVFI void store_nat_m(bfraw* base, long ld, f32x4 (&a)[8], int fr) {
;   const bool odd = fr & 1;
;   bfraw* p0 = base + (odd ? 15 + fr : fr);
; #pragma unroll
;   for (int j = 0; j < 4; ++j)
; #pragma unroll
;     for (int n0 = 0; n0 < 8; n0 += 2) { const float own0 = a[n0][j], own1 = a[n0 + 1][j];
;       const float recv = dpp_xor1(odd ? own0 : own1);
;       const unsigned pk = odd ? cvtpk(recv, own1) : cvtpk(own0, recv);
;       *reinterpret_cast<unsigned*>(p0 + (long)j * ld + n0 * 16) = pk; }
; }
; __global__ void __launch_bounds__(512) mega(Params p) {
;     ...
;             if (u >= n_in && s != 0) store_nat(XBF + ((long)(s - 1) * T_SB + brow + wr0) * 1024 + bcol + wc0, 1024, acc, fr, fq);
.LBB0_150:
	s_or_b64 s[4:5], s[18:19], s[2:3]
	v_lshrrev_b32_e32 v147, 4, v204
	v_lshlrev_b32_e64 v128, 6, s27
	v_lshlrev_b32_e32 v133, 7, v206
	s_mov_b64 s[2:3], -1
	s_and_b64 vcc, exec, s[4:5]
	s_cbranch_vccnz .LBB0_408
	s_mov_b64 s[2:3], s[0:1]
	s_load_dwordx2 s[2:3], s[2:3], 0xe8
	v_and_b32_e32 v129, 1, v203
	v_cmp_eq_u32_e64 s[6:7], 0, v129
	v_cmp_eq_u32_e64 s[4:5], 1, v129
	s_nop 0
	v_cndmask_b32_e64 v129, v124, v120, s[6:7]
	s_nop 1
	v_mov_b32_dpp v129, v129 quad_perm:[1,0,3,2] row_mask:0xf bank_mask:0xf bound_ctrl:1
	v_cndmask_b32_e64 v136, v124, v129, s[4:5]
	v_cndmask_b32_e64 v129, v129, v120, s[4:5]
	v_cvt_pk_bf16_f32 v136, v136, v129
	s_ashr_i32 s77, s76, 31
	v_ashrrev_i32_e32 v129, 31, v128
	v_lshl_add_u64 v[130:131], s[76:77], 0, v[128:129]
	s_waitcnt lgkmcnt(0)
	s_add_u32 s2, s2, s57
	v_lshlrev_b64 v[130:131], 11, v[130:131]
	s_addc_u32 s3, s3, s84
	v_lshl_add_u64 v[130:131], s[2:3], 0, v[130:131]
	s_ashr_i32 s27, s26, 31
	v_lshl_add_u64 v[130:131], s[26:27], 1, v[130:131]
	v_lshlrev_b32_e32 v176, 1, v133
	v_lshl_add_u64 v[130:131], v[130:131], 0, v[176:177]
	v_lshlrev_b32_e32 v176, 13, v147
	v_add_u32_e32 v129, 15, v202
	v_lshl_add_u64 v[130:131], v[130:131], 0, v[176:177]
	s_mov_b64 s[2:3], 0x7720000
	v_cndmask_b32_e64 v129, v129, v202, s[6:7]
	v_lshl_add_u64 v[130:131], v[130:131], 0, s[2:3]
	v_lshlrev_b32_e32 v176, 1, v129
	v_lshl_add_u64 v[134:135], v[130:131], 0, v[176:177]
	v_cndmask_b32_e64 v129, v108, v104, s[6:7]
	global_store_dword v[134:135], v136, off
	s_nop 0
	v_mov_b32_dpp v136, v129 quad_perm:[1,0,3,2] row_mask:0xf bank_mask:0xf bound_ctrl:1
	v_cndmask_b32_e64 v129, v108, v136, s[4:5]
	v_cndmask_b32_e64 v136, v136, v104, s[4:5]
	v_cvt_pk_bf16_f32 v129, v129, v136
	global_store_dword v[134:135], v129, off offset:64
	v_cndmask_b32_e64 v129, v116, v112, s[6:7]
	s_nop 1
	v_mov_b32_dpp v136, v129 quad_perm:[1,0,3,2] row_mask:0xf bank_mask:0xf bound_ctrl:1
	v_cndmask_b32_e64 v129, v116, v136, s[4:5]
	v_cndmask_b32_e64 v136, v136, v112, s[4:5]
	v_cvt_pk_bf16_f32 v129, v129, v136
	global_store_dword v[134:135], v129, off offset:128
	v_cndmask_b32_e64 v129, v100, v96, s[6:7]
	s_nop 1
	v_mov_b32_dpp v136, v129 quad_perm:[1,0,3,2] row_mask:0xf bank_mask:0xf bound_ctrl:1
	v_cndmask_b32_e64 v129, v100, v136, s[4:5]
	v_cndmask_b32_e64 v136, v136, v96, s[4:5]
	v_cvt_pk_bf16_f32 v129, v129, v136
	global_store_dword v[134:135], v129, off offset:192
	v_cndmask_b32_e64 v129, v125, v121, s[6:7]
	s_nop 1
	v_mov_b32_dpp v136, v129 quad_perm:[1,0,3,2] row_mask:0xf bank_mask:0xf bound_ctrl:1
	v_cndmask_b32_e64 v129, v125, v136, s[4:5]
	v_cndmask_b32_e64 v136, v136, v121, s[4:5]
	v_cvt_pk_bf16_f32 v129, v129, v136
	global_store_dword v[134:135], v129, off offset:2048
	v_cndmask_b32_e64 v129, v109, v105, s[6:7]
	s_nop 1
	v_mov_b32_dpp v136, v129 quad_perm:[1,0,3,2] row_mask:0xf bank_mask:0xf bound_ctrl:1
	v_cndmask_b32_e64 v129, v109, v136, s[4:5]
	v_cndmask_b32_e64 v136, v136, v105, s[4:5]
	v_cvt_pk_bf16_f32 v129, v129, v136
	global_store_dword v[134:135], v129, off offset:2112
	v_cndmask_b32_e64 v129, v117, v113, s[6:7]
	s_nop 1
	v_mov_b32_dpp v136, v129 quad_perm:[1,0,3,2] row_mask:0xf bank_mask:0xf bound_ctrl:1
	v_cndmask_b32_e64 v129, v117, v136, s[4:5]
	v_cndmask_b32_e64 v136, v136, v113, s[4:5]
	v_cvt_pk_bf16_f32 v129, v129, v136
	global_store_dword v[134:135], v129, off offset:2176
	v_cndmask_b32_e64 v129, v101, v97, s[6:7]
	s_nop 1
	v_mov_b32_dpp v136, v129 quad_perm:[1,0,3,2] row_mask:0xf bank_mask:0xf bound_ctrl:1
	v_cndmask_b32_e64 v129, v101, v136, s[4:5]
	v_cndmask_b32_e64 v136, v136, v97, s[4:5]
	v_cvt_pk_bf16_f32 v129, v129, v136
	global_store_dword v[134:135], v129, off offset:2240
	v_cndmask_b32_e64 v129, v126, v122, s[6:7]
	s_nop 1
	v_mov_b32_dpp v136, v129 quad_perm:[1,0,3,2] row_mask:0xf bank_mask:0xf bound_ctrl:1
	v_cndmask_b32_e64 v129, v126, v136, s[4:5]
	v_cndmask_b32_e64 v136, v136, v122, s[4:5]
	v_cvt_pk_bf16_f32 v129, v129, v136
	v_add_co_u32_e32 v136, vcc, 0x1000, v134
	s_nop 1
	v_addc_co_u32_e32 v137, vcc, 0, v135, vcc
	global_store_dword v[136:137], v129, off
	v_cndmask_b32_e64 v129, v110, v106, s[6:7]
	s_nop 1
	v_mov_b32_dpp v136, v129 quad_perm:[1,0,3,2] row_mask:0xf bank_mask:0xf bound_ctrl:1
	v_cndmask_b32_e64 v129, v110, v136, s[4:5]
	v_cndmask_b32_e64 v136, v136, v106, s[4:5]
	v_cvt_pk_bf16_f32 v129, v129, v136
	v_add_co_u32_e32 v136, vcc, 0x1000, v134
	s_nop 1
	v_addc_co_u32_e32 v137, vcc, 0, v135, vcc
	global_store_dword v[136:137], v129, off offset:64
	v_cndmask_b32_e64 v129, v118, v114, s[6:7]
	s_nop 1
	v_mov_b32_dpp v136, v129 quad_perm:[1,0,3,2] row_mask:0xf bank_mask:0xf bound_ctrl:1
	v_cndmask_b32_e64 v129, v118, v136, s[4:5]
	v_cndmask_b32_e64 v136, v136, v114, s[4:5]
	v_cvt_pk_bf16_f32 v129, v129, v136
	v_add_co_u32_e32 v136, vcc, 0x1000, v134
	s_nop 1
	v_addc_co_u32_e32 v137, vcc, 0, v135, vcc
	global_store_dword v[136:137], v129, off offset:128
	v_cndmask_b32_e64 v129, v102, v98, s[6:7]
	s_nop 1
	v_mov_b32_dpp v136, v129 quad_perm:[1,0,3,2] row_mask:0xf bank_mask:0xf bound_ctrl:1
	v_cndmask_b32_e64 v129, v102, v136, s[4:5]
	v_cndmask_b32_e64 v136, v136, v98, s[4:5]
	v_cvt_pk_bf16_f32 v129, v129, v136
	v_add_co_u32_e32 v136, vcc, 0x1000, v134
	s_nop 1
	v_addc_co_u32_e32 v137, vcc, 0, v135, vcc
	global_store_dword v[136:137], v129, off offset:192
	v_cndmask_b32_e64 v129, v127, v123, s[6:7]
	s_nop 1
	v_mov_b32_dpp v136, v129 quad_perm:[1,0,3,2] row_mask:0xf bank_mask:0xf bound_ctrl:1
	v_cndmask_b32_e64 v129, v127, v136, s[4:5]
	v_cndmask_b32_e64 v136, v136, v123, s[4:5]
	v_cvt_pk_bf16_f32 v129, v129, v136
	v_add_co_u32_e32 v136, vcc, 0x1000, v134
	s_nop 1
	v_addc_co_u32_e32 v137, vcc, 0, v135, vcc
; DEVFI float dpp_xor1(float x) { return __int_as_float(__builtin_amdgcn_update_dpp(0, __float_as_int(x), 0xB1, 0xF, 0xF, true)); }
; #define XBF ((bfraw*)(kargs()->ws + O_XBF))
; DEVFI void store_nat_m(bfraw* base, long ld, f32x4 (&a)[8], int fr) {
;   const bool odd = fr & 1;
;   bfraw* p0 = base + (odd ? 15 + fr : fr);
; #pragma unroll
;   for (int j = 0; j < 4; ++j)
; #pragma unroll
;     for (int n0 = 0; n0 < 8; n0 += 2) { const float own0 = a[n0][j], own1 = a[n0 + 1][j];
;       const float recv = dpp_xor1(odd ? own0 : own1);
;       const unsigned pk = odd ? cvtpk(recv, own1) : cvtpk(own0, recv);
;       *reinterpret_cast<unsigned*>(p0 + (long)j * ld + n0 * 16) = pk; }
; }
; __global__ void __launch_bounds__(512) mega(Params p) {
;     ...
;             if (u >= n_in && s != 0) store_nat(XBF + ((long)(s - 1) * T_SB + brow + wr0) * 1024 + bcol + wc0, 1024, acc, fr, fq);
	global_store_dword v[136:137], v129, off offset:2048
	v_cndmask_b32_e64 v129, v111, v107, s[6:7]
	s_nop 1
	v_mov_b32_dpp v136, v129 quad_perm:[1,0,3,2] row_mask:0xf bank_mask:0xf bound_ctrl:1
	v_cndmask_b32_e64 v129, v111, v136, s[4:5]
	v_cndmask_b32_e64 v136, v136, v107, s[4:5]
	v_cvt_pk_bf16_f32 v129, v129, v136
	v_add_co_u32_e32 v136, vcc, 0x1000, v134
	s_nop 1
	v_addc_co_u32_e32 v137, vcc, 0, v135, vcc
	global_store_dword v[136:137], v129, off offset:2112
	v_cndmask_b32_e64 v129, v119, v115, s[6:7]
	s_nop 1
	v_mov_b32_dpp v136, v129 quad_perm:[1,0,3,2] row_mask:0xf bank_mask:0xf bound_ctrl:1
	v_cndmask_b32_e64 v129, v119, v136, s[4:5]
	v_cndmask_b32_e64 v136, v136, v115, s[4:5]
	v_cvt_pk_bf16_f32 v129, v129, v136
	v_add_co_u32_e32 v136, vcc, 0x1000, v134
	s_nop 1
	v_addc_co_u32_e32 v137, vcc, 0, v135, vcc
	global_store_dword v[136:137], v129, off offset:2176
	v_cndmask_b32_e64 v129, v103, v99, s[6:7]
	s_nop 1
	v_mov_b32_dpp v136, v129 quad_perm:[1,0,3,2] row_mask:0xf bank_mask:0xf bound_ctrl:1
	v_cndmask_b32_e64 v129, v103, v136, s[4:5]
	v_cndmask_b32_e64 v136, v136, v99, s[4:5]
	v_cvt_pk_bf16_f32 v129, v129, v136
	v_add_co_u32_e32 v134, vcc, 0x1000, v134
	s_nop 1
	v_addc_co_u32_e32 v135, vcc, 0, v135, vcc
	global_store_dword v[134:135], v129, off offset:2240
	v_cndmask_b32_e64 v129, v92, v88, s[6:7]
	s_nop 1
	v_mov_b32_dpp v134, v129 quad_perm:[1,0,3,2] row_mask:0xf bank_mask:0xf bound_ctrl:1
	v_cndmask_b32_e64 v129, v92, v134, s[4:5]
	v_cndmask_b32_e64 v134, v134, v88, s[4:5]
	v_cvt_pk_bf16_f32 v129, v129, v134
	v_lshl_add_u64 v[134:135], v[130:131], 0, v[176:177]
	v_add_co_u32_e32 v136, vcc, 0x8000, v134
	s_nop 1
	v_addc_co_u32_e32 v137, vcc, 0, v135, vcc
	global_store_dword v[136:137], v129, off
	v_cndmask_b32_e64 v129, v76, v72, s[6:7]
	s_nop 1
	v_mov_b32_dpp v136, v129 quad_perm:[1,0,3,2] row_mask:0xf bank_mask:0xf bound_ctrl:1
	v_cndmask_b32_e64 v129, v76, v136, s[4:5]
	v_cndmask_b32_e64 v136, v136, v72, s[4:5]
	v_cvt_pk_bf16_f32 v129, v129, v136
	s_mov_b64 s[2:3], 0x8000
	v_lshl_add_u64 v[134:135], v[134:135], 0, s[2:3]
	global_store_dword v[134:135], v129, off offset:64
	v_cndmask_b32_e64 v129, v84, v80, s[6:7]
	s_nop 1
	v_mov_b32_dpp v136, v129 quad_perm:[1,0,3,2] row_mask:0xf bank_mask:0xf bound_ctrl:1
	v_cndmask_b32_e64 v129, v84, v136, s[4:5]
	v_cndmask_b32_e64 v136, v136, v80, s[4:5]
	v_cvt_pk_bf16_f32 v129, v129, v136
	global_store_dword v[134:135], v129, off offset:128
	v_cndmask_b32_e64 v129, v68, v64, s[6:7]
	s_nop 1
	v_mov_b32_dpp v136, v129 quad_perm:[1,0,3,2] row_mask:0xf bank_mask:0xf bound_ctrl:1
	v_cndmask_b32_e64 v129, v68, v136, s[4:5]
	v_cndmask_b32_e64 v136, v136, v64, s[4:5]
	v_cvt_pk_bf16_f32 v129, v129, v136
	global_store_dword v[134:135], v129, off offset:192
	v_cndmask_b32_e64 v129, v93, v89, s[6:7]
	s_nop 1
	v_mov_b32_dpp v136, v129 quad_perm:[1,0,3,2] row_mask:0xf bank_mask:0xf bound_ctrl:1
	v_cndmask_b32_e64 v129, v93, v136, s[4:5]
	v_cndmask_b32_e64 v136, v136, v89, s[4:5]
	v_cvt_pk_bf16_f32 v129, v129, v136
	global_store_dword v[134:135], v129, off offset:2048
	v_cndmask_b32_e64 v129, v77, v73, s[6:7]
	s_nop 1
	v_mov_b32_dpp v136, v129 quad_perm:[1,0,3,2] row_mask:0xf bank_mask:0xf bound_ctrl:1
	v_cndmask_b32_e64 v129, v77, v136, s[4:5]
	v_cndmask_b32_e64 v136, v136, v73, s[4:5]
	v_cvt_pk_bf16_f32 v129, v129, v136
	global_store_dword v[134:135], v129, off offset:2112
	v_cndmask_b32_e64 v129, v85, v81, s[6:7]
	s_nop 1
	v_mov_b32_dpp v136, v129 quad_perm:[1,0,3,2] row_mask:0xf bank_mask:0xf bound_ctrl:1
	v_cndmask_b32_e64 v129, v85, v136, s[4:5]
	v_cndmask_b32_e64 v136, v136, v81, s[4:5]
	v_cvt_pk_bf16_f32 v129, v129, v136
	global_store_dword v[134:135], v129, off offset:2176
	v_cndmask_b32_e64 v129, v69, v65, s[6:7]
	s_nop 1
	v_mov_b32_dpp v136, v129 quad_perm:[1,0,3,2] row_mask:0xf bank_mask:0xf bound_ctrl:1
	v_cndmask_b32_e64 v129, v69, v136, s[4:5]
	v_cndmask_b32_e64 v136, v136, v65, s[4:5]
	v_cvt_pk_bf16_f32 v129, v129, v136
	global_store_dword v[134:135], v129, off offset:2240
	v_cndmask_b32_e64 v129, v94, v90, s[6:7]
	s_nop 1
	v_mov_b32_dpp v136, v129 quad_perm:[1,0,3,2] row_mask:0xf bank_mask:0xf bound_ctrl:1
	v_cndmask_b32_e64 v129, v94, v136, s[4:5]
	v_cndmask_b32_e64 v136, v136, v90, s[4:5]
	v_cvt_pk_bf16_f32 v129, v129, v136
	v_add_co_u32_e32 v136, vcc, 0x1000, v134
	s_nop 1
	v_addc_co_u32_e32 v137, vcc, 0, v135, vcc
	global_store_dword v[136:137], v129, off
	v_cndmask_b32_e64 v129, v78, v74, s[6:7]
	s_nop 1
	v_mov_b32_dpp v136, v129 quad_perm:[1,0,3,2] row_mask:0xf bank_mask:0xf bound_ctrl:1
	v_cndmask_b32_e64 v129, v78, v136, s[4:5]
	v_cndmask_b32_e64 v136, v136, v74, s[4:5]
	v_cvt_pk_bf16_f32 v129, v129, v136
	v_add_co_u32_e32 v136, vcc, 0x1000, v134
	s_nop 1
	v_addc_co_u32_e32 v137, vcc, 0, v135, vcc
	global_store_dword v[136:137], v129, off offset:64
	v_cndmask_b32_e64 v129, v86, v82, s[6:7]
	s_nop 1
	v_mov_b32_dpp v136, v129 quad_perm:[1,0,3,2] row_mask:0xf bank_mask:0xf bound_ctrl:1
	v_cndmask_b32_e64 v129, v86, v136, s[4:5]
	v_cndmask_b32_e64 v136, v136, v82, s[4:5]
	v_cvt_pk_bf16_f32 v129, v129, v136
	v_add_co_u32_e32 v136, vcc, 0x1000, v134
	s_nop 1
	v_addc_co_u32_e32 v137, vcc, 0, v135, vcc
	global_store_dword v[136:137], v129, off offset:128
	v_cndmask_b32_e64 v129, v70, v66, s[6:7]
	s_nop 1
	v_mov_b32_dpp v136, v129 quad_perm:[1,0,3,2] row_mask:0xf bank_mask:0xf bound_ctrl:1
	v_cndmask_b32_e64 v129, v70, v136, s[4:5]
	v_cndmask_b32_e64 v136, v136, v66, s[4:5]
	v_cvt_pk_bf16_f32 v129, v129, v136
	v_add_co_u32_e32 v136, vcc, 0x1000, v134
	s_nop 1
	v_addc_co_u32_e32 v137, vcc, 0, v135, vcc
	global_store_dword v[136:137], v129, off offset:192
	v_cndmask_b32_e64 v129, v95, v91, s[6:7]
; DEVFI float dpp_xor1(float x) { return __int_as_float(__builtin_amdgcn_update_dpp(0, __float_as_int(x), 0xB1, 0xF, 0xF, true)); }
; #define XBF ((bfraw*)(kargs()->ws + O_XBF))
; DEVFI void store_nat_m(bfraw* base, long ld, f32x4 (&a)[8], int fr) {
;   const bool odd = fr & 1;
;   bfraw* p0 = base + (odd ? 15 + fr : fr);
; #pragma unroll
;   for (int j = 0; j < 4; ++j)
; #pragma unroll
;     for (int n0 = 0; n0 < 8; n0 += 2) { const float own0 = a[n0][j], own1 = a[n0 + 1][j];
;       const float recv = dpp_xor1(odd ? own0 : own1);
;       const unsigned pk = odd ? cvtpk(recv, own1) : cvtpk(own0, recv);
;       *reinterpret_cast<unsigned*>(p0 + (long)j * ld + n0 * 16) = pk; }
; }
; __global__ void __launch_bounds__(512) mega(Params p) {
;     ...
;             if (u >= n_in && s != 0) store_nat(XBF + ((long)(s - 1) * T_SB + brow + wr0) * 1024 + bcol + wc0, 1024, acc, fr, fq);
	s_nop 1
	v_mov_b32_dpp v136, v129 quad_perm:[1,0,3,2] row_mask:0xf bank_mask:0xf bound_ctrl:1
	v_cndmask_b32_e64 v129, v95, v136, s[4:5]
	v_cndmask_b32_e64 v136, v136, v91, s[4:5]
	v_cvt_pk_bf16_f32 v129, v129, v136
	v_add_co_u32_e32 v136, vcc, 0x1000, v134
	s_nop 1
	v_addc_co_u32_e32 v137, vcc, 0, v135, vcc
	global_store_dword v[136:137], v129, off offset:2048
	v_cndmask_b32_e64 v129, v79, v75, s[6:7]
	s_nop 1
	v_mov_b32_dpp v136, v129 quad_perm:[1,0,3,2] row_mask:0xf bank_mask:0xf bound_ctrl:1
	v_cndmask_b32_e64 v129, v79, v136, s[4:5]
	v_cndmask_b32_e64 v136, v136, v75, s[4:5]
	v_cvt_pk_bf16_f32 v129, v129, v136
	v_add_co_u32_e32 v136, vcc, 0x1000, v134
	s_nop 1
	v_addc_co_u32_e32 v137, vcc, 0, v135, vcc
	global_store_dword v[136:137], v129, off offset:2112
	v_cndmask_b32_e64 v129, v87, v83, s[6:7]
	s_nop 1
	v_mov_b32_dpp v136, v129 quad_perm:[1,0,3,2] row_mask:0xf bank_mask:0xf bound_ctrl:1
	v_cndmask_b32_e64 v129, v87, v136, s[4:5]
	v_cndmask_b32_e64 v136, v136, v83, s[4:5]
	v_cvt_pk_bf16_f32 v129, v129, v136
	v_add_co_u32_e32 v136, vcc, 0x1000, v134
	s_nop 1
	v_addc_co_u32_e32 v137, vcc, 0, v135, vcc
	global_store_dword v[136:137], v129, off offset:2176
	v_cndmask_b32_e64 v129, v71, v67, s[6:7]
	s_nop 1
	v_mov_b32_dpp v136, v129 quad_perm:[1,0,3,2] row_mask:0xf bank_mask:0xf bound_ctrl:1
	v_cndmask_b32_e64 v129, v71, v136, s[4:5]
	v_cndmask_b32_e64 v136, v136, v67, s[4:5]
	v_cvt_pk_bf16_f32 v129, v129, v136
	v_add_co_u32_e32 v134, vcc, 0x1000, v134
	s_nop 1
	v_addc_co_u32_e32 v135, vcc, 0, v135, vcc
	global_store_dword v[134:135], v129, off offset:2240
	v_cndmask_b32_e64 v129, v60, v56, s[6:7]
	s_nop 1
	v_mov_b32_dpp v134, v129 quad_perm:[1,0,3,2] row_mask:0xf bank_mask:0xf bound_ctrl:1
	v_cndmask_b32_e64 v129, v60, v134, s[4:5]
	v_cndmask_b32_e64 v134, v134, v56, s[4:5]
	v_cvt_pk_bf16_f32 v129, v129, v134
	v_lshl_add_u64 v[134:135], v[130:131], 0, v[176:177]
	v_add_co_u32_e32 v136, vcc, 0x10000, v134
	s_nop 1
	v_addc_co_u32_e32 v137, vcc, 0, v135, vcc
	global_store_dword v[136:137], v129, off
	v_cndmask_b32_e64 v129, v44, v40, s[6:7]
	s_nop 1
	v_mov_b32_dpp v136, v129 quad_perm:[1,0,3,2] row_mask:0xf bank_mask:0xf bound_ctrl:1
	v_cndmask_b32_e64 v129, v44, v136, s[4:5]
	v_cndmask_b32_e64 v136, v136, v40, s[4:5]
	v_cvt_pk_bf16_f32 v129, v129, v136
	v_lshl_add_u64 v[134:135], v[134:135], 0, s[48:49]
	global_store_dword v[134:135], v129, off offset:64
	v_cndmask_b32_e64 v129, v52, v48, s[6:7]
	s_nop 1
	v_mov_b32_dpp v136, v129 quad_perm:[1,0,3,2] row_mask:0xf bank_mask:0xf bound_ctrl:1
	v_cndmask_b32_e64 v129, v52, v136, s[4:5]
	v_cndmask_b32_e64 v136, v136, v48, s[4:5]
	v_cvt_pk_bf16_f32 v129, v129, v136
	global_store_dword v[134:135], v129, off offset:128
	v_cndmask_b32_e64 v129, v36, v32, s[6:7]
	s_nop 1
	v_mov_b32_dpp v136, v129 quad_perm:[1,0,3,2] row_mask:0xf bank_mask:0xf bound_ctrl:1
	v_cndmask_b32_e64 v129, v36, v136, s[4:5]
	v_cndmask_b32_e64 v136, v136, v32, s[4:5]
	v_cvt_pk_bf16_f32 v129, v129, v136
	global_store_dword v[134:135], v129, off offset:192
	v_cndmask_b32_e64 v129, v61, v57, s[6:7]
	s_nop 1
	v_mov_b32_dpp v136, v129 quad_perm:[1,0,3,2] row_mask:0xf bank_mask:0xf bound_ctrl:1
	v_cndmask_b32_e64 v129, v61, v136, s[4:5]
	v_cndmask_b32_e64 v136, v136, v57, s[4:5]
	v_cvt_pk_bf16_f32 v129, v129, v136
	global_store_dword v[134:135], v129, off offset:2048
	v_cndmask_b32_e64 v129, v45, v41, s[6:7]
	s_nop 1
	v_mov_b32_dpp v136, v129 quad_perm:[1,0,3,2] row_mask:0xf bank_mask:0xf bound_ctrl:1
	v_cndmask_b32_e64 v129, v45, v136, s[4:5]
	v_cndmask_b32_e64 v136, v136, v41, s[4:5]
	v_cvt_pk_bf16_f32 v129, v129, v136
	global_store_dword v[134:135], v129, off offset:2112
	v_cndmask_b32_e64 v129, v53, v49, s[6:7]
	s_nop 1
	v_mov_b32_dpp v136, v129 quad_perm:[1,0,3,2] row_mask:0xf bank_mask:0xf bound_ctrl:1
	v_cndmask_b32_e64 v129, v53, v136, s[4:5]
	v_cndmask_b32_e64 v136, v136, v49, s[4:5]
	v_cvt_pk_bf16_f32 v129, v129, v136
	global_store_dword v[134:135], v129, off offset:2176
	v_cndmask_b32_e64 v129, v37, v33, s[6:7]
	s_nop 1
	v_mov_b32_dpp v136, v129 quad_perm:[1,0,3,2] row_mask:0xf bank_mask:0xf bound_ctrl:1
	v_cndmask_b32_e64 v129, v37, v136, s[4:5]
	v_cndmask_b32_e64 v136, v136, v33, s[4:5]
	v_cvt_pk_bf16_f32 v129, v129, v136
	global_store_dword v[134:135], v129, off offset:2240
	v_cndmask_b32_e64 v129, v62, v58, s[6:7]
	s_nop 1
	v_mov_b32_dpp v136, v129 quad_perm:[1,0,3,2] row_mask:0xf bank_mask:0xf bound_ctrl:1
	v_cndmask_b32_e64 v129, v62, v136, s[4:5]
	v_cndmask_b32_e64 v136, v136, v58, s[4:5]
	v_cvt_pk_bf16_f32 v129, v129, v136
	v_add_co_u32_e32 v136, vcc, 0x1000, v134
	s_nop 1
	v_addc_co_u32_e32 v137, vcc, 0, v135, vcc
	global_store_dword v[136:137], v129, off
	v_cndmask_b32_e64 v129, v46, v42, s[6:7]
	s_nop 1
	v_mov_b32_dpp v136, v129 quad_perm:[1,0,3,2] row_mask:0xf bank_mask:0xf bound_ctrl:1
	v_cndmask_b32_e64 v129, v46, v136, s[4:5]
	v_cndmask_b32_e64 v136, v136, v42, s[4:5]
	v_cvt_pk_bf16_f32 v129, v129, v136
	v_add_co_u32_e32 v136, vcc, 0x1000, v134
	s_nop 1
	v_addc_co_u32_e32 v137, vcc, 0, v135, vcc
	global_store_dword v[136:137], v129, off offset:64
	v_cndmask_b32_e64 v129, v54, v50, s[6:7]
	s_nop 1
	v_mov_b32_dpp v136, v129 quad_perm:[1,0,3,2] row_mask:0xf bank_mask:0xf bound_ctrl:1
	v_cndmask_b32_e64 v129, v54, v136, s[4:5]
	v_cndmask_b32_e64 v136, v136, v50, s[4:5]
	v_cvt_pk_bf16_f32 v129, v129, v136
	v_add_co_u32_e32 v136, vcc, 0x1000, v134
	s_nop 1
	v_addc_co_u32_e32 v137, vcc, 0, v135, vcc
	global_store_dword v[136:137], v129, off offset:128
	v_cndmask_b32_e64 v129, v38, v34, s[6:7]
	s_nop 1
	v_mov_b32_dpp v136, v129 quad_perm:[1,0,3,2] row_mask:0xf bank_mask:0xf bound_ctrl:1
	v_cndmask_b32_e64 v129, v38, v136, s[4:5]
; DEVFI float dpp_xor1(float x) { return __int_as_float(__builtin_amdgcn_update_dpp(0, __float_as_int(x), 0xB1, 0xF, 0xF, true)); }
; #define XBF ((bfraw*)(kargs()->ws + O_XBF))
; DEVFI void store_nat_m(bfraw* base, long ld, f32x4 (&a)[8], int fr) {
;   const bool odd = fr & 1;
;   bfraw* p0 = base + (odd ? 15 + fr : fr);
; #pragma unroll
;   for (int j = 0; j < 4; ++j)
; #pragma unroll
;     for (int n0 = 0; n0 < 8; n0 += 2) { const float own0 = a[n0][j], own1 = a[n0 + 1][j];
;       const float recv = dpp_xor1(odd ? own0 : own1);
;       const unsigned pk = odd ? cvtpk(recv, own1) : cvtpk(own0, recv);
;       *reinterpret_cast<unsigned*>(p0 + (long)j * ld + n0 * 16) = pk; }
; }
; __global__ void __launch_bounds__(512) mega(Params p) {
;     ...
;             if (u >= n_in && s != 0) store_nat(XBF + ((long)(s - 1) * T_SB + brow + wr0) * 1024 + bcol + wc0, 1024, acc, fr, fq);
	v_cndmask_b32_e64 v136, v136, v34, s[4:5]
	v_cvt_pk_bf16_f32 v129, v129, v136
	v_add_co_u32_e32 v136, vcc, 0x1000, v134
	s_nop 1
	v_addc_co_u32_e32 v137, vcc, 0, v135, vcc
	global_store_dword v[136:137], v129, off offset:192
	v_cndmask_b32_e64 v129, v63, v59, s[6:7]
	s_nop 1
	v_mov_b32_dpp v136, v129 quad_perm:[1,0,3,2] row_mask:0xf bank_mask:0xf bound_ctrl:1
	v_cndmask_b32_e64 v129, v63, v136, s[4:5]
	v_cndmask_b32_e64 v136, v136, v59, s[4:5]
	v_cvt_pk_bf16_f32 v129, v129, v136
	v_add_co_u32_e32 v136, vcc, 0x1000, v134
	s_nop 1
	v_addc_co_u32_e32 v137, vcc, 0, v135, vcc
	global_store_dword v[136:137], v129, off offset:2048
	v_cndmask_b32_e64 v129, v47, v43, s[6:7]
	s_nop 1
	v_mov_b32_dpp v136, v129 quad_perm:[1,0,3,2] row_mask:0xf bank_mask:0xf bound_ctrl:1
	v_cndmask_b32_e64 v129, v47, v136, s[4:5]
	v_cndmask_b32_e64 v136, v136, v43, s[4:5]
	v_cvt_pk_bf16_f32 v129, v129, v136
	v_add_co_u32_e32 v136, vcc, 0x1000, v134
	s_nop 1
	v_addc_co_u32_e32 v137, vcc, 0, v135, vcc
	global_store_dword v[136:137], v129, off offset:2112
	v_cndmask_b32_e64 v129, v55, v51, s[6:7]
	s_nop 1
	v_mov_b32_dpp v136, v129 quad_perm:[1,0,3,2] row_mask:0xf bank_mask:0xf bound_ctrl:1
	v_cndmask_b32_e64 v129, v55, v136, s[4:5]
	v_cndmask_b32_e64 v136, v136, v51, s[4:5]
	v_cvt_pk_bf16_f32 v129, v129, v136
	v_add_co_u32_e32 v136, vcc, 0x1000, v134
	s_nop 1
	v_addc_co_u32_e32 v137, vcc, 0, v135, vcc
	global_store_dword v[136:137], v129, off offset:2176
	v_cndmask_b32_e64 v129, v39, v35, s[6:7]
	s_nop 1
	v_mov_b32_dpp v136, v129 quad_perm:[1,0,3,2] row_mask:0xf bank_mask:0xf bound_ctrl:1
	v_cndmask_b32_e64 v129, v39, v136, s[4:5]
	v_cndmask_b32_e64 v136, v136, v35, s[4:5]
	v_cvt_pk_bf16_f32 v129, v129, v136
	v_add_co_u32_e32 v134, vcc, 0x1000, v134
	s_nop 1
	v_addc_co_u32_e32 v135, vcc, 0, v135, vcc
	global_store_dword v[134:135], v129, off offset:2240
	v_cndmask_b32_e64 v129, v28, v24, s[6:7]
	s_nop 1
	v_mov_b32_dpp v134, v129 quad_perm:[1,0,3,2] row_mask:0xf bank_mask:0xf bound_ctrl:1
	v_cndmask_b32_e64 v129, v28, v134, s[4:5]
	v_cndmask_b32_e64 v134, v134, v24, s[4:5]
	v_cvt_pk_bf16_f32 v129, v129, v134
	v_lshl_add_u64 v[130:131], v[130:131], 0, v[176:177]
	v_add_co_u32_e32 v134, vcc, 0x18000, v130
	s_nop 1
	v_addc_co_u32_e32 v135, vcc, 0, v131, vcc
	global_store_dword v[134:135], v129, off
	v_cndmask_b32_e64 v129, v12, v8, s[6:7]
	s_nop 1
	v_mov_b32_dpp v134, v129 quad_perm:[1,0,3,2] row_mask:0xf bank_mask:0xf bound_ctrl:1
	v_cndmask_b32_e64 v129, v12, v134, s[4:5]
	v_cndmask_b32_e64 v134, v134, v8, s[4:5]
	v_cvt_pk_bf16_f32 v129, v129, v134
	s_mov_b64 s[2:3], 0x18000
	v_lshl_add_u64 v[130:131], v[130:131], 0, s[2:3]
	global_store_dword v[130:131], v129, off offset:64
	v_cndmask_b32_e64 v129, v20, v16, s[6:7]
	s_nop 1
	v_mov_b32_dpp v134, v129 quad_perm:[1,0,3,2] row_mask:0xf bank_mask:0xf bound_ctrl:1
	v_cndmask_b32_e64 v129, v20, v134, s[4:5]
	v_cndmask_b32_e64 v134, v134, v16, s[4:5]
	v_cvt_pk_bf16_f32 v129, v129, v134
	global_store_dword v[130:131], v129, off offset:128
	v_cndmask_b32_e64 v129, v4, v0, s[6:7]
	s_nop 1
	v_mov_b32_dpp v134, v129 quad_perm:[1,0,3,2] row_mask:0xf bank_mask:0xf bound_ctrl:1
	v_cndmask_b32_e64 v129, v4, v134, s[4:5]
	v_cndmask_b32_e64 v134, v134, v0, s[4:5]
	v_cvt_pk_bf16_f32 v129, v129, v134
	global_store_dword v[130:131], v129, off offset:192
	v_cndmask_b32_e64 v129, v29, v25, s[6:7]
	s_nop 1
	v_mov_b32_dpp v134, v129 quad_perm:[1,0,3,2] row_mask:0xf bank_mask:0xf bound_ctrl:1
	v_cndmask_b32_e64 v129, v29, v134, s[4:5]
	v_cndmask_b32_e64 v134, v134, v25, s[4:5]
	v_cvt_pk_bf16_f32 v129, v129, v134
	global_store_dword v[130:131], v129, off offset:2048
	v_cndmask_b32_e64 v129, v13, v9, s[6:7]
	s_nop 1
	v_mov_b32_dpp v134, v129 quad_perm:[1,0,3,2] row_mask:0xf bank_mask:0xf bound_ctrl:1
	v_cndmask_b32_e64 v129, v13, v134, s[4:5]
	v_cndmask_b32_e64 v134, v134, v9, s[4:5]
	v_cvt_pk_bf16_f32 v129, v129, v134
; DEVFI float dpp_xor1(float x) { return __int_as_float(__builtin_amdgcn_update_dpp(0, __float_as_int(x), 0xB1, 0xF, 0xF, true)); }
; #define XBF ((bfraw*)(kargs()->ws + O_XBF))
; DEVFI void store_nat_m(bfraw* base, long ld, f32x4 (&a)[8], int fr) {
;   const bool odd = fr & 1;
;   bfraw* p0 = base + (odd ? 15 + fr : fr);
; #pragma unroll
;   for (int j = 0; j < 4; ++j)
; #pragma unroll
;     for (int n0 = 0; n0 < 8; n0 += 2) { const float own0 = a[n0][j], own1 = a[n0 + 1][j];
;       const float recv = dpp_xor1(odd ? own0 : own1);
;       const unsigned pk = odd ? cvtpk(recv, own1) : cvtpk(own0, recv);
;       *reinterpret_cast<unsigned*>(p0 + (long)j * ld + n0 * 16) = pk; }
; }
; __global__ void __launch_bounds__(512) mega(Params p) {
;     ...
;             if (u >= n_in && s != 0) store_nat(XBF + ((long)(s - 1) * T_SB + brow + wr0) * 1024 + bcol + wc0, 1024, acc, fr, fq);
	global_store_dword v[130:131], v129, off offset:2112
	v_cndmask_b32_e64 v129, v21, v17, s[6:7]
	s_nop 1
	v_mov_b32_dpp v134, v129 quad_perm:[1,0,3,2] row_mask:0xf bank_mask:0xf bound_ctrl:1
	v_cndmask_b32_e64 v129, v21, v134, s[4:5]
	v_cndmask_b32_e64 v134, v134, v17, s[4:5]
	v_cvt_pk_bf16_f32 v129, v129, v134
	global_store_dword v[130:131], v129, off offset:2176
	v_cndmask_b32_e64 v129, v5, v1, s[6:7]
	s_nop 1
	v_mov_b32_dpp v134, v129 quad_perm:[1,0,3,2] row_mask:0xf bank_mask:0xf bound_ctrl:1
	v_cndmask_b32_e64 v129, v5, v134, s[4:5]
	v_cndmask_b32_e64 v134, v134, v1, s[4:5]
	v_cvt_pk_bf16_f32 v129, v129, v134
	global_store_dword v[130:131], v129, off offset:2240
	v_cndmask_b32_e64 v129, v30, v26, s[6:7]
	s_nop 1
	v_mov_b32_dpp v134, v129 quad_perm:[1,0,3,2] row_mask:0xf bank_mask:0xf bound_ctrl:1
	v_cndmask_b32_e64 v129, v30, v134, s[4:5]
	v_cndmask_b32_e64 v134, v134, v26, s[4:5]
	v_cvt_pk_bf16_f32 v129, v129, v134
	v_add_co_u32_e32 v134, vcc, 0x1000, v130
	s_nop 1
	v_addc_co_u32_e32 v135, vcc, 0, v131, vcc
	global_store_dword v[134:135], v129, off
	v_cndmask_b32_e64 v129, v14, v10, s[6:7]
	s_nop 1
	v_mov_b32_dpp v134, v129 quad_perm:[1,0,3,2] row_mask:0xf bank_mask:0xf bound_ctrl:1
	v_cndmask_b32_e64 v129, v14, v134, s[4:5]
	v_cndmask_b32_e64 v134, v134, v10, s[4:5]
	v_cvt_pk_bf16_f32 v129, v129, v134
	v_add_co_u32_e32 v134, vcc, 0x1000, v130
	s_nop 1
	v_addc_co_u32_e32 v135, vcc, 0, v131, vcc
	global_store_dword v[134:135], v129, off offset:64
	v_cndmask_b32_e64 v129, v22, v18, s[6:7]
	s_nop 1
	v_mov_b32_dpp v134, v129 quad_perm:[1,0,3,2] row_mask:0xf bank_mask:0xf bound_ctrl:1
	v_cndmask_b32_e64 v129, v22, v134, s[4:5]
	v_cndmask_b32_e64 v134, v134, v18, s[4:5]
	v_cvt_pk_bf16_f32 v129, v129, v134
	v_add_co_u32_e32 v134, vcc, 0x1000, v130
	s_nop 1
	v_addc_co_u32_e32 v135, vcc, 0, v131, vcc
	global_store_dword v[134:135], v129, off offset:128
	v_cndmask_b32_e64 v129, v6, v2, s[6:7]
	s_nop 1
	v_mov_b32_dpp v134, v129 quad_perm:[1,0,3,2] row_mask:0xf bank_mask:0xf bound_ctrl:1
	v_cndmask_b32_e64 v129, v6, v134, s[4:5]
	v_cndmask_b32_e64 v134, v134, v2, s[4:5]
	v_cvt_pk_bf16_f32 v129, v129, v134
	v_add_co_u32_e32 v134, vcc, 0x1000, v130
	s_nop 1
	v_addc_co_u32_e32 v135, vcc, 0, v131, vcc
	global_store_dword v[134:135], v129, off offset:192
	v_cndmask_b32_e64 v129, v31, v27, s[6:7]
	s_nop 1
	v_mov_b32_dpp v134, v129 quad_perm:[1,0,3,2] row_mask:0xf bank_mask:0xf bound_ctrl:1
	v_cndmask_b32_e64 v129, v31, v134, s[4:5]
	v_cndmask_b32_e64 v134, v134, v27, s[4:5]
	v_cvt_pk_bf16_f32 v129, v129, v134
	v_add_co_u32_e32 v134, vcc, 0x1000, v130
	s_nop 1
	v_addc_co_u32_e32 v135, vcc, 0, v131, vcc
	global_store_dword v[134:135], v129, off offset:2048
	v_cndmask_b32_e64 v129, v15, v11, s[6:7]
	s_nop 1
	v_mov_b32_dpp v134, v129 quad_perm:[1,0,3,2] row_mask:0xf bank_mask:0xf bound_ctrl:1
	v_cndmask_b32_e64 v129, v15, v134, s[4:5]
	v_cndmask_b32_e64 v134, v134, v11, s[4:5]
	v_cvt_pk_bf16_f32 v129, v129, v134
	v_add_co_u32_e32 v134, vcc, 0x1000, v130
	s_nop 1
	v_addc_co_u32_e32 v135, vcc, 0, v131, vcc
	global_store_dword v[134:135], v129, off offset:2112
	v_cndmask_b32_e64 v129, v23, v19, s[6:7]
	s_nop 1
	v_mov_b32_dpp v134, v129 quad_perm:[1,0,3,2] row_mask:0xf bank_mask:0xf bound_ctrl:1
	v_cndmask_b32_e64 v129, v23, v134, s[4:5]
	v_cndmask_b32_e64 v134, v134, v19, s[4:5]
	v_cvt_pk_bf16_f32 v129, v129, v134
	v_add_co_u32_e32 v134, vcc, 0x1000, v130
	s_nop 1
	v_addc_co_u32_e32 v135, vcc, 0, v131, vcc
	global_store_dword v[134:135], v129, off offset:2176
	v_cndmask_b32_e64 v129, v7, v3, s[6:7]
	s_nop 1
	v_mov_b32_dpp v134, v129 quad_perm:[1,0,3,2] row_mask:0xf bank_mask:0xf bound_ctrl:1
	v_cndmask_b32_e64 v129, v7, v134, s[4:5]
	v_cndmask_b32_e64 v134, v134, v3, s[4:5]
	v_cvt_pk_bf16_f32 v129, v129, v134
	v_add_co_u32_e32 v130, vcc, 0x1000, v130
	s_nop 1
	v_addc_co_u32_e32 v131, vcc, 0, v131, vcc
	global_store_dword v[130:131], v129, off offset:2240
	s_mov_b64 s[2:3], 0

; DEVFI float dpp_xor1(float x) { return __int_as_float(__builtin_amdgcn_update_dpp(0, __float_as_int(x), 0xB1, 0xF, 0xF, true)); }
; #define KM ((bfraw*)(kargs()->ws + O_KM))
; DEVFI void store_nat_m(bfraw* base, long ld, f32x4 (&a)[8], int fr) {
;   const bool odd = fr & 1;
;   bfraw* p0 = base + (odd ? 15 + fr : fr);
; #pragma unroll
;   for (int j = 0; j < 4; ++j)
; #pragma unroll
;     for (int n0 = 0; n0 < 8; n0 += 2) { const float own0 = a[n0][j], own1 = a[n0 + 1][j];
;       const float recv = dpp_xor1(odd ? own0 : own1);
;       const unsigned pk = odd ? cvtpk(recv, own1) : cvtpk(own0, recv);
;       *reinterpret_cast<unsigned*>(p0 + (long)j * ld + n0 * 16) = pk; }
; }
; __global__ void __launch_bounds__(512) mega(Params p) {
;     ...
;                 if (c0 < 1024) store_nat(KM + (long)r0 * 1024 + c0, 1024, acc, fr, fq);
.LBB0_412:
	s_andn2_saveexec_b64 s[8:9], s[2:3]
	s_cbranch_execz .LBB0_670
	s_mov_b64 s[2:3], s[0:1]
	s_load_dwordx2 s[2:3], s[2:3], 0xe8
	v_and_b32_e32 v129, 1, v203
	v_cmp_eq_u32_e64 s[6:7], 0, v129
	v_cmp_eq_u32_e64 s[4:5], 1, v129
	s_nop 0
	v_cndmask_b32_e64 v129, v124, v120, s[6:7]
	s_nop 1
	v_mov_b32_dpp v131, v129 quad_perm:[1,0,3,2] row_mask:0xf bank_mask:0xf bound_ctrl:1
	v_cndmask_b32_e64 v129, v124, v131, s[4:5]
	v_cndmask_b32_e64 v131, v131, v120, s[4:5]
	v_cvt_pk_bf16_f32 v129, v129, v131
	v_ashrrev_i32_e32 v131, 31, v130
	v_lshlrev_b64 v[130:131], 11, v[130:131]
	s_waitcnt lgkmcnt(0)
	v_lshl_add_u64 v[130:131], s[2:3], 0, v[130:131]
	v_ashrrev_i32_e32 v135, 31, v176
	v_mov_b32_e32 v134, v176
	v_lshl_add_u64 v[130:131], v[134:135], 1, v[130:131]
	v_lshlrev_b32_e32 v134, 13, v147
	v_mov_b32_e32 v135, v177
	v_add_u32_e32 v133, 15, v202
	v_lshl_add_u64 v[130:131], v[130:131], 0, v[134:135]
	s_mov_b64 s[2:3], 0x5620000
	v_cndmask_b32_e64 v133, v133, v202, s[6:7]
	v_lshl_add_u64 v[130:131], v[130:131], 0, s[2:3]
	v_lshlrev_b32_e32 v134, 1, v133
	v_lshl_add_u64 v[136:137], v[130:131], 0, v[134:135]
	global_store_dword v[136:137], v129, off
	v_cndmask_b32_e64 v129, v108, v104, s[6:7]
	s_nop 1
	v_mov_b32_dpp v133, v129 quad_perm:[1,0,3,2] row_mask:0xf bank_mask:0xf bound_ctrl:1
	v_cndmask_b32_e64 v129, v108, v133, s[4:5]
	v_cndmask_b32_e64 v133, v133, v104, s[4:5]
	v_cvt_pk_bf16_f32 v129, v129, v133
	global_store_dword v[136:137], v129, off offset:64
	v_cndmask_b32_e64 v129, v116, v112, s[6:7]
	s_nop 1
	v_mov_b32_dpp v133, v129 quad_perm:[1,0,3,2] row_mask:0xf bank_mask:0xf bound_ctrl:1
	v_cndmask_b32_e64 v129, v116, v133, s[4:5]
	v_cndmask_b32_e64 v133, v133, v112, s[4:5]
	v_cvt_pk_bf16_f32 v129, v129, v133
	global_store_dword v[136:137], v129, off offset:128
	v_cndmask_b32_e64 v129, v100, v96, s[6:7]
	s_nop 1
	v_mov_b32_dpp v133, v129 quad_perm:[1,0,3,2] row_mask:0xf bank_mask:0xf bound_ctrl:1
	v_cndmask_b32_e64 v129, v100, v133, s[4:5]
	v_cndmask_b32_e64 v133, v133, v96, s[4:5]
	v_cvt_pk_bf16_f32 v129, v129, v133
	global_store_dword v[136:137], v129, off offset:192
	v_cndmask_b32_e64 v129, v125, v121, s[6:7]
	s_nop 1
	v_mov_b32_dpp v133, v129 quad_perm:[1,0,3,2] row_mask:0xf bank_mask:0xf bound_ctrl:1
	v_cndmask_b32_e64 v129, v125, v133, s[4:5]
	v_cndmask_b32_e64 v133, v133, v121, s[4:5]
	v_cvt_pk_bf16_f32 v129, v129, v133
	global_store_dword v[136:137], v129, off offset:2048
	v_cndmask_b32_e64 v129, v109, v105, s[6:7]
	s_nop 1
	v_mov_b32_dpp v133, v129 quad_perm:[1,0,3,2] row_mask:0xf bank_mask:0xf bound_ctrl:1
	v_cndmask_b32_e64 v129, v109, v133, s[4:5]
	v_cndmask_b32_e64 v133, v133, v105, s[4:5]
	v_cvt_pk_bf16_f32 v129, v129, v133
	global_store_dword v[136:137], v129, off offset:2112
	v_cndmask_b32_e64 v129, v117, v113, s[6:7]
	s_nop 1
	v_mov_b32_dpp v133, v129 quad_perm:[1,0,3,2] row_mask:0xf bank_mask:0xf bound_ctrl:1
	v_cndmask_b32_e64 v129, v117, v133, s[4:5]
	v_cndmask_b32_e64 v133, v133, v113, s[4:5]
	v_cvt_pk_bf16_f32 v129, v129, v133
	global_store_dword v[136:137], v129, off offset:2176
	v_cndmask_b32_e64 v129, v101, v97, s[6:7]
	s_nop 1
	v_mov_b32_dpp v133, v129 quad_perm:[1,0,3,2] row_mask:0xf bank_mask:0xf bound_ctrl:1
	v_cndmask_b32_e64 v129, v101, v133, s[4:5]
	v_cndmask_b32_e64 v133, v133, v97, s[4:5]
	v_cvt_pk_bf16_f32 v129, v129, v133
	global_store_dword v[136:137], v129, off offset:2240
	v_cndmask_b32_e64 v129, v126, v122, s[6:7]
	s_nop 1
	v_mov_b32_dpp v133, v129 quad_perm:[1,0,3,2] row_mask:0xf bank_mask:0xf bound_ctrl:1
	v_cndmask_b32_e64 v129, v126, v133, s[4:5]
	v_cndmask_b32_e64 v133, v133, v122, s[4:5]
	v_cvt_pk_bf16_f32 v129, v129, v133
	v_add_co_u32_e32 v138, vcc, 0x1000, v136
	s_nop 1
	v_addc_co_u32_e32 v139, vcc, 0, v137, vcc
	global_store_dword v[138:139], v129, off
	v_cndmask_b32_e64 v129, v110, v106, s[6:7]
	s_nop 1
	v_mov_b32_dpp v133, v129 quad_perm:[1,0,3,2] row_mask:0xf bank_mask:0xf bound_ctrl:1
	v_cndmask_b32_e64 v129, v110, v133, s[4:5]
	v_cndmask_b32_e64 v133, v133, v106, s[4:5]
	v_cvt_pk_bf16_f32 v129, v129, v133
	v_add_co_u32_e32 v138, vcc, 0x1000, v136
	s_nop 1
	v_addc_co_u32_e32 v139, vcc, 0, v137, vcc
	global_store_dword v[138:139], v129, off offset:64
	v_cndmask_b32_e64 v129, v118, v114, s[6:7]
	s_nop 1
	v_mov_b32_dpp v133, v129 quad_perm:[1,0,3,2] row_mask:0xf bank_mask:0xf bound_ctrl:1
	v_cndmask_b32_e64 v129, v118, v133, s[4:5]
	v_cndmask_b32_e64 v133, v133, v114, s[4:5]
	v_cvt_pk_bf16_f32 v129, v129, v133
	v_add_co_u32_e32 v138, vcc, 0x1000, v136
	s_nop 1
	v_addc_co_u32_e32 v139, vcc, 0, v137, vcc
	global_store_dword v[138:139], v129, off offset:128
	v_cndmask_b32_e64 v129, v102, v98, s[6:7]
	s_nop 1
	v_mov_b32_dpp v133, v129 quad_perm:[1,0,3,2] row_mask:0xf bank_mask:0xf bound_ctrl:1
	v_cndmask_b32_e64 v129, v102, v133, s[4:5]
	v_cndmask_b32_e64 v133, v133, v98, s[4:5]
	v_cvt_pk_bf16_f32 v129, v129, v133
	v_add_co_u32_e32 v138, vcc, 0x1000, v136
	s_nop 1
	v_addc_co_u32_e32 v139, vcc, 0, v137, vcc
	global_store_dword v[138:139], v129, off offset:192
	v_cndmask_b32_e64 v129, v127, v123, s[6:7]
	s_nop 1
	v_mov_b32_dpp v133, v129 quad_perm:[1,0,3,2] row_mask:0xf bank_mask:0xf bound_ctrl:1
	v_cndmask_b32_e64 v129, v127, v133, s[4:5]
	v_cndmask_b32_e64 v133, v133, v123, s[4:5]
	v_cvt_pk_bf16_f32 v129, v129, v133
	v_add_co_u32_e32 v138, vcc, 0x1000, v136
	s_nop 1
	v_addc_co_u32_e32 v139, vcc, 0, v137, vcc
	global_store_dword v[138:139], v129, off offset:2048
	v_cndmask_b32_e64 v129, v111, v107, s[6:7]
	s_nop 1
	v_mov_b32_dpp v133, v129 quad_perm:[1,0,3,2] row_mask:0xf bank_mask:0xf bound_ctrl:1
	v_cndmask_b32_e64 v129, v111, v133, s[4:5]
	v_cndmask_b32_e64 v133, v133, v107, s[4:5]
; DEVFI float dpp_xor1(float x) { return __int_as_float(__builtin_amdgcn_update_dpp(0, __float_as_int(x), 0xB1, 0xF, 0xF, true)); }
; #define KM ((bfraw*)(kargs()->ws + O_KM))
; DEVFI void store_nat_m(bfraw* base, long ld, f32x4 (&a)[8], int fr) {
;   const bool odd = fr & 1;
;   bfraw* p0 = base + (odd ? 15 + fr : fr);
; #pragma unroll
;   for (int j = 0; j < 4; ++j)
; #pragma unroll
;     for (int n0 = 0; n0 < 8; n0 += 2) { const float own0 = a[n0][j], own1 = a[n0 + 1][j];
;       const float recv = dpp_xor1(odd ? own0 : own1);
;       const unsigned pk = odd ? cvtpk(recv, own1) : cvtpk(own0, recv);
;       *reinterpret_cast<unsigned*>(p0 + (long)j * ld + n0 * 16) = pk; }
; }
; __global__ void __launch_bounds__(512) mega(Params p) {
;     ...
;                 if (c0 < 1024) store_nat(KM + (long)r0 * 1024 + c0, 1024, acc, fr, fq);
	v_cvt_pk_bf16_f32 v129, v129, v133
	v_add_co_u32_e32 v138, vcc, 0x1000, v136
	s_nop 1
	v_addc_co_u32_e32 v139, vcc, 0, v137, vcc
	global_store_dword v[138:139], v129, off offset:2112
	v_cndmask_b32_e64 v129, v119, v115, s[6:7]
	s_nop 1
	v_mov_b32_dpp v133, v129 quad_perm:[1,0,3,2] row_mask:0xf bank_mask:0xf bound_ctrl:1
	v_cndmask_b32_e64 v129, v119, v133, s[4:5]
	v_cndmask_b32_e64 v133, v133, v115, s[4:5]
	v_cvt_pk_bf16_f32 v129, v129, v133
	v_add_co_u32_e32 v138, vcc, 0x1000, v136
	s_nop 1
	v_addc_co_u32_e32 v139, vcc, 0, v137, vcc
	global_store_dword v[138:139], v129, off offset:2176
	v_cndmask_b32_e64 v129, v103, v99, s[6:7]
	s_nop 1
	v_mov_b32_dpp v133, v129 quad_perm:[1,0,3,2] row_mask:0xf bank_mask:0xf bound_ctrl:1
	v_cndmask_b32_e64 v129, v103, v133, s[4:5]
	v_cndmask_b32_e64 v133, v133, v99, s[4:5]
	v_cvt_pk_bf16_f32 v129, v129, v133
	v_add_co_u32_e32 v136, vcc, 0x1000, v136
	s_nop 1
	v_addc_co_u32_e32 v137, vcc, 0, v137, vcc
	global_store_dword v[136:137], v129, off offset:2240
	v_cndmask_b32_e64 v129, v92, v88, s[6:7]
	s_nop 1
	v_mov_b32_dpp v133, v129 quad_perm:[1,0,3,2] row_mask:0xf bank_mask:0xf bound_ctrl:1
	v_cndmask_b32_e64 v129, v92, v133, s[4:5]
	v_cndmask_b32_e64 v133, v133, v88, s[4:5]
	v_cvt_pk_bf16_f32 v129, v129, v133
	v_mov_b32_e32 v135, v177
	v_lshl_add_u64 v[136:137], v[130:131], 0, v[134:135]
	v_add_co_u32_e32 v138, vcc, 0x8000, v136
	s_nop 1
	v_addc_co_u32_e32 v139, vcc, 0, v137, vcc
	global_store_dword v[138:139], v129, off
	v_cndmask_b32_e64 v129, v76, v72, s[6:7]
	s_nop 1
	v_mov_b32_dpp v133, v129 quad_perm:[1,0,3,2] row_mask:0xf bank_mask:0xf bound_ctrl:1
	v_cndmask_b32_e64 v129, v76, v133, s[4:5]
	v_cndmask_b32_e64 v133, v133, v72, s[4:5]
	v_cvt_pk_bf16_f32 v129, v129, v133
	s_mov_b64 s[2:3], 0x8000
	v_lshl_add_u64 v[136:137], v[136:137], 0, s[2:3]
	global_store_dword v[136:137], v129, off offset:64
	v_cndmask_b32_e64 v129, v84, v80, s[6:7]
	s_nop 1
	v_mov_b32_dpp v133, v129 quad_perm:[1,0,3,2] row_mask:0xf bank_mask:0xf bound_ctrl:1
	v_cndmask_b32_e64 v129, v84, v133, s[4:5]
	v_cndmask_b32_e64 v133, v133, v80, s[4:5]
	v_cvt_pk_bf16_f32 v129, v129, v133
	global_store_dword v[136:137], v129, off offset:128
	v_cndmask_b32_e64 v129, v68, v64, s[6:7]
	s_nop 1
	v_mov_b32_dpp v133, v129 quad_perm:[1,0,3,2] row_mask:0xf bank_mask:0xf bound_ctrl:1
	v_cndmask_b32_e64 v129, v68, v133, s[4:5]
	v_cndmask_b32_e64 v133, v133, v64, s[4:5]
	v_cvt_pk_bf16_f32 v129, v129, v133
	global_store_dword v[136:137], v129, off offset:192
	v_cndmask_b32_e64 v129, v93, v89, s[6:7]
	s_nop 1
	v_mov_b32_dpp v133, v129 quad_perm:[1,0,3,2] row_mask:0xf bank_mask:0xf bound_ctrl:1
	v_cndmask_b32_e64 v129, v93, v133, s[4:5]
	v_cndmask_b32_e64 v133, v133, v89, s[4:5]
	v_cvt_pk_bf16_f32 v129, v129, v133
	global_store_dword v[136:137], v129, off offset:2048
	v_cndmask_b32_e64 v129, v77, v73, s[6:7]
	s_nop 1
	v_mov_b32_dpp v133, v129 quad_perm:[1,0,3,2] row_mask:0xf bank_mask:0xf bound_ctrl:1
	v_cndmask_b32_e64 v129, v77, v133, s[4:5]
	v_cndmask_b32_e64 v133, v133, v73, s[4:5]
	v_cvt_pk_bf16_f32 v129, v129, v133
	global_store_dword v[136:137], v129, off offset:2112
	v_cndmask_b32_e64 v129, v85, v81, s[6:7]
	s_nop 1
	v_mov_b32_dpp v133, v129 quad_perm:[1,0,3,2] row_mask:0xf bank_mask:0xf bound_ctrl:1
	v_cndmask_b32_e64 v129, v85, v133, s[4:5]
	v_cndmask_b32_e64 v133, v133, v81, s[4:5]
	v_cvt_pk_bf16_f32 v129, v129, v133
	global_store_dword v[136:137], v129, off offset:2176
	v_cndmask_b32_e64 v129, v69, v65, s[6:7]
	s_nop 1
	v_mov_b32_dpp v133, v129 quad_perm:[1,0,3,2] row_mask:0xf bank_mask:0xf bound_ctrl:1
	v_cndmask_b32_e64 v129, v69, v133, s[4:5]
	v_cndmask_b32_e64 v133, v133, v65, s[4:5]
	v_cvt_pk_bf16_f32 v129, v129, v133
	global_store_dword v[136:137], v129, off offset:2240
	v_cndmask_b32_e64 v129, v94, v90, s[6:7]
	s_nop 1
	v_mov_b32_dpp v133, v129 quad_perm:[1,0,3,2] row_mask:0xf bank_mask:0xf bound_ctrl:1
	v_cndmask_b32_e64 v129, v94, v133, s[4:5]
	v_cndmask_b32_e64 v133, v133, v90, s[4:5]
	v_cvt_pk_bf16_f32 v129, v129, v133
	v_add_co_u32_e32 v138, vcc, 0x1000, v136
	s_nop 1
	v_addc_co_u32_e32 v139, vcc, 0, v137, vcc
	global_store_dword v[138:139], v129, off
	v_cndmask_b32_e64 v129, v78, v74, s[6:7]
	s_nop 1
	v_mov_b32_dpp v133, v129 quad_perm:[1,0,3,2] row_mask:0xf bank_mask:0xf bound_ctrl:1
	v_cndmask_b32_e64 v129, v78, v133, s[4:5]
	v_cndmask_b32_e64 v133, v133, v74, s[4:5]
	v_cvt_pk_bf16_f32 v129, v129, v133
	v_add_co_u32_e32 v138, vcc, 0x1000, v136
	s_nop 1
	v_addc_co_u32_e32 v139, vcc, 0, v137, vcc
	global_store_dword v[138:139], v129, off offset:64
	v_cndmask_b32_e64 v129, v86, v82, s[6:7]
	s_nop 1
	v_mov_b32_dpp v133, v129 quad_perm:[1,0,3,2] row_mask:0xf bank_mask:0xf bound_ctrl:1
	v_cndmask_b32_e64 v129, v86, v133, s[4:5]
	v_cndmask_b32_e64 v133, v133, v82, s[4:5]
	v_cvt_pk_bf16_f32 v129, v129, v133
	v_add_co_u32_e32 v138, vcc, 0x1000, v136
	s_nop 1
	v_addc_co_u32_e32 v139, vcc, 0, v137, vcc
	global_store_dword v[138:139], v129, off offset:128
	v_cndmask_b32_e64 v129, v70, v66, s[6:7]
	s_nop 1
	v_mov_b32_dpp v133, v129 quad_perm:[1,0,3,2] row_mask:0xf bank_mask:0xf bound_ctrl:1
	v_cndmask_b32_e64 v129, v70, v133, s[4:5]
	v_cndmask_b32_e64 v133, v133, v66, s[4:5]
	v_cvt_pk_bf16_f32 v129, v129, v133
	v_add_co_u32_e32 v138, vcc, 0x1000, v136
	s_nop 1
	v_addc_co_u32_e32 v139, vcc, 0, v137, vcc
	global_store_dword v[138:139], v129, off offset:192
	v_cndmask_b32_e64 v129, v95, v91, s[6:7]
	s_nop 1
	v_mov_b32_dpp v133, v129 quad_perm:[1,0,3,2] row_mask:0xf bank_mask:0xf bound_ctrl:1
	v_cndmask_b32_e64 v129, v95, v133, s[4:5]
	v_cndmask_b32_e64 v133, v133, v91, s[4:5]
	v_cvt_pk_bf16_f32 v129, v129, v133
	v_add_co_u32_e32 v138, vcc, 0x1000, v136
; DEVFI float dpp_xor1(float x) { return __int_as_float(__builtin_amdgcn_update_dpp(0, __float_as_int(x), 0xB1, 0xF, 0xF, true)); }
; #define KM ((bfraw*)(kargs()->ws + O_KM))
; DEVFI void store_nat_m(bfraw* base, long ld, f32x4 (&a)[8], int fr) {
;   const bool odd = fr & 1;
;   bfraw* p0 = base + (odd ? 15 + fr : fr);
; #pragma unroll
;   for (int j = 0; j < 4; ++j)
; #pragma unroll
;     for (int n0 = 0; n0 < 8; n0 += 2) { const float own0 = a[n0][j], own1 = a[n0 + 1][j];
;       const float recv = dpp_xor1(odd ? own0 : own1);
;       const unsigned pk = odd ? cvtpk(recv, own1) : cvtpk(own0, recv);
;       *reinterpret_cast<unsigned*>(p0 + (long)j * ld + n0 * 16) = pk; }
; }
; __global__ void __launch_bounds__(512) mega(Params p) {
;     ...
;                 if (c0 < 1024) store_nat(KM + (long)r0 * 1024 + c0, 1024, acc, fr, fq);
	s_nop 1
	v_addc_co_u32_e32 v139, vcc, 0, v137, vcc
	global_store_dword v[138:139], v129, off offset:2048
	v_cndmask_b32_e64 v129, v79, v75, s[6:7]
	s_nop 1
	v_mov_b32_dpp v133, v129 quad_perm:[1,0,3,2] row_mask:0xf bank_mask:0xf bound_ctrl:1
	v_cndmask_b32_e64 v129, v79, v133, s[4:5]
	v_cndmask_b32_e64 v133, v133, v75, s[4:5]
	v_cvt_pk_bf16_f32 v129, v129, v133
	v_add_co_u32_e32 v138, vcc, 0x1000, v136
	s_nop 1
	v_addc_co_u32_e32 v139, vcc, 0, v137, vcc
	global_store_dword v[138:139], v129, off offset:2112
	v_cndmask_b32_e64 v129, v87, v83, s[6:7]
	s_nop 1
	v_mov_b32_dpp v133, v129 quad_perm:[1,0,3,2] row_mask:0xf bank_mask:0xf bound_ctrl:1
	v_cndmask_b32_e64 v129, v87, v133, s[4:5]
	v_cndmask_b32_e64 v133, v133, v83, s[4:5]
	v_cvt_pk_bf16_f32 v129, v129, v133
	v_add_co_u32_e32 v138, vcc, 0x1000, v136
	s_nop 1
	v_addc_co_u32_e32 v139, vcc, 0, v137, vcc
	global_store_dword v[138:139], v129, off offset:2176
	v_cndmask_b32_e64 v129, v71, v67, s[6:7]
	s_nop 1
	v_mov_b32_dpp v133, v129 quad_perm:[1,0,3,2] row_mask:0xf bank_mask:0xf bound_ctrl:1
	v_cndmask_b32_e64 v129, v71, v133, s[4:5]
	v_cndmask_b32_e64 v133, v133, v67, s[4:5]
	v_cvt_pk_bf16_f32 v129, v129, v133
	v_add_co_u32_e32 v136, vcc, 0x1000, v136
	s_nop 1
	v_addc_co_u32_e32 v137, vcc, 0, v137, vcc
	global_store_dword v[136:137], v129, off offset:2240
	v_cndmask_b32_e64 v129, v60, v56, s[6:7]
	s_nop 1
	v_mov_b32_dpp v133, v129 quad_perm:[1,0,3,2] row_mask:0xf bank_mask:0xf bound_ctrl:1
	v_cndmask_b32_e64 v129, v60, v133, s[4:5]
	v_cndmask_b32_e64 v133, v133, v56, s[4:5]
	v_cvt_pk_bf16_f32 v129, v129, v133
	v_mov_b32_e32 v135, v177
	v_lshl_add_u64 v[136:137], v[130:131], 0, v[134:135]
	v_add_co_u32_e32 v138, vcc, 0x10000, v136
	s_nop 1
	v_addc_co_u32_e32 v139, vcc, 0, v137, vcc
	global_store_dword v[138:139], v129, off
	v_cndmask_b32_e64 v129, v44, v40, s[6:7]
	s_nop 1
	v_mov_b32_dpp v133, v129 quad_perm:[1,0,3,2] row_mask:0xf bank_mask:0xf bound_ctrl:1
	v_cndmask_b32_e64 v129, v44, v133, s[4:5]
	v_cndmask_b32_e64 v133, v133, v40, s[4:5]
	v_cvt_pk_bf16_f32 v129, v129, v133
	v_lshl_add_u64 v[136:137], v[136:137], 0, s[48:49]
	global_store_dword v[136:137], v129, off offset:64
	v_cndmask_b32_e64 v129, v52, v48, s[6:7]
	s_nop 1
	v_mov_b32_dpp v133, v129 quad_perm:[1,0,3,2] row_mask:0xf bank_mask:0xf bound_ctrl:1
	v_cndmask_b32_e64 v129, v52, v133, s[4:5]
	v_cndmask_b32_e64 v133, v133, v48, s[4:5]
	v_cvt_pk_bf16_f32 v129, v129, v133
	global_store_dword v[136:137], v129, off offset:128
	v_cndmask_b32_e64 v129, v36, v32, s[6:7]
	s_nop 1
	v_mov_b32_dpp v133, v129 quad_perm:[1,0,3,2] row_mask:0xf bank_mask:0xf bound_ctrl:1
	v_cndmask_b32_e64 v129, v36, v133, s[4:5]
	v_cndmask_b32_e64 v133, v133, v32, s[4:5]
	v_cvt_pk_bf16_f32 v129, v129, v133
	global_store_dword v[136:137], v129, off offset:192
	v_cndmask_b32_e64 v129, v61, v57, s[6:7]
	s_nop 1
	v_mov_b32_dpp v133, v129 quad_perm:[1,0,3,2] row_mask:0xf bank_mask:0xf bound_ctrl:1
	v_cndmask_b32_e64 v129, v61, v133, s[4:5]
	v_cndmask_b32_e64 v133, v133, v57, s[4:5]
	v_cvt_pk_bf16_f32 v129, v129, v133
	global_store_dword v[136:137], v129, off offset:2048
	v_cndmask_b32_e64 v129, v45, v41, s[6:7]
	s_nop 1
	v_mov_b32_dpp v133, v129 quad_perm:[1,0,3,2] row_mask:0xf bank_mask:0xf bound_ctrl:1
	v_cndmask_b32_e64 v129, v45, v133, s[4:5]
	v_cndmask_b32_e64 v133, v133, v41, s[4:5]
	v_cvt_pk_bf16_f32 v129, v129, v133
	global_store_dword v[136:137], v129, off offset:2112
	v_cndmask_b32_e64 v129, v53, v49, s[6:7]
	s_nop 1
	v_mov_b32_dpp v133, v129 quad_perm:[1,0,3,2] row_mask:0xf bank_mask:0xf bound_ctrl:1
	v_cndmask_b32_e64 v129, v53, v133, s[4:5]
	v_cndmask_b32_e64 v133, v133, v49, s[4:5]
	v_cvt_pk_bf16_f32 v129, v129, v133
	global_store_dword v[136:137], v129, off offset:2176
	v_cndmask_b32_e64 v129, v37, v33, s[6:7]
	s_nop 1
	v_mov_b32_dpp v133, v129 quad_perm:[1,0,3,2] row_mask:0xf bank_mask:0xf bound_ctrl:1
	v_cndmask_b32_e64 v129, v37, v133, s[4:5]
	v_cndmask_b32_e64 v133, v133, v33, s[4:5]
	v_cvt_pk_bf16_f32 v129, v129, v133
	global_store_dword v[136:137], v129, off offset:2240
	v_cndmask_b32_e64 v129, v62, v58, s[6:7]
	s_nop 1
	v_mov_b32_dpp v133, v129 quad_perm:[1,0,3,2] row_mask:0xf bank_mask:0xf bound_ctrl:1
	v_cndmask_b32_e64 v129, v62, v133, s[4:5]
	v_cndmask_b32_e64 v133, v133, v58, s[4:5]
	v_cvt_pk_bf16_f32 v129, v129, v133
	v_add_co_u32_e32 v138, vcc, 0x1000, v136
	s_nop 1
	v_addc_co_u32_e32 v139, vcc, 0, v137, vcc
	global_store_dword v[138:139], v129, off
	v_cndmask_b32_e64 v129, v46, v42, s[6:7]
	s_nop 1
	v_mov_b32_dpp v133, v129 quad_perm:[1,0,3,2] row_mask:0xf bank_mask:0xf bound_ctrl:1
	v_cndmask_b32_e64 v129, v46, v133, s[4:5]
	v_cndmask_b32_e64 v133, v133, v42, s[4:5]
	v_cvt_pk_bf16_f32 v129, v129, v133
	v_add_co_u32_e32 v138, vcc, 0x1000, v136
	s_nop 1
	v_addc_co_u32_e32 v139, vcc, 0, v137, vcc
	global_store_dword v[138:139], v129, off offset:64
	v_cndmask_b32_e64 v129, v54, v50, s[6:7]
	s_nop 1
	v_mov_b32_dpp v133, v129 quad_perm:[1,0,3,2] row_mask:0xf bank_mask:0xf bound_ctrl:1
	v_cndmask_b32_e64 v129, v54, v133, s[4:5]
	v_cndmask_b32_e64 v133, v133, v50, s[4:5]
	v_cvt_pk_bf16_f32 v129, v129, v133
	v_add_co_u32_e32 v138, vcc, 0x1000, v136
	s_nop 1
	v_addc_co_u32_e32 v139, vcc, 0, v137, vcc
	global_store_dword v[138:139], v129, off offset:128
	v_cndmask_b32_e64 v129, v38, v34, s[6:7]
	s_nop 1
	v_mov_b32_dpp v133, v129 quad_perm:[1,0,3,2] row_mask:0xf bank_mask:0xf bound_ctrl:1
	v_cndmask_b32_e64 v129, v38, v133, s[4:5]
	v_cndmask_b32_e64 v133, v133, v34, s[4:5]
	v_cvt_pk_bf16_f32 v129, v129, v133
	v_add_co_u32_e32 v138, vcc, 0x1000, v136
	s_nop 1
	v_addc_co_u32_e32 v139, vcc, 0, v137, vcc
	global_store_dword v[138:139], v129, off offset:192
; DEVFI float dpp_xor1(float x) { return __int_as_float(__builtin_amdgcn_update_dpp(0, __float_as_int(x), 0xB1, 0xF, 0xF, true)); }
; #define KM ((bfraw*)(kargs()->ws + O_KM))
; DEVFI void store_nat_m(bfraw* base, long ld, f32x4 (&a)[8], int fr) {
;   const bool odd = fr & 1;
;   bfraw* p0 = base + (odd ? 15 + fr : fr);
; #pragma unroll
;   for (int j = 0; j < 4; ++j)
; #pragma unroll
;     for (int n0 = 0; n0 < 8; n0 += 2) { const float own0 = a[n0][j], own1 = a[n0 + 1][j];
;       const float recv = dpp_xor1(odd ? own0 : own1);
;       const unsigned pk = odd ? cvtpk(recv, own1) : cvtpk(own0, recv);
;       *reinterpret_cast<unsigned*>(p0 + (long)j * ld + n0 * 16) = pk; }
; }
; __global__ void __launch_bounds__(512) mega(Params p) {
;     ...
;                 if (c0 < 1024) store_nat(KM + (long)r0 * 1024 + c0, 1024, acc, fr, fq);
	v_cndmask_b32_e64 v129, v63, v59, s[6:7]
	s_nop 1
	v_mov_b32_dpp v133, v129 quad_perm:[1,0,3,2] row_mask:0xf bank_mask:0xf bound_ctrl:1
	v_cndmask_b32_e64 v129, v63, v133, s[4:5]
	v_cndmask_b32_e64 v133, v133, v59, s[4:5]
	v_cvt_pk_bf16_f32 v129, v129, v133
	v_add_co_u32_e32 v138, vcc, 0x1000, v136
	s_nop 1
	v_addc_co_u32_e32 v139, vcc, 0, v137, vcc
	global_store_dword v[138:139], v129, off offset:2048
	v_cndmask_b32_e64 v129, v47, v43, s[6:7]
	s_nop 1
	v_mov_b32_dpp v133, v129 quad_perm:[1,0,3,2] row_mask:0xf bank_mask:0xf bound_ctrl:1
	v_cndmask_b32_e64 v129, v47, v133, s[4:5]
	v_cndmask_b32_e64 v133, v133, v43, s[4:5]
	v_cvt_pk_bf16_f32 v129, v129, v133
	v_add_co_u32_e32 v138, vcc, 0x1000, v136
	s_nop 1
	v_addc_co_u32_e32 v139, vcc, 0, v137, vcc
	global_store_dword v[138:139], v129, off offset:2112
	v_cndmask_b32_e64 v129, v55, v51, s[6:7]
	s_nop 1
	v_mov_b32_dpp v133, v129 quad_perm:[1,0,3,2] row_mask:0xf bank_mask:0xf bound_ctrl:1
	v_cndmask_b32_e64 v129, v55, v133, s[4:5]
	v_cndmask_b32_e64 v133, v133, v51, s[4:5]
	v_cvt_pk_bf16_f32 v129, v129, v133
	v_add_co_u32_e32 v138, vcc, 0x1000, v136
	s_nop 1
	v_addc_co_u32_e32 v139, vcc, 0, v137, vcc
	global_store_dword v[138:139], v129, off offset:2176
	v_cndmask_b32_e64 v129, v39, v35, s[6:7]
	s_nop 1
	v_mov_b32_dpp v133, v129 quad_perm:[1,0,3,2] row_mask:0xf bank_mask:0xf bound_ctrl:1
	v_cndmask_b32_e64 v129, v39, v133, s[4:5]
	v_cndmask_b32_e64 v133, v133, v35, s[4:5]
	v_cvt_pk_bf16_f32 v129, v129, v133
	v_add_co_u32_e32 v136, vcc, 0x1000, v136
	s_nop 1
	v_addc_co_u32_e32 v137, vcc, 0, v137, vcc
	global_store_dword v[136:137], v129, off offset:2240
	v_cndmask_b32_e64 v129, v28, v24, s[6:7]
	s_nop 1
	v_mov_b32_dpp v133, v129 quad_perm:[1,0,3,2] row_mask:0xf bank_mask:0xf bound_ctrl:1
	v_cndmask_b32_e64 v129, v28, v133, s[4:5]
	v_cndmask_b32_e64 v133, v133, v24, s[4:5]
	v_cvt_pk_bf16_f32 v129, v129, v133
	v_mov_b32_e32 v135, v177
	v_lshl_add_u64 v[130:131], v[130:131], 0, v[134:135]
	v_add_co_u32_e32 v134, vcc, 0x18000, v130
	s_nop 1
	v_addc_co_u32_e32 v135, vcc, 0, v131, vcc
	global_store_dword v[134:135], v129, off
	v_cndmask_b32_e64 v129, v12, v8, s[6:7]
	s_nop 1
	v_mov_b32_dpp v133, v129 quad_perm:[1,0,3,2] row_mask:0xf bank_mask:0xf bound_ctrl:1
	v_cndmask_b32_e64 v129, v12, v133, s[4:5]
	v_cndmask_b32_e64 v133, v133, v8, s[4:5]
	v_cvt_pk_bf16_f32 v129, v129, v133
	s_mov_b64 s[2:3], 0x18000
	v_lshl_add_u64 v[130:131], v[130:131], 0, s[2:3]
	global_store_dword v[130:131], v129, off offset:64
	v_cndmask_b32_e64 v129, v20, v16, s[6:7]
	s_nop 1
	v_mov_b32_dpp v133, v129 quad_perm:[1,0,3,2] row_mask:0xf bank_mask:0xf bound_ctrl:1
	v_cndmask_b32_e64 v129, v20, v133, s[4:5]
	v_cndmask_b32_e64 v133, v133, v16, s[4:5]
	v_cvt_pk_bf16_f32 v129, v129, v133
	global_store_dword v[130:131], v129, off offset:128
	v_cndmask_b32_e64 v129, v4, v0, s[6:7]
	s_nop 1
	v_mov_b32_dpp v133, v129 quad_perm:[1,0,3,2] row_mask:0xf bank_mask:0xf bound_ctrl:1
	v_cndmask_b32_e64 v129, v4, v133, s[4:5]
	v_cndmask_b32_e64 v133, v133, v0, s[4:5]
	v_cvt_pk_bf16_f32 v129, v129, v133
	global_store_dword v[130:131], v129, off offset:192
	v_cndmask_b32_e64 v129, v29, v25, s[6:7]
	s_nop 1
	v_mov_b32_dpp v133, v129 quad_perm:[1,0,3,2] row_mask:0xf bank_mask:0xf bound_ctrl:1
	v_cndmask_b32_e64 v129, v29, v133, s[4:5]
	v_cndmask_b32_e64 v133, v133, v25, s[4:5]
	v_cvt_pk_bf16_f32 v129, v129, v133
	global_store_dword v[130:131], v129, off offset:2048
	v_cndmask_b32_e64 v129, v13, v9, s[6:7]
	s_nop 1
	v_mov_b32_dpp v133, v129 quad_perm:[1,0,3,2] row_mask:0xf bank_mask:0xf bound_ctrl:1
	v_cndmask_b32_e64 v129, v13, v133, s[4:5]
	v_cndmask_b32_e64 v133, v133, v9, s[4:5]
	v_cvt_pk_bf16_f32 v129, v129, v133
	global_store_dword v[130:131], v129, off offset:2112
	v_cndmask_b32_e64 v129, v21, v17, s[6:7]
	s_nop 1
; DEVFI float dpp_xor1(float x) { return __int_as_float(__builtin_amdgcn_update_dpp(0, __float_as_int(x), 0xB1, 0xF, 0xF, true)); }
; #define KM ((bfraw*)(kargs()->ws + O_KM))
; DEVFI void store_nat_m(bfraw* base, long ld, f32x4 (&a)[8], int fr) {
;   const bool odd = fr & 1;
;   bfraw* p0 = base + (odd ? 15 + fr : fr);
; #pragma unroll
;   for (int j = 0; j < 4; ++j)
; #pragma unroll
;     for (int n0 = 0; n0 < 8; n0 += 2) { const float own0 = a[n0][j], own1 = a[n0 + 1][j];
;       const float recv = dpp_xor1(odd ? own0 : own1);
;       const unsigned pk = odd ? cvtpk(recv, own1) : cvtpk(own0, recv);
;       *reinterpret_cast<unsigned*>(p0 + (long)j * ld + n0 * 16) = pk; }
; }
; __global__ void __launch_bounds__(512) mega(Params p) {
;     ...
;                 if (c0 < 1024) store_nat(KM + (long)r0 * 1024 + c0, 1024, acc, fr, fq);
	v_mov_b32_dpp v133, v129 quad_perm:[1,0,3,2] row_mask:0xf bank_mask:0xf bound_ctrl:1
	v_cndmask_b32_e64 v129, v21, v133, s[4:5]
	v_cndmask_b32_e64 v133, v133, v17, s[4:5]
	v_cvt_pk_bf16_f32 v129, v129, v133
	global_store_dword v[130:131], v129, off offset:2176
	v_cndmask_b32_e64 v129, v5, v1, s[6:7]
	s_nop 1
	v_mov_b32_dpp v133, v129 quad_perm:[1,0,3,2] row_mask:0xf bank_mask:0xf bound_ctrl:1
	v_cndmask_b32_e64 v129, v5, v133, s[4:5]
	v_cndmask_b32_e64 v133, v133, v1, s[4:5]
	v_cvt_pk_bf16_f32 v129, v129, v133
	global_store_dword v[130:131], v129, off offset:2240
	v_cndmask_b32_e64 v129, v30, v26, s[6:7]
	s_nop 1
	v_mov_b32_dpp v133, v129 quad_perm:[1,0,3,2] row_mask:0xf bank_mask:0xf bound_ctrl:1
	v_cndmask_b32_e64 v129, v30, v133, s[4:5]
	v_cndmask_b32_e64 v133, v133, v26, s[4:5]
	v_cvt_pk_bf16_f32 v129, v129, v133
	v_add_co_u32_e32 v134, vcc, 0x1000, v130
	s_nop 1
	v_addc_co_u32_e32 v135, vcc, 0, v131, vcc
	global_store_dword v[134:135], v129, off
	v_cndmask_b32_e64 v129, v14, v10, s[6:7]
	s_nop 1
	v_mov_b32_dpp v133, v129 quad_perm:[1,0,3,2] row_mask:0xf bank_mask:0xf bound_ctrl:1
	v_cndmask_b32_e64 v129, v14, v133, s[4:5]
	v_cndmask_b32_e64 v133, v133, v10, s[4:5]
	v_cvt_pk_bf16_f32 v129, v129, v133
	v_add_co_u32_e32 v134, vcc, 0x1000, v130
	s_nop 1
	v_addc_co_u32_e32 v135, vcc, 0, v131, vcc
	global_store_dword v[134:135], v129, off offset:64
	v_cndmask_b32_e64 v129, v22, v18, s[6:7]
	s_nop 1
	v_mov_b32_dpp v133, v129 quad_perm:[1,0,3,2] row_mask:0xf bank_mask:0xf bound_ctrl:1
	v_cndmask_b32_e64 v129, v22, v133, s[4:5]
	v_cndmask_b32_e64 v133, v133, v18, s[4:5]
	v_cvt_pk_bf16_f32 v129, v129, v133
	v_add_co_u32_e32 v134, vcc, 0x1000, v130
	s_nop 1
	v_addc_co_u32_e32 v135, vcc, 0, v131, vcc
	global_store_dword v[134:135], v129, off offset:128
	v_cndmask_b32_e64 v129, v6, v2, s[6:7]
	s_nop 1
	v_mov_b32_dpp v133, v129 quad_perm:[1,0,3,2] row_mask:0xf bank_mask:0xf bound_ctrl:1
	v_cndmask_b32_e64 v129, v6, v133, s[4:5]
	v_cndmask_b32_e64 v133, v133, v2, s[4:5]
	v_cvt_pk_bf16_f32 v129, v129, v133
	v_add_co_u32_e32 v134, vcc, 0x1000, v130
	s_nop 1
	v_addc_co_u32_e32 v135, vcc, 0, v131, vcc
	global_store_dword v[134:135], v129, off offset:192
	v_cndmask_b32_e64 v129, v31, v27, s[6:7]
	s_nop 1
	v_mov_b32_dpp v133, v129 quad_perm:[1,0,3,2] row_mask:0xf bank_mask:0xf bound_ctrl:1
	v_cndmask_b32_e64 v129, v31, v133, s[4:5]
	v_cndmask_b32_e64 v133, v133, v27, s[4:5]
	v_cvt_pk_bf16_f32 v129, v129, v133
	v_add_co_u32_e32 v134, vcc, 0x1000, v130
	s_nop 1
	v_addc_co_u32_e32 v135, vcc, 0, v131, vcc
	global_store_dword v[134:135], v129, off offset:2048
	v_cndmask_b32_e64 v129, v15, v11, s[6:7]
	s_nop 1
	v_mov_b32_dpp v133, v129 quad_perm:[1,0,3,2] row_mask:0xf bank_mask:0xf bound_ctrl:1
	v_cndmask_b32_e64 v129, v15, v133, s[4:5]
	v_cndmask_b32_e64 v133, v133, v11, s[4:5]
	v_cvt_pk_bf16_f32 v129, v129, v133
	v_add_co_u32_e32 v134, vcc, 0x1000, v130
	s_nop 1
	v_addc_co_u32_e32 v135, vcc, 0, v131, vcc
	global_store_dword v[134:135], v129, off offset:2112
	v_cndmask_b32_e64 v129, v23, v19, s[6:7]
	s_nop 1
	v_mov_b32_dpp v133, v129 quad_perm:[1,0,3,2] row_mask:0xf bank_mask:0xf bound_ctrl:1
	v_cndmask_b32_e64 v129, v23, v133, s[4:5]
	v_cndmask_b32_e64 v133, v133, v19, s[4:5]
	v_cvt_pk_bf16_f32 v129, v129, v133
	v_add_co_u32_e32 v134, vcc, 0x1000, v130
	s_nop 1
	v_addc_co_u32_e32 v135, vcc, 0, v131, vcc
	global_store_dword v[134:135], v129, off offset:2176
	v_cndmask_b32_e64 v129, v7, v3, s[6:7]
	s_nop 1
	v_mov_b32_dpp v133, v129 quad_perm:[1,0,3,2] row_mask:0xf bank_mask:0xf bound_ctrl:1
	v_cndmask_b32_e64 v129, v7, v133, s[4:5]
	v_cndmask_b32_e64 v133, v133, v3, s[4:5]
	v_cvt_pk_bf16_f32 v129, v129, v133
	v_add_co_u32_e32 v130, vcc, 0x1000, v130
	s_nop 1
	v_addc_co_u32_e32 v131, vcc, 0, v131, vcc
	global_store_dword v[130:131], v129, off offset:2240

; DEVFI float dpp_xor1(float x) { return __int_as_float(__builtin_amdgcn_update_dpp(0, __float_as_int(x), 0xB1, 0xF, 0xF, true)); }
; #define AQ ((bfraw*)(kargs()->ws + O_AQ))
; #define AK ((bfraw*)(kargs()->ws + O_AK))
; #define AV ((bfraw*)(kargs()->ws + O_AV))
; DEVFI void store_nat_m(bfraw* base, long ld, f32x4 (&a)[8], int fr) {
;   const bool odd = fr & 1;
;   bfraw* p0 = base + (odd ? 15 + fr : fr);
; #pragma unroll
;   for (int j = 0; j < 4; ++j)
; #pragma unroll
;     for (int n0 = 0; n0 < 8; n0 += 2) { const float own0 = a[n0][j], own1 = a[n0 + 1][j];
;       const float recv = dpp_xor1(odd ? own0 : own1);
;       const unsigned pk = odd ? cvtpk(recv, own1) : cvtpk(own0, recv);
;       *reinterpret_cast<unsigned*>(p0 + (long)j * ld + n0 * 16) = pk; }
; }
; __global__ void __launch_bounds__(512) mega(Params p) {
;     ...
;                     if (isk) store_nat_m(AK + (long)r0 * 256 + (c0 - 7168), 256, a, fr);
;                     else store_nat_m(AQ + (long)r0 * 1024 + (c0 - 6144), 1024, a, fr);
;                   } else if (c0 < 7680) {
;                     store_nat_m(AV + (long)r0 * 256 + (c0 - 7424), 256, a, fr);
.LBB0_691:
	s_andn2_b64 vcc, exec, s[2:3]
	s_cbranch_vccnz .LBB0_757
	s_mov_b64 s[2:3], s[0:1]
	s_load_dwordx2 s[2:3], s[2:3], 0xe8
	v_and_b32_e32 v128, 1, v203
	v_cmp_eq_u32_e64 s[8:9], 0, v128
	v_cmp_eq_u32_e64 s[6:7], 1, v128
	s_nop 0
	v_cndmask_b32_e64 v128, v124, v120, s[8:9]
	s_nop 1
	v_mov_b32_dpp v128, v128 quad_perm:[1,0,3,2] row_mask:0xf bank_mask:0xf bound_ctrl:1
	v_cndmask_b32_e64 v130, v124, v128, s[6:7]
	v_cndmask_b32_e64 v128, v128, v120, s[6:7]
	v_cvt_pk_bf16_f32 v130, v130, v128
	v_ashrrev_i32_e32 v163, 31, v162
	v_lshlrev_b64 v[128:129], 9, v[162:163]
	v_add_u32_e32 v131, 15, v202
	s_waitcnt lgkmcnt(0)
	v_lshl_add_u64 v[128:129], s[2:3], 0, v[128:129]
	v_cndmask_b32_e64 v131, v131, v202, s[8:9]
	v_lshl_add_u64 v[128:129], v[176:177], 1, v[128:129]
	v_lshlrev_b32_e32 v134, 1, v131
	v_mov_b32_e32 v135, v177
	v_lshl_add_u64 v[128:129], v[128:129], 0, v[134:135]
	v_add_co_u32_e32 v134, vcc, 0x21f1c000, v128
	s_nop 1
	v_addc_co_u32_e32 v135, vcc, 0, v129, vcc
	global_store_dword v[134:135], v130, off offset:1536
	v_cndmask_b32_e64 v130, v108, v104, s[8:9]
	s_nop 1
	v_mov_b32_dpp v131, v130 quad_perm:[1,0,3,2] row_mask:0xf bank_mask:0xf bound_ctrl:1
	v_cndmask_b32_e64 v130, v108, v131, s[6:7]
	v_cndmask_b32_e64 v131, v131, v104, s[6:7]
	v_cvt_pk_bf16_f32 v130, v130, v131
	s_mov_b64 s[2:3], 0x21f1c600
	v_lshl_add_u64 v[128:129], v[128:129], 0, s[2:3]
	global_store_dword v[128:129], v130, off offset:64
	v_cndmask_b32_e64 v130, v116, v112, s[8:9]
	s_nop 1
	v_mov_b32_dpp v131, v130 quad_perm:[1,0,3,2] row_mask:0xf bank_mask:0xf bound_ctrl:1
	v_cndmask_b32_e64 v130, v116, v131, s[6:7]
	v_cndmask_b32_e64 v131, v131, v112, s[6:7]
	v_cvt_pk_bf16_f32 v130, v130, v131
	global_store_dword v[128:129], v130, off offset:128
	v_cndmask_b32_e64 v130, v100, v96, s[8:9]
	s_nop 1
	v_mov_b32_dpp v131, v130 quad_perm:[1,0,3,2] row_mask:0xf bank_mask:0xf bound_ctrl:1
	v_cndmask_b32_e64 v130, v100, v131, s[6:7]
	v_cndmask_b32_e64 v131, v131, v96, s[6:7]
	v_cvt_pk_bf16_f32 v130, v130, v131
	global_store_dword v[128:129], v130, off offset:192
	v_cndmask_b32_e64 v130, v125, v121, s[8:9]
	s_nop 1
	v_mov_b32_dpp v131, v130 quad_perm:[1,0,3,2] row_mask:0xf bank_mask:0xf bound_ctrl:1
	v_cndmask_b32_e64 v130, v125, v131, s[6:7]
	v_cndmask_b32_e64 v131, v131, v121, s[6:7]
	v_cvt_pk_bf16_f32 v130, v130, v131
	global_store_dword v[128:129], v130, off offset:512
	v_cndmask_b32_e64 v130, v109, v105, s[8:9]
	s_nop 1
	v_mov_b32_dpp v131, v130 quad_perm:[1,0,3,2] row_mask:0xf bank_mask:0xf bound_ctrl:1
	v_cndmask_b32_e64 v130, v109, v131, s[6:7]
	v_cndmask_b32_e64 v131, v131, v105, s[6:7]
	v_cvt_pk_bf16_f32 v130, v130, v131
	global_store_dword v[128:129], v130, off offset:576
	v_cndmask_b32_e64 v130, v117, v113, s[8:9]
	s_nop 1
	v_mov_b32_dpp v131, v130 quad_perm:[1,0,3,2] row_mask:0xf bank_mask:0xf bound_ctrl:1
	v_cndmask_b32_e64 v130, v117, v131, s[6:7]
	v_cndmask_b32_e64 v131, v131, v113, s[6:7]
	v_cvt_pk_bf16_f32 v130, v130, v131
	global_store_dword v[128:129], v130, off offset:640
	v_cndmask_b32_e64 v130, v101, v97, s[8:9]
	s_nop 1
	v_mov_b32_dpp v131, v130 quad_perm:[1,0,3,2] row_mask:0xf bank_mask:0xf bound_ctrl:1
	v_cndmask_b32_e64 v130, v101, v131, s[6:7]
	v_cndmask_b32_e64 v131, v131, v97, s[6:7]
	v_cvt_pk_bf16_f32 v130, v130, v131
	global_store_dword v[128:129], v130, off offset:704
	v_cndmask_b32_e64 v130, v126, v122, s[8:9]
	s_nop 1
	v_mov_b32_dpp v131, v130 quad_perm:[1,0,3,2] row_mask:0xf bank_mask:0xf bound_ctrl:1
	v_cndmask_b32_e64 v130, v126, v131, s[6:7]
	v_cndmask_b32_e64 v131, v131, v122, s[6:7]
	v_cvt_pk_bf16_f32 v130, v130, v131
	global_store_dword v[128:129], v130, off offset:1024
	v_cndmask_b32_e64 v130, v110, v106, s[8:9]
	s_nop 1
	v_mov_b32_dpp v131, v130 quad_perm:[1,0,3,2] row_mask:0xf bank_mask:0xf bound_ctrl:1
	v_cndmask_b32_e64 v130, v110, v131, s[6:7]
	v_cndmask_b32_e64 v131, v131, v106, s[6:7]
	v_cvt_pk_bf16_f32 v130, v130, v131
	global_store_dword v[128:129], v130, off offset:1088
	v_cndmask_b32_e64 v130, v118, v114, s[8:9]
	s_nop 1
	v_mov_b32_dpp v131, v130 quad_perm:[1,0,3,2] row_mask:0xf bank_mask:0xf bound_ctrl:1
	v_cndmask_b32_e64 v130, v118, v131, s[6:7]
	v_cndmask_b32_e64 v131, v131, v114, s[6:7]
	v_cvt_pk_bf16_f32 v130, v130, v131
	global_store_dword v[128:129], v130, off offset:1152
	v_cndmask_b32_e64 v130, v102, v98, s[8:9]
	s_nop 1
	v_mov_b32_dpp v131, v130 quad_perm:[1,0,3,2] row_mask:0xf bank_mask:0xf bound_ctrl:1
	v_cndmask_b32_e64 v130, v102, v131, s[6:7]
	v_cndmask_b32_e64 v131, v131, v98, s[6:7]
	v_cvt_pk_bf16_f32 v130, v130, v131
	global_store_dword v[128:129], v130, off offset:1216
	v_cndmask_b32_e64 v130, v127, v123, s[8:9]
	s_nop 1
	v_mov_b32_dpp v131, v130 quad_perm:[1,0,3,2] row_mask:0xf bank_mask:0xf bound_ctrl:1
	v_cndmask_b32_e64 v130, v127, v131, s[6:7]
	v_cndmask_b32_e64 v131, v131, v123, s[6:7]
	v_cvt_pk_bf16_f32 v130, v130, v131
	global_store_dword v[128:129], v130, off offset:1536
	v_cndmask_b32_e64 v130, v111, v107, s[8:9]
	s_nop 1
	v_mov_b32_dpp v131, v130 quad_perm:[1,0,3,2] row_mask:0xf bank_mask:0xf bound_ctrl:1
	v_cndmask_b32_e64 v130, v111, v131, s[6:7]
	v_cndmask_b32_e64 v131, v131, v107, s[6:7]
	v_cvt_pk_bf16_f32 v130, v130, v131
	global_store_dword v[128:129], v130, off offset:1600
	v_cndmask_b32_e64 v130, v119, v115, s[8:9]
	s_nop 1
	v_mov_b32_dpp v131, v130 quad_perm:[1,0,3,2] row_mask:0xf bank_mask:0xf bound_ctrl:1
	v_cndmask_b32_e64 v130, v119, v131, s[6:7]
	v_cndmask_b32_e64 v131, v131, v115, s[6:7]
	v_cvt_pk_bf16_f32 v130, v130, v131
	global_store_dword v[128:129], v130, off offset:1664
	v_cndmask_b32_e64 v130, v103, v99, s[8:9]
	s_nop 1
	v_mov_b32_dpp v131, v130 quad_perm:[1,0,3,2] row_mask:0xf bank_mask:0xf bound_ctrl:1
	v_cndmask_b32_e64 v130, v103, v131, s[6:7]
	v_cndmask_b32_e64 v131, v131, v99, s[6:7]
	v_cvt_pk_bf16_f32 v130, v130, v131
	global_store_dword v[128:129], v130, off offset:1728

; DEVFI float dpp_xor1(float x) { return __int_as_float(__builtin_amdgcn_update_dpp(0, __float_as_int(x), 0xB1, 0xF, 0xF, true)); }
; #define RG ((bfraw*)(kargs()->ws + O_RG))
; #define SU ((bfraw*)(kargs()->ws + O_SU))
; #define SV ((bfraw*)(kargs()->ws + O_SV))
; #define SVSTAT ((float*)(kargs()->ws + O_SVSTAT))
; DEVFI void store_nat_m(bfraw* base, long ld, f32x4 (&a)[8], int fr) {
;   const bool odd = fr & 1;
;   bfraw* p0 = base + (odd ? 15 + fr : fr);
; #pragma unroll
;   for (int j = 0; j < 4; ++j)
; #pragma unroll
;     for (int n0 = 0; n0 < 8; n0 += 2) { const float own0 = a[n0][j], own1 = a[n0 + 1][j];
;       const float recv = dpp_xor1(odd ? own0 : own1);
;       const unsigned pk = odd ? cvtpk(recv, own1) : cvtpk(own0, recv);
;       *reinterpret_cast<unsigned*>(p0 + (long)j * ld + n0 * 16) = pk; }
; }
; __global__ void __launch_bounds__(512) mega(Params p) {
;     ...
;                     store_nat_m(RG + (long)r0 * 1024 + (c0 - 3072), 1024, a, fr);
;                   } else if (c0 < 6144) {
; #pragma unroll
;                     for (int n = 0; n < 8; ++n)
; #pragma unroll
;                       for (int j = 0; j < 4; ++j) a[n][j] = gelu_tanh(a[n][j]);
;                     if (c0 >= 5120) { float* stp = SVSTAT + (long)r0 * 16 + ((c0 - 5120) >> 7) * 2;
; #pragma unroll
;                       for (int j = 0; j < 4; ++j) { float s1 = 0, s2 = 0;
; #pragma unroll
;                         for (int n = 0; n < 8; ++n) { s1 += a[n][j]; s2 += a[n][j] * a[n][j]; }
;                         s1 = red16(s1); s2 = red16(s2);
;                         if (fr == 0) { stp[j * 16] = s1; stp[j * 16 + 1] = s2; } } }
;                     store_nat_m((c0 < 5120 ? SU + (c0 - 4096) : SV + (c0 - 5120)) + (long)r0 * 1024, 1024, a, fr);
.LBB0_824:
	s_or_b64 exec, exec, s[2:3]
	v_add_co_u32_e32 v170, vcc, 0x1000, v128
	v_mov_b32_dpp v168, v169 quad_perm:[1,0,3,2] row_mask:0xf bank_mask:0xf bound_ctrl:1
	s_nop 0
	v_addc_co_u32_e32 v171, vcc, 0, v129, vcc
	global_store_dword v[170:171], v167, off offset:2176
	v_cndmask_b32_e64 v167, v157, v168, s[6:7]
	v_cndmask_b32_e64 v168, v168, v130, s[6:7]
	v_cvt_pk_bf16_f32 v167, v167, v168
	v_add_co_u32_e32 v128, vcc, 0x1000, v128
	s_mov_b64 s[2:3], 0
	s_nop 0
	v_addc_co_u32_e32 v129, vcc, 0, v129, vcc
	global_store_dword v[128:129], v167, off offset:2240

; DEVFI float dpp_xor1(float x) { return __int_as_float(__builtin_amdgcn_update_dpp(0, __float_as_int(x), 0xB1, 0xF, 0xF, true)); }
; #define AQ ((bfraw*)(kargs()->ws + O_AQ))
; #define AK ((bfraw*)(kargs()->ws + O_AK))
; DEVFI void store_nat_m(bfraw* base, long ld, f32x4 (&a)[8], int fr) {
;   const bool odd = fr & 1;
;   bfraw* p0 = base + (odd ? 15 + fr : fr);
; #pragma unroll
;   for (int j = 0; j < 4; ++j)
; #pragma unroll
;     for (int n0 = 0; n0 < 8; n0 += 2) { const float own0 = a[n0][j], own1 = a[n0 + 1][j];
;       const float recv = dpp_xor1(odd ? own0 : own1);
;       const unsigned pk = odd ? cvtpk(recv, own1) : cvtpk(own0, recv);
;       *reinterpret_cast<unsigned*>(p0 + (long)j * ld + n0 * 16) = pk; }
; }
; __global__ void __launch_bounds__(512) mega(Params p) {
;     ...
;                     if (isk) store_nat_m(AK + (long)r0 * 256 + (c0 - 7168), 256, a, fr);
;                     else store_nat_m(AQ + (long)r0 * 1024 + (c0 - 6144), 1024, a, fr);
.LBB0_890:
	s_or_b64 exec, exec, s[2:3]
	s_nop 0
	v_mov_b32_dpp v133, v134 quad_perm:[1,0,3,2] row_mask:0xf bank_mask:0xf bound_ctrl:1
	global_store_dword v[128:129], v131, off offset:1664
	v_cndmask_b32_e64 v131, v157, v133, s[6:7]
	v_cndmask_b32_e64 v133, v133, v130, s[6:7]
	v_cvt_pk_bf16_f32 v131, v131, v133
	global_store_dword v[128:129], v131, off offset:1728

; DEVFI void store_nat_m(bfraw* base, long ld, f32x4 (&a)[8], int fr) {
;   const bool odd = fr & 1;
;   bfraw* p0 = base + (odd ? 15 + fr : fr);
; #pragma unroll
;   for (int j = 0; j < 4; ++j)
; #pragma unroll
;     for (int n0 = 0; n0 < 8; n0 += 2) { const float own0 = a[n0][j], own1 = a[n0 + 1][j];
;       const float recv = dpp_xor1(odd ? own0 : own1);
;       const unsigned pk = odd ? cvtpk(recv, own1) : cvtpk(own0, recv);
;       *reinterpret_cast<unsigned*>(p0 + (long)j * ld + n0 * 16) = pk; }
; }
; __global__ void __launch_bounds__(512) mega(Params p) {
;     ...
;                     store_nat_m((isk ? RK : RQ) + (long)r0 * 1024 + cc, 1024, a, fr);
;                     if (isk) store_tr_m(RKT + ((long)((r0 >> 7) * 8 + head) * 128 + fr) * 128 + (r0 & 127), 128, a);
;                   } else if (c0 < 3072) {
;                     const int head = (c0 - 2048) >> 7;
;                     store_tr_m(RVT + ((long)((r0 >> 7) * 8 + head) * 128 + fr) * 128 + (r0 & 127), 128, a);
;                   } else if (c0 < 4096) {
; #pragma unroll
;                     for (int n = 0; n < 8; ++n)
; #pragma unroll
;                       for (int j = 0; j < 4; ++j) { const float x = a[n][j]; a[n][j] = x * sigmoidf_(x); }
;                     store_nat_m(RG + (long)r0 * 1024 + (c0 - 3072), 1024, a, fr);
;                   } else if (c0 < 6144) {
; #pragma unroll
;                     for (int n = 0; n < 8; ++n)
; #pragma unroll
;                       for (int j = 0; j < 4; ++j) a[n][j] = gelu_tanh(a[n][j]);
;                     if (c0 >= 5120) { float* stp = SVSTAT + (long)r0 * 16 + ((c0 - 5120) >> 7) * 2;
; #pragma unroll
;                       for (int j = 0; j < 4; ++j) { float s1 = 0, s2 = 0;
; #pragma unroll
;                         for (int n = 0; n < 8; ++n) { s1 += a[n][j]; s2 += a[n][j] * a[n][j]; }
;                         s1 = red16(s1); s2 = red16(s2);
;                         if (fr == 0) { stp[j * 16] = s1; stp[j * 16 + 1] = s2; } } }
;                     store_nat_m((c0 < 5120 ? SU + (c0 - 4096) : SV + (c0 - 5120)) + (long)r0 * 1024, 1024, a, fr);
;                   } else if (c0 < 7424) {
;                     const bool isk = c0 >= 7168; const float* nw = isk ? kn_w : qn_w; const float2* attt = ATTT;
; #pragma unroll
;                     for (int j = 0; j < 4; ++j) { const int pos = (r0 + j) & (seqlen - 1);
;                       float ss = 0;
.LBB0_969:
	s_or_b64 exec, exec, s[2:3]
	v_add_co_u32_e32 v134, vcc, 0x1000, v144
	v_mov_b32_dpp v129, v130 quad_perm:[1,0,3,2] row_mask:0xf bank_mask:0xf bound_ctrl:1
	s_nop 0
	v_addc_co_u32_e32 v135, vcc, 0, v145, vcc
	global_store_dword v[134:135], v128, off offset:2176
	v_cndmask_b32_e64 v128, v154, v129, s[6:7]
	v_cndmask_b32_e64 v129, v129, v166, s[6:7]
	v_cvt_pk_bf16_f32 v128, v128, v129
	v_add_co_u32_e32 v130, vcc, 0x1000, v144
	s_nop 1
	v_addc_co_u32_e32 v131, vcc, 0, v145, vcc
	global_store_dword v[130:131], v128, off offset:2240

; DEVFI void store_nat_m(bfraw* base, long ld, f32x4 (&a)[8], int fr) {
;   const bool odd = fr & 1;
;   bfraw* p0 = base + (odd ? 15 + fr : fr);
; #pragma unroll
;   for (int j = 0; j < 4; ++j)
; #pragma unroll
;     for (int n0 = 0; n0 < 8; n0 += 2) { const float own0 = a[n0][j], own1 = a[n0 + 1][j];
;       const float recv = dpp_xor1(odd ? own0 : own1);
;       const unsigned pk = odd ? cvtpk(recv, own1) : cvtpk(own0, recv);
;       *reinterpret_cast<unsigned*>(p0 + (long)j * ld + n0 * 16) = pk; }
; }
; __global__ void __launch_bounds__(512) mega(Params p) {
;     ...
;                     store_nat_m((isk ? RK : RQ) + (long)r0 * 1024 + cc, 1024, a, fr);
;                     if (isk) store_tr_m(RKT + ((long)((r0 >> 7) * 8 + head) * 128 + fr) * 128 + (r0 & 127), 128, a);
;                   } else if (c0 < 3072) {
;                     const int head = (c0 - 2048) >> 7;
;                     store_tr_m(RVT + ((long)((r0 >> 7) * 8 + head) * 128 + fr) * 128 + (r0 & 127), 128, a);
;                   } else if (c0 < 4096) {
; #pragma unroll
;                     for (int n = 0; n < 8; ++n)
; #pragma unroll
;                       for (int j = 0; j < 4; ++j) { const float x = a[n][j]; a[n][j] = x * sigmoidf_(x); }
;                     store_nat_m(RG + (long)r0 * 1024 + (c0 - 3072), 1024, a, fr);
;                   } else if (c0 < 6144) {
; #pragma unroll
;                     for (int n = 0; n < 8; ++n)
; #pragma unroll
;                       for (int j = 0; j < 4; ++j) a[n][j] = gelu_tanh(a[n][j]);
;                     if (c0 >= 5120) { float* stp = SVSTAT + (long)r0 * 16 + ((c0 - 5120) >> 7) * 2;
; #pragma unroll
;                       for (int j = 0; j < 4; ++j) { float s1 = 0, s2 = 0;
; #pragma unroll
;                         for (int n = 0; n < 8; ++n) { s1 += a[n][j]; s2 += a[n][j] * a[n][j]; }
;                         s1 = red16(s1); s2 = red16(s2);
;                         if (fr == 0) { stp[j * 16] = s1; stp[j * 16 + 1] = s2; } } }
;                     store_nat_m((c0 < 5120 ? SU + (c0 - 4096) : SV + (c0 - 5120)) + (long)r0 * 1024, 1024, a, fr);
;                   } else if (c0 < 7424) {
;                     const bool isk = c0 >= 7168; const float* nw = isk ? kn_w : qn_w; const float2* attt = ATTT;
; #pragma unroll
;                     for (int j = 0; j < 4; ++j) { const int pos = (r0 + j) & (seqlen - 1);
;                       float ss = 0;
.LBB0_1036:
	s_or_b64 exec, exec, s[2:3]
	v_add_co_u32_e32 v136, vcc, 0x1000, v128
	s_nop 1
	v_addc_co_u32_e32 v137, vcc, 0, v129, vcc
	global_store_dword v[136:137], v133, off offset:2176
	v_mov_b32_dpp v133, v135 quad_perm:[1,0,3,2] row_mask:0xf bank_mask:0xf bound_ctrl:1
	v_cndmask_b32_e64 v131, v130, v133, s[6:7]
	v_cndmask_b32_e64 v133, v133, v134, s[6:7]
	v_cvt_pk_bf16_f32 v131, v131, v133
	v_add_co_u32_e32 v128, vcc, 0x1000, v128
	s_nop 1
	v_addc_co_u32_e32 v129, vcc, 0, v129, vcc
	global_store_dword v[128:129], v131, off offset:2240

; DEVFI float dpp_xor1(float x) { return __int_as_float(__builtin_amdgcn_update_dpp(0, __float_as_int(x), 0xB1, 0xF, 0xF, true)); }
; DEVFI void store_nat_m(bfraw* base, long ld, f32x4 (&a)[8], int fr) {
;   const bool odd = fr & 1;
;   bfraw* p0 = base + (odd ? 15 + fr : fr);
; #pragma unroll
;   for (int j = 0; j < 4; ++j)
; #pragma unroll
;     for (int n0 = 0; n0 < 8; n0 += 2) { const float own0 = a[n0][j], own1 = a[n0 + 1][j];
;       const float recv = dpp_xor1(odd ? own0 : own1);
;       const unsigned pk = odd ? cvtpk(recv, own1) : cvtpk(own0, recv);
;       *reinterpret_cast<unsigned*>(p0 + (long)j * ld + n0 * 16) = pk; }
; }
; DEVFI void store_tr_m(bfraw* dstT, long ldT, f32x4 (&a)[8]) {
; #pragma unroll
;   for (int n = 0; n < 8; ++n) { u32x2 w = {cvtpk(a[n][0], a[n][1]), cvtpk(a[n][2], a[n][3])};
;     *reinterpret_cast<u32x2*>(dstT + (long)(n * 16) * ldT) = w; }
; }
.LBB0_1109:
	s_or_b64 exec, exec, s[2:3]
	v_add_co_u32_e32 v130, vcc, 0x1000, v164
	v_mov_b32_dpp v127, v128 quad_perm:[1,0,3,2] row_mask:0xf bank_mask:0xf bound_ctrl:1
	s_nop 0
	v_addc_co_u32_e32 v131, vcc, 0, v165, vcc
	global_store_dword v[130:131], v123, off offset:2176
	v_cndmask_b32_e64 v123, v111, v127, s[8:9]
	v_cndmask_b32_e64 v127, v127, v107, s[8:9]
	v_cvt_pk_bf16_f32 v123, v123, v127
	v_add_co_u32_e32 v128, vcc, 0x1000, v164
	s_nop 1
	v_addc_co_u32_e32 v129, vcc, 0, v165, vcc
	global_store_dword v[128:129], v123, off offset:2240
	s_and_saveexec_b64 s[2:3], s[6:7]
	s_cbranch_execz .LBB0_1115
	s_mov_b64 s[6:7], s[0:1]
	s_load_dwordx2 s[6:7], s[6:7], 0xe8
	v_lshrrev_b32_e32 v107, 7, v171
	v_ashrrev_i32_e32 v111, 4, v162
	v_and_or_b32 v128, v111, -8, v107
	v_ashrrev_i32_e32 v129, 31, v128
	v_lshlrev_b64 v[128:129], 15, v[128:129]
	s_waitcnt lgkmcnt(0)
	v_lshl_add_u64 v[128:129], s[6:7], 0, v[128:129]
	v_lshlrev_b32_e32 v130, 8, v202
	v_mov_b32_e32 v131, v177
	v_and_b32_e32 v107, 0x7f, v162
	v_lshl_add_u64 v[128:129], v[128:129], 0, v[130:131]
	v_lshlrev_b32_e32 v130, 1, v107
	v_lshl_add_u64 v[128:129], v[128:129], 0, v[130:131]
	s_mov_b32 s6, 0x15721000
	v_cvt_pk_bf16_f32 v108, v168, v108
	v_cvt_pk_bf16_f32 v109, v109, v110
	v_add_co_u32_e32 v110, vcc, s6, v128
	s_mov_b32 s6, 0x15723000
	s_nop 0
	v_addc_co_u32_e32 v111, vcc, 0, v129, vcc
	global_store_dwordx2 v[110:111], v[108:109], off offset:-4096
	v_cvt_pk_bf16_f32 v104, v161, v104
	v_cvt_pk_bf16_f32 v105, v105, v106
	v_add_co_u32_e32 v106, vcc, s6, v128
	global_store_dwordx2 v[110:111], v[104:105], off
	v_cvt_pk_bf16_f32 v104, v170, v124
	v_cvt_pk_bf16_f32 v105, v125, v126
	s_nop 0
	v_addc_co_u32_e32 v107, vcc, 0, v129, vcc
	s_mov_b32 s6, 0x15725000
	global_store_dwordx2 v[106:107], v[104:105], off offset:-4096
	v_cvt_pk_bf16_f32 v104, v169, v120
	v_cvt_pk_bf16_f32 v105, v121, v122
	global_store_dwordx2 v[106:107], v[104:105], off
	v_add_co_u32_e32 v106, vcc, s6, v128
	v_cvt_pk_bf16_f32 v104, v116, v117
	v_cvt_pk_bf16_f32 v105, v118, v119
	s_mov_b32 s6, 0x15726000
	s_nop 0
	v_addc_co_u32_e32 v107, vcc, 0, v129, vcc
	global_store_dwordx2 v[106:107], v[104:105], off offset:-4096
	v_cvt_pk_bf16_f32 v104, v112, v113
	v_cvt_pk_bf16_f32 v105, v114, v115
	global_store_dwordx2 v[106:107], v[104:105], off
	v_cvt_pk_bf16_f32 v100, v100, v101
	v_cvt_pk_bf16_f32 v101, v102, v103
	v_add_co_u32_e32 v102, vcc, s6, v128
	s_nop 1
	v_addc_co_u32_e32 v103, vcc, 0, v129, vcc
	global_store_dwordx2 v[102:103], v[100:101], off
	v_cvt_pk_bf16_f32 v96, v96, v97
	v_cvt_pk_bf16_f32 v97, v98, v99
	v_add_co_u32_e32 v98, vcc, 0x15727000, v128
	s_nop 1
	v_addc_co_u32_e32 v99, vcc, 0, v129, vcc
	global_store_dwordx2 v[98:99], v[96:97], off

; DEVFI float dpp_xor1(float x) { return __int_as_float(__builtin_amdgcn_update_dpp(0, __float_as_int(x), 0xB1, 0xF, 0xF, true)); }
; #define AQ ((bfraw*)(kargs()->ws + O_AQ))
; #define AK ((bfraw*)(kargs()->ws + O_AK))
; #define AV ((bfraw*)(kargs()->ws + O_AV))
; DEVFI void store_nat_m(bfraw* base, long ld, f32x4 (&a)[8], int fr) {
;   const bool odd = fr & 1;
;   bfraw* p0 = base + (odd ? 15 + fr : fr);
; #pragma unroll
;   for (int j = 0; j < 4; ++j)
; #pragma unroll
;     for (int n0 = 0; n0 < 8; n0 += 2) { const float own0 = a[n0][j], own1 = a[n0 + 1][j];
;       const float recv = dpp_xor1(odd ? own0 : own1);
;       const unsigned pk = odd ? cvtpk(recv, own1) : cvtpk(own0, recv);
;       *reinterpret_cast<unsigned*>(p0 + (long)j * ld + n0 * 16) = pk; }
; }
; __global__ void __launch_bounds__(512) mega(Params p) {
;     ...
;                     if (isk) store_nat_m(AK + (long)r0 * 256 + (c0 - 7168), 256, a, fr);
;                     else store_nat_m(AQ + (long)r0 * 1024 + (c0 - 6144), 1024, a, fr);
;                   } else if (c0 < 7680) {
;                     store_nat_m(AV + (long)r0 * 256 + (c0 - 7424), 256, a, fr);
.LBB0_1123:
	s_andn2_b64 vcc, exec, s[2:3]
	s_cbranch_vccnz .LBB0_1189
	s_mov_b64 s[2:3], s[0:1]
	s_load_dwordx2 s[2:3], s[2:3], 0xe8
	v_and_b32_e32 v96, 1, v203
	v_cmp_eq_u32_e64 s[8:9], 0, v96
	v_cmp_eq_u32_e64 s[6:7], 1, v96
	s_nop 0
	v_cndmask_b32_e64 v96, v92, v88, s[8:9]
	s_nop 1
	v_mov_b32_dpp v96, v96 quad_perm:[1,0,3,2] row_mask:0xf bank_mask:0xf bound_ctrl:1
	v_cndmask_b32_e64 v98, v92, v96, s[6:7]
	v_cndmask_b32_e64 v96, v96, v88, s[6:7]
	v_cvt_pk_bf16_f32 v98, v98, v96
	v_ashrrev_i32_e32 v129, 31, v128
	v_lshlrev_b64 v[96:97], 9, v[128:129]
	v_add_u32_e32 v99, 15, v202
	s_waitcnt lgkmcnt(0)
	v_lshl_add_u64 v[96:97], s[2:3], 0, v[96:97]
	v_cndmask_b32_e64 v99, v99, v202, s[8:9]
	v_lshl_add_u64 v[96:97], v[176:177], 1, v[96:97]
	v_lshlrev_b32_e32 v100, 1, v99
	v_mov_b32_e32 v101, v177
	v_lshl_add_u64 v[96:97], v[96:97], 0, v[100:101]
	v_add_co_u32_e32 v100, vcc, 0x21f1c000, v96
	s_nop 1
	v_addc_co_u32_e32 v101, vcc, 0, v97, vcc
	global_store_dword v[100:101], v98, off offset:1536
	v_cndmask_b32_e64 v98, v76, v72, s[8:9]
	s_nop 1
	v_mov_b32_dpp v99, v98 quad_perm:[1,0,3,2] row_mask:0xf bank_mask:0xf bound_ctrl:1
	v_cndmask_b32_e64 v98, v76, v99, s[6:7]
	v_cndmask_b32_e64 v99, v99, v72, s[6:7]
	v_cvt_pk_bf16_f32 v98, v98, v99
	s_mov_b64 s[2:3], 0x21f1c600
	v_lshl_add_u64 v[96:97], v[96:97], 0, s[2:3]
	global_store_dword v[96:97], v98, off offset:64
	v_cndmask_b32_e64 v98, v84, v80, s[8:9]
	s_nop 1
	v_mov_b32_dpp v99, v98 quad_perm:[1,0,3,2] row_mask:0xf bank_mask:0xf bound_ctrl:1
	v_cndmask_b32_e64 v98, v84, v99, s[6:7]
	v_cndmask_b32_e64 v99, v99, v80, s[6:7]
	v_cvt_pk_bf16_f32 v98, v98, v99
	global_store_dword v[96:97], v98, off offset:128
	v_cndmask_b32_e64 v98, v68, v64, s[8:9]
	s_nop 1
	v_mov_b32_dpp v99, v98 quad_perm:[1,0,3,2] row_mask:0xf bank_mask:0xf bound_ctrl:1
	v_cndmask_b32_e64 v98, v68, v99, s[6:7]
	v_cndmask_b32_e64 v99, v99, v64, s[6:7]
	v_cvt_pk_bf16_f32 v98, v98, v99
	global_store_dword v[96:97], v98, off offset:192
	v_cndmask_b32_e64 v98, v93, v89, s[8:9]
	s_nop 1
	v_mov_b32_dpp v99, v98 quad_perm:[1,0,3,2] row_mask:0xf bank_mask:0xf bound_ctrl:1
	v_cndmask_b32_e64 v98, v93, v99, s[6:7]
	v_cndmask_b32_e64 v99, v99, v89, s[6:7]
	v_cvt_pk_bf16_f32 v98, v98, v99
	global_store_dword v[96:97], v98, off offset:512
	v_cndmask_b32_e64 v98, v77, v73, s[8:9]
	s_nop 1
	v_mov_b32_dpp v99, v98 quad_perm:[1,0,3,2] row_mask:0xf bank_mask:0xf bound_ctrl:1
	v_cndmask_b32_e64 v98, v77, v99, s[6:7]
	v_cndmask_b32_e64 v99, v99, v73, s[6:7]
	v_cvt_pk_bf16_f32 v98, v98, v99
	global_store_dword v[96:97], v98, off offset:576
	v_cndmask_b32_e64 v98, v85, v81, s[8:9]
	s_nop 1
	v_mov_b32_dpp v99, v98 quad_perm:[1,0,3,2] row_mask:0xf bank_mask:0xf bound_ctrl:1
	v_cndmask_b32_e64 v98, v85, v99, s[6:7]
	v_cndmask_b32_e64 v99, v99, v81, s[6:7]
	v_cvt_pk_bf16_f32 v98, v98, v99
	global_store_dword v[96:97], v98, off offset:640
	v_cndmask_b32_e64 v98, v69, v65, s[8:9]
	s_nop 1
	v_mov_b32_dpp v99, v98 quad_perm:[1,0,3,2] row_mask:0xf bank_mask:0xf bound_ctrl:1
	v_cndmask_b32_e64 v98, v69, v99, s[6:7]
	v_cndmask_b32_e64 v99, v99, v65, s[6:7]
	v_cvt_pk_bf16_f32 v98, v98, v99
	global_store_dword v[96:97], v98, off offset:704
	v_cndmask_b32_e64 v98, v94, v90, s[8:9]
	s_nop 1
	v_mov_b32_dpp v99, v98 quad_perm:[1,0,3,2] row_mask:0xf bank_mask:0xf bound_ctrl:1
	v_cndmask_b32_e64 v98, v94, v99, s[6:7]
	v_cndmask_b32_e64 v99, v99, v90, s[6:7]
	v_cvt_pk_bf16_f32 v98, v98, v99
	global_store_dword v[96:97], v98, off offset:1024
	v_cndmask_b32_e64 v98, v78, v74, s[8:9]
	s_nop 1
	v_mov_b32_dpp v99, v98 quad_perm:[1,0,3,2] row_mask:0xf bank_mask:0xf bound_ctrl:1
	v_cndmask_b32_e64 v98, v78, v99, s[6:7]
	v_cndmask_b32_e64 v99, v99, v74, s[6:7]
	v_cvt_pk_bf16_f32 v98, v98, v99
	global_store_dword v[96:97], v98, off offset:1088
	v_cndmask_b32_e64 v98, v86, v82, s[8:9]
	s_nop 1
	v_mov_b32_dpp v99, v98 quad_perm:[1,0,3,2] row_mask:0xf bank_mask:0xf bound_ctrl:1
	v_cndmask_b32_e64 v98, v86, v99, s[6:7]
	v_cndmask_b32_e64 v99, v99, v82, s[6:7]
	v_cvt_pk_bf16_f32 v98, v98, v99
	global_store_dword v[96:97], v98, off offset:1152
	v_cndmask_b32_e64 v98, v70, v66, s[8:9]
	s_nop 1
	v_mov_b32_dpp v99, v98 quad_perm:[1,0,3,2] row_mask:0xf bank_mask:0xf bound_ctrl:1
	v_cndmask_b32_e64 v98, v70, v99, s[6:7]
	v_cndmask_b32_e64 v99, v99, v66, s[6:7]
	v_cvt_pk_bf16_f32 v98, v98, v99
	global_store_dword v[96:97], v98, off offset:1216
	v_cndmask_b32_e64 v98, v95, v91, s[8:9]
	s_nop 1
	v_mov_b32_dpp v99, v98 quad_perm:[1,0,3,2] row_mask:0xf bank_mask:0xf bound_ctrl:1
	v_cndmask_b32_e64 v98, v95, v99, s[6:7]
	v_cndmask_b32_e64 v99, v99, v91, s[6:7]
	v_cvt_pk_bf16_f32 v98, v98, v99
	global_store_dword v[96:97], v98, off offset:1536
	v_cndmask_b32_e64 v98, v79, v75, s[8:9]
	s_nop 1
	v_mov_b32_dpp v99, v98 quad_perm:[1,0,3,2] row_mask:0xf bank_mask:0xf bound_ctrl:1
	v_cndmask_b32_e64 v98, v79, v99, s[6:7]
	v_cndmask_b32_e64 v99, v99, v75, s[6:7]
	v_cvt_pk_bf16_f32 v98, v98, v99
	global_store_dword v[96:97], v98, off offset:1600
	v_cndmask_b32_e64 v98, v87, v83, s[8:9]
	s_nop 1
	v_mov_b32_dpp v99, v98 quad_perm:[1,0,3,2] row_mask:0xf bank_mask:0xf bound_ctrl:1
	v_cndmask_b32_e64 v98, v87, v99, s[6:7]
	v_cndmask_b32_e64 v99, v99, v83, s[6:7]
	v_cvt_pk_bf16_f32 v98, v98, v99
	global_store_dword v[96:97], v98, off offset:1664
	v_cndmask_b32_e64 v98, v71, v67, s[8:9]
	s_nop 1
	v_mov_b32_dpp v99, v98 quad_perm:[1,0,3,2] row_mask:0xf bank_mask:0xf bound_ctrl:1
	v_cndmask_b32_e64 v98, v71, v99, s[6:7]
	v_cndmask_b32_e64 v99, v99, v67, s[6:7]
	v_cvt_pk_bf16_f32 v98, v98, v99
	global_store_dword v[96:97], v98, off offset:1728

; DEVFI float dpp_xor1(float x) { return __int_as_float(__builtin_amdgcn_update_dpp(0, __float_as_int(x), 0xB1, 0xF, 0xF, true)); }
; #define RG ((bfraw*)(kargs()->ws + O_RG))
; #define SU ((bfraw*)(kargs()->ws + O_SU))
; #define SV ((bfraw*)(kargs()->ws + O_SV))
; #define SVSTAT ((float*)(kargs()->ws + O_SVSTAT))
; DEVFI void store_nat_m(bfraw* base, long ld, f32x4 (&a)[8], int fr) {
;   const bool odd = fr & 1;
;   bfraw* p0 = base + (odd ? 15 + fr : fr);
; #pragma unroll
;   for (int j = 0; j < 4; ++j)
; #pragma unroll
;     for (int n0 = 0; n0 < 8; n0 += 2) { const float own0 = a[n0][j], own1 = a[n0 + 1][j];
;       const float recv = dpp_xor1(odd ? own0 : own1);
;       const unsigned pk = odd ? cvtpk(recv, own1) : cvtpk(own0, recv);
;       *reinterpret_cast<unsigned*>(p0 + (long)j * ld + n0 * 16) = pk; }
; }
; __global__ void __launch_bounds__(512) mega(Params p) {
;     ...
;                     store_nat_m(RG + (long)r0 * 1024 + (c0 - 3072), 1024, a, fr);
;                   } else if (c0 < 6144) {
; #pragma unroll
;                     for (int n = 0; n < 8; ++n)
; #pragma unroll
;                       for (int j = 0; j < 4; ++j) a[n][j] = gelu_tanh(a[n][j]);
;                     if (c0 >= 5120) { float* stp = SVSTAT + (long)r0 * 16 + ((c0 - 5120) >> 7) * 2;
; #pragma unroll
;                       for (int j = 0; j < 4; ++j) { float s1 = 0, s2 = 0;
; #pragma unroll
;                         for (int n = 0; n < 8; ++n) { s1 += a[n][j]; s2 += a[n][j] * a[n][j]; }
;                         s1 = red16(s1); s2 = red16(s2);
;                         if (fr == 0) { stp[j * 16] = s1; stp[j * 16 + 1] = s2; } } }
;                     store_nat_m((c0 < 5120 ? SU + (c0 - 4096) : SV + (c0 - 5120)) + (long)r0 * 1024, 1024, a, fr);
.LBB0_1256:
	s_or_b64 exec, exec, s[2:3]
	v_add_co_u32_e32 v138, vcc, 0x1000, v96
	v_mov_b32_dpp v135, v136 quad_perm:[1,0,3,2] row_mask:0xf bank_mask:0xf bound_ctrl:1
	s_nop 0
	v_addc_co_u32_e32 v139, vcc, 0, v97, vcc
	global_store_dword v[138:139], v134, off offset:2176
	v_cndmask_b32_e64 v134, v124, v135, s[6:7]
	v_cndmask_b32_e64 v135, v135, v98, s[6:7]
	v_cvt_pk_bf16_f32 v134, v134, v135
	v_add_co_u32_e32 v96, vcc, 0x1000, v96
	s_mov_b64 s[2:3], 0
	s_nop 0
	v_addc_co_u32_e32 v97, vcc, 0, v97, vcc
	global_store_dword v[96:97], v134, off offset:2240

; DEVFI float dpp_xor1(float x) { return __int_as_float(__builtin_amdgcn_update_dpp(0, __float_as_int(x), 0xB1, 0xF, 0xF, true)); }
; #define AQ ((bfraw*)(kargs()->ws + O_AQ))
; #define AK ((bfraw*)(kargs()->ws + O_AK))
; DEVFI void store_nat_m(bfraw* base, long ld, f32x4 (&a)[8], int fr) {
;   const bool odd = fr & 1;
;   bfraw* p0 = base + (odd ? 15 + fr : fr);
; #pragma unroll
;   for (int j = 0; j < 4; ++j)
; #pragma unroll
;     for (int n0 = 0; n0 < 8; n0 += 2) { const float own0 = a[n0][j], own1 = a[n0 + 1][j];
;       const float recv = dpp_xor1(odd ? own0 : own1);
;       const unsigned pk = odd ? cvtpk(recv, own1) : cvtpk(own0, recv);
;       *reinterpret_cast<unsigned*>(p0 + (long)j * ld + n0 * 16) = pk; }
; }
; __global__ void __launch_bounds__(512) mega(Params p) {
;     ...
;                     if (isk) store_nat_m(AK + (long)r0 * 256 + (c0 - 7168), 256, a, fr);
;                     else store_nat_m(AQ + (long)r0 * 1024 + (c0 - 6144), 1024, a, fr);
.LBB0_1322:
	s_or_b64 exec, exec, s[2:3]
	s_nop 0
	v_mov_b32_dpp v100, v101 quad_perm:[1,0,3,2] row_mask:0xf bank_mask:0xf bound_ctrl:1
	global_store_dword v[96:97], v99, off offset:1664
	v_cndmask_b32_e64 v99, v124, v100, s[6:7]
	v_cndmask_b32_e64 v100, v100, v98, s[6:7]
	v_cvt_pk_bf16_f32 v99, v99, v100
	global_store_dword v[96:97], v99, off offset:1728

; DEVFI void store_nat_m(bfraw* base, long ld, f32x4 (&a)[8], int fr) {
;   const bool odd = fr & 1;
;   bfraw* p0 = base + (odd ? 15 + fr : fr);
; #pragma unroll
;   for (int j = 0; j < 4; ++j)
; #pragma unroll
;     for (int n0 = 0; n0 < 8; n0 += 2) { const float own0 = a[n0][j], own1 = a[n0 + 1][j];
;       const float recv = dpp_xor1(odd ? own0 : own1);
;       const unsigned pk = odd ? cvtpk(recv, own1) : cvtpk(own0, recv);
;       *reinterpret_cast<unsigned*>(p0 + (long)j * ld + n0 * 16) = pk; }
; }
; __global__ void __launch_bounds__(512) mega(Params p) {
;     ...
;                     store_nat_m((isk ? RK : RQ) + (long)r0 * 1024 + cc, 1024, a, fr);
;                     if (isk) store_tr_m(RKT + ((long)((r0 >> 7) * 8 + head) * 128 + fr) * 128 + (r0 & 127), 128, a);
;                   } else if (c0 < 3072) {
;                     const int head = (c0 - 2048) >> 7;
;                     store_tr_m(RVT + ((long)((r0 >> 7) * 8 + head) * 128 + fr) * 128 + (r0 & 127), 128, a);
;                   } else if (c0 < 4096) {
; #pragma unroll
;                     for (int n = 0; n < 8; ++n)
; #pragma unroll
;                       for (int j = 0; j < 4; ++j) { const float x = a[n][j]; a[n][j] = x * sigmoidf_(x); }
;                     store_nat_m(RG + (long)r0 * 1024 + (c0 - 3072), 1024, a, fr);
;                   } else if (c0 < 6144) {
; #pragma unroll
;                     for (int n = 0; n < 8; ++n)
; #pragma unroll
;                       for (int j = 0; j < 4; ++j) a[n][j] = gelu_tanh(a[n][j]);
;                     if (c0 >= 5120) { float* stp = SVSTAT + (long)r0 * 16 + ((c0 - 5120) >> 7) * 2;
; #pragma unroll
;                       for (int j = 0; j < 4; ++j) { float s1 = 0, s2 = 0;
; #pragma unroll
;                         for (int n = 0; n < 8; ++n) { s1 += a[n][j]; s2 += a[n][j] * a[n][j]; }
;                         s1 = red16(s1); s2 = red16(s2);
;                         if (fr == 0) { stp[j * 16] = s1; stp[j * 16 + 1] = s2; } } }
;                     store_nat_m((c0 < 5120 ? SU + (c0 - 4096) : SV + (c0 - 5120)) + (long)r0 * 1024, 1024, a, fr);
;                   } else if (c0 < 7424) {
;                     const bool isk = c0 >= 7168; const float* nw = isk ? kn_w : qn_w; const float2* attt = ATTT;
; #pragma unroll
;                     for (int j = 0; j < 4; ++j) { const int pos = (r0 + j) & (seqlen - 1);
;                       float ss = 0;
.LBB0_1401:
	s_or_b64 exec, exec, s[2:3]
	v_add_co_u32_e32 v100, vcc, 0x1000, v110
	v_mov_b32_dpp v97, v98 quad_perm:[1,0,3,2] row_mask:0xf bank_mask:0xf bound_ctrl:1
	s_nop 0
	v_addc_co_u32_e32 v101, vcc, 0, v111, vcc
	global_store_dword v[100:101], v96, off offset:2176
	v_cndmask_b32_e64 v96, v120, v97, s[6:7]
	v_cndmask_b32_e64 v97, v97, v132, s[6:7]
	v_cvt_pk_bf16_f32 v96, v96, v97
	v_add_co_u32_e32 v98, vcc, 0x1000, v110
	s_nop 1
	v_addc_co_u32_e32 v99, vcc, 0, v111, vcc
	global_store_dword v[98:99], v96, off offset:2240

; DEVFI void store_nat_m(bfraw* base, long ld, f32x4 (&a)[8], int fr) {
;   const bool odd = fr & 1;
;   bfraw* p0 = base + (odd ? 15 + fr : fr);
; #pragma unroll
;   for (int j = 0; j < 4; ++j)
; #pragma unroll
;     for (int n0 = 0; n0 < 8; n0 += 2) { const float own0 = a[n0][j], own1 = a[n0 + 1][j];
;       const float recv = dpp_xor1(odd ? own0 : own1);
;       const unsigned pk = odd ? cvtpk(recv, own1) : cvtpk(own0, recv);
;       *reinterpret_cast<unsigned*>(p0 + (long)j * ld + n0 * 16) = pk; }
; }
; __global__ void __launch_bounds__(512) mega(Params p) {
;     ...
;                     store_nat_m((isk ? RK : RQ) + (long)r0 * 1024 + cc, 1024, a, fr);
;                     if (isk) store_tr_m(RKT + ((long)((r0 >> 7) * 8 + head) * 128 + fr) * 128 + (r0 & 127), 128, a);
;                   } else if (c0 < 3072) {
;                     const int head = (c0 - 2048) >> 7;
;                     store_tr_m(RVT + ((long)((r0 >> 7) * 8 + head) * 128 + fr) * 128 + (r0 & 127), 128, a);
;                   } else if (c0 < 4096) {
; #pragma unroll
;                     for (int n = 0; n < 8; ++n)
; #pragma unroll
;                       for (int j = 0; j < 4; ++j) { const float x = a[n][j]; a[n][j] = x * sigmoidf_(x); }
;                     store_nat_m(RG + (long)r0 * 1024 + (c0 - 3072), 1024, a, fr);
;                   } else if (c0 < 6144) {
; #pragma unroll
;                     for (int n = 0; n < 8; ++n)
; #pragma unroll
;                       for (int j = 0; j < 4; ++j) a[n][j] = gelu_tanh(a[n][j]);
;                     if (c0 >= 5120) { float* stp = SVSTAT + (long)r0 * 16 + ((c0 - 5120) >> 7) * 2;
; #pragma unroll
;                       for (int j = 0; j < 4; ++j) { float s1 = 0, s2 = 0;
; #pragma unroll
;                         for (int n = 0; n < 8; ++n) { s1 += a[n][j]; s2 += a[n][j] * a[n][j]; }
;                         s1 = red16(s1); s2 = red16(s2);
;                         if (fr == 0) { stp[j * 16] = s1; stp[j * 16 + 1] = s2; } } }
;                     store_nat_m((c0 < 5120 ? SU + (c0 - 4096) : SV + (c0 - 5120)) + (long)r0 * 1024, 1024, a, fr);
;                   } else if (c0 < 7424) {
;                     const bool isk = c0 >= 7168; const float* nw = isk ? kn_w : qn_w; const float2* attt = ATTT;
; #pragma unroll
;                     for (int j = 0; j < 4; ++j) { const int pos = (r0 + j) & (seqlen - 1);
;                       float ss = 0;
.LBB0_1468:
	s_or_b64 exec, exec, s[2:3]
	v_add_co_u32_e32 v104, vcc, 0x1000, v96
	s_nop 1
	v_addc_co_u32_e32 v105, vcc, 0, v97, vcc
	global_store_dword v[104:105], v100, off offset:2176
	v_mov_b32_dpp v100, v102 quad_perm:[1,0,3,2] row_mask:0xf bank_mask:0xf bound_ctrl:1
	v_cndmask_b32_e64 v99, v98, v100, s[6:7]
	v_cndmask_b32_e64 v100, v100, v101, s[6:7]
	v_cvt_pk_bf16_f32 v99, v99, v100
	v_add_co_u32_e32 v96, vcc, 0x1000, v96
	s_nop 1
	v_addc_co_u32_e32 v97, vcc, 0, v97, vcc
	global_store_dword v[96:97], v99, off offset:2240

; DEVFI float dpp_xor1(float x) { return __int_as_float(__builtin_amdgcn_update_dpp(0, __float_as_int(x), 0xB1, 0xF, 0xF, true)); }
; DEVFI void store_nat_m(bfraw* base, long ld, f32x4 (&a)[8], int fr) {
;   const bool odd = fr & 1;
;   bfraw* p0 = base + (odd ? 15 + fr : fr);
; #pragma unroll
;   for (int j = 0; j < 4; ++j)
; #pragma unroll
;     for (int n0 = 0; n0 < 8; n0 += 2) { const float own0 = a[n0][j], own1 = a[n0 + 1][j];
;       const float recv = dpp_xor1(odd ? own0 : own1);
;       const unsigned pk = odd ? cvtpk(recv, own1) : cvtpk(own0, recv);
;       *reinterpret_cast<unsigned*>(p0 + (long)j * ld + n0 * 16) = pk; }
; }
; DEVFI void store_tr_m(bfraw* dstT, long ldT, f32x4 (&a)[8]) {
; #pragma unroll
;   for (int n = 0; n < 8; ++n) { u32x2 w = {cvtpk(a[n][0], a[n][1]), cvtpk(a[n][2], a[n][3])};
;     *reinterpret_cast<u32x2*>(dstT + (long)(n * 16) * ldT) = w; }
; }
.LBB0_1541:
	s_or_b64 exec, exec, s[2:3]
	v_add_co_u32_e32 v98, vcc, 0x1000, v130
	v_mov_b32_dpp v95, v96 quad_perm:[1,0,3,2] row_mask:0xf bank_mask:0xf bound_ctrl:1
	s_nop 0
	v_addc_co_u32_e32 v99, vcc, 0, v131, vcc
	global_store_dword v[98:99], v91, off offset:2176
	v_cndmask_b32_e64 v91, v79, v95, s[8:9]
	v_cndmask_b32_e64 v95, v95, v75, s[8:9]
	v_cvt_pk_bf16_f32 v91, v91, v95
	v_add_co_u32_e32 v96, vcc, 0x1000, v130
	s_nop 1
	v_addc_co_u32_e32 v97, vcc, 0, v131, vcc
	global_store_dword v[96:97], v91, off offset:2240
	s_and_saveexec_b64 s[2:3], s[6:7]
	s_cbranch_execz .LBB0_1547
	s_mov_b64 s[6:7], s[0:1]
	s_load_dwordx2 s[6:7], s[6:7], 0xe8
	v_lshrrev_b32_e32 v75, 7, v138
	v_ashrrev_i32_e32 v79, 4, v128
	v_and_or_b32 v96, v79, -8, v75
	v_ashrrev_i32_e32 v97, 31, v96
	v_lshlrev_b64 v[96:97], 15, v[96:97]
	s_waitcnt lgkmcnt(0)
	v_lshl_add_u64 v[96:97], s[6:7], 0, v[96:97]
	v_lshlrev_b32_e32 v98, 8, v202
	v_mov_b32_e32 v99, v177
	v_and_b32_e32 v75, 0x7f, v128
	v_lshl_add_u64 v[96:97], v[96:97], 0, v[98:99]
	v_lshlrev_b32_e32 v98, 1, v75
	v_lshl_add_u64 v[96:97], v[96:97], 0, v[98:99]
	s_mov_b32 s6, 0x15721000
	v_cvt_pk_bf16_f32 v76, v135, v76
	v_cvt_pk_bf16_f32 v77, v77, v78
	v_add_co_u32_e32 v78, vcc, s6, v96
	s_mov_b32 s6, 0x15723000
	s_nop 0
	v_addc_co_u32_e32 v79, vcc, 0, v97, vcc
	global_store_dwordx2 v[78:79], v[76:77], off offset:-4096
	v_cvt_pk_bf16_f32 v72, v134, v72
	v_cvt_pk_bf16_f32 v73, v73, v74
	v_add_co_u32_e32 v74, vcc, s6, v96
	global_store_dwordx2 v[78:79], v[72:73], off
	v_cvt_pk_bf16_f32 v72, v137, v92
	v_cvt_pk_bf16_f32 v73, v93, v94
	s_nop 0
	v_addc_co_u32_e32 v75, vcc, 0, v97, vcc
	s_mov_b32 s6, 0x15725000
	global_store_dwordx2 v[74:75], v[72:73], off offset:-4096
	v_cvt_pk_bf16_f32 v72, v136, v88
	v_cvt_pk_bf16_f32 v73, v89, v90
	global_store_dwordx2 v[74:75], v[72:73], off
	v_add_co_u32_e32 v74, vcc, s6, v96
	v_cvt_pk_bf16_f32 v72, v84, v85
	v_cvt_pk_bf16_f32 v73, v86, v87
	s_mov_b32 s6, 0x15726000
	s_nop 0
	v_addc_co_u32_e32 v75, vcc, 0, v97, vcc
	global_store_dwordx2 v[74:75], v[72:73], off offset:-4096
	v_cvt_pk_bf16_f32 v72, v80, v81
	v_cvt_pk_bf16_f32 v73, v82, v83
	global_store_dwordx2 v[74:75], v[72:73], off
	v_cvt_pk_bf16_f32 v68, v68, v69
	v_cvt_pk_bf16_f32 v69, v70, v71
	v_add_co_u32_e32 v70, vcc, s6, v96
	s_nop 1
	v_addc_co_u32_e32 v71, vcc, 0, v97, vcc
	global_store_dwordx2 v[70:71], v[68:69], off
	v_cvt_pk_bf16_f32 v64, v64, v65
	v_cvt_pk_bf16_f32 v65, v66, v67
	v_add_co_u32_e32 v66, vcc, 0x15727000, v96
	s_nop 1
	v_addc_co_u32_e32 v67, vcc, 0, v97, vcc
	global_store_dwordx2 v[66:67], v[64:65], off

; DEVFI float dpp_xor1(float x) { return __int_as_float(__builtin_amdgcn_update_dpp(0, __float_as_int(x), 0xB1, 0xF, 0xF, true)); }
; #define AQ ((bfraw*)(kargs()->ws + O_AQ))
; #define AK ((bfraw*)(kargs()->ws + O_AK))
; #define AV ((bfraw*)(kargs()->ws + O_AV))
; DEVFI void store_nat_m(bfraw* base, long ld, f32x4 (&a)[8], int fr) {
;   const bool odd = fr & 1;
;   bfraw* p0 = base + (odd ? 15 + fr : fr);
; #pragma unroll
;   for (int j = 0; j < 4; ++j)
; #pragma unroll
;     for (int n0 = 0; n0 < 8; n0 += 2) { const float own0 = a[n0][j], own1 = a[n0 + 1][j];
;       const float recv = dpp_xor1(odd ? own0 : own1);
;       const unsigned pk = odd ? cvtpk(recv, own1) : cvtpk(own0, recv);
;       *reinterpret_cast<unsigned*>(p0 + (long)j * ld + n0 * 16) = pk; }
; }
; __global__ void __launch_bounds__(512) mega(Params p) {
;     ...
;                     if (isk) store_nat_m(AK + (long)r0 * 256 + (c0 - 7168), 256, a, fr);
;                     else store_nat_m(AQ + (long)r0 * 1024 + (c0 - 6144), 1024, a, fr);
;                   } else if (c0 < 7680) {
;                     store_nat_m(AV + (long)r0 * 256 + (c0 - 7424), 256, a, fr);
.LBB0_1555:
	s_andn2_b64 vcc, exec, s[2:3]
	s_cbranch_vccnz .LBB0_1621
	s_mov_b64 s[2:3], s[0:1]
	s_load_dwordx2 s[2:3], s[2:3], 0xe8
	v_and_b32_e32 v64, 1, v203
	v_cmp_eq_u32_e64 s[8:9], 0, v64
	v_cmp_eq_u32_e64 s[6:7], 1, v64
	s_nop 0
	v_cndmask_b32_e64 v64, v60, v56, s[8:9]
	s_nop 1
	v_mov_b32_dpp v64, v64 quad_perm:[1,0,3,2] row_mask:0xf bank_mask:0xf bound_ctrl:1
	v_cndmask_b32_e64 v66, v60, v64, s[6:7]
	v_cndmask_b32_e64 v64, v64, v56, s[6:7]
	v_cvt_pk_bf16_f32 v66, v66, v64
	v_ashrrev_i32_e32 v97, 31, v96
	v_lshlrev_b64 v[64:65], 9, v[96:97]
	v_add_u32_e32 v67, 15, v202
	s_waitcnt lgkmcnt(0)
	v_lshl_add_u64 v[64:65], s[2:3], 0, v[64:65]
	v_cndmask_b32_e64 v67, v67, v202, s[8:9]
	v_lshl_add_u64 v[64:65], v[176:177], 1, v[64:65]
	v_lshlrev_b32_e32 v68, 1, v67
	v_mov_b32_e32 v69, v177
	v_lshl_add_u64 v[64:65], v[64:65], 0, v[68:69]
	v_add_co_u32_e32 v68, vcc, 0x21f1c000, v64
	s_nop 1
	v_addc_co_u32_e32 v69, vcc, 0, v65, vcc
	global_store_dword v[68:69], v66, off offset:1536
	v_cndmask_b32_e64 v66, v44, v40, s[8:9]
	s_nop 1
	v_mov_b32_dpp v67, v66 quad_perm:[1,0,3,2] row_mask:0xf bank_mask:0xf bound_ctrl:1
	v_cndmask_b32_e64 v66, v44, v67, s[6:7]
	v_cndmask_b32_e64 v67, v67, v40, s[6:7]
	v_cvt_pk_bf16_f32 v66, v66, v67
	s_mov_b64 s[2:3], 0x21f1c600
	v_lshl_add_u64 v[64:65], v[64:65], 0, s[2:3]
	global_store_dword v[64:65], v66, off offset:64
	v_cndmask_b32_e64 v66, v52, v48, s[8:9]
	s_nop 1
	v_mov_b32_dpp v67, v66 quad_perm:[1,0,3,2] row_mask:0xf bank_mask:0xf bound_ctrl:1
	v_cndmask_b32_e64 v66, v52, v67, s[6:7]
	v_cndmask_b32_e64 v67, v67, v48, s[6:7]
	v_cvt_pk_bf16_f32 v66, v66, v67
	global_store_dword v[64:65], v66, off offset:128
	v_cndmask_b32_e64 v66, v36, v32, s[8:9]
	s_nop 1
	v_mov_b32_dpp v67, v66 quad_perm:[1,0,3,2] row_mask:0xf bank_mask:0xf bound_ctrl:1
	v_cndmask_b32_e64 v66, v36, v67, s[6:7]
	v_cndmask_b32_e64 v67, v67, v32, s[6:7]
	v_cvt_pk_bf16_f32 v66, v66, v67
	global_store_dword v[64:65], v66, off offset:192
	v_cndmask_b32_e64 v66, v61, v57, s[8:9]
	s_nop 1
	v_mov_b32_dpp v67, v66 quad_perm:[1,0,3,2] row_mask:0xf bank_mask:0xf bound_ctrl:1
	v_cndmask_b32_e64 v66, v61, v67, s[6:7]
	v_cndmask_b32_e64 v67, v67, v57, s[6:7]
	v_cvt_pk_bf16_f32 v66, v66, v67
	global_store_dword v[64:65], v66, off offset:512
	v_cndmask_b32_e64 v66, v45, v41, s[8:9]
	s_nop 1
	v_mov_b32_dpp v67, v66 quad_perm:[1,0,3,2] row_mask:0xf bank_mask:0xf bound_ctrl:1
	v_cndmask_b32_e64 v66, v45, v67, s[6:7]
	v_cndmask_b32_e64 v67, v67, v41, s[6:7]
	v_cvt_pk_bf16_f32 v66, v66, v67
	global_store_dword v[64:65], v66, off offset:576
	v_cndmask_b32_e64 v66, v53, v49, s[8:9]
	s_nop 1
	v_mov_b32_dpp v67, v66 quad_perm:[1,0,3,2] row_mask:0xf bank_mask:0xf bound_ctrl:1
	v_cndmask_b32_e64 v66, v53, v67, s[6:7]
	v_cndmask_b32_e64 v67, v67, v49, s[6:7]
	v_cvt_pk_bf16_f32 v66, v66, v67
	global_store_dword v[64:65], v66, off offset:640
	v_cndmask_b32_e64 v66, v37, v33, s[8:9]
	s_nop 1
	v_mov_b32_dpp v67, v66 quad_perm:[1,0,3,2] row_mask:0xf bank_mask:0xf bound_ctrl:1
	v_cndmask_b32_e64 v66, v37, v67, s[6:7]
	v_cndmask_b32_e64 v67, v67, v33, s[6:7]
	v_cvt_pk_bf16_f32 v66, v66, v67
	global_store_dword v[64:65], v66, off offset:704
	v_cndmask_b32_e64 v66, v62, v58, s[8:9]
	s_nop 1
	v_mov_b32_dpp v67, v66 quad_perm:[1,0,3,2] row_mask:0xf bank_mask:0xf bound_ctrl:1
	v_cndmask_b32_e64 v66, v62, v67, s[6:7]
	v_cndmask_b32_e64 v67, v67, v58, s[6:7]
	v_cvt_pk_bf16_f32 v66, v66, v67
	global_store_dword v[64:65], v66, off offset:1024
	v_cndmask_b32_e64 v66, v46, v42, s[8:9]
	s_nop 1
	v_mov_b32_dpp v67, v66 quad_perm:[1,0,3,2] row_mask:0xf bank_mask:0xf bound_ctrl:1
	v_cndmask_b32_e64 v66, v46, v67, s[6:7]
	v_cndmask_b32_e64 v67, v67, v42, s[6:7]
	v_cvt_pk_bf16_f32 v66, v66, v67
	global_store_dword v[64:65], v66, off offset:1088
	v_cndmask_b32_e64 v66, v54, v50, s[8:9]
	s_nop 1
	v_mov_b32_dpp v67, v66 quad_perm:[1,0,3,2] row_mask:0xf bank_mask:0xf bound_ctrl:1
	v_cndmask_b32_e64 v66, v54, v67, s[6:7]
	v_cndmask_b32_e64 v67, v67, v50, s[6:7]
	v_cvt_pk_bf16_f32 v66, v66, v67
	global_store_dword v[64:65], v66, off offset:1152
	v_cndmask_b32_e64 v66, v38, v34, s[8:9]
	s_nop 1
	v_mov_b32_dpp v67, v66 quad_perm:[1,0,3,2] row_mask:0xf bank_mask:0xf bound_ctrl:1
	v_cndmask_b32_e64 v66, v38, v67, s[6:7]
	v_cndmask_b32_e64 v67, v67, v34, s[6:7]
	v_cvt_pk_bf16_f32 v66, v66, v67
	global_store_dword v[64:65], v66, off offset:1216
	v_cndmask_b32_e64 v66, v63, v59, s[8:9]
	s_nop 1
	v_mov_b32_dpp v67, v66 quad_perm:[1,0,3,2] row_mask:0xf bank_mask:0xf bound_ctrl:1
	v_cndmask_b32_e64 v66, v63, v67, s[6:7]
	v_cndmask_b32_e64 v67, v67, v59, s[6:7]
	v_cvt_pk_bf16_f32 v66, v66, v67
	global_store_dword v[64:65], v66, off offset:1536
	v_cndmask_b32_e64 v66, v47, v43, s[8:9]
	s_nop 1
	v_mov_b32_dpp v67, v66 quad_perm:[1,0,3,2] row_mask:0xf bank_mask:0xf bound_ctrl:1
	v_cndmask_b32_e64 v66, v47, v67, s[6:7]
	v_cndmask_b32_e64 v67, v67, v43, s[6:7]
	v_cvt_pk_bf16_f32 v66, v66, v67
	global_store_dword v[64:65], v66, off offset:1600
	v_cndmask_b32_e64 v66, v55, v51, s[8:9]
	s_nop 1
	v_mov_b32_dpp v67, v66 quad_perm:[1,0,3,2] row_mask:0xf bank_mask:0xf bound_ctrl:1
	v_cndmask_b32_e64 v66, v55, v67, s[6:7]
	v_cndmask_b32_e64 v67, v67, v51, s[6:7]
	v_cvt_pk_bf16_f32 v66, v66, v67
	global_store_dword v[64:65], v66, off offset:1664
	v_cndmask_b32_e64 v66, v39, v35, s[8:9]
	s_nop 1
	v_mov_b32_dpp v67, v66 quad_perm:[1,0,3,2] row_mask:0xf bank_mask:0xf bound_ctrl:1
	v_cndmask_b32_e64 v66, v39, v67, s[6:7]
	v_cndmask_b32_e64 v67, v67, v35, s[6:7]
	v_cvt_pk_bf16_f32 v66, v66, v67
	global_store_dword v[64:65], v66, off offset:1728

; DEVFI float dpp_xor1(float x) { return __int_as_float(__builtin_amdgcn_update_dpp(0, __float_as_int(x), 0xB1, 0xF, 0xF, true)); }
; #define RG ((bfraw*)(kargs()->ws + O_RG))
; #define SU ((bfraw*)(kargs()->ws + O_SU))
; #define SV ((bfraw*)(kargs()->ws + O_SV))
; #define SVSTAT ((float*)(kargs()->ws + O_SVSTAT))
; DEVFI void store_nat_m(bfraw* base, long ld, f32x4 (&a)[8], int fr) {
;   const bool odd = fr & 1;
;   bfraw* p0 = base + (odd ? 15 + fr : fr);
; #pragma unroll
;   for (int j = 0; j < 4; ++j)
; #pragma unroll
;     for (int n0 = 0; n0 < 8; n0 += 2) { const float own0 = a[n0][j], own1 = a[n0 + 1][j];
;       const float recv = dpp_xor1(odd ? own0 : own1);
;       const unsigned pk = odd ? cvtpk(recv, own1) : cvtpk(own0, recv);
;       *reinterpret_cast<unsigned*>(p0 + (long)j * ld + n0 * 16) = pk; }
; }
; __global__ void __launch_bounds__(512) mega(Params p) {
;     ...
;                     store_nat_m(RG + (long)r0 * 1024 + (c0 - 3072), 1024, a, fr);
;                   } else if (c0 < 6144) {
; #pragma unroll
;                     for (int n = 0; n < 8; ++n)
; #pragma unroll
;                       for (int j = 0; j < 4; ++j) a[n][j] = gelu_tanh(a[n][j]);
;                     if (c0 >= 5120) { float* stp = SVSTAT + (long)r0 * 16 + ((c0 - 5120) >> 7) * 2;
; #pragma unroll
;                       for (int j = 0; j < 4; ++j) { float s1 = 0, s2 = 0;
; #pragma unroll
;                         for (int n = 0; n < 8; ++n) { s1 += a[n][j]; s2 += a[n][j] * a[n][j]; }
;                         s1 = red16(s1); s2 = red16(s2);
;                         if (fr == 0) { stp[j * 16] = s1; stp[j * 16 + 1] = s2; } } }
;                     store_nat_m((c0 < 5120 ? SU + (c0 - 4096) : SV + (c0 - 5120)) + (long)r0 * 1024, 1024, a, fr);
.LBB0_1688:
	s_or_b64 exec, exec, s[2:3]
	v_add_co_u32_e32 v106, vcc, 0x1000, v64
	v_mov_b32_dpp v103, v104 quad_perm:[1,0,3,2] row_mask:0xf bank_mask:0xf bound_ctrl:1
	s_nop 0
	v_addc_co_u32_e32 v107, vcc, 0, v65, vcc
	global_store_dword v[106:107], v102, off offset:2176
	v_cndmask_b32_e64 v102, v92, v103, s[6:7]
	v_cndmask_b32_e64 v103, v103, v66, s[6:7]
	v_cvt_pk_bf16_f32 v102, v102, v103
	v_add_co_u32_e32 v64, vcc, 0x1000, v64
	s_mov_b64 s[2:3], 0
	s_nop 0
	v_addc_co_u32_e32 v65, vcc, 0, v65, vcc
	global_store_dword v[64:65], v102, off offset:2240

; DEVFI float dpp_xor1(float x) { return __int_as_float(__builtin_amdgcn_update_dpp(0, __float_as_int(x), 0xB1, 0xF, 0xF, true)); }
; #define AQ ((bfraw*)(kargs()->ws + O_AQ))
; #define AK ((bfraw*)(kargs()->ws + O_AK))
; DEVFI void store_nat_m(bfraw* base, long ld, f32x4 (&a)[8], int fr) {
;   const bool odd = fr & 1;
;   bfraw* p0 = base + (odd ? 15 + fr : fr);
; #pragma unroll
;   for (int j = 0; j < 4; ++j)
; #pragma unroll
;     for (int n0 = 0; n0 < 8; n0 += 2) { const float own0 = a[n0][j], own1 = a[n0 + 1][j];
;       const float recv = dpp_xor1(odd ? own0 : own1);
;       const unsigned pk = odd ? cvtpk(recv, own1) : cvtpk(own0, recv);
;       *reinterpret_cast<unsigned*>(p0 + (long)j * ld + n0 * 16) = pk; }
; }
; __global__ void __launch_bounds__(512) mega(Params p) {
;     ...
;                     if (isk) store_nat_m(AK + (long)r0 * 256 + (c0 - 7168), 256, a, fr);
;                     else store_nat_m(AQ + (long)r0 * 1024 + (c0 - 6144), 1024, a, fr);
.LBB0_1754:
	s_or_b64 exec, exec, s[2:3]
	s_nop 0
	v_mov_b32_dpp v68, v69 quad_perm:[1,0,3,2] row_mask:0xf bank_mask:0xf bound_ctrl:1
	global_store_dword v[64:65], v67, off offset:1664
	v_cndmask_b32_e64 v67, v92, v68, s[6:7]
	v_cndmask_b32_e64 v68, v68, v66, s[6:7]
	v_cvt_pk_bf16_f32 v67, v67, v68
	global_store_dword v[64:65], v67, off offset:1728

; DEVFI void store_nat_m(bfraw* base, long ld, f32x4 (&a)[8], int fr) {
;   const bool odd = fr & 1;
;   bfraw* p0 = base + (odd ? 15 + fr : fr);
; #pragma unroll
;   for (int j = 0; j < 4; ++j)
; #pragma unroll
;     for (int n0 = 0; n0 < 8; n0 += 2) { const float own0 = a[n0][j], own1 = a[n0 + 1][j];
;       const float recv = dpp_xor1(odd ? own0 : own1);
;       const unsigned pk = odd ? cvtpk(recv, own1) : cvtpk(own0, recv);
;       *reinterpret_cast<unsigned*>(p0 + (long)j * ld + n0 * 16) = pk; }
; }
; __global__ void __launch_bounds__(512) mega(Params p) {
;     ...
;                     store_nat_m((isk ? RK : RQ) + (long)r0 * 1024 + cc, 1024, a, fr);
;                     if (isk) store_tr_m(RKT + ((long)((r0 >> 7) * 8 + head) * 128 + fr) * 128 + (r0 & 127), 128, a);
;                   } else if (c0 < 3072) {
;                     const int head = (c0 - 2048) >> 7;
;                     store_tr_m(RVT + ((long)((r0 >> 7) * 8 + head) * 128 + fr) * 128 + (r0 & 127), 128, a);
;                   } else if (c0 < 4096) {
; #pragma unroll
;                     for (int n = 0; n < 8; ++n)
; #pragma unroll
;                       for (int j = 0; j < 4; ++j) { const float x = a[n][j]; a[n][j] = x * sigmoidf_(x); }
;                     store_nat_m(RG + (long)r0 * 1024 + (c0 - 3072), 1024, a, fr);
;                   } else if (c0 < 6144) {
; #pragma unroll
;                     for (int n = 0; n < 8; ++n)
; #pragma unroll
;                       for (int j = 0; j < 4; ++j) a[n][j] = gelu_tanh(a[n][j]);
;                     if (c0 >= 5120) { float* stp = SVSTAT + (long)r0 * 16 + ((c0 - 5120) >> 7) * 2;
; #pragma unroll
;                       for (int j = 0; j < 4; ++j) { float s1 = 0, s2 = 0;
; #pragma unroll
;                         for (int n = 0; n < 8; ++n) { s1 += a[n][j]; s2 += a[n][j] * a[n][j]; }
;                         s1 = red16(s1); s2 = red16(s2);
;                         if (fr == 0) { stp[j * 16] = s1; stp[j * 16 + 1] = s2; } } }
;                     store_nat_m((c0 < 5120 ? SU + (c0 - 4096) : SV + (c0 - 5120)) + (long)r0 * 1024, 1024, a, fr);
;                   } else if (c0 < 7424) {
;                     const bool isk = c0 >= 7168; const float* nw = isk ? kn_w : qn_w; const float2* attt = ATTT;
; #pragma unroll
;                     for (int j = 0; j < 4; ++j) { const int pos = (r0 + j) & (seqlen - 1);
;                       float ss = 0;
.LBB0_1833:
	s_or_b64 exec, exec, s[2:3]
	v_add_co_u32_e32 v68, vcc, 0x1000, v78
	v_mov_b32_dpp v65, v66 quad_perm:[1,0,3,2] row_mask:0xf bank_mask:0xf bound_ctrl:1
	s_nop 0
	v_addc_co_u32_e32 v69, vcc, 0, v79, vcc
	global_store_dword v[68:69], v64, off offset:2176
	v_cndmask_b32_e64 v64, v88, v65, s[6:7]
	v_cndmask_b32_e64 v65, v65, v100, s[6:7]
	v_cvt_pk_bf16_f32 v64, v64, v65
	v_add_co_u32_e32 v66, vcc, 0x1000, v78
	s_nop 1
	v_addc_co_u32_e32 v67, vcc, 0, v79, vcc
	global_store_dword v[66:67], v64, off offset:2240

; DEVFI void store_nat_m(bfraw* base, long ld, f32x4 (&a)[8], int fr) {
;   const bool odd = fr & 1;
;   bfraw* p0 = base + (odd ? 15 + fr : fr);
; #pragma unroll
;   for (int j = 0; j < 4; ++j)
; #pragma unroll
;     for (int n0 = 0; n0 < 8; n0 += 2) { const float own0 = a[n0][j], own1 = a[n0 + 1][j];
;       const float recv = dpp_xor1(odd ? own0 : own1);
;       const unsigned pk = odd ? cvtpk(recv, own1) : cvtpk(own0, recv);
;       *reinterpret_cast<unsigned*>(p0 + (long)j * ld + n0 * 16) = pk; }
; }
; __global__ void __launch_bounds__(512) mega(Params p) {
;     ...
;                     store_nat_m((isk ? RK : RQ) + (long)r0 * 1024 + cc, 1024, a, fr);
;                     if (isk) store_tr_m(RKT + ((long)((r0 >> 7) * 8 + head) * 128 + fr) * 128 + (r0 & 127), 128, a);
;                   } else if (c0 < 3072) {
;                     const int head = (c0 - 2048) >> 7;
;                     store_tr_m(RVT + ((long)((r0 >> 7) * 8 + head) * 128 + fr) * 128 + (r0 & 127), 128, a);
;                   } else if (c0 < 4096) {
; #pragma unroll
;                     for (int n = 0; n < 8; ++n)
; #pragma unroll
;                       for (int j = 0; j < 4; ++j) { const float x = a[n][j]; a[n][j] = x * sigmoidf_(x); }
;                     store_nat_m(RG + (long)r0 * 1024 + (c0 - 3072), 1024, a, fr);
;                   } else if (c0 < 6144) {
; #pragma unroll
;                     for (int n = 0; n < 8; ++n)
; #pragma unroll
;                       for (int j = 0; j < 4; ++j) a[n][j] = gelu_tanh(a[n][j]);
;                     if (c0 >= 5120) { float* stp = SVSTAT + (long)r0 * 16 + ((c0 - 5120) >> 7) * 2;
; #pragma unroll
;                       for (int j = 0; j < 4; ++j) { float s1 = 0, s2 = 0;
; #pragma unroll
;                         for (int n = 0; n < 8; ++n) { s1 += a[n][j]; s2 += a[n][j] * a[n][j]; }
;                         s1 = red16(s1); s2 = red16(s2);
;                         if (fr == 0) { stp[j * 16] = s1; stp[j * 16 + 1] = s2; } } }
;                     store_nat_m((c0 < 5120 ? SU + (c0 - 4096) : SV + (c0 - 5120)) + (long)r0 * 1024, 1024, a, fr);
;                   } else if (c0 < 7424) {
;                     const bool isk = c0 >= 7168; const float* nw = isk ? kn_w : qn_w; const float2* attt = ATTT;
; #pragma unroll
;                     for (int j = 0; j < 4; ++j) { const int pos = (r0 + j) & (seqlen - 1);
;                       float ss = 0;
.LBB0_1900:
	s_or_b64 exec, exec, s[2:3]
	v_add_co_u32_e32 v72, vcc, 0x1000, v64
	s_nop 1
	v_addc_co_u32_e32 v73, vcc, 0, v65, vcc
	global_store_dword v[72:73], v68, off offset:2176
	v_mov_b32_dpp v68, v70 quad_perm:[1,0,3,2] row_mask:0xf bank_mask:0xf bound_ctrl:1
	v_cndmask_b32_e64 v67, v66, v68, s[6:7]
	v_cndmask_b32_e64 v68, v68, v69, s[6:7]
	v_cvt_pk_bf16_f32 v67, v67, v68
	v_add_co_u32_e32 v64, vcc, 0x1000, v64
	s_nop 1
	v_addc_co_u32_e32 v65, vcc, 0, v65, vcc
	global_store_dword v[64:65], v67, off offset:2240

; DEVFI float dpp_xor1(float x) { return __int_as_float(__builtin_amdgcn_update_dpp(0, __float_as_int(x), 0xB1, 0xF, 0xF, true)); }
; DEVFI void store_nat_m(bfraw* base, long ld, f32x4 (&a)[8], int fr) {
;   const bool odd = fr & 1;
;   bfraw* p0 = base + (odd ? 15 + fr : fr);
; #pragma unroll
;   for (int j = 0; j < 4; ++j)
; #pragma unroll
;     for (int n0 = 0; n0 < 8; n0 += 2) { const float own0 = a[n0][j], own1 = a[n0 + 1][j];
;       const float recv = dpp_xor1(odd ? own0 : own1);
;       const unsigned pk = odd ? cvtpk(recv, own1) : cvtpk(own0, recv);
;       *reinterpret_cast<unsigned*>(p0 + (long)j * ld + n0 * 16) = pk; }
; }
; DEVFI void store_tr_m(bfraw* dstT, long ldT, f32x4 (&a)[8]) {
; #pragma unroll
;   for (int n = 0; n < 8; ++n) { u32x2 w = {cvtpk(a[n][0], a[n][1]), cvtpk(a[n][2], a[n][3])};
;     *reinterpret_cast<u32x2*>(dstT + (long)(n * 16) * ldT) = w; }
; }
.LBB0_1973:
	s_or_b64 exec, exec, s[2:3]
	v_add_co_u32_e32 v66, vcc, 0x1000, v98
	v_mov_b32_dpp v63, v64 quad_perm:[1,0,3,2] row_mask:0xf bank_mask:0xf bound_ctrl:1
	s_nop 0
	v_addc_co_u32_e32 v67, vcc, 0, v99, vcc
	global_store_dword v[66:67], v59, off offset:2176
	v_cndmask_b32_e64 v59, v47, v63, s[8:9]
	v_cndmask_b32_e64 v63, v63, v43, s[8:9]
	v_cvt_pk_bf16_f32 v59, v59, v63
	v_add_co_u32_e32 v64, vcc, 0x1000, v98
	s_nop 1
	v_addc_co_u32_e32 v65, vcc, 0, v99, vcc
	global_store_dword v[64:65], v59, off offset:2240
	s_and_saveexec_b64 s[2:3], s[6:7]
	s_cbranch_execz .LBB0_1979
	s_mov_b64 s[6:7], s[0:1]
	s_load_dwordx2 s[6:7], s[6:7], 0xe8
	v_lshrrev_b32_e32 v43, 7, v106
	v_ashrrev_i32_e32 v47, 4, v96
	v_and_or_b32 v64, v47, -8, v43
	v_ashrrev_i32_e32 v65, 31, v64
	v_lshlrev_b64 v[64:65], 15, v[64:65]
	s_waitcnt lgkmcnt(0)
	v_lshl_add_u64 v[64:65], s[6:7], 0, v[64:65]
	v_lshlrev_b32_e32 v66, 8, v202
	v_mov_b32_e32 v67, v177
	v_and_b32_e32 v43, 0x7f, v96
	v_lshl_add_u64 v[64:65], v[64:65], 0, v[66:67]
	v_lshlrev_b32_e32 v66, 1, v43
	v_lshl_add_u64 v[64:65], v[64:65], 0, v[66:67]
	s_mov_b32 s6, 0x15721000
	v_cvt_pk_bf16_f32 v44, v103, v44
	v_cvt_pk_bf16_f32 v45, v45, v46
	v_add_co_u32_e32 v46, vcc, s6, v64
	s_mov_b32 s6, 0x15723000
	s_nop 0
	v_addc_co_u32_e32 v47, vcc, 0, v65, vcc
	global_store_dwordx2 v[46:47], v[44:45], off offset:-4096
	v_cvt_pk_bf16_f32 v40, v102, v40
	v_cvt_pk_bf16_f32 v41, v41, v42
	v_add_co_u32_e32 v42, vcc, s6, v64
	global_store_dwordx2 v[46:47], v[40:41], off
	v_cvt_pk_bf16_f32 v40, v105, v60
	v_cvt_pk_bf16_f32 v41, v61, v62
	s_nop 0
	v_addc_co_u32_e32 v43, vcc, 0, v65, vcc
	s_mov_b32 s6, 0x15725000
	global_store_dwordx2 v[42:43], v[40:41], off offset:-4096
	v_cvt_pk_bf16_f32 v40, v104, v56
	v_cvt_pk_bf16_f32 v41, v57, v58
	global_store_dwordx2 v[42:43], v[40:41], off
	v_add_co_u32_e32 v42, vcc, s6, v64
	v_cvt_pk_bf16_f32 v40, v52, v53
	v_cvt_pk_bf16_f32 v41, v54, v55
	s_mov_b32 s6, 0x15726000
	s_nop 0
	v_addc_co_u32_e32 v43, vcc, 0, v65, vcc
	global_store_dwordx2 v[42:43], v[40:41], off offset:-4096
	v_cvt_pk_bf16_f32 v40, v48, v49
	v_cvt_pk_bf16_f32 v41, v50, v51
	global_store_dwordx2 v[42:43], v[40:41], off
	v_cvt_pk_bf16_f32 v36, v36, v37
	v_cvt_pk_bf16_f32 v37, v38, v39
	v_add_co_u32_e32 v38, vcc, s6, v64
	s_nop 1
	v_addc_co_u32_e32 v39, vcc, 0, v65, vcc
	global_store_dwordx2 v[38:39], v[36:37], off
	v_cvt_pk_bf16_f32 v32, v32, v33
	v_cvt_pk_bf16_f32 v33, v34, v35
	v_add_co_u32_e32 v34, vcc, 0x15727000, v64
	s_nop 1
	v_addc_co_u32_e32 v35, vcc, 0, v65, vcc
	global_store_dwordx2 v[34:35], v[32:33], off

; DEVFI float dpp_xor1(float x) { return __int_as_float(__builtin_amdgcn_update_dpp(0, __float_as_int(x), 0xB1, 0xF, 0xF, true)); }
; #define AQ ((bfraw*)(kargs()->ws + O_AQ))
; #define AK ((bfraw*)(kargs()->ws + O_AK))
; #define AV ((bfraw*)(kargs()->ws + O_AV))
; DEVFI void store_nat_m(bfraw* base, long ld, f32x4 (&a)[8], int fr) {
;   const bool odd = fr & 1;
;   bfraw* p0 = base + (odd ? 15 + fr : fr);
; #pragma unroll
;   for (int j = 0; j < 4; ++j)
; #pragma unroll
;     for (int n0 = 0; n0 < 8; n0 += 2) { const float own0 = a[n0][j], own1 = a[n0 + 1][j];
;       const float recv = dpp_xor1(odd ? own0 : own1);
;       const unsigned pk = odd ? cvtpk(recv, own1) : cvtpk(own0, recv);
;       *reinterpret_cast<unsigned*>(p0 + (long)j * ld + n0 * 16) = pk; }
; }
; __global__ void __launch_bounds__(512) mega(Params p) {
;     ...
;                     if (isk) store_nat_m(AK + (long)r0 * 256 + (c0 - 7168), 256, a, fr);
;                     else store_nat_m(AQ + (long)r0 * 1024 + (c0 - 6144), 1024, a, fr);
;                   } else if (c0 < 7680) {
;                     store_nat_m(AV + (long)r0 * 256 + (c0 - 7424), 256, a, fr);
.LBB0_1987:
	s_andn2_b64 vcc, exec, s[2:3]
	s_cbranch_vccnz .LBB0_2053
	s_mov_b64 s[2:3], s[0:1]
	s_load_dwordx2 s[2:3], s[2:3], 0xe8
	v_and_b32_e32 v32, 1, v203
	v_cmp_eq_u32_e64 s[6:7], 0, v32
	v_cmp_eq_u32_e64 s[4:5], 1, v32
	s_nop 0
	v_cndmask_b32_e64 v32, v28, v24, s[6:7]
	s_nop 1
	v_mov_b32_dpp v32, v32 quad_perm:[1,0,3,2] row_mask:0xf bank_mask:0xf bound_ctrl:1
	v_cndmask_b32_e64 v34, v28, v32, s[4:5]
	v_cndmask_b32_e64 v32, v32, v24, s[4:5]
	v_cvt_pk_bf16_f32 v34, v34, v32
	v_ashrrev_i32_e32 v65, 31, v64
	v_lshlrev_b64 v[32:33], 9, v[64:65]
	v_add_u32_e32 v35, 15, v202
	s_waitcnt lgkmcnt(0)
	v_lshl_add_u64 v[32:33], s[2:3], 0, v[32:33]
	v_cndmask_b32_e64 v35, v35, v202, s[6:7]
	v_lshl_add_u64 v[32:33], v[176:177], 1, v[32:33]
	v_lshlrev_b32_e32 v36, 1, v35
	v_mov_b32_e32 v37, v177
	v_lshl_add_u64 v[32:33], v[32:33], 0, v[36:37]
	v_add_co_u32_e32 v36, vcc, 0x21f1c000, v32
	s_nop 1
	v_addc_co_u32_e32 v37, vcc, 0, v33, vcc
	global_store_dword v[36:37], v34, off offset:1536
	v_cndmask_b32_e64 v34, v12, v8, s[6:7]
	s_nop 1
	v_mov_b32_dpp v35, v34 quad_perm:[1,0,3,2] row_mask:0xf bank_mask:0xf bound_ctrl:1
	v_cndmask_b32_e64 v34, v12, v35, s[4:5]
	v_cndmask_b32_e64 v35, v35, v8, s[4:5]
	v_cvt_pk_bf16_f32 v34, v34, v35
	s_mov_b64 s[2:3], 0x21f1c600
	v_lshl_add_u64 v[32:33], v[32:33], 0, s[2:3]
	global_store_dword v[32:33], v34, off offset:64
	v_cndmask_b32_e64 v34, v20, v16, s[6:7]
	s_nop 1
	v_mov_b32_dpp v35, v34 quad_perm:[1,0,3,2] row_mask:0xf bank_mask:0xf bound_ctrl:1
	v_cndmask_b32_e64 v34, v20, v35, s[4:5]
	v_cndmask_b32_e64 v35, v35, v16, s[4:5]
	v_cvt_pk_bf16_f32 v34, v34, v35
	global_store_dword v[32:33], v34, off offset:128
	v_cndmask_b32_e64 v34, v4, v0, s[6:7]
	s_nop 1
	v_mov_b32_dpp v35, v34 quad_perm:[1,0,3,2] row_mask:0xf bank_mask:0xf bound_ctrl:1
	v_cndmask_b32_e64 v34, v4, v35, s[4:5]
	v_cndmask_b32_e64 v35, v35, v0, s[4:5]
	v_cvt_pk_bf16_f32 v34, v34, v35
	global_store_dword v[32:33], v34, off offset:192
	v_cndmask_b32_e64 v34, v29, v25, s[6:7]
	s_nop 1
	v_mov_b32_dpp v35, v34 quad_perm:[1,0,3,2] row_mask:0xf bank_mask:0xf bound_ctrl:1
	v_cndmask_b32_e64 v34, v29, v35, s[4:5]
	v_cndmask_b32_e64 v35, v35, v25, s[4:5]
	v_cvt_pk_bf16_f32 v34, v34, v35
	global_store_dword v[32:33], v34, off offset:512
	v_cndmask_b32_e64 v34, v13, v9, s[6:7]
	s_nop 1
	v_mov_b32_dpp v35, v34 quad_perm:[1,0,3,2] row_mask:0xf bank_mask:0xf bound_ctrl:1
	v_cndmask_b32_e64 v34, v13, v35, s[4:5]
	v_cndmask_b32_e64 v35, v35, v9, s[4:5]
	v_cvt_pk_bf16_f32 v34, v34, v35
	global_store_dword v[32:33], v34, off offset:576
	v_cndmask_b32_e64 v34, v21, v17, s[6:7]
	s_nop 1
	v_mov_b32_dpp v35, v34 quad_perm:[1,0,3,2] row_mask:0xf bank_mask:0xf bound_ctrl:1
	v_cndmask_b32_e64 v34, v21, v35, s[4:5]
	v_cndmask_b32_e64 v35, v35, v17, s[4:5]
	v_cvt_pk_bf16_f32 v34, v34, v35
	global_store_dword v[32:33], v34, off offset:640
	v_cndmask_b32_e64 v34, v5, v1, s[6:7]
	s_nop 1
	v_mov_b32_dpp v35, v34 quad_perm:[1,0,3,2] row_mask:0xf bank_mask:0xf bound_ctrl:1
	v_cndmask_b32_e64 v34, v5, v35, s[4:5]
	v_cndmask_b32_e64 v35, v35, v1, s[4:5]
	v_cvt_pk_bf16_f32 v34, v34, v35
	global_store_dword v[32:33], v34, off offset:704
	v_cndmask_b32_e64 v34, v30, v26, s[6:7]
	s_nop 1
	v_mov_b32_dpp v35, v34 quad_perm:[1,0,3,2] row_mask:0xf bank_mask:0xf bound_ctrl:1
	v_cndmask_b32_e64 v34, v30, v35, s[4:5]
	v_cndmask_b32_e64 v35, v35, v26, s[4:5]
	v_cvt_pk_bf16_f32 v34, v34, v35
	global_store_dword v[32:33], v34, off offset:1024
	v_cndmask_b32_e64 v34, v14, v10, s[6:7]
	s_nop 1
	v_mov_b32_dpp v35, v34 quad_perm:[1,0,3,2] row_mask:0xf bank_mask:0xf bound_ctrl:1
	v_cndmask_b32_e64 v34, v14, v35, s[4:5]
	v_cndmask_b32_e64 v35, v35, v10, s[4:5]
	v_cvt_pk_bf16_f32 v34, v34, v35
	global_store_dword v[32:33], v34, off offset:1088
	v_cndmask_b32_e64 v34, v22, v18, s[6:7]
	s_nop 1
	v_mov_b32_dpp v35, v34 quad_perm:[1,0,3,2] row_mask:0xf bank_mask:0xf bound_ctrl:1
	v_cndmask_b32_e64 v34, v22, v35, s[4:5]
	v_cndmask_b32_e64 v35, v35, v18, s[4:5]
	v_cvt_pk_bf16_f32 v34, v34, v35
	global_store_dword v[32:33], v34, off offset:1152
	v_cndmask_b32_e64 v34, v6, v2, s[6:7]
	s_nop 1
	v_mov_b32_dpp v35, v34 quad_perm:[1,0,3,2] row_mask:0xf bank_mask:0xf bound_ctrl:1
	v_cndmask_b32_e64 v34, v6, v35, s[4:5]
	v_cndmask_b32_e64 v35, v35, v2, s[4:5]
	v_cvt_pk_bf16_f32 v34, v34, v35
	global_store_dword v[32:33], v34, off offset:1216
	v_cndmask_b32_e64 v34, v31, v27, s[6:7]
	s_nop 1
	v_mov_b32_dpp v35, v34 quad_perm:[1,0,3,2] row_mask:0xf bank_mask:0xf bound_ctrl:1
	v_cndmask_b32_e64 v34, v31, v35, s[4:5]
	v_cndmask_b32_e64 v35, v35, v27, s[4:5]
	v_cvt_pk_bf16_f32 v34, v34, v35
	global_store_dword v[32:33], v34, off offset:1536
	v_cndmask_b32_e64 v34, v15, v11, s[6:7]
	s_nop 1
	v_mov_b32_dpp v35, v34 quad_perm:[1,0,3,2] row_mask:0xf bank_mask:0xf bound_ctrl:1
	v_cndmask_b32_e64 v34, v15, v35, s[4:5]
	v_cndmask_b32_e64 v35, v35, v11, s[4:5]
	v_cvt_pk_bf16_f32 v34, v34, v35
	global_store_dword v[32:33], v34, off offset:1600
	v_cndmask_b32_e64 v34, v23, v19, s[6:7]
	s_nop 1
	v_mov_b32_dpp v35, v34 quad_perm:[1,0,3,2] row_mask:0xf bank_mask:0xf bound_ctrl:1
	v_cndmask_b32_e64 v34, v23, v35, s[4:5]
	v_cndmask_b32_e64 v35, v35, v19, s[4:5]
	v_cvt_pk_bf16_f32 v34, v34, v35
	global_store_dword v[32:33], v34, off offset:1664
	v_cndmask_b32_e64 v34, v7, v3, s[6:7]
	s_nop 1
	v_mov_b32_dpp v35, v34 quad_perm:[1,0,3,2] row_mask:0xf bank_mask:0xf bound_ctrl:1
	v_cndmask_b32_e64 v34, v7, v35, s[4:5]
	v_cndmask_b32_e64 v35, v35, v3, s[4:5]
	v_cvt_pk_bf16_f32 v34, v34, v35
	global_store_dword v[32:33], v34, off offset:1728

; DEVFI float dpp_xor1(float x) { return __int_as_float(__builtin_amdgcn_update_dpp(0, __float_as_int(x), 0xB1, 0xF, 0xF, true)); }
; #define RG ((bfraw*)(kargs()->ws + O_RG))
; #define SU ((bfraw*)(kargs()->ws + O_SU))
; #define SV ((bfraw*)(kargs()->ws + O_SV))
; #define SVSTAT ((float*)(kargs()->ws + O_SVSTAT))
; DEVFI void store_nat_m(bfraw* base, long ld, f32x4 (&a)[8], int fr) {
;   const bool odd = fr & 1;
;   bfraw* p0 = base + (odd ? 15 + fr : fr);
; #pragma unroll
;   for (int j = 0; j < 4; ++j)
; #pragma unroll
;     for (int n0 = 0; n0 < 8; n0 += 2) { const float own0 = a[n0][j], own1 = a[n0 + 1][j];
;       const float recv = dpp_xor1(odd ? own0 : own1);
;       const unsigned pk = odd ? cvtpk(recv, own1) : cvtpk(own0, recv);
;       *reinterpret_cast<unsigned*>(p0 + (long)j * ld + n0 * 16) = pk; }
; }
; __global__ void __launch_bounds__(512) mega(Params p) {
;     ...
;                     store_nat_m(RG + (long)r0 * 1024 + (c0 - 3072), 1024, a, fr);
;                   } else if (c0 < 6144) {
; #pragma unroll
;                     for (int n = 0; n < 8; ++n)
; #pragma unroll
;                       for (int j = 0; j < 4; ++j) a[n][j] = gelu_tanh(a[n][j]);
;                     if (c0 >= 5120) { float* stp = SVSTAT + (long)r0 * 16 + ((c0 - 5120) >> 7) * 2;
; #pragma unroll
;                       for (int j = 0; j < 4; ++j) { float s1 = 0, s2 = 0;
; #pragma unroll
;                         for (int n = 0; n < 8; ++n) { s1 += a[n][j]; s2 += a[n][j] * a[n][j]; }
;                         s1 = red16(s1); s2 = red16(s2);
;                         if (fr == 0) { stp[j * 16] = s1; stp[j * 16 + 1] = s2; } } }
;                     store_nat_m((c0 < 5120 ? SU + (c0 - 4096) : SV + (c0 - 5120)) + (long)r0 * 1024, 1024, a, fr);
.LBB0_2120:
	s_or_b64 exec, exec, s[2:3]
	v_add_co_u32_e32 v74, vcc, 0x1000, v32
	v_mov_b32_dpp v71, v72 quad_perm:[1,0,3,2] row_mask:0xf bank_mask:0xf bound_ctrl:1
	s_nop 0
	v_addc_co_u32_e32 v75, vcc, 0, v33, vcc
	global_store_dword v[74:75], v70, off offset:2176
	v_cndmask_b32_e64 v70, v60, v71, s[4:5]
	v_cndmask_b32_e64 v71, v71, v34, s[4:5]
	v_cvt_pk_bf16_f32 v70, v70, v71
	v_add_co_u32_e32 v32, vcc, 0x1000, v32
	s_mov_b64 s[2:3], 0
	s_nop 0
	v_addc_co_u32_e32 v33, vcc, 0, v33, vcc
	global_store_dword v[32:33], v70, off offset:2240

; DEVFI float dpp_xor1(float x) { return __int_as_float(__builtin_amdgcn_update_dpp(0, __float_as_int(x), 0xB1, 0xF, 0xF, true)); }
; #define AQ ((bfraw*)(kargs()->ws + O_AQ))
; #define AK ((bfraw*)(kargs()->ws + O_AK))
; DEVFI void store_nat_m(bfraw* base, long ld, f32x4 (&a)[8], int fr) {
;   const bool odd = fr & 1;
;   bfraw* p0 = base + (odd ? 15 + fr : fr);
; #pragma unroll
;   for (int j = 0; j < 4; ++j)
; #pragma unroll
;     for (int n0 = 0; n0 < 8; n0 += 2) { const float own0 = a[n0][j], own1 = a[n0 + 1][j];
;       const float recv = dpp_xor1(odd ? own0 : own1);
;       const unsigned pk = odd ? cvtpk(recv, own1) : cvtpk(own0, recv);
;       *reinterpret_cast<unsigned*>(p0 + (long)j * ld + n0 * 16) = pk; }
; }
; __global__ void __launch_bounds__(512) mega(Params p) {
;     ...
;                     if (isk) store_nat_m(AK + (long)r0 * 256 + (c0 - 7168), 256, a, fr);
;                     else store_nat_m(AQ + (long)r0 * 1024 + (c0 - 6144), 1024, a, fr);
.LBB0_2186:
	s_or_b64 exec, exec, s[2:3]
	s_nop 0
	v_mov_b32_dpp v36, v37 quad_perm:[1,0,3,2] row_mask:0xf bank_mask:0xf bound_ctrl:1
	global_store_dword v[32:33], v35, off offset:1664
	v_cndmask_b32_e64 v35, v60, v36, s[4:5]
	v_cndmask_b32_e64 v36, v36, v34, s[4:5]
	v_cvt_pk_bf16_f32 v35, v35, v36
	global_store_dword v[32:33], v35, off offset:1728

; DEVFI void store_nat_m(bfraw* base, long ld, f32x4 (&a)[8], int fr) {
;   const bool odd = fr & 1;
;   bfraw* p0 = base + (odd ? 15 + fr : fr);
; #pragma unroll
;   for (int j = 0; j < 4; ++j)
; #pragma unroll
;     for (int n0 = 0; n0 < 8; n0 += 2) { const float own0 = a[n0][j], own1 = a[n0 + 1][j];
;       const float recv = dpp_xor1(odd ? own0 : own1);
;       const unsigned pk = odd ? cvtpk(recv, own1) : cvtpk(own0, recv);
;       *reinterpret_cast<unsigned*>(p0 + (long)j * ld + n0 * 16) = pk; }
; }
; __global__ void __launch_bounds__(512) mega(Params p) {
;     ...
;                     store_nat_m((isk ? RK : RQ) + (long)r0 * 1024 + cc, 1024, a, fr);
;                     if (isk) store_tr_m(RKT + ((long)((r0 >> 7) * 8 + head) * 128 + fr) * 128 + (r0 & 127), 128, a);
;                   } else if (c0 < 3072) {
;                     const int head = (c0 - 2048) >> 7;
;                     store_tr_m(RVT + ((long)((r0 >> 7) * 8 + head) * 128 + fr) * 128 + (r0 & 127), 128, a);
;                   } else if (c0 < 4096) {
; #pragma unroll
;                     for (int n = 0; n < 8; ++n)
; #pragma unroll
;                       for (int j = 0; j < 4; ++j) { const float x = a[n][j]; a[n][j] = x * sigmoidf_(x); }
;                     store_nat_m(RG + (long)r0 * 1024 + (c0 - 3072), 1024, a, fr);
;                   } else if (c0 < 6144) {
; #pragma unroll
;                     for (int n = 0; n < 8; ++n)
; #pragma unroll
;                       for (int j = 0; j < 4; ++j) a[n][j] = gelu_tanh(a[n][j]);
;                     if (c0 >= 5120) { float* stp = SVSTAT + (long)r0 * 16 + ((c0 - 5120) >> 7) * 2;
; #pragma unroll
;                       for (int j = 0; j < 4; ++j) { float s1 = 0, s2 = 0;
; #pragma unroll
;                         for (int n = 0; n < 8; ++n) { s1 += a[n][j]; s2 += a[n][j] * a[n][j]; }
;                         s1 = red16(s1); s2 = red16(s2);
;                         if (fr == 0) { stp[j * 16] = s1; stp[j * 16 + 1] = s2; } } }
;                     store_nat_m((c0 < 5120 ? SU + (c0 - 4096) : SV + (c0 - 5120)) + (long)r0 * 1024, 1024, a, fr);
;                   } else if (c0 < 7424) {
;                     const bool isk = c0 >= 7168; const float* nw = isk ? kn_w : qn_w; const float2* attt = ATTT;
; #pragma unroll
;                     for (int j = 0; j < 4; ++j) { const int pos = (r0 + j) & (seqlen - 1);
;                       float ss = 0;
.LBB0_2265:
	s_or_b64 exec, exec, s[2:3]
	v_add_co_u32_e32 v36, vcc, 0x1000, v40
	v_mov_b32_dpp v33, v34 quad_perm:[1,0,3,2] row_mask:0xf bank_mask:0xf bound_ctrl:1
	s_nop 0
	v_addc_co_u32_e32 v37, vcc, 0, v41, vcc
	global_store_dword v[36:37], v32, off offset:2176
	v_cndmask_b32_e64 v32, v70, v33, s[4:5]
	v_cndmask_b32_e64 v33, v33, v80, s[4:5]
	v_cvt_pk_bf16_f32 v32, v32, v33
	v_add_co_u32_e32 v34, vcc, 0x1000, v40
	s_nop 1
	v_addc_co_u32_e32 v35, vcc, 0, v41, vcc
	global_store_dword v[34:35], v32, off offset:2240

; DEVFI void store_nat_m(bfraw* base, long ld, f32x4 (&a)[8], int fr) {
;   const bool odd = fr & 1;
;   bfraw* p0 = base + (odd ? 15 + fr : fr);
; #pragma unroll
;   for (int j = 0; j < 4; ++j)
; #pragma unroll
;     for (int n0 = 0; n0 < 8; n0 += 2) { const float own0 = a[n0][j], own1 = a[n0 + 1][j];
;       const float recv = dpp_xor1(odd ? own0 : own1);
;       const unsigned pk = odd ? cvtpk(recv, own1) : cvtpk(own0, recv);
;       *reinterpret_cast<unsigned*>(p0 + (long)j * ld + n0 * 16) = pk; }
; }
; __global__ void __launch_bounds__(512) mega(Params p) {
;     ...
;                     store_nat_m((isk ? RK : RQ) + (long)r0 * 1024 + cc, 1024, a, fr);
;                     if (isk) store_tr_m(RKT + ((long)((r0 >> 7) * 8 + head) * 128 + fr) * 128 + (r0 & 127), 128, a);
;                   } else if (c0 < 3072) {
;                     const int head = (c0 - 2048) >> 7;
;                     store_tr_m(RVT + ((long)((r0 >> 7) * 8 + head) * 128 + fr) * 128 + (r0 & 127), 128, a);
;                   } else if (c0 < 4096) {
; #pragma unroll
;                     for (int n = 0; n < 8; ++n)
; #pragma unroll
;                       for (int j = 0; j < 4; ++j) { const float x = a[n][j]; a[n][j] = x * sigmoidf_(x); }
;                     store_nat_m(RG + (long)r0 * 1024 + (c0 - 3072), 1024, a, fr);
;                   } else if (c0 < 6144) {
; #pragma unroll
;                     for (int n = 0; n < 8; ++n)
; #pragma unroll
;                       for (int j = 0; j < 4; ++j) a[n][j] = gelu_tanh(a[n][j]);
;                     if (c0 >= 5120) { float* stp = SVSTAT + (long)r0 * 16 + ((c0 - 5120) >> 7) * 2;
; #pragma unroll
;                       for (int j = 0; j < 4; ++j) { float s1 = 0, s2 = 0;
; #pragma unroll
;                         for (int n = 0; n < 8; ++n) { s1 += a[n][j]; s2 += a[n][j] * a[n][j]; }
;                         s1 = red16(s1); s2 = red16(s2);
;                         if (fr == 0) { stp[j * 16] = s1; stp[j * 16 + 1] = s2; } } }
;                     store_nat_m((c0 < 5120 ? SU + (c0 - 4096) : SV + (c0 - 5120)) + (long)r0 * 1024, 1024, a, fr);
;                   } else if (c0 < 7424) {
;                     const bool isk = c0 >= 7168; const float* nw = isk ? kn_w : qn_w; const float2* attt = ATTT;
; #pragma unroll
;                     for (int j = 0; j < 4; ++j) { const int pos = (r0 + j) & (seqlen - 1);
;                       float ss = 0;
.LBB0_2332:
	s_or_b64 exec, exec, s[2:3]
	v_add_co_u32_e32 v40, vcc, 0x1000, v32
	s_nop 1
	v_addc_co_u32_e32 v41, vcc, 0, v33, vcc
	global_store_dword v[40:41], v36, off offset:2176
	v_mov_b32_dpp v36, v38 quad_perm:[1,0,3,2] row_mask:0xf bank_mask:0xf bound_ctrl:1
	v_cndmask_b32_e64 v35, v34, v36, s[4:5]
	v_cndmask_b32_e64 v36, v36, v37, s[4:5]
	v_cvt_pk_bf16_f32 v35, v35, v36
	v_add_co_u32_e32 v32, vcc, 0x1000, v32
	s_nop 1
	v_addc_co_u32_e32 v33, vcc, 0, v33, vcc
	global_store_dword v[32:33], v35, off offset:2240

; DEVFI float dpp_xor1(float x) { return __int_as_float(__builtin_amdgcn_update_dpp(0, __float_as_int(x), 0xB1, 0xF, 0xF, true)); }
; DEVFI void store_nat_m(bfraw* base, long ld, f32x4 (&a)[8], int fr) {
;   const bool odd = fr & 1;
;   bfraw* p0 = base + (odd ? 15 + fr : fr);
; #pragma unroll
;   for (int j = 0; j < 4; ++j)
; #pragma unroll
;     for (int n0 = 0; n0 < 8; n0 += 2) { const float own0 = a[n0][j], own1 = a[n0 + 1][j];
;       const float recv = dpp_xor1(odd ? own0 : own1);
;       const unsigned pk = odd ? cvtpk(recv, own1) : cvtpk(own0, recv);
;       *reinterpret_cast<unsigned*>(p0 + (long)j * ld + n0 * 16) = pk; }
; }
; DEVFI void store_tr_m(bfraw* dstT, long ldT, f32x4 (&a)[8]) {
; #pragma unroll
;   for (int n = 0; n < 8; ++n) { u32x2 w = {cvtpk(a[n][0], a[n][1]), cvtpk(a[n][2], a[n][3])};
;     *reinterpret_cast<u32x2*>(dstT + (long)(n * 16) * ldT) = w; }
; }
.LBB0_2405:
	s_or_b64 exec, exec, s[2:3]
	v_add_co_u32_e32 v34, vcc, 0x1000, v66
	v_mov_b32_dpp v31, v32 quad_perm:[1,0,3,2] row_mask:0xf bank_mask:0xf bound_ctrl:1
	s_nop 0
	v_addc_co_u32_e32 v35, vcc, 0, v67, vcc
	global_store_dword v[34:35], v27, off offset:2176
	v_cndmask_b32_e64 v27, v15, v31, s[6:7]
	v_cndmask_b32_e64 v31, v31, v11, s[6:7]
	v_cvt_pk_bf16_f32 v27, v27, v31
	v_add_co_u32_e32 v32, vcc, 0x1000, v66
	s_nop 1
	v_addc_co_u32_e32 v33, vcc, 0, v67, vcc
	global_store_dword v[32:33], v27, off offset:2240
	s_and_saveexec_b64 s[2:3], s[4:5]
	s_cbranch_execz .LBB0_118
	s_mov_b64 s[4:5], s[0:1]
	s_load_dwordx2 s[4:5], s[4:5], 0xe8
	v_lshrrev_b32_e32 v11, 7, v74
	v_ashrrev_i32_e32 v15, 4, v64
	v_and_or_b32 v32, v15, -8, v11
	v_ashrrev_i32_e32 v33, 31, v32
	v_lshlrev_b64 v[32:33], 15, v[32:33]
	s_waitcnt lgkmcnt(0)
	v_lshl_add_u64 v[32:33], s[4:5], 0, v[32:33]
	v_lshlrev_b32_e32 v176, 8, v202
	v_and_b32_e32 v11, 0x7f, v64
	v_lshl_add_u64 v[32:33], v[32:33], 0, v[176:177]
	v_lshlrev_b32_e32 v176, 1, v11
	v_lshl_add_u64 v[32:33], v[32:33], 0, v[176:177]
	s_mov_b32 s4, 0x15721000
	v_cvt_pk_bf16_f32 v12, v71, v12
	v_cvt_pk_bf16_f32 v13, v13, v14
	v_add_co_u32_e32 v14, vcc, s4, v32
	s_mov_b32 s4, 0x15723000
	s_nop 0
	v_addc_co_u32_e32 v15, vcc, 0, v33, vcc
	global_store_dwordx2 v[14:15], v[12:13], off offset:-4096
	v_cvt_pk_bf16_f32 v8, v70, v8
	v_cvt_pk_bf16_f32 v9, v9, v10
	v_add_co_u32_e32 v10, vcc, s4, v32
	global_store_dwordx2 v[14:15], v[8:9], off
	v_cvt_pk_bf16_f32 v8, v73, v28
	v_cvt_pk_bf16_f32 v9, v29, v30
	s_nop 0
	v_addc_co_u32_e32 v11, vcc, 0, v33, vcc
	s_mov_b32 s4, 0x15725000
	global_store_dwordx2 v[10:11], v[8:9], off offset:-4096
	v_cvt_pk_bf16_f32 v8, v72, v24
	v_cvt_pk_bf16_f32 v9, v25, v26
	global_store_dwordx2 v[10:11], v[8:9], off
	v_add_co_u32_e32 v10, vcc, s4, v32
	v_cvt_pk_bf16_f32 v8, v20, v21
	v_cvt_pk_bf16_f32 v9, v22, v23
	s_mov_b32 s4, 0x15726000
	s_nop 0
	v_addc_co_u32_e32 v11, vcc, 0, v33, vcc
	global_store_dwordx2 v[10:11], v[8:9], off offset:-4096
	v_cvt_pk_bf16_f32 v8, v16, v17
	v_cvt_pk_bf16_f32 v9, v18, v19
	global_store_dwordx2 v[10:11], v[8:9], off
	v_cvt_pk_bf16_f32 v4, v4, v5
	v_cvt_pk_bf16_f32 v5, v6, v7
	v_add_co_u32_e32 v6, vcc, s4, v32
	s_nop 1
	v_addc_co_u32_e32 v7, vcc, 0, v33, vcc
	global_store_dwordx2 v[6:7], v[4:5], off
	v_cvt_pk_bf16_f32 v0, v0, v1
	v_cvt_pk_bf16_f32 v1, v2, v3
	v_add_co_u32_e32 v2, vcc, 0x15727000, v32
	s_nop 1
	v_addc_co_u32_e32 v3, vcc, 0, v33, vcc
	global_store_dwordx2 v[2:3], v[0:1], off
	s_branch .LBB0_118

; DEVFI int opaque_tid(const int wv) { return (wv << 6) | lane_opaque(); }
; #define WAIT_V0() asm volatile("s_waitcnt vmcnt(0)" ::: "memory")
; #define GLDS_STAGE(buf, kt) gemm_stage(t, (buf), (kt), shm, wid, lane)
; DEVFI void gemm_stage(const TileSrc& t, const int buf, const int kt, char* shm, const int wid, const int lane) {
;   int R, C; stage_rc<G_KS>(wid * 1024 + lane * 16, R, C);
;   const int oa = R * t.lda + C, ob = R * t.ldb + C;
; #pragma unroll
;   for (int i = 0; i < G_GL; ++i) {
;     __builtin_amdgcn_global_load_lds((const unsigned*)(t.A + (i * 64 * t.lda + kt * G_BK) + oa), (unsigned*)(shm + buf * G_STAGE_B + wid * 1024 + i * 8192), 16, 0, 0);
;     __builtin_amdgcn_global_load_lds((const unsigned*)(t.B + (i * 64 * t.ldb + kt * G_BK) + ob), (unsigned*)(shm + buf * G_STAGE_B + G_TILE_B + wid * 1024 + i * 8192), 16, 0, 0); }
; }
; DEVFI void gemm_issue0(const TileSrc& t, char* shm, const int wv) { const int tid = opaque_tid(wv); gemm_stage(t, 0, 0, shm, tid >> 6, tid & 63); }
; template <class Epi>
; DEVFI void gemm_main(const TileSrc t, const int K, char* shm, const bool pf, const TileSrc nx, const int wv, Epi epi) {
;   const int tid = opaque_tid(wv), wid = tid >> 6, lane = tid & 63, wr = wid >> 1, wc = wid & 1, fr = lane & 15, fq = lane >> 4;
;     ...
;   f32x4 acc[4][8] = {};
;   const int nt = K / G_BK;
;   const int sw = (fr * 64 + fq * 16) ^ ((fr >> 3) << 5);
;   const char* aBase = shm + wr * 8192 + sw;
;   const char* bBase = shm + G_TILE_B + wc * 16384 + sw;
;   WAIT_V0(); __syncthreads();
;   for (int t_ = 0; t_ < nt; ++t_) { const int cur = t_ & 1;
;     if (t_ + 1 < nt) GLDS_STAGE(cur ^ 1, t_ + 1);
; #pragma unroll
;     for (int ks = 0; ks < G_KS; ++ks) {
;       bf16x8 At[4], Bf[8];
; #pragma unroll
;       for (int n = 0; n < 8; ++n) Bf[n] = *(const bf16x8*)(bBase + cur * G_STAGE_B + (n * 2048 + ks * 1024));
.LBB0_2516:
	s_mov_b32 s8, -1
	s_waitcnt vmcnt(0)
	s_mov_b32 s9, 0
	v_mbcnt_lo_u32_b32 v0, s8, 0
	v_mbcnt_hi_u32_b32 v165, s8, v0
	v_or_b32_e32 v136, s33, v165
	v_ashrrev_i32_e32 v139, 6, v136
	s_ashr_i32 s8, s33, 7
	v_and_b32_e32 v167, 1, v139
	v_and_b32_e32 v164, 15, v165
	v_and_b32_e32 v137, 48, v165
	v_lshlrev_b32_e32 v1, 2, v165
	v_lshl_or_b32 v0, v164, 6, v137
	v_and_b32_e32 v1, 32, v1
	s_lshl_b32 s18, s8, 13
	v_lshlrev_b32_e32 v2, 14, v167
	v_bitop3_b32 v132, s18, v0, v1 bitop3:0xf6
	v_bitop3_b32 v133, v2, v0, v1 bitop3:0xf6
	v_lshlrev_b32_e32 v0, 4, v165
	v_and_b32_e32 v1, 32, v165
	v_lshrrev_b32_e32 v2, 31, v139
	v_add_u32_e32 v2, v139, v2
	v_bitop3_b32 v0, v0, v1, 48 bitop3:0x6c
	v_ashrrev_i32_e32 v144, 1, v2
	v_lshrrev_b32_e32 v145, 1, v0
	v_lshlrev_b32_e32 v0, 8, v165
	v_and_b32_e32 v146, 0x3c00, v0
	v_mul_lo_u32 v0, v144, s66
	v_or_b32_e32 v0, v145, v0
	v_lshlrev_b32_e32 v1, 5, v139
	v_add3_u32 v0, v0, v146, v1
	v_ashrrev_i32_e32 v1, 31, v0
	v_lshlrev_b64 v[0:1], 1, v[0:1]
	v_lshl_add_u64 v[128:129], s[6:7], 0, v[0:1]
	v_lshl_add_u64 v[130:131], s[2:3], 0, v[0:1]
	v_mov_b32_e32 v0, 0
	v_and_b32_e32 v166, 63, v165
	v_lshlrev_b32_e32 v138, 10, v139
	s_mov_b64 s[6:7], 0
	v_mov_b32_e32 v1, v0
	v_mov_b32_e32 v2, v0
	v_mov_b32_e32 v3, v0
	v_mov_b32_e32 v4, v0
	v_mov_b32_e32 v5, v0
	v_mov_b32_e32 v6, v0
	v_mov_b32_e32 v7, v0
	v_mov_b32_e32 v8, v0
	v_mov_b32_e32 v9, v0
	v_mov_b32_e32 v10, v0
	v_mov_b32_e32 v11, v0
	v_mov_b32_e32 v12, v0
	v_mov_b32_e32 v13, v0
	v_mov_b32_e32 v14, v0
	v_mov_b32_e32 v15, v0
	v_mov_b32_e32 v16, v0
	v_mov_b32_e32 v17, v0
	v_mov_b32_e32 v18, v0
	v_mov_b32_e32 v19, v0
	v_mov_b32_e32 v20, v0
	v_mov_b32_e32 v21, v0
	v_mov_b32_e32 v22, v0
	v_mov_b32_e32 v23, v0
	v_mov_b32_e32 v24, v0
	v_mov_b32_e32 v25, v0
	v_mov_b32_e32 v26, v0
	v_mov_b32_e32 v27, v0
	v_mov_b32_e32 v28, v0
	v_mov_b32_e32 v29, v0
	v_mov_b32_e32 v30, v0
	v_mov_b32_e32 v31, v0
	v_mov_b32_e32 v32, v0
	v_mov_b32_e32 v33, v0
	v_mov_b32_e32 v34, v0
	v_mov_b32_e32 v35, v0
	v_mov_b32_e32 v36, v0
	v_mov_b32_e32 v37, v0
	v_mov_b32_e32 v38, v0
	v_mov_b32_e32 v39, v0
	v_mov_b32_e32 v40, v0
	v_mov_b32_e32 v41, v0
	v_mov_b32_e32 v42, v0
	v_mov_b32_e32 v43, v0
	v_mov_b32_e32 v44, v0
	v_mov_b32_e32 v45, v0
	v_mov_b32_e32 v46, v0
	v_mov_b32_e32 v47, v0
	v_mov_b32_e32 v48, v0
	v_mov_b32_e32 v49, v0
	v_mov_b32_e32 v50, v0
	v_mov_b32_e32 v51, v0
	v_mov_b32_e32 v52, v0
	v_mov_b32_e32 v53, v0
	v_mov_b32_e32 v54, v0
	v_mov_b32_e32 v55, v0
	v_mov_b32_e32 v56, v0
	v_mov_b32_e32 v57, v0
	v_mov_b32_e32 v58, v0
	v_mov_b32_e32 v59, v0
	v_mov_b32_e32 v60, v0
	v_mov_b32_e32 v61, v0
	v_mov_b32_e32 v62, v0
	v_mov_b32_e32 v63, v0
	v_mov_b32_e32 v64, v0
	v_mov_b32_e32 v65, v0
	v_mov_b32_e32 v66, v0
	v_mov_b32_e32 v67, v0
	v_mov_b32_e32 v68, v0
	v_mov_b32_e32 v69, v0
	v_mov_b32_e32 v70, v0
	v_mov_b32_e32 v71, v0
	v_mov_b32_e32 v72, v0
	v_mov_b32_e32 v73, v0
	v_mov_b32_e32 v74, v0
	v_mov_b32_e32 v75, v0
	v_mov_b32_e32 v76, v0
	v_mov_b32_e32 v77, v0
	v_mov_b32_e32 v78, v0
	v_mov_b32_e32 v79, v0
	v_mov_b32_e32 v80, v0
	v_mov_b32_e32 v81, v0
	v_mov_b32_e32 v82, v0
	v_mov_b32_e32 v83, v0
	v_mov_b32_e32 v84, v0
	v_mov_b32_e32 v85, v0
	v_mov_b32_e32 v86, v0
	v_mov_b32_e32 v87, v0
	v_mov_b32_e32 v88, v0
	v_mov_b32_e32 v89, v0
	v_mov_b32_e32 v90, v0
	v_mov_b32_e32 v91, v0
	v_mov_b32_e32 v92, v0
	v_mov_b32_e32 v93, v0
	v_mov_b32_e32 v94, v0
	v_mov_b32_e32 v95, v0
	v_mov_b32_e32 v96, v0
	v_mov_b32_e32 v97, v0
	v_mov_b32_e32 v98, v0
	v_mov_b32_e32 v99, v0
	v_mov_b32_e32 v100, v0
	v_mov_b32_e32 v101, v0
	v_mov_b32_e32 v102, v0
	v_mov_b32_e32 v103, v0
	v_mov_b32_e32 v104, v0
	v_mov_b32_e32 v105, v0
	v_mov_b32_e32 v106, v0
	v_mov_b32_e32 v107, v0
	v_mov_b32_e32 v108, v0
	v_mov_b32_e32 v109, v0
	v_mov_b32_e32 v110, v0
	v_mov_b32_e32 v111, v0
	v_mov_b32_e32 v112, v0
	v_mov_b32_e32 v113, v0
	v_mov_b32_e32 v114, v0
	v_mov_b32_e32 v115, v0
	v_mov_b32_e32 v116, v0
	v_mov_b32_e32 v117, v0
	v_mov_b32_e32 v118, v0
	v_mov_b32_e32 v119, v0
	v_mov_b32_e32 v120, v0
	v_mov_b32_e32 v121, v0
	v_mov_b32_e32 v122, v0
	v_mov_b32_e32 v123, v0
	v_mov_b32_e32 v124, v0
	v_mov_b32_e32 v125, v0
	v_mov_b32_e32 v126, v0
	v_mov_b32_e32 v127, v0
	s_waitcnt lgkmcnt(0)
	s_lshr_b32 s2, s33, 6
	s_lshr_b32 s3, s2, 1
	s_sub_u32 s3, s2, s3
	s_mov_b32 s6, 0x20000
	s_lshr_b32 s7, s6, 2
	s_mul_i32 s3, s3, s7
	s_and_b32 s7, s2, 1
	s_lshl_b32 s7, s7, 6
	s_sub_u32 s3, s3, s7
	s_add_u32 s3, s3, 0x80
	s_lshl_b32 s9, s6, 1
	s_lshl_b32 s2, s2, 11
	s_mov_b32 vcc_hi, 0
	s_mov_b32 vcc_lo, s3
	v_lshl_add_u64 v[130:131], v[130:131], 0, vcc
	v_lshl_add_u64 v[128:129], v[128:129], 0, vcc
	s_mov_b32 vcc_lo, s9
	v_lshl_add_u64 v[214:215], v[130:131], 0, vcc
	v_lshl_add_u64 v[236:237], v[128:129], 0, vcc
	v_add_u32_e32 v147, 0x10000, v132
	v_add_u32_e32 v212, 0x10000, v133
	s_nop 0
	v_readfirstlane_b32 s6, v130
	v_readfirstlane_b32 s7, v131
	v_readfirstlane_b32 vcc_lo, v128
	v_readfirstlane_b32 vcc_hi, v129
	s_nop 1
	v_subrev_u32_e32 v130, s6, v130
	v_subrev_u32_e32 v128, vcc_lo, v128
	v_add_u32_e32 v214, s9, v130
	v_add_u32_e32 v236, s9, v128
	s_nop 4
	s_add_u32 m0, s2, 0x10000
	s_nop 0
	global_load_lds_dwordx4 v130, s[6:7]
	s_add_u32 m0, s2, 0x14000
	s_nop 0
	global_load_lds_dwordx4 v214, s[6:7]
	s_add_u32 s6, s6, 64
	s_addc_u32 s7, s7, 0
	s_add_u32 m0, s2, 0x18000
	s_nop 0
	global_load_lds_dwordx4 v128, vcc
	s_add_u32 m0, s2, 0x1c000
	s_nop 0
	global_load_lds_dwordx4 v236, vcc
	s_add_u32 vcc_lo, vcc_lo, 64
	s_addc_u32 vcc_hi, vcc_hi, 0
	s_add_u32 m0, s2, 0x10400
	s_nop 0
	global_load_lds_dwordx4 v130, s[6:7]
	s_add_u32 m0, s2, 0x14400
	s_nop 0
	global_load_lds_dwordx4 v214, s[6:7]
	s_add_u32 s6, s6, 64
	s_addc_u32 s7, s7, 0
	s_add_u32 m0, s2, 0x18400
	s_nop 0
	global_load_lds_dwordx4 v128, vcc
	s_add_u32 m0, s2, 0x1c400
	s_nop 0
	global_load_lds_dwordx4 v236, vcc
	s_add_u32 vcc_lo, vcc_lo, 64
	s_addc_u32 vcc_hi, vcc_hi, 0
	s_waitcnt vmcnt(8)
	s_barrier
	ds_read_b128 v[148:151], v132
	ds_read_b128 v[152:155], v132 offset:2048
	ds_read_b128 v[156:159], v132 offset:4096
	ds_read_b128 v[160:163], v132 offset:6144
	ds_read_b128 v[188:191], v133 offset:32768
	ds_read_b128 v[192:195], v133 offset:34816
	ds_read_b128 v[196:199], v133 offset:36864
	ds_read_b128 v[200:203], v133 offset:38912
	ds_read_b128 v[204:207], v133 offset:40960
	ds_read_b128 v[208:211], v133 offset:43008
	ds_read_b128 v[218:221], v133 offset:45056
	ds_read_b128 v[228:231], v133 offset:47104
	s_mov_b32 s3, 7
; #define SBAR() __builtin_amdgcn_sched_barrier(0)
; #define WAIT_V0() asm volatile("s_waitcnt vmcnt(0)" ::: "memory")
; #define GLDS_STAGE(buf, kt) gemm_stage(t, (buf), (kt), shm, wid, lane)
; template <class Epi>
; DEVFI void gemm_main(const TileSrc t, const int K, char* shm, const bool pf, const TileSrc nx, const int wv, Epi epi) {
;     ...
;   for (int t_ = 0; t_ < nt; ++t_) { const int cur = t_ & 1;
;     if (t_ + 1 < nt) GLDS_STAGE(cur ^ 1, t_ + 1);
; #pragma unroll
;     for (int ks = 0; ks < G_KS; ++ks) {
;       bf16x8 At[4], Bf[8];
; #pragma unroll
;       for (int n = 0; n < 8; ++n) Bf[n] = *(const bf16x8*)(bBase + cur * G_STAGE_B + (n * 2048 + ks * 1024));
;       SBAR();
;       At[0] = *(const bf16x8*)(aBase + cur * G_STAGE_B + (0 * 2048 + ks * 1024)); SBAR();
;       At[1] = *(const bf16x8*)(aBase + cur * G_STAGE_B + (1 * 2048 + ks * 1024)); SBAR();
;       At[2] = *(const bf16x8*)(aBase + cur * G_STAGE_B + (2 * 2048 + ks * 1024)); SBAR();
;       At[3] = *(const bf16x8*)(aBase + cur * G_STAGE_B + (3 * 2048 + ks * 1024));
;       SBAR();
;       __builtin_amdgcn_s_setprio(1);
; #pragma unroll
;       for (int m = 0; m < 4; ++m)
; #pragma unroll
;         for (int n = 0; n < 8; ++n) acc[m][n] = __builtin_amdgcn_mfma_f32_16x16x32_bf16(At[m], Bf[n], acc[m][n], 0, 0, 0);
;       __builtin_amdgcn_s_setprio(0);
;       SBAR();
;     }
;     WAIT_V0(); __syncthreads();
;   }
.LgkE_loop:
	s_waitcnt lgkmcnt(0)
	s_waitcnt vmcnt(8)
	s_barrier
	v_mfma_f32_16x16x32_bf16 v[116:119], v[148:151], v[188:191], v[116:119]
	ds_read_b128 v[168:171], v132 offset:1024
	s_add_u32 m0, s2, 0x0
	v_mfma_f32_16x16x32_bf16 v[92:95], v[152:155], v[188:191], v[92:95]
	ds_read_b128 v[172:175], v132 offset:3072
	v_mfma_f32_16x16x32_bf16 v[60:63], v[156:159], v[188:191], v[60:63]
	ds_read_b128 v[178:181], v132 offset:5120
	global_load_lds_dwordx4 v130, s[6:7]
	v_mfma_f32_16x16x32_bf16 v[28:31], v[160:163], v[188:191], v[28:31]
	ds_read_b128 v[184:187], v132 offset:7168
	v_mfma_f32_16x16x32_bf16 v[112:115], v[148:151], v[192:195], v[112:115]
	ds_read_b128 v[224:227], v133 offset:46080
	v_mfma_f32_16x16x32_bf16 v[88:91], v[152:155], v[192:195], v[88:91]
	ds_read_b128 v[232:235], v133 offset:48128
	v_mfma_f32_16x16x32_bf16 v[56:59], v[156:159], v[192:195], v[56:59]
	ds_read_b128 v[188:191], v133 offset:33792
	v_mfma_f32_16x16x32_bf16 v[24:27], v[160:163], v[192:195], v[24:27]
	ds_read_b128 v[192:195], v133 offset:35840
	v_mfma_f32_16x16x32_bf16 v[124:127], v[148:151], v[196:199], v[124:127]
	s_add_u32 m0, s2, 0x4000
	v_mfma_f32_16x16x32_bf16 v[84:87], v[152:155], v[196:199], v[84:87]
	v_mfma_f32_16x16x32_bf16 v[52:55], v[156:159], v[196:199], v[52:55]
	global_load_lds_dwordx4 v214, s[6:7]
	v_mfma_f32_16x16x32_bf16 v[20:23], v[160:163], v[196:199], v[20:23]
	ds_read_b128 v[196:199], v133 offset:37888
	s_add_u32 s6, s6, 64
	s_addc_u32 s7, s7, 0
	v_mfma_f32_16x16x32_bf16 v[120:123], v[148:151], v[200:203], v[120:123]
	v_mfma_f32_16x16x32_bf16 v[80:83], v[152:155], v[200:203], v[80:83]
	v_mfma_f32_16x16x32_bf16 v[48:51], v[156:159], v[200:203], v[48:51]
	v_mfma_f32_16x16x32_bf16 v[16:19], v[160:163], v[200:203], v[16:19]
	ds_read_b128 v[200:203], v133 offset:39936
	v_mfma_f32_16x16x32_bf16 v[108:111], v[148:151], v[204:207], v[108:111]
	s_add_u32 m0, s2, 0x8000
	v_mfma_f32_16x16x32_bf16 v[76:79], v[152:155], v[204:207], v[76:79]
	v_mfma_f32_16x16x32_bf16 v[44:47], v[156:159], v[204:207], v[44:47]
	global_load_lds_dwordx4 v128, vcc
	v_mfma_f32_16x16x32_bf16 v[12:15], v[160:163], v[204:207], v[12:15]
	ds_read_b128 v[204:207], v133 offset:41984
	v_mfma_f32_16x16x32_bf16 v[104:107], v[148:151], v[208:211], v[104:107]
	v_mfma_f32_16x16x32_bf16 v[72:75], v[152:155], v[208:211], v[72:75]
	v_mfma_f32_16x16x32_bf16 v[40:43], v[156:159], v[208:211], v[40:43]
	v_mfma_f32_16x16x32_bf16 v[8:11], v[160:163], v[208:211], v[8:11]
	ds_read_b128 v[208:211], v133 offset:44032
	v_mfma_f32_16x16x32_bf16 v[100:103], v[148:151], v[218:221], v[100:103]
	s_add_u32 m0, s2, 0xc000
	v_mfma_f32_16x16x32_bf16 v[68:71], v[152:155], v[218:221], v[68:71]
	v_mfma_f32_16x16x32_bf16 v[36:39], v[156:159], v[218:221], v[36:39]
	global_load_lds_dwordx4 v236, vcc
	v_mfma_f32_16x16x32_bf16 v[4:7], v[160:163], v[218:221], v[4:7]
	s_add_u32 vcc_lo, vcc_lo, 64
	s_addc_u32 vcc_hi, vcc_hi, 0
	v_mfma_f32_16x16x32_bf16 v[96:99], v[148:151], v[228:231], v[96:99]
	v_mfma_f32_16x16x32_bf16 v[64:67], v[152:155], v[228:231], v[64:67]
	v_mfma_f32_16x16x32_bf16 v[32:35], v[156:159], v[228:231], v[32:35]
	v_mfma_f32_16x16x32_bf16 v[0:3], v[160:163], v[228:231], v[0:3]
	s_waitcnt lgkmcnt(0)
	s_waitcnt vmcnt(8)
	s_barrier
	v_mfma_f32_16x16x32_bf16 v[116:119], v[168:171], v[188:191], v[116:119]
	ds_read_b128 v[148:151], v147
	s_add_u32 m0, s2, 0x400
	v_mfma_f32_16x16x32_bf16 v[92:95], v[172:175], v[188:191], v[92:95]
	ds_read_b128 v[152:155], v147 offset:2048
	v_mfma_f32_16x16x32_bf16 v[60:63], v[178:181], v[188:191], v[60:63]
	ds_read_b128 v[156:159], v147 offset:4096
	global_load_lds_dwordx4 v130, s[6:7]
	v_mfma_f32_16x16x32_bf16 v[28:31], v[184:187], v[188:191], v[28:31]
	ds_read_b128 v[160:163], v147 offset:6144
	v_mfma_f32_16x16x32_bf16 v[112:115], v[168:171], v[192:195], v[112:115]
	ds_read_b128 v[218:221], v212 offset:45056
	v_mfma_f32_16x16x32_bf16 v[88:91], v[172:175], v[192:195], v[88:91]
	ds_read_b128 v[228:231], v212 offset:47104
	v_mfma_f32_16x16x32_bf16 v[56:59], v[178:181], v[192:195], v[56:59]
	ds_read_b128 v[188:191], v212 offset:32768
	v_mfma_f32_16x16x32_bf16 v[24:27], v[184:187], v[192:195], v[24:27]
	ds_read_b128 v[192:195], v212 offset:34816
	v_mfma_f32_16x16x32_bf16 v[124:127], v[168:171], v[196:199], v[124:127]
	s_add_u32 m0, s2, 0x4400
	v_mfma_f32_16x16x32_bf16 v[84:87], v[172:175], v[196:199], v[84:87]
	v_mfma_f32_16x16x32_bf16 v[52:55], v[178:181], v[196:199], v[52:55]
	global_load_lds_dwordx4 v214, s[6:7]
	v_mfma_f32_16x16x32_bf16 v[20:23], v[184:187], v[196:199], v[20:23]
	ds_read_b128 v[196:199], v212 offset:36864
	s_add_u32 s6, s6, 64
	s_addc_u32 s7, s7, 0
	v_mfma_f32_16x16x32_bf16 v[120:123], v[168:171], v[200:203], v[120:123]
	v_mfma_f32_16x16x32_bf16 v[80:83], v[172:175], v[200:203], v[80:83]
	v_mfma_f32_16x16x32_bf16 v[48:51], v[178:181], v[200:203], v[48:51]
	v_mfma_f32_16x16x32_bf16 v[16:19], v[184:187], v[200:203], v[16:19]
	ds_read_b128 v[200:203], v212 offset:38912
	v_mfma_f32_16x16x32_bf16 v[108:111], v[168:171], v[204:207], v[108:111]
	s_add_u32 m0, s2, 0x8400
	v_mfma_f32_16x16x32_bf16 v[76:79], v[172:175], v[204:207], v[76:79]
	v_mfma_f32_16x16x32_bf16 v[44:47], v[178:181], v[204:207], v[44:47]
	global_load_lds_dwordx4 v128, vcc
	v_mfma_f32_16x16x32_bf16 v[12:15], v[184:187], v[204:207], v[12:15]
	ds_read_b128 v[204:207], v212 offset:40960
	v_mfma_f32_16x16x32_bf16 v[104:107], v[168:171], v[208:211], v[104:107]
	v_mfma_f32_16x16x32_bf16 v[72:75], v[172:175], v[208:211], v[72:75]
	v_mfma_f32_16x16x32_bf16 v[40:43], v[178:181], v[208:211], v[40:43]
	v_mfma_f32_16x16x32_bf16 v[8:11], v[184:187], v[208:211], v[8:11]
	ds_read_b128 v[208:211], v212 offset:43008
	v_mfma_f32_16x16x32_bf16 v[100:103], v[168:171], v[224:227], v[100:103]
	s_add_u32 m0, s2, 0xc400
	v_mfma_f32_16x16x32_bf16 v[68:71], v[172:175], v[224:227], v[68:71]
	v_mfma_f32_16x16x32_bf16 v[36:39], v[178:181], v[224:227], v[36:39]
	global_load_lds_dwordx4 v236, vcc
	v_mfma_f32_16x16x32_bf16 v[4:7], v[184:187], v[224:227], v[4:7]
	s_add_u32 vcc_lo, vcc_lo, 64
	s_addc_u32 vcc_hi, vcc_hi, 0
	v_mfma_f32_16x16x32_bf16 v[96:99], v[168:171], v[232:235], v[96:99]
	v_mfma_f32_16x16x32_bf16 v[64:67], v[172:175], v[232:235], v[64:67]
	v_mfma_f32_16x16x32_bf16 v[32:35], v[178:181], v[232:235], v[32:35]
	v_mfma_f32_16x16x32_bf16 v[0:3], v[184:187], v[232:235], v[0:3]
	s_waitcnt lgkmcnt(0)
	s_waitcnt vmcnt(8)
	s_barrier
; #define SBAR() __builtin_amdgcn_sched_barrier(0)
; #define WAIT_V0() asm volatile("s_waitcnt vmcnt(0)" ::: "memory")
; #define GLDS_STAGE(buf, kt) gemm_stage(t, (buf), (kt), shm, wid, lane)
; template <class Epi>
; DEVFI void gemm_main(const TileSrc t, const int K, char* shm, const bool pf, const TileSrc nx, const int wv, Epi epi) {
;     ...
;   for (int t_ = 0; t_ < nt; ++t_) { const int cur = t_ & 1;
;     if (t_ + 1 < nt) GLDS_STAGE(cur ^ 1, t_ + 1);
; #pragma unroll
;     for (int ks = 0; ks < G_KS; ++ks) {
;       bf16x8 At[4], Bf[8];
; #pragma unroll
;       for (int n = 0; n < 8; ++n) Bf[n] = *(const bf16x8*)(bBase + cur * G_STAGE_B + (n * 2048 + ks * 1024));
;       SBAR();
;       At[0] = *(const bf16x8*)(aBase + cur * G_STAGE_B + (0 * 2048 + ks * 1024)); SBAR();
;       At[1] = *(const bf16x8*)(aBase + cur * G_STAGE_B + (1 * 2048 + ks * 1024)); SBAR();
;       At[2] = *(const bf16x8*)(aBase + cur * G_STAGE_B + (2 * 2048 + ks * 1024)); SBAR();
;       At[3] = *(const bf16x8*)(aBase + cur * G_STAGE_B + (3 * 2048 + ks * 1024));
;       SBAR();
;       __builtin_amdgcn_s_setprio(1);
; #pragma unroll
;       for (int m = 0; m < 4; ++m)
; #pragma unroll
;         for (int n = 0; n < 8; ++n) acc[m][n] = __builtin_amdgcn_mfma_f32_16x16x32_bf16(At[m], Bf[n], acc[m][n], 0, 0, 0);
;       __builtin_amdgcn_s_setprio(0);
;       SBAR();
;     }
;     WAIT_V0(); __syncthreads();
;   }
	v_mfma_f32_16x16x32_bf16 v[116:119], v[148:151], v[188:191], v[116:119]
	ds_read_b128 v[168:171], v147 offset:1024
	s_add_u32 m0, s2, 0x10000
	v_mfma_f32_16x16x32_bf16 v[92:95], v[152:155], v[188:191], v[92:95]
	ds_read_b128 v[172:175], v147 offset:3072
	v_mfma_f32_16x16x32_bf16 v[60:63], v[156:159], v[188:191], v[60:63]
	ds_read_b128 v[178:181], v147 offset:5120
	global_load_lds_dwordx4 v130, s[6:7]
	v_mfma_f32_16x16x32_bf16 v[28:31], v[160:163], v[188:191], v[28:31]
	ds_read_b128 v[184:187], v147 offset:7168
	v_mfma_f32_16x16x32_bf16 v[112:115], v[148:151], v[192:195], v[112:115]
	ds_read_b128 v[224:227], v212 offset:46080
	v_mfma_f32_16x16x32_bf16 v[88:91], v[152:155], v[192:195], v[88:91]
	ds_read_b128 v[232:235], v212 offset:48128
	v_mfma_f32_16x16x32_bf16 v[56:59], v[156:159], v[192:195], v[56:59]
	ds_read_b128 v[188:191], v212 offset:33792
	v_mfma_f32_16x16x32_bf16 v[24:27], v[160:163], v[192:195], v[24:27]
	ds_read_b128 v[192:195], v212 offset:35840
	v_mfma_f32_16x16x32_bf16 v[124:127], v[148:151], v[196:199], v[124:127]
	s_add_u32 m0, s2, 0x14000
	v_mfma_f32_16x16x32_bf16 v[84:87], v[152:155], v[196:199], v[84:87]
	v_mfma_f32_16x16x32_bf16 v[52:55], v[156:159], v[196:199], v[52:55]
	global_load_lds_dwordx4 v214, s[6:7]
	v_mfma_f32_16x16x32_bf16 v[20:23], v[160:163], v[196:199], v[20:23]
	ds_read_b128 v[196:199], v212 offset:37888
	s_add_u32 s6, s6, 64
	s_addc_u32 s7, s7, 0
	v_mfma_f32_16x16x32_bf16 v[120:123], v[148:151], v[200:203], v[120:123]
	v_mfma_f32_16x16x32_bf16 v[80:83], v[152:155], v[200:203], v[80:83]
	v_mfma_f32_16x16x32_bf16 v[48:51], v[156:159], v[200:203], v[48:51]
	v_mfma_f32_16x16x32_bf16 v[16:19], v[160:163], v[200:203], v[16:19]
	ds_read_b128 v[200:203], v212 offset:39936
	v_mfma_f32_16x16x32_bf16 v[108:111], v[148:151], v[204:207], v[108:111]
	s_add_u32 m0, s2, 0x18000
	v_mfma_f32_16x16x32_bf16 v[76:79], v[152:155], v[204:207], v[76:79]
	v_mfma_f32_16x16x32_bf16 v[44:47], v[156:159], v[204:207], v[44:47]
	global_load_lds_dwordx4 v128, vcc
	v_mfma_f32_16x16x32_bf16 v[12:15], v[160:163], v[204:207], v[12:15]
	ds_read_b128 v[204:207], v212 offset:41984
	v_mfma_f32_16x16x32_bf16 v[104:107], v[148:151], v[208:211], v[104:107]
	v_mfma_f32_16x16x32_bf16 v[72:75], v[152:155], v[208:211], v[72:75]
	v_mfma_f32_16x16x32_bf16 v[40:43], v[156:159], v[208:211], v[40:43]
	v_mfma_f32_16x16x32_bf16 v[8:11], v[160:163], v[208:211], v[8:11]
	ds_read_b128 v[208:211], v212 offset:44032
	v_mfma_f32_16x16x32_bf16 v[100:103], v[148:151], v[218:221], v[100:103]
	s_add_u32 m0, s2, 0x1c000
	v_mfma_f32_16x16x32_bf16 v[68:71], v[152:155], v[218:221], v[68:71]
	v_mfma_f32_16x16x32_bf16 v[36:39], v[156:159], v[218:221], v[36:39]
	global_load_lds_dwordx4 v236, vcc
	v_mfma_f32_16x16x32_bf16 v[4:7], v[160:163], v[218:221], v[4:7]
	s_add_u32 vcc_lo, vcc_lo, 64
	s_addc_u32 vcc_hi, vcc_hi, 0
	v_mfma_f32_16x16x32_bf16 v[96:99], v[148:151], v[228:231], v[96:99]
	v_mfma_f32_16x16x32_bf16 v[64:67], v[152:155], v[228:231], v[64:67]
	v_mfma_f32_16x16x32_bf16 v[32:35], v[156:159], v[228:231], v[32:35]
	v_mfma_f32_16x16x32_bf16 v[0:3], v[160:163], v[228:231], v[0:3]
	s_waitcnt lgkmcnt(0)
	s_waitcnt vmcnt(8)
	s_barrier
	v_mfma_f32_16x16x32_bf16 v[116:119], v[168:171], v[188:191], v[116:119]
	ds_read_b128 v[148:151], v132
	s_add_u32 m0, s2, 0x10400
	v_mfma_f32_16x16x32_bf16 v[92:95], v[172:175], v[188:191], v[92:95]
	ds_read_b128 v[152:155], v132 offset:2048
	v_mfma_f32_16x16x32_bf16 v[60:63], v[178:181], v[188:191], v[60:63]
	ds_read_b128 v[156:159], v132 offset:4096
	global_load_lds_dwordx4 v130, s[6:7]
	v_mfma_f32_16x16x32_bf16 v[28:31], v[184:187], v[188:191], v[28:31]
	ds_read_b128 v[160:163], v132 offset:6144
	v_mfma_f32_16x16x32_bf16 v[112:115], v[168:171], v[192:195], v[112:115]
	ds_read_b128 v[218:221], v133 offset:45056
	v_mfma_f32_16x16x32_bf16 v[88:91], v[172:175], v[192:195], v[88:91]
	ds_read_b128 v[228:231], v133 offset:47104
	v_mfma_f32_16x16x32_bf16 v[56:59], v[178:181], v[192:195], v[56:59]
	ds_read_b128 v[188:191], v133 offset:32768
	v_mfma_f32_16x16x32_bf16 v[24:27], v[184:187], v[192:195], v[24:27]
	ds_read_b128 v[192:195], v133 offset:34816
	v_mfma_f32_16x16x32_bf16 v[124:127], v[168:171], v[196:199], v[124:127]
	s_add_u32 m0, s2, 0x14400
	v_mfma_f32_16x16x32_bf16 v[84:87], v[172:175], v[196:199], v[84:87]
	v_mfma_f32_16x16x32_bf16 v[52:55], v[178:181], v[196:199], v[52:55]
	global_load_lds_dwordx4 v214, s[6:7]
	v_mfma_f32_16x16x32_bf16 v[20:23], v[184:187], v[196:199], v[20:23]
	ds_read_b128 v[196:199], v133 offset:36864
	s_add_u32 s6, s6, 64
	s_addc_u32 s7, s7, 0
	v_mfma_f32_16x16x32_bf16 v[120:123], v[168:171], v[200:203], v[120:123]
	v_mfma_f32_16x16x32_bf16 v[80:83], v[172:175], v[200:203], v[80:83]
	v_mfma_f32_16x16x32_bf16 v[48:51], v[178:181], v[200:203], v[48:51]
	v_mfma_f32_16x16x32_bf16 v[16:19], v[184:187], v[200:203], v[16:19]
	ds_read_b128 v[200:203], v133 offset:38912
	v_mfma_f32_16x16x32_bf16 v[108:111], v[168:171], v[204:207], v[108:111]
	s_add_u32 m0, s2, 0x18400
	v_mfma_f32_16x16x32_bf16 v[76:79], v[172:175], v[204:207], v[76:79]
	v_mfma_f32_16x16x32_bf16 v[44:47], v[178:181], v[204:207], v[44:47]
	global_load_lds_dwordx4 v128, vcc
	v_mfma_f32_16x16x32_bf16 v[12:15], v[184:187], v[204:207], v[12:15]
	ds_read_b128 v[204:207], v133 offset:40960
	v_mfma_f32_16x16x32_bf16 v[104:107], v[168:171], v[208:211], v[104:107]
	v_mfma_f32_16x16x32_bf16 v[72:75], v[172:175], v[208:211], v[72:75]
	v_mfma_f32_16x16x32_bf16 v[40:43], v[178:181], v[208:211], v[40:43]
	v_mfma_f32_16x16x32_bf16 v[8:11], v[184:187], v[208:211], v[8:11]
	ds_read_b128 v[208:211], v133 offset:43008
	v_mfma_f32_16x16x32_bf16 v[100:103], v[168:171], v[224:227], v[100:103]
	s_add_u32 m0, s2, 0x1c400
	v_mfma_f32_16x16x32_bf16 v[68:71], v[172:175], v[224:227], v[68:71]
	v_mfma_f32_16x16x32_bf16 v[36:39], v[178:181], v[224:227], v[36:39]
	global_load_lds_dwordx4 v236, vcc
	v_mfma_f32_16x16x32_bf16 v[4:7], v[184:187], v[224:227], v[4:7]
	s_add_u32 vcc_lo, vcc_lo, 64
	s_addc_u32 vcc_hi, vcc_hi, 0
	v_mfma_f32_16x16x32_bf16 v[96:99], v[168:171], v[232:235], v[96:99]
	v_mfma_f32_16x16x32_bf16 v[64:67], v[172:175], v[232:235], v[64:67]
	v_mfma_f32_16x16x32_bf16 v[32:35], v[178:181], v[232:235], v[32:35]
	v_mfma_f32_16x16x32_bf16 v[0:3], v[184:187], v[232:235], v[0:3]
	s_sub_u32 s3, s3, 1
	s_cmp_lg_u32 s3, 0
	s_cbranch_scc1 .LgkE_loop
; #define SBAR() __builtin_amdgcn_sched_barrier(0)
; #define WAIT_V0() asm volatile("s_waitcnt vmcnt(0)" ::: "memory")
; #define GLDS_STAGE(buf, kt) gemm_stage(t, (buf), (kt), shm, wid, lane)
; template <class Epi>
; DEVFI void gemm_main(const TileSrc t, const int K, char* shm, const bool pf, const TileSrc nx, const int wv, Epi epi) {
;     ...
;   for (int t_ = 0; t_ < nt; ++t_) { const int cur = t_ & 1;
;     if (t_ + 1 < nt) GLDS_STAGE(cur ^ 1, t_ + 1);
; #pragma unroll
;     for (int ks = 0; ks < G_KS; ++ks) {
;       bf16x8 At[4], Bf[8];
; #pragma unroll
;       for (int n = 0; n < 8; ++n) Bf[n] = *(const bf16x8*)(bBase + cur * G_STAGE_B + (n * 2048 + ks * 1024));
;       SBAR();
;       At[0] = *(const bf16x8*)(aBase + cur * G_STAGE_B + (0 * 2048 + ks * 1024)); SBAR();
;       At[1] = *(const bf16x8*)(aBase + cur * G_STAGE_B + (1 * 2048 + ks * 1024)); SBAR();
;       At[2] = *(const bf16x8*)(aBase + cur * G_STAGE_B + (2 * 2048 + ks * 1024)); SBAR();
;       At[3] = *(const bf16x8*)(aBase + cur * G_STAGE_B + (3 * 2048 + ks * 1024));
;       SBAR();
;       __builtin_amdgcn_s_setprio(1);
; #pragma unroll
;       for (int m = 0; m < 4; ++m)
; #pragma unroll
;         for (int n = 0; n < 8; ++n) acc[m][n] = __builtin_amdgcn_mfma_f32_16x16x32_bf16(At[m], Bf[n], acc[m][n], 0, 0, 0);
;       __builtin_amdgcn_s_setprio(0);
;       SBAR();
;     }
;     WAIT_V0(); __syncthreads();
;   }
	s_waitcnt lgkmcnt(0)
	s_waitcnt vmcnt(8)
	s_barrier
	v_mfma_f32_16x16x32_bf16 v[116:119], v[148:151], v[188:191], v[116:119]
	ds_read_b128 v[168:171], v132 offset:1024
	v_mfma_f32_16x16x32_bf16 v[92:95], v[152:155], v[188:191], v[92:95]
	ds_read_b128 v[172:175], v132 offset:3072
	v_mfma_f32_16x16x32_bf16 v[60:63], v[156:159], v[188:191], v[60:63]
	ds_read_b128 v[178:181], v132 offset:5120
	v_mfma_f32_16x16x32_bf16 v[28:31], v[160:163], v[188:191], v[28:31]
	ds_read_b128 v[184:187], v132 offset:7168
	v_mfma_f32_16x16x32_bf16 v[112:115], v[148:151], v[192:195], v[112:115]
	ds_read_b128 v[224:227], v133 offset:46080
	v_mfma_f32_16x16x32_bf16 v[88:91], v[152:155], v[192:195], v[88:91]
	ds_read_b128 v[232:235], v133 offset:48128
	v_mfma_f32_16x16x32_bf16 v[56:59], v[156:159], v[192:195], v[56:59]
	ds_read_b128 v[188:191], v133 offset:33792
	v_mfma_f32_16x16x32_bf16 v[24:27], v[160:163], v[192:195], v[24:27]
	ds_read_b128 v[192:195], v133 offset:35840
	v_mfma_f32_16x16x32_bf16 v[124:127], v[148:151], v[196:199], v[124:127]
	v_mfma_f32_16x16x32_bf16 v[84:87], v[152:155], v[196:199], v[84:87]
	v_mfma_f32_16x16x32_bf16 v[52:55], v[156:159], v[196:199], v[52:55]
	v_mfma_f32_16x16x32_bf16 v[20:23], v[160:163], v[196:199], v[20:23]
	ds_read_b128 v[196:199], v133 offset:37888
	v_mfma_f32_16x16x32_bf16 v[120:123], v[148:151], v[200:203], v[120:123]
	v_mfma_f32_16x16x32_bf16 v[80:83], v[152:155], v[200:203], v[80:83]
	v_mfma_f32_16x16x32_bf16 v[48:51], v[156:159], v[200:203], v[48:51]
	v_mfma_f32_16x16x32_bf16 v[16:19], v[160:163], v[200:203], v[16:19]
	ds_read_b128 v[200:203], v133 offset:39936
	v_mfma_f32_16x16x32_bf16 v[108:111], v[148:151], v[204:207], v[108:111]
	v_mfma_f32_16x16x32_bf16 v[76:79], v[152:155], v[204:207], v[76:79]
	v_mfma_f32_16x16x32_bf16 v[44:47], v[156:159], v[204:207], v[44:47]
	v_mfma_f32_16x16x32_bf16 v[12:15], v[160:163], v[204:207], v[12:15]
	ds_read_b128 v[204:207], v133 offset:41984
	v_mfma_f32_16x16x32_bf16 v[104:107], v[148:151], v[208:211], v[104:107]
	v_mfma_f32_16x16x32_bf16 v[72:75], v[152:155], v[208:211], v[72:75]
	v_mfma_f32_16x16x32_bf16 v[40:43], v[156:159], v[208:211], v[40:43]
	v_mfma_f32_16x16x32_bf16 v[8:11], v[160:163], v[208:211], v[8:11]
	ds_read_b128 v[208:211], v133 offset:44032
	v_mfma_f32_16x16x32_bf16 v[100:103], v[148:151], v[218:221], v[100:103]
	v_mfma_f32_16x16x32_bf16 v[68:71], v[152:155], v[218:221], v[68:71]
	v_mfma_f32_16x16x32_bf16 v[36:39], v[156:159], v[218:221], v[36:39]
	v_mfma_f32_16x16x32_bf16 v[4:7], v[160:163], v[218:221], v[4:7]
	v_mfma_f32_16x16x32_bf16 v[96:99], v[148:151], v[228:231], v[96:99]
	v_mfma_f32_16x16x32_bf16 v[64:67], v[152:155], v[228:231], v[64:67]
	v_mfma_f32_16x16x32_bf16 v[32:35], v[156:159], v[228:231], v[32:35]
	v_mfma_f32_16x16x32_bf16 v[0:3], v[160:163], v[228:231], v[0:3]
	s_waitcnt lgkmcnt(0)
	s_waitcnt vmcnt(4)
	s_barrier
	v_mfma_f32_16x16x32_bf16 v[116:119], v[168:171], v[188:191], v[116:119]
	ds_read_b128 v[148:151], v147
	v_mfma_f32_16x16x32_bf16 v[92:95], v[172:175], v[188:191], v[92:95]
	ds_read_b128 v[152:155], v147 offset:2048
	v_mfma_f32_16x16x32_bf16 v[60:63], v[178:181], v[188:191], v[60:63]
	ds_read_b128 v[156:159], v147 offset:4096
	v_mfma_f32_16x16x32_bf16 v[28:31], v[184:187], v[188:191], v[28:31]
	ds_read_b128 v[160:163], v147 offset:6144
	v_mfma_f32_16x16x32_bf16 v[112:115], v[168:171], v[192:195], v[112:115]
	ds_read_b128 v[218:221], v212 offset:45056
	v_mfma_f32_16x16x32_bf16 v[88:91], v[172:175], v[192:195], v[88:91]
	ds_read_b128 v[228:231], v212 offset:47104
	v_mfma_f32_16x16x32_bf16 v[56:59], v[178:181], v[192:195], v[56:59]
	ds_read_b128 v[188:191], v212 offset:32768
	v_mfma_f32_16x16x32_bf16 v[24:27], v[184:187], v[192:195], v[24:27]
	ds_read_b128 v[192:195], v212 offset:34816
	v_mfma_f32_16x16x32_bf16 v[124:127], v[168:171], v[196:199], v[124:127]
	v_mfma_f32_16x16x32_bf16 v[84:87], v[172:175], v[196:199], v[84:87]
	v_mfma_f32_16x16x32_bf16 v[52:55], v[178:181], v[196:199], v[52:55]
	v_mfma_f32_16x16x32_bf16 v[20:23], v[184:187], v[196:199], v[20:23]
	ds_read_b128 v[196:199], v212 offset:36864
	v_mfma_f32_16x16x32_bf16 v[120:123], v[168:171], v[200:203], v[120:123]
	v_mfma_f32_16x16x32_bf16 v[80:83], v[172:175], v[200:203], v[80:83]
	v_mfma_f32_16x16x32_bf16 v[48:51], v[178:181], v[200:203], v[48:51]
	v_mfma_f32_16x16x32_bf16 v[16:19], v[184:187], v[200:203], v[16:19]
	ds_read_b128 v[200:203], v212 offset:38912
	v_mfma_f32_16x16x32_bf16 v[108:111], v[168:171], v[204:207], v[108:111]
	v_mfma_f32_16x16x32_bf16 v[76:79], v[172:175], v[204:207], v[76:79]
	v_mfma_f32_16x16x32_bf16 v[44:47], v[178:181], v[204:207], v[44:47]
	v_mfma_f32_16x16x32_bf16 v[12:15], v[184:187], v[204:207], v[12:15]
	ds_read_b128 v[204:207], v212 offset:40960
	v_mfma_f32_16x16x32_bf16 v[104:107], v[168:171], v[208:211], v[104:107]
	v_mfma_f32_16x16x32_bf16 v[72:75], v[172:175], v[208:211], v[72:75]
	v_mfma_f32_16x16x32_bf16 v[40:43], v[178:181], v[208:211], v[40:43]
	v_mfma_f32_16x16x32_bf16 v[8:11], v[184:187], v[208:211], v[8:11]
	ds_read_b128 v[208:211], v212 offset:43008
	v_mfma_f32_16x16x32_bf16 v[100:103], v[168:171], v[224:227], v[100:103]
	v_mfma_f32_16x16x32_bf16 v[68:71], v[172:175], v[224:227], v[68:71]
	v_mfma_f32_16x16x32_bf16 v[36:39], v[178:181], v[224:227], v[36:39]
	v_mfma_f32_16x16x32_bf16 v[4:7], v[184:187], v[224:227], v[4:7]
	v_mfma_f32_16x16x32_bf16 v[96:99], v[168:171], v[232:235], v[96:99]
	v_mfma_f32_16x16x32_bf16 v[64:67], v[172:175], v[232:235], v[64:67]
	v_mfma_f32_16x16x32_bf16 v[32:35], v[178:181], v[232:235], v[32:35]
	v_mfma_f32_16x16x32_bf16 v[0:3], v[184:187], v[232:235], v[0:3]
	s_waitcnt lgkmcnt(0)
	s_waitcnt vmcnt(0)
	s_barrier
; #define SBAR() __builtin_amdgcn_sched_barrier(0)
; #define WAIT_V0() asm volatile("s_waitcnt vmcnt(0)" ::: "memory")
; DEVFI void gemm_stage(const TileSrc& t, const int buf, const int kt, char* shm, const int wid, const int lane) {
;   int R, C; stage_rc<G_KS>(wid * 1024 + lane * 16, R, C);
;   const int oa = R * t.lda + C, ob = R * t.ldb + C;
; #pragma unroll
;   for (int i = 0; i < G_GL; ++i) {
;     __builtin_amdgcn_global_load_lds((const unsigned*)(t.A + (i * 64 * t.lda + kt * G_BK) + oa), (unsigned*)(shm + buf * G_STAGE_B + wid * 1024 + i * 8192), 16, 0, 0);
;     __builtin_amdgcn_global_load_lds((const unsigned*)(t.B + (i * 64 * t.ldb + kt * G_BK) + ob), (unsigned*)(shm + buf * G_STAGE_B + G_TILE_B + wid * 1024 + i * 8192), 16, 0, 0); }
; template <class Epi>
; DEVFI void gemm_main(const TileSrc t, const int K, char* shm, const bool pf, const TileSrc nx, const int wv, Epi epi) {
;     ...
;       for (int m = 0; m < 4; ++m)
; #pragma unroll
;         for (int n = 0; n < 8; ++n) acc[m][n] = __builtin_amdgcn_mfma_f32_16x16x32_bf16(At[m], Bf[n], acc[m][n], 0, 0, 0);
;       __builtin_amdgcn_s_setprio(0);
;       SBAR();
;     }
;     WAIT_V0(); __syncthreads();
;   }
;     ...
;   if (pf) gemm_stage(nx, 0, 0, shm, wid, lane);
	v_mfma_f32_16x16x32_bf16 v[116:119], v[148:151], v[188:191], v[116:119]
	ds_read_b128 v[168:171], v147 offset:1024
	v_mfma_f32_16x16x32_bf16 v[92:95], v[152:155], v[188:191], v[92:95]
	ds_read_b128 v[172:175], v147 offset:3072
	v_mfma_f32_16x16x32_bf16 v[60:63], v[156:159], v[188:191], v[60:63]
	ds_read_b128 v[178:181], v147 offset:5120
	v_mfma_f32_16x16x32_bf16 v[28:31], v[160:163], v[188:191], v[28:31]
	ds_read_b128 v[184:187], v147 offset:7168
	v_mfma_f32_16x16x32_bf16 v[112:115], v[148:151], v[192:195], v[112:115]
	ds_read_b128 v[224:227], v212 offset:46080
	v_mfma_f32_16x16x32_bf16 v[88:91], v[152:155], v[192:195], v[88:91]
	ds_read_b128 v[232:235], v212 offset:48128
	v_mfma_f32_16x16x32_bf16 v[56:59], v[156:159], v[192:195], v[56:59]
	ds_read_b128 v[188:191], v212 offset:33792
	v_mfma_f32_16x16x32_bf16 v[24:27], v[160:163], v[192:195], v[24:27]
	ds_read_b128 v[192:195], v212 offset:35840
	v_mfma_f32_16x16x32_bf16 v[124:127], v[148:151], v[196:199], v[124:127]
	v_mfma_f32_16x16x32_bf16 v[84:87], v[152:155], v[196:199], v[84:87]
	v_mfma_f32_16x16x32_bf16 v[52:55], v[156:159], v[196:199], v[52:55]
	v_mfma_f32_16x16x32_bf16 v[20:23], v[160:163], v[196:199], v[20:23]
	ds_read_b128 v[196:199], v212 offset:37888
	v_mfma_f32_16x16x32_bf16 v[120:123], v[148:151], v[200:203], v[120:123]
	v_mfma_f32_16x16x32_bf16 v[80:83], v[152:155], v[200:203], v[80:83]
	v_mfma_f32_16x16x32_bf16 v[48:51], v[156:159], v[200:203], v[48:51]
	v_mfma_f32_16x16x32_bf16 v[16:19], v[160:163], v[200:203], v[16:19]
	ds_read_b128 v[200:203], v212 offset:39936
	v_mfma_f32_16x16x32_bf16 v[108:111], v[148:151], v[204:207], v[108:111]
	v_mfma_f32_16x16x32_bf16 v[76:79], v[152:155], v[204:207], v[76:79]
	v_mfma_f32_16x16x32_bf16 v[44:47], v[156:159], v[204:207], v[44:47]
	v_mfma_f32_16x16x32_bf16 v[12:15], v[160:163], v[204:207], v[12:15]
	ds_read_b128 v[204:207], v212 offset:41984
	v_mfma_f32_16x16x32_bf16 v[104:107], v[148:151], v[208:211], v[104:107]
	v_mfma_f32_16x16x32_bf16 v[72:75], v[152:155], v[208:211], v[72:75]
	v_mfma_f32_16x16x32_bf16 v[40:43], v[156:159], v[208:211], v[40:43]
	v_mfma_f32_16x16x32_bf16 v[8:11], v[160:163], v[208:211], v[8:11]
	ds_read_b128 v[208:211], v212 offset:44032
	v_mfma_f32_16x16x32_bf16 v[100:103], v[148:151], v[218:221], v[100:103]
	v_mfma_f32_16x16x32_bf16 v[68:71], v[152:155], v[218:221], v[68:71]
	v_mfma_f32_16x16x32_bf16 v[36:39], v[156:159], v[218:221], v[36:39]
	v_mfma_f32_16x16x32_bf16 v[4:7], v[160:163], v[218:221], v[4:7]
	v_mfma_f32_16x16x32_bf16 v[96:99], v[148:151], v[228:231], v[96:99]
	v_mfma_f32_16x16x32_bf16 v[64:67], v[152:155], v[228:231], v[64:67]
	v_mfma_f32_16x16x32_bf16 v[32:35], v[156:159], v[228:231], v[32:35]
	v_mfma_f32_16x16x32_bf16 v[0:3], v[160:163], v[228:231], v[0:3]
	s_waitcnt lgkmcnt(0)
	s_barrier
	v_mfma_f32_16x16x32_bf16 v[116:119], v[168:171], v[188:191], v[116:119]
	v_mfma_f32_16x16x32_bf16 v[92:95], v[172:175], v[188:191], v[92:95]
	v_mfma_f32_16x16x32_bf16 v[60:63], v[178:181], v[188:191], v[60:63]
	v_mfma_f32_16x16x32_bf16 v[28:31], v[184:187], v[188:191], v[28:31]
	v_mfma_f32_16x16x32_bf16 v[112:115], v[168:171], v[192:195], v[112:115]
	v_mfma_f32_16x16x32_bf16 v[88:91], v[172:175], v[192:195], v[88:91]
	v_mfma_f32_16x16x32_bf16 v[56:59], v[178:181], v[192:195], v[56:59]
	v_mfma_f32_16x16x32_bf16 v[24:27], v[184:187], v[192:195], v[24:27]
	v_mfma_f32_16x16x32_bf16 v[124:127], v[168:171], v[196:199], v[124:127]
	v_mfma_f32_16x16x32_bf16 v[84:87], v[172:175], v[196:199], v[84:87]
	v_mfma_f32_16x16x32_bf16 v[52:55], v[178:181], v[196:199], v[52:55]
	v_mfma_f32_16x16x32_bf16 v[20:23], v[184:187], v[196:199], v[20:23]
	v_mfma_f32_16x16x32_bf16 v[120:123], v[168:171], v[200:203], v[120:123]
	v_mfma_f32_16x16x32_bf16 v[80:83], v[172:175], v[200:203], v[80:83]
	v_mfma_f32_16x16x32_bf16 v[48:51], v[178:181], v[200:203], v[48:51]
	v_mfma_f32_16x16x32_bf16 v[16:19], v[184:187], v[200:203], v[16:19]
	v_mfma_f32_16x16x32_bf16 v[108:111], v[168:171], v[204:207], v[108:111]
	v_mfma_f32_16x16x32_bf16 v[76:79], v[172:175], v[204:207], v[76:79]
	v_mfma_f32_16x16x32_bf16 v[44:47], v[178:181], v[204:207], v[44:47]
	v_mfma_f32_16x16x32_bf16 v[12:15], v[184:187], v[204:207], v[12:15]
	v_mfma_f32_16x16x32_bf16 v[104:107], v[168:171], v[208:211], v[104:107]
	v_mfma_f32_16x16x32_bf16 v[72:75], v[172:175], v[208:211], v[72:75]
	v_mfma_f32_16x16x32_bf16 v[40:43], v[178:181], v[208:211], v[40:43]
	v_mfma_f32_16x16x32_bf16 v[8:11], v[184:187], v[208:211], v[8:11]
	v_mfma_f32_16x16x32_bf16 v[100:103], v[168:171], v[224:227], v[100:103]
	v_mfma_f32_16x16x32_bf16 v[68:71], v[172:175], v[224:227], v[68:71]
	v_mfma_f32_16x16x32_bf16 v[36:39], v[178:181], v[224:227], v[36:39]
	v_mfma_f32_16x16x32_bf16 v[4:7], v[184:187], v[224:227], v[4:7]
	v_mfma_f32_16x16x32_bf16 v[96:99], v[168:171], v[232:235], v[96:99]
	v_mfma_f32_16x16x32_bf16 v[64:67], v[172:175], v[232:235], v[64:67]
	v_mfma_f32_16x16x32_bf16 v[32:35], v[178:181], v[232:235], v[32:35]
	v_mfma_f32_16x16x32_bf16 v[0:3], v[184:187], v[232:235], v[0:3]
	s_nop 7
	s_nop 3
	v_mov_b32_e32 v140, v116
	v_mov_b32_e32 v141, v117
	v_mov_b32_e32 v142, v118
	v_mov_b32_e32 v143, v119
	v_mov_b32_e32 v132, v112
	v_mov_b32_e32 v133, v113
	v_mov_b32_e32 v134, v114
	v_mov_b32_e32 v135, v115
	s_mov_b64 s[6:7], 0x780
	s_mov_b32 s9, 0xf0000
	s_and_b64 vcc, exec, s[4:5]
	s_cbranch_vccz .LBB0_2520
	v_lshlrev_b32_e32 v112, 1, v144
	v_sub_u32_e32 v112, v139, v112
	v_lshl_or_b32 v113, v144, 14, v146
	v_lshl_add_u32 v112, v112, 5, v113
	v_or_b32_e32 v112, v112, v145
	v_ashrrev_i32_e32 v113, 31, v112
	v_add_u32_e32 v116, 0x8000, v138
	v_lshlrev_b64 v[112:113], 1, v[112:113]
	v_readfirstlane_b32 s2, v138
	v_lshl_add_u64 v[114:115], s[14:15], 0, v[112:113]
	s_mov_b32 m0, s2
	v_readfirstlane_b32 s2, v116
	v_add_u32_e32 v118, 0x2000, v138
	global_load_lds_dwordx4 v[114:115], off
	v_lshl_add_u64 v[112:113], s[16:17], 0, v[112:113]
	s_mov_b32 m0, s2
	v_readfirstlane_b32 s2, v118
	v_add_u32_e32 v118, 0xa000, v138
	global_load_lds_dwordx4 v[112:113], off
	v_lshl_add_u64 v[116:117], v[114:115], 0, s[86:87]
	s_mov_b32 m0, s2
	v_readfirstlane_b32 s2, v118
	v_add_u32_e32 v118, 0x4000, v138
	global_load_lds_dwordx4 v[116:117], off
	v_lshl_add_u64 v[116:117], v[112:113], 0, s[86:87]
	s_mov_b32 m0, s2
	v_readfirstlane_b32 s2, v118
	v_add_u32_e32 v118, 0xc000, v138
	global_load_lds_dwordx4 v[116:117], off
	v_lshl_add_u64 v[116:117], v[114:115], 0, s[88:89]
	s_mov_b32 m0, s2
	v_readfirstlane_b32 s2, v118
	global_load_lds_dwordx4 v[116:117], off
	v_lshl_add_u64 v[116:117], v[112:113], 0, s[88:89]
	s_mov_b32 m0, s2
	v_lshl_add_u64 v[114:115], v[114:115], 0, s[90:91]
	global_load_lds_dwordx4 v[116:117], off
	v_add_u32_e32 v116, 0x6000, v138
	v_lshl_add_u64 v[112:113], v[112:113], 0, s[90:91]
	v_readfirstlane_b32 s2, v116
	s_mov_b32 m0, s2
	s_nop 0
	global_load_lds_dwordx4 v[114:115], off
	v_add_u32_e32 v114, 0xe000, v138
	s_nop 0
	v_readfirstlane_b32 s2, v114
	s_mov_b32 m0, s2
	s_nop 0
	global_load_lds_dwordx4 v[112:113], off

; __global__ void __launch_bounds__(512) mega(Params p) {
;     ...
;               for (int q = 0; q < 4; ++q) g4[q] = __builtin_nontemporal_load((const u32x4*)(gt + q * 512 * 8));
;               u32x4 p4[4] = {};
;               if (pass != 0) {
; #pragma unroll
;                 for (int q = 0; q < 4; ++q) p4[q] = *(const u32x4*)(mf + q * 512 * 8); }
; #pragma unroll
;               for (int n = 0; n < 8; ++n) { const unsigned lo = g4[n >> 1][(n & 1) * 2], hi = g4[n >> 1][(n & 1) * 2 + 1];
;                 const float g0 = __uint_as_float(lo << 16), g1 = __uint_as_float(lo & 0xffff0000u), g2 = __uint_as_float(hi << 16), g3 = __uint_as_float(hi & 0xffff0000u);
;                 a[n][0] *= g0; a[n][1] *= g1; a[n][2] *= g2; a[n][3] *= g3;
;                 if (pass != 0) { const unsigned plo = p4[n >> 1][(n & 1) * 2], phi = p4[n >> 1][(n & 1) * 2 + 1];
;                   a[n][0] += __uint_as_float(plo << 16); a[n][1] += __uint_as_float(plo & 0xffff0000u); a[n][2] += __uint_as_float(phi << 16); a[n][3] += __uint_as_float(phi & 0xffff0000u); } }
.LBB0_2536:
	v_lshlrev_b32_e32 v112, 16, v114
	v_and_b32_e32 v113, 0xffff0000, v114
	s_lshl_b32 s3, s3, 5
	v_pk_mul_f32 v[96:97], v[96:97], v[112:113]
	v_lshlrev_b32_e32 v112, 16, v115
	v_and_b32_e32 v113, 0xffff0000, v115
	s_and_b32 s38, s3, 0x300
	v_lshrrev_b32_e32 v131, 4, v166
	v_lshlrev_b32_e64 v136, 6, s8
	v_lshlrev_b32_e32 v130, 7, v167
	s_lshl_b32 s39, s2, 8
	s_and_b64 vcc, exec, s[4:5]
	v_pk_mul_f32 v[98:99], v[98:99], v[112:113]
	s_cbranch_vccnz .LBB0_2603
	v_lshlrev_b32_e32 v112, 16, v118
	v_and_b32_e32 v113, 0xffff0000, v118
	v_pk_add_f32 v[96:97], v[96:97], v[112:113]
	v_lshlrev_b32_e32 v112, 16, v119
	v_and_b32_e32 v113, 0xffff0000, v119
	v_pk_add_f32 v[98:99], v[98:99], v[112:113]
	s_cmp_eq_u32 s37, 2
	s_mov_b64 s[2:3], -1
	s_cbranch_scc0 .LBB0_2604
; DEVFI float dpp_xor1(float x) { return __int_as_float(__builtin_amdgcn_update_dpp(0, __float_as_int(x), 0xB1, 0xF, 0xF, true)); }
; #define MERGED ((bfraw*)(kargs()->ws + O_MERGED))
; DEVFI void store_nat_m(bfraw* base, long ld, f32x4 (&a)[8], int fr) {
;   const bool odd = fr & 1;
;   bfraw* p0 = base + (odd ? 15 + fr : fr);
; #pragma unroll
;   for (int j = 0; j < 4; ++j)
; #pragma unroll
;     for (int n0 = 0; n0 < 8; n0 += 2) { const float own0 = a[n0][j], own1 = a[n0 + 1][j];
;       const float recv = dpp_xor1(odd ? own0 : own1);
;       const unsigned pk = odd ? cvtpk(recv, own1) : cvtpk(own0, recv);
;       *reinterpret_cast<unsigned*>(p0 + (long)j * ld + n0 * 16) = pk; }
; }
; __global__ void __launch_bounds__(512) mega(Params p) {
;     ...
;               } else store_nat_m(MERGED + (long)(brow + wr0 + m * 16 + fq * 4) * 1024 + bcol + wc0, 1024, a, fr);
	s_mov_b64 s[2:3], s[0:1]
	s_load_dwordx2 s[2:3], s[2:3], 0xe8
	v_and_b32_e32 v112, 1, v165
	v_cmp_eq_u32_e64 s[8:9], 0, v112
	v_cmp_eq_u32_e64 s[6:7], 1, v112
	s_nop 0
	v_cndmask_b32_e64 v112, v140, v132, s[8:9]
	s_nop 1
	v_mov_b32_dpp v112, v112 quad_perm:[1,0,3,2] row_mask:0xf bank_mask:0xf bound_ctrl:1
	v_cndmask_b32_e64 v114, v140, v112, s[6:7]
	v_cndmask_b32_e64 v112, v112, v132, s[6:7]
	v_cvt_pk_bf16_f32 v114, v114, v112
	v_lshl_or_b32 v112, v131, 2, v136
	v_add_u32_e32 v112, s39, v112
	v_ashrrev_i32_e32 v113, 31, v112
	v_lshlrev_b64 v[112:113], 11, v[112:113]
	s_waitcnt lgkmcnt(0)
	v_lshl_add_u64 v[112:113], s[2:3], 0, v[112:113]
	s_lshl_b32 s12, s38, 1
	v_add_u32_e32 v115, 15, v164
	v_lshl_add_u64 v[112:113], v[112:113], 0, s[12:13]
	v_lshlrev_b32_e32 v176, 1, v130
	v_cndmask_b32_e64 v115, v115, v164, s[8:9]
	v_lshl_add_u64 v[112:113], v[112:113], 0, v[176:177]
	v_lshlrev_b32_e32 v176, 1, v115
	v_lshl_add_u64 v[112:113], v[112:113], 0, v[176:177]
	v_add_co_u32_e32 v116, vcc, 0x38720000, v112
	s_nop 1
	v_addc_co_u32_e32 v117, vcc, 0, v113, vcc
	global_store_dword v[116:117], v114, off
	v_cndmask_b32_e64 v114, v124, v120, s[8:9]
	s_nop 1
	v_mov_b32_dpp v115, v114 quad_perm:[1,0,3,2] row_mask:0xf bank_mask:0xf bound_ctrl:1
	v_cndmask_b32_e64 v114, v124, v115, s[6:7]
	v_cndmask_b32_e64 v115, v115, v120, s[6:7]
	v_cvt_pk_bf16_f32 v114, v114, v115
	s_mov_b64 s[2:3], 0x38720000
	v_lshl_add_u64 v[112:113], v[112:113], 0, s[2:3]
	global_store_dword v[112:113], v114, off offset:64
	v_cndmask_b32_e64 v114, v108, v104, s[8:9]
	s_nop 1
	v_mov_b32_dpp v115, v114 quad_perm:[1,0,3,2] row_mask:0xf bank_mask:0xf bound_ctrl:1
	v_cndmask_b32_e64 v114, v108, v115, s[6:7]
	v_cndmask_b32_e64 v115, v115, v104, s[6:7]
	v_cvt_pk_bf16_f32 v114, v114, v115
	global_store_dword v[112:113], v114, off offset:128
	v_cndmask_b32_e64 v114, v100, v96, s[8:9]
	s_nop 1
	v_mov_b32_dpp v115, v114 quad_perm:[1,0,3,2] row_mask:0xf bank_mask:0xf bound_ctrl:1
	v_cndmask_b32_e64 v114, v100, v115, s[6:7]
	v_cndmask_b32_e64 v115, v115, v96, s[6:7]
	v_cvt_pk_bf16_f32 v114, v114, v115
	global_store_dword v[112:113], v114, off offset:192
	v_cndmask_b32_e64 v114, v141, v133, s[8:9]
	s_nop 1
	v_mov_b32_dpp v115, v114 quad_perm:[1,0,3,2] row_mask:0xf bank_mask:0xf bound_ctrl:1
	v_cndmask_b32_e64 v114, v141, v115, s[6:7]
	v_cndmask_b32_e64 v115, v115, v133, s[6:7]
	v_cvt_pk_bf16_f32 v114, v114, v115
	global_store_dword v[112:113], v114, off offset:2048
	v_cndmask_b32_e64 v114, v125, v121, s[8:9]
	s_nop 1
	v_mov_b32_dpp v115, v114 quad_perm:[1,0,3,2] row_mask:0xf bank_mask:0xf bound_ctrl:1
	v_cndmask_b32_e64 v114, v125, v115, s[6:7]
	v_cndmask_b32_e64 v115, v115, v121, s[6:7]
	v_cvt_pk_bf16_f32 v114, v114, v115
	global_store_dword v[112:113], v114, off offset:2112
	v_cndmask_b32_e64 v114, v109, v105, s[8:9]
	s_nop 1
	v_mov_b32_dpp v115, v114 quad_perm:[1,0,3,2] row_mask:0xf bank_mask:0xf bound_ctrl:1
	v_cndmask_b32_e64 v114, v109, v115, s[6:7]
	v_cndmask_b32_e64 v115, v115, v105, s[6:7]
	v_cvt_pk_bf16_f32 v114, v114, v115
	global_store_dword v[112:113], v114, off offset:2176
	v_cndmask_b32_e64 v114, v101, v97, s[8:9]
	s_nop 1
	v_mov_b32_dpp v115, v114 quad_perm:[1,0,3,2] row_mask:0xf bank_mask:0xf bound_ctrl:1
	v_cndmask_b32_e64 v114, v101, v115, s[6:7]
	v_cndmask_b32_e64 v115, v115, v97, s[6:7]
	v_cvt_pk_bf16_f32 v114, v114, v115
	global_store_dword v[112:113], v114, off offset:2240
	v_cndmask_b32_e64 v114, v142, v134, s[8:9]
	s_nop 1
	v_mov_b32_dpp v115, v114 quad_perm:[1,0,3,2] row_mask:0xf bank_mask:0xf bound_ctrl:1
	v_cndmask_b32_e64 v114, v142, v115, s[6:7]
	v_cndmask_b32_e64 v115, v115, v134, s[6:7]
	v_cvt_pk_bf16_f32 v114, v114, v115
	v_add_co_u32_e32 v116, vcc, 0x1000, v112
	s_nop 1
	v_addc_co_u32_e32 v117, vcc, 0, v113, vcc
	global_store_dword v[116:117], v114, off
	v_cndmask_b32_e64 v114, v126, v122, s[8:9]
	s_nop 1
	v_mov_b32_dpp v115, v114 quad_perm:[1,0,3,2] row_mask:0xf bank_mask:0xf bound_ctrl:1
	v_cndmask_b32_e64 v114, v126, v115, s[6:7]
	v_cndmask_b32_e64 v115, v115, v122, s[6:7]
	v_cvt_pk_bf16_f32 v114, v114, v115
	v_add_co_u32_e32 v116, vcc, 0x1000, v112
	s_nop 1
	v_addc_co_u32_e32 v117, vcc, 0, v113, vcc
	global_store_dword v[116:117], v114, off offset:64
	v_cndmask_b32_e64 v114, v110, v106, s[8:9]
	s_nop 1
	v_mov_b32_dpp v115, v114 quad_perm:[1,0,3,2] row_mask:0xf bank_mask:0xf bound_ctrl:1
	v_cndmask_b32_e64 v114, v110, v115, s[6:7]
	v_cndmask_b32_e64 v115, v115, v106, s[6:7]
	v_cvt_pk_bf16_f32 v114, v114, v115
	v_add_co_u32_e32 v116, vcc, 0x1000, v112
	s_nop 1
	v_addc_co_u32_e32 v117, vcc, 0, v113, vcc
	global_store_dword v[116:117], v114, off offset:128
	v_cndmask_b32_e64 v114, v102, v98, s[8:9]
	s_nop 1
	v_mov_b32_dpp v115, v114 quad_perm:[1,0,3,2] row_mask:0xf bank_mask:0xf bound_ctrl:1
	v_cndmask_b32_e64 v114, v102, v115, s[6:7]
	v_cndmask_b32_e64 v115, v115, v98, s[6:7]
	v_cvt_pk_bf16_f32 v114, v114, v115
	v_add_co_u32_e32 v116, vcc, 0x1000, v112
	s_nop 1
	v_addc_co_u32_e32 v117, vcc, 0, v113, vcc
	global_store_dword v[116:117], v114, off offset:192
	v_cndmask_b32_e64 v114, v143, v135, s[8:9]
	s_nop 1
	v_mov_b32_dpp v115, v114 quad_perm:[1,0,3,2] row_mask:0xf bank_mask:0xf bound_ctrl:1
	v_cndmask_b32_e64 v114, v143, v115, s[6:7]
	v_cndmask_b32_e64 v115, v115, v135, s[6:7]
	v_cvt_pk_bf16_f32 v114, v114, v115
	v_add_co_u32_e32 v116, vcc, 0x1000, v112
	s_nop 1
	v_addc_co_u32_e32 v117, vcc, 0, v113, vcc
	global_store_dword v[116:117], v114, off offset:2048
	v_cndmask_b32_e64 v114, v127, v123, s[8:9]
	s_nop 1
	v_mov_b32_dpp v115, v114 quad_perm:[1,0,3,2] row_mask:0xf bank_mask:0xf bound_ctrl:1
	v_cndmask_b32_e64 v114, v127, v115, s[6:7]
	v_cndmask_b32_e64 v115, v115, v123, s[6:7]
	v_cvt_pk_bf16_f32 v114, v114, v115
	v_add_co_u32_e32 v116, vcc, 0x1000, v112
	s_nop 1
	v_addc_co_u32_e32 v117, vcc, 0, v113, vcc
	global_store_dword v[116:117], v114, off offset:2112
	v_cndmask_b32_e64 v114, v111, v107, s[8:9]
	s_nop 1
	v_mov_b32_dpp v115, v114 quad_perm:[1,0,3,2] row_mask:0xf bank_mask:0xf bound_ctrl:1
	v_cndmask_b32_e64 v114, v111, v115, s[6:7]
	v_cndmask_b32_e64 v115, v115, v107, s[6:7]
	v_cvt_pk_bf16_f32 v114, v114, v115
	v_add_co_u32_e32 v116, vcc, 0x1000, v112
	s_nop 1
	v_addc_co_u32_e32 v117, vcc, 0, v113, vcc
	global_store_dword v[116:117], v114, off offset:2176
	v_cndmask_b32_e64 v114, v103, v99, s[8:9]
	s_nop 1
	v_mov_b32_dpp v115, v114 quad_perm:[1,0,3,2] row_mask:0xf bank_mask:0xf bound_ctrl:1
	v_cndmask_b32_e64 v114, v103, v115, s[6:7]
	v_cndmask_b32_e64 v115, v115, v99, s[6:7]
	v_cvt_pk_bf16_f32 v114, v114, v115
	v_add_co_u32_e32 v112, vcc, 0x1000, v112
	s_mov_b64 s[2:3], 0
	s_nop 0
	v_addc_co_u32_e32 v113, vcc, 0, v113, vcc
	global_store_dword v[112:113], v114, off offset:2240
	s_branch .LBB0_2604

; DEVFI float dpp_xor1(float x) { return __int_as_float(__builtin_amdgcn_update_dpp(0, __float_as_int(x), 0xB1, 0xF, 0xF, true)); }
; #define MERGED ((bfraw*)(kargs()->ws + O_MERGED))
; DEVFI void store_nat_m(bfraw* base, long ld, f32x4 (&a)[8], int fr) {
;   const bool odd = fr & 1;
;   bfraw* p0 = base + (odd ? 15 + fr : fr);
; #pragma unroll
;   for (int j = 0; j < 4; ++j)
; #pragma unroll
;     for (int n0 = 0; n0 < 8; n0 += 2) { const float own0 = a[n0][j], own1 = a[n0 + 1][j];
;       const float recv = dpp_xor1(odd ? own0 : own1);
;       const unsigned pk = odd ? cvtpk(recv, own1) : cvtpk(own0, recv);
;       *reinterpret_cast<unsigned*>(p0 + (long)j * ld + n0 * 16) = pk; }
; }
; __global__ void __launch_bounds__(512) mega(Params p) {
;     ...
;               if (pass != 0) {
; #pragma unroll
;                 for (int q = 0; q < 4; ++q) p4[q] = *(const u32x4*)(mf + q * 512 * 8); }
; #pragma unroll
;               for (int n = 0; n < 8; ++n) { const unsigned lo = g4[n >> 1][(n & 1) * 2], hi = g4[n >> 1][(n & 1) * 2 + 1];
;                 const float g0 = __uint_as_float(lo << 16), g1 = __uint_as_float(lo & 0xffff0000u), g2 = __uint_as_float(hi << 16), g3 = __uint_as_float(hi & 0xffff0000u);
;                 a[n][0] *= g0; a[n][1] *= g1; a[n][2] *= g2; a[n][3] *= g3;
;                 if (pass != 0) { const unsigned plo = p4[n >> 1][(n & 1) * 2], phi = p4[n >> 1][(n & 1) * 2 + 1];
;                   a[n][0] += __uint_as_float(plo << 16); a[n][1] += __uint_as_float(plo & 0xffff0000u); a[n][2] += __uint_as_float(phi << 16); a[n][3] += __uint_as_float(phi & 0xffff0000u); } }
;               if (pass != 2) {
; #pragma unroll
;                 for (int q = 0; q < 4; ++q) { u32x4 w4 = {cvtpk(a[2 * q][0], a[2 * q][1]), cvtpk(a[2 * q][2], a[2 * q][3]), cvtpk(a[2 * q + 1][0], a[2 * q + 1][1]), cvtpk(a[2 * q + 1][2], a[2 * q + 1][3])};
;                   *(u32x4*)(mf + q * 512 * 8) = w4; }
;               } else store_nat_m(MERGED + (long)(brow + wr0 + m * 16 + fq * 4) * 1024 + bcol + wc0, 1024, a, fr);
.LBB0_2622:
	v_lshlrev_b32_e32 v96, 16, v98
	v_and_b32_e32 v97, 0xffff0000, v98
	v_pk_mul_f32 v[64:65], v[64:65], v[96:97]
	v_lshlrev_b32_e32 v96, 16, v99
	v_and_b32_e32 v97, 0xffff0000, v99
	s_and_b64 vcc, exec, s[4:5]
	v_pk_mul_f32 v[66:67], v[66:67], v[96:97]
	s_cbranch_vccnz .LBB0_2689
	v_lshlrev_b32_e32 v96, 16, v102
	v_and_b32_e32 v97, 0xffff0000, v102
	v_pk_add_f32 v[64:65], v[64:65], v[96:97]
	v_lshlrev_b32_e32 v96, 16, v103
	v_and_b32_e32 v97, 0xffff0000, v103
	v_pk_add_f32 v[66:67], v[66:67], v[96:97]
	s_cmp_eq_u32 s37, 2
	s_mov_b64 s[2:3], -1
	s_cbranch_scc0 .LBB0_2690
	s_mov_b64 s[2:3], s[0:1]
	s_load_dwordx2 s[2:3], s[2:3], 0xe8
	v_and_b32_e32 v96, 1, v165
	v_cmp_eq_u32_e64 s[8:9], 0, v96
	v_cmp_eq_u32_e64 s[6:7], 1, v96
	s_nop 0
	v_cndmask_b32_e64 v96, v92, v88, s[8:9]
	s_nop 1
	v_mov_b32_dpp v96, v96 quad_perm:[1,0,3,2] row_mask:0xf bank_mask:0xf bound_ctrl:1
	v_cndmask_b32_e64 v98, v92, v96, s[6:7]
	v_cndmask_b32_e64 v96, v96, v88, s[6:7]
	v_cvt_pk_bf16_f32 v98, v98, v96
	v_lshl_or_b32 v96, v131, 2, v136
	v_add3_u32 v96, s39, v96, 16
	v_ashrrev_i32_e32 v97, 31, v96
	v_lshlrev_b64 v[96:97], 11, v[96:97]
	s_waitcnt lgkmcnt(0)
	v_lshl_add_u64 v[96:97], s[2:3], 0, v[96:97]
	s_lshl_b32 s12, s38, 1
	v_add_u32_e32 v99, 15, v164
	v_lshl_add_u64 v[96:97], v[96:97], 0, s[12:13]
	v_lshlrev_b32_e32 v176, 1, v130
	v_cndmask_b32_e64 v99, v99, v164, s[8:9]
	v_lshl_add_u64 v[96:97], v[96:97], 0, v[176:177]
	v_lshlrev_b32_e32 v176, 1, v99
	v_lshl_add_u64 v[96:97], v[96:97], 0, v[176:177]
	v_add_co_u32_e32 v100, vcc, 0x38720000, v96
	s_nop 1
	v_addc_co_u32_e32 v101, vcc, 0, v97, vcc
	global_store_dword v[100:101], v98, off
	v_cndmask_b32_e64 v98, v84, v80, s[8:9]
	s_nop 1
	v_mov_b32_dpp v99, v98 quad_perm:[1,0,3,2] row_mask:0xf bank_mask:0xf bound_ctrl:1
	v_cndmask_b32_e64 v98, v84, v99, s[6:7]
	v_cndmask_b32_e64 v99, v99, v80, s[6:7]
	v_cvt_pk_bf16_f32 v98, v98, v99
	s_mov_b64 s[2:3], 0x38720000
	v_lshl_add_u64 v[96:97], v[96:97], 0, s[2:3]
	global_store_dword v[96:97], v98, off offset:64
	v_cndmask_b32_e64 v98, v76, v72, s[8:9]
	s_nop 1
	v_mov_b32_dpp v99, v98 quad_perm:[1,0,3,2] row_mask:0xf bank_mask:0xf bound_ctrl:1
	v_cndmask_b32_e64 v98, v76, v99, s[6:7]
	v_cndmask_b32_e64 v99, v99, v72, s[6:7]
	v_cvt_pk_bf16_f32 v98, v98, v99
	global_store_dword v[96:97], v98, off offset:128
	v_cndmask_b32_e64 v98, v68, v64, s[8:9]
	s_nop 1
	v_mov_b32_dpp v99, v98 quad_perm:[1,0,3,2] row_mask:0xf bank_mask:0xf bound_ctrl:1
	v_cndmask_b32_e64 v98, v68, v99, s[6:7]
	v_cndmask_b32_e64 v99, v99, v64, s[6:7]
	v_cvt_pk_bf16_f32 v98, v98, v99
	global_store_dword v[96:97], v98, off offset:192
	v_cndmask_b32_e64 v98, v93, v89, s[8:9]
	s_nop 1
	v_mov_b32_dpp v99, v98 quad_perm:[1,0,3,2] row_mask:0xf bank_mask:0xf bound_ctrl:1
	v_cndmask_b32_e64 v98, v93, v99, s[6:7]
	v_cndmask_b32_e64 v99, v99, v89, s[6:7]
	v_cvt_pk_bf16_f32 v98, v98, v99
	global_store_dword v[96:97], v98, off offset:2048
	v_cndmask_b32_e64 v98, v85, v81, s[8:9]
	s_nop 1
	v_mov_b32_dpp v99, v98 quad_perm:[1,0,3,2] row_mask:0xf bank_mask:0xf bound_ctrl:1
	v_cndmask_b32_e64 v98, v85, v99, s[6:7]
	v_cndmask_b32_e64 v99, v99, v81, s[6:7]
	v_cvt_pk_bf16_f32 v98, v98, v99
	global_store_dword v[96:97], v98, off offset:2112
	v_cndmask_b32_e64 v98, v77, v73, s[8:9]
	s_nop 1
	v_mov_b32_dpp v99, v98 quad_perm:[1,0,3,2] row_mask:0xf bank_mask:0xf bound_ctrl:1
	v_cndmask_b32_e64 v98, v77, v99, s[6:7]
	v_cndmask_b32_e64 v99, v99, v73, s[6:7]
	v_cvt_pk_bf16_f32 v98, v98, v99
	global_store_dword v[96:97], v98, off offset:2176
	v_cndmask_b32_e64 v98, v69, v65, s[8:9]
	s_nop 1
	v_mov_b32_dpp v99, v98 quad_perm:[1,0,3,2] row_mask:0xf bank_mask:0xf bound_ctrl:1
	v_cndmask_b32_e64 v98, v69, v99, s[6:7]
	v_cndmask_b32_e64 v99, v99, v65, s[6:7]
	v_cvt_pk_bf16_f32 v98, v98, v99
	global_store_dword v[96:97], v98, off offset:2240
	v_cndmask_b32_e64 v98, v94, v90, s[8:9]
	s_nop 1
	v_mov_b32_dpp v99, v98 quad_perm:[1,0,3,2] row_mask:0xf bank_mask:0xf bound_ctrl:1
	v_cndmask_b32_e64 v98, v94, v99, s[6:7]
	v_cndmask_b32_e64 v99, v99, v90, s[6:7]
	v_cvt_pk_bf16_f32 v98, v98, v99
	v_add_co_u32_e32 v100, vcc, 0x1000, v96
	s_nop 1
	v_addc_co_u32_e32 v101, vcc, 0, v97, vcc
	global_store_dword v[100:101], v98, off
	v_cndmask_b32_e64 v98, v86, v82, s[8:9]
	s_nop 1
	v_mov_b32_dpp v99, v98 quad_perm:[1,0,3,2] row_mask:0xf bank_mask:0xf bound_ctrl:1
	v_cndmask_b32_e64 v98, v86, v99, s[6:7]
	v_cndmask_b32_e64 v99, v99, v82, s[6:7]
	v_cvt_pk_bf16_f32 v98, v98, v99
	v_add_co_u32_e32 v100, vcc, 0x1000, v96
	s_nop 1
	v_addc_co_u32_e32 v101, vcc, 0, v97, vcc
	global_store_dword v[100:101], v98, off offset:64
	v_cndmask_b32_e64 v98, v78, v74, s[8:9]
	s_nop 1
	v_mov_b32_dpp v99, v98 quad_perm:[1,0,3,2] row_mask:0xf bank_mask:0xf bound_ctrl:1
	v_cndmask_b32_e64 v98, v78, v99, s[6:7]
	v_cndmask_b32_e64 v99, v99, v74, s[6:7]
	v_cvt_pk_bf16_f32 v98, v98, v99
	v_add_co_u32_e32 v100, vcc, 0x1000, v96
	s_nop 1
	v_addc_co_u32_e32 v101, vcc, 0, v97, vcc
	global_store_dword v[100:101], v98, off offset:128
	v_cndmask_b32_e64 v98, v70, v66, s[8:9]
	s_nop 1
	v_mov_b32_dpp v99, v98 quad_perm:[1,0,3,2] row_mask:0xf bank_mask:0xf bound_ctrl:1
	v_cndmask_b32_e64 v98, v70, v99, s[6:7]
	v_cndmask_b32_e64 v99, v99, v66, s[6:7]
	v_cvt_pk_bf16_f32 v98, v98, v99
	v_add_co_u32_e32 v100, vcc, 0x1000, v96
	s_nop 1
	v_addc_co_u32_e32 v101, vcc, 0, v97, vcc
	global_store_dword v[100:101], v98, off offset:192
	v_cndmask_b32_e64 v98, v95, v91, s[8:9]
	s_nop 1
	v_mov_b32_dpp v99, v98 quad_perm:[1,0,3,2] row_mask:0xf bank_mask:0xf bound_ctrl:1
	v_cndmask_b32_e64 v98, v95, v99, s[6:7]
	v_cndmask_b32_e64 v99, v99, v91, s[6:7]
	v_cvt_pk_bf16_f32 v98, v98, v99
	v_add_co_u32_e32 v100, vcc, 0x1000, v96
	s_nop 1
	v_addc_co_u32_e32 v101, vcc, 0, v97, vcc
	global_store_dword v[100:101], v98, off offset:2048
	v_cndmask_b32_e64 v98, v87, v83, s[8:9]
	s_nop 1
	v_mov_b32_dpp v99, v98 quad_perm:[1,0,3,2] row_mask:0xf bank_mask:0xf bound_ctrl:1
	v_cndmask_b32_e64 v98, v87, v99, s[6:7]
	v_cndmask_b32_e64 v99, v99, v83, s[6:7]
	v_cvt_pk_bf16_f32 v98, v98, v99
	v_add_co_u32_e32 v100, vcc, 0x1000, v96
	s_nop 1
	v_addc_co_u32_e32 v101, vcc, 0, v97, vcc
	global_store_dword v[100:101], v98, off offset:2112
	v_cndmask_b32_e64 v98, v79, v75, s[8:9]
	s_nop 1
	v_mov_b32_dpp v99, v98 quad_perm:[1,0,3,2] row_mask:0xf bank_mask:0xf bound_ctrl:1
	v_cndmask_b32_e64 v98, v79, v99, s[6:7]
	v_cndmask_b32_e64 v99, v99, v75, s[6:7]
	v_cvt_pk_bf16_f32 v98, v98, v99
	v_add_co_u32_e32 v100, vcc, 0x1000, v96
	s_nop 1
	v_addc_co_u32_e32 v101, vcc, 0, v97, vcc
	global_store_dword v[100:101], v98, off offset:2176
	v_cndmask_b32_e64 v98, v71, v67, s[8:9]
	s_nop 1
	v_mov_b32_dpp v99, v98 quad_perm:[1,0,3,2] row_mask:0xf bank_mask:0xf bound_ctrl:1
	v_cndmask_b32_e64 v98, v71, v99, s[6:7]
	v_cndmask_b32_e64 v99, v99, v67, s[6:7]
	v_cvt_pk_bf16_f32 v98, v98, v99
	v_add_co_u32_e32 v96, vcc, 0x1000, v96
	s_mov_b64 s[2:3], 0
	s_nop 0
	v_addc_co_u32_e32 v97, vcc, 0, v97, vcc
	global_store_dword v[96:97], v98, off offset:2240
	s_branch .LBB0_2690

; DEVFI float dpp_xor1(float x) { return __int_as_float(__builtin_amdgcn_update_dpp(0, __float_as_int(x), 0xB1, 0xF, 0xF, true)); }
; #define MERGED ((bfraw*)(kargs()->ws + O_MERGED))
; DEVFI void store_nat_m(bfraw* base, long ld, f32x4 (&a)[8], int fr) {
;   const bool odd = fr & 1;
;   bfraw* p0 = base + (odd ? 15 + fr : fr);
; #pragma unroll
;   for (int j = 0; j < 4; ++j)
; #pragma unroll
;     for (int n0 = 0; n0 < 8; n0 += 2) { const float own0 = a[n0][j], own1 = a[n0 + 1][j];
;       const float recv = dpp_xor1(odd ? own0 : own1);
;       const unsigned pk = odd ? cvtpk(recv, own1) : cvtpk(own0, recv);
;       *reinterpret_cast<unsigned*>(p0 + (long)j * ld + n0 * 16) = pk; }
; }
; __global__ void __launch_bounds__(512) mega(Params p) {
;     ...
;               if (pass != 0) {
; #pragma unroll
;                 for (int q = 0; q < 4; ++q) p4[q] = *(const u32x4*)(mf + q * 512 * 8); }
; #pragma unroll
;               for (int n = 0; n < 8; ++n) { const unsigned lo = g4[n >> 1][(n & 1) * 2], hi = g4[n >> 1][(n & 1) * 2 + 1];
;                 const float g0 = __uint_as_float(lo << 16), g1 = __uint_as_float(lo & 0xffff0000u), g2 = __uint_as_float(hi << 16), g3 = __uint_as_float(hi & 0xffff0000u);
;                 a[n][0] *= g0; a[n][1] *= g1; a[n][2] *= g2; a[n][3] *= g3;
;                 if (pass != 0) { const unsigned plo = p4[n >> 1][(n & 1) * 2], phi = p4[n >> 1][(n & 1) * 2 + 1];
;                   a[n][0] += __uint_as_float(plo << 16); a[n][1] += __uint_as_float(plo & 0xffff0000u); a[n][2] += __uint_as_float(phi << 16); a[n][3] += __uint_as_float(phi & 0xffff0000u); } }
;               if (pass != 2) {
; #pragma unroll
;                 for (int q = 0; q < 4; ++q) { u32x4 w4 = {cvtpk(a[2 * q][0], a[2 * q][1]), cvtpk(a[2 * q][2], a[2 * q][3]), cvtpk(a[2 * q + 1][0], a[2 * q + 1][1]), cvtpk(a[2 * q + 1][2], a[2 * q + 1][3])};
;                   *(u32x4*)(mf + q * 512 * 8) = w4; }
;               } else store_nat_m(MERGED + (long)(brow + wr0 + m * 16 + fq * 4) * 1024 + bcol + wc0, 1024, a, fr);
.LBB0_2708:
	v_lshlrev_b32_e32 v64, 16, v66
	v_and_b32_e32 v65, 0xffff0000, v66
	v_pk_mul_f32 v[32:33], v[32:33], v[64:65]
	v_lshlrev_b32_e32 v64, 16, v67
	v_and_b32_e32 v65, 0xffff0000, v67
	s_and_b64 vcc, exec, s[4:5]
	v_pk_mul_f32 v[34:35], v[34:35], v[64:65]
	s_cbranch_vccnz .LBB0_2775
	v_lshlrev_b32_e32 v64, 16, v70
	v_and_b32_e32 v65, 0xffff0000, v70
	v_pk_add_f32 v[32:33], v[32:33], v[64:65]
	v_lshlrev_b32_e32 v64, 16, v71
	v_and_b32_e32 v65, 0xffff0000, v71
	v_pk_add_f32 v[34:35], v[34:35], v[64:65]
	s_cmp_eq_u32 s37, 2
	s_mov_b64 s[2:3], -1
	s_cbranch_scc0 .LBB0_2776
	s_mov_b64 s[2:3], s[0:1]
	s_load_dwordx2 s[2:3], s[2:3], 0xe8
	v_and_b32_e32 v64, 1, v165
	v_cmp_eq_u32_e64 s[8:9], 0, v64
	v_cmp_eq_u32_e64 s[6:7], 1, v64
	s_nop 0
	v_cndmask_b32_e64 v64, v60, v56, s[8:9]
	s_nop 1
	v_mov_b32_dpp v64, v64 quad_perm:[1,0,3,2] row_mask:0xf bank_mask:0xf bound_ctrl:1
	v_cndmask_b32_e64 v66, v60, v64, s[6:7]
	v_cndmask_b32_e64 v64, v64, v56, s[6:7]
	v_cvt_pk_bf16_f32 v66, v66, v64
	v_lshl_or_b32 v64, v131, 2, v136
	v_add3_u32 v64, s39, v64, 32
	v_ashrrev_i32_e32 v65, 31, v64
	v_lshlrev_b64 v[64:65], 11, v[64:65]
	s_waitcnt lgkmcnt(0)
	v_lshl_add_u64 v[64:65], s[2:3], 0, v[64:65]
	s_lshl_b32 s12, s38, 1
	v_add_u32_e32 v67, 15, v164
	v_lshl_add_u64 v[64:65], v[64:65], 0, s[12:13]
	v_lshlrev_b32_e32 v176, 1, v130
	v_cndmask_b32_e64 v67, v67, v164, s[8:9]
	v_lshl_add_u64 v[64:65], v[64:65], 0, v[176:177]
	v_lshlrev_b32_e32 v176, 1, v67
	v_lshl_add_u64 v[64:65], v[64:65], 0, v[176:177]
	v_add_co_u32_e32 v68, vcc, 0x38720000, v64
	s_nop 1
	v_addc_co_u32_e32 v69, vcc, 0, v65, vcc
	global_store_dword v[68:69], v66, off
	v_cndmask_b32_e64 v66, v52, v48, s[8:9]
	s_nop 1
	v_mov_b32_dpp v67, v66 quad_perm:[1,0,3,2] row_mask:0xf bank_mask:0xf bound_ctrl:1
	v_cndmask_b32_e64 v66, v52, v67, s[6:7]
	v_cndmask_b32_e64 v67, v67, v48, s[6:7]
	v_cvt_pk_bf16_f32 v66, v66, v67
	s_mov_b64 s[2:3], 0x38720000
	v_lshl_add_u64 v[64:65], v[64:65], 0, s[2:3]
	global_store_dword v[64:65], v66, off offset:64
	v_cndmask_b32_e64 v66, v44, v40, s[8:9]
	s_nop 1
	v_mov_b32_dpp v67, v66 quad_perm:[1,0,3,2] row_mask:0xf bank_mask:0xf bound_ctrl:1
	v_cndmask_b32_e64 v66, v44, v67, s[6:7]
	v_cndmask_b32_e64 v67, v67, v40, s[6:7]
	v_cvt_pk_bf16_f32 v66, v66, v67
	global_store_dword v[64:65], v66, off offset:128
	v_cndmask_b32_e64 v66, v36, v32, s[8:9]
	s_nop 1
	v_mov_b32_dpp v67, v66 quad_perm:[1,0,3,2] row_mask:0xf bank_mask:0xf bound_ctrl:1
	v_cndmask_b32_e64 v66, v36, v67, s[6:7]
	v_cndmask_b32_e64 v67, v67, v32, s[6:7]
	v_cvt_pk_bf16_f32 v66, v66, v67
	global_store_dword v[64:65], v66, off offset:192
	v_cndmask_b32_e64 v66, v61, v57, s[8:9]
	s_nop 1
	v_mov_b32_dpp v67, v66 quad_perm:[1,0,3,2] row_mask:0xf bank_mask:0xf bound_ctrl:1
	v_cndmask_b32_e64 v66, v61, v67, s[6:7]
	v_cndmask_b32_e64 v67, v67, v57, s[6:7]
	v_cvt_pk_bf16_f32 v66, v66, v67
	global_store_dword v[64:65], v66, off offset:2048
	v_cndmask_b32_e64 v66, v53, v49, s[8:9]
	s_nop 1
	v_mov_b32_dpp v67, v66 quad_perm:[1,0,3,2] row_mask:0xf bank_mask:0xf bound_ctrl:1
	v_cndmask_b32_e64 v66, v53, v67, s[6:7]
	v_cndmask_b32_e64 v67, v67, v49, s[6:7]
	v_cvt_pk_bf16_f32 v66, v66, v67
	global_store_dword v[64:65], v66, off offset:2112
	v_cndmask_b32_e64 v66, v45, v41, s[8:9]
	s_nop 1
	v_mov_b32_dpp v67, v66 quad_perm:[1,0,3,2] row_mask:0xf bank_mask:0xf bound_ctrl:1
	v_cndmask_b32_e64 v66, v45, v67, s[6:7]
	v_cndmask_b32_e64 v67, v67, v41, s[6:7]
	v_cvt_pk_bf16_f32 v66, v66, v67
	global_store_dword v[64:65], v66, off offset:2176
	v_cndmask_b32_e64 v66, v37, v33, s[8:9]
	s_nop 1
	v_mov_b32_dpp v67, v66 quad_perm:[1,0,3,2] row_mask:0xf bank_mask:0xf bound_ctrl:1
	v_cndmask_b32_e64 v66, v37, v67, s[6:7]
	v_cndmask_b32_e64 v67, v67, v33, s[6:7]
	v_cvt_pk_bf16_f32 v66, v66, v67
	global_store_dword v[64:65], v66, off offset:2240
	v_cndmask_b32_e64 v66, v62, v58, s[8:9]
	s_nop 1
	v_mov_b32_dpp v67, v66 quad_perm:[1,0,3,2] row_mask:0xf bank_mask:0xf bound_ctrl:1
	v_cndmask_b32_e64 v66, v62, v67, s[6:7]
	v_cndmask_b32_e64 v67, v67, v58, s[6:7]
	v_cvt_pk_bf16_f32 v66, v66, v67
	v_add_co_u32_e32 v68, vcc, 0x1000, v64
	s_nop 1
	v_addc_co_u32_e32 v69, vcc, 0, v65, vcc
	global_store_dword v[68:69], v66, off
	v_cndmask_b32_e64 v66, v54, v50, s[8:9]
	s_nop 1
	v_mov_b32_dpp v67, v66 quad_perm:[1,0,3,2] row_mask:0xf bank_mask:0xf bound_ctrl:1
	v_cndmask_b32_e64 v66, v54, v67, s[6:7]
	v_cndmask_b32_e64 v67, v67, v50, s[6:7]
	v_cvt_pk_bf16_f32 v66, v66, v67
	v_add_co_u32_e32 v68, vcc, 0x1000, v64
	s_nop 1
	v_addc_co_u32_e32 v69, vcc, 0, v65, vcc
	global_store_dword v[68:69], v66, off offset:64
	v_cndmask_b32_e64 v66, v46, v42, s[8:9]
	s_nop 1
	v_mov_b32_dpp v67, v66 quad_perm:[1,0,3,2] row_mask:0xf bank_mask:0xf bound_ctrl:1
	v_cndmask_b32_e64 v66, v46, v67, s[6:7]
	v_cndmask_b32_e64 v67, v67, v42, s[6:7]
	v_cvt_pk_bf16_f32 v66, v66, v67
	v_add_co_u32_e32 v68, vcc, 0x1000, v64
	s_nop 1
	v_addc_co_u32_e32 v69, vcc, 0, v65, vcc
	global_store_dword v[68:69], v66, off offset:128
	v_cndmask_b32_e64 v66, v38, v34, s[8:9]
	s_nop 1
	v_mov_b32_dpp v67, v66 quad_perm:[1,0,3,2] row_mask:0xf bank_mask:0xf bound_ctrl:1
	v_cndmask_b32_e64 v66, v38, v67, s[6:7]
	v_cndmask_b32_e64 v67, v67, v34, s[6:7]
	v_cvt_pk_bf16_f32 v66, v66, v67
	v_add_co_u32_e32 v68, vcc, 0x1000, v64
	s_nop 1
	v_addc_co_u32_e32 v69, vcc, 0, v65, vcc
	global_store_dword v[68:69], v66, off offset:192
	v_cndmask_b32_e64 v66, v63, v59, s[8:9]
	s_nop 1
	v_mov_b32_dpp v67, v66 quad_perm:[1,0,3,2] row_mask:0xf bank_mask:0xf bound_ctrl:1
	v_cndmask_b32_e64 v66, v63, v67, s[6:7]
	v_cndmask_b32_e64 v67, v67, v59, s[6:7]
	v_cvt_pk_bf16_f32 v66, v66, v67
	v_add_co_u32_e32 v68, vcc, 0x1000, v64
	s_nop 1
	v_addc_co_u32_e32 v69, vcc, 0, v65, vcc
	global_store_dword v[68:69], v66, off offset:2048
	v_cndmask_b32_e64 v66, v55, v51, s[8:9]
	s_nop 1
	v_mov_b32_dpp v67, v66 quad_perm:[1,0,3,2] row_mask:0xf bank_mask:0xf bound_ctrl:1
	v_cndmask_b32_e64 v66, v55, v67, s[6:7]
	v_cndmask_b32_e64 v67, v67, v51, s[6:7]
	v_cvt_pk_bf16_f32 v66, v66, v67
	v_add_co_u32_e32 v68, vcc, 0x1000, v64
	s_nop 1
	v_addc_co_u32_e32 v69, vcc, 0, v65, vcc
	global_store_dword v[68:69], v66, off offset:2112
	v_cndmask_b32_e64 v66, v47, v43, s[8:9]
	s_nop 1
	v_mov_b32_dpp v67, v66 quad_perm:[1,0,3,2] row_mask:0xf bank_mask:0xf bound_ctrl:1
	v_cndmask_b32_e64 v66, v47, v67, s[6:7]
	v_cndmask_b32_e64 v67, v67, v43, s[6:7]
	v_cvt_pk_bf16_f32 v66, v66, v67
	v_add_co_u32_e32 v68, vcc, 0x1000, v64
	s_nop 1
	v_addc_co_u32_e32 v69, vcc, 0, v65, vcc
	global_store_dword v[68:69], v66, off offset:2176
	v_cndmask_b32_e64 v66, v39, v35, s[8:9]
	s_nop 1
	v_mov_b32_dpp v67, v66 quad_perm:[1,0,3,2] row_mask:0xf bank_mask:0xf bound_ctrl:1
	v_cndmask_b32_e64 v66, v39, v67, s[6:7]
	v_cndmask_b32_e64 v67, v67, v35, s[6:7]
	v_cvt_pk_bf16_f32 v66, v66, v67
	v_add_co_u32_e32 v64, vcc, 0x1000, v64
	s_mov_b64 s[2:3], 0
	s_nop 0
	v_addc_co_u32_e32 v65, vcc, 0, v65, vcc
	global_store_dword v[64:65], v66, off offset:2240
	s_branch .LBB0_2776

; DEVFI float dpp_xor1(float x) { return __int_as_float(__builtin_amdgcn_update_dpp(0, __float_as_int(x), 0xB1, 0xF, 0xF, true)); }
; #define MERGED ((bfraw*)(kargs()->ws + O_MERGED))
; DEVFI void store_nat_m(bfraw* base, long ld, f32x4 (&a)[8], int fr) {
;   const bool odd = fr & 1;
;   bfraw* p0 = base + (odd ? 15 + fr : fr);
; #pragma unroll
;   for (int j = 0; j < 4; ++j)
; #pragma unroll
;     for (int n0 = 0; n0 < 8; n0 += 2) { const float own0 = a[n0][j], own1 = a[n0 + 1][j];
;       const float recv = dpp_xor1(odd ? own0 : own1);
;       const unsigned pk = odd ? cvtpk(recv, own1) : cvtpk(own0, recv);
;       *reinterpret_cast<unsigned*>(p0 + (long)j * ld + n0 * 16) = pk; }
; }
; __global__ void __launch_bounds__(512) mega(Params p) {
;     ...
;               if (pass != 0) {
; #pragma unroll
;                 for (int q = 0; q < 4; ++q) p4[q] = *(const u32x4*)(mf + q * 512 * 8); }
; #pragma unroll
;               for (int n = 0; n < 8; ++n) { const unsigned lo = g4[n >> 1][(n & 1) * 2], hi = g4[n >> 1][(n & 1) * 2 + 1];
;                 const float g0 = __uint_as_float(lo << 16), g1 = __uint_as_float(lo & 0xffff0000u), g2 = __uint_as_float(hi << 16), g3 = __uint_as_float(hi & 0xffff0000u);
;                 a[n][0] *= g0; a[n][1] *= g1; a[n][2] *= g2; a[n][3] *= g3;
;                 if (pass != 0) { const unsigned plo = p4[n >> 1][(n & 1) * 2], phi = p4[n >> 1][(n & 1) * 2 + 1];
;                   a[n][0] += __uint_as_float(plo << 16); a[n][1] += __uint_as_float(plo & 0xffff0000u); a[n][2] += __uint_as_float(phi << 16); a[n][3] += __uint_as_float(phi & 0xffff0000u); } }
;               if (pass != 2) {
; #pragma unroll
;                 for (int q = 0; q < 4; ++q) { u32x4 w4 = {cvtpk(a[2 * q][0], a[2 * q][1]), cvtpk(a[2 * q][2], a[2 * q][3]), cvtpk(a[2 * q + 1][0], a[2 * q + 1][1]), cvtpk(a[2 * q + 1][2], a[2 * q + 1][3])};
;                   *(u32x4*)(mf + q * 512 * 8) = w4; }
;               } else store_nat_m(MERGED + (long)(brow + wr0 + m * 16 + fq * 4) * 1024 + bcol + wc0, 1024, a, fr);
.LBB0_2794:
	v_lshlrev_b32_e32 v32, 16, v34
	v_and_b32_e32 v33, 0xffff0000, v34
	v_pk_mul_f32 v[0:1], v[0:1], v[32:33]
	v_lshlrev_b32_e32 v32, 16, v35
	v_and_b32_e32 v33, 0xffff0000, v35
	s_and_b64 vcc, exec, s[4:5]
	v_pk_mul_f32 v[2:3], v[2:3], v[32:33]
	s_cbranch_vccnz .LBB0_2861
	v_lshlrev_b32_e32 v32, 16, v38
	v_and_b32_e32 v33, 0xffff0000, v38
	v_pk_add_f32 v[0:1], v[0:1], v[32:33]
	v_lshlrev_b32_e32 v32, 16, v39
	v_and_b32_e32 v33, 0xffff0000, v39
	v_pk_add_f32 v[2:3], v[2:3], v[32:33]
	s_cmp_eq_u32 s37, 2
	s_mov_b64 s[18:19], -1
	s_cbranch_scc0 .LBB0_2861
	s_mov_b64 s[2:3], s[0:1]
	s_load_dwordx2 s[2:3], s[2:3], 0xe8
	v_and_b32_e32 v32, 1, v165
	v_cmp_eq_u32_e64 s[6:7], 0, v32
	v_cmp_eq_u32_e64 s[4:5], 1, v32
	s_nop 0
	v_cndmask_b32_e64 v32, v28, v24, s[6:7]
	s_nop 1
	v_mov_b32_dpp v32, v32 quad_perm:[1,0,3,2] row_mask:0xf bank_mask:0xf bound_ctrl:1
	v_cndmask_b32_e64 v34, v28, v32, s[4:5]
	v_cndmask_b32_e64 v32, v32, v24, s[4:5]
	v_cvt_pk_bf16_f32 v34, v34, v32
	v_lshl_or_b32 v32, v131, 2, v136
	v_add3_u32 v32, s39, v32, 48
	v_ashrrev_i32_e32 v33, 31, v32
	v_lshlrev_b64 v[32:33], 11, v[32:33]
	s_waitcnt lgkmcnt(0)
	v_lshl_add_u64 v[32:33], s[2:3], 0, v[32:33]
	s_lshl_b32 s12, s38, 1
	v_add_u32_e32 v35, 15, v164
	v_lshl_add_u64 v[32:33], v[32:33], 0, s[12:13]
	v_lshlrev_b32_e32 v176, 1, v130
	v_cndmask_b32_e64 v35, v35, v164, s[6:7]
	v_lshl_add_u64 v[32:33], v[32:33], 0, v[176:177]
	v_lshlrev_b32_e32 v176, 1, v35
	v_lshl_add_u64 v[32:33], v[32:33], 0, v[176:177]
	v_add_co_u32_e32 v36, vcc, 0x38720000, v32
	s_nop 1
	v_addc_co_u32_e32 v37, vcc, 0, v33, vcc
	global_store_dword v[36:37], v34, off
	v_cndmask_b32_e64 v34, v20, v16, s[6:7]
	s_nop 1
	v_mov_b32_dpp v35, v34 quad_perm:[1,0,3,2] row_mask:0xf bank_mask:0xf bound_ctrl:1
	v_cndmask_b32_e64 v34, v20, v35, s[4:5]
	v_cndmask_b32_e64 v35, v35, v16, s[4:5]
	v_cvt_pk_bf16_f32 v34, v34, v35
	s_mov_b64 s[2:3], 0x38720000
	v_lshl_add_u64 v[32:33], v[32:33], 0, s[2:3]
	global_store_dword v[32:33], v34, off offset:64
	v_cndmask_b32_e64 v34, v12, v8, s[6:7]
	s_nop 1
	v_mov_b32_dpp v35, v34 quad_perm:[1,0,3,2] row_mask:0xf bank_mask:0xf bound_ctrl:1
	v_cndmask_b32_e64 v34, v12, v35, s[4:5]
	v_cndmask_b32_e64 v35, v35, v8, s[4:5]
	v_cvt_pk_bf16_f32 v34, v34, v35
	global_store_dword v[32:33], v34, off offset:128
	v_cndmask_b32_e64 v34, v4, v0, s[6:7]
	s_nop 1
	v_mov_b32_dpp v35, v34 quad_perm:[1,0,3,2] row_mask:0xf bank_mask:0xf bound_ctrl:1
	v_cndmask_b32_e64 v34, v4, v35, s[4:5]
	v_cndmask_b32_e64 v35, v35, v0, s[4:5]
	v_cvt_pk_bf16_f32 v34, v34, v35
	global_store_dword v[32:33], v34, off offset:192
	v_cndmask_b32_e64 v34, v29, v25, s[6:7]
	s_nop 1
	v_mov_b32_dpp v35, v34 quad_perm:[1,0,3,2] row_mask:0xf bank_mask:0xf bound_ctrl:1
	v_cndmask_b32_e64 v34, v29, v35, s[4:5]
	v_cndmask_b32_e64 v35, v35, v25, s[4:5]
	v_cvt_pk_bf16_f32 v34, v34, v35
	global_store_dword v[32:33], v34, off offset:2048
	v_cndmask_b32_e64 v34, v21, v17, s[6:7]
	s_nop 1
	v_mov_b32_dpp v35, v34 quad_perm:[1,0,3,2] row_mask:0xf bank_mask:0xf bound_ctrl:1
	v_cndmask_b32_e64 v34, v21, v35, s[4:5]
	v_cndmask_b32_e64 v35, v35, v17, s[4:5]
	v_cvt_pk_bf16_f32 v34, v34, v35
	global_store_dword v[32:33], v34, off offset:2112
	v_cndmask_b32_e64 v34, v13, v9, s[6:7]
	s_nop 1
	v_mov_b32_dpp v35, v34 quad_perm:[1,0,3,2] row_mask:0xf bank_mask:0xf bound_ctrl:1
	v_cndmask_b32_e64 v34, v13, v35, s[4:5]
	v_cndmask_b32_e64 v35, v35, v9, s[4:5]
	v_cvt_pk_bf16_f32 v34, v34, v35
	global_store_dword v[32:33], v34, off offset:2176
	v_cndmask_b32_e64 v34, v5, v1, s[6:7]
	s_nop 1
	v_mov_b32_dpp v35, v34 quad_perm:[1,0,3,2] row_mask:0xf bank_mask:0xf bound_ctrl:1
	v_cndmask_b32_e64 v34, v5, v35, s[4:5]
	v_cndmask_b32_e64 v35, v35, v1, s[4:5]
	v_cvt_pk_bf16_f32 v34, v34, v35
	global_store_dword v[32:33], v34, off offset:2240
	v_cndmask_b32_e64 v34, v30, v26, s[6:7]
	s_nop 1
	v_mov_b32_dpp v35, v34 quad_perm:[1,0,3,2] row_mask:0xf bank_mask:0xf bound_ctrl:1
	v_cndmask_b32_e64 v34, v30, v35, s[4:5]
	v_cndmask_b32_e64 v35, v35, v26, s[4:5]
	v_cvt_pk_bf16_f32 v34, v34, v35
	v_add_co_u32_e32 v36, vcc, 0x1000, v32
	s_nop 1
	v_addc_co_u32_e32 v37, vcc, 0, v33, vcc
	global_store_dword v[36:37], v34, off
	v_cndmask_b32_e64 v34, v22, v18, s[6:7]
	s_nop 1
	v_mov_b32_dpp v35, v34 quad_perm:[1,0,3,2] row_mask:0xf bank_mask:0xf bound_ctrl:1
	v_cndmask_b32_e64 v34, v22, v35, s[4:5]
	v_cndmask_b32_e64 v35, v35, v18, s[4:5]
	v_cvt_pk_bf16_f32 v34, v34, v35
	v_add_co_u32_e32 v36, vcc, 0x1000, v32
	s_nop 1
	v_addc_co_u32_e32 v37, vcc, 0, v33, vcc
	global_store_dword v[36:37], v34, off offset:64
	v_cndmask_b32_e64 v34, v14, v10, s[6:7]
	s_nop 1
	v_mov_b32_dpp v35, v34 quad_perm:[1,0,3,2] row_mask:0xf bank_mask:0xf bound_ctrl:1
	v_cndmask_b32_e64 v34, v14, v35, s[4:5]
	v_cndmask_b32_e64 v35, v35, v10, s[4:5]
	v_cvt_pk_bf16_f32 v34, v34, v35
	v_add_co_u32_e32 v36, vcc, 0x1000, v32
	s_nop 1
	v_addc_co_u32_e32 v37, vcc, 0, v33, vcc
	global_store_dword v[36:37], v34, off offset:128
	v_cndmask_b32_e64 v34, v6, v2, s[6:7]
	s_nop 1
	v_mov_b32_dpp v35, v34 quad_perm:[1,0,3,2] row_mask:0xf bank_mask:0xf bound_ctrl:1
	v_cndmask_b32_e64 v34, v6, v35, s[4:5]
	v_cndmask_b32_e64 v35, v35, v2, s[4:5]
	v_cvt_pk_bf16_f32 v34, v34, v35
	v_add_co_u32_e32 v36, vcc, 0x1000, v32
	s_nop 1
	v_addc_co_u32_e32 v37, vcc, 0, v33, vcc
	global_store_dword v[36:37], v34, off offset:192
	v_cndmask_b32_e64 v34, v31, v27, s[6:7]
	s_nop 1
	v_mov_b32_dpp v35, v34 quad_perm:[1,0,3,2] row_mask:0xf bank_mask:0xf bound_ctrl:1
	v_cndmask_b32_e64 v34, v31, v35, s[4:5]
	v_cndmask_b32_e64 v35, v35, v27, s[4:5]
	v_cvt_pk_bf16_f32 v34, v34, v35
	v_add_co_u32_e32 v36, vcc, 0x1000, v32
	s_nop 1
	v_addc_co_u32_e32 v37, vcc, 0, v33, vcc
	global_store_dword v[36:37], v34, off offset:2048
	v_cndmask_b32_e64 v34, v23, v19, s[6:7]
	s_nop 1
	v_mov_b32_dpp v35, v34 quad_perm:[1,0,3,2] row_mask:0xf bank_mask:0xf bound_ctrl:1
	v_cndmask_b32_e64 v34, v23, v35, s[4:5]
	v_cndmask_b32_e64 v35, v35, v19, s[4:5]
	v_cvt_pk_bf16_f32 v34, v34, v35
	v_add_co_u32_e32 v36, vcc, 0x1000, v32
	s_nop 1
	v_addc_co_u32_e32 v37, vcc, 0, v33, vcc
	global_store_dword v[36:37], v34, off offset:2112
	v_cndmask_b32_e64 v34, v15, v11, s[6:7]
	s_nop 1
	v_mov_b32_dpp v35, v34 quad_perm:[1,0,3,2] row_mask:0xf bank_mask:0xf bound_ctrl:1
	v_cndmask_b32_e64 v34, v15, v35, s[4:5]
	v_cndmask_b32_e64 v35, v35, v11, s[4:5]
	v_cvt_pk_bf16_f32 v34, v34, v35
	v_add_co_u32_e32 v36, vcc, 0x1000, v32
	s_nop 1
	v_addc_co_u32_e32 v37, vcc, 0, v33, vcc
	global_store_dword v[36:37], v34, off offset:2176
	v_cndmask_b32_e64 v34, v7, v3, s[6:7]
	s_nop 1
	v_mov_b32_dpp v35, v34 quad_perm:[1,0,3,2] row_mask:0xf bank_mask:0xf bound_ctrl:1
	v_cndmask_b32_e64 v34, v7, v35, s[4:5]
	v_cndmask_b32_e64 v35, v35, v3, s[4:5]
	v_cvt_pk_bf16_f32 v34, v34, v35
	v_add_co_u32_e32 v32, vcc, 0x1000, v32
	s_mov_b64 s[18:19], 0
	s_nop 0
	v_addc_co_u32_e32 v33, vcc, 0, v33, vcc
	global_store_dword v[32:33], v34, off offset:2240

; DEVFI int opaque_tid(const int wv) { return (wv << 6) | lane_opaque(); }
; #define SBAR() __builtin_amdgcn_sched_barrier(0)
; #define WAIT_V0() asm volatile("s_waitcnt vmcnt(0)" ::: "memory")
; #define GLDS_STAGE(buf, kt) gemm_stage(t, (buf), (kt), shm, wid, lane)
; DEVFI void gemm_stage(const TileSrc& t, const int buf, const int kt, char* shm, const int wid, const int lane) {
;   int R, C; stage_rc<G_KS>(wid * 1024 + lane * 16, R, C);
;   const int oa = R * t.lda + C, ob = R * t.ldb + C;
; #pragma unroll
;   for (int i = 0; i < G_GL; ++i) {
;     __builtin_amdgcn_global_load_lds((const unsigned*)(t.A + (i * 64 * t.lda + kt * G_BK) + oa), (unsigned*)(shm + buf * G_STAGE_B + wid * 1024 + i * 8192), 16, 0, 0);
;     __builtin_amdgcn_global_load_lds((const unsigned*)(t.B + (i * 64 * t.ldb + kt * G_BK) + ob), (unsigned*)(shm + buf * G_STAGE_B + G_TILE_B + wid * 1024 + i * 8192), 16, 0, 0); }
; template <class Epi>
; DEVFI void gemm_main(const TileSrc t, const int K, char* shm, const bool pf, const TileSrc nx, const int wv, Epi epi) {
;   const int tid = opaque_tid(wv), wid = tid >> 6, lane = tid & 63, wr = wid >> 1, wc = wid & 1, fr = lane & 15, fq = lane >> 4;
;     ...
;   f32x4 acc[4][8] = {};
;   const int nt = K / G_BK;
;   const int sw = (fr * 64 + fq * 16) ^ ((fr >> 3) << 5);
;   const char* aBase = shm + wr * 8192 + sw;
;   const char* bBase = shm + G_TILE_B + wc * 16384 + sw;
;   WAIT_V0(); __syncthreads();
;   for (int t_ = 0; t_ < nt; ++t_) { const int cur = t_ & 1;
;     if (t_ + 1 < nt) GLDS_STAGE(cur ^ 1, t_ + 1);
; #pragma unroll
;     for (int ks = 0; ks < G_KS; ++ks) {
;       bf16x8 At[4], Bf[8];
; #pragma unroll
;       for (int n = 0; n < 8; ++n) Bf[n] = *(const bf16x8*)(bBase + cur * G_STAGE_B + (n * 2048 + ks * 1024));
;       SBAR();
;       At[0] = *(const bf16x8*)(aBase + cur * G_STAGE_B + (0 * 2048 + ks * 1024)); SBAR();
.LBB0_2876:
	s_mov_b32 s17, -1
	s_ashr_i32 s19, s33, 7
	v_mbcnt_lo_u32_b32 v0, s17, 0
	v_mbcnt_hi_u32_b32 v135, s17, v0
	v_or_b32_e32 v0, s33, v135
	v_ashrrev_i32_e32 v137, 6, v0
	v_and_b32_e32 v134, 1, v137
	v_and_b32_e32 v132, 15, v135
	v_and_b32_e32 v0, 48, v135
	v_lshlrev_b32_e32 v1, 2, v135
	v_lshl_or_b32 v0, v132, 6, v0
	v_and_b32_e32 v1, 32, v1
	s_lshl_b32 s17, s19, 13
	v_lshlrev_b32_e32 v2, 14, v134
	v_bitop3_b32 v141, s17, v0, v1 bitop3:0xf6
	v_bitop3_b32 v142, v2, v0, v1 bitop3:0xf6
	v_lshlrev_b32_e32 v0, 4, v135
	v_and_b32_e32 v1, 32, v135
	v_lshrrev_b32_e32 v2, 31, v137
	v_add_u32_e32 v2, v137, v2
	v_bitop3_b32 v0, v0, v1, 48 bitop3:0x6c
	v_ashrrev_i32_e32 v138, 1, v2
	v_lshrrev_b32_e32 v139, 1, v0
	v_lshlrev_b32_e32 v0, 8, v135
	v_and_b32_e32 v140, 0x3c00, v0
	v_mul_lo_u32 v0, v138, s66
	v_or_b32_e32 v0, v139, v0
	v_lshlrev_b32_e32 v1, 5, v137
	v_add3_u32 v0, v0, v140, v1
	v_ashrrev_i32_e32 v1, 31, v0
	s_waitcnt vmcnt(0)
	v_lshlrev_b64 v[0:1], 1, v[0:1]
	v_lshl_add_u64 v[128:129], s[6:7], 0, v[0:1]
	v_lshl_add_u64 v[130:131], s[2:3], 0, v[0:1]
	v_mov_b32_e32 v0, 0
	v_mov_b32_e32 v252, 0x3a720000
	s_mov_b32 s16, 0
	v_and_b32_e32 v133, 63, v135
	v_lshlrev_b32_e32 v136, 10, v137
	s_mov_b64 s[6:7], 0
	v_mov_b32_e32 v1, v0
	v_mov_b32_e32 v2, v0
	v_mov_b32_e32 v3, v0
	v_mov_b32_e32 v4, v0
	v_mov_b32_e32 v5, v0
	v_mov_b32_e32 v6, v0
	v_mov_b32_e32 v7, v0
	v_mov_b32_e32 v8, v0
	v_mov_b32_e32 v9, v0
	v_mov_b32_e32 v10, v0
	v_mov_b32_e32 v11, v0
	v_mov_b32_e32 v12, v0
	v_mov_b32_e32 v13, v0
	v_mov_b32_e32 v14, v0
	v_mov_b32_e32 v15, v0
	v_mov_b32_e32 v16, v0
	v_mov_b32_e32 v17, v0
	v_mov_b32_e32 v18, v0
	v_mov_b32_e32 v19, v0
	v_mov_b32_e32 v20, v0
	v_mov_b32_e32 v21, v0
	v_mov_b32_e32 v22, v0
	v_mov_b32_e32 v23, v0
	v_mov_b32_e32 v24, v0
	v_mov_b32_e32 v25, v0
	v_mov_b32_e32 v26, v0
	v_mov_b32_e32 v27, v0
	v_mov_b32_e32 v28, v0
	v_mov_b32_e32 v29, v0
	v_mov_b32_e32 v30, v0
	v_mov_b32_e32 v31, v0
	v_mov_b32_e32 v32, v0
	v_mov_b32_e32 v33, v0
	v_mov_b32_e32 v34, v0
	v_mov_b32_e32 v35, v0
	v_mov_b32_e32 v36, v0
	v_mov_b32_e32 v37, v0
	v_mov_b32_e32 v38, v0
	v_mov_b32_e32 v39, v0
	v_mov_b32_e32 v40, v0
	v_mov_b32_e32 v41, v0
	v_mov_b32_e32 v42, v0
	v_mov_b32_e32 v43, v0
	v_mov_b32_e32 v44, v0
	v_mov_b32_e32 v45, v0
	v_mov_b32_e32 v46, v0
	v_mov_b32_e32 v47, v0
	v_mov_b32_e32 v48, v0
	v_mov_b32_e32 v49, v0
	v_mov_b32_e32 v50, v0
	v_mov_b32_e32 v51, v0
	v_mov_b32_e32 v52, v0
	v_mov_b32_e32 v53, v0
	v_mov_b32_e32 v54, v0
	v_mov_b32_e32 v55, v0
	v_mov_b32_e32 v56, v0
	v_mov_b32_e32 v57, v0
	v_mov_b32_e32 v58, v0
	v_mov_b32_e32 v59, v0
	v_mov_b32_e32 v60, v0
	v_mov_b32_e32 v61, v0
	v_mov_b32_e32 v62, v0
	v_mov_b32_e32 v63, v0
	v_mov_b32_e32 v64, v0
	v_mov_b32_e32 v65, v0
	v_mov_b32_e32 v66, v0
	v_mov_b32_e32 v67, v0
	v_mov_b32_e32 v68, v0
	v_mov_b32_e32 v69, v0
	v_mov_b32_e32 v70, v0
	v_mov_b32_e32 v71, v0
	v_mov_b32_e32 v72, v0
	v_mov_b32_e32 v73, v0
	v_mov_b32_e32 v74, v0
	v_mov_b32_e32 v75, v0
	v_mov_b32_e32 v76, v0
	v_mov_b32_e32 v77, v0
	v_mov_b32_e32 v78, v0
	v_mov_b32_e32 v79, v0
	v_mov_b32_e32 v80, v0
	v_mov_b32_e32 v81, v0
	v_mov_b32_e32 v82, v0
	v_mov_b32_e32 v83, v0
	v_mov_b32_e32 v84, v0
	v_mov_b32_e32 v85, v0
	v_mov_b32_e32 v86, v0
	v_mov_b32_e32 v87, v0
	v_mov_b32_e32 v88, v0
	v_mov_b32_e32 v89, v0
	v_mov_b32_e32 v90, v0
	v_mov_b32_e32 v91, v0
	v_mov_b32_e32 v92, v0
	v_mov_b32_e32 v93, v0
	v_mov_b32_e32 v94, v0
	v_mov_b32_e32 v95, v0
	v_mov_b32_e32 v96, v0
	v_mov_b32_e32 v97, v0
	v_mov_b32_e32 v98, v0
	v_mov_b32_e32 v99, v0
	v_mov_b32_e32 v100, v0
	v_mov_b32_e32 v101, v0
	v_mov_b32_e32 v102, v0
	v_mov_b32_e32 v103, v0
	v_mov_b32_e32 v104, v0
	v_mov_b32_e32 v105, v0
	v_mov_b32_e32 v106, v0
	v_mov_b32_e32 v107, v0
	v_mov_b32_e32 v108, v0
	v_mov_b32_e32 v109, v0
	v_mov_b32_e32 v110, v0
	v_mov_b32_e32 v111, v0
	v_mov_b32_e32 v112, v0
	v_mov_b32_e32 v113, v0
	v_mov_b32_e32 v114, v0
	v_mov_b32_e32 v115, v0
	v_mov_b32_e32 v116, v0
	v_mov_b32_e32 v117, v0
	v_mov_b32_e32 v118, v0
	v_mov_b32_e32 v119, v0
	v_mov_b32_e32 v120, v0
	v_mov_b32_e32 v121, v0
	v_mov_b32_e32 v122, v0
	v_mov_b32_e32 v123, v0
	v_mov_b32_e32 v124, v0
	v_mov_b32_e32 v125, v0
	v_mov_b32_e32 v126, v0
	v_mov_b32_e32 v127, v0
	s_waitcnt lgkmcnt(0)
	s_lshr_b32 s2, s33, 6
	s_lshr_b32 s3, s2, 1
	s_sub_u32 s3, s2, s3
	s_mov_b32 s6, 0x20000
	s_lshr_b32 s7, s6, 2
	s_mul_i32 s3, s3, s7
	s_and_b32 s7, s2, 1
	s_lshl_b32 s7, s7, 6
	s_sub_u32 s3, s3, s7
	s_add_u32 s3, s3, 0x80
	s_lshl_b32 s16, s6, 1
	s_lshl_b32 s2, s2, 11
	s_mov_b32 vcc_hi, 0
	s_mov_b32 vcc_lo, s3
	v_lshl_add_u64 v[130:131], v[130:131], 0, vcc
	v_lshl_add_u64 v[128:129], v[128:129], 0, vcc
	s_mov_b32 vcc_lo, s16
	v_lshl_add_u64 v[214:215], v[130:131], 0, vcc
	v_lshl_add_u64 v[228:229], v[128:129], 0, vcc
	v_add_u32_e32 v143, 0x10000, v141
	v_add_u32_e32 v176, 0x10000, v142
	s_nop 0
	v_readfirstlane_b32 s6, v130
	v_readfirstlane_b32 s7, v131
	v_readfirstlane_b32 vcc_lo, v128
	v_readfirstlane_b32 vcc_hi, v129
	s_nop 1
	v_subrev_u32_e32 v130, s6, v130
	v_subrev_u32_e32 v128, vcc_lo, v128
	v_add_u32_e32 v214, s16, v130
	v_add_u32_e32 v228, s16, v128
	s_nop 4
	s_add_u32 m0, s2, 0x10000
	s_nop 0
	global_load_lds_dwordx4 v130, s[6:7]
	s_add_u32 m0, s2, 0x14000
	s_nop 0
	global_load_lds_dwordx4 v214, s[6:7]
	s_add_u32 s6, s6, 64
	s_addc_u32 s7, s7, 0
	s_add_u32 m0, s2, 0x18000
	s_nop 0
	global_load_lds_dwordx4 v128, vcc
	s_add_u32 m0, s2, 0x1c000
	s_nop 0
	global_load_lds_dwordx4 v228, vcc
	s_add_u32 vcc_lo, vcc_lo, 64
	s_addc_u32 vcc_hi, vcc_hi, 0
	s_add_u32 m0, s2, 0x10400
	s_nop 0
	global_load_lds_dwordx4 v130, s[6:7]
	s_add_u32 m0, s2, 0x14400
	s_nop 0
	global_load_lds_dwordx4 v214, s[6:7]
	s_add_u32 s6, s6, 64
	s_addc_u32 s7, s7, 0
	s_add_u32 m0, s2, 0x18400
	s_nop 0
	global_load_lds_dwordx4 v128, vcc
	s_add_u32 m0, s2, 0x1c400
	s_nop 0
	global_load_lds_dwordx4 v228, vcc
	s_add_u32 vcc_lo, vcc_lo, 64
	s_addc_u32 vcc_hi, vcc_hi, 0
	s_waitcnt vmcnt(8)
	s_barrier
	ds_read_b128 v[144:147], v141
	ds_read_b128 v[148:151], v141 offset:2048
	ds_read_b128 v[152:155], v141 offset:4096
	ds_read_b128 v[156:159], v141 offset:6144
	ds_read_b128 v[178:181], v142 offset:32768
	ds_read_b128 v[184:187], v142 offset:34816
	ds_read_b128 v[188:191], v142 offset:36864
	ds_read_b128 v[192:195], v142 offset:38912
	ds_read_b128 v[196:199], v142 offset:40960
	ds_read_b128 v[200:203], v142 offset:43008
	ds_read_b128 v[204:207], v142 offset:45056
	ds_read_b128 v[218:221], v142 offset:47104
	s_mov_b32 s3, 7
; #define SBAR() __builtin_amdgcn_sched_barrier(0)
; #define WAIT_V0() asm volatile("s_waitcnt vmcnt(0)" ::: "memory")
; #define GLDS_STAGE(buf, kt) gemm_stage(t, (buf), (kt), shm, wid, lane)
; template <class Epi>
; DEVFI void gemm_main(const TileSrc t, const int K, char* shm, const bool pf, const TileSrc nx, const int wv, Epi epi) {
;     ...
;   for (int t_ = 0; t_ < nt; ++t_) { const int cur = t_ & 1;
;     if (t_ + 1 < nt) GLDS_STAGE(cur ^ 1, t_ + 1);
; #pragma unroll
;     for (int ks = 0; ks < G_KS; ++ks) {
;       bf16x8 At[4], Bf[8];
; #pragma unroll
;       for (int n = 0; n < 8; ++n) Bf[n] = *(const bf16x8*)(bBase + cur * G_STAGE_B + (n * 2048 + ks * 1024));
;       SBAR();
;       At[0] = *(const bf16x8*)(aBase + cur * G_STAGE_B + (0 * 2048 + ks * 1024)); SBAR();
;       At[1] = *(const bf16x8*)(aBase + cur * G_STAGE_B + (1 * 2048 + ks * 1024)); SBAR();
;       At[2] = *(const bf16x8*)(aBase + cur * G_STAGE_B + (2 * 2048 + ks * 1024)); SBAR();
;       At[3] = *(const bf16x8*)(aBase + cur * G_STAGE_B + (3 * 2048 + ks * 1024));
;       SBAR();
;       __builtin_amdgcn_s_setprio(1);
; #pragma unroll
;       for (int m = 0; m < 4; ++m)
; #pragma unroll
;         for (int n = 0; n < 8; ++n) acc[m][n] = __builtin_amdgcn_mfma_f32_16x16x32_bf16(At[m], Bf[n], acc[m][n], 0, 0, 0);
;       __builtin_amdgcn_s_setprio(0);
;       SBAR();
;     }
;     WAIT_V0(); __syncthreads();
.LgkF_loop:
	s_waitcnt lgkmcnt(0)
	s_waitcnt vmcnt(8)
	s_barrier
	v_mfma_f32_16x16x32_bf16 v[120:123], v[144:147], v[178:181], v[120:123]
	ds_read_b128 v[160:163], v141 offset:1024
	s_add_u32 m0, s2, 0x0
	v_mfma_f32_16x16x32_bf16 v[88:91], v[148:151], v[178:181], v[88:91]
	ds_read_b128 v[164:167], v141 offset:3072
	v_mfma_f32_16x16x32_bf16 v[56:59], v[152:155], v[178:181], v[56:59]
	ds_read_b128 v[168:171], v141 offset:5120
	global_load_lds_dwordx4 v130, s[6:7]
	v_mfma_f32_16x16x32_bf16 v[24:27], v[156:159], v[178:181], v[24:27]
	ds_read_b128 v[172:175], v141 offset:7168
	v_mfma_f32_16x16x32_bf16 v[124:127], v[144:147], v[184:187], v[124:127]
	ds_read_b128 v[208:211], v142 offset:46080
	v_mfma_f32_16x16x32_bf16 v[92:95], v[148:151], v[184:187], v[92:95]
	ds_read_b128 v[224:227], v142 offset:48128
	v_mfma_f32_16x16x32_bf16 v[60:63], v[152:155], v[184:187], v[60:63]
	ds_read_b128 v[178:181], v142 offset:33792
	v_mfma_f32_16x16x32_bf16 v[28:31], v[156:159], v[184:187], v[28:31]
	ds_read_b128 v[184:187], v142 offset:35840
	v_mfma_f32_16x16x32_bf16 v[112:115], v[144:147], v[188:191], v[112:115]
	s_add_u32 m0, s2, 0x4000
	v_mfma_f32_16x16x32_bf16 v[80:83], v[148:151], v[188:191], v[80:83]
	v_mfma_f32_16x16x32_bf16 v[48:51], v[152:155], v[188:191], v[48:51]
	global_load_lds_dwordx4 v214, s[6:7]
	v_mfma_f32_16x16x32_bf16 v[16:19], v[156:159], v[188:191], v[16:19]
	ds_read_b128 v[188:191], v142 offset:37888
	s_add_u32 s6, s6, 64
	s_addc_u32 s7, s7, 0
	v_mfma_f32_16x16x32_bf16 v[116:119], v[144:147], v[192:195], v[116:119]
	v_mfma_f32_16x16x32_bf16 v[84:87], v[148:151], v[192:195], v[84:87]
	v_mfma_f32_16x16x32_bf16 v[52:55], v[152:155], v[192:195], v[52:55]
	v_mfma_f32_16x16x32_bf16 v[20:23], v[156:159], v[192:195], v[20:23]
	ds_read_b128 v[192:195], v142 offset:39936
	v_mfma_f32_16x16x32_bf16 v[104:107], v[144:147], v[196:199], v[104:107]
	s_add_u32 m0, s2, 0x8000
	v_mfma_f32_16x16x32_bf16 v[72:75], v[148:151], v[196:199], v[72:75]
	v_mfma_f32_16x16x32_bf16 v[40:43], v[152:155], v[196:199], v[40:43]
	global_load_lds_dwordx4 v128, vcc
	v_mfma_f32_16x16x32_bf16 v[8:11], v[156:159], v[196:199], v[8:11]
	ds_read_b128 v[196:199], v142 offset:41984
	v_mfma_f32_16x16x32_bf16 v[108:111], v[144:147], v[200:203], v[108:111]
	v_mfma_f32_16x16x32_bf16 v[76:79], v[148:151], v[200:203], v[76:79]
	v_mfma_f32_16x16x32_bf16 v[44:47], v[152:155], v[200:203], v[44:47]
	v_mfma_f32_16x16x32_bf16 v[12:15], v[156:159], v[200:203], v[12:15]
	ds_read_b128 v[200:203], v142 offset:44032
	v_mfma_f32_16x16x32_bf16 v[96:99], v[144:147], v[204:207], v[96:99]
	s_add_u32 m0, s2, 0xc000
	v_mfma_f32_16x16x32_bf16 v[64:67], v[148:151], v[204:207], v[64:67]
	v_mfma_f32_16x16x32_bf16 v[32:35], v[152:155], v[204:207], v[32:35]
	global_load_lds_dwordx4 v228, vcc
	v_mfma_f32_16x16x32_bf16 v[0:3], v[156:159], v[204:207], v[0:3]
	s_add_u32 vcc_lo, vcc_lo, 64
	s_addc_u32 vcc_hi, vcc_hi, 0
	v_mfma_f32_16x16x32_bf16 v[100:103], v[144:147], v[218:221], v[100:103]
	v_mfma_f32_16x16x32_bf16 v[68:71], v[148:151], v[218:221], v[68:71]
	v_mfma_f32_16x16x32_bf16 v[36:39], v[152:155], v[218:221], v[36:39]
	v_mfma_f32_16x16x32_bf16 v[4:7], v[156:159], v[218:221], v[4:7]
	s_waitcnt lgkmcnt(0)
	s_waitcnt vmcnt(8)
	s_barrier
	v_mfma_f32_16x16x32_bf16 v[120:123], v[160:163], v[178:181], v[120:123]
	ds_read_b128 v[144:147], v143
	s_add_u32 m0, s2, 0x400
	v_mfma_f32_16x16x32_bf16 v[88:91], v[164:167], v[178:181], v[88:91]
	ds_read_b128 v[148:151], v143 offset:2048
	v_mfma_f32_16x16x32_bf16 v[56:59], v[168:171], v[178:181], v[56:59]
	ds_read_b128 v[152:155], v143 offset:4096
	global_load_lds_dwordx4 v130, s[6:7]
	v_mfma_f32_16x16x32_bf16 v[24:27], v[172:175], v[178:181], v[24:27]
	ds_read_b128 v[156:159], v143 offset:6144
	v_mfma_f32_16x16x32_bf16 v[124:127], v[160:163], v[184:187], v[124:127]
	ds_read_b128 v[204:207], v176 offset:45056
	v_mfma_f32_16x16x32_bf16 v[92:95], v[164:167], v[184:187], v[92:95]
	ds_read_b128 v[218:221], v176 offset:47104
	v_mfma_f32_16x16x32_bf16 v[60:63], v[168:171], v[184:187], v[60:63]
	ds_read_b128 v[178:181], v176 offset:32768
	v_mfma_f32_16x16x32_bf16 v[28:31], v[172:175], v[184:187], v[28:31]
	ds_read_b128 v[184:187], v176 offset:34816
	v_mfma_f32_16x16x32_bf16 v[112:115], v[160:163], v[188:191], v[112:115]
	s_add_u32 m0, s2, 0x4400
	v_mfma_f32_16x16x32_bf16 v[80:83], v[164:167], v[188:191], v[80:83]
	v_mfma_f32_16x16x32_bf16 v[48:51], v[168:171], v[188:191], v[48:51]
	global_load_lds_dwordx4 v214, s[6:7]
	v_mfma_f32_16x16x32_bf16 v[16:19], v[172:175], v[188:191], v[16:19]
	ds_read_b128 v[188:191], v176 offset:36864
	s_add_u32 s6, s6, 64
	s_addc_u32 s7, s7, 0
	v_mfma_f32_16x16x32_bf16 v[116:119], v[160:163], v[192:195], v[116:119]
	v_mfma_f32_16x16x32_bf16 v[84:87], v[164:167], v[192:195], v[84:87]
	v_mfma_f32_16x16x32_bf16 v[52:55], v[168:171], v[192:195], v[52:55]
	v_mfma_f32_16x16x32_bf16 v[20:23], v[172:175], v[192:195], v[20:23]
	ds_read_b128 v[192:195], v176 offset:38912
	v_mfma_f32_16x16x32_bf16 v[104:107], v[160:163], v[196:199], v[104:107]
	s_add_u32 m0, s2, 0x8400
	v_mfma_f32_16x16x32_bf16 v[72:75], v[164:167], v[196:199], v[72:75]
	v_mfma_f32_16x16x32_bf16 v[40:43], v[168:171], v[196:199], v[40:43]
	global_load_lds_dwordx4 v128, vcc
	v_mfma_f32_16x16x32_bf16 v[8:11], v[172:175], v[196:199], v[8:11]
	ds_read_b128 v[196:199], v176 offset:40960
	v_mfma_f32_16x16x32_bf16 v[108:111], v[160:163], v[200:203], v[108:111]
	v_mfma_f32_16x16x32_bf16 v[76:79], v[164:167], v[200:203], v[76:79]
	v_mfma_f32_16x16x32_bf16 v[44:47], v[168:171], v[200:203], v[44:47]
	v_mfma_f32_16x16x32_bf16 v[12:15], v[172:175], v[200:203], v[12:15]
	ds_read_b128 v[200:203], v176 offset:43008
	v_mfma_f32_16x16x32_bf16 v[96:99], v[160:163], v[208:211], v[96:99]
	s_add_u32 m0, s2, 0xc400
	v_mfma_f32_16x16x32_bf16 v[64:67], v[164:167], v[208:211], v[64:67]
	v_mfma_f32_16x16x32_bf16 v[32:35], v[168:171], v[208:211], v[32:35]
	global_load_lds_dwordx4 v228, vcc
	v_mfma_f32_16x16x32_bf16 v[0:3], v[172:175], v[208:211], v[0:3]
	s_add_u32 vcc_lo, vcc_lo, 64
	s_addc_u32 vcc_hi, vcc_hi, 0
	v_mfma_f32_16x16x32_bf16 v[100:103], v[160:163], v[224:227], v[100:103]
	v_mfma_f32_16x16x32_bf16 v[68:71], v[164:167], v[224:227], v[68:71]
	v_mfma_f32_16x16x32_bf16 v[36:39], v[168:171], v[224:227], v[36:39]
	v_mfma_f32_16x16x32_bf16 v[4:7], v[172:175], v[224:227], v[4:7]
	s_waitcnt lgkmcnt(0)
	s_waitcnt vmcnt(8)
	s_barrier
; #define SBAR() __builtin_amdgcn_sched_barrier(0)
; #define WAIT_V0() asm volatile("s_waitcnt vmcnt(0)" ::: "memory")
; #define GLDS_STAGE(buf, kt) gemm_stage(t, (buf), (kt), shm, wid, lane)
; template <class Epi>
; DEVFI void gemm_main(const TileSrc t, const int K, char* shm, const bool pf, const TileSrc nx, const int wv, Epi epi) {
;     ...
;   for (int t_ = 0; t_ < nt; ++t_) { const int cur = t_ & 1;
;     if (t_ + 1 < nt) GLDS_STAGE(cur ^ 1, t_ + 1);
; #pragma unroll
;     for (int ks = 0; ks < G_KS; ++ks) {
;       bf16x8 At[4], Bf[8];
; #pragma unroll
;       for (int n = 0; n < 8; ++n) Bf[n] = *(const bf16x8*)(bBase + cur * G_STAGE_B + (n * 2048 + ks * 1024));
;       SBAR();
;       At[0] = *(const bf16x8*)(aBase + cur * G_STAGE_B + (0 * 2048 + ks * 1024)); SBAR();
;       At[1] = *(const bf16x8*)(aBase + cur * G_STAGE_B + (1 * 2048 + ks * 1024)); SBAR();
;       At[2] = *(const bf16x8*)(aBase + cur * G_STAGE_B + (2 * 2048 + ks * 1024)); SBAR();
;       At[3] = *(const bf16x8*)(aBase + cur * G_STAGE_B + (3 * 2048 + ks * 1024));
;       SBAR();
;       __builtin_amdgcn_s_setprio(1);
; #pragma unroll
;       for (int m = 0; m < 4; ++m)
; #pragma unroll
;         for (int n = 0; n < 8; ++n) acc[m][n] = __builtin_amdgcn_mfma_f32_16x16x32_bf16(At[m], Bf[n], acc[m][n], 0, 0, 0);
;       __builtin_amdgcn_s_setprio(0);
;       SBAR();
;     }
;     WAIT_V0(); __syncthreads();
	v_mfma_f32_16x16x32_bf16 v[120:123], v[144:147], v[178:181], v[120:123]
	ds_read_b128 v[160:163], v143 offset:1024
	s_add_u32 m0, s2, 0x10000
	v_mfma_f32_16x16x32_bf16 v[88:91], v[148:151], v[178:181], v[88:91]
	ds_read_b128 v[164:167], v143 offset:3072
	v_mfma_f32_16x16x32_bf16 v[56:59], v[152:155], v[178:181], v[56:59]
	ds_read_b128 v[168:171], v143 offset:5120
	global_load_lds_dwordx4 v130, s[6:7]
	v_mfma_f32_16x16x32_bf16 v[24:27], v[156:159], v[178:181], v[24:27]
	ds_read_b128 v[172:175], v143 offset:7168
	v_mfma_f32_16x16x32_bf16 v[124:127], v[144:147], v[184:187], v[124:127]
	ds_read_b128 v[208:211], v176 offset:46080
	v_mfma_f32_16x16x32_bf16 v[92:95], v[148:151], v[184:187], v[92:95]
	ds_read_b128 v[224:227], v176 offset:48128
	v_mfma_f32_16x16x32_bf16 v[60:63], v[152:155], v[184:187], v[60:63]
	ds_read_b128 v[178:181], v176 offset:33792
	v_mfma_f32_16x16x32_bf16 v[28:31], v[156:159], v[184:187], v[28:31]
	ds_read_b128 v[184:187], v176 offset:35840
	v_mfma_f32_16x16x32_bf16 v[112:115], v[144:147], v[188:191], v[112:115]
	s_add_u32 m0, s2, 0x14000
	v_mfma_f32_16x16x32_bf16 v[80:83], v[148:151], v[188:191], v[80:83]
	v_mfma_f32_16x16x32_bf16 v[48:51], v[152:155], v[188:191], v[48:51]
	global_load_lds_dwordx4 v214, s[6:7]
	v_mfma_f32_16x16x32_bf16 v[16:19], v[156:159], v[188:191], v[16:19]
	ds_read_b128 v[188:191], v176 offset:37888
	s_add_u32 s6, s6, 64
	s_addc_u32 s7, s7, 0
	v_mfma_f32_16x16x32_bf16 v[116:119], v[144:147], v[192:195], v[116:119]
	v_mfma_f32_16x16x32_bf16 v[84:87], v[148:151], v[192:195], v[84:87]
	v_mfma_f32_16x16x32_bf16 v[52:55], v[152:155], v[192:195], v[52:55]
	v_mfma_f32_16x16x32_bf16 v[20:23], v[156:159], v[192:195], v[20:23]
	ds_read_b128 v[192:195], v176 offset:39936
	v_mfma_f32_16x16x32_bf16 v[104:107], v[144:147], v[196:199], v[104:107]
	s_add_u32 m0, s2, 0x18000
	v_mfma_f32_16x16x32_bf16 v[72:75], v[148:151], v[196:199], v[72:75]
	v_mfma_f32_16x16x32_bf16 v[40:43], v[152:155], v[196:199], v[40:43]
	global_load_lds_dwordx4 v128, vcc
	v_mfma_f32_16x16x32_bf16 v[8:11], v[156:159], v[196:199], v[8:11]
	ds_read_b128 v[196:199], v176 offset:41984
	v_mfma_f32_16x16x32_bf16 v[108:111], v[144:147], v[200:203], v[108:111]
	v_mfma_f32_16x16x32_bf16 v[76:79], v[148:151], v[200:203], v[76:79]
	v_mfma_f32_16x16x32_bf16 v[44:47], v[152:155], v[200:203], v[44:47]
	v_mfma_f32_16x16x32_bf16 v[12:15], v[156:159], v[200:203], v[12:15]
	ds_read_b128 v[200:203], v176 offset:44032
	v_mfma_f32_16x16x32_bf16 v[96:99], v[144:147], v[204:207], v[96:99]
	s_add_u32 m0, s2, 0x1c000
	v_mfma_f32_16x16x32_bf16 v[64:67], v[148:151], v[204:207], v[64:67]
	v_mfma_f32_16x16x32_bf16 v[32:35], v[152:155], v[204:207], v[32:35]
	global_load_lds_dwordx4 v228, vcc
	v_mfma_f32_16x16x32_bf16 v[0:3], v[156:159], v[204:207], v[0:3]
	s_add_u32 vcc_lo, vcc_lo, 64
	s_addc_u32 vcc_hi, vcc_hi, 0
	v_mfma_f32_16x16x32_bf16 v[100:103], v[144:147], v[218:221], v[100:103]
	v_mfma_f32_16x16x32_bf16 v[68:71], v[148:151], v[218:221], v[68:71]
	v_mfma_f32_16x16x32_bf16 v[36:39], v[152:155], v[218:221], v[36:39]
	v_mfma_f32_16x16x32_bf16 v[4:7], v[156:159], v[218:221], v[4:7]
	s_waitcnt lgkmcnt(0)
	s_waitcnt vmcnt(8)
	s_barrier
	v_mfma_f32_16x16x32_bf16 v[120:123], v[160:163], v[178:181], v[120:123]
	ds_read_b128 v[144:147], v141
	s_add_u32 m0, s2, 0x10400
	v_mfma_f32_16x16x32_bf16 v[88:91], v[164:167], v[178:181], v[88:91]
	ds_read_b128 v[148:151], v141 offset:2048
	v_mfma_f32_16x16x32_bf16 v[56:59], v[168:171], v[178:181], v[56:59]
	ds_read_b128 v[152:155], v141 offset:4096
	global_load_lds_dwordx4 v130, s[6:7]
	v_mfma_f32_16x16x32_bf16 v[24:27], v[172:175], v[178:181], v[24:27]
	ds_read_b128 v[156:159], v141 offset:6144
	v_mfma_f32_16x16x32_bf16 v[124:127], v[160:163], v[184:187], v[124:127]
	ds_read_b128 v[204:207], v142 offset:45056
	v_mfma_f32_16x16x32_bf16 v[92:95], v[164:167], v[184:187], v[92:95]
	ds_read_b128 v[218:221], v142 offset:47104
	v_mfma_f32_16x16x32_bf16 v[60:63], v[168:171], v[184:187], v[60:63]
	ds_read_b128 v[178:181], v142 offset:32768
	v_mfma_f32_16x16x32_bf16 v[28:31], v[172:175], v[184:187], v[28:31]
	ds_read_b128 v[184:187], v142 offset:34816
	v_mfma_f32_16x16x32_bf16 v[112:115], v[160:163], v[188:191], v[112:115]
	s_add_u32 m0, s2, 0x14400
	v_mfma_f32_16x16x32_bf16 v[80:83], v[164:167], v[188:191], v[80:83]
	v_mfma_f32_16x16x32_bf16 v[48:51], v[168:171], v[188:191], v[48:51]
	global_load_lds_dwordx4 v214, s[6:7]
	v_mfma_f32_16x16x32_bf16 v[16:19], v[172:175], v[188:191], v[16:19]
	ds_read_b128 v[188:191], v142 offset:36864
	s_add_u32 s6, s6, 64
	s_addc_u32 s7, s7, 0
	v_mfma_f32_16x16x32_bf16 v[116:119], v[160:163], v[192:195], v[116:119]
	v_mfma_f32_16x16x32_bf16 v[84:87], v[164:167], v[192:195], v[84:87]
	v_mfma_f32_16x16x32_bf16 v[52:55], v[168:171], v[192:195], v[52:55]
	v_mfma_f32_16x16x32_bf16 v[20:23], v[172:175], v[192:195], v[20:23]
	ds_read_b128 v[192:195], v142 offset:38912
	v_mfma_f32_16x16x32_bf16 v[104:107], v[160:163], v[196:199], v[104:107]
	s_add_u32 m0, s2, 0x18400
	v_mfma_f32_16x16x32_bf16 v[72:75], v[164:167], v[196:199], v[72:75]
	v_mfma_f32_16x16x32_bf16 v[40:43], v[168:171], v[196:199], v[40:43]
	global_load_lds_dwordx4 v128, vcc
	v_mfma_f32_16x16x32_bf16 v[8:11], v[172:175], v[196:199], v[8:11]
	ds_read_b128 v[196:199], v142 offset:40960
	v_mfma_f32_16x16x32_bf16 v[108:111], v[160:163], v[200:203], v[108:111]
	v_mfma_f32_16x16x32_bf16 v[76:79], v[164:167], v[200:203], v[76:79]
	v_mfma_f32_16x16x32_bf16 v[44:47], v[168:171], v[200:203], v[44:47]
	v_mfma_f32_16x16x32_bf16 v[12:15], v[172:175], v[200:203], v[12:15]
	ds_read_b128 v[200:203], v142 offset:43008
	v_mfma_f32_16x16x32_bf16 v[96:99], v[160:163], v[208:211], v[96:99]
	s_add_u32 m0, s2, 0x1c400
	v_mfma_f32_16x16x32_bf16 v[64:67], v[164:167], v[208:211], v[64:67]
	v_mfma_f32_16x16x32_bf16 v[32:35], v[168:171], v[208:211], v[32:35]
	global_load_lds_dwordx4 v228, vcc
	v_mfma_f32_16x16x32_bf16 v[0:3], v[172:175], v[208:211], v[0:3]
	s_add_u32 vcc_lo, vcc_lo, 64
	s_addc_u32 vcc_hi, vcc_hi, 0
	v_mfma_f32_16x16x32_bf16 v[100:103], v[160:163], v[224:227], v[100:103]
	v_mfma_f32_16x16x32_bf16 v[68:71], v[164:167], v[224:227], v[68:71]
	v_mfma_f32_16x16x32_bf16 v[36:39], v[168:171], v[224:227], v[36:39]
	v_mfma_f32_16x16x32_bf16 v[4:7], v[172:175], v[224:227], v[4:7]
	s_sub_u32 s3, s3, 1
	s_cmp_lg_u32 s3, 0
	s_cbranch_scc1 .LgkF_loop
; #define SBAR() __builtin_amdgcn_sched_barrier(0)
; #define WAIT_V0() asm volatile("s_waitcnt vmcnt(0)" ::: "memory")
; #define GLDS_STAGE(buf, kt) gemm_stage(t, (buf), (kt), shm, wid, lane)
; template <class Epi>
; DEVFI void gemm_main(const TileSrc t, const int K, char* shm, const bool pf, const TileSrc nx, const int wv, Epi epi) {
;     ...
;   for (int t_ = 0; t_ < nt; ++t_) { const int cur = t_ & 1;
;     if (t_ + 1 < nt) GLDS_STAGE(cur ^ 1, t_ + 1);
; #pragma unroll
;     for (int ks = 0; ks < G_KS; ++ks) {
;       bf16x8 At[4], Bf[8];
; #pragma unroll
;       for (int n = 0; n < 8; ++n) Bf[n] = *(const bf16x8*)(bBase + cur * G_STAGE_B + (n * 2048 + ks * 1024));
;       SBAR();
;       At[0] = *(const bf16x8*)(aBase + cur * G_STAGE_B + (0 * 2048 + ks * 1024)); SBAR();
;       At[1] = *(const bf16x8*)(aBase + cur * G_STAGE_B + (1 * 2048 + ks * 1024)); SBAR();
;       At[2] = *(const bf16x8*)(aBase + cur * G_STAGE_B + (2 * 2048 + ks * 1024)); SBAR();
;       At[3] = *(const bf16x8*)(aBase + cur * G_STAGE_B + (3 * 2048 + ks * 1024));
;       SBAR();
;       __builtin_amdgcn_s_setprio(1);
; #pragma unroll
;       for (int m = 0; m < 4; ++m)
; #pragma unroll
;         for (int n = 0; n < 8; ++n) acc[m][n] = __builtin_amdgcn_mfma_f32_16x16x32_bf16(At[m], Bf[n], acc[m][n], 0, 0, 0);
;       __builtin_amdgcn_s_setprio(0);
;       SBAR();
;     }
;     WAIT_V0(); __syncthreads();
	s_waitcnt lgkmcnt(0)
	s_waitcnt vmcnt(8)
	s_barrier
	v_mfma_f32_16x16x32_bf16 v[120:123], v[144:147], v[178:181], v[120:123]
	ds_read_b128 v[160:163], v141 offset:1024
	v_mfma_f32_16x16x32_bf16 v[88:91], v[148:151], v[178:181], v[88:91]
	ds_read_b128 v[164:167], v141 offset:3072
	v_mfma_f32_16x16x32_bf16 v[56:59], v[152:155], v[178:181], v[56:59]
	ds_read_b128 v[168:171], v141 offset:5120
	v_mfma_f32_16x16x32_bf16 v[24:27], v[156:159], v[178:181], v[24:27]
	ds_read_b128 v[172:175], v141 offset:7168
	v_mfma_f32_16x16x32_bf16 v[124:127], v[144:147], v[184:187], v[124:127]
	ds_read_b128 v[208:211], v142 offset:46080
	v_mfma_f32_16x16x32_bf16 v[92:95], v[148:151], v[184:187], v[92:95]
	ds_read_b128 v[224:227], v142 offset:48128
	v_mfma_f32_16x16x32_bf16 v[60:63], v[152:155], v[184:187], v[60:63]
	ds_read_b128 v[178:181], v142 offset:33792
	v_mfma_f32_16x16x32_bf16 v[28:31], v[156:159], v[184:187], v[28:31]
	ds_read_b128 v[184:187], v142 offset:35840
	v_mfma_f32_16x16x32_bf16 v[112:115], v[144:147], v[188:191], v[112:115]
	v_mfma_f32_16x16x32_bf16 v[80:83], v[148:151], v[188:191], v[80:83]
	v_mfma_f32_16x16x32_bf16 v[48:51], v[152:155], v[188:191], v[48:51]
	v_mfma_f32_16x16x32_bf16 v[16:19], v[156:159], v[188:191], v[16:19]
	ds_read_b128 v[188:191], v142 offset:37888
	v_mfma_f32_16x16x32_bf16 v[116:119], v[144:147], v[192:195], v[116:119]
	v_mfma_f32_16x16x32_bf16 v[84:87], v[148:151], v[192:195], v[84:87]
	v_mfma_f32_16x16x32_bf16 v[52:55], v[152:155], v[192:195], v[52:55]
	v_mfma_f32_16x16x32_bf16 v[20:23], v[156:159], v[192:195], v[20:23]
	ds_read_b128 v[192:195], v142 offset:39936
	v_mfma_f32_16x16x32_bf16 v[104:107], v[144:147], v[196:199], v[104:107]
	v_mfma_f32_16x16x32_bf16 v[72:75], v[148:151], v[196:199], v[72:75]
	v_mfma_f32_16x16x32_bf16 v[40:43], v[152:155], v[196:199], v[40:43]
	v_mfma_f32_16x16x32_bf16 v[8:11], v[156:159], v[196:199], v[8:11]
	ds_read_b128 v[196:199], v142 offset:41984
	v_mfma_f32_16x16x32_bf16 v[108:111], v[144:147], v[200:203], v[108:111]
	v_mfma_f32_16x16x32_bf16 v[76:79], v[148:151], v[200:203], v[76:79]
	v_mfma_f32_16x16x32_bf16 v[44:47], v[152:155], v[200:203], v[44:47]
	v_mfma_f32_16x16x32_bf16 v[12:15], v[156:159], v[200:203], v[12:15]
	ds_read_b128 v[200:203], v142 offset:44032
	v_mfma_f32_16x16x32_bf16 v[96:99], v[144:147], v[204:207], v[96:99]
	v_mfma_f32_16x16x32_bf16 v[64:67], v[148:151], v[204:207], v[64:67]
	v_mfma_f32_16x16x32_bf16 v[32:35], v[152:155], v[204:207], v[32:35]
	v_mfma_f32_16x16x32_bf16 v[0:3], v[156:159], v[204:207], v[0:3]
	v_mfma_f32_16x16x32_bf16 v[100:103], v[144:147], v[218:221], v[100:103]
	v_mfma_f32_16x16x32_bf16 v[68:71], v[148:151], v[218:221], v[68:71]
	v_mfma_f32_16x16x32_bf16 v[36:39], v[152:155], v[218:221], v[36:39]
	v_mfma_f32_16x16x32_bf16 v[4:7], v[156:159], v[218:221], v[4:7]
	s_waitcnt lgkmcnt(0)
	s_waitcnt vmcnt(4)
	s_barrier
	v_mfma_f32_16x16x32_bf16 v[120:123], v[160:163], v[178:181], v[120:123]
	ds_read_b128 v[144:147], v143
	v_mfma_f32_16x16x32_bf16 v[88:91], v[164:167], v[178:181], v[88:91]
	ds_read_b128 v[148:151], v143 offset:2048
	v_mfma_f32_16x16x32_bf16 v[56:59], v[168:171], v[178:181], v[56:59]
	ds_read_b128 v[152:155], v143 offset:4096
	v_mfma_f32_16x16x32_bf16 v[24:27], v[172:175], v[178:181], v[24:27]
	ds_read_b128 v[156:159], v143 offset:6144
	v_mfma_f32_16x16x32_bf16 v[124:127], v[160:163], v[184:187], v[124:127]
	ds_read_b128 v[204:207], v176 offset:45056
	v_mfma_f32_16x16x32_bf16 v[92:95], v[164:167], v[184:187], v[92:95]
	ds_read_b128 v[218:221], v176 offset:47104
	v_mfma_f32_16x16x32_bf16 v[60:63], v[168:171], v[184:187], v[60:63]
	ds_read_b128 v[178:181], v176 offset:32768
	v_mfma_f32_16x16x32_bf16 v[28:31], v[172:175], v[184:187], v[28:31]
	ds_read_b128 v[184:187], v176 offset:34816
	v_mfma_f32_16x16x32_bf16 v[112:115], v[160:163], v[188:191], v[112:115]
	v_mfma_f32_16x16x32_bf16 v[80:83], v[164:167], v[188:191], v[80:83]
	v_mfma_f32_16x16x32_bf16 v[48:51], v[168:171], v[188:191], v[48:51]
	v_mfma_f32_16x16x32_bf16 v[16:19], v[172:175], v[188:191], v[16:19]
	ds_read_b128 v[188:191], v176 offset:36864
	v_mfma_f32_16x16x32_bf16 v[116:119], v[160:163], v[192:195], v[116:119]
	v_mfma_f32_16x16x32_bf16 v[84:87], v[164:167], v[192:195], v[84:87]
	v_mfma_f32_16x16x32_bf16 v[52:55], v[168:171], v[192:195], v[52:55]
	v_mfma_f32_16x16x32_bf16 v[20:23], v[172:175], v[192:195], v[20:23]
	ds_read_b128 v[192:195], v176 offset:38912
	v_mfma_f32_16x16x32_bf16 v[104:107], v[160:163], v[196:199], v[104:107]
	v_mfma_f32_16x16x32_bf16 v[72:75], v[164:167], v[196:199], v[72:75]
	v_mfma_f32_16x16x32_bf16 v[40:43], v[168:171], v[196:199], v[40:43]
	v_mfma_f32_16x16x32_bf16 v[8:11], v[172:175], v[196:199], v[8:11]
	ds_read_b128 v[196:199], v176 offset:40960
	v_mfma_f32_16x16x32_bf16 v[108:111], v[160:163], v[200:203], v[108:111]
	v_mfma_f32_16x16x32_bf16 v[76:79], v[164:167], v[200:203], v[76:79]
	v_mfma_f32_16x16x32_bf16 v[44:47], v[168:171], v[200:203], v[44:47]
	v_mfma_f32_16x16x32_bf16 v[12:15], v[172:175], v[200:203], v[12:15]
	ds_read_b128 v[200:203], v176 offset:43008
	v_mfma_f32_16x16x32_bf16 v[96:99], v[160:163], v[208:211], v[96:99]
	v_mfma_f32_16x16x32_bf16 v[64:67], v[164:167], v[208:211], v[64:67]
	v_mfma_f32_16x16x32_bf16 v[32:35], v[168:171], v[208:211], v[32:35]
	v_mfma_f32_16x16x32_bf16 v[0:3], v[172:175], v[208:211], v[0:3]
	v_mfma_f32_16x16x32_bf16 v[100:103], v[160:163], v[224:227], v[100:103]
	v_mfma_f32_16x16x32_bf16 v[68:71], v[164:167], v[224:227], v[68:71]
	v_mfma_f32_16x16x32_bf16 v[36:39], v[168:171], v[224:227], v[36:39]
	v_mfma_f32_16x16x32_bf16 v[4:7], v[172:175], v[224:227], v[4:7]
	s_waitcnt lgkmcnt(0)
	s_waitcnt vmcnt(0)
	s_barrier
; #define SBAR() __builtin_amdgcn_sched_barrier(0)
; #define WAIT_V0() asm volatile("s_waitcnt vmcnt(0)" ::: "memory")
; #define GLDS_STAGE(buf, kt) gemm_stage(t, (buf), (kt), shm, wid, lane)
; template <class Epi>
; DEVFI void gemm_main(const TileSrc t, const int K, char* shm, const bool pf, const TileSrc nx, const int wv, Epi epi) {
;     ...
;   for (int t_ = 0; t_ < nt; ++t_) { const int cur = t_ & 1;
;     if (t_ + 1 < nt) GLDS_STAGE(cur ^ 1, t_ + 1);
; #pragma unroll
;     for (int ks = 0; ks < G_KS; ++ks) {
;       bf16x8 At[4], Bf[8];
; #pragma unroll
;       for (int n = 0; n < 8; ++n) Bf[n] = *(const bf16x8*)(bBase + cur * G_STAGE_B + (n * 2048 + ks * 1024));
;       SBAR();
;       At[0] = *(const bf16x8*)(aBase + cur * G_STAGE_B + (0 * 2048 + ks * 1024)); SBAR();
;       At[1] = *(const bf16x8*)(aBase + cur * G_STAGE_B + (1 * 2048 + ks * 1024)); SBAR();
;       At[2] = *(const bf16x8*)(aBase + cur * G_STAGE_B + (2 * 2048 + ks * 1024)); SBAR();
;       At[3] = *(const bf16x8*)(aBase + cur * G_STAGE_B + (3 * 2048 + ks * 1024));
;       SBAR();
;       __builtin_amdgcn_s_setprio(1);
; #pragma unroll
;       for (int m = 0; m < 4; ++m)
; #pragma unroll
;         for (int n = 0; n < 8; ++n) acc[m][n] = __builtin_amdgcn_mfma_f32_16x16x32_bf16(At[m], Bf[n], acc[m][n], 0, 0, 0);
;       __builtin_amdgcn_s_setprio(0);
;       SBAR();
;     }
;     WAIT_V0(); __syncthreads();
;   }
;     ...
;   if (pf) gemm_stage(nx, 0, 0, shm, wid, lane);
	v_mfma_f32_16x16x32_bf16 v[120:123], v[144:147], v[178:181], v[120:123]
	ds_read_b128 v[160:163], v143 offset:1024
	v_mfma_f32_16x16x32_bf16 v[88:91], v[148:151], v[178:181], v[88:91]
	ds_read_b128 v[164:167], v143 offset:3072
	v_mfma_f32_16x16x32_bf16 v[56:59], v[152:155], v[178:181], v[56:59]
	ds_read_b128 v[168:171], v143 offset:5120
	v_mfma_f32_16x16x32_bf16 v[24:27], v[156:159], v[178:181], v[24:27]
	ds_read_b128 v[172:175], v143 offset:7168
	v_mfma_f32_16x16x32_bf16 v[124:127], v[144:147], v[184:187], v[124:127]
	ds_read_b128 v[208:211], v176 offset:46080
	v_mfma_f32_16x16x32_bf16 v[92:95], v[148:151], v[184:187], v[92:95]
	ds_read_b128 v[224:227], v176 offset:48128
	v_mfma_f32_16x16x32_bf16 v[60:63], v[152:155], v[184:187], v[60:63]
	ds_read_b128 v[178:181], v176 offset:33792
	v_mfma_f32_16x16x32_bf16 v[28:31], v[156:159], v[184:187], v[28:31]
	ds_read_b128 v[184:187], v176 offset:35840
	v_mfma_f32_16x16x32_bf16 v[112:115], v[144:147], v[188:191], v[112:115]
	v_mfma_f32_16x16x32_bf16 v[80:83], v[148:151], v[188:191], v[80:83]
	v_mfma_f32_16x16x32_bf16 v[48:51], v[152:155], v[188:191], v[48:51]
	v_mfma_f32_16x16x32_bf16 v[16:19], v[156:159], v[188:191], v[16:19]
	ds_read_b128 v[188:191], v176 offset:37888
	v_mfma_f32_16x16x32_bf16 v[116:119], v[144:147], v[192:195], v[116:119]
	v_mfma_f32_16x16x32_bf16 v[84:87], v[148:151], v[192:195], v[84:87]
	v_mfma_f32_16x16x32_bf16 v[52:55], v[152:155], v[192:195], v[52:55]
	v_mfma_f32_16x16x32_bf16 v[20:23], v[156:159], v[192:195], v[20:23]
	ds_read_b128 v[192:195], v176 offset:39936
	v_mfma_f32_16x16x32_bf16 v[104:107], v[144:147], v[196:199], v[104:107]
	v_mfma_f32_16x16x32_bf16 v[72:75], v[148:151], v[196:199], v[72:75]
	v_mfma_f32_16x16x32_bf16 v[40:43], v[152:155], v[196:199], v[40:43]
	v_mfma_f32_16x16x32_bf16 v[8:11], v[156:159], v[196:199], v[8:11]
	ds_read_b128 v[196:199], v176 offset:41984
	v_mfma_f32_16x16x32_bf16 v[108:111], v[144:147], v[200:203], v[108:111]
	v_mfma_f32_16x16x32_bf16 v[76:79], v[148:151], v[200:203], v[76:79]
	v_mfma_f32_16x16x32_bf16 v[44:47], v[152:155], v[200:203], v[44:47]
	v_mfma_f32_16x16x32_bf16 v[12:15], v[156:159], v[200:203], v[12:15]
	ds_read_b128 v[200:203], v176 offset:44032
	v_mfma_f32_16x16x32_bf16 v[96:99], v[144:147], v[204:207], v[96:99]
	v_mfma_f32_16x16x32_bf16 v[64:67], v[148:151], v[204:207], v[64:67]
	v_mfma_f32_16x16x32_bf16 v[32:35], v[152:155], v[204:207], v[32:35]
	v_mfma_f32_16x16x32_bf16 v[0:3], v[156:159], v[204:207], v[0:3]
	v_mfma_f32_16x16x32_bf16 v[100:103], v[144:147], v[218:221], v[100:103]
	v_mfma_f32_16x16x32_bf16 v[68:71], v[148:151], v[218:221], v[68:71]
	v_mfma_f32_16x16x32_bf16 v[36:39], v[152:155], v[218:221], v[36:39]
	v_mfma_f32_16x16x32_bf16 v[4:7], v[156:159], v[218:221], v[4:7]
	s_waitcnt lgkmcnt(0)
	s_barrier
	v_mfma_f32_16x16x32_bf16 v[120:123], v[160:163], v[178:181], v[120:123]
	v_mfma_f32_16x16x32_bf16 v[88:91], v[164:167], v[178:181], v[88:91]
	v_mfma_f32_16x16x32_bf16 v[56:59], v[168:171], v[178:181], v[56:59]
	v_mfma_f32_16x16x32_bf16 v[24:27], v[172:175], v[178:181], v[24:27]
	v_mfma_f32_16x16x32_bf16 v[124:127], v[160:163], v[184:187], v[124:127]
	v_mfma_f32_16x16x32_bf16 v[92:95], v[164:167], v[184:187], v[92:95]
	v_mfma_f32_16x16x32_bf16 v[60:63], v[168:171], v[184:187], v[60:63]
	v_mfma_f32_16x16x32_bf16 v[28:31], v[172:175], v[184:187], v[28:31]
	v_mfma_f32_16x16x32_bf16 v[112:115], v[160:163], v[188:191], v[112:115]
	v_mfma_f32_16x16x32_bf16 v[80:83], v[164:167], v[188:191], v[80:83]
	v_mfma_f32_16x16x32_bf16 v[48:51], v[168:171], v[188:191], v[48:51]
	v_mfma_f32_16x16x32_bf16 v[16:19], v[172:175], v[188:191], v[16:19]
	v_mfma_f32_16x16x32_bf16 v[116:119], v[160:163], v[192:195], v[116:119]
	v_mfma_f32_16x16x32_bf16 v[84:87], v[164:167], v[192:195], v[84:87]
	v_mfma_f32_16x16x32_bf16 v[52:55], v[168:171], v[192:195], v[52:55]
	v_mfma_f32_16x16x32_bf16 v[20:23], v[172:175], v[192:195], v[20:23]
	v_mfma_f32_16x16x32_bf16 v[104:107], v[160:163], v[196:199], v[104:107]
	v_mfma_f32_16x16x32_bf16 v[72:75], v[164:167], v[196:199], v[72:75]
	v_mfma_f32_16x16x32_bf16 v[40:43], v[168:171], v[196:199], v[40:43]
	v_mfma_f32_16x16x32_bf16 v[8:11], v[172:175], v[196:199], v[8:11]
	v_mfma_f32_16x16x32_bf16 v[108:111], v[160:163], v[200:203], v[108:111]
	v_mfma_f32_16x16x32_bf16 v[76:79], v[164:167], v[200:203], v[76:79]
	v_mfma_f32_16x16x32_bf16 v[44:47], v[168:171], v[200:203], v[44:47]
	v_mfma_f32_16x16x32_bf16 v[12:15], v[172:175], v[200:203], v[12:15]
	v_mfma_f32_16x16x32_bf16 v[96:99], v[160:163], v[208:211], v[96:99]
	v_mfma_f32_16x16x32_bf16 v[64:67], v[164:167], v[208:211], v[64:67]
	v_mfma_f32_16x16x32_bf16 v[32:35], v[168:171], v[208:211], v[32:35]
	v_mfma_f32_16x16x32_bf16 v[0:3], v[172:175], v[208:211], v[0:3]
	v_mfma_f32_16x16x32_bf16 v[100:103], v[160:163], v[224:227], v[100:103]
	v_mfma_f32_16x16x32_bf16 v[68:71], v[164:167], v[224:227], v[68:71]
	v_mfma_f32_16x16x32_bf16 v[36:39], v[168:171], v[224:227], v[36:39]
	v_mfma_f32_16x16x32_bf16 v[4:7], v[172:175], v[224:227], v[4:7]
	s_nop 7
	s_nop 3
	s_mov_b64 s[6:7], 0x780
	s_mov_b32 s16, 0xf0000
	s_and_b64 vcc, exec, s[4:5]
	s_cbranch_vccz .LBB0_2880
	v_lshlrev_b32_e32 v128, 1, v138
	v_sub_u32_e32 v128, v137, v128
	v_lshl_or_b32 v129, v138, 14, v140
	v_lshl_add_u32 v128, v128, 5, v129
	v_or_b32_e32 v128, v128, v139
	v_ashrrev_i32_e32 v129, 31, v128
	v_add_u32_e32 v137, 0x8000, v136
	v_lshlrev_b64 v[128:129], 1, v[128:129]
	v_readfirstlane_b32 s2, v136
	v_lshl_add_u64 v[130:131], s[10:11], 0, v[128:129]
	s_mov_b32 m0, s2
	v_readfirstlane_b32 s2, v137
	v_add_u32_e32 v137, 0x2000, v136
	global_load_lds_dwordx4 v[130:131], off
	v_lshl_add_u64 v[128:129], s[14:15], 0, v[128:129]
	s_mov_b32 m0, s2
	v_readfirstlane_b32 s2, v137
	v_add_u32_e32 v137, 0xa000, v136
	global_load_lds_dwordx4 v[128:129], off
	v_lshl_add_u64 v[138:139], v[130:131], 0, s[86:87]
	s_mov_b32 m0, s2
	v_readfirstlane_b32 s2, v137
	v_add_u32_e32 v137, 0x4000, v136
	global_load_lds_dwordx4 v[138:139], off
	v_lshl_add_u64 v[138:139], v[128:129], 0, s[86:87]
	s_mov_b32 m0, s2
	v_readfirstlane_b32 s2, v137
	v_add_u32_e32 v137, 0xc000, v136
	global_load_lds_dwordx4 v[138:139], off
	v_lshl_add_u64 v[138:139], v[130:131], 0, s[88:89]
	s_mov_b32 m0, s2
	v_readfirstlane_b32 s2, v137
	v_add_u32_e32 v137, 0x6000, v136
	global_load_lds_dwordx4 v[138:139], off
	v_lshl_add_u64 v[138:139], v[128:129], 0, s[88:89]
	s_mov_b32 m0, s2
	v_readfirstlane_b32 s2, v137
	global_load_lds_dwordx4 v[138:139], off
	v_lshl_add_u64 v[130:131], v[130:131], 0, s[90:91]
	s_mov_b32 m0, s2
	v_lshl_add_u64 v[128:129], v[128:129], 0, s[90:91]
	global_load_lds_dwordx4 v[130:131], off
	v_add_u32_e32 v130, 0xe000, v136
	s_nop 0
	v_readfirstlane_b32 s2, v130
	s_mov_b32 m0, s2
	s_nop 0
	global_load_lds_dwordx4 v[128:129], off
; #define SBAR() __builtin_amdgcn_sched_barrier(0)
; DEVFI float dpp_xor1(float x) { return __int_as_float(__builtin_amdgcn_update_dpp(0, __float_as_int(x), 0xB1, 0xF, 0xF, true)); }
; DEVFI void store_nat_m(bfraw* base, long ld, f32x4 (&a)[8], int fr) {
;   const bool odd = fr & 1;
;   bfraw* p0 = base + (odd ? 15 + fr : fr);
; #pragma unroll
;   for (int j = 0; j < 4; ++j)
; #pragma unroll
;     for (int n0 = 0; n0 < 8; n0 += 2) { const float own0 = a[n0][j], own1 = a[n0 + 1][j];
;       const float recv = dpp_xor1(odd ? own0 : own1);
;       const unsigned pk = odd ? cvtpk(recv, own1) : cvtpk(own0, recv);
;       *reinterpret_cast<unsigned*>(p0 + (long)j * ld + n0 * 16) = pk; }
; }
; DEVFI void store_nat(bfraw* dst, long ld, f32x4 (&acc)[4][8], int fr, int fq) {
;   store_nat_m(dst + (long)(0 * 16 + fq * 4) * ld, ld, acc[0], fr); SBAR();
;   store_nat_m(dst + (long)(1 * 16 + fq * 4) * ld, ld, acc[1], fr); SBAR();
;   store_nat_m(dst + (long)(2 * 16 + fq * 4) * ld, ld, acc[2], fr); SBAR();
;   store_nat_m(dst + (long)(3 * 16 + fq * 4) * ld, ld, acc[3], fr); SBAR();
; }
.LBB0_2880:
	s_mov_b64 s[2:3], s[0:1]
	s_load_dwordx2 s[2:3], s[2:3], 0xe8
	v_and_b32_e32 v128, 1, v135
	v_cmp_eq_u32_e64 s[6:7], 0, v128
	v_cmp_eq_u32_e64 s[4:5], 1, v128
	s_nop 0
	v_cndmask_b32_e64 v128, v120, v124, s[6:7]
	s_nop 1
	v_mov_b32_dpp v128, v128 quad_perm:[1,0,3,2] row_mask:0xf bank_mask:0xf bound_ctrl:1
	v_cndmask_b32_e64 v135, v120, v128, s[4:5]
	v_cndmask_b32_e64 v128, v128, v124, s[4:5]
	v_cvt_pk_bf16_f32 v135, v135, v128
	s_lshr_b32 s16, s12, 2
	s_and_b32 s16, s16, 0xfffff8
	s_and_b32 s17, s12, 7
	s_or_b32 s16, s16, s17
	s_lshl_b32 s16, s16, 8
	v_lshl_add_u32 v128, s19, 6, v182
	s_ashr_i32 s17, s16, 31
	v_ashrrev_i32_e32 v129, 31, v128
	v_lshl_add_u64 v[128:129], v[128:129], 0, s[16:17]
	v_lshlrev_b64 v[128:129], 11, v[128:129]
	s_waitcnt lgkmcnt(0)
	v_lshl_add_u64 v[128:129], s[2:3], 0, v[128:129]
	s_lshl_b32 s2, s12, 6
	s_and_b32 s12, s2, 0x600
	v_lshl_add_u64 v[128:129], v[128:129], 0, s[12:13]
	v_lshlrev_b32_e32 v176, 8, v134
	v_lshlrev_b32_e32 v120, 9, v133
	v_lshl_add_u64 v[128:129], v[128:129], 0, v[176:177]
	v_and_b32_e32 v176, 0x6000, v120
	v_add_u32_e32 v120, 15, v132
	v_lshl_add_u64 v[128:129], v[128:129], 0, v[176:177]
	s_mov_b64 s[2:3], 0x7720000
	v_cndmask_b32_e64 v120, v120, v132, s[6:7]
	v_lshl_add_u64 v[128:129], v[128:129], 0, s[2:3]
	v_lshlrev_b32_e32 v176, 1, v120
	v_cndmask_b32_e64 v120, v112, v116, s[6:7]
	v_lshl_add_u64 v[130:131], v[128:129], 0, v[176:177]
	global_store_dword v[130:131], v135, off
	v_mov_b32_dpp v124, v120 quad_perm:[1,0,3,2] row_mask:0xf bank_mask:0xf bound_ctrl:1
	v_cndmask_b32_e64 v120, v112, v124, s[4:5]
	v_cndmask_b32_e64 v124, v124, v116, s[4:5]
	v_cvt_pk_bf16_f32 v120, v120, v124
	v_cndmask_b32_e64 v112, v104, v108, s[6:7]
	global_store_dword v[130:131], v120, off offset:64
	s_nop 0
	v_mov_b32_dpp v116, v112 quad_perm:[1,0,3,2] row_mask:0xf bank_mask:0xf bound_ctrl:1
	v_cndmask_b32_e64 v112, v104, v116, s[4:5]
	v_cndmask_b32_e64 v116, v116, v108, s[4:5]
	v_cvt_pk_bf16_f32 v112, v112, v116
	v_cndmask_b32_e64 v104, v96, v100, s[6:7]
	global_store_dword v[130:131], v112, off offset:128
	s_nop 0
	v_mov_b32_dpp v108, v104 quad_perm:[1,0,3,2] row_mask:0xf bank_mask:0xf bound_ctrl:1
	v_cndmask_b32_e64 v104, v96, v108, s[4:5]
	v_cndmask_b32_e64 v108, v108, v100, s[4:5]
	v_cvt_pk_bf16_f32 v104, v104, v108
	v_cndmask_b32_e64 v96, v121, v125, s[6:7]
	global_store_dword v[130:131], v104, off offset:192
	s_nop 0
	v_mov_b32_dpp v100, v96 quad_perm:[1,0,3,2] row_mask:0xf bank_mask:0xf bound_ctrl:1
	v_cndmask_b32_e64 v96, v121, v100, s[4:5]
	v_cndmask_b32_e64 v100, v100, v125, s[4:5]
	v_cvt_pk_bf16_f32 v96, v96, v100
	global_store_dword v[130:131], v96, off offset:2048
	v_cndmask_b32_e64 v96, v113, v117, s[6:7]
	s_nop 1
	v_mov_b32_dpp v100, v96 quad_perm:[1,0,3,2] row_mask:0xf bank_mask:0xf bound_ctrl:1
	v_cndmask_b32_e64 v96, v113, v100, s[4:5]
	v_cndmask_b32_e64 v100, v100, v117, s[4:5]
	v_cvt_pk_bf16_f32 v96, v96, v100
	global_store_dword v[130:131], v96, off offset:2112
	v_cndmask_b32_e64 v96, v105, v109, s[6:7]
	s_nop 1
	v_mov_b32_dpp v100, v96 quad_perm:[1,0,3,2] row_mask:0xf bank_mask:0xf bound_ctrl:1
	v_cndmask_b32_e64 v96, v105, v100, s[4:5]
	v_cndmask_b32_e64 v100, v100, v109, s[4:5]
	v_cvt_pk_bf16_f32 v96, v96, v100
	global_store_dword v[130:131], v96, off offset:2176
	v_cndmask_b32_e64 v96, v97, v101, s[6:7]
	s_nop 1
	v_mov_b32_dpp v100, v96 quad_perm:[1,0,3,2] row_mask:0xf bank_mask:0xf bound_ctrl:1
	v_cndmask_b32_e64 v96, v97, v100, s[4:5]
	v_cndmask_b32_e64 v100, v100, v101, s[4:5]
	v_cvt_pk_bf16_f32 v96, v96, v100
	global_store_dword v[130:131], v96, off offset:2240
	v_cndmask_b32_e64 v96, v122, v126, s[6:7]
	s_nop 1
	v_mov_b32_dpp v97, v96 quad_perm:[1,0,3,2] row_mask:0xf bank_mask:0xf bound_ctrl:1
	v_cndmask_b32_e64 v96, v122, v97, s[4:5]
	v_cndmask_b32_e64 v97, v97, v126, s[4:5]
	v_cvt_pk_bf16_f32 v96, v96, v97
	v_add_co_u32_e32 v100, vcc, 0x1000, v130
	s_nop 1
	v_addc_co_u32_e32 v101, vcc, 0, v131, vcc
	global_store_dword v[100:101], v96, off
	v_cndmask_b32_e64 v96, v114, v118, s[6:7]
	s_nop 1
	v_mov_b32_dpp v97, v96 quad_perm:[1,0,3,2] row_mask:0xf bank_mask:0xf bound_ctrl:1
	v_cndmask_b32_e64 v96, v114, v97, s[4:5]
	v_cndmask_b32_e64 v97, v97, v118, s[4:5]
	v_cvt_pk_bf16_f32 v96, v96, v97
	v_add_co_u32_e32 v100, vcc, 0x1000, v130
	s_nop 1
	v_addc_co_u32_e32 v101, vcc, 0, v131, vcc
	global_store_dword v[100:101], v96, off offset:64
	v_cndmask_b32_e64 v96, v106, v110, s[6:7]
	s_nop 1
	v_mov_b32_dpp v97, v96 quad_perm:[1,0,3,2] row_mask:0xf bank_mask:0xf bound_ctrl:1
	v_cndmask_b32_e64 v96, v106, v97, s[4:5]
	v_cndmask_b32_e64 v97, v97, v110, s[4:5]
	v_cvt_pk_bf16_f32 v96, v96, v97
	v_add_co_u32_e32 v100, vcc, 0x1000, v130
	s_nop 1
	v_addc_co_u32_e32 v101, vcc, 0, v131, vcc
	global_store_dword v[100:101], v96, off offset:128
	v_cndmask_b32_e64 v96, v98, v102, s[6:7]
	s_nop 1
	v_mov_b32_dpp v97, v96 quad_perm:[1,0,3,2] row_mask:0xf bank_mask:0xf bound_ctrl:1
	v_cndmask_b32_e64 v96, v98, v97, s[4:5]
	v_cndmask_b32_e64 v97, v97, v102, s[4:5]
	v_cvt_pk_bf16_f32 v96, v96, v97
	v_add_co_u32_e32 v100, vcc, 0x1000, v130
	s_nop 1
	v_addc_co_u32_e32 v101, vcc, 0, v131, vcc
	global_store_dword v[100:101], v96, off offset:192
	v_cndmask_b32_e64 v96, v123, v127, s[6:7]
	s_nop 1
	v_mov_b32_dpp v97, v96 quad_perm:[1,0,3,2] row_mask:0xf bank_mask:0xf bound_ctrl:1
	v_cndmask_b32_e64 v96, v123, v97, s[4:5]
	v_cndmask_b32_e64 v97, v97, v127, s[4:5]
	v_cvt_pk_bf16_f32 v96, v96, v97
	v_add_co_u32_e32 v100, vcc, 0x1000, v130
	s_nop 1
	v_addc_co_u32_e32 v101, vcc, 0, v131, vcc
	global_store_dword v[100:101], v96, off offset:2048
	v_cndmask_b32_e64 v96, v115, v119, s[6:7]
	s_nop 1
; #define SBAR() __builtin_amdgcn_sched_barrier(0)
; DEVFI float dpp_xor1(float x) { return __int_as_float(__builtin_amdgcn_update_dpp(0, __float_as_int(x), 0xB1, 0xF, 0xF, true)); }
; DEVFI void store_nat_m(bfraw* base, long ld, f32x4 (&a)[8], int fr) {
;   const bool odd = fr & 1;
;   bfraw* p0 = base + (odd ? 15 + fr : fr);
; #pragma unroll
;   for (int j = 0; j < 4; ++j)
; #pragma unroll
;     for (int n0 = 0; n0 < 8; n0 += 2) { const float own0 = a[n0][j], own1 = a[n0 + 1][j];
;       const float recv = dpp_xor1(odd ? own0 : own1);
;       const unsigned pk = odd ? cvtpk(recv, own1) : cvtpk(own0, recv);
;       *reinterpret_cast<unsigned*>(p0 + (long)j * ld + n0 * 16) = pk; }
; }
; DEVFI void store_nat(bfraw* dst, long ld, f32x4 (&acc)[4][8], int fr, int fq) {
;   store_nat_m(dst + (long)(0 * 16 + fq * 4) * ld, ld, acc[0], fr); SBAR();
;   store_nat_m(dst + (long)(1 * 16 + fq * 4) * ld, ld, acc[1], fr); SBAR();
;   store_nat_m(dst + (long)(2 * 16 + fq * 4) * ld, ld, acc[2], fr); SBAR();
;   store_nat_m(dst + (long)(3 * 16 + fq * 4) * ld, ld, acc[3], fr); SBAR();
; }
	v_mov_b32_dpp v97, v96 quad_perm:[1,0,3,2] row_mask:0xf bank_mask:0xf bound_ctrl:1
	v_cndmask_b32_e64 v96, v115, v97, s[4:5]
	v_cndmask_b32_e64 v97, v97, v119, s[4:5]
	v_cvt_pk_bf16_f32 v96, v96, v97
	v_add_co_u32_e32 v100, vcc, 0x1000, v130
	s_nop 1
	v_addc_co_u32_e32 v101, vcc, 0, v131, vcc
	global_store_dword v[100:101], v96, off offset:2112
	v_cndmask_b32_e64 v96, v107, v111, s[6:7]
	s_nop 1
	v_mov_b32_dpp v97, v96 quad_perm:[1,0,3,2] row_mask:0xf bank_mask:0xf bound_ctrl:1
	v_cndmask_b32_e64 v96, v107, v97, s[4:5]
	v_cndmask_b32_e64 v97, v97, v111, s[4:5]
	v_cvt_pk_bf16_f32 v96, v96, v97
	v_add_co_u32_e32 v100, vcc, 0x1000, v130
	s_nop 1
	v_addc_co_u32_e32 v101, vcc, 0, v131, vcc
	global_store_dword v[100:101], v96, off offset:2176
	v_cndmask_b32_e64 v96, v99, v103, s[6:7]
	s_nop 1
	v_mov_b32_dpp v96, v96 quad_perm:[1,0,3,2] row_mask:0xf bank_mask:0xf bound_ctrl:1
	v_cndmask_b32_e64 v100, v99, v96, s[4:5]
	v_cndmask_b32_e64 v96, v96, v103, s[4:5]
	v_cvt_pk_bf16_f32 v100, v100, v96
	v_add_co_u32_e32 v96, vcc, 0x1000, v130
	s_nop 1
	v_addc_co_u32_e32 v97, vcc, 0, v131, vcc
	global_store_dword v[96:97], v100, off offset:2240
	v_cndmask_b32_e64 v96, v88, v92, s[6:7]
	s_nop 1
	v_mov_b32_dpp v96, v96 quad_perm:[1,0,3,2] row_mask:0xf bank_mask:0xf bound_ctrl:1
	v_cndmask_b32_e64 v98, v88, v96, s[4:5]
	v_cndmask_b32_e64 v96, v96, v92, s[4:5]
	v_cvt_pk_bf16_f32 v98, v98, v96
	v_lshl_add_u64 v[96:97], v[128:129], 0, v[176:177]
	v_add_co_u32_e32 v100, vcc, 0x8000, v96
	v_cndmask_b32_e64 v88, v80, v84, s[6:7]
	s_nop 0
	v_addc_co_u32_e32 v101, vcc, 0, v97, vcc
	v_mov_b32_dpp v92, v88 quad_perm:[1,0,3,2] row_mask:0xf bank_mask:0xf bound_ctrl:1
	global_store_dword v[100:101], v98, off
	v_cndmask_b32_e64 v88, v80, v92, s[4:5]
	v_cndmask_b32_e64 v92, v92, v84, s[4:5]
	v_cvt_pk_bf16_f32 v88, v88, v92
	s_mov_b64 s[2:3], 0x8000
	v_cndmask_b32_e64 v80, v72, v76, s[6:7]
	v_lshl_add_u64 v[96:97], v[96:97], 0, s[2:3]
	global_store_dword v[96:97], v88, off offset:64
	v_mov_b32_dpp v84, v80 quad_perm:[1,0,3,2] row_mask:0xf bank_mask:0xf bound_ctrl:1
	v_cndmask_b32_e64 v80, v72, v84, s[4:5]
	v_cndmask_b32_e64 v84, v84, v76, s[4:5]
	v_cvt_pk_bf16_f32 v80, v80, v84
	v_cndmask_b32_e64 v72, v64, v68, s[6:7]
	global_store_dword v[96:97], v80, off offset:128
	s_nop 0
	v_mov_b32_dpp v76, v72 quad_perm:[1,0,3,2] row_mask:0xf bank_mask:0xf bound_ctrl:1
	v_cndmask_b32_e64 v72, v64, v76, s[4:5]
	v_cndmask_b32_e64 v76, v76, v68, s[4:5]
	v_cvt_pk_bf16_f32 v72, v72, v76
	v_cndmask_b32_e64 v64, v89, v93, s[6:7]
	global_store_dword v[96:97], v72, off offset:192
	s_nop 0
	v_mov_b32_dpp v68, v64 quad_perm:[1,0,3,2] row_mask:0xf bank_mask:0xf bound_ctrl:1
	v_cndmask_b32_e64 v64, v89, v68, s[4:5]
	v_cndmask_b32_e64 v68, v68, v93, s[4:5]
	v_cvt_pk_bf16_f32 v64, v64, v68
	global_store_dword v[96:97], v64, off offset:2048
	v_cndmask_b32_e64 v64, v81, v85, s[6:7]
	s_nop 1
	v_mov_b32_dpp v68, v64 quad_perm:[1,0,3,2] row_mask:0xf bank_mask:0xf bound_ctrl:1
	v_cndmask_b32_e64 v64, v81, v68, s[4:5]
	v_cndmask_b32_e64 v68, v68, v85, s[4:5]
	v_cvt_pk_bf16_f32 v64, v64, v68
	global_store_dword v[96:97], v64, off offset:2112
	v_cndmask_b32_e64 v64, v73, v77, s[6:7]
	s_nop 1
	v_mov_b32_dpp v68, v64 quad_perm:[1,0,3,2] row_mask:0xf bank_mask:0xf bound_ctrl:1
	v_cndmask_b32_e64 v64, v73, v68, s[4:5]
	v_cndmask_b32_e64 v68, v68, v77, s[4:5]
	v_cvt_pk_bf16_f32 v64, v64, v68
	global_store_dword v[96:97], v64, off offset:2176
	v_cndmask_b32_e64 v64, v65, v69, s[6:7]
	s_nop 1
	v_mov_b32_dpp v68, v64 quad_perm:[1,0,3,2] row_mask:0xf bank_mask:0xf bound_ctrl:1
	v_cndmask_b32_e64 v64, v65, v68, s[4:5]
	v_cndmask_b32_e64 v68, v68, v69, s[4:5]
	v_cvt_pk_bf16_f32 v64, v64, v68
	global_store_dword v[96:97], v64, off offset:2240
	v_cndmask_b32_e64 v64, v90, v94, s[6:7]
	s_nop 1
	v_mov_b32_dpp v65, v64 quad_perm:[1,0,3,2] row_mask:0xf bank_mask:0xf bound_ctrl:1
	v_cndmask_b32_e64 v64, v90, v65, s[4:5]
	v_cndmask_b32_e64 v65, v65, v94, s[4:5]
	v_cvt_pk_bf16_f32 v64, v64, v65
	v_add_co_u32_e32 v68, vcc, 0x1000, v96
	s_nop 1
	v_addc_co_u32_e32 v69, vcc, 0, v97, vcc
	global_store_dword v[68:69], v64, off
	v_cndmask_b32_e64 v64, v82, v86, s[6:7]
	s_nop 1
	v_mov_b32_dpp v65, v64 quad_perm:[1,0,3,2] row_mask:0xf bank_mask:0xf bound_ctrl:1
	v_cndmask_b32_e64 v64, v82, v65, s[4:5]
	v_cndmask_b32_e64 v65, v65, v86, s[4:5]
	v_cvt_pk_bf16_f32 v64, v64, v65
	v_add_co_u32_e32 v68, vcc, 0x1000, v96
	s_nop 1
	v_addc_co_u32_e32 v69, vcc, 0, v97, vcc
	global_store_dword v[68:69], v64, off offset:64
	v_cndmask_b32_e64 v64, v74, v78, s[6:7]
	s_nop 1
	v_mov_b32_dpp v65, v64 quad_perm:[1,0,3,2] row_mask:0xf bank_mask:0xf bound_ctrl:1
	v_cndmask_b32_e64 v64, v74, v65, s[4:5]
	v_cndmask_b32_e64 v65, v65, v78, s[4:5]
	v_cvt_pk_bf16_f32 v64, v64, v65
	v_add_co_u32_e32 v68, vcc, 0x1000, v96
	s_nop 1
	v_addc_co_u32_e32 v69, vcc, 0, v97, vcc
	global_store_dword v[68:69], v64, off offset:128
	v_cndmask_b32_e64 v64, v66, v70, s[6:7]
	s_nop 1
	v_mov_b32_dpp v65, v64 quad_perm:[1,0,3,2] row_mask:0xf bank_mask:0xf bound_ctrl:1
	v_cndmask_b32_e64 v64, v66, v65, s[4:5]
	v_cndmask_b32_e64 v65, v65, v70, s[4:5]
	v_cvt_pk_bf16_f32 v64, v64, v65
	v_add_co_u32_e32 v68, vcc, 0x1000, v96
	s_nop 1
	v_addc_co_u32_e32 v69, vcc, 0, v97, vcc
	global_store_dword v[68:69], v64, off offset:192
	v_cndmask_b32_e64 v64, v91, v95, s[6:7]
	s_nop 1
	v_mov_b32_dpp v65, v64 quad_perm:[1,0,3,2] row_mask:0xf bank_mask:0xf bound_ctrl:1
	v_cndmask_b32_e64 v64, v91, v65, s[4:5]
	v_cndmask_b32_e64 v65, v65, v95, s[4:5]
	v_cvt_pk_bf16_f32 v64, v64, v65
	v_add_co_u32_e32 v68, vcc, 0x1000, v96
	s_nop 1
	v_addc_co_u32_e32 v69, vcc, 0, v97, vcc
	global_store_dword v[68:69], v64, off offset:2048
; #define SBAR() __builtin_amdgcn_sched_barrier(0)
; DEVFI float dpp_xor1(float x) { return __int_as_float(__builtin_amdgcn_update_dpp(0, __float_as_int(x), 0xB1, 0xF, 0xF, true)); }
; DEVFI void store_nat_m(bfraw* base, long ld, f32x4 (&a)[8], int fr) {
;   const bool odd = fr & 1;
;   bfraw* p0 = base + (odd ? 15 + fr : fr);
; #pragma unroll
;   for (int j = 0; j < 4; ++j)
; #pragma unroll
;     for (int n0 = 0; n0 < 8; n0 += 2) { const float own0 = a[n0][j], own1 = a[n0 + 1][j];
;       const float recv = dpp_xor1(odd ? own0 : own1);
;       const unsigned pk = odd ? cvtpk(recv, own1) : cvtpk(own0, recv);
;       *reinterpret_cast<unsigned*>(p0 + (long)j * ld + n0 * 16) = pk; }
; }
; DEVFI void store_nat(bfraw* dst, long ld, f32x4 (&acc)[4][8], int fr, int fq) {
;   store_nat_m(dst + (long)(0 * 16 + fq * 4) * ld, ld, acc[0], fr); SBAR();
;   store_nat_m(dst + (long)(1 * 16 + fq * 4) * ld, ld, acc[1], fr); SBAR();
;   store_nat_m(dst + (long)(2 * 16 + fq * 4) * ld, ld, acc[2], fr); SBAR();
;   store_nat_m(dst + (long)(3 * 16 + fq * 4) * ld, ld, acc[3], fr); SBAR();
; }
	v_cndmask_b32_e64 v64, v83, v87, s[6:7]
	s_nop 1
	v_mov_b32_dpp v65, v64 quad_perm:[1,0,3,2] row_mask:0xf bank_mask:0xf bound_ctrl:1
	v_cndmask_b32_e64 v64, v83, v65, s[4:5]
	v_cndmask_b32_e64 v65, v65, v87, s[4:5]
	v_cvt_pk_bf16_f32 v64, v64, v65
	v_add_co_u32_e32 v68, vcc, 0x1000, v96
	s_nop 1
	v_addc_co_u32_e32 v69, vcc, 0, v97, vcc
	global_store_dword v[68:69], v64, off offset:2112
	v_cndmask_b32_e64 v64, v75, v79, s[6:7]
	s_nop 1
	v_mov_b32_dpp v65, v64 quad_perm:[1,0,3,2] row_mask:0xf bank_mask:0xf bound_ctrl:1
	v_cndmask_b32_e64 v64, v75, v65, s[4:5]
	v_cndmask_b32_e64 v65, v65, v79, s[4:5]
	v_cvt_pk_bf16_f32 v64, v64, v65
	v_add_co_u32_e32 v68, vcc, 0x1000, v96
	s_nop 1
	v_addc_co_u32_e32 v69, vcc, 0, v97, vcc
	global_store_dword v[68:69], v64, off offset:2176
	v_cndmask_b32_e64 v64, v67, v71, s[6:7]
	s_nop 1
	v_mov_b32_dpp v64, v64 quad_perm:[1,0,3,2] row_mask:0xf bank_mask:0xf bound_ctrl:1
	v_cndmask_b32_e64 v68, v67, v64, s[4:5]
	v_cndmask_b32_e64 v64, v64, v71, s[4:5]
	v_cvt_pk_bf16_f32 v68, v68, v64
	v_add_co_u32_e32 v64, vcc, 0x1000, v96
	s_nop 1
	v_addc_co_u32_e32 v65, vcc, 0, v97, vcc
	global_store_dword v[64:65], v68, off offset:2240
	v_cndmask_b32_e64 v64, v56, v60, s[6:7]
	s_nop 1
	v_mov_b32_dpp v64, v64 quad_perm:[1,0,3,2] row_mask:0xf bank_mask:0xf bound_ctrl:1
	v_cndmask_b32_e64 v66, v56, v64, s[4:5]
	v_cndmask_b32_e64 v64, v64, v60, s[4:5]
	v_cvt_pk_bf16_f32 v66, v66, v64
	v_lshl_add_u64 v[64:65], v[128:129], 0, v[176:177]
	v_add_co_u32_e32 v68, vcc, 0x10000, v64
	v_cndmask_b32_e64 v56, v48, v52, s[6:7]
	s_nop 0
	v_addc_co_u32_e32 v69, vcc, 0, v65, vcc
	v_mov_b32_dpp v60, v56 quad_perm:[1,0,3,2] row_mask:0xf bank_mask:0xf bound_ctrl:1
	global_store_dword v[68:69], v66, off
	v_cndmask_b32_e64 v56, v48, v60, s[4:5]
	v_cndmask_b32_e64 v60, v60, v52, s[4:5]
	v_cvt_pk_bf16_f32 v56, v56, v60
	v_cndmask_b32_e64 v48, v40, v44, s[6:7]
	v_lshl_add_u64 v[64:65], v[64:65], 0, s[48:49]
	global_store_dword v[64:65], v56, off offset:64
	v_mov_b32_dpp v52, v48 quad_perm:[1,0,3,2] row_mask:0xf bank_mask:0xf bound_ctrl:1
	v_cndmask_b32_e64 v48, v40, v52, s[4:5]
	v_cndmask_b32_e64 v52, v52, v44, s[4:5]
	v_cvt_pk_bf16_f32 v48, v48, v52
	v_cndmask_b32_e64 v40, v32, v36, s[6:7]
	global_store_dword v[64:65], v48, off offset:128
	s_nop 0
	v_mov_b32_dpp v44, v40 quad_perm:[1,0,3,2] row_mask:0xf bank_mask:0xf bound_ctrl:1
	v_cndmask_b32_e64 v40, v32, v44, s[4:5]
	v_cndmask_b32_e64 v44, v44, v36, s[4:5]
	v_cvt_pk_bf16_f32 v40, v40, v44
	v_cndmask_b32_e64 v32, v57, v61, s[6:7]
	global_store_dword v[64:65], v40, off offset:192
	s_nop 0
	v_mov_b32_dpp v36, v32 quad_perm:[1,0,3,2] row_mask:0xf bank_mask:0xf bound_ctrl:1
	v_cndmask_b32_e64 v32, v57, v36, s[4:5]
	v_cndmask_b32_e64 v36, v36, v61, s[4:5]
	v_cvt_pk_bf16_f32 v32, v32, v36
	global_store_dword v[64:65], v32, off offset:2048
	v_cndmask_b32_e64 v32, v49, v53, s[6:7]
	s_nop 1
	v_mov_b32_dpp v36, v32 quad_perm:[1,0,3,2] row_mask:0xf bank_mask:0xf bound_ctrl:1
	v_cndmask_b32_e64 v32, v49, v36, s[4:5]
	v_cndmask_b32_e64 v36, v36, v53, s[4:5]
	v_cvt_pk_bf16_f32 v32, v32, v36
	global_store_dword v[64:65], v32, off offset:2112
	v_cndmask_b32_e64 v32, v41, v45, s[6:7]
	s_nop 1
	v_mov_b32_dpp v36, v32 quad_perm:[1,0,3,2] row_mask:0xf bank_mask:0xf bound_ctrl:1
	v_cndmask_b32_e64 v32, v41, v36, s[4:5]
	v_cndmask_b32_e64 v36, v36, v45, s[4:5]
	v_cvt_pk_bf16_f32 v32, v32, v36
	global_store_dword v[64:65], v32, off offset:2176
	v_cndmask_b32_e64 v32, v33, v37, s[6:7]
	s_nop 1
	v_mov_b32_dpp v36, v32 quad_perm:[1,0,3,2] row_mask:0xf bank_mask:0xf bound_ctrl:1
	v_cndmask_b32_e64 v32, v33, v36, s[4:5]
	v_cndmask_b32_e64 v36, v36, v37, s[4:5]
	v_cvt_pk_bf16_f32 v32, v32, v36
	global_store_dword v[64:65], v32, off offset:2240
	v_cndmask_b32_e64 v32, v58, v62, s[6:7]
	s_nop 1
	v_mov_b32_dpp v33, v32 quad_perm:[1,0,3,2] row_mask:0xf bank_mask:0xf bound_ctrl:1
	v_cndmask_b32_e64 v32, v58, v33, s[4:5]
	v_cndmask_b32_e64 v33, v33, v62, s[4:5]
	v_cvt_pk_bf16_f32 v32, v32, v33
	v_add_co_u32_e32 v36, vcc, 0x1000, v64
	s_nop 1
	v_addc_co_u32_e32 v37, vcc, 0, v65, vcc
	global_store_dword v[36:37], v32, off
	v_cndmask_b32_e64 v32, v50, v54, s[6:7]
	s_nop 1
	v_mov_b32_dpp v33, v32 quad_perm:[1,0,3,2] row_mask:0xf bank_mask:0xf bound_ctrl:1
	v_cndmask_b32_e64 v32, v50, v33, s[4:5]
	v_cndmask_b32_e64 v33, v33, v54, s[4:5]
	v_cvt_pk_bf16_f32 v32, v32, v33
	v_add_co_u32_e32 v36, vcc, 0x1000, v64
	s_nop 1
	v_addc_co_u32_e32 v37, vcc, 0, v65, vcc
	global_store_dword v[36:37], v32, off offset:64
	v_cndmask_b32_e64 v32, v42, v46, s[6:7]
	s_nop 1
	v_mov_b32_dpp v33, v32 quad_perm:[1,0,3,2] row_mask:0xf bank_mask:0xf bound_ctrl:1
	v_cndmask_b32_e64 v32, v42, v33, s[4:5]
	v_cndmask_b32_e64 v33, v33, v46, s[4:5]
	v_cvt_pk_bf16_f32 v32, v32, v33
	v_add_co_u32_e32 v36, vcc, 0x1000, v64
	s_nop 1
	v_addc_co_u32_e32 v37, vcc, 0, v65, vcc
	global_store_dword v[36:37], v32, off offset:128
	v_cndmask_b32_e64 v32, v34, v38, s[6:7]
	s_nop 1
	v_mov_b32_dpp v33, v32 quad_perm:[1,0,3,2] row_mask:0xf bank_mask:0xf bound_ctrl:1
	v_cndmask_b32_e64 v32, v34, v33, s[4:5]
	v_cndmask_b32_e64 v33, v33, v38, s[4:5]
	v_cvt_pk_bf16_f32 v32, v32, v33
	v_add_co_u32_e32 v36, vcc, 0x1000, v64
	s_nop 1
	v_addc_co_u32_e32 v37, vcc, 0, v65, vcc
	global_store_dword v[36:37], v32, off offset:192
	v_cndmask_b32_e64 v32, v59, v63, s[6:7]
	s_nop 1
	v_mov_b32_dpp v33, v32 quad_perm:[1,0,3,2] row_mask:0xf bank_mask:0xf bound_ctrl:1
	v_cndmask_b32_e64 v32, v59, v33, s[4:5]
	v_cndmask_b32_e64 v33, v33, v63, s[4:5]
	v_cvt_pk_bf16_f32 v32, v32, v33
	v_add_co_u32_e32 v36, vcc, 0x1000, v64
	s_nop 1
	v_addc_co_u32_e32 v37, vcc, 0, v65, vcc
	global_store_dword v[36:37], v32, off offset:2048
; #define SBAR() __builtin_amdgcn_sched_barrier(0)
; DEVFI float dpp_xor1(float x) { return __int_as_float(__builtin_amdgcn_update_dpp(0, __float_as_int(x), 0xB1, 0xF, 0xF, true)); }
; DEVFI void store_nat_m(bfraw* base, long ld, f32x4 (&a)[8], int fr) {
;   const bool odd = fr & 1;
;   bfraw* p0 = base + (odd ? 15 + fr : fr);
; #pragma unroll
;   for (int j = 0; j < 4; ++j)
; #pragma unroll
;     for (int n0 = 0; n0 < 8; n0 += 2) { const float own0 = a[n0][j], own1 = a[n0 + 1][j];
;       const float recv = dpp_xor1(odd ? own0 : own1);
;       const unsigned pk = odd ? cvtpk(recv, own1) : cvtpk(own0, recv);
;       *reinterpret_cast<unsigned*>(p0 + (long)j * ld + n0 * 16) = pk; }
; }
; DEVFI void store_nat(bfraw* dst, long ld, f32x4 (&acc)[4][8], int fr, int fq) {
;   store_nat_m(dst + (long)(0 * 16 + fq * 4) * ld, ld, acc[0], fr); SBAR();
;   store_nat_m(dst + (long)(1 * 16 + fq * 4) * ld, ld, acc[1], fr); SBAR();
;   store_nat_m(dst + (long)(2 * 16 + fq * 4) * ld, ld, acc[2], fr); SBAR();
;   store_nat_m(dst + (long)(3 * 16 + fq * 4) * ld, ld, acc[3], fr); SBAR();
; }
	v_cndmask_b32_e64 v32, v51, v55, s[6:7]
	s_nop 1
	v_mov_b32_dpp v33, v32 quad_perm:[1,0,3,2] row_mask:0xf bank_mask:0xf bound_ctrl:1
	v_cndmask_b32_e64 v32, v51, v33, s[4:5]
	v_cndmask_b32_e64 v33, v33, v55, s[4:5]
	v_cvt_pk_bf16_f32 v32, v32, v33
	v_add_co_u32_e32 v36, vcc, 0x1000, v64
	s_nop 1
	v_addc_co_u32_e32 v37, vcc, 0, v65, vcc
	global_store_dword v[36:37], v32, off offset:2112
	v_cndmask_b32_e64 v32, v43, v47, s[6:7]
	s_nop 1
	v_mov_b32_dpp v33, v32 quad_perm:[1,0,3,2] row_mask:0xf bank_mask:0xf bound_ctrl:1
	v_cndmask_b32_e64 v32, v43, v33, s[4:5]
	v_cndmask_b32_e64 v33, v33, v47, s[4:5]
	v_cvt_pk_bf16_f32 v32, v32, v33
	v_add_co_u32_e32 v36, vcc, 0x1000, v64
	s_nop 1
	v_addc_co_u32_e32 v37, vcc, 0, v65, vcc
	global_store_dword v[36:37], v32, off offset:2176
	v_cndmask_b32_e64 v32, v35, v39, s[6:7]
	s_nop 1
	v_mov_b32_dpp v32, v32 quad_perm:[1,0,3,2] row_mask:0xf bank_mask:0xf bound_ctrl:1
	v_cndmask_b32_e64 v36, v35, v32, s[4:5]
	v_cndmask_b32_e64 v32, v32, v39, s[4:5]
	v_cvt_pk_bf16_f32 v36, v36, v32
	v_add_co_u32_e32 v32, vcc, 0x1000, v64
	s_nop 1
	v_addc_co_u32_e32 v33, vcc, 0, v65, vcc
	global_store_dword v[32:33], v36, off offset:2240
	v_cndmask_b32_e64 v32, v24, v28, s[6:7]
	s_nop 1
	v_mov_b32_dpp v32, v32 quad_perm:[1,0,3,2] row_mask:0xf bank_mask:0xf bound_ctrl:1
	v_cndmask_b32_e64 v34, v24, v32, s[4:5]
	v_cndmask_b32_e64 v32, v32, v28, s[4:5]
	v_cvt_pk_bf16_f32 v34, v34, v32
	v_lshl_add_u64 v[32:33], v[128:129], 0, v[176:177]
	v_add_co_u32_e32 v36, vcc, 0x18000, v32
	v_cndmask_b32_e64 v24, v16, v20, s[6:7]
	s_nop 0
	v_addc_co_u32_e32 v37, vcc, 0, v33, vcc
	v_mov_b32_dpp v28, v24 quad_perm:[1,0,3,2] row_mask:0xf bank_mask:0xf bound_ctrl:1
	global_store_dword v[36:37], v34, off
	v_cndmask_b32_e64 v24, v16, v28, s[4:5]
	v_cndmask_b32_e64 v28, v28, v20, s[4:5]
	v_cvt_pk_bf16_f32 v24, v24, v28
	s_mov_b64 s[2:3], 0x18000
	v_cndmask_b32_e64 v16, v8, v12, s[6:7]
	v_lshl_add_u64 v[32:33], v[32:33], 0, s[2:3]
	global_store_dword v[32:33], v24, off offset:64
	v_mov_b32_dpp v20, v16 quad_perm:[1,0,3,2] row_mask:0xf bank_mask:0xf bound_ctrl:1
	v_cndmask_b32_e64 v16, v8, v20, s[4:5]
	v_cndmask_b32_e64 v20, v20, v12, s[4:5]
	v_cvt_pk_bf16_f32 v16, v16, v20
	v_cndmask_b32_e64 v8, v0, v4, s[6:7]
	global_store_dword v[32:33], v16, off offset:128
	s_nop 0
	v_mov_b32_dpp v12, v8 quad_perm:[1,0,3,2] row_mask:0xf bank_mask:0xf bound_ctrl:1
	v_cndmask_b32_e64 v8, v0, v12, s[4:5]
	v_cndmask_b32_e64 v12, v12, v4, s[4:5]
	v_cvt_pk_bf16_f32 v8, v8, v12
	v_cndmask_b32_e64 v0, v25, v29, s[6:7]
	global_store_dword v[32:33], v8, off offset:192
	s_nop 0
	v_mov_b32_dpp v4, v0 quad_perm:[1,0,3,2] row_mask:0xf bank_mask:0xf bound_ctrl:1
	v_cndmask_b32_e64 v0, v25, v4, s[4:5]
	v_cndmask_b32_e64 v4, v4, v29, s[4:5]
	v_cvt_pk_bf16_f32 v0, v0, v4
	global_store_dword v[32:33], v0, off offset:2048
	v_cndmask_b32_e64 v0, v17, v21, s[6:7]
	s_nop 1
	v_mov_b32_dpp v4, v0 quad_perm:[1,0,3,2] row_mask:0xf bank_mask:0xf bound_ctrl:1
	v_cndmask_b32_e64 v0, v17, v4, s[4:5]
	v_cndmask_b32_e64 v4, v4, v21, s[4:5]
	v_cvt_pk_bf16_f32 v0, v0, v4
	global_store_dword v[32:33], v0, off offset:2112
	v_cndmask_b32_e64 v0, v9, v13, s[6:7]
	s_nop 1
	v_mov_b32_dpp v4, v0 quad_perm:[1,0,3,2] row_mask:0xf bank_mask:0xf bound_ctrl:1
	v_cndmask_b32_e64 v0, v9, v4, s[4:5]
	v_cndmask_b32_e64 v4, v4, v13, s[4:5]
	v_cvt_pk_bf16_f32 v0, v0, v4
	global_store_dword v[32:33], v0, off offset:2176
	v_cndmask_b32_e64 v0, v1, v5, s[6:7]
	s_nop 1
	v_mov_b32_dpp v4, v0 quad_perm:[1,0,3,2] row_mask:0xf bank_mask:0xf bound_ctrl:1
	v_cndmask_b32_e64 v0, v1, v4, s[4:5]
	v_cndmask_b32_e64 v4, v4, v5, s[4:5]
	v_cvt_pk_bf16_f32 v0, v0, v4
	global_store_dword v[32:33], v0, off offset:2240
	v_cndmask_b32_e64 v0, v26, v30, s[6:7]
	s_nop 1
	v_mov_b32_dpp v1, v0 quad_perm:[1,0,3,2] row_mask:0xf bank_mask:0xf bound_ctrl:1
	v_cndmask_b32_e64 v0, v26, v1, s[4:5]
	v_cndmask_b32_e64 v1, v1, v30, s[4:5]
	v_cvt_pk_bf16_f32 v0, v0, v1
	v_add_co_u32_e32 v4, vcc, 0x1000, v32
	s_nop 1
	v_addc_co_u32_e32 v5, vcc, 0, v33, vcc
	global_store_dword v[4:5], v0, off
	v_cndmask_b32_e64 v0, v18, v22, s[6:7]
	s_nop 1
	v_mov_b32_dpp v1, v0 quad_perm:[1,0,3,2] row_mask:0xf bank_mask:0xf bound_ctrl:1
	v_cndmask_b32_e64 v0, v18, v1, s[4:5]
	v_cndmask_b32_e64 v1, v1, v22, s[4:5]
	v_cvt_pk_bf16_f32 v0, v0, v1
	v_add_co_u32_e32 v4, vcc, 0x1000, v32
	s_nop 1
	v_addc_co_u32_e32 v5, vcc, 0, v33, vcc
	global_store_dword v[4:5], v0, off offset:64
	v_cndmask_b32_e64 v0, v10, v14, s[6:7]
	s_nop 1
	v_mov_b32_dpp v1, v0 quad_perm:[1,0,3,2] row_mask:0xf bank_mask:0xf bound_ctrl:1
	v_cndmask_b32_e64 v0, v10, v1, s[4:5]
	v_cndmask_b32_e64 v1, v1, v14, s[4:5]
	v_cvt_pk_bf16_f32 v0, v0, v1
	v_add_co_u32_e32 v4, vcc, 0x1000, v32
	s_nop 1
	v_addc_co_u32_e32 v5, vcc, 0, v33, vcc
	global_store_dword v[4:5], v0, off offset:128
	v_cndmask_b32_e64 v0, v2, v6, s[6:7]
	s_nop 1
	v_mov_b32_dpp v1, v0 quad_perm:[1,0,3,2] row_mask:0xf bank_mask:0xf bound_ctrl:1
	v_cndmask_b32_e64 v0, v2, v1, s[4:5]
	v_cndmask_b32_e64 v1, v1, v6, s[4:5]
	v_cvt_pk_bf16_f32 v0, v0, v1
	v_add_co_u32_e32 v4, vcc, 0x1000, v32
	s_nop 1
	v_addc_co_u32_e32 v5, vcc, 0, v33, vcc
	global_store_dword v[4:5], v0, off offset:192
	v_cndmask_b32_e64 v0, v27, v31, s[6:7]
	s_nop 1
	v_mov_b32_dpp v1, v0 quad_perm:[1,0,3,2] row_mask:0xf bank_mask:0xf bound_ctrl:1
	v_cndmask_b32_e64 v0, v27, v1, s[4:5]
	v_cndmask_b32_e64 v1, v1, v31, s[4:5]
	v_cvt_pk_bf16_f32 v0, v0, v1
	v_add_co_u32_e32 v4, vcc, 0x1000, v32
	s_nop 1
	v_addc_co_u32_e32 v5, vcc, 0, v33, vcc
	global_store_dword v[4:5], v0, off offset:2048
	v_cndmask_b32_e64 v0, v19, v23, s[6:7]
	s_nop 1
	v_mov_b32_dpp v1, v0 quad_perm:[1,0,3,2] row_mask:0xf bank_mask:0xf bound_ctrl:1
	v_cndmask_b32_e64 v0, v19, v1, s[4:5]
	v_cndmask_b32_e64 v1, v1, v23, s[4:5]
	v_cvt_pk_bf16_f32 v0, v0, v1
	v_add_co_u32_e32 v4, vcc, 0x1000, v32
	s_nop 1
	v_addc_co_u32_e32 v5, vcc, 0, v33, vcc
	global_store_dword v[4:5], v0, off offset:2112
	v_cndmask_b32_e64 v0, v11, v15, s[6:7]
	s_nop 1
	v_mov_b32_dpp v1, v0 quad_perm:[1,0,3,2] row_mask:0xf bank_mask:0xf bound_ctrl:1
	v_cndmask_b32_e64 v0, v11, v1, s[4:5]
	v_cndmask_b32_e64 v1, v1, v15, s[4:5]
	v_cvt_pk_bf16_f32 v0, v0, v1
	v_add_co_u32_e32 v4, vcc, 0x1000, v32
	s_nop 1
	v_addc_co_u32_e32 v5, vcc, 0, v33, vcc
	global_store_dword v[4:5], v0, off offset:2176
	v_cndmask_b32_e64 v0, v3, v7, s[6:7]
	s_nop 1
	v_mov_b32_dpp v0, v0 quad_perm:[1,0,3,2] row_mask:0xf bank_mask:0xf bound_ctrl:1
	s_and_saveexec_b64 s[2:3], s[4:5]
	s_xor_b64 s[2:3], exec, s[2:3]
	s_cbranch_execz .LBB0_3134
	v_cvt_pk_bf16_f32 v4, v0, v7

; DEVFI int opaque_tid(const int wv) { return (wv << 6) | lane_opaque(); }
; #define SBAR() __builtin_amdgcn_sched_barrier(0)
; #define WAIT_V0() asm volatile("s_waitcnt vmcnt(0)" ::: "memory")
; #define GLDS_STAGE(buf, kt) gemm_stage(t, (buf), (kt), shm, wid, lane)
; DEVFI void gemm_stage(const TileSrc& t, const int buf, const int kt, char* shm, const int wid, const int lane) {
;   int R, C; stage_rc<G_KS>(wid * 1024 + lane * 16, R, C);
;   const int oa = R * t.lda + C, ob = R * t.ldb + C;
; #pragma unroll
;   for (int i = 0; i < G_GL; ++i) {
;     __builtin_amdgcn_global_load_lds((const unsigned*)(t.A + (i * 64 * t.lda + kt * G_BK) + oa), (unsigned*)(shm + buf * G_STAGE_B + wid * 1024 + i * 8192), 16, 0, 0);
;     __builtin_amdgcn_global_load_lds((const unsigned*)(t.B + (i * 64 * t.ldb + kt * G_BK) + ob), (unsigned*)(shm + buf * G_STAGE_B + G_TILE_B + wid * 1024 + i * 8192), 16, 0, 0); }
; template <class Epi>
; DEVFI void gemm_main(const TileSrc t, const int K, char* shm, const bool pf, const TileSrc nx, const int wv, Epi epi) {
;   const int tid = opaque_tid(wv), wid = tid >> 6, lane = tid & 63, wr = wid >> 1, wc = wid & 1, fr = lane & 15, fq = lane >> 4;
;     ...
;   f32x4 acc[4][8] = {};
;   const int nt = K / G_BK;
;   const int sw = (fr * 64 + fq * 16) ^ ((fr >> 3) << 5);
;   const char* aBase = shm + wr * 8192 + sw;
;   const char* bBase = shm + G_TILE_B + wc * 16384 + sw;
;   WAIT_V0(); __syncthreads();
;   for (int t_ = 0; t_ < nt; ++t_) { const int cur = t_ & 1;
;     if (t_ + 1 < nt) GLDS_STAGE(cur ^ 1, t_ + 1);
; #pragma unroll
;     for (int ks = 0; ks < G_KS; ++ks) {
;       bf16x8 At[4], Bf[8];
; #pragma unroll
;       for (int n = 0; n < 8; ++n) Bf[n] = *(const bf16x8*)(bBase + cur * G_STAGE_B + (n * 2048 + ks * 1024));
;       SBAR();
;       At[0] = *(const bf16x8*)(aBase + cur * G_STAGE_B + (0 * 2048 + ks * 1024)); SBAR();
.LBB0_3184:
	s_mov_b32 s19, -1
	s_ashr_i32 s21, s33, 7
	v_mbcnt_lo_u32_b32 v0, s19, 0
	v_mbcnt_hi_u32_b32 v135, s19, v0
	v_or_b32_e32 v0, s33, v135
	v_ashrrev_i32_e32 v137, 6, v0
	v_and_b32_e32 v134, 1, v137
	v_and_b32_e32 v132, 15, v135
	v_and_b32_e32 v0, 48, v135
	v_lshlrev_b32_e32 v1, 2, v135
	v_lshl_or_b32 v0, v132, 6, v0
	v_and_b32_e32 v1, 32, v1
	s_lshl_b32 s19, s21, 13
	v_lshlrev_b32_e32 v2, 14, v134
	v_bitop3_b32 v141, s19, v0, v1 bitop3:0xf6
	v_bitop3_b32 v142, v2, v0, v1 bitop3:0xf6
	v_lshlrev_b32_e32 v0, 4, v135
	v_and_b32_e32 v1, 32, v135
	v_lshrrev_b32_e32 v2, 31, v137
	v_add_u32_e32 v2, v137, v2
	v_bitop3_b32 v0, v0, v1, 48 bitop3:0x6c
	v_ashrrev_i32_e32 v138, 1, v2
	v_lshrrev_b32_e32 v139, 1, v0
	v_lshlrev_b32_e32 v0, 8, v135
	v_and_b32_e32 v140, 0x3c00, v0
	v_mul_lo_u32 v0, v138, s66
	v_or_b32_e32 v0, v139, v0
	v_lshlrev_b32_e32 v1, 5, v137
	v_add3_u32 v0, v0, v140, v1
	v_ashrrev_i32_e32 v1, 31, v0
	s_waitcnt vmcnt(0)
	v_lshlrev_b64 v[0:1], 1, v[0:1]
	v_lshl_add_u64 v[128:129], s[8:9], 0, v[0:1]
	v_lshl_add_u64 v[130:131], s[2:3], 0, v[0:1]
	v_mov_b32_e32 v0, 0
	v_mov_b32_e32 v252, 0x3a720000
	s_mov_b32 s18, 0
	v_and_b32_e32 v133, 63, v135
	v_lshlrev_b32_e32 v136, 10, v137
	s_mov_b64 s[8:9], 0
	v_mov_b32_e32 v1, v0
	v_mov_b32_e32 v2, v0
	v_mov_b32_e32 v3, v0
	v_mov_b32_e32 v4, v0
	v_mov_b32_e32 v5, v0
	v_mov_b32_e32 v6, v0
	v_mov_b32_e32 v7, v0
	v_mov_b32_e32 v8, v0
	v_mov_b32_e32 v9, v0
	v_mov_b32_e32 v10, v0
	v_mov_b32_e32 v11, v0
	v_mov_b32_e32 v12, v0
	v_mov_b32_e32 v13, v0
	v_mov_b32_e32 v14, v0
	v_mov_b32_e32 v15, v0
	v_mov_b32_e32 v16, v0
	v_mov_b32_e32 v17, v0
	v_mov_b32_e32 v18, v0
	v_mov_b32_e32 v19, v0
	v_mov_b32_e32 v20, v0
	v_mov_b32_e32 v21, v0
	v_mov_b32_e32 v22, v0
	v_mov_b32_e32 v23, v0
	v_mov_b32_e32 v24, v0
	v_mov_b32_e32 v25, v0
	v_mov_b32_e32 v26, v0
	v_mov_b32_e32 v27, v0
	v_mov_b32_e32 v28, v0
	v_mov_b32_e32 v29, v0
	v_mov_b32_e32 v30, v0
	v_mov_b32_e32 v31, v0
	v_mov_b32_e32 v32, v0
	v_mov_b32_e32 v33, v0
	v_mov_b32_e32 v34, v0
	v_mov_b32_e32 v35, v0
	v_mov_b32_e32 v36, v0
	v_mov_b32_e32 v37, v0
	v_mov_b32_e32 v38, v0
	v_mov_b32_e32 v39, v0
	v_mov_b32_e32 v40, v0
	v_mov_b32_e32 v41, v0
	v_mov_b32_e32 v42, v0
	v_mov_b32_e32 v43, v0
	v_mov_b32_e32 v44, v0
	v_mov_b32_e32 v45, v0
	v_mov_b32_e32 v46, v0
	v_mov_b32_e32 v47, v0
	v_mov_b32_e32 v48, v0
	v_mov_b32_e32 v49, v0
	v_mov_b32_e32 v50, v0
	v_mov_b32_e32 v51, v0
	v_mov_b32_e32 v52, v0
	v_mov_b32_e32 v53, v0
	v_mov_b32_e32 v54, v0
	v_mov_b32_e32 v55, v0
	v_mov_b32_e32 v56, v0
	v_mov_b32_e32 v57, v0
	v_mov_b32_e32 v58, v0
	v_mov_b32_e32 v59, v0
	v_mov_b32_e32 v60, v0
	v_mov_b32_e32 v61, v0
	v_mov_b32_e32 v62, v0
	v_mov_b32_e32 v63, v0
	v_mov_b32_e32 v64, v0
	v_mov_b32_e32 v65, v0
	v_mov_b32_e32 v66, v0
	v_mov_b32_e32 v67, v0
	v_mov_b32_e32 v68, v0
	v_mov_b32_e32 v69, v0
	v_mov_b32_e32 v70, v0
	v_mov_b32_e32 v71, v0
	v_mov_b32_e32 v72, v0
	v_mov_b32_e32 v73, v0
	v_mov_b32_e32 v74, v0
	v_mov_b32_e32 v75, v0
	v_mov_b32_e32 v76, v0
	v_mov_b32_e32 v77, v0
	v_mov_b32_e32 v78, v0
	v_mov_b32_e32 v79, v0
	v_mov_b32_e32 v80, v0
	v_mov_b32_e32 v81, v0
	v_mov_b32_e32 v82, v0
	v_mov_b32_e32 v83, v0
	v_mov_b32_e32 v84, v0
	v_mov_b32_e32 v85, v0
	v_mov_b32_e32 v86, v0
	v_mov_b32_e32 v87, v0
	v_mov_b32_e32 v88, v0
	v_mov_b32_e32 v89, v0
	v_mov_b32_e32 v90, v0
	v_mov_b32_e32 v91, v0
	v_mov_b32_e32 v92, v0
	v_mov_b32_e32 v93, v0
	v_mov_b32_e32 v94, v0
	v_mov_b32_e32 v95, v0
	v_mov_b32_e32 v96, v0
	v_mov_b32_e32 v97, v0
	v_mov_b32_e32 v98, v0
	v_mov_b32_e32 v99, v0
	v_mov_b32_e32 v100, v0
	v_mov_b32_e32 v101, v0
	v_mov_b32_e32 v102, v0
	v_mov_b32_e32 v103, v0
	v_mov_b32_e32 v104, v0
	v_mov_b32_e32 v105, v0
	v_mov_b32_e32 v106, v0
	v_mov_b32_e32 v107, v0
	v_mov_b32_e32 v108, v0
	v_mov_b32_e32 v109, v0
	v_mov_b32_e32 v110, v0
	v_mov_b32_e32 v111, v0
	v_mov_b32_e32 v112, v0
	v_mov_b32_e32 v113, v0
	v_mov_b32_e32 v114, v0
	v_mov_b32_e32 v115, v0
	v_mov_b32_e32 v116, v0
	v_mov_b32_e32 v117, v0
	v_mov_b32_e32 v118, v0
	v_mov_b32_e32 v119, v0
	v_mov_b32_e32 v120, v0
	v_mov_b32_e32 v121, v0
	v_mov_b32_e32 v122, v0
	v_mov_b32_e32 v123, v0
	v_mov_b32_e32 v124, v0
	v_mov_b32_e32 v125, v0
	v_mov_b32_e32 v126, v0
	v_mov_b32_e32 v127, v0
	s_waitcnt lgkmcnt(0)
	s_lshr_b32 s2, s33, 6
	s_lshr_b32 s3, s2, 1
	s_sub_u32 s3, s2, s3
	s_mov_b32 s8, 0x20000
	s_lshr_b32 s9, s8, 2
	s_mul_i32 s3, s3, s9
	s_and_b32 s9, s2, 1
	s_lshl_b32 s9, s9, 6
	s_sub_u32 s3, s3, s9
	s_add_u32 s3, s3, 0x80
	s_lshl_b32 s18, s8, 1
	s_lshl_b32 s2, s2, 11
	s_mov_b32 vcc_hi, 0
	s_mov_b32 vcc_lo, s3
	v_lshl_add_u64 v[130:131], v[130:131], 0, vcc
	v_lshl_add_u64 v[128:129], v[128:129], 0, vcc
	s_mov_b32 vcc_lo, s18
	v_lshl_add_u64 v[214:215], v[130:131], 0, vcc
	v_lshl_add_u64 v[228:229], v[128:129], 0, vcc
	v_add_u32_e32 v143, 0x10000, v141
	v_add_u32_e32 v176, 0x10000, v142
	s_nop 0
	v_readfirstlane_b32 s8, v130
	v_readfirstlane_b32 s9, v131
	v_readfirstlane_b32 vcc_lo, v128
	v_readfirstlane_b32 vcc_hi, v129
	s_nop 1
	v_subrev_u32_e32 v130, s8, v130
	v_subrev_u32_e32 v128, vcc_lo, v128
	v_add_u32_e32 v214, s18, v130
	v_add_u32_e32 v228, s18, v128
	s_nop 4
	s_add_u32 m0, s2, 0x10000
	s_nop 0
	global_load_lds_dwordx4 v130, s[8:9]
	s_add_u32 m0, s2, 0x14000
	s_nop 0
	global_load_lds_dwordx4 v214, s[8:9]
	s_add_u32 s8, s8, 64
	s_addc_u32 s9, s9, 0
	s_add_u32 m0, s2, 0x18000
	s_nop 0
	global_load_lds_dwordx4 v128, vcc
	s_add_u32 m0, s2, 0x1c000
	s_nop 0
	global_load_lds_dwordx4 v228, vcc
	s_add_u32 vcc_lo, vcc_lo, 64
	s_addc_u32 vcc_hi, vcc_hi, 0
	s_add_u32 m0, s2, 0x10400
	s_nop 0
	global_load_lds_dwordx4 v130, s[8:9]
	s_add_u32 m0, s2, 0x14400
	s_nop 0
	global_load_lds_dwordx4 v214, s[8:9]
	s_add_u32 s8, s8, 64
	s_addc_u32 s9, s9, 0
	s_add_u32 m0, s2, 0x18400
	s_nop 0
	global_load_lds_dwordx4 v128, vcc
	s_add_u32 m0, s2, 0x1c400
	s_nop 0
	global_load_lds_dwordx4 v228, vcc
	s_add_u32 vcc_lo, vcc_lo, 64
	s_addc_u32 vcc_hi, vcc_hi, 0
	s_waitcnt vmcnt(8)
	s_barrier
	ds_read_b128 v[144:147], v141
	ds_read_b128 v[148:151], v141 offset:2048
	ds_read_b128 v[152:155], v141 offset:4096
	ds_read_b128 v[156:159], v141 offset:6144
	ds_read_b128 v[178:181], v142 offset:32768
	ds_read_b128 v[184:187], v142 offset:34816
	ds_read_b128 v[188:191], v142 offset:36864
	ds_read_b128 v[192:195], v142 offset:38912
	ds_read_b128 v[196:199], v142 offset:40960
	ds_read_b128 v[200:203], v142 offset:43008
	ds_read_b128 v[204:207], v142 offset:45056
	ds_read_b128 v[218:221], v142 offset:47104
	s_mov_b32 s3, 7
; #define SBAR() __builtin_amdgcn_sched_barrier(0)
; #define WAIT_V0() asm volatile("s_waitcnt vmcnt(0)" ::: "memory")
; #define GLDS_STAGE(buf, kt) gemm_stage(t, (buf), (kt), shm, wid, lane)
; DEVFI void gemm_stage(const TileSrc& t, const int buf, const int kt, char* shm, const int wid, const int lane) {
;   int R, C; stage_rc<G_KS>(wid * 1024 + lane * 16, R, C);
;   const int oa = R * t.lda + C, ob = R * t.ldb + C;
; #pragma unroll
;   for (int i = 0; i < G_GL; ++i) {
;     __builtin_amdgcn_global_load_lds((const unsigned*)(t.A + (i * 64 * t.lda + kt * G_BK) + oa), (unsigned*)(shm + buf * G_STAGE_B + wid * 1024 + i * 8192), 16, 0, 0);
;     __builtin_amdgcn_global_load_lds((const unsigned*)(t.B + (i * 64 * t.ldb + kt * G_BK) + ob), (unsigned*)(shm + buf * G_STAGE_B + G_TILE_B + wid * 1024 + i * 8192), 16, 0, 0); }
; }
; template <class Epi>
; DEVFI void gemm_main(const TileSrc t, const int K, char* shm, const bool pf, const TileSrc nx, const int wv, Epi epi) {
;     ...
;   for (int t_ = 0; t_ < nt; ++t_) { const int cur = t_ & 1;
;     if (t_ + 1 < nt) GLDS_STAGE(cur ^ 1, t_ + 1);
; #pragma unroll
;     for (int ks = 0; ks < G_KS; ++ks) {
;       bf16x8 At[4], Bf[8];
; #pragma unroll
;       for (int n = 0; n < 8; ++n) Bf[n] = *(const bf16x8*)(bBase + cur * G_STAGE_B + (n * 2048 + ks * 1024));
;       SBAR();
;       At[0] = *(const bf16x8*)(aBase + cur * G_STAGE_B + (0 * 2048 + ks * 1024)); SBAR();
;       At[1] = *(const bf16x8*)(aBase + cur * G_STAGE_B + (1 * 2048 + ks * 1024)); SBAR();
;       At[2] = *(const bf16x8*)(aBase + cur * G_STAGE_B + (2 * 2048 + ks * 1024)); SBAR();
;       At[3] = *(const bf16x8*)(aBase + cur * G_STAGE_B + (3 * 2048 + ks * 1024));
;       SBAR();
;       __builtin_amdgcn_s_setprio(1);
; #pragma unroll
;       for (int m = 0; m < 4; ++m)
; #pragma unroll
;         for (int n = 0; n < 8; ++n) acc[m][n] = __builtin_amdgcn_mfma_f32_16x16x32_bf16(At[m], Bf[n], acc[m][n], 0, 0, 0);
;       __builtin_amdgcn_s_setprio(0);
;       SBAR();
;     }
;     WAIT_V0(); __syncthreads();
;   }
.LgkH_loop:
	s_waitcnt lgkmcnt(0)
	s_waitcnt vmcnt(8)
	s_barrier
	v_mfma_f32_16x16x32_bf16 v[120:123], v[144:147], v[178:181], v[120:123]
	ds_read_b128 v[160:163], v141 offset:1024
	s_add_u32 m0, s2, 0x0
	v_mfma_f32_16x16x32_bf16 v[88:91], v[148:151], v[178:181], v[88:91]
	ds_read_b128 v[164:167], v141 offset:3072
	v_mfma_f32_16x16x32_bf16 v[56:59], v[152:155], v[178:181], v[56:59]
	ds_read_b128 v[168:171], v141 offset:5120
	global_load_lds_dwordx4 v130, s[8:9]
	v_mfma_f32_16x16x32_bf16 v[24:27], v[156:159], v[178:181], v[24:27]
	ds_read_b128 v[172:175], v141 offset:7168
	v_mfma_f32_16x16x32_bf16 v[124:127], v[144:147], v[184:187], v[124:127]
	ds_read_b128 v[208:211], v142 offset:46080
	v_mfma_f32_16x16x32_bf16 v[92:95], v[148:151], v[184:187], v[92:95]
	ds_read_b128 v[224:227], v142 offset:48128
	v_mfma_f32_16x16x32_bf16 v[60:63], v[152:155], v[184:187], v[60:63]
	ds_read_b128 v[178:181], v142 offset:33792
	v_mfma_f32_16x16x32_bf16 v[28:31], v[156:159], v[184:187], v[28:31]
	ds_read_b128 v[184:187], v142 offset:35840
	v_mfma_f32_16x16x32_bf16 v[112:115], v[144:147], v[188:191], v[112:115]
	s_add_u32 m0, s2, 0x4000
	v_mfma_f32_16x16x32_bf16 v[80:83], v[148:151], v[188:191], v[80:83]
	v_mfma_f32_16x16x32_bf16 v[48:51], v[152:155], v[188:191], v[48:51]
	global_load_lds_dwordx4 v214, s[8:9]
	v_mfma_f32_16x16x32_bf16 v[16:19], v[156:159], v[188:191], v[16:19]
	ds_read_b128 v[188:191], v142 offset:37888
	s_add_u32 s8, s8, 64
	s_addc_u32 s9, s9, 0
	v_mfma_f32_16x16x32_bf16 v[116:119], v[144:147], v[192:195], v[116:119]
	v_mfma_f32_16x16x32_bf16 v[84:87], v[148:151], v[192:195], v[84:87]
	v_mfma_f32_16x16x32_bf16 v[52:55], v[152:155], v[192:195], v[52:55]
	v_mfma_f32_16x16x32_bf16 v[20:23], v[156:159], v[192:195], v[20:23]
	ds_read_b128 v[192:195], v142 offset:39936
	v_mfma_f32_16x16x32_bf16 v[104:107], v[144:147], v[196:199], v[104:107]
	s_add_u32 m0, s2, 0x8000
	v_mfma_f32_16x16x32_bf16 v[72:75], v[148:151], v[196:199], v[72:75]
	v_mfma_f32_16x16x32_bf16 v[40:43], v[152:155], v[196:199], v[40:43]
	global_load_lds_dwordx4 v128, vcc
	v_mfma_f32_16x16x32_bf16 v[8:11], v[156:159], v[196:199], v[8:11]
	ds_read_b128 v[196:199], v142 offset:41984
	v_mfma_f32_16x16x32_bf16 v[108:111], v[144:147], v[200:203], v[108:111]
	v_mfma_f32_16x16x32_bf16 v[76:79], v[148:151], v[200:203], v[76:79]
	v_mfma_f32_16x16x32_bf16 v[44:47], v[152:155], v[200:203], v[44:47]
	v_mfma_f32_16x16x32_bf16 v[12:15], v[156:159], v[200:203], v[12:15]
	ds_read_b128 v[200:203], v142 offset:44032
	v_mfma_f32_16x16x32_bf16 v[96:99], v[144:147], v[204:207], v[96:99]
	s_add_u32 m0, s2, 0xc000
	v_mfma_f32_16x16x32_bf16 v[64:67], v[148:151], v[204:207], v[64:67]
	v_mfma_f32_16x16x32_bf16 v[32:35], v[152:155], v[204:207], v[32:35]
	global_load_lds_dwordx4 v228, vcc
	v_mfma_f32_16x16x32_bf16 v[0:3], v[156:159], v[204:207], v[0:3]
	s_add_u32 vcc_lo, vcc_lo, 64
	s_addc_u32 vcc_hi, vcc_hi, 0
	v_mfma_f32_16x16x32_bf16 v[100:103], v[144:147], v[218:221], v[100:103]
	v_mfma_f32_16x16x32_bf16 v[68:71], v[148:151], v[218:221], v[68:71]
	v_mfma_f32_16x16x32_bf16 v[36:39], v[152:155], v[218:221], v[36:39]
	v_mfma_f32_16x16x32_bf16 v[4:7], v[156:159], v[218:221], v[4:7]
	s_waitcnt lgkmcnt(0)
	s_waitcnt vmcnt(8)
	s_barrier
	v_mfma_f32_16x16x32_bf16 v[120:123], v[160:163], v[178:181], v[120:123]
	ds_read_b128 v[144:147], v143
	s_add_u32 m0, s2, 0x400
	v_mfma_f32_16x16x32_bf16 v[88:91], v[164:167], v[178:181], v[88:91]
	ds_read_b128 v[148:151], v143 offset:2048
	v_mfma_f32_16x16x32_bf16 v[56:59], v[168:171], v[178:181], v[56:59]
	ds_read_b128 v[152:155], v143 offset:4096
	global_load_lds_dwordx4 v130, s[8:9]
	v_mfma_f32_16x16x32_bf16 v[24:27], v[172:175], v[178:181], v[24:27]
	ds_read_b128 v[156:159], v143 offset:6144
	v_mfma_f32_16x16x32_bf16 v[124:127], v[160:163], v[184:187], v[124:127]
	ds_read_b128 v[204:207], v176 offset:45056
	v_mfma_f32_16x16x32_bf16 v[92:95], v[164:167], v[184:187], v[92:95]
	ds_read_b128 v[218:221], v176 offset:47104
	v_mfma_f32_16x16x32_bf16 v[60:63], v[168:171], v[184:187], v[60:63]
	ds_read_b128 v[178:181], v176 offset:32768
	v_mfma_f32_16x16x32_bf16 v[28:31], v[172:175], v[184:187], v[28:31]
	ds_read_b128 v[184:187], v176 offset:34816
	v_mfma_f32_16x16x32_bf16 v[112:115], v[160:163], v[188:191], v[112:115]
	s_add_u32 m0, s2, 0x4400
	v_mfma_f32_16x16x32_bf16 v[80:83], v[164:167], v[188:191], v[80:83]
	v_mfma_f32_16x16x32_bf16 v[48:51], v[168:171], v[188:191], v[48:51]
	global_load_lds_dwordx4 v214, s[8:9]
	v_mfma_f32_16x16x32_bf16 v[16:19], v[172:175], v[188:191], v[16:19]
	ds_read_b128 v[188:191], v176 offset:36864
	s_add_u32 s8, s8, 64
	s_addc_u32 s9, s9, 0
	v_mfma_f32_16x16x32_bf16 v[116:119], v[160:163], v[192:195], v[116:119]
	v_mfma_f32_16x16x32_bf16 v[84:87], v[164:167], v[192:195], v[84:87]
	v_mfma_f32_16x16x32_bf16 v[52:55], v[168:171], v[192:195], v[52:55]
	v_mfma_f32_16x16x32_bf16 v[20:23], v[172:175], v[192:195], v[20:23]
	ds_read_b128 v[192:195], v176 offset:38912
	v_mfma_f32_16x16x32_bf16 v[104:107], v[160:163], v[196:199], v[104:107]
	s_add_u32 m0, s2, 0x8400
	v_mfma_f32_16x16x32_bf16 v[72:75], v[164:167], v[196:199], v[72:75]
	v_mfma_f32_16x16x32_bf16 v[40:43], v[168:171], v[196:199], v[40:43]
	global_load_lds_dwordx4 v128, vcc
	v_mfma_f32_16x16x32_bf16 v[8:11], v[172:175], v[196:199], v[8:11]
	ds_read_b128 v[196:199], v176 offset:40960
	v_mfma_f32_16x16x32_bf16 v[108:111], v[160:163], v[200:203], v[108:111]
	v_mfma_f32_16x16x32_bf16 v[76:79], v[164:167], v[200:203], v[76:79]
	v_mfma_f32_16x16x32_bf16 v[44:47], v[168:171], v[200:203], v[44:47]
	v_mfma_f32_16x16x32_bf16 v[12:15], v[172:175], v[200:203], v[12:15]
	ds_read_b128 v[200:203], v176 offset:43008
	v_mfma_f32_16x16x32_bf16 v[96:99], v[160:163], v[208:211], v[96:99]
	s_add_u32 m0, s2, 0xc400
	v_mfma_f32_16x16x32_bf16 v[64:67], v[164:167], v[208:211], v[64:67]
	v_mfma_f32_16x16x32_bf16 v[32:35], v[168:171], v[208:211], v[32:35]
	global_load_lds_dwordx4 v228, vcc
	v_mfma_f32_16x16x32_bf16 v[0:3], v[172:175], v[208:211], v[0:3]
	s_add_u32 vcc_lo, vcc_lo, 64
	s_addc_u32 vcc_hi, vcc_hi, 0
	v_mfma_f32_16x16x32_bf16 v[100:103], v[160:163], v[224:227], v[100:103]
	v_mfma_f32_16x16x32_bf16 v[68:71], v[164:167], v[224:227], v[68:71]
	v_mfma_f32_16x16x32_bf16 v[36:39], v[168:171], v[224:227], v[36:39]
	v_mfma_f32_16x16x32_bf16 v[4:7], v[172:175], v[224:227], v[4:7]
	s_waitcnt lgkmcnt(0)
	s_waitcnt vmcnt(8)
	s_barrier
; #define SBAR() __builtin_amdgcn_sched_barrier(0)
; #define WAIT_V0() asm volatile("s_waitcnt vmcnt(0)" ::: "memory")
; #define GLDS_STAGE(buf, kt) gemm_stage(t, (buf), (kt), shm, wid, lane)
; DEVFI void gemm_stage(const TileSrc& t, const int buf, const int kt, char* shm, const int wid, const int lane) {
;   int R, C; stage_rc<G_KS>(wid * 1024 + lane * 16, R, C);
;   const int oa = R * t.lda + C, ob = R * t.ldb + C;
; #pragma unroll
;   for (int i = 0; i < G_GL; ++i) {
;     __builtin_amdgcn_global_load_lds((const unsigned*)(t.A + (i * 64 * t.lda + kt * G_BK) + oa), (unsigned*)(shm + buf * G_STAGE_B + wid * 1024 + i * 8192), 16, 0, 0);
;     __builtin_amdgcn_global_load_lds((const unsigned*)(t.B + (i * 64 * t.ldb + kt * G_BK) + ob), (unsigned*)(shm + buf * G_STAGE_B + G_TILE_B + wid * 1024 + i * 8192), 16, 0, 0); }
; }
; template <class Epi>
; DEVFI void gemm_main(const TileSrc t, const int K, char* shm, const bool pf, const TileSrc nx, const int wv, Epi epi) {
;     ...
;   for (int t_ = 0; t_ < nt; ++t_) { const int cur = t_ & 1;
;     if (t_ + 1 < nt) GLDS_STAGE(cur ^ 1, t_ + 1);
; #pragma unroll
;     for (int ks = 0; ks < G_KS; ++ks) {
;       bf16x8 At[4], Bf[8];
; #pragma unroll
;       for (int n = 0; n < 8; ++n) Bf[n] = *(const bf16x8*)(bBase + cur * G_STAGE_B + (n * 2048 + ks * 1024));
;       SBAR();
;       At[0] = *(const bf16x8*)(aBase + cur * G_STAGE_B + (0 * 2048 + ks * 1024)); SBAR();
;       At[1] = *(const bf16x8*)(aBase + cur * G_STAGE_B + (1 * 2048 + ks * 1024)); SBAR();
;       At[2] = *(const bf16x8*)(aBase + cur * G_STAGE_B + (2 * 2048 + ks * 1024)); SBAR();
;       At[3] = *(const bf16x8*)(aBase + cur * G_STAGE_B + (3 * 2048 + ks * 1024));
;       SBAR();
;       __builtin_amdgcn_s_setprio(1);
; #pragma unroll
;       for (int m = 0; m < 4; ++m)
; #pragma unroll
;         for (int n = 0; n < 8; ++n) acc[m][n] = __builtin_amdgcn_mfma_f32_16x16x32_bf16(At[m], Bf[n], acc[m][n], 0, 0, 0);
;       __builtin_amdgcn_s_setprio(0);
;       SBAR();
;     }
;     WAIT_V0(); __syncthreads();
;   }
	v_mfma_f32_16x16x32_bf16 v[120:123], v[144:147], v[178:181], v[120:123]
	ds_read_b128 v[160:163], v143 offset:1024
	s_add_u32 m0, s2, 0x10000
	v_mfma_f32_16x16x32_bf16 v[88:91], v[148:151], v[178:181], v[88:91]
	ds_read_b128 v[164:167], v143 offset:3072
	v_mfma_f32_16x16x32_bf16 v[56:59], v[152:155], v[178:181], v[56:59]
	ds_read_b128 v[168:171], v143 offset:5120
	global_load_lds_dwordx4 v130, s[8:9]
	v_mfma_f32_16x16x32_bf16 v[24:27], v[156:159], v[178:181], v[24:27]
	ds_read_b128 v[172:175], v143 offset:7168
	v_mfma_f32_16x16x32_bf16 v[124:127], v[144:147], v[184:187], v[124:127]
	ds_read_b128 v[208:211], v176 offset:46080
	v_mfma_f32_16x16x32_bf16 v[92:95], v[148:151], v[184:187], v[92:95]
	ds_read_b128 v[224:227], v176 offset:48128
	v_mfma_f32_16x16x32_bf16 v[60:63], v[152:155], v[184:187], v[60:63]
	ds_read_b128 v[178:181], v176 offset:33792
	v_mfma_f32_16x16x32_bf16 v[28:31], v[156:159], v[184:187], v[28:31]
	ds_read_b128 v[184:187], v176 offset:35840
	v_mfma_f32_16x16x32_bf16 v[112:115], v[144:147], v[188:191], v[112:115]
	s_add_u32 m0, s2, 0x14000
	v_mfma_f32_16x16x32_bf16 v[80:83], v[148:151], v[188:191], v[80:83]
	v_mfma_f32_16x16x32_bf16 v[48:51], v[152:155], v[188:191], v[48:51]
	global_load_lds_dwordx4 v214, s[8:9]
	v_mfma_f32_16x16x32_bf16 v[16:19], v[156:159], v[188:191], v[16:19]
	ds_read_b128 v[188:191], v176 offset:37888
	s_add_u32 s8, s8, 64
	s_addc_u32 s9, s9, 0
	v_mfma_f32_16x16x32_bf16 v[116:119], v[144:147], v[192:195], v[116:119]
	v_mfma_f32_16x16x32_bf16 v[84:87], v[148:151], v[192:195], v[84:87]
	v_mfma_f32_16x16x32_bf16 v[52:55], v[152:155], v[192:195], v[52:55]
	v_mfma_f32_16x16x32_bf16 v[20:23], v[156:159], v[192:195], v[20:23]
	ds_read_b128 v[192:195], v176 offset:39936
	v_mfma_f32_16x16x32_bf16 v[104:107], v[144:147], v[196:199], v[104:107]
	s_add_u32 m0, s2, 0x18000
	v_mfma_f32_16x16x32_bf16 v[72:75], v[148:151], v[196:199], v[72:75]
	v_mfma_f32_16x16x32_bf16 v[40:43], v[152:155], v[196:199], v[40:43]
	global_load_lds_dwordx4 v128, vcc
	v_mfma_f32_16x16x32_bf16 v[8:11], v[156:159], v[196:199], v[8:11]
	ds_read_b128 v[196:199], v176 offset:41984
	v_mfma_f32_16x16x32_bf16 v[108:111], v[144:147], v[200:203], v[108:111]
	v_mfma_f32_16x16x32_bf16 v[76:79], v[148:151], v[200:203], v[76:79]
	v_mfma_f32_16x16x32_bf16 v[44:47], v[152:155], v[200:203], v[44:47]
	v_mfma_f32_16x16x32_bf16 v[12:15], v[156:159], v[200:203], v[12:15]
	ds_read_b128 v[200:203], v176 offset:44032
	v_mfma_f32_16x16x32_bf16 v[96:99], v[144:147], v[204:207], v[96:99]
	s_add_u32 m0, s2, 0x1c000
	v_mfma_f32_16x16x32_bf16 v[64:67], v[148:151], v[204:207], v[64:67]
	v_mfma_f32_16x16x32_bf16 v[32:35], v[152:155], v[204:207], v[32:35]
	global_load_lds_dwordx4 v228, vcc
	v_mfma_f32_16x16x32_bf16 v[0:3], v[156:159], v[204:207], v[0:3]
	s_add_u32 vcc_lo, vcc_lo, 64
	s_addc_u32 vcc_hi, vcc_hi, 0
	v_mfma_f32_16x16x32_bf16 v[100:103], v[144:147], v[218:221], v[100:103]
	v_mfma_f32_16x16x32_bf16 v[68:71], v[148:151], v[218:221], v[68:71]
	v_mfma_f32_16x16x32_bf16 v[36:39], v[152:155], v[218:221], v[36:39]
	v_mfma_f32_16x16x32_bf16 v[4:7], v[156:159], v[218:221], v[4:7]
	s_waitcnt lgkmcnt(0)
	s_waitcnt vmcnt(8)
	s_barrier
	v_mfma_f32_16x16x32_bf16 v[120:123], v[160:163], v[178:181], v[120:123]
	ds_read_b128 v[144:147], v141
	s_add_u32 m0, s2, 0x10400
	v_mfma_f32_16x16x32_bf16 v[88:91], v[164:167], v[178:181], v[88:91]
	ds_read_b128 v[148:151], v141 offset:2048
	v_mfma_f32_16x16x32_bf16 v[56:59], v[168:171], v[178:181], v[56:59]
	ds_read_b128 v[152:155], v141 offset:4096
	global_load_lds_dwordx4 v130, s[8:9]
	v_mfma_f32_16x16x32_bf16 v[24:27], v[172:175], v[178:181], v[24:27]
	ds_read_b128 v[156:159], v141 offset:6144
	v_mfma_f32_16x16x32_bf16 v[124:127], v[160:163], v[184:187], v[124:127]
	ds_read_b128 v[204:207], v142 offset:45056
	v_mfma_f32_16x16x32_bf16 v[92:95], v[164:167], v[184:187], v[92:95]
	ds_read_b128 v[218:221], v142 offset:47104
	v_mfma_f32_16x16x32_bf16 v[60:63], v[168:171], v[184:187], v[60:63]
	ds_read_b128 v[178:181], v142 offset:32768
	v_mfma_f32_16x16x32_bf16 v[28:31], v[172:175], v[184:187], v[28:31]
	ds_read_b128 v[184:187], v142 offset:34816
	v_mfma_f32_16x16x32_bf16 v[112:115], v[160:163], v[188:191], v[112:115]
	s_add_u32 m0, s2, 0x14400
	v_mfma_f32_16x16x32_bf16 v[80:83], v[164:167], v[188:191], v[80:83]
	v_mfma_f32_16x16x32_bf16 v[48:51], v[168:171], v[188:191], v[48:51]
	global_load_lds_dwordx4 v214, s[8:9]
	v_mfma_f32_16x16x32_bf16 v[16:19], v[172:175], v[188:191], v[16:19]
	ds_read_b128 v[188:191], v142 offset:36864
	s_add_u32 s8, s8, 64
	s_addc_u32 s9, s9, 0
	v_mfma_f32_16x16x32_bf16 v[116:119], v[160:163], v[192:195], v[116:119]
	v_mfma_f32_16x16x32_bf16 v[84:87], v[164:167], v[192:195], v[84:87]
	v_mfma_f32_16x16x32_bf16 v[52:55], v[168:171], v[192:195], v[52:55]
	v_mfma_f32_16x16x32_bf16 v[20:23], v[172:175], v[192:195], v[20:23]
	ds_read_b128 v[192:195], v142 offset:38912
	v_mfma_f32_16x16x32_bf16 v[104:107], v[160:163], v[196:199], v[104:107]
	s_add_u32 m0, s2, 0x18400
	v_mfma_f32_16x16x32_bf16 v[72:75], v[164:167], v[196:199], v[72:75]
	v_mfma_f32_16x16x32_bf16 v[40:43], v[168:171], v[196:199], v[40:43]
	global_load_lds_dwordx4 v128, vcc
	v_mfma_f32_16x16x32_bf16 v[8:11], v[172:175], v[196:199], v[8:11]
	ds_read_b128 v[196:199], v142 offset:40960
	v_mfma_f32_16x16x32_bf16 v[108:111], v[160:163], v[200:203], v[108:111]
	v_mfma_f32_16x16x32_bf16 v[76:79], v[164:167], v[200:203], v[76:79]
	v_mfma_f32_16x16x32_bf16 v[44:47], v[168:171], v[200:203], v[44:47]
	v_mfma_f32_16x16x32_bf16 v[12:15], v[172:175], v[200:203], v[12:15]
	ds_read_b128 v[200:203], v142 offset:43008
	v_mfma_f32_16x16x32_bf16 v[96:99], v[160:163], v[208:211], v[96:99]
	s_add_u32 m0, s2, 0x1c400
	v_mfma_f32_16x16x32_bf16 v[64:67], v[164:167], v[208:211], v[64:67]
	v_mfma_f32_16x16x32_bf16 v[32:35], v[168:171], v[208:211], v[32:35]
	global_load_lds_dwordx4 v228, vcc
	v_mfma_f32_16x16x32_bf16 v[0:3], v[172:175], v[208:211], v[0:3]
	s_add_u32 vcc_lo, vcc_lo, 64
	s_addc_u32 vcc_hi, vcc_hi, 0
	v_mfma_f32_16x16x32_bf16 v[100:103], v[160:163], v[224:227], v[100:103]
	v_mfma_f32_16x16x32_bf16 v[68:71], v[164:167], v[224:227], v[68:71]
	v_mfma_f32_16x16x32_bf16 v[36:39], v[168:171], v[224:227], v[36:39]
	v_mfma_f32_16x16x32_bf16 v[4:7], v[172:175], v[224:227], v[4:7]
	s_sub_u32 s3, s3, 1
	s_cmp_lg_u32 s3, 0
	s_cbranch_scc1 .LgkH_loop
; #define SBAR() __builtin_amdgcn_sched_barrier(0)
; #define WAIT_V0() asm volatile("s_waitcnt vmcnt(0)" ::: "memory")
; template <class Epi>
; DEVFI void gemm_main(const TileSrc t, const int K, char* shm, const bool pf, const TileSrc nx, const int wv, Epi epi) {
;     ...
; #pragma unroll
;     for (int ks = 0; ks < G_KS; ++ks) {
;       bf16x8 At[4], Bf[8];
; #pragma unroll
;       for (int n = 0; n < 8; ++n) Bf[n] = *(const bf16x8*)(bBase + cur * G_STAGE_B + (n * 2048 + ks * 1024));
;       SBAR();
;       At[0] = *(const bf16x8*)(aBase + cur * G_STAGE_B + (0 * 2048 + ks * 1024)); SBAR();
;       At[1] = *(const bf16x8*)(aBase + cur * G_STAGE_B + (1 * 2048 + ks * 1024)); SBAR();
;       At[2] = *(const bf16x8*)(aBase + cur * G_STAGE_B + (2 * 2048 + ks * 1024)); SBAR();
;       At[3] = *(const bf16x8*)(aBase + cur * G_STAGE_B + (3 * 2048 + ks * 1024));
;       SBAR();
;       __builtin_amdgcn_s_setprio(1);
; #pragma unroll
;       for (int m = 0; m < 4; ++m)
; #pragma unroll
;         for (int n = 0; n < 8; ++n) acc[m][n] = __builtin_amdgcn_mfma_f32_16x16x32_bf16(At[m], Bf[n], acc[m][n], 0, 0, 0);
;       __builtin_amdgcn_s_setprio(0);
;       SBAR();
;     }
;     WAIT_V0(); __syncthreads();
	s_waitcnt lgkmcnt(0)
	s_waitcnt vmcnt(8)
	s_barrier
	v_mfma_f32_16x16x32_bf16 v[120:123], v[144:147], v[178:181], v[120:123]
	ds_read_b128 v[160:163], v141 offset:1024
	v_mfma_f32_16x16x32_bf16 v[88:91], v[148:151], v[178:181], v[88:91]
	ds_read_b128 v[164:167], v141 offset:3072
	v_mfma_f32_16x16x32_bf16 v[56:59], v[152:155], v[178:181], v[56:59]
	ds_read_b128 v[168:171], v141 offset:5120
	v_mfma_f32_16x16x32_bf16 v[24:27], v[156:159], v[178:181], v[24:27]
	ds_read_b128 v[172:175], v141 offset:7168
	v_mfma_f32_16x16x32_bf16 v[124:127], v[144:147], v[184:187], v[124:127]
	ds_read_b128 v[208:211], v142 offset:46080
	v_mfma_f32_16x16x32_bf16 v[92:95], v[148:151], v[184:187], v[92:95]
	ds_read_b128 v[224:227], v142 offset:48128
	v_mfma_f32_16x16x32_bf16 v[60:63], v[152:155], v[184:187], v[60:63]
	ds_read_b128 v[178:181], v142 offset:33792
	v_mfma_f32_16x16x32_bf16 v[28:31], v[156:159], v[184:187], v[28:31]
	ds_read_b128 v[184:187], v142 offset:35840
	v_mfma_f32_16x16x32_bf16 v[112:115], v[144:147], v[188:191], v[112:115]
	v_mfma_f32_16x16x32_bf16 v[80:83], v[148:151], v[188:191], v[80:83]
	v_mfma_f32_16x16x32_bf16 v[48:51], v[152:155], v[188:191], v[48:51]
	v_mfma_f32_16x16x32_bf16 v[16:19], v[156:159], v[188:191], v[16:19]
	ds_read_b128 v[188:191], v142 offset:37888
	v_mfma_f32_16x16x32_bf16 v[116:119], v[144:147], v[192:195], v[116:119]
	v_mfma_f32_16x16x32_bf16 v[84:87], v[148:151], v[192:195], v[84:87]
	v_mfma_f32_16x16x32_bf16 v[52:55], v[152:155], v[192:195], v[52:55]
	v_mfma_f32_16x16x32_bf16 v[20:23], v[156:159], v[192:195], v[20:23]
	ds_read_b128 v[192:195], v142 offset:39936
	v_mfma_f32_16x16x32_bf16 v[104:107], v[144:147], v[196:199], v[104:107]
	v_mfma_f32_16x16x32_bf16 v[72:75], v[148:151], v[196:199], v[72:75]
	v_mfma_f32_16x16x32_bf16 v[40:43], v[152:155], v[196:199], v[40:43]
	v_mfma_f32_16x16x32_bf16 v[8:11], v[156:159], v[196:199], v[8:11]
	ds_read_b128 v[196:199], v142 offset:41984
	v_mfma_f32_16x16x32_bf16 v[108:111], v[144:147], v[200:203], v[108:111]
	v_mfma_f32_16x16x32_bf16 v[76:79], v[148:151], v[200:203], v[76:79]
	v_mfma_f32_16x16x32_bf16 v[44:47], v[152:155], v[200:203], v[44:47]
	v_mfma_f32_16x16x32_bf16 v[12:15], v[156:159], v[200:203], v[12:15]
	ds_read_b128 v[200:203], v142 offset:44032
	v_mfma_f32_16x16x32_bf16 v[96:99], v[144:147], v[204:207], v[96:99]
	v_mfma_f32_16x16x32_bf16 v[64:67], v[148:151], v[204:207], v[64:67]
	v_mfma_f32_16x16x32_bf16 v[32:35], v[152:155], v[204:207], v[32:35]
	v_mfma_f32_16x16x32_bf16 v[0:3], v[156:159], v[204:207], v[0:3]
	v_mfma_f32_16x16x32_bf16 v[100:103], v[144:147], v[218:221], v[100:103]
	v_mfma_f32_16x16x32_bf16 v[68:71], v[148:151], v[218:221], v[68:71]
	v_mfma_f32_16x16x32_bf16 v[36:39], v[152:155], v[218:221], v[36:39]
	v_mfma_f32_16x16x32_bf16 v[4:7], v[156:159], v[218:221], v[4:7]
	s_waitcnt lgkmcnt(0)
	s_waitcnt vmcnt(4)
	s_barrier
	v_mfma_f32_16x16x32_bf16 v[120:123], v[160:163], v[178:181], v[120:123]
	ds_read_b128 v[144:147], v143
	v_mfma_f32_16x16x32_bf16 v[88:91], v[164:167], v[178:181], v[88:91]
	ds_read_b128 v[148:151], v143 offset:2048
	v_mfma_f32_16x16x32_bf16 v[56:59], v[168:171], v[178:181], v[56:59]
	ds_read_b128 v[152:155], v143 offset:4096
	v_mfma_f32_16x16x32_bf16 v[24:27], v[172:175], v[178:181], v[24:27]
	ds_read_b128 v[156:159], v143 offset:6144
	v_mfma_f32_16x16x32_bf16 v[124:127], v[160:163], v[184:187], v[124:127]
	ds_read_b128 v[204:207], v176 offset:45056
	v_mfma_f32_16x16x32_bf16 v[92:95], v[164:167], v[184:187], v[92:95]
	ds_read_b128 v[218:221], v176 offset:47104
	v_mfma_f32_16x16x32_bf16 v[60:63], v[168:171], v[184:187], v[60:63]
	ds_read_b128 v[178:181], v176 offset:32768
	v_mfma_f32_16x16x32_bf16 v[28:31], v[172:175], v[184:187], v[28:31]
	ds_read_b128 v[184:187], v176 offset:34816
	v_mfma_f32_16x16x32_bf16 v[112:115], v[160:163], v[188:191], v[112:115]
	v_mfma_f32_16x16x32_bf16 v[80:83], v[164:167], v[188:191], v[80:83]
	v_mfma_f32_16x16x32_bf16 v[48:51], v[168:171], v[188:191], v[48:51]
	v_mfma_f32_16x16x32_bf16 v[16:19], v[172:175], v[188:191], v[16:19]
	ds_read_b128 v[188:191], v176 offset:36864
	v_mfma_f32_16x16x32_bf16 v[116:119], v[160:163], v[192:195], v[116:119]
	v_mfma_f32_16x16x32_bf16 v[84:87], v[164:167], v[192:195], v[84:87]
	v_mfma_f32_16x16x32_bf16 v[52:55], v[168:171], v[192:195], v[52:55]
	v_mfma_f32_16x16x32_bf16 v[20:23], v[172:175], v[192:195], v[20:23]
	ds_read_b128 v[192:195], v176 offset:38912
	v_mfma_f32_16x16x32_bf16 v[104:107], v[160:163], v[196:199], v[104:107]
	v_mfma_f32_16x16x32_bf16 v[72:75], v[164:167], v[196:199], v[72:75]
	v_mfma_f32_16x16x32_bf16 v[40:43], v[168:171], v[196:199], v[40:43]
	v_mfma_f32_16x16x32_bf16 v[8:11], v[172:175], v[196:199], v[8:11]
	ds_read_b128 v[196:199], v176 offset:40960
	v_mfma_f32_16x16x32_bf16 v[108:111], v[160:163], v[200:203], v[108:111]
	v_mfma_f32_16x16x32_bf16 v[76:79], v[164:167], v[200:203], v[76:79]
	v_mfma_f32_16x16x32_bf16 v[44:47], v[168:171], v[200:203], v[44:47]
	v_mfma_f32_16x16x32_bf16 v[12:15], v[172:175], v[200:203], v[12:15]
	ds_read_b128 v[200:203], v176 offset:43008
	v_mfma_f32_16x16x32_bf16 v[96:99], v[160:163], v[208:211], v[96:99]
	v_mfma_f32_16x16x32_bf16 v[64:67], v[164:167], v[208:211], v[64:67]
	v_mfma_f32_16x16x32_bf16 v[32:35], v[168:171], v[208:211], v[32:35]
	v_mfma_f32_16x16x32_bf16 v[0:3], v[172:175], v[208:211], v[0:3]
	v_mfma_f32_16x16x32_bf16 v[100:103], v[160:163], v[224:227], v[100:103]
	v_mfma_f32_16x16x32_bf16 v[68:71], v[164:167], v[224:227], v[68:71]
	v_mfma_f32_16x16x32_bf16 v[36:39], v[168:171], v[224:227], v[36:39]
	v_mfma_f32_16x16x32_bf16 v[4:7], v[172:175], v[224:227], v[4:7]
	s_waitcnt lgkmcnt(0)
	s_waitcnt vmcnt(0)
	s_barrier
; #define SBAR() __builtin_amdgcn_sched_barrier(0)
; #define WAIT_V0() asm volatile("s_waitcnt vmcnt(0)" ::: "memory")
; DEVFI void gemm_stage(const TileSrc& t, const int buf, const int kt, char* shm, const int wid, const int lane) {
;   int R, C; stage_rc<G_KS>(wid * 1024 + lane * 16, R, C);
;   const int oa = R * t.lda + C, ob = R * t.ldb + C;
; #pragma unroll
;   for (int i = 0; i < G_GL; ++i) {
;     __builtin_amdgcn_global_load_lds((const unsigned*)(t.A + (i * 64 * t.lda + kt * G_BK) + oa), (unsigned*)(shm + buf * G_STAGE_B + wid * 1024 + i * 8192), 16, 0, 0);
;     __builtin_amdgcn_global_load_lds((const unsigned*)(t.B + (i * 64 * t.ldb + kt * G_BK) + ob), (unsigned*)(shm + buf * G_STAGE_B + G_TILE_B + wid * 1024 + i * 8192), 16, 0, 0); }
; }
; template <class Epi>
; DEVFI void gemm_main(const TileSrc t, const int K, char* shm, const bool pf, const TileSrc nx, const int wv, Epi epi) {
;     ...
; #pragma unroll
;     for (int ks = 0; ks < G_KS; ++ks) {
;       bf16x8 At[4], Bf[8];
; #pragma unroll
;       for (int n = 0; n < 8; ++n) Bf[n] = *(const bf16x8*)(bBase + cur * G_STAGE_B + (n * 2048 + ks * 1024));
;       SBAR();
;       At[0] = *(const bf16x8*)(aBase + cur * G_STAGE_B + (0 * 2048 + ks * 1024)); SBAR();
;       At[1] = *(const bf16x8*)(aBase + cur * G_STAGE_B + (1 * 2048 + ks * 1024)); SBAR();
;       At[2] = *(const bf16x8*)(aBase + cur * G_STAGE_B + (2 * 2048 + ks * 1024)); SBAR();
;       At[3] = *(const bf16x8*)(aBase + cur * G_STAGE_B + (3 * 2048 + ks * 1024));
;       SBAR();
;       __builtin_amdgcn_s_setprio(1);
; #pragma unroll
;       for (int m = 0; m < 4; ++m)
; #pragma unroll
;         for (int n = 0; n < 8; ++n) acc[m][n] = __builtin_amdgcn_mfma_f32_16x16x32_bf16(At[m], Bf[n], acc[m][n], 0, 0, 0);
;       __builtin_amdgcn_s_setprio(0);
;       SBAR();
;     }
;     WAIT_V0(); __syncthreads();
;   }
;     ...
;   if (pf) gemm_stage(nx, 0, 0, shm, wid, lane);
	v_mfma_f32_16x16x32_bf16 v[120:123], v[144:147], v[178:181], v[120:123]
	ds_read_b128 v[160:163], v143 offset:1024
	v_mfma_f32_16x16x32_bf16 v[88:91], v[148:151], v[178:181], v[88:91]
	ds_read_b128 v[164:167], v143 offset:3072
	v_mfma_f32_16x16x32_bf16 v[56:59], v[152:155], v[178:181], v[56:59]
	ds_read_b128 v[168:171], v143 offset:5120
	v_mfma_f32_16x16x32_bf16 v[24:27], v[156:159], v[178:181], v[24:27]
	ds_read_b128 v[172:175], v143 offset:7168
	v_mfma_f32_16x16x32_bf16 v[124:127], v[144:147], v[184:187], v[124:127]
	ds_read_b128 v[208:211], v176 offset:46080
	v_mfma_f32_16x16x32_bf16 v[92:95], v[148:151], v[184:187], v[92:95]
	ds_read_b128 v[224:227], v176 offset:48128
	v_mfma_f32_16x16x32_bf16 v[60:63], v[152:155], v[184:187], v[60:63]
	ds_read_b128 v[178:181], v176 offset:33792
	v_mfma_f32_16x16x32_bf16 v[28:31], v[156:159], v[184:187], v[28:31]
	ds_read_b128 v[184:187], v176 offset:35840
	v_mfma_f32_16x16x32_bf16 v[112:115], v[144:147], v[188:191], v[112:115]
	v_mfma_f32_16x16x32_bf16 v[80:83], v[148:151], v[188:191], v[80:83]
	v_mfma_f32_16x16x32_bf16 v[48:51], v[152:155], v[188:191], v[48:51]
	v_mfma_f32_16x16x32_bf16 v[16:19], v[156:159], v[188:191], v[16:19]
	ds_read_b128 v[188:191], v176 offset:37888
	v_mfma_f32_16x16x32_bf16 v[116:119], v[144:147], v[192:195], v[116:119]
	v_mfma_f32_16x16x32_bf16 v[84:87], v[148:151], v[192:195], v[84:87]
	v_mfma_f32_16x16x32_bf16 v[52:55], v[152:155], v[192:195], v[52:55]
	v_mfma_f32_16x16x32_bf16 v[20:23], v[156:159], v[192:195], v[20:23]
	ds_read_b128 v[192:195], v176 offset:39936
	v_mfma_f32_16x16x32_bf16 v[104:107], v[144:147], v[196:199], v[104:107]
	v_mfma_f32_16x16x32_bf16 v[72:75], v[148:151], v[196:199], v[72:75]
	v_mfma_f32_16x16x32_bf16 v[40:43], v[152:155], v[196:199], v[40:43]
	v_mfma_f32_16x16x32_bf16 v[8:11], v[156:159], v[196:199], v[8:11]
	ds_read_b128 v[196:199], v176 offset:41984
	v_mfma_f32_16x16x32_bf16 v[108:111], v[144:147], v[200:203], v[108:111]
	v_mfma_f32_16x16x32_bf16 v[76:79], v[148:151], v[200:203], v[76:79]
	v_mfma_f32_16x16x32_bf16 v[44:47], v[152:155], v[200:203], v[44:47]
	v_mfma_f32_16x16x32_bf16 v[12:15], v[156:159], v[200:203], v[12:15]
	ds_read_b128 v[200:203], v176 offset:44032
	v_mfma_f32_16x16x32_bf16 v[96:99], v[144:147], v[204:207], v[96:99]
	v_mfma_f32_16x16x32_bf16 v[64:67], v[148:151], v[204:207], v[64:67]
	v_mfma_f32_16x16x32_bf16 v[32:35], v[152:155], v[204:207], v[32:35]
	v_mfma_f32_16x16x32_bf16 v[0:3], v[156:159], v[204:207], v[0:3]
	v_mfma_f32_16x16x32_bf16 v[100:103], v[144:147], v[218:221], v[100:103]
	v_mfma_f32_16x16x32_bf16 v[68:71], v[148:151], v[218:221], v[68:71]
	v_mfma_f32_16x16x32_bf16 v[36:39], v[152:155], v[218:221], v[36:39]
	v_mfma_f32_16x16x32_bf16 v[4:7], v[156:159], v[218:221], v[4:7]
	s_waitcnt lgkmcnt(0)
	s_barrier
	v_mfma_f32_16x16x32_bf16 v[120:123], v[160:163], v[178:181], v[120:123]
	v_mfma_f32_16x16x32_bf16 v[88:91], v[164:167], v[178:181], v[88:91]
	v_mfma_f32_16x16x32_bf16 v[56:59], v[168:171], v[178:181], v[56:59]
	v_mfma_f32_16x16x32_bf16 v[24:27], v[172:175], v[178:181], v[24:27]
	v_mfma_f32_16x16x32_bf16 v[124:127], v[160:163], v[184:187], v[124:127]
	v_mfma_f32_16x16x32_bf16 v[92:95], v[164:167], v[184:187], v[92:95]
	v_mfma_f32_16x16x32_bf16 v[60:63], v[168:171], v[184:187], v[60:63]
	v_mfma_f32_16x16x32_bf16 v[28:31], v[172:175], v[184:187], v[28:31]
	v_mfma_f32_16x16x32_bf16 v[112:115], v[160:163], v[188:191], v[112:115]
	v_mfma_f32_16x16x32_bf16 v[80:83], v[164:167], v[188:191], v[80:83]
	v_mfma_f32_16x16x32_bf16 v[48:51], v[168:171], v[188:191], v[48:51]
	v_mfma_f32_16x16x32_bf16 v[16:19], v[172:175], v[188:191], v[16:19]
	v_mfma_f32_16x16x32_bf16 v[116:119], v[160:163], v[192:195], v[116:119]
	v_mfma_f32_16x16x32_bf16 v[84:87], v[164:167], v[192:195], v[84:87]
	v_mfma_f32_16x16x32_bf16 v[52:55], v[168:171], v[192:195], v[52:55]
	v_mfma_f32_16x16x32_bf16 v[20:23], v[172:175], v[192:195], v[20:23]
	v_mfma_f32_16x16x32_bf16 v[104:107], v[160:163], v[196:199], v[104:107]
	v_mfma_f32_16x16x32_bf16 v[72:75], v[164:167], v[196:199], v[72:75]
	v_mfma_f32_16x16x32_bf16 v[40:43], v[168:171], v[196:199], v[40:43]
	v_mfma_f32_16x16x32_bf16 v[8:11], v[172:175], v[196:199], v[8:11]
	v_mfma_f32_16x16x32_bf16 v[108:111], v[160:163], v[200:203], v[108:111]
	v_mfma_f32_16x16x32_bf16 v[76:79], v[164:167], v[200:203], v[76:79]
	v_mfma_f32_16x16x32_bf16 v[44:47], v[168:171], v[200:203], v[44:47]
	v_mfma_f32_16x16x32_bf16 v[12:15], v[172:175], v[200:203], v[12:15]
	v_mfma_f32_16x16x32_bf16 v[96:99], v[160:163], v[208:211], v[96:99]
	v_mfma_f32_16x16x32_bf16 v[64:67], v[164:167], v[208:211], v[64:67]
	v_mfma_f32_16x16x32_bf16 v[32:35], v[168:171], v[208:211], v[32:35]
	v_mfma_f32_16x16x32_bf16 v[0:3], v[172:175], v[208:211], v[0:3]
	v_mfma_f32_16x16x32_bf16 v[100:103], v[160:163], v[224:227], v[100:103]
	v_mfma_f32_16x16x32_bf16 v[68:71], v[164:167], v[224:227], v[68:71]
	v_mfma_f32_16x16x32_bf16 v[36:39], v[168:171], v[224:227], v[36:39]
	v_mfma_f32_16x16x32_bf16 v[4:7], v[172:175], v[224:227], v[4:7]
	s_nop 7
	s_nop 3
	s_mov_b64 s[8:9], 0x780
	s_mov_b32 s18, 0xf0000
	s_and_b64 vcc, exec, s[6:7]
	s_cbranch_vccz .LBB0_3188
	v_lshlrev_b32_e32 v128, 1, v138
	v_sub_u32_e32 v128, v137, v128
	v_lshl_or_b32 v129, v138, 14, v140
	v_lshl_add_u32 v128, v128, 5, v129
	v_or_b32_e32 v128, v128, v139
	v_ashrrev_i32_e32 v129, 31, v128
	v_add_u32_e32 v137, 0x8000, v136
	v_lshlrev_b64 v[128:129], 1, v[128:129]
	v_readfirstlane_b32 s2, v136
	v_lshl_add_u64 v[130:131], s[14:15], 0, v[128:129]
	s_mov_b32 m0, s2
	v_readfirstlane_b32 s2, v137
	v_add_u32_e32 v137, 0x2000, v136
	global_load_lds_dwordx4 v[130:131], off
	v_lshl_add_u64 v[128:129], s[16:17], 0, v[128:129]
	s_mov_b32 m0, s2
	v_readfirstlane_b32 s2, v137
	v_add_u32_e32 v137, 0xa000, v136
	global_load_lds_dwordx4 v[128:129], off
	v_lshl_add_u64 v[138:139], v[130:131], 0, s[86:87]
	s_mov_b32 m0, s2
	v_readfirstlane_b32 s2, v137
	v_add_u32_e32 v137, 0x4000, v136
	global_load_lds_dwordx4 v[138:139], off
	v_lshl_add_u64 v[138:139], v[128:129], 0, s[86:87]
	s_mov_b32 m0, s2
	v_readfirstlane_b32 s2, v137
	v_add_u32_e32 v137, 0xc000, v136
	global_load_lds_dwordx4 v[138:139], off
	v_lshl_add_u64 v[138:139], v[130:131], 0, s[88:89]
	s_mov_b32 m0, s2
	v_readfirstlane_b32 s2, v137
	v_add_u32_e32 v137, 0x6000, v136
	global_load_lds_dwordx4 v[138:139], off
	v_lshl_add_u64 v[138:139], v[128:129], 0, s[88:89]
	s_mov_b32 m0, s2
	v_readfirstlane_b32 s2, v137
	global_load_lds_dwordx4 v[138:139], off
	v_lshl_add_u64 v[130:131], v[130:131], 0, s[90:91]
	s_mov_b32 m0, s2
	v_lshl_add_u64 v[128:129], v[128:129], 0, s[90:91]
	global_load_lds_dwordx4 v[130:131], off
	v_add_u32_e32 v130, 0xe000, v136
	s_nop 0
	v_readfirstlane_b32 s2, v130
	s_mov_b32 m0, s2
	s_nop 0
	global_load_lds_dwordx4 v[128:129], off
; #define SBAR() __builtin_amdgcn_sched_barrier(0)
; DEVFI float dpp_xor1(float x) { return __int_as_float(__builtin_amdgcn_update_dpp(0, __float_as_int(x), 0xB1, 0xF, 0xF, true)); }
; DEVFI void store_nat_m(bfraw* base, long ld, f32x4 (&a)[8], int fr) {
;   const bool odd = fr & 1;
;   bfraw* p0 = base + (odd ? 15 + fr : fr);
; #pragma unroll
;   for (int j = 0; j < 4; ++j)
; #pragma unroll
;     for (int n0 = 0; n0 < 8; n0 += 2) { const float own0 = a[n0][j], own1 = a[n0 + 1][j];
;       const float recv = dpp_xor1(odd ? own0 : own1);
;       const unsigned pk = odd ? cvtpk(recv, own1) : cvtpk(own0, recv);
;       *reinterpret_cast<unsigned*>(p0 + (long)j * ld + n0 * 16) = pk; }
; }
; DEVFI void store_nat(bfraw* dst, long ld, f32x4 (&acc)[4][8], int fr, int fq) {
;   store_nat_m(dst + (long)(0 * 16 + fq * 4) * ld, ld, acc[0], fr); SBAR();
;   store_nat_m(dst + (long)(1 * 16 + fq * 4) * ld, ld, acc[1], fr); SBAR();
;   store_nat_m(dst + (long)(2 * 16 + fq * 4) * ld, ld, acc[2], fr); SBAR();
;   store_nat_m(dst + (long)(3 * 16 + fq * 4) * ld, ld, acc[3], fr); SBAR();
; }
.LBB0_3188:
	s_mov_b64 s[2:3], s[0:1]
	s_load_dwordx2 s[2:3], s[2:3], 0xe8
	v_and_b32_e32 v128, 1, v135
	v_cmp_eq_u32_e64 s[8:9], 0, v128
	v_cmp_eq_u32_e64 s[6:7], 1, v128
	s_nop 0
	v_cndmask_b32_e64 v128, v120, v124, s[8:9]
	s_nop 1
	v_mov_b32_dpp v128, v128 quad_perm:[1,0,3,2] row_mask:0xf bank_mask:0xf bound_ctrl:1
	v_cndmask_b32_e64 v135, v120, v128, s[6:7]
	v_cndmask_b32_e64 v128, v128, v124, s[6:7]
	v_cvt_pk_bf16_f32 v135, v135, v128
	s_lshr_b32 s18, s12, 2
	s_and_b32 s18, s18, 0xfffff8
	s_and_b32 s19, s12, 7
	s_or_b32 s18, s18, s19
	s_lshl_b32 s18, s18, 8
	v_mov_b32_e32 v120, s18
	v_lshl_add_u32 v128, s21, 6, v120
	v_ashrrev_i32_e32 v129, 31, v128
	v_lshlrev_b64 v[128:129], 11, v[128:129]
	s_waitcnt lgkmcnt(0)
	v_lshl_add_u64 v[128:129], s[2:3], 0, v[128:129]
	s_lshl_b32 s2, s12, 6
	s_and_b32 s12, s2, 0x600
	v_lshl_add_u64 v[128:129], v[128:129], 0, s[12:13]
	v_lshlrev_b32_e32 v176, 8, v134
	v_lshlrev_b32_e32 v120, 9, v133
	v_lshl_add_u64 v[128:129], v[128:129], 0, v[176:177]
	v_and_b32_e32 v176, 0x6000, v120
	v_add_u32_e32 v120, 15, v132
	v_lshl_add_u64 v[128:129], v[128:129], 0, v[176:177]
	s_mov_b64 s[2:3], 0x30720000
	v_cndmask_b32_e64 v120, v120, v132, s[8:9]
	v_lshl_add_u64 v[128:129], v[128:129], 0, s[2:3]
	v_lshlrev_b32_e32 v176, 1, v120
	v_cndmask_b32_e64 v120, v112, v116, s[8:9]
	v_lshl_add_u64 v[130:131], v[128:129], 0, v[176:177]
	global_store_dword v[130:131], v135, off
	v_mov_b32_dpp v124, v120 quad_perm:[1,0,3,2] row_mask:0xf bank_mask:0xf bound_ctrl:1
	v_cndmask_b32_e64 v120, v112, v124, s[6:7]
	v_cndmask_b32_e64 v124, v124, v116, s[6:7]
	v_cvt_pk_bf16_f32 v120, v120, v124
	v_cndmask_b32_e64 v112, v104, v108, s[8:9]
	global_store_dword v[130:131], v120, off offset:64
	s_nop 0
	v_mov_b32_dpp v116, v112 quad_perm:[1,0,3,2] row_mask:0xf bank_mask:0xf bound_ctrl:1
	v_cndmask_b32_e64 v112, v104, v116, s[6:7]
	v_cndmask_b32_e64 v116, v116, v108, s[6:7]
	v_cvt_pk_bf16_f32 v112, v112, v116
	v_cndmask_b32_e64 v104, v96, v100, s[8:9]
	global_store_dword v[130:131], v112, off offset:128
	s_nop 0
	v_mov_b32_dpp v108, v104 quad_perm:[1,0,3,2] row_mask:0xf bank_mask:0xf bound_ctrl:1
	v_cndmask_b32_e64 v104, v96, v108, s[6:7]
	v_cndmask_b32_e64 v108, v108, v100, s[6:7]
	v_cvt_pk_bf16_f32 v104, v104, v108
	v_cndmask_b32_e64 v96, v121, v125, s[8:9]
	global_store_dword v[130:131], v104, off offset:192
	s_nop 0
	v_mov_b32_dpp v100, v96 quad_perm:[1,0,3,2] row_mask:0xf bank_mask:0xf bound_ctrl:1
	v_cndmask_b32_e64 v96, v121, v100, s[6:7]
	v_cndmask_b32_e64 v100, v100, v125, s[6:7]
	v_cvt_pk_bf16_f32 v96, v96, v100
	global_store_dword v[130:131], v96, off offset:2048
	v_cndmask_b32_e64 v96, v113, v117, s[8:9]
	s_nop 1
	v_mov_b32_dpp v100, v96 quad_perm:[1,0,3,2] row_mask:0xf bank_mask:0xf bound_ctrl:1
	v_cndmask_b32_e64 v96, v113, v100, s[6:7]
	v_cndmask_b32_e64 v100, v100, v117, s[6:7]
	v_cvt_pk_bf16_f32 v96, v96, v100
	global_store_dword v[130:131], v96, off offset:2112
	v_cndmask_b32_e64 v96, v105, v109, s[8:9]
	s_nop 1
	v_mov_b32_dpp v100, v96 quad_perm:[1,0,3,2] row_mask:0xf bank_mask:0xf bound_ctrl:1
	v_cndmask_b32_e64 v96, v105, v100, s[6:7]
	v_cndmask_b32_e64 v100, v100, v109, s[6:7]
	v_cvt_pk_bf16_f32 v96, v96, v100
	global_store_dword v[130:131], v96, off offset:2176
	v_cndmask_b32_e64 v96, v97, v101, s[8:9]
	s_nop 1
	v_mov_b32_dpp v100, v96 quad_perm:[1,0,3,2] row_mask:0xf bank_mask:0xf bound_ctrl:1
	v_cndmask_b32_e64 v96, v97, v100, s[6:7]
	v_cndmask_b32_e64 v100, v100, v101, s[6:7]
	v_cvt_pk_bf16_f32 v96, v96, v100
	global_store_dword v[130:131], v96, off offset:2240
	v_cndmask_b32_e64 v96, v122, v126, s[8:9]
	s_nop 1
	v_mov_b32_dpp v97, v96 quad_perm:[1,0,3,2] row_mask:0xf bank_mask:0xf bound_ctrl:1
	v_cndmask_b32_e64 v96, v122, v97, s[6:7]
	v_cndmask_b32_e64 v97, v97, v126, s[6:7]
	v_cvt_pk_bf16_f32 v96, v96, v97
	v_add_co_u32_e32 v100, vcc, 0x1000, v130
	s_nop 1
	v_addc_co_u32_e32 v101, vcc, 0, v131, vcc
	global_store_dword v[100:101], v96, off
	v_cndmask_b32_e64 v96, v114, v118, s[8:9]
	s_nop 1
	v_mov_b32_dpp v97, v96 quad_perm:[1,0,3,2] row_mask:0xf bank_mask:0xf bound_ctrl:1
	v_cndmask_b32_e64 v96, v114, v97, s[6:7]
	v_cndmask_b32_e64 v97, v97, v118, s[6:7]
	v_cvt_pk_bf16_f32 v96, v96, v97
	v_add_co_u32_e32 v100, vcc, 0x1000, v130
	s_nop 1
	v_addc_co_u32_e32 v101, vcc, 0, v131, vcc
	global_store_dword v[100:101], v96, off offset:64
	v_cndmask_b32_e64 v96, v106, v110, s[8:9]
	s_nop 1
	v_mov_b32_dpp v97, v96 quad_perm:[1,0,3,2] row_mask:0xf bank_mask:0xf bound_ctrl:1
	v_cndmask_b32_e64 v96, v106, v97, s[6:7]
	v_cndmask_b32_e64 v97, v97, v110, s[6:7]
	v_cvt_pk_bf16_f32 v96, v96, v97
	v_add_co_u32_e32 v100, vcc, 0x1000, v130
	s_nop 1
	v_addc_co_u32_e32 v101, vcc, 0, v131, vcc
	global_store_dword v[100:101], v96, off offset:128
	v_cndmask_b32_e64 v96, v98, v102, s[8:9]
	s_nop 1
	v_mov_b32_dpp v97, v96 quad_perm:[1,0,3,2] row_mask:0xf bank_mask:0xf bound_ctrl:1
	v_cndmask_b32_e64 v96, v98, v97, s[6:7]
	v_cndmask_b32_e64 v97, v97, v102, s[6:7]
	v_cvt_pk_bf16_f32 v96, v96, v97
	v_add_co_u32_e32 v100, vcc, 0x1000, v130
	s_nop 1
	v_addc_co_u32_e32 v101, vcc, 0, v131, vcc
	global_store_dword v[100:101], v96, off offset:192
	v_cndmask_b32_e64 v96, v123, v127, s[8:9]
	s_nop 1
	v_mov_b32_dpp v97, v96 quad_perm:[1,0,3,2] row_mask:0xf bank_mask:0xf bound_ctrl:1
	v_cndmask_b32_e64 v96, v123, v97, s[6:7]
	v_cndmask_b32_e64 v97, v97, v127, s[6:7]
	v_cvt_pk_bf16_f32 v96, v96, v97
	v_add_co_u32_e32 v100, vcc, 0x1000, v130
	s_nop 1
	v_addc_co_u32_e32 v101, vcc, 0, v131, vcc
	global_store_dword v[100:101], v96, off offset:2048
	v_cndmask_b32_e64 v96, v115, v119, s[8:9]
	s_nop 1
	v_mov_b32_dpp v97, v96 quad_perm:[1,0,3,2] row_mask:0xf bank_mask:0xf bound_ctrl:1
; #define SBAR() __builtin_amdgcn_sched_barrier(0)
; DEVFI float dpp_xor1(float x) { return __int_as_float(__builtin_amdgcn_update_dpp(0, __float_as_int(x), 0xB1, 0xF, 0xF, true)); }
; DEVFI void store_nat_m(bfraw* base, long ld, f32x4 (&a)[8], int fr) {
;   const bool odd = fr & 1;
;   bfraw* p0 = base + (odd ? 15 + fr : fr);
; #pragma unroll
;   for (int j = 0; j < 4; ++j)
; #pragma unroll
;     for (int n0 = 0; n0 < 8; n0 += 2) { const float own0 = a[n0][j], own1 = a[n0 + 1][j];
;       const float recv = dpp_xor1(odd ? own0 : own1);
;       const unsigned pk = odd ? cvtpk(recv, own1) : cvtpk(own0, recv);
;       *reinterpret_cast<unsigned*>(p0 + (long)j * ld + n0 * 16) = pk; }
; }
; DEVFI void store_nat(bfraw* dst, long ld, f32x4 (&acc)[4][8], int fr, int fq) {
;   store_nat_m(dst + (long)(0 * 16 + fq * 4) * ld, ld, acc[0], fr); SBAR();
;   store_nat_m(dst + (long)(1 * 16 + fq * 4) * ld, ld, acc[1], fr); SBAR();
;   store_nat_m(dst + (long)(2 * 16 + fq * 4) * ld, ld, acc[2], fr); SBAR();
;   store_nat_m(dst + (long)(3 * 16 + fq * 4) * ld, ld, acc[3], fr); SBAR();
; }
	v_cndmask_b32_e64 v96, v115, v97, s[6:7]
	v_cndmask_b32_e64 v97, v97, v119, s[6:7]
	v_cvt_pk_bf16_f32 v96, v96, v97
	v_add_co_u32_e32 v100, vcc, 0x1000, v130
	s_nop 1
	v_addc_co_u32_e32 v101, vcc, 0, v131, vcc
	global_store_dword v[100:101], v96, off offset:2112
	v_cndmask_b32_e64 v96, v107, v111, s[8:9]
	s_nop 1
	v_mov_b32_dpp v97, v96 quad_perm:[1,0,3,2] row_mask:0xf bank_mask:0xf bound_ctrl:1
	v_cndmask_b32_e64 v96, v107, v97, s[6:7]
	v_cndmask_b32_e64 v97, v97, v111, s[6:7]
	v_cvt_pk_bf16_f32 v96, v96, v97
	v_add_co_u32_e32 v100, vcc, 0x1000, v130
	s_nop 1
	v_addc_co_u32_e32 v101, vcc, 0, v131, vcc
	global_store_dword v[100:101], v96, off offset:2176
	v_cndmask_b32_e64 v96, v99, v103, s[8:9]
	s_nop 1
	v_mov_b32_dpp v96, v96 quad_perm:[1,0,3,2] row_mask:0xf bank_mask:0xf bound_ctrl:1
	v_cndmask_b32_e64 v100, v99, v96, s[6:7]
	v_cndmask_b32_e64 v96, v96, v103, s[6:7]
	v_cvt_pk_bf16_f32 v100, v100, v96
	v_add_co_u32_e32 v96, vcc, 0x1000, v130
	s_nop 1
	v_addc_co_u32_e32 v97, vcc, 0, v131, vcc
	global_store_dword v[96:97], v100, off offset:2240
	v_cndmask_b32_e64 v96, v88, v92, s[8:9]
	s_nop 1
	v_mov_b32_dpp v96, v96 quad_perm:[1,0,3,2] row_mask:0xf bank_mask:0xf bound_ctrl:1
	v_cndmask_b32_e64 v98, v88, v96, s[6:7]
	v_cndmask_b32_e64 v96, v96, v92, s[6:7]
	v_cvt_pk_bf16_f32 v98, v98, v96
	v_lshl_add_u64 v[96:97], v[128:129], 0, v[176:177]
	v_add_co_u32_e32 v100, vcc, 0x8000, v96
	v_cndmask_b32_e64 v88, v80, v84, s[8:9]
	s_nop 0
	v_addc_co_u32_e32 v101, vcc, 0, v97, vcc
	v_mov_b32_dpp v92, v88 quad_perm:[1,0,3,2] row_mask:0xf bank_mask:0xf bound_ctrl:1
	global_store_dword v[100:101], v98, off
	v_cndmask_b32_e64 v88, v80, v92, s[6:7]
	v_cndmask_b32_e64 v92, v92, v84, s[6:7]
	v_cvt_pk_bf16_f32 v88, v88, v92
	s_mov_b64 s[2:3], 0x8000
	v_cndmask_b32_e64 v80, v72, v76, s[8:9]
	v_lshl_add_u64 v[96:97], v[96:97], 0, s[2:3]
	global_store_dword v[96:97], v88, off offset:64
	v_mov_b32_dpp v84, v80 quad_perm:[1,0,3,2] row_mask:0xf bank_mask:0xf bound_ctrl:1
	v_cndmask_b32_e64 v80, v72, v84, s[6:7]
	v_cndmask_b32_e64 v84, v84, v76, s[6:7]
	v_cvt_pk_bf16_f32 v80, v80, v84
	v_cndmask_b32_e64 v72, v64, v68, s[8:9]
	global_store_dword v[96:97], v80, off offset:128
	s_nop 0
	v_mov_b32_dpp v76, v72 quad_perm:[1,0,3,2] row_mask:0xf bank_mask:0xf bound_ctrl:1
	v_cndmask_b32_e64 v72, v64, v76, s[6:7]
	v_cndmask_b32_e64 v76, v76, v68, s[6:7]
	v_cvt_pk_bf16_f32 v72, v72, v76
	v_cndmask_b32_e64 v64, v89, v93, s[8:9]
	global_store_dword v[96:97], v72, off offset:192
	s_nop 0
	v_mov_b32_dpp v68, v64 quad_perm:[1,0,3,2] row_mask:0xf bank_mask:0xf bound_ctrl:1
	v_cndmask_b32_e64 v64, v89, v68, s[6:7]
	v_cndmask_b32_e64 v68, v68, v93, s[6:7]
	v_cvt_pk_bf16_f32 v64, v64, v68
	global_store_dword v[96:97], v64, off offset:2048
	v_cndmask_b32_e64 v64, v81, v85, s[8:9]
	s_nop 1
	v_mov_b32_dpp v68, v64 quad_perm:[1,0,3,2] row_mask:0xf bank_mask:0xf bound_ctrl:1
	v_cndmask_b32_e64 v64, v81, v68, s[6:7]
	v_cndmask_b32_e64 v68, v68, v85, s[6:7]
	v_cvt_pk_bf16_f32 v64, v64, v68
	global_store_dword v[96:97], v64, off offset:2112
	v_cndmask_b32_e64 v64, v73, v77, s[8:9]
	s_nop 1
	v_mov_b32_dpp v68, v64 quad_perm:[1,0,3,2] row_mask:0xf bank_mask:0xf bound_ctrl:1
	v_cndmask_b32_e64 v64, v73, v68, s[6:7]
	v_cndmask_b32_e64 v68, v68, v77, s[6:7]
	v_cvt_pk_bf16_f32 v64, v64, v68
	global_store_dword v[96:97], v64, off offset:2176
	v_cndmask_b32_e64 v64, v65, v69, s[8:9]
	s_nop 1
	v_mov_b32_dpp v68, v64 quad_perm:[1,0,3,2] row_mask:0xf bank_mask:0xf bound_ctrl:1
	v_cndmask_b32_e64 v64, v65, v68, s[6:7]
	v_cndmask_b32_e64 v68, v68, v69, s[6:7]
	v_cvt_pk_bf16_f32 v64, v64, v68
	global_store_dword v[96:97], v64, off offset:2240
	v_cndmask_b32_e64 v64, v90, v94, s[8:9]
	s_nop 1
	v_mov_b32_dpp v65, v64 quad_perm:[1,0,3,2] row_mask:0xf bank_mask:0xf bound_ctrl:1
	v_cndmask_b32_e64 v64, v90, v65, s[6:7]
	v_cndmask_b32_e64 v65, v65, v94, s[6:7]
	v_cvt_pk_bf16_f32 v64, v64, v65
	v_add_co_u32_e32 v68, vcc, 0x1000, v96
	s_nop 1
	v_addc_co_u32_e32 v69, vcc, 0, v97, vcc
	global_store_dword v[68:69], v64, off
	v_cndmask_b32_e64 v64, v82, v86, s[8:9]
	s_nop 1
	v_mov_b32_dpp v65, v64 quad_perm:[1,0,3,2] row_mask:0xf bank_mask:0xf bound_ctrl:1
	v_cndmask_b32_e64 v64, v82, v65, s[6:7]
	v_cndmask_b32_e64 v65, v65, v86, s[6:7]
	v_cvt_pk_bf16_f32 v64, v64, v65
	v_add_co_u32_e32 v68, vcc, 0x1000, v96
	s_nop 1
	v_addc_co_u32_e32 v69, vcc, 0, v97, vcc
	global_store_dword v[68:69], v64, off offset:64
	v_cndmask_b32_e64 v64, v74, v78, s[8:9]
	s_nop 1
	v_mov_b32_dpp v65, v64 quad_perm:[1,0,3,2] row_mask:0xf bank_mask:0xf bound_ctrl:1
	v_cndmask_b32_e64 v64, v74, v65, s[6:7]
	v_cndmask_b32_e64 v65, v65, v78, s[6:7]
	v_cvt_pk_bf16_f32 v64, v64, v65
	v_add_co_u32_e32 v68, vcc, 0x1000, v96
	s_nop 1
	v_addc_co_u32_e32 v69, vcc, 0, v97, vcc
	global_store_dword v[68:69], v64, off offset:128
	v_cndmask_b32_e64 v64, v66, v70, s[8:9]
	s_nop 1
	v_mov_b32_dpp v65, v64 quad_perm:[1,0,3,2] row_mask:0xf bank_mask:0xf bound_ctrl:1
	v_cndmask_b32_e64 v64, v66, v65, s[6:7]
	v_cndmask_b32_e64 v65, v65, v70, s[6:7]
	v_cvt_pk_bf16_f32 v64, v64, v65
	v_add_co_u32_e32 v68, vcc, 0x1000, v96
	s_nop 1
	v_addc_co_u32_e32 v69, vcc, 0, v97, vcc
	global_store_dword v[68:69], v64, off offset:192
	v_cndmask_b32_e64 v64, v91, v95, s[8:9]
	s_nop 1
	v_mov_b32_dpp v65, v64 quad_perm:[1,0,3,2] row_mask:0xf bank_mask:0xf bound_ctrl:1
	v_cndmask_b32_e64 v64, v91, v65, s[6:7]
	v_cndmask_b32_e64 v65, v65, v95, s[6:7]
	v_cvt_pk_bf16_f32 v64, v64, v65
	v_add_co_u32_e32 v68, vcc, 0x1000, v96
	s_nop 1
	v_addc_co_u32_e32 v69, vcc, 0, v97, vcc
	global_store_dword v[68:69], v64, off offset:2048
	v_cndmask_b32_e64 v64, v83, v87, s[8:9]
	s_nop 1
; #define SBAR() __builtin_amdgcn_sched_barrier(0)
; DEVFI float dpp_xor1(float x) { return __int_as_float(__builtin_amdgcn_update_dpp(0, __float_as_int(x), 0xB1, 0xF, 0xF, true)); }
; DEVFI void store_nat_m(bfraw* base, long ld, f32x4 (&a)[8], int fr) {
;   const bool odd = fr & 1;
;   bfraw* p0 = base + (odd ? 15 + fr : fr);
; #pragma unroll
;   for (int j = 0; j < 4; ++j)
; #pragma unroll
;     for (int n0 = 0; n0 < 8; n0 += 2) { const float own0 = a[n0][j], own1 = a[n0 + 1][j];
;       const float recv = dpp_xor1(odd ? own0 : own1);
;       const unsigned pk = odd ? cvtpk(recv, own1) : cvtpk(own0, recv);
;       *reinterpret_cast<unsigned*>(p0 + (long)j * ld + n0 * 16) = pk; }
; }
; DEVFI void store_nat(bfraw* dst, long ld, f32x4 (&acc)[4][8], int fr, int fq) {
;   store_nat_m(dst + (long)(0 * 16 + fq * 4) * ld, ld, acc[0], fr); SBAR();
;   store_nat_m(dst + (long)(1 * 16 + fq * 4) * ld, ld, acc[1], fr); SBAR();
;   store_nat_m(dst + (long)(2 * 16 + fq * 4) * ld, ld, acc[2], fr); SBAR();
;   store_nat_m(dst + (long)(3 * 16 + fq * 4) * ld, ld, acc[3], fr); SBAR();
; }
	v_mov_b32_dpp v65, v64 quad_perm:[1,0,3,2] row_mask:0xf bank_mask:0xf bound_ctrl:1
	v_cndmask_b32_e64 v64, v83, v65, s[6:7]
	v_cndmask_b32_e64 v65, v65, v87, s[6:7]
	v_cvt_pk_bf16_f32 v64, v64, v65
	v_add_co_u32_e32 v68, vcc, 0x1000, v96
	s_nop 1
	v_addc_co_u32_e32 v69, vcc, 0, v97, vcc
	global_store_dword v[68:69], v64, off offset:2112
	v_cndmask_b32_e64 v64, v75, v79, s[8:9]
	s_nop 1
	v_mov_b32_dpp v65, v64 quad_perm:[1,0,3,2] row_mask:0xf bank_mask:0xf bound_ctrl:1
	v_cndmask_b32_e64 v64, v75, v65, s[6:7]
	v_cndmask_b32_e64 v65, v65, v79, s[6:7]
	v_cvt_pk_bf16_f32 v64, v64, v65
	v_add_co_u32_e32 v68, vcc, 0x1000, v96
	s_nop 1
	v_addc_co_u32_e32 v69, vcc, 0, v97, vcc
	global_store_dword v[68:69], v64, off offset:2176
	v_cndmask_b32_e64 v64, v67, v71, s[8:9]
	s_nop 1
	v_mov_b32_dpp v64, v64 quad_perm:[1,0,3,2] row_mask:0xf bank_mask:0xf bound_ctrl:1
	v_cndmask_b32_e64 v68, v67, v64, s[6:7]
	v_cndmask_b32_e64 v64, v64, v71, s[6:7]
	v_cvt_pk_bf16_f32 v68, v68, v64
	v_add_co_u32_e32 v64, vcc, 0x1000, v96
	s_nop 1
	v_addc_co_u32_e32 v65, vcc, 0, v97, vcc
	global_store_dword v[64:65], v68, off offset:2240
	v_cndmask_b32_e64 v64, v56, v60, s[8:9]
	s_nop 1
	v_mov_b32_dpp v64, v64 quad_perm:[1,0,3,2] row_mask:0xf bank_mask:0xf bound_ctrl:1
	v_cndmask_b32_e64 v66, v56, v64, s[6:7]
	v_cndmask_b32_e64 v64, v64, v60, s[6:7]
	v_cvt_pk_bf16_f32 v66, v66, v64
	v_lshl_add_u64 v[64:65], v[128:129], 0, v[176:177]
	v_add_co_u32_e32 v68, vcc, 0x10000, v64
	v_cndmask_b32_e64 v56, v48, v52, s[8:9]
	s_nop 0
	v_addc_co_u32_e32 v69, vcc, 0, v65, vcc
	v_mov_b32_dpp v60, v56 quad_perm:[1,0,3,2] row_mask:0xf bank_mask:0xf bound_ctrl:1
	global_store_dword v[68:69], v66, off
	v_cndmask_b32_e64 v56, v48, v60, s[6:7]
	v_cndmask_b32_e64 v60, v60, v52, s[6:7]
	v_cvt_pk_bf16_f32 v56, v56, v60
	v_cndmask_b32_e64 v48, v40, v44, s[8:9]
	v_lshl_add_u64 v[64:65], v[64:65], 0, s[48:49]
	global_store_dword v[64:65], v56, off offset:64
	v_mov_b32_dpp v52, v48 quad_perm:[1,0,3,2] row_mask:0xf bank_mask:0xf bound_ctrl:1
	v_cndmask_b32_e64 v48, v40, v52, s[6:7]
	v_cndmask_b32_e64 v52, v52, v44, s[6:7]
	v_cvt_pk_bf16_f32 v48, v48, v52
	v_cndmask_b32_e64 v40, v32, v36, s[8:9]
	global_store_dword v[64:65], v48, off offset:128
	s_nop 0
	v_mov_b32_dpp v44, v40 quad_perm:[1,0,3,2] row_mask:0xf bank_mask:0xf bound_ctrl:1
	v_cndmask_b32_e64 v40, v32, v44, s[6:7]
	v_cndmask_b32_e64 v44, v44, v36, s[6:7]
	v_cvt_pk_bf16_f32 v40, v40, v44
	v_cndmask_b32_e64 v32, v57, v61, s[8:9]
	global_store_dword v[64:65], v40, off offset:192
	s_nop 0
	v_mov_b32_dpp v36, v32 quad_perm:[1,0,3,2] row_mask:0xf bank_mask:0xf bound_ctrl:1
	v_cndmask_b32_e64 v32, v57, v36, s[6:7]
	v_cndmask_b32_e64 v36, v36, v61, s[6:7]
	v_cvt_pk_bf16_f32 v32, v32, v36
	global_store_dword v[64:65], v32, off offset:2048
	v_cndmask_b32_e64 v32, v49, v53, s[8:9]
	s_nop 1
	v_mov_b32_dpp v36, v32 quad_perm:[1,0,3,2] row_mask:0xf bank_mask:0xf bound_ctrl:1
	v_cndmask_b32_e64 v32, v49, v36, s[6:7]
	v_cndmask_b32_e64 v36, v36, v53, s[6:7]
	v_cvt_pk_bf16_f32 v32, v32, v36
	global_store_dword v[64:65], v32, off offset:2112
	v_cndmask_b32_e64 v32, v41, v45, s[8:9]
	s_nop 1
	v_mov_b32_dpp v36, v32 quad_perm:[1,0,3,2] row_mask:0xf bank_mask:0xf bound_ctrl:1
	v_cndmask_b32_e64 v32, v41, v36, s[6:7]
	v_cndmask_b32_e64 v36, v36, v45, s[6:7]
	v_cvt_pk_bf16_f32 v32, v32, v36
	global_store_dword v[64:65], v32, off offset:2176
	v_cndmask_b32_e64 v32, v33, v37, s[8:9]
	s_nop 1
	v_mov_b32_dpp v36, v32 quad_perm:[1,0,3,2] row_mask:0xf bank_mask:0xf bound_ctrl:1
	v_cndmask_b32_e64 v32, v33, v36, s[6:7]
	v_cndmask_b32_e64 v36, v36, v37, s[6:7]
	v_cvt_pk_bf16_f32 v32, v32, v36
	global_store_dword v[64:65], v32, off offset:2240
	v_cndmask_b32_e64 v32, v58, v62, s[8:9]
	s_nop 1
	v_mov_b32_dpp v33, v32 quad_perm:[1,0,3,2] row_mask:0xf bank_mask:0xf bound_ctrl:1
	v_cndmask_b32_e64 v32, v58, v33, s[6:7]
	v_cndmask_b32_e64 v33, v33, v62, s[6:7]
	v_cvt_pk_bf16_f32 v32, v32, v33
	v_add_co_u32_e32 v36, vcc, 0x1000, v64
	s_nop 1
	v_addc_co_u32_e32 v37, vcc, 0, v65, vcc
	global_store_dword v[36:37], v32, off
	v_cndmask_b32_e64 v32, v50, v54, s[8:9]
	s_nop 1
	v_mov_b32_dpp v33, v32 quad_perm:[1,0,3,2] row_mask:0xf bank_mask:0xf bound_ctrl:1
	v_cndmask_b32_e64 v32, v50, v33, s[6:7]
	v_cndmask_b32_e64 v33, v33, v54, s[6:7]
	v_cvt_pk_bf16_f32 v32, v32, v33
	v_add_co_u32_e32 v36, vcc, 0x1000, v64
	s_nop 1
	v_addc_co_u32_e32 v37, vcc, 0, v65, vcc
	global_store_dword v[36:37], v32, off offset:64
	v_cndmask_b32_e64 v32, v42, v46, s[8:9]
	s_nop 1
	v_mov_b32_dpp v33, v32 quad_perm:[1,0,3,2] row_mask:0xf bank_mask:0xf bound_ctrl:1
	v_cndmask_b32_e64 v32, v42, v33, s[6:7]
	v_cndmask_b32_e64 v33, v33, v46, s[6:7]
	v_cvt_pk_bf16_f32 v32, v32, v33
	v_add_co_u32_e32 v36, vcc, 0x1000, v64
	s_nop 1
	v_addc_co_u32_e32 v37, vcc, 0, v65, vcc
	global_store_dword v[36:37], v32, off offset:128
	v_cndmask_b32_e64 v32, v34, v38, s[8:9]
	s_nop 1
	v_mov_b32_dpp v33, v32 quad_perm:[1,0,3,2] row_mask:0xf bank_mask:0xf bound_ctrl:1
	v_cndmask_b32_e64 v32, v34, v33, s[6:7]
	v_cndmask_b32_e64 v33, v33, v38, s[6:7]
	v_cvt_pk_bf16_f32 v32, v32, v33
	v_add_co_u32_e32 v36, vcc, 0x1000, v64
	s_nop 1
	v_addc_co_u32_e32 v37, vcc, 0, v65, vcc
	global_store_dword v[36:37], v32, off offset:192
	v_cndmask_b32_e64 v32, v59, v63, s[8:9]
	s_nop 1
	v_mov_b32_dpp v33, v32 quad_perm:[1,0,3,2] row_mask:0xf bank_mask:0xf bound_ctrl:1
	v_cndmask_b32_e64 v32, v59, v33, s[6:7]
	v_cndmask_b32_e64 v33, v33, v63, s[6:7]
	v_cvt_pk_bf16_f32 v32, v32, v33
	v_add_co_u32_e32 v36, vcc, 0x1000, v64
	s_nop 1
	v_addc_co_u32_e32 v37, vcc, 0, v65, vcc
	global_store_dword v[36:37], v32, off offset:2048
	v_cndmask_b32_e64 v32, v51, v55, s[8:9]
; #define SBAR() __builtin_amdgcn_sched_barrier(0)
; DEVFI float dpp_xor1(float x) { return __int_as_float(__builtin_amdgcn_update_dpp(0, __float_as_int(x), 0xB1, 0xF, 0xF, true)); }
; DEVFI void store_nat_m(bfraw* base, long ld, f32x4 (&a)[8], int fr) {
;   const bool odd = fr & 1;
;   bfraw* p0 = base + (odd ? 15 + fr : fr);
; #pragma unroll
;   for (int j = 0; j < 4; ++j)
; #pragma unroll
;     for (int n0 = 0; n0 < 8; n0 += 2) { const float own0 = a[n0][j], own1 = a[n0 + 1][j];
;       const float recv = dpp_xor1(odd ? own0 : own1);
;       const unsigned pk = odd ? cvtpk(recv, own1) : cvtpk(own0, recv);
;       *reinterpret_cast<unsigned*>(p0 + (long)j * ld + n0 * 16) = pk; }
; }
; DEVFI void store_nat(bfraw* dst, long ld, f32x4 (&acc)[4][8], int fr, int fq) {
;   store_nat_m(dst + (long)(0 * 16 + fq * 4) * ld, ld, acc[0], fr); SBAR();
;   store_nat_m(dst + (long)(1 * 16 + fq * 4) * ld, ld, acc[1], fr); SBAR();
;   store_nat_m(dst + (long)(2 * 16 + fq * 4) * ld, ld, acc[2], fr); SBAR();
;   store_nat_m(dst + (long)(3 * 16 + fq * 4) * ld, ld, acc[3], fr); SBAR();
; }
	s_nop 1
	v_mov_b32_dpp v33, v32 quad_perm:[1,0,3,2] row_mask:0xf bank_mask:0xf bound_ctrl:1
	v_cndmask_b32_e64 v32, v51, v33, s[6:7]
	v_cndmask_b32_e64 v33, v33, v55, s[6:7]
	v_cvt_pk_bf16_f32 v32, v32, v33
	v_add_co_u32_e32 v36, vcc, 0x1000, v64
	s_nop 1
	v_addc_co_u32_e32 v37, vcc, 0, v65, vcc
	global_store_dword v[36:37], v32, off offset:2112
	v_cndmask_b32_e64 v32, v43, v47, s[8:9]
	s_nop 1
	v_mov_b32_dpp v33, v32 quad_perm:[1,0,3,2] row_mask:0xf bank_mask:0xf bound_ctrl:1
	v_cndmask_b32_e64 v32, v43, v33, s[6:7]
	v_cndmask_b32_e64 v33, v33, v47, s[6:7]
	v_cvt_pk_bf16_f32 v32, v32, v33
	v_add_co_u32_e32 v36, vcc, 0x1000, v64
	s_nop 1
	v_addc_co_u32_e32 v37, vcc, 0, v65, vcc
	global_store_dword v[36:37], v32, off offset:2176
	v_cndmask_b32_e64 v32, v35, v39, s[8:9]
	s_nop 1
	v_mov_b32_dpp v32, v32 quad_perm:[1,0,3,2] row_mask:0xf bank_mask:0xf bound_ctrl:1
	v_cndmask_b32_e64 v36, v35, v32, s[6:7]
	v_cndmask_b32_e64 v32, v32, v39, s[6:7]
	v_cvt_pk_bf16_f32 v36, v36, v32
	v_add_co_u32_e32 v32, vcc, 0x1000, v64
	s_nop 1
	v_addc_co_u32_e32 v33, vcc, 0, v65, vcc
	global_store_dword v[32:33], v36, off offset:2240
	v_cndmask_b32_e64 v32, v24, v28, s[8:9]
	s_nop 1
	v_mov_b32_dpp v32, v32 quad_perm:[1,0,3,2] row_mask:0xf bank_mask:0xf bound_ctrl:1
	v_cndmask_b32_e64 v34, v24, v32, s[6:7]
	v_cndmask_b32_e64 v32, v32, v28, s[6:7]
	v_cvt_pk_bf16_f32 v34, v34, v32
	v_lshl_add_u64 v[32:33], v[128:129], 0, v[176:177]
	v_add_co_u32_e32 v36, vcc, 0x18000, v32
	v_cndmask_b32_e64 v24, v16, v20, s[8:9]
	s_nop 0
	v_addc_co_u32_e32 v37, vcc, 0, v33, vcc
	v_mov_b32_dpp v28, v24 quad_perm:[1,0,3,2] row_mask:0xf bank_mask:0xf bound_ctrl:1
	global_store_dword v[36:37], v34, off
	v_cndmask_b32_e64 v24, v16, v28, s[6:7]
	v_cndmask_b32_e64 v28, v28, v20, s[6:7]
	v_cvt_pk_bf16_f32 v24, v24, v28
	s_mov_b64 s[2:3], 0x18000
	v_cndmask_b32_e64 v16, v8, v12, s[8:9]
	v_lshl_add_u64 v[32:33], v[32:33], 0, s[2:3]
	global_store_dword v[32:33], v24, off offset:64
	v_mov_b32_dpp v20, v16 quad_perm:[1,0,3,2] row_mask:0xf bank_mask:0xf bound_ctrl:1
	v_cndmask_b32_e64 v16, v8, v20, s[6:7]
	v_cndmask_b32_e64 v20, v20, v12, s[6:7]
	v_cvt_pk_bf16_f32 v16, v16, v20
	v_cndmask_b32_e64 v8, v0, v4, s[8:9]
	global_store_dword v[32:33], v16, off offset:128
	s_nop 0
	v_mov_b32_dpp v12, v8 quad_perm:[1,0,3,2] row_mask:0xf bank_mask:0xf bound_ctrl:1
	v_cndmask_b32_e64 v8, v0, v12, s[6:7]
	v_cndmask_b32_e64 v12, v12, v4, s[6:7]
	v_cvt_pk_bf16_f32 v8, v8, v12
	v_cndmask_b32_e64 v0, v25, v29, s[8:9]
	global_store_dword v[32:33], v8, off offset:192
	s_nop 0
	v_mov_b32_dpp v4, v0 quad_perm:[1,0,3,2] row_mask:0xf bank_mask:0xf bound_ctrl:1
	v_cndmask_b32_e64 v0, v25, v4, s[6:7]
	v_cndmask_b32_e64 v4, v4, v29, s[6:7]
	v_cvt_pk_bf16_f32 v0, v0, v4
	global_store_dword v[32:33], v0, off offset:2048
	v_cndmask_b32_e64 v0, v17, v21, s[8:9]
	s_nop 1
	v_mov_b32_dpp v4, v0 quad_perm:[1,0,3,2] row_mask:0xf bank_mask:0xf bound_ctrl:1
	v_cndmask_b32_e64 v0, v17, v4, s[6:7]
	v_cndmask_b32_e64 v4, v4, v21, s[6:7]
	v_cvt_pk_bf16_f32 v0, v0, v4
	global_store_dword v[32:33], v0, off offset:2112
	v_cndmask_b32_e64 v0, v9, v13, s[8:9]
	s_nop 1
	v_mov_b32_dpp v4, v0 quad_perm:[1,0,3,2] row_mask:0xf bank_mask:0xf bound_ctrl:1
	v_cndmask_b32_e64 v0, v9, v4, s[6:7]
	v_cndmask_b32_e64 v4, v4, v13, s[6:7]
	v_cvt_pk_bf16_f32 v0, v0, v4
	global_store_dword v[32:33], v0, off offset:2176
	v_cndmask_b32_e64 v0, v1, v5, s[8:9]
	s_nop 1
	v_mov_b32_dpp v4, v0 quad_perm:[1,0,3,2] row_mask:0xf bank_mask:0xf bound_ctrl:1
	v_cndmask_b32_e64 v0, v1, v4, s[6:7]
	v_cndmask_b32_e64 v4, v4, v5, s[6:7]
	v_cvt_pk_bf16_f32 v0, v0, v4
	global_store_dword v[32:33], v0, off offset:2240
	v_cndmask_b32_e64 v0, v26, v30, s[8:9]
	s_nop 1
	v_mov_b32_dpp v1, v0 quad_perm:[1,0,3,2] row_mask:0xf bank_mask:0xf bound_ctrl:1
	v_cndmask_b32_e64 v0, v26, v1, s[6:7]
	v_cndmask_b32_e64 v1, v1, v30, s[6:7]
	v_cvt_pk_bf16_f32 v0, v0, v1
	v_add_co_u32_e32 v4, vcc, 0x1000, v32
	s_nop 1
	v_addc_co_u32_e32 v5, vcc, 0, v33, vcc
	global_store_dword v[4:5], v0, off
	v_cndmask_b32_e64 v0, v18, v22, s[8:9]
	s_nop 1
	v_mov_b32_dpp v1, v0 quad_perm:[1,0,3,2] row_mask:0xf bank_mask:0xf bound_ctrl:1
	v_cndmask_b32_e64 v0, v18, v1, s[6:7]
	v_cndmask_b32_e64 v1, v1, v22, s[6:7]
	v_cvt_pk_bf16_f32 v0, v0, v1
	v_add_co_u32_e32 v4, vcc, 0x1000, v32
	s_nop 1
	v_addc_co_u32_e32 v5, vcc, 0, v33, vcc
	global_store_dword v[4:5], v0, off offset:64
	v_cndmask_b32_e64 v0, v10, v14, s[8:9]
	s_nop 1
	v_mov_b32_dpp v1, v0 quad_perm:[1,0,3,2] row_mask:0xf bank_mask:0xf bound_ctrl:1
	v_cndmask_b32_e64 v0, v10, v1, s[6:7]
	v_cndmask_b32_e64 v1, v1, v14, s[6:7]
	v_cvt_pk_bf16_f32 v0, v0, v1
	v_add_co_u32_e32 v4, vcc, 0x1000, v32
	s_nop 1
	v_addc_co_u32_e32 v5, vcc, 0, v33, vcc
	global_store_dword v[4:5], v0, off offset:128
	v_cndmask_b32_e64 v0, v2, v6, s[8:9]
	s_nop 1
	v_mov_b32_dpp v1, v0 quad_perm:[1,0,3,2] row_mask:0xf bank_mask:0xf bound_ctrl:1
	v_cndmask_b32_e64 v0, v2, v1, s[6:7]
	v_cndmask_b32_e64 v1, v1, v6, s[6:7]
	v_cvt_pk_bf16_f32 v0, v0, v1
	v_add_co_u32_e32 v4, vcc, 0x1000, v32
	s_nop 1
	v_addc_co_u32_e32 v5, vcc, 0, v33, vcc
	global_store_dword v[4:5], v0, off offset:192
	v_cndmask_b32_e64 v0, v27, v31, s[8:9]
	s_nop 1
	v_mov_b32_dpp v1, v0 quad_perm:[1,0,3,2] row_mask:0xf bank_mask:0xf bound_ctrl:1
	v_cndmask_b32_e64 v0, v27, v1, s[6:7]
	v_cndmask_b32_e64 v1, v1, v31, s[6:7]
	v_cvt_pk_bf16_f32 v0, v0, v1
	v_add_co_u32_e32 v4, vcc, 0x1000, v32
	s_nop 1
	v_addc_co_u32_e32 v5, vcc, 0, v33, vcc
	global_store_dword v[4:5], v0, off offset:2048
	v_cndmask_b32_e64 v0, v19, v23, s[8:9]
	s_nop 1
	v_mov_b32_dpp v1, v0 quad_perm:[1,0,3,2] row_mask:0xf bank_mask:0xf bound_ctrl:1
	v_cndmask_b32_e64 v0, v19, v1, s[6:7]
	v_cndmask_b32_e64 v1, v1, v23, s[6:7]
	v_cvt_pk_bf16_f32 v0, v0, v1
	v_add_co_u32_e32 v4, vcc, 0x1000, v32
	s_nop 1
	v_addc_co_u32_e32 v5, vcc, 0, v33, vcc
	global_store_dword v[4:5], v0, off offset:2112
	v_cndmask_b32_e64 v0, v11, v15, s[8:9]
	s_nop 1
	v_mov_b32_dpp v1, v0 quad_perm:[1,0,3,2] row_mask:0xf bank_mask:0xf bound_ctrl:1
	v_cndmask_b32_e64 v0, v11, v1, s[6:7]
	v_cndmask_b32_e64 v1, v1, v15, s[6:7]
	v_cvt_pk_bf16_f32 v0, v0, v1
	v_add_co_u32_e32 v4, vcc, 0x1000, v32
	s_nop 1
	v_addc_co_u32_e32 v5, vcc, 0, v33, vcc
	global_store_dword v[4:5], v0, off offset:2176
	v_cndmask_b32_e64 v0, v3, v7, s[8:9]
	s_nop 1
	v_mov_b32_dpp v0, v0 quad_perm:[1,0,3,2] row_mask:0xf bank_mask:0xf bound_ctrl:1
	s_and_saveexec_b64 s[2:3], s[6:7]
	s_xor_b64 s[2:3], exec, s[2:3]
	s_cbranch_execz .LBB0_3442
	v_cvt_pk_bf16_f32 v4, v0, v7

; #define SBAR() __builtin_amdgcn_sched_barrier(0)
; DEVFI float dpp_xor1(float x) { return __int_as_float(__builtin_amdgcn_update_dpp(0, __float_as_int(x), 0xB1, 0xF, 0xF, true)); }
; #define QB ((bfraw*)(kargs()->ws + O_QB))
; DEVFI void store_nat_m(bfraw* base, long ld, f32x4 (&a)[8], int fr) {
;   const bool odd = fr & 1;
;   bfraw* p0 = base + (odd ? 15 + fr : fr);
; #pragma unroll
;   for (int j = 0; j < 4; ++j)
; #pragma unroll
;     for (int n0 = 0; n0 < 8; n0 += 2) { const float own0 = a[n0][j], own1 = a[n0 + 1][j];
;       const float recv = dpp_xor1(odd ? own0 : own1);
;       const unsigned pk = odd ? cvtpk(recv, own1) : cvtpk(own0, recv);
;       *reinterpret_cast<unsigned*>(p0 + (long)j * ld + n0 * 16) = pk; }
; }
; __global__ void __launch_bounds__(512) mega(Params p) {
;     ...
;             auto snorm = [&](f32x4 (&a)[8], const int m) {
; #pragma unroll
;               for (int j = 0; j < 4; ++j) { const int rr = rb + m * 16 + j; const float inv = 1.f / (red[512 + rr] + red[768 + rr]);
; #pragma unroll
;                 for (int n = 0; n < 8; ++n) a[n][j] *= inv; }
;               store_nat_m(QB + (long)(brow + rb + m * 16) * 1024 + hh * 256 + wc0, 1024, a, fr);
;               SBAR(); };
.LBB0_3584:
	s_or_b64 exec, exec, s[2:3]
	v_add_co_u32_e32 v6, vcc, 0x1000, v8
	s_nop 1
	v_addc_co_u32_e32 v7, vcc, 0, v9, vcc
	global_store_dword v[6:7], v3, off offset:2176
	v_mov_b32_dpp v3, v4 quad_perm:[1,0,3,2] row_mask:0xf bank_mask:0xf bound_ctrl:1
	v_cndmask_b32_e64 v2, v1, v3, s[8:9]
	v_cndmask_b32_e64 v3, v3, v0, s[8:9]
	v_cvt_pk_bf16_f32 v2, v2, v3
	v_add_co_u32_e32 v0, vcc, 0x1000, v8
	s_nop 1
	v_addc_co_u32_e32 v1, vcc, 0, v9, vcc
	global_store_dword v[0:1], v2, off offset:2240
	ds_read_b128 v[0:3], v129 offset:2112
	ds_read_b128 v[4:7], v129 offset:3136
	s_mov_b64 s[2:3], s[0:1]
	s_load_dwordx2 s[2:3], s[2:3], 0xe8
	s_waitcnt lgkmcnt(0)
	v_add_f32_e32 v0, v0, v4
	v_div_scale_f32 v4, s[20:21], v0, v0, 1.0
	v_rcp_f32_e32 v8, v4
	v_div_scale_f32 v9, vcc, 1.0, v0, 1.0
	v_fma_f32 v10, -v4, v8, 1.0
	v_fmac_f32_e32 v8, v10, v8
	v_mul_f32_e32 v10, v9, v8
	v_fma_f32 v11, -v4, v10, v9
	v_fmac_f32_e32 v10, v11, v8
	v_fma_f32 v4, -v4, v10, v9
	v_div_fmas_f32 v4, v4, v8, v10
	v_div_fixup_f32 v0, v4, v0, 1.0
	v_mul_f32_e32 v8, v115, v0
	v_mul_f32_e32 v4, v116, v0
	v_cndmask_b32_e64 v9, v8, v4, s[10:11]
	s_nop 1
	v_mov_b32_dpp v9, v9 quad_perm:[1,0,3,2] row_mask:0xf bank_mask:0xf bound_ctrl:1
	s_and_saveexec_b64 s[20:21], s[8:9]
	s_xor_b64 s[20:21], exec, s[20:21]
	s_cbranch_execz .LBB0_3590
	v_cvt_pk_bf16_f32 v19, v9, v4

; #define SBAR() __builtin_amdgcn_sched_barrier(0)
; DEVFI float dpp_xor1(float x) { return __int_as_float(__builtin_amdgcn_update_dpp(0, __float_as_int(x), 0xB1, 0xF, 0xF, true)); }
; #define QB ((bfraw*)(kargs()->ws + O_QB))
; DEVFI void store_nat_m(bfraw* base, long ld, f32x4 (&a)[8], int fr) {
;   const bool odd = fr & 1;
;   bfraw* p0 = base + (odd ? 15 + fr : fr);
; #pragma unroll
;   for (int j = 0; j < 4; ++j)
; #pragma unroll
;     for (int n0 = 0; n0 < 8; n0 += 2) { const float own0 = a[n0][j], own1 = a[n0 + 1][j];
;       const float recv = dpp_xor1(odd ? own0 : own1);
;       const unsigned pk = odd ? cvtpk(recv, own1) : cvtpk(own0, recv);
;       *reinterpret_cast<unsigned*>(p0 + (long)j * ld + n0 * 16) = pk; }
; }
; __global__ void __launch_bounds__(512) mega(Params p) {
;     ...
;             auto snorm = [&](f32x4 (&a)[8], const int m) {
; #pragma unroll
;               for (int j = 0; j < 4; ++j) { const int rr = rb + m * 16 + j; const float inv = 1.f / (red[512 + rr] + red[768 + rr]);
; #pragma unroll
;                 for (int n = 0; n < 8; ++n) a[n][j] *= inv; }
;               store_nat_m(QB + (long)(brow + rb + m * 16) * 1024 + hh * 256 + wc0, 1024, a, fr);
;               SBAR(); };
.LBB0_3648:
	s_or_b64 exec, exec, s[2:3]
	v_add_co_u32_e32 v6, vcc, 0x1000, v10
	s_nop 1
	v_addc_co_u32_e32 v7, vcc, 0, v11, vcc
	global_store_dword v[6:7], v3, off offset:2176
	v_mov_b32_dpp v3, v4 quad_perm:[1,0,3,2] row_mask:0xf bank_mask:0xf bound_ctrl:1
	v_cndmask_b32_e64 v2, v1, v3, s[8:9]
	v_cndmask_b32_e64 v3, v3, v0, s[8:9]
	v_cvt_pk_bf16_f32 v2, v2, v3
	v_add_co_u32_e32 v0, vcc, 0x1000, v10
	s_nop 1
	v_addc_co_u32_e32 v1, vcc, 0, v11, vcc
	global_store_dword v[0:1], v2, off offset:2240
	ds_read_b128 v[0:3], v129 offset:2176
	ds_read_b128 v[4:7], v129 offset:3200
	s_mov_b64 s[2:3], s[0:1]
	s_load_dwordx2 s[2:3], s[2:3], 0xe8
	s_waitcnt lgkmcnt(0)
	v_add_f32_e32 v0, v0, v4
	v_div_scale_f32 v4, s[20:21], v0, v0, 1.0
	v_rcp_f32_e32 v9, v4
	v_div_scale_f32 v10, vcc, 1.0, v0, 1.0
	v_fma_f32 v11, -v4, v9, 1.0
	v_fmac_f32_e32 v9, v11, v9
	v_mul_f32_e32 v11, v10, v9
	v_fma_f32 v19, -v4, v11, v10
	v_fmac_f32_e32 v11, v19, v9
	v_fma_f32 v4, -v4, v11, v10
	v_div_fmas_f32 v4, v4, v9, v11
	v_div_fixup_f32 v0, v4, v0, 1.0
	v_mul_f32_e32 v9, v81, v0
	v_mul_f32_e32 v4, v82, v0
	v_cndmask_b32_e64 v10, v9, v4, s[10:11]
	s_nop 1
	v_mov_b32_dpp v10, v10 quad_perm:[1,0,3,2] row_mask:0xf bank_mask:0xf bound_ctrl:1
	s_and_saveexec_b64 s[20:21], s[8:9]
	s_xor_b64 s[20:21], exec, s[20:21]
	s_cbranch_execz .LBB0_3654
	v_cvt_pk_bf16_f32 v19, v10, v4

; #define SBAR() __builtin_amdgcn_sched_barrier(0)
; DEVFI float dpp_xor1(float x) { return __int_as_float(__builtin_amdgcn_update_dpp(0, __float_as_int(x), 0xB1, 0xF, 0xF, true)); }
; #define QB ((bfraw*)(kargs()->ws + O_QB))
; DEVFI void store_nat_m(bfraw* base, long ld, f32x4 (&a)[8], int fr) {
;   const bool odd = fr & 1;
;   bfraw* p0 = base + (odd ? 15 + fr : fr);
; #pragma unroll
;   for (int j = 0; j < 4; ++j)
; #pragma unroll
;     for (int n0 = 0; n0 < 8; n0 += 2) { const float own0 = a[n0][j], own1 = a[n0 + 1][j];
;       const float recv = dpp_xor1(odd ? own0 : own1);
;       const unsigned pk = odd ? cvtpk(recv, own1) : cvtpk(own0, recv);
;       *reinterpret_cast<unsigned*>(p0 + (long)j * ld + n0 * 16) = pk; }
; }
; __global__ void __launch_bounds__(512) mega(Params p) {
;     ...
;             auto snorm = [&](f32x4 (&a)[8], const int m) {
; #pragma unroll
;               for (int j = 0; j < 4; ++j) { const int rr = rb + m * 16 + j; const float inv = 1.f / (red[512 + rr] + red[768 + rr]);
; #pragma unroll
;                 for (int n = 0; n < 8; ++n) a[n][j] *= inv; }
;               store_nat_m(QB + (long)(brow + rb + m * 16) * 1024 + hh * 256 + wc0, 1024, a, fr);
;               SBAR(); };
.LBB0_3712:
	s_or_b64 exec, exec, s[2:3]
	v_add_co_u32_e32 v6, vcc, 0x1000, v10
	s_nop 1
	v_addc_co_u32_e32 v7, vcc, 0, v11, vcc
	global_store_dword v[6:7], v3, off offset:2176
	v_mov_b32_dpp v3, v4 quad_perm:[1,0,3,2] row_mask:0xf bank_mask:0xf bound_ctrl:1
	v_cndmask_b32_e64 v2, v1, v3, s[8:9]
	v_cndmask_b32_e64 v3, v3, v0, s[8:9]
	v_cvt_pk_bf16_f32 v2, v2, v3
	v_add_co_u32_e32 v0, vcc, 0x1000, v10
	s_nop 1
	v_addc_co_u32_e32 v1, vcc, 0, v11, vcc
	global_store_dword v[0:1], v2, off offset:2240
	ds_read_b128 v[0:3], v129 offset:2240
	ds_read_b128 v[4:7], v129 offset:3264
	s_mov_b64 s[2:3], s[0:1]
	s_load_dwordx2 s[2:3], s[2:3], 0xe8
	s_waitcnt lgkmcnt(0)
	v_add_f32_e32 v0, v0, v4
	v_div_scale_f32 v4, s[20:21], v0, v0, 1.0
	v_rcp_f32_e32 v9, v4
	v_div_scale_f32 v10, vcc, 1.0, v0, 1.0
	v_fma_f32 v11, -v4, v9, 1.0
	v_fmac_f32_e32 v9, v11, v9
	v_mul_f32_e32 v11, v10, v9
	v_fma_f32 v19, -v4, v11, v10
	v_fmac_f32_e32 v11, v19, v9
	v_fma_f32 v4, -v4, v11, v10
	v_div_fmas_f32 v4, v4, v9, v11
	v_div_fixup_f32 v0, v4, v0, 1.0
	v_mul_f32_e32 v9, v46, v0
	v_mul_f32_e32 v4, v47, v0
	v_cndmask_b32_e64 v10, v9, v4, s[10:11]
	s_nop 1
	v_mov_b32_dpp v23, v10 quad_perm:[1,0,3,2] row_mask:0xf bank_mask:0xf bound_ctrl:1
	s_and_saveexec_b64 s[10:11], s[8:9]
	s_xor_b64 s[10:11], exec, s[10:11]
	s_cbranch_execz .LBB0_3718
	v_cvt_pk_bf16_f32 v10, v23, v4

; #define SBAR() __builtin_amdgcn_sched_barrier(0)
; DEVFI float dpp_xor1(float x) { return __int_as_float(__builtin_amdgcn_update_dpp(0, __float_as_int(x), 0xB1, 0xF, 0xF, true)); }
; DEVFI void store_nat_m(bfraw* base, long ld, f32x4 (&a)[8], int fr) {
;   const bool odd = fr & 1;
;   bfraw* p0 = base + (odd ? 15 + fr : fr);
; #pragma unroll
;   for (int j = 0; j < 4; ++j)
; #pragma unroll
;     for (int n0 = 0; n0 < 8; n0 += 2) { const float own0 = a[n0][j], own1 = a[n0 + 1][j];
;       const float recv = dpp_xor1(odd ? own0 : own1);
;       const unsigned pk = odd ? cvtpk(recv, own1) : cvtpk(own0, recv);
;       *reinterpret_cast<unsigned*>(p0 + (long)j * ld + n0 * 16) = pk; }
; }
; DEVFI void store_nat(bfraw* dst, long ld, f32x4 (&acc)[4][8], int fr, int fq) {
;   store_nat_m(dst + (long)(0 * 16 + fq * 4) * ld, ld, acc[0], fr); SBAR();
;   store_nat_m(dst + (long)(1 * 16 + fq * 4) * ld, ld, acc[1], fr); SBAR();
;   store_nat_m(dst + (long)(2 * 16 + fq * 4) * ld, ld, acc[2], fr); SBAR();
;   store_nat_m(dst + (long)(3 * 16 + fq * 4) * ld, ld, acc[3], fr); SBAR();
; }
.LBB0_3801:
	s_or_b64 exec, exec, s[18:19]
	v_mov_b32_e32 v32, s22
	s_and_b32 s12, s12, 0x3fffffc
	v_add_lshl_u32 v32, v32, s12, 6
	v_ashrrev_i32_e32 v33, 31, v32
	v_lshlrev_b64 v[32:33], 11, v[32:33]
	s_waitcnt lgkmcnt(0)
	v_lshl_add_u64 v[32:33], s[2:3], 0, v[32:33]
	s_and_b32 s2, s20, 0x300
	v_and_b32_e32 v34, 63, v134
	s_lshl_b32 s12, s2, 1
	v_lshl_add_u64 v[32:33], v[32:33], 0, s[12:13]
	v_lshlrev_b32_e32 v176, 8, v133
	v_lshlrev_b32_e32 v34, 9, v34
	v_lshl_add_u64 v[32:33], v[32:33], 0, v[176:177]
	v_and_b32_e32 v176, 0x6000, v34
	v_lshl_add_u64 v[32:33], v[32:33], 0, v[176:177]
	s_mov_b64 s[2:3], 0x30720000
	v_lshl_add_u64 v[128:129], v[32:33], 0, s[2:3]
	v_add_u32_e32 v32, 15, v132
	v_cndmask_b32_e64 v32, v32, v132, s[8:9]
	v_lshlrev_b32_e32 v176, 1, v32
	v_cndmask_b32_e64 v32, v112, v116, s[8:9]
	v_lshl_add_u64 v[130:131], v[128:129], 0, v[176:177]
	global_store_dword v[130:131], v135, off
	v_mov_b32_dpp v124, v32 quad_perm:[1,0,3,2] row_mask:0xf bank_mask:0xf bound_ctrl:1
	v_cndmask_b32_e64 v120, v112, v124, s[6:7]
	v_cndmask_b32_e64 v124, v124, v116, s[6:7]
	v_cvt_pk_bf16_f32 v120, v120, v124
	v_cndmask_b32_e64 v32, v104, v108, s[8:9]
	global_store_dword v[130:131], v120, off offset:64
	s_nop 0
	v_mov_b32_dpp v116, v32 quad_perm:[1,0,3,2] row_mask:0xf bank_mask:0xf bound_ctrl:1
	v_cndmask_b32_e64 v112, v104, v116, s[6:7]
	v_cndmask_b32_e64 v116, v116, v108, s[6:7]
	v_cvt_pk_bf16_f32 v112, v112, v116
	v_cndmask_b32_e64 v32, v96, v100, s[8:9]
	global_store_dword v[130:131], v112, off offset:128
	s_nop 0
	v_mov_b32_dpp v108, v32 quad_perm:[1,0,3,2] row_mask:0xf bank_mask:0xf bound_ctrl:1
	v_cndmask_b32_e64 v104, v96, v108, s[6:7]
	v_cndmask_b32_e64 v108, v108, v100, s[6:7]
	v_cvt_pk_bf16_f32 v104, v104, v108
	v_cndmask_b32_e64 v32, v121, v125, s[8:9]
	global_store_dword v[130:131], v104, off offset:192
	s_nop 0
	v_mov_b32_dpp v100, v32 quad_perm:[1,0,3,2] row_mask:0xf bank_mask:0xf bound_ctrl:1
	v_cndmask_b32_e64 v96, v121, v100, s[6:7]
	v_cndmask_b32_e64 v100, v100, v125, s[6:7]
	v_cvt_pk_bf16_f32 v96, v96, v100
	v_cndmask_b32_e64 v32, v113, v117, s[8:9]
	global_store_dword v[130:131], v96, off offset:2048
	s_nop 0
	v_mov_b32_dpp v100, v32 quad_perm:[1,0,3,2] row_mask:0xf bank_mask:0xf bound_ctrl:1
	v_cndmask_b32_e64 v96, v113, v100, s[6:7]
	v_cndmask_b32_e64 v100, v100, v117, s[6:7]
	v_cvt_pk_bf16_f32 v96, v96, v100
	v_cndmask_b32_e64 v32, v105, v109, s[8:9]
	global_store_dword v[130:131], v96, off offset:2112
	s_nop 0
	v_mov_b32_dpp v100, v32 quad_perm:[1,0,3,2] row_mask:0xf bank_mask:0xf bound_ctrl:1
	v_cndmask_b32_e64 v96, v105, v100, s[6:7]
	v_cndmask_b32_e64 v100, v100, v109, s[6:7]
	v_cvt_pk_bf16_f32 v96, v96, v100
	v_cndmask_b32_e64 v32, v97, v101, s[8:9]
	global_store_dword v[130:131], v96, off offset:2176
	s_nop 0
	v_mov_b32_dpp v100, v32 quad_perm:[1,0,3,2] row_mask:0xf bank_mask:0xf bound_ctrl:1
	v_cndmask_b32_e64 v96, v97, v100, s[6:7]
	v_cndmask_b32_e64 v100, v100, v101, s[6:7]
	v_cvt_pk_bf16_f32 v96, v96, v100
	v_cndmask_b32_e64 v32, v122, v126, s[8:9]
	global_store_dword v[130:131], v96, off offset:2240
	s_nop 0
	v_mov_b32_dpp v97, v32 quad_perm:[1,0,3,2] row_mask:0xf bank_mask:0xf bound_ctrl:1
	v_cndmask_b32_e64 v96, v122, v97, s[6:7]
	v_cndmask_b32_e64 v97, v97, v126, s[6:7]
	v_cvt_pk_bf16_f32 v96, v96, v97
	v_add_co_u32_e32 v32, vcc, 0x1000, v130
	s_nop 1
	v_addc_co_u32_e32 v33, vcc, 0, v131, vcc
	global_store_dword v[32:33], v96, off
	v_cndmask_b32_e64 v32, v114, v118, s[8:9]
	s_nop 1
	v_mov_b32_dpp v97, v32 quad_perm:[1,0,3,2] row_mask:0xf bank_mask:0xf bound_ctrl:1
	v_cndmask_b32_e64 v96, v114, v97, s[6:7]
	v_cndmask_b32_e64 v97, v97, v118, s[6:7]
	v_cvt_pk_bf16_f32 v96, v96, v97
	v_add_co_u32_e32 v32, vcc, 0x1000, v130
	s_nop 1
	v_addc_co_u32_e32 v33, vcc, 0, v131, vcc
	global_store_dword v[32:33], v96, off offset:64
	v_cndmask_b32_e64 v32, v106, v110, s[8:9]
	s_nop 1
	v_mov_b32_dpp v97, v32 quad_perm:[1,0,3,2] row_mask:0xf bank_mask:0xf bound_ctrl:1
	v_cndmask_b32_e64 v96, v106, v97, s[6:7]
	v_cndmask_b32_e64 v97, v97, v110, s[6:7]
	v_cvt_pk_bf16_f32 v96, v96, v97
	v_add_co_u32_e32 v32, vcc, 0x1000, v130
	s_nop 1
	v_addc_co_u32_e32 v33, vcc, 0, v131, vcc
	global_store_dword v[32:33], v96, off offset:128
	v_cndmask_b32_e64 v32, v98, v102, s[8:9]
	s_nop 1
	v_mov_b32_dpp v97, v32 quad_perm:[1,0,3,2] row_mask:0xf bank_mask:0xf bound_ctrl:1
	v_cndmask_b32_e64 v96, v98, v97, s[6:7]
	v_cndmask_b32_e64 v97, v97, v102, s[6:7]
	v_cvt_pk_bf16_f32 v96, v96, v97
	v_add_co_u32_e32 v32, vcc, 0x1000, v130
	s_nop 1
	v_addc_co_u32_e32 v33, vcc, 0, v131, vcc
	global_store_dword v[32:33], v96, off offset:192
	v_cndmask_b32_e64 v32, v123, v127, s[8:9]
	s_nop 1
	v_mov_b32_dpp v97, v32 quad_perm:[1,0,3,2] row_mask:0xf bank_mask:0xf bound_ctrl:1
	v_cndmask_b32_e64 v96, v123, v97, s[6:7]
	v_cndmask_b32_e64 v97, v97, v127, s[6:7]
	v_cvt_pk_bf16_f32 v96, v96, v97
	v_add_co_u32_e32 v32, vcc, 0x1000, v130
	s_nop 1
	v_addc_co_u32_e32 v33, vcc, 0, v131, vcc
	global_store_dword v[32:33], v96, off offset:2048
	v_cndmask_b32_e64 v32, v115, v119, s[8:9]
	s_nop 1
	v_mov_b32_dpp v97, v32 quad_perm:[1,0,3,2] row_mask:0xf bank_mask:0xf bound_ctrl:1
	v_cndmask_b32_e64 v96, v115, v97, s[6:7]
	v_cndmask_b32_e64 v97, v97, v119, s[6:7]
	v_cvt_pk_bf16_f32 v96, v96, v97
	v_add_co_u32_e32 v32, vcc, 0x1000, v130
	s_nop 1
	v_addc_co_u32_e32 v33, vcc, 0, v131, vcc
	global_store_dword v[32:33], v96, off offset:2112
	v_cndmask_b32_e64 v32, v107, v111, s[8:9]
	s_nop 1
	v_mov_b32_dpp v97, v32 quad_perm:[1,0,3,2] row_mask:0xf bank_mask:0xf bound_ctrl:1
	v_cndmask_b32_e64 v96, v107, v97, s[6:7]
	v_cndmask_b32_e64 v97, v97, v111, s[6:7]
	v_cvt_pk_bf16_f32 v96, v96, v97
; #define SBAR() __builtin_amdgcn_sched_barrier(0)
; DEVFI float dpp_xor1(float x) { return __int_as_float(__builtin_amdgcn_update_dpp(0, __float_as_int(x), 0xB1, 0xF, 0xF, true)); }
; DEVFI void store_nat_m(bfraw* base, long ld, f32x4 (&a)[8], int fr) {
;   const bool odd = fr & 1;
;   bfraw* p0 = base + (odd ? 15 + fr : fr);
; #pragma unroll
;   for (int j = 0; j < 4; ++j)
; #pragma unroll
;     for (int n0 = 0; n0 < 8; n0 += 2) { const float own0 = a[n0][j], own1 = a[n0 + 1][j];
;       const float recv = dpp_xor1(odd ? own0 : own1);
;       const unsigned pk = odd ? cvtpk(recv, own1) : cvtpk(own0, recv);
;       *reinterpret_cast<unsigned*>(p0 + (long)j * ld + n0 * 16) = pk; }
; }
; DEVFI void store_nat(bfraw* dst, long ld, f32x4 (&acc)[4][8], int fr, int fq) {
;   store_nat_m(dst + (long)(0 * 16 + fq * 4) * ld, ld, acc[0], fr); SBAR();
;   store_nat_m(dst + (long)(1 * 16 + fq * 4) * ld, ld, acc[1], fr); SBAR();
;   store_nat_m(dst + (long)(2 * 16 + fq * 4) * ld, ld, acc[2], fr); SBAR();
;   store_nat_m(dst + (long)(3 * 16 + fq * 4) * ld, ld, acc[3], fr); SBAR();
; }
	v_add_co_u32_e32 v32, vcc, 0x1000, v130
	s_nop 1
	v_addc_co_u32_e32 v33, vcc, 0, v131, vcc
	global_store_dword v[32:33], v96, off offset:2176
	v_cndmask_b32_e64 v32, v99, v103, s[8:9]
	s_nop 1
	v_mov_b32_dpp v96, v32 quad_perm:[1,0,3,2] row_mask:0xf bank_mask:0xf bound_ctrl:1
	v_cndmask_b32_e64 v100, v99, v96, s[6:7]
	v_cndmask_b32_e64 v96, v96, v103, s[6:7]
	v_cvt_pk_bf16_f32 v100, v100, v96
	v_add_co_u32_e32 v32, vcc, 0x1000, v130
	s_nop 1
	v_addc_co_u32_e32 v33, vcc, 0, v131, vcc
	global_store_dword v[32:33], v100, off offset:2240
	v_cndmask_b32_e64 v32, v88, v92, s[8:9]
	s_nop 1
	v_mov_b32_dpp v96, v32 quad_perm:[1,0,3,2] row_mask:0xf bank_mask:0xf bound_ctrl:1
	v_cndmask_b32_e64 v98, v88, v96, s[6:7]
	v_cndmask_b32_e64 v96, v96, v92, s[6:7]
	v_cvt_pk_bf16_f32 v98, v98, v96
	v_lshl_add_u64 v[96:97], v[128:129], 0, v[176:177]
	v_add_co_u32_e32 v32, vcc, 0x8000, v96
	s_nop 1
	v_addc_co_u32_e32 v33, vcc, 0, v97, vcc
	global_store_dword v[32:33], v98, off
	v_cndmask_b32_e64 v32, v80, v84, s[8:9]
	s_nop 1
	v_mov_b32_dpp v92, v32 quad_perm:[1,0,3,2] row_mask:0xf bank_mask:0xf bound_ctrl:1
	v_cndmask_b32_e64 v88, v80, v92, s[6:7]
	v_cndmask_b32_e64 v92, v92, v84, s[6:7]
	v_cvt_pk_bf16_f32 v88, v88, v92
	s_mov_b64 s[2:3], 0x8000
	v_cndmask_b32_e64 v32, v72, v76, s[8:9]
	v_lshl_add_u64 v[96:97], v[96:97], 0, s[2:3]
	global_store_dword v[96:97], v88, off offset:64
	v_mov_b32_dpp v84, v32 quad_perm:[1,0,3,2] row_mask:0xf bank_mask:0xf bound_ctrl:1
	v_cndmask_b32_e64 v80, v72, v84, s[6:7]
	v_cndmask_b32_e64 v84, v84, v76, s[6:7]
	v_cvt_pk_bf16_f32 v80, v80, v84
	v_cndmask_b32_e64 v32, v64, v68, s[8:9]
	global_store_dword v[96:97], v80, off offset:128
	s_nop 0
	v_mov_b32_dpp v76, v32 quad_perm:[1,0,3,2] row_mask:0xf bank_mask:0xf bound_ctrl:1
	v_cndmask_b32_e64 v72, v64, v76, s[6:7]
	v_cndmask_b32_e64 v76, v76, v68, s[6:7]
	v_cvt_pk_bf16_f32 v72, v72, v76
	v_cndmask_b32_e64 v32, v89, v93, s[8:9]
	global_store_dword v[96:97], v72, off offset:192
	s_nop 0
	v_mov_b32_dpp v68, v32 quad_perm:[1,0,3,2] row_mask:0xf bank_mask:0xf bound_ctrl:1
	v_cndmask_b32_e64 v64, v89, v68, s[6:7]
	v_cndmask_b32_e64 v68, v68, v93, s[6:7]
	v_cvt_pk_bf16_f32 v64, v64, v68
	v_cndmask_b32_e64 v32, v81, v85, s[8:9]
	global_store_dword v[96:97], v64, off offset:2048
	s_nop 0
	v_mov_b32_dpp v68, v32 quad_perm:[1,0,3,2] row_mask:0xf bank_mask:0xf bound_ctrl:1
	v_cndmask_b32_e64 v64, v81, v68, s[6:7]
	v_cndmask_b32_e64 v68, v68, v85, s[6:7]
	v_cvt_pk_bf16_f32 v64, v64, v68
	v_cndmask_b32_e64 v32, v73, v77, s[8:9]
	global_store_dword v[96:97], v64, off offset:2112
	s_nop 0
	v_mov_b32_dpp v68, v32 quad_perm:[1,0,3,2] row_mask:0xf bank_mask:0xf bound_ctrl:1
	v_cndmask_b32_e64 v64, v73, v68, s[6:7]
	v_cndmask_b32_e64 v68, v68, v77, s[6:7]
	v_cvt_pk_bf16_f32 v64, v64, v68
	v_cndmask_b32_e64 v32, v65, v69, s[8:9]
	global_store_dword v[96:97], v64, off offset:2176
	s_nop 0
	v_mov_b32_dpp v68, v32 quad_perm:[1,0,3,2] row_mask:0xf bank_mask:0xf bound_ctrl:1
	v_cndmask_b32_e64 v64, v65, v68, s[6:7]
	v_cndmask_b32_e64 v68, v68, v69, s[6:7]
	v_cvt_pk_bf16_f32 v64, v64, v68
	v_cndmask_b32_e64 v32, v90, v94, s[8:9]
	global_store_dword v[96:97], v64, off offset:2240
	s_nop 0
	v_mov_b32_dpp v65, v32 quad_perm:[1,0,3,2] row_mask:0xf bank_mask:0xf bound_ctrl:1
	v_cndmask_b32_e64 v64, v90, v65, s[6:7]
	v_cndmask_b32_e64 v65, v65, v94, s[6:7]
	v_cvt_pk_bf16_f32 v64, v64, v65
	v_add_co_u32_e32 v32, vcc, 0x1000, v96
	s_nop 1
	v_addc_co_u32_e32 v33, vcc, 0, v97, vcc
	global_store_dword v[32:33], v64, off
	v_cndmask_b32_e64 v32, v82, v86, s[8:9]
	s_nop 1
	v_mov_b32_dpp v65, v32 quad_perm:[1,0,3,2] row_mask:0xf bank_mask:0xf bound_ctrl:1
	v_cndmask_b32_e64 v64, v82, v65, s[6:7]
	v_cndmask_b32_e64 v65, v65, v86, s[6:7]
	v_cvt_pk_bf16_f32 v64, v64, v65
	v_add_co_u32_e32 v32, vcc, 0x1000, v96
	s_nop 1
	v_addc_co_u32_e32 v33, vcc, 0, v97, vcc
	global_store_dword v[32:33], v64, off offset:64
	v_cndmask_b32_e64 v32, v74, v78, s[8:9]
	s_nop 1
	v_mov_b32_dpp v65, v32 quad_perm:[1,0,3,2] row_mask:0xf bank_mask:0xf bound_ctrl:1
	v_cndmask_b32_e64 v64, v74, v65, s[6:7]
	v_cndmask_b32_e64 v65, v65, v78, s[6:7]
	v_cvt_pk_bf16_f32 v64, v64, v65
	v_add_co_u32_e32 v32, vcc, 0x1000, v96
	s_nop 1
	v_addc_co_u32_e32 v33, vcc, 0, v97, vcc
	global_store_dword v[32:33], v64, off offset:128
	v_cndmask_b32_e64 v32, v66, v70, s[8:9]
	s_nop 1
	v_mov_b32_dpp v65, v32 quad_perm:[1,0,3,2] row_mask:0xf bank_mask:0xf bound_ctrl:1
	v_cndmask_b32_e64 v64, v66, v65, s[6:7]
	v_cndmask_b32_e64 v65, v65, v70, s[6:7]
	v_cvt_pk_bf16_f32 v64, v64, v65
	v_add_co_u32_e32 v32, vcc, 0x1000, v96
	s_nop 1
	v_addc_co_u32_e32 v33, vcc, 0, v97, vcc
	global_store_dword v[32:33], v64, off offset:192
	v_cndmask_b32_e64 v32, v91, v95, s[8:9]
	s_nop 1
	v_mov_b32_dpp v65, v32 quad_perm:[1,0,3,2] row_mask:0xf bank_mask:0xf bound_ctrl:1
	v_cndmask_b32_e64 v64, v91, v65, s[6:7]
	v_cndmask_b32_e64 v65, v65, v95, s[6:7]
	v_cvt_pk_bf16_f32 v64, v64, v65
	v_add_co_u32_e32 v32, vcc, 0x1000, v96
	s_nop 1
	v_addc_co_u32_e32 v33, vcc, 0, v97, vcc
	global_store_dword v[32:33], v64, off offset:2048
	v_cndmask_b32_e64 v32, v83, v87, s[8:9]
	s_nop 1
	v_mov_b32_dpp v65, v32 quad_perm:[1,0,3,2] row_mask:0xf bank_mask:0xf bound_ctrl:1
	v_cndmask_b32_e64 v64, v83, v65, s[6:7]
	v_cndmask_b32_e64 v65, v65, v87, s[6:7]
	v_cvt_pk_bf16_f32 v64, v64, v65
	v_add_co_u32_e32 v32, vcc, 0x1000, v96
	s_nop 1
	v_addc_co_u32_e32 v33, vcc, 0, v97, vcc
	global_store_dword v[32:33], v64, off offset:2112
	v_cndmask_b32_e64 v32, v75, v79, s[8:9]
	s_nop 1
	v_mov_b32_dpp v65, v32 quad_perm:[1,0,3,2] row_mask:0xf bank_mask:0xf bound_ctrl:1
	v_cndmask_b32_e64 v64, v75, v65, s[6:7]
; #define SBAR() __builtin_amdgcn_sched_barrier(0)
; DEVFI float dpp_xor1(float x) { return __int_as_float(__builtin_amdgcn_update_dpp(0, __float_as_int(x), 0xB1, 0xF, 0xF, true)); }
; DEVFI void store_nat_m(bfraw* base, long ld, f32x4 (&a)[8], int fr) {
;   const bool odd = fr & 1;
;   bfraw* p0 = base + (odd ? 15 + fr : fr);
; #pragma unroll
;   for (int j = 0; j < 4; ++j)
; #pragma unroll
;     for (int n0 = 0; n0 < 8; n0 += 2) { const float own0 = a[n0][j], own1 = a[n0 + 1][j];
;       const float recv = dpp_xor1(odd ? own0 : own1);
;       const unsigned pk = odd ? cvtpk(recv, own1) : cvtpk(own0, recv);
;       *reinterpret_cast<unsigned*>(p0 + (long)j * ld + n0 * 16) = pk; }
; }
; DEVFI void store_nat(bfraw* dst, long ld, f32x4 (&acc)[4][8], int fr, int fq) {
;   store_nat_m(dst + (long)(0 * 16 + fq * 4) * ld, ld, acc[0], fr); SBAR();
;   store_nat_m(dst + (long)(1 * 16 + fq * 4) * ld, ld, acc[1], fr); SBAR();
;   store_nat_m(dst + (long)(2 * 16 + fq * 4) * ld, ld, acc[2], fr); SBAR();
;   store_nat_m(dst + (long)(3 * 16 + fq * 4) * ld, ld, acc[3], fr); SBAR();
; }
	v_cndmask_b32_e64 v65, v65, v79, s[6:7]
	v_cvt_pk_bf16_f32 v64, v64, v65
	v_add_co_u32_e32 v32, vcc, 0x1000, v96
	s_nop 1
	v_addc_co_u32_e32 v33, vcc, 0, v97, vcc
	global_store_dword v[32:33], v64, off offset:2176
	v_cndmask_b32_e64 v32, v67, v71, s[8:9]
	s_nop 1
	v_mov_b32_dpp v64, v32 quad_perm:[1,0,3,2] row_mask:0xf bank_mask:0xf bound_ctrl:1
	v_cndmask_b32_e64 v68, v67, v64, s[6:7]
	v_cndmask_b32_e64 v64, v64, v71, s[6:7]
	v_cvt_pk_bf16_f32 v68, v68, v64
	v_add_co_u32_e32 v32, vcc, 0x1000, v96
	s_nop 1
	v_addc_co_u32_e32 v33, vcc, 0, v97, vcc
	global_store_dword v[32:33], v68, off offset:2240
	v_cndmask_b32_e64 v32, v56, v60, s[8:9]
	s_nop 1
	v_mov_b32_dpp v64, v32 quad_perm:[1,0,3,2] row_mask:0xf bank_mask:0xf bound_ctrl:1
	v_cndmask_b32_e64 v66, v56, v64, s[6:7]
	v_cndmask_b32_e64 v64, v64, v60, s[6:7]
	v_cvt_pk_bf16_f32 v66, v66, v64
	v_lshl_add_u64 v[64:65], v[128:129], 0, v[176:177]
	v_add_co_u32_e32 v32, vcc, 0x10000, v64
	s_nop 1
	v_addc_co_u32_e32 v33, vcc, 0, v65, vcc
	global_store_dword v[32:33], v66, off
	v_cndmask_b32_e64 v32, v48, v52, s[8:9]
	s_nop 1
	v_mov_b32_dpp v60, v32 quad_perm:[1,0,3,2] row_mask:0xf bank_mask:0xf bound_ctrl:1
	v_cndmask_b32_e64 v56, v48, v60, s[6:7]
	v_cndmask_b32_e64 v60, v60, v52, s[6:7]
	v_cvt_pk_bf16_f32 v56, v56, v60
	v_cndmask_b32_e64 v32, v40, v44, s[8:9]
	v_lshl_add_u64 v[64:65], v[64:65], 0, s[48:49]
	global_store_dword v[64:65], v56, off offset:64
	v_mov_b32_dpp v52, v32 quad_perm:[1,0,3,2] row_mask:0xf bank_mask:0xf bound_ctrl:1
	v_cndmask_b32_e64 v48, v40, v52, s[6:7]
	v_cndmask_b32_e64 v52, v52, v44, s[6:7]
	v_cvt_pk_bf16_f32 v48, v48, v52
	v_cndmask_b32_e64 v32, v144, v36, s[8:9]
	global_store_dword v[64:65], v48, off offset:128
	s_nop 0
	v_mov_b32_dpp v44, v32 quad_perm:[1,0,3,2] row_mask:0xf bank_mask:0xf bound_ctrl:1
	v_cndmask_b32_e64 v40, v144, v44, s[6:7]
	v_cndmask_b32_e64 v44, v44, v36, s[6:7]
	v_cvt_pk_bf16_f32 v40, v40, v44
	v_cndmask_b32_e64 v32, v57, v61, s[8:9]
	global_store_dword v[64:65], v40, off offset:192
	s_nop 0
	v_mov_b32_dpp v36, v32 quad_perm:[1,0,3,2] row_mask:0xf bank_mask:0xf bound_ctrl:1
	v_cndmask_b32_e64 v32, v57, v36, s[6:7]
	v_cndmask_b32_e64 v36, v36, v61, s[6:7]
	v_cvt_pk_bf16_f32 v32, v32, v36
	global_store_dword v[64:65], v32, off offset:2048
	v_cndmask_b32_e64 v32, v49, v53, s[8:9]
	s_nop 1
	v_mov_b32_dpp v36, v32 quad_perm:[1,0,3,2] row_mask:0xf bank_mask:0xf bound_ctrl:1
	v_cndmask_b32_e64 v32, v49, v36, s[6:7]
	v_cndmask_b32_e64 v36, v36, v53, s[6:7]
	v_cvt_pk_bf16_f32 v32, v32, v36
	global_store_dword v[64:65], v32, off offset:2112
	v_cndmask_b32_e64 v32, v41, v45, s[8:9]
	s_nop 1
	v_mov_b32_dpp v36, v32 quad_perm:[1,0,3,2] row_mask:0xf bank_mask:0xf bound_ctrl:1
	v_cndmask_b32_e64 v32, v41, v36, s[6:7]
	v_cndmask_b32_e64 v36, v36, v45, s[6:7]
	v_cvt_pk_bf16_f32 v32, v32, v36
	global_store_dword v[64:65], v32, off offset:2176
	v_cndmask_b32_e64 v32, v145, v37, s[8:9]
	s_nop 1
	v_mov_b32_dpp v36, v32 quad_perm:[1,0,3,2] row_mask:0xf bank_mask:0xf bound_ctrl:1
	v_cndmask_b32_e64 v32, v145, v36, s[6:7]
	v_cndmask_b32_e64 v36, v36, v37, s[6:7]
	v_cvt_pk_bf16_f32 v32, v32, v36
	global_store_dword v[64:65], v32, off offset:2240
	v_cndmask_b32_e64 v32, v58, v62, s[8:9]
	s_nop 1
	v_mov_b32_dpp v33, v32 quad_perm:[1,0,3,2] row_mask:0xf bank_mask:0xf bound_ctrl:1
	v_cndmask_b32_e64 v32, v58, v33, s[6:7]
	v_cndmask_b32_e64 v33, v33, v62, s[6:7]
	v_cvt_pk_bf16_f32 v32, v32, v33
	v_add_co_u32_e32 v34, vcc, 0x1000, v64
	s_nop 1
	v_addc_co_u32_e32 v35, vcc, 0, v65, vcc
	global_store_dword v[34:35], v32, off
	v_cndmask_b32_e64 v32, v50, v54, s[8:9]
	s_nop 1
	v_mov_b32_dpp v33, v32 quad_perm:[1,0,3,2] row_mask:0xf bank_mask:0xf bound_ctrl:1
	v_cndmask_b32_e64 v32, v50, v33, s[6:7]
	v_cndmask_b32_e64 v33, v33, v54, s[6:7]
	v_cvt_pk_bf16_f32 v32, v32, v33
	v_add_co_u32_e32 v34, vcc, 0x1000, v64
	s_nop 1
	v_addc_co_u32_e32 v35, vcc, 0, v65, vcc
	global_store_dword v[34:35], v32, off offset:64
	v_cndmask_b32_e64 v32, v42, v46, s[8:9]
	s_nop 1
	v_mov_b32_dpp v33, v32 quad_perm:[1,0,3,2] row_mask:0xf bank_mask:0xf bound_ctrl:1
	v_cndmask_b32_e64 v32, v42, v33, s[6:7]
	v_cndmask_b32_e64 v33, v33, v46, s[6:7]
	v_cvt_pk_bf16_f32 v32, v32, v33
	v_add_co_u32_e32 v34, vcc, 0x1000, v64
	s_nop 1
	v_addc_co_u32_e32 v35, vcc, 0, v65, vcc
	global_store_dword v[34:35], v32, off offset:128
	v_cndmask_b32_e64 v32, v146, v38, s[8:9]
	s_nop 1
	v_mov_b32_dpp v33, v32 quad_perm:[1,0,3,2] row_mask:0xf bank_mask:0xf bound_ctrl:1
	v_cndmask_b32_e64 v32, v146, v33, s[6:7]
	v_cndmask_b32_e64 v33, v33, v38, s[6:7]
	v_cvt_pk_bf16_f32 v32, v32, v33
	v_add_co_u32_e32 v34, vcc, 0x1000, v64
	s_nop 1
	v_addc_co_u32_e32 v35, vcc, 0, v65, vcc
	global_store_dword v[34:35], v32, off offset:192
	v_cndmask_b32_e64 v32, v59, v63, s[8:9]
	s_nop 1
	v_mov_b32_dpp v33, v32 quad_perm:[1,0,3,2] row_mask:0xf bank_mask:0xf bound_ctrl:1
	v_cndmask_b32_e64 v32, v59, v33, s[6:7]
	v_cndmask_b32_e64 v33, v33, v63, s[6:7]
	v_cvt_pk_bf16_f32 v32, v32, v33
	v_add_co_u32_e32 v34, vcc, 0x1000, v64
	s_nop 1
	v_addc_co_u32_e32 v35, vcc, 0, v65, vcc
	global_store_dword v[34:35], v32, off offset:2048
	v_cndmask_b32_e64 v32, v51, v55, s[8:9]
	s_nop 1
	v_mov_b32_dpp v33, v32 quad_perm:[1,0,3,2] row_mask:0xf bank_mask:0xf bound_ctrl:1
	v_cndmask_b32_e64 v32, v51, v33, s[6:7]
	v_cndmask_b32_e64 v33, v33, v55, s[6:7]
	v_cvt_pk_bf16_f32 v32, v32, v33
	v_add_co_u32_e32 v34, vcc, 0x1000, v64
	s_nop 1
	v_addc_co_u32_e32 v35, vcc, 0, v65, vcc
	global_store_dword v[34:35], v32, off offset:2112
	v_cndmask_b32_e64 v32, v43, v47, s[8:9]
	s_nop 1
	v_mov_b32_dpp v33, v32 quad_perm:[1,0,3,2] row_mask:0xf bank_mask:0xf bound_ctrl:1
; #define SBAR() __builtin_amdgcn_sched_barrier(0)
; DEVFI float dpp_xor1(float x) { return __int_as_float(__builtin_amdgcn_update_dpp(0, __float_as_int(x), 0xB1, 0xF, 0xF, true)); }
; DEVFI void store_nat_m(bfraw* base, long ld, f32x4 (&a)[8], int fr) {
;   const bool odd = fr & 1;
;   bfraw* p0 = base + (odd ? 15 + fr : fr);
; #pragma unroll
;   for (int j = 0; j < 4; ++j)
; #pragma unroll
;     for (int n0 = 0; n0 < 8; n0 += 2) { const float own0 = a[n0][j], own1 = a[n0 + 1][j];
;       const float recv = dpp_xor1(odd ? own0 : own1);
;       const unsigned pk = odd ? cvtpk(recv, own1) : cvtpk(own0, recv);
;       *reinterpret_cast<unsigned*>(p0 + (long)j * ld + n0 * 16) = pk; }
; }
; DEVFI void store_nat(bfraw* dst, long ld, f32x4 (&acc)[4][8], int fr, int fq) {
;   store_nat_m(dst + (long)(0 * 16 + fq * 4) * ld, ld, acc[0], fr); SBAR();
;   store_nat_m(dst + (long)(1 * 16 + fq * 4) * ld, ld, acc[1], fr); SBAR();
;   store_nat_m(dst + (long)(2 * 16 + fq * 4) * ld, ld, acc[2], fr); SBAR();
;   store_nat_m(dst + (long)(3 * 16 + fq * 4) * ld, ld, acc[3], fr); SBAR();
; }
	v_cndmask_b32_e64 v32, v43, v33, s[6:7]
	v_cndmask_b32_e64 v33, v33, v47, s[6:7]
	v_cvt_pk_bf16_f32 v32, v32, v33
	v_add_co_u32_e32 v34, vcc, 0x1000, v64
	s_nop 1
	v_addc_co_u32_e32 v35, vcc, 0, v65, vcc
	global_store_dword v[34:35], v32, off offset:2176
	v_cndmask_b32_e64 v32, v147, v39, s[8:9]
	s_nop 1
	v_mov_b32_dpp v32, v32 quad_perm:[1,0,3,2] row_mask:0xf bank_mask:0xf bound_ctrl:1
	v_cndmask_b32_e64 v36, v147, v32, s[6:7]
	v_cndmask_b32_e64 v32, v32, v39, s[6:7]
	v_cvt_pk_bf16_f32 v36, v36, v32
	v_add_co_u32_e32 v32, vcc, 0x1000, v64
	s_nop 1
	v_addc_co_u32_e32 v33, vcc, 0, v65, vcc
	global_store_dword v[32:33], v36, off offset:2240
	v_cndmask_b32_e64 v32, v24, v28, s[8:9]
	s_nop 1
	v_mov_b32_dpp v32, v32 quad_perm:[1,0,3,2] row_mask:0xf bank_mask:0xf bound_ctrl:1
	v_cndmask_b32_e64 v34, v24, v32, s[6:7]
	v_cndmask_b32_e64 v32, v32, v28, s[6:7]
	v_cvt_pk_bf16_f32 v34, v34, v32
	v_lshl_add_u64 v[32:33], v[128:129], 0, v[176:177]
	v_add_co_u32_e32 v36, vcc, 0x18000, v32
	v_cndmask_b32_e64 v24, v16, v20, s[8:9]
	s_nop 0
	v_addc_co_u32_e32 v37, vcc, 0, v33, vcc
	v_mov_b32_dpp v28, v24 quad_perm:[1,0,3,2] row_mask:0xf bank_mask:0xf bound_ctrl:1
	global_store_dword v[36:37], v34, off
	v_cndmask_b32_e64 v24, v16, v28, s[6:7]
	v_cndmask_b32_e64 v28, v28, v20, s[6:7]
	v_cvt_pk_bf16_f32 v24, v24, v28
	s_mov_b64 s[2:3], 0x18000
	v_cndmask_b32_e64 v16, v8, v12, s[8:9]
	v_lshl_add_u64 v[32:33], v[32:33], 0, s[2:3]
	global_store_dword v[32:33], v24, off offset:64
	v_mov_b32_dpp v20, v16 quad_perm:[1,0,3,2] row_mask:0xf bank_mask:0xf bound_ctrl:1
	v_cndmask_b32_e64 v16, v8, v20, s[6:7]
	v_cndmask_b32_e64 v20, v20, v12, s[6:7]
	v_cvt_pk_bf16_f32 v16, v16, v20
	v_cndmask_b32_e64 v8, v0, v4, s[8:9]
	global_store_dword v[32:33], v16, off offset:128
	s_nop 0
	v_mov_b32_dpp v12, v8 quad_perm:[1,0,3,2] row_mask:0xf bank_mask:0xf bound_ctrl:1
	v_cndmask_b32_e64 v8, v0, v12, s[6:7]
	v_cndmask_b32_e64 v12, v12, v4, s[6:7]
	v_cvt_pk_bf16_f32 v8, v8, v12
	v_cndmask_b32_e64 v0, v25, v29, s[8:9]
	global_store_dword v[32:33], v8, off offset:192
	s_nop 0
	v_mov_b32_dpp v4, v0 quad_perm:[1,0,3,2] row_mask:0xf bank_mask:0xf bound_ctrl:1
	v_cndmask_b32_e64 v0, v25, v4, s[6:7]
	v_cndmask_b32_e64 v4, v4, v29, s[6:7]
	v_cvt_pk_bf16_f32 v0, v0, v4
	global_store_dword v[32:33], v0, off offset:2048
	v_cndmask_b32_e64 v0, v17, v21, s[8:9]
	s_nop 1
	v_mov_b32_dpp v4, v0 quad_perm:[1,0,3,2] row_mask:0xf bank_mask:0xf bound_ctrl:1
	v_cndmask_b32_e64 v0, v17, v4, s[6:7]
	v_cndmask_b32_e64 v4, v4, v21, s[6:7]
	v_cvt_pk_bf16_f32 v0, v0, v4
	global_store_dword v[32:33], v0, off offset:2112
	v_cndmask_b32_e64 v0, v9, v13, s[8:9]
	s_nop 1
	v_mov_b32_dpp v4, v0 quad_perm:[1,0,3,2] row_mask:0xf bank_mask:0xf bound_ctrl:1
	v_cndmask_b32_e64 v0, v9, v4, s[6:7]
	v_cndmask_b32_e64 v4, v4, v13, s[6:7]
	v_cvt_pk_bf16_f32 v0, v0, v4
	global_store_dword v[32:33], v0, off offset:2176
	v_cndmask_b32_e64 v0, v1, v5, s[8:9]
	s_nop 1
	v_mov_b32_dpp v4, v0 quad_perm:[1,0,3,2] row_mask:0xf bank_mask:0xf bound_ctrl:1
	v_cndmask_b32_e64 v0, v1, v4, s[6:7]
	v_cndmask_b32_e64 v4, v4, v5, s[6:7]
	v_cvt_pk_bf16_f32 v0, v0, v4
	global_store_dword v[32:33], v0, off offset:2240
	v_cndmask_b32_e64 v0, v26, v30, s[8:9]
	s_nop 1
	v_mov_b32_dpp v1, v0 quad_perm:[1,0,3,2] row_mask:0xf bank_mask:0xf bound_ctrl:1
	v_cndmask_b32_e64 v0, v26, v1, s[6:7]
	v_cndmask_b32_e64 v1, v1, v30, s[6:7]
	v_cvt_pk_bf16_f32 v0, v0, v1
	v_add_co_u32_e32 v4, vcc, 0x1000, v32
	s_nop 1
	v_addc_co_u32_e32 v5, vcc, 0, v33, vcc
	global_store_dword v[4:5], v0, off
	v_cndmask_b32_e64 v0, v18, v22, s[8:9]
	s_nop 1
	v_mov_b32_dpp v1, v0 quad_perm:[1,0,3,2] row_mask:0xf bank_mask:0xf bound_ctrl:1
	v_cndmask_b32_e64 v0, v18, v1, s[6:7]
	v_cndmask_b32_e64 v1, v1, v22, s[6:7]
	v_cvt_pk_bf16_f32 v0, v0, v1
	v_add_co_u32_e32 v4, vcc, 0x1000, v32
	s_nop 1
	v_addc_co_u32_e32 v5, vcc, 0, v33, vcc
	global_store_dword v[4:5], v0, off offset:64
	v_cndmask_b32_e64 v0, v10, v14, s[8:9]
	s_nop 1
	v_mov_b32_dpp v1, v0 quad_perm:[1,0,3,2] row_mask:0xf bank_mask:0xf bound_ctrl:1
	v_cndmask_b32_e64 v0, v10, v1, s[6:7]
	v_cndmask_b32_e64 v1, v1, v14, s[6:7]
	v_cvt_pk_bf16_f32 v0, v0, v1
	v_add_co_u32_e32 v4, vcc, 0x1000, v32
	s_nop 1
	v_addc_co_u32_e32 v5, vcc, 0, v33, vcc
	global_store_dword v[4:5], v0, off offset:128
	v_cndmask_b32_e64 v0, v2, v6, s[8:9]
	s_nop 1
	v_mov_b32_dpp v1, v0 quad_perm:[1,0,3,2] row_mask:0xf bank_mask:0xf bound_ctrl:1
	v_cndmask_b32_e64 v0, v2, v1, s[6:7]
	v_cndmask_b32_e64 v1, v1, v6, s[6:7]
	v_cvt_pk_bf16_f32 v0, v0, v1
	v_add_co_u32_e32 v4, vcc, 0x1000, v32
	s_nop 1
	v_addc_co_u32_e32 v5, vcc, 0, v33, vcc
	global_store_dword v[4:5], v0, off offset:192
	v_cndmask_b32_e64 v0, v27, v31, s[8:9]
	s_nop 1
	v_mov_b32_dpp v1, v0 quad_perm:[1,0,3,2] row_mask:0xf bank_mask:0xf bound_ctrl:1
	v_cndmask_b32_e64 v0, v27, v1, s[6:7]
	v_cndmask_b32_e64 v1, v1, v31, s[6:7]
	v_cvt_pk_bf16_f32 v0, v0, v1
	v_add_co_u32_e32 v4, vcc, 0x1000, v32
	s_nop 1
	v_addc_co_u32_e32 v5, vcc, 0, v33, vcc
	global_store_dword v[4:5], v0, off offset:2048
	v_cndmask_b32_e64 v0, v19, v23, s[8:9]
	s_nop 1
	v_mov_b32_dpp v1, v0 quad_perm:[1,0,3,2] row_mask:0xf bank_mask:0xf bound_ctrl:1
	v_cndmask_b32_e64 v0, v19, v1, s[6:7]
	v_cndmask_b32_e64 v1, v1, v23, s[6:7]
	v_cvt_pk_bf16_f32 v0, v0, v1
	v_add_co_u32_e32 v4, vcc, 0x1000, v32
	s_nop 1
	v_addc_co_u32_e32 v5, vcc, 0, v33, vcc
	global_store_dword v[4:5], v0, off offset:2112
	v_cndmask_b32_e64 v0, v11, v15, s[8:9]
	s_nop 1
	v_mov_b32_dpp v1, v0 quad_perm:[1,0,3,2] row_mask:0xf bank_mask:0xf bound_ctrl:1
	v_cndmask_b32_e64 v0, v11, v1, s[6:7]
	v_cndmask_b32_e64 v1, v1, v15, s[6:7]
	v_cvt_pk_bf16_f32 v0, v0, v1
	v_add_co_u32_e32 v4, vcc, 0x1000, v32
	s_nop 1
	v_addc_co_u32_e32 v5, vcc, 0, v33, vcc
	global_store_dword v[4:5], v0, off offset:2176
	v_cndmask_b32_e64 v0, v3, v7, s[8:9]
	s_nop 1
	v_mov_b32_dpp v0, v0 quad_perm:[1,0,3,2] row_mask:0xf bank_mask:0xf bound_ctrl:1
	s_and_saveexec_b64 s[2:3], s[6:7]
	s_xor_b64 s[2:3], exec, s[2:3]
	s_cbranch_execz .LBB0_4051
	v_cvt_pk_bf16_f32 v4, v0, v7

; DEVFI int opaque_tid(const int wv) { return (wv << 6) | lane_opaque(); }
; #define WAIT_V0() asm volatile("s_waitcnt vmcnt(0)" ::: "memory")
; DEVFI void gemm_stage(const TileSrc& t, const int buf, const int kt, char* shm, const int wid, const int lane) {
;   int R, C; stage_rc<G_KS>(wid * 1024 + lane * 16, R, C);
;   const int oa = R * t.lda + C, ob = R * t.ldb + C;
; #pragma unroll
;   for (int i = 0; i < G_GL; ++i) {
;     __builtin_amdgcn_global_load_lds((const unsigned*)(t.A + (i * 64 * t.lda + kt * G_BK) + oa), (unsigned*)(shm + buf * G_STAGE_B + wid * 1024 + i * 8192), 16, 0, 0);
;     __builtin_amdgcn_global_load_lds((const unsigned*)(t.B + (i * 64 * t.ldb + kt * G_BK) + ob), (unsigned*)(shm + buf * G_STAGE_B + G_TILE_B + wid * 1024 + i * 8192), 16, 0, 0); }
; }
; DEVFI void gemm_issue0(const TileSrc& t, char* shm, const int wv) { const int tid = opaque_tid(wv); gemm_stage(t, 0, 0, shm, tid >> 6, tid & 63); }
; template <class Epi>
; DEVFI void gemm_main(const TileSrc t, const int K, char* shm, const bool pf, const TileSrc nx, const int wv, Epi epi) {
;   const int tid = opaque_tid(wv), wid = tid >> 6, lane = tid & 63, wr = wid >> 1, wc = wid & 1, fr = lane & 15, fq = lane >> 4;
;     ...
;   f32x4 acc[4][8] = {};
;   const int nt = K / G_BK;
;   const int sw = (fr * 64 + fq * 16) ^ ((fr >> 3) << 5);
;   const char* aBase = shm + wr * 8192 + sw;
;   const char* bBase = shm + G_TILE_B + wc * 16384 + sw;
;   WAIT_V0(); __syncthreads();
.LBB0_4068:
	s_mov_b32 s19, -1
	s_ashr_i32 s21, s33, 7
	v_mbcnt_lo_u32_b32 v0, s19, 0
	v_mbcnt_hi_u32_b32 v135, s19, v0
	v_or_b32_e32 v0, s33, v135
	v_ashrrev_i32_e32 v137, 6, v0
	v_and_b32_e32 v134, 1, v137
	v_and_b32_e32 v132, 15, v135
	v_and_b32_e32 v0, 48, v135
	v_lshlrev_b32_e32 v1, 2, v135
	v_lshl_or_b32 v0, v132, 6, v0
	v_and_b32_e32 v1, 32, v1
	s_lshl_b32 s19, s21, 13
	v_lshlrev_b32_e32 v2, 14, v134
	v_bitop3_b32 v141, s19, v0, v1 bitop3:0xf6
	v_bitop3_b32 v142, v2, v0, v1 bitop3:0xf6
	v_lshlrev_b32_e32 v0, 4, v135
	v_and_b32_e32 v1, 32, v135
	v_lshrrev_b32_e32 v2, 31, v137
	v_add_u32_e32 v2, v137, v2
	v_bitop3_b32 v0, v0, v1, 48 bitop3:0x6c
	v_ashrrev_i32_e32 v138, 1, v2
	v_lshrrev_b32_e32 v139, 1, v0
	v_lshlrev_b32_e32 v0, 8, v135
	v_and_b32_e32 v140, 0x3c00, v0
	v_mul_lo_u32 v0, v138, s66
	v_or_b32_e32 v0, v139, v0
	v_lshlrev_b32_e32 v1, 5, v137
	v_add3_u32 v0, v0, v140, v1
	v_ashrrev_i32_e32 v1, 31, v0
	s_waitcnt vmcnt(0)
	v_lshlrev_b64 v[0:1], 1, v[0:1]
	v_lshl_add_u64 v[128:129], s[8:9], 0, v[0:1]
	v_lshl_add_u64 v[130:131], s[2:3], 0, v[0:1]
	v_mov_b32_e32 v0, 0
	s_mov_b32 s18, 0
	v_and_b32_e32 v133, 63, v135
	v_lshlrev_b32_e32 v136, 10, v137
	s_mov_b64 s[8:9], 0
	v_mov_b32_e32 v1, v0
	v_mov_b32_e32 v2, v0
	v_mov_b32_e32 v3, v0
	v_mov_b32_e32 v4, v0
	v_mov_b32_e32 v5, v0
	v_mov_b32_e32 v6, v0
	v_mov_b32_e32 v7, v0
	v_mov_b32_e32 v8, v0
	v_mov_b32_e32 v9, v0
	v_mov_b32_e32 v10, v0
	v_mov_b32_e32 v11, v0
	v_mov_b32_e32 v12, v0
	v_mov_b32_e32 v13, v0
	v_mov_b32_e32 v14, v0
	v_mov_b32_e32 v15, v0
	v_mov_b32_e32 v16, v0
	v_mov_b32_e32 v17, v0
	v_mov_b32_e32 v18, v0
	v_mov_b32_e32 v19, v0
	v_mov_b32_e32 v20, v0
	v_mov_b32_e32 v21, v0
	v_mov_b32_e32 v22, v0
	v_mov_b32_e32 v23, v0
	v_mov_b32_e32 v24, v0
	v_mov_b32_e32 v25, v0
	v_mov_b32_e32 v26, v0
	v_mov_b32_e32 v27, v0
	v_mov_b32_e32 v28, v0
	v_mov_b32_e32 v29, v0
	v_mov_b32_e32 v30, v0
	v_mov_b32_e32 v31, v0
	v_mov_b32_e32 v32, v0
	v_mov_b32_e32 v33, v0
	v_mov_b32_e32 v34, v0
	v_mov_b32_e32 v35, v0
	v_mov_b32_e32 v36, v0
	v_mov_b32_e32 v37, v0
	v_mov_b32_e32 v38, v0
	v_mov_b32_e32 v39, v0
	v_mov_b32_e32 v40, v0
	v_mov_b32_e32 v41, v0
	v_mov_b32_e32 v42, v0
	v_mov_b32_e32 v43, v0
	v_mov_b32_e32 v44, v0
	v_mov_b32_e32 v45, v0
	v_mov_b32_e32 v46, v0
	v_mov_b32_e32 v47, v0
	v_mov_b32_e32 v48, v0
	v_mov_b32_e32 v49, v0
	v_mov_b32_e32 v50, v0
	v_mov_b32_e32 v51, v0
	v_mov_b32_e32 v52, v0
	v_mov_b32_e32 v53, v0
	v_mov_b32_e32 v54, v0
	v_mov_b32_e32 v55, v0
	v_mov_b32_e32 v56, v0
	v_mov_b32_e32 v57, v0
	v_mov_b32_e32 v58, v0
	v_mov_b32_e32 v59, v0
	v_mov_b32_e32 v60, v0
	v_mov_b32_e32 v61, v0
	v_mov_b32_e32 v62, v0
	v_mov_b32_e32 v63, v0
	v_mov_b32_e32 v64, v0
	v_mov_b32_e32 v65, v0
	v_mov_b32_e32 v66, v0
	v_mov_b32_e32 v67, v0
	v_mov_b32_e32 v68, v0
	v_mov_b32_e32 v69, v0
	v_mov_b32_e32 v70, v0
	v_mov_b32_e32 v71, v0
	v_mov_b32_e32 v72, v0
	v_mov_b32_e32 v73, v0
	v_mov_b32_e32 v74, v0
	v_mov_b32_e32 v75, v0
	v_mov_b32_e32 v76, v0
	v_mov_b32_e32 v77, v0
	v_mov_b32_e32 v78, v0
	v_mov_b32_e32 v79, v0
	v_mov_b32_e32 v80, v0
	v_mov_b32_e32 v81, v0
	v_mov_b32_e32 v82, v0
	v_mov_b32_e32 v83, v0
	v_mov_b32_e32 v84, v0
	v_mov_b32_e32 v85, v0
	v_mov_b32_e32 v86, v0
	v_mov_b32_e32 v87, v0
	v_mov_b32_e32 v88, v0
	v_mov_b32_e32 v89, v0
	v_mov_b32_e32 v90, v0
	v_mov_b32_e32 v91, v0
	v_mov_b32_e32 v92, v0
	v_mov_b32_e32 v93, v0
	v_mov_b32_e32 v94, v0
	v_mov_b32_e32 v95, v0
	v_mov_b32_e32 v96, v0
	v_mov_b32_e32 v97, v0
	v_mov_b32_e32 v98, v0
	v_mov_b32_e32 v99, v0
	v_mov_b32_e32 v100, v0
	v_mov_b32_e32 v101, v0
	v_mov_b32_e32 v102, v0
	v_mov_b32_e32 v103, v0
	v_mov_b32_e32 v104, v0
	v_mov_b32_e32 v105, v0
	v_mov_b32_e32 v106, v0
	v_mov_b32_e32 v107, v0
	v_mov_b32_e32 v108, v0
	v_mov_b32_e32 v109, v0
	v_mov_b32_e32 v110, v0
	v_mov_b32_e32 v111, v0
	v_mov_b32_e32 v112, v0
	v_mov_b32_e32 v113, v0
	v_mov_b32_e32 v114, v0
	v_mov_b32_e32 v115, v0
	v_mov_b32_e32 v116, v0
	v_mov_b32_e32 v117, v0
	v_mov_b32_e32 v118, v0
	v_mov_b32_e32 v119, v0
	v_mov_b32_e32 v120, v0
	v_mov_b32_e32 v121, v0
	v_mov_b32_e32 v122, v0
	v_mov_b32_e32 v123, v0
	v_mov_b32_e32 v124, v0
	v_mov_b32_e32 v125, v0
	v_mov_b32_e32 v126, v0
	v_mov_b32_e32 v127, v0
	s_waitcnt lgkmcnt(0)
	s_lshr_b32 s2, s33, 6
	s_lshr_b32 s3, s2, 1
	s_sub_u32 s3, s2, s3
	s_mov_b32 s8, 0x20000
	s_lshr_b32 s9, s8, 2
	s_mul_i32 s3, s3, s9
	s_and_b32 s9, s2, 1
	s_lshl_b32 s9, s9, 6
	s_sub_u32 s3, s3, s9
	s_add_u32 s3, s3, 0x80
	s_lshl_b32 s18, s8, 1
	s_lshl_b32 s2, s2, 11
	s_mov_b32 vcc_hi, 0
	s_mov_b32 vcc_lo, s3
	v_lshl_add_u64 v[130:131], v[130:131], 0, vcc
	v_lshl_add_u64 v[128:129], v[128:129], 0, vcc
	s_mov_b32 vcc_lo, s18
	v_lshl_add_u64 v[224:225], v[130:131], 0, vcc
	v_lshl_add_u64 v[226:227], v[128:129], 0, vcc
	v_add_u32_e32 v143, 0x10000, v141
	v_add_u32_e32 v176, 0x10000, v142
	s_nop 0
	v_readfirstlane_b32 s8, v130
	v_readfirstlane_b32 s9, v131
	v_readfirstlane_b32 vcc_lo, v128
	v_readfirstlane_b32 vcc_hi, v129
	s_nop 1
	v_subrev_u32_e32 v130, s8, v130
	v_subrev_u32_e32 v128, vcc_lo, v128
	v_add_u32_e32 v224, s18, v130
	v_add_u32_e32 v226, s18, v128
	s_nop 4
	s_add_u32 m0, s2, 0x10000
	s_nop 0
	global_load_lds_dwordx4 v130, s[8:9]
	s_add_u32 m0, s2, 0x14000
	s_nop 0
	global_load_lds_dwordx4 v224, s[8:9]
	s_add_u32 s8, s8, 64
	s_addc_u32 s9, s9, 0
	s_add_u32 m0, s2, 0x18000
	s_nop 0
	global_load_lds_dwordx4 v128, vcc
	s_add_u32 m0, s2, 0x1c000
	s_nop 0
	global_load_lds_dwordx4 v226, vcc
	s_add_u32 vcc_lo, vcc_lo, 64
	s_addc_u32 vcc_hi, vcc_hi, 0
	s_add_u32 m0, s2, 0x10400
	s_nop 0
	global_load_lds_dwordx4 v130, s[8:9]
	s_add_u32 m0, s2, 0x14400
	s_nop 0
	global_load_lds_dwordx4 v224, s[8:9]
	s_add_u32 s8, s8, 64
	s_addc_u32 s9, s9, 0
	s_add_u32 m0, s2, 0x18400
	s_nop 0
	global_load_lds_dwordx4 v128, vcc
	s_add_u32 m0, s2, 0x1c400
	s_nop 0
	global_load_lds_dwordx4 v226, vcc
	s_add_u32 vcc_lo, vcc_lo, 64
	s_addc_u32 vcc_hi, vcc_hi, 0
	s_waitcnt vmcnt(8)
	s_barrier
	ds_read_b128 v[144:147], v141
	ds_read_b128 v[148:151], v141 offset:2048
	ds_read_b128 v[152:155], v141 offset:4096
	ds_read_b128 v[156:159], v141 offset:6144
	ds_read_b128 v[178:181], v142 offset:32768
	ds_read_b128 v[184:187], v142 offset:34816
	ds_read_b128 v[188:191], v142 offset:36864
	ds_read_b128 v[192:195], v142 offset:38912
	ds_read_b128 v[196:199], v142 offset:40960
	ds_read_b128 v[200:203], v142 offset:43008
	ds_read_b128 v[204:207], v142 offset:45056
	ds_read_b128 v[212:215], v142 offset:47104
	s_mov_b32 s3, 7
; #define SBAR() __builtin_amdgcn_sched_barrier(0)
; #define WAIT_V0() asm volatile("s_waitcnt vmcnt(0)" ::: "memory")
; #define GLDS_STAGE(buf, kt) gemm_stage(t, (buf), (kt), shm, wid, lane)
; template <class Epi>
; DEVFI void gemm_main(const TileSrc t, const int K, char* shm, const bool pf, const TileSrc nx, const int wv, Epi epi) {
;     ...
;   for (int t_ = 0; t_ < nt; ++t_) { const int cur = t_ & 1;
;     if (t_ + 1 < nt) GLDS_STAGE(cur ^ 1, t_ + 1);
; #pragma unroll
;     for (int ks = 0; ks < G_KS; ++ks) {
;       bf16x8 At[4], Bf[8];
; #pragma unroll
;       for (int n = 0; n < 8; ++n) Bf[n] = *(const bf16x8*)(bBase + cur * G_STAGE_B + (n * 2048 + ks * 1024));
;       SBAR();
;       At[0] = *(const bf16x8*)(aBase + cur * G_STAGE_B + (0 * 2048 + ks * 1024)); SBAR();
;       At[1] = *(const bf16x8*)(aBase + cur * G_STAGE_B + (1 * 2048 + ks * 1024)); SBAR();
;       At[2] = *(const bf16x8*)(aBase + cur * G_STAGE_B + (2 * 2048 + ks * 1024)); SBAR();
;       At[3] = *(const bf16x8*)(aBase + cur * G_STAGE_B + (3 * 2048 + ks * 1024));
;       SBAR();
;       __builtin_amdgcn_s_setprio(1);
; #pragma unroll
;       for (int m = 0; m < 4; ++m)
; #pragma unroll
;         for (int n = 0; n < 8; ++n) acc[m][n] = __builtin_amdgcn_mfma_f32_16x16x32_bf16(At[m], Bf[n], acc[m][n], 0, 0, 0);
;       __builtin_amdgcn_s_setprio(0);
;       SBAR();
;     }
;     WAIT_V0(); __syncthreads();
;   }
.LgkK_loop:
	s_waitcnt lgkmcnt(0)
	s_waitcnt vmcnt(8)
	s_barrier
	v_mfma_f32_16x16x32_bf16 v[120:123], v[144:147], v[178:181], v[120:123]
	ds_read_b128 v[160:163], v141 offset:1024
	s_add_u32 m0, s2, 0x0
	v_mfma_f32_16x16x32_bf16 v[88:91], v[148:151], v[178:181], v[88:91]
	ds_read_b128 v[164:167], v141 offset:3072
	v_mfma_f32_16x16x32_bf16 v[56:59], v[152:155], v[178:181], v[56:59]
	ds_read_b128 v[168:171], v141 offset:5120
	global_load_lds_dwordx4 v130, s[8:9]
	v_mfma_f32_16x16x32_bf16 v[24:27], v[156:159], v[178:181], v[24:27]
	ds_read_b128 v[172:175], v141 offset:7168
	v_mfma_f32_16x16x32_bf16 v[124:127], v[144:147], v[184:187], v[124:127]
	ds_read_b128 v[208:211], v142 offset:46080
	v_mfma_f32_16x16x32_bf16 v[92:95], v[148:151], v[184:187], v[92:95]
	ds_read_b128 v[218:221], v142 offset:48128
	v_mfma_f32_16x16x32_bf16 v[60:63], v[152:155], v[184:187], v[60:63]
	ds_read_b128 v[178:181], v142 offset:33792
	v_mfma_f32_16x16x32_bf16 v[28:31], v[156:159], v[184:187], v[28:31]
	ds_read_b128 v[184:187], v142 offset:35840
	v_mfma_f32_16x16x32_bf16 v[112:115], v[144:147], v[188:191], v[112:115]
	s_add_u32 m0, s2, 0x4000
	v_mfma_f32_16x16x32_bf16 v[80:83], v[148:151], v[188:191], v[80:83]
	v_mfma_f32_16x16x32_bf16 v[48:51], v[152:155], v[188:191], v[48:51]
	global_load_lds_dwordx4 v224, s[8:9]
	v_mfma_f32_16x16x32_bf16 v[16:19], v[156:159], v[188:191], v[16:19]
	ds_read_b128 v[188:191], v142 offset:37888
	s_add_u32 s8, s8, 64
	s_addc_u32 s9, s9, 0
	v_mfma_f32_16x16x32_bf16 v[116:119], v[144:147], v[192:195], v[116:119]
	v_mfma_f32_16x16x32_bf16 v[84:87], v[148:151], v[192:195], v[84:87]
	v_mfma_f32_16x16x32_bf16 v[52:55], v[152:155], v[192:195], v[52:55]
	v_mfma_f32_16x16x32_bf16 v[20:23], v[156:159], v[192:195], v[20:23]
	ds_read_b128 v[192:195], v142 offset:39936
	v_mfma_f32_16x16x32_bf16 v[104:107], v[144:147], v[196:199], v[104:107]
	s_add_u32 m0, s2, 0x8000
	v_mfma_f32_16x16x32_bf16 v[72:75], v[148:151], v[196:199], v[72:75]
	v_mfma_f32_16x16x32_bf16 v[40:43], v[152:155], v[196:199], v[40:43]
	global_load_lds_dwordx4 v128, vcc
	v_mfma_f32_16x16x32_bf16 v[8:11], v[156:159], v[196:199], v[8:11]
	ds_read_b128 v[196:199], v142 offset:41984
	v_mfma_f32_16x16x32_bf16 v[108:111], v[144:147], v[200:203], v[108:111]
	v_mfma_f32_16x16x32_bf16 v[76:79], v[148:151], v[200:203], v[76:79]
	v_mfma_f32_16x16x32_bf16 v[44:47], v[152:155], v[200:203], v[44:47]
	v_mfma_f32_16x16x32_bf16 v[12:15], v[156:159], v[200:203], v[12:15]
	ds_read_b128 v[200:203], v142 offset:44032
	v_mfma_f32_16x16x32_bf16 v[96:99], v[144:147], v[204:207], v[96:99]
	s_add_u32 m0, s2, 0xc000
	v_mfma_f32_16x16x32_bf16 v[64:67], v[148:151], v[204:207], v[64:67]
	v_mfma_f32_16x16x32_bf16 v[32:35], v[152:155], v[204:207], v[32:35]
	global_load_lds_dwordx4 v226, vcc
	v_mfma_f32_16x16x32_bf16 v[0:3], v[156:159], v[204:207], v[0:3]
	s_add_u32 vcc_lo, vcc_lo, 64
	s_addc_u32 vcc_hi, vcc_hi, 0
	v_mfma_f32_16x16x32_bf16 v[100:103], v[144:147], v[212:215], v[100:103]
	v_mfma_f32_16x16x32_bf16 v[68:71], v[148:151], v[212:215], v[68:71]
	v_mfma_f32_16x16x32_bf16 v[36:39], v[152:155], v[212:215], v[36:39]
	v_mfma_f32_16x16x32_bf16 v[4:7], v[156:159], v[212:215], v[4:7]
	s_waitcnt lgkmcnt(0)
	s_waitcnt vmcnt(8)
	s_barrier
	v_mfma_f32_16x16x32_bf16 v[120:123], v[160:163], v[178:181], v[120:123]
	ds_read_b128 v[144:147], v143
	s_add_u32 m0, s2, 0x400
	v_mfma_f32_16x16x32_bf16 v[88:91], v[164:167], v[178:181], v[88:91]
	ds_read_b128 v[148:151], v143 offset:2048
	v_mfma_f32_16x16x32_bf16 v[56:59], v[168:171], v[178:181], v[56:59]
	ds_read_b128 v[152:155], v143 offset:4096
	global_load_lds_dwordx4 v130, s[8:9]
	v_mfma_f32_16x16x32_bf16 v[24:27], v[172:175], v[178:181], v[24:27]
	ds_read_b128 v[156:159], v143 offset:6144
	v_mfma_f32_16x16x32_bf16 v[124:127], v[160:163], v[184:187], v[124:127]
	ds_read_b128 v[204:207], v176 offset:45056
	v_mfma_f32_16x16x32_bf16 v[92:95], v[164:167], v[184:187], v[92:95]
	ds_read_b128 v[212:215], v176 offset:47104
	v_mfma_f32_16x16x32_bf16 v[60:63], v[168:171], v[184:187], v[60:63]
	ds_read_b128 v[178:181], v176 offset:32768
	v_mfma_f32_16x16x32_bf16 v[28:31], v[172:175], v[184:187], v[28:31]
	ds_read_b128 v[184:187], v176 offset:34816
	v_mfma_f32_16x16x32_bf16 v[112:115], v[160:163], v[188:191], v[112:115]
	s_add_u32 m0, s2, 0x4400
	v_mfma_f32_16x16x32_bf16 v[80:83], v[164:167], v[188:191], v[80:83]
	v_mfma_f32_16x16x32_bf16 v[48:51], v[168:171], v[188:191], v[48:51]
	global_load_lds_dwordx4 v224, s[8:9]
	v_mfma_f32_16x16x32_bf16 v[16:19], v[172:175], v[188:191], v[16:19]
	ds_read_b128 v[188:191], v176 offset:36864
	s_add_u32 s8, s8, 64
	s_addc_u32 s9, s9, 0
	v_mfma_f32_16x16x32_bf16 v[116:119], v[160:163], v[192:195], v[116:119]
	v_mfma_f32_16x16x32_bf16 v[84:87], v[164:167], v[192:195], v[84:87]
	v_mfma_f32_16x16x32_bf16 v[52:55], v[168:171], v[192:195], v[52:55]
	v_mfma_f32_16x16x32_bf16 v[20:23], v[172:175], v[192:195], v[20:23]
	ds_read_b128 v[192:195], v176 offset:38912
	v_mfma_f32_16x16x32_bf16 v[104:107], v[160:163], v[196:199], v[104:107]
	s_add_u32 m0, s2, 0x8400
	v_mfma_f32_16x16x32_bf16 v[72:75], v[164:167], v[196:199], v[72:75]
	v_mfma_f32_16x16x32_bf16 v[40:43], v[168:171], v[196:199], v[40:43]
	global_load_lds_dwordx4 v128, vcc
	v_mfma_f32_16x16x32_bf16 v[8:11], v[172:175], v[196:199], v[8:11]
	ds_read_b128 v[196:199], v176 offset:40960
	v_mfma_f32_16x16x32_bf16 v[108:111], v[160:163], v[200:203], v[108:111]
	v_mfma_f32_16x16x32_bf16 v[76:79], v[164:167], v[200:203], v[76:79]
	v_mfma_f32_16x16x32_bf16 v[44:47], v[168:171], v[200:203], v[44:47]
	v_mfma_f32_16x16x32_bf16 v[12:15], v[172:175], v[200:203], v[12:15]
	ds_read_b128 v[200:203], v176 offset:43008
	v_mfma_f32_16x16x32_bf16 v[96:99], v[160:163], v[208:211], v[96:99]
	s_add_u32 m0, s2, 0xc400
	v_mfma_f32_16x16x32_bf16 v[64:67], v[164:167], v[208:211], v[64:67]
	v_mfma_f32_16x16x32_bf16 v[32:35], v[168:171], v[208:211], v[32:35]
	global_load_lds_dwordx4 v226, vcc
	v_mfma_f32_16x16x32_bf16 v[0:3], v[172:175], v[208:211], v[0:3]
	s_add_u32 vcc_lo, vcc_lo, 64
	s_addc_u32 vcc_hi, vcc_hi, 0
	v_mfma_f32_16x16x32_bf16 v[100:103], v[160:163], v[218:221], v[100:103]
	v_mfma_f32_16x16x32_bf16 v[68:71], v[164:167], v[218:221], v[68:71]
	v_mfma_f32_16x16x32_bf16 v[36:39], v[168:171], v[218:221], v[36:39]
	v_mfma_f32_16x16x32_bf16 v[4:7], v[172:175], v[218:221], v[4:7]
	s_waitcnt lgkmcnt(0)
	s_waitcnt vmcnt(8)
	s_barrier
; #define SBAR() __builtin_amdgcn_sched_barrier(0)
; #define WAIT_V0() asm volatile("s_waitcnt vmcnt(0)" ::: "memory")
; #define GLDS_STAGE(buf, kt) gemm_stage(t, (buf), (kt), shm, wid, lane)
; template <class Epi>
; DEVFI void gemm_main(const TileSrc t, const int K, char* shm, const bool pf, const TileSrc nx, const int wv, Epi epi) {
;     ...
;   for (int t_ = 0; t_ < nt; ++t_) { const int cur = t_ & 1;
;     if (t_ + 1 < nt) GLDS_STAGE(cur ^ 1, t_ + 1);
; #pragma unroll
;     for (int ks = 0; ks < G_KS; ++ks) {
;       bf16x8 At[4], Bf[8];
; #pragma unroll
;       for (int n = 0; n < 8; ++n) Bf[n] = *(const bf16x8*)(bBase + cur * G_STAGE_B + (n * 2048 + ks * 1024));
;       SBAR();
;       At[0] = *(const bf16x8*)(aBase + cur * G_STAGE_B + (0 * 2048 + ks * 1024)); SBAR();
;       At[1] = *(const bf16x8*)(aBase + cur * G_STAGE_B + (1 * 2048 + ks * 1024)); SBAR();
;       At[2] = *(const bf16x8*)(aBase + cur * G_STAGE_B + (2 * 2048 + ks * 1024)); SBAR();
;       At[3] = *(const bf16x8*)(aBase + cur * G_STAGE_B + (3 * 2048 + ks * 1024));
;       SBAR();
;       __builtin_amdgcn_s_setprio(1);
; #pragma unroll
;       for (int m = 0; m < 4; ++m)
; #pragma unroll
;         for (int n = 0; n < 8; ++n) acc[m][n] = __builtin_amdgcn_mfma_f32_16x16x32_bf16(At[m], Bf[n], acc[m][n], 0, 0, 0);
;       __builtin_amdgcn_s_setprio(0);
;       SBAR();
;     }
;     WAIT_V0(); __syncthreads();
;   }
	v_mfma_f32_16x16x32_bf16 v[120:123], v[144:147], v[178:181], v[120:123]
	ds_read_b128 v[160:163], v143 offset:1024
	s_add_u32 m0, s2, 0x10000
	v_mfma_f32_16x16x32_bf16 v[88:91], v[148:151], v[178:181], v[88:91]
	ds_read_b128 v[164:167], v143 offset:3072
	v_mfma_f32_16x16x32_bf16 v[56:59], v[152:155], v[178:181], v[56:59]
	ds_read_b128 v[168:171], v143 offset:5120
	global_load_lds_dwordx4 v130, s[8:9]
	v_mfma_f32_16x16x32_bf16 v[24:27], v[156:159], v[178:181], v[24:27]
	ds_read_b128 v[172:175], v143 offset:7168
	v_mfma_f32_16x16x32_bf16 v[124:127], v[144:147], v[184:187], v[124:127]
	ds_read_b128 v[208:211], v176 offset:46080
	v_mfma_f32_16x16x32_bf16 v[92:95], v[148:151], v[184:187], v[92:95]
	ds_read_b128 v[218:221], v176 offset:48128
	v_mfma_f32_16x16x32_bf16 v[60:63], v[152:155], v[184:187], v[60:63]
	ds_read_b128 v[178:181], v176 offset:33792
	v_mfma_f32_16x16x32_bf16 v[28:31], v[156:159], v[184:187], v[28:31]
	ds_read_b128 v[184:187], v176 offset:35840
	v_mfma_f32_16x16x32_bf16 v[112:115], v[144:147], v[188:191], v[112:115]
	s_add_u32 m0, s2, 0x14000
	v_mfma_f32_16x16x32_bf16 v[80:83], v[148:151], v[188:191], v[80:83]
	v_mfma_f32_16x16x32_bf16 v[48:51], v[152:155], v[188:191], v[48:51]
	global_load_lds_dwordx4 v224, s[8:9]
	v_mfma_f32_16x16x32_bf16 v[16:19], v[156:159], v[188:191], v[16:19]
	ds_read_b128 v[188:191], v176 offset:37888
	s_add_u32 s8, s8, 64
	s_addc_u32 s9, s9, 0
	v_mfma_f32_16x16x32_bf16 v[116:119], v[144:147], v[192:195], v[116:119]
	v_mfma_f32_16x16x32_bf16 v[84:87], v[148:151], v[192:195], v[84:87]
	v_mfma_f32_16x16x32_bf16 v[52:55], v[152:155], v[192:195], v[52:55]
	v_mfma_f32_16x16x32_bf16 v[20:23], v[156:159], v[192:195], v[20:23]
	ds_read_b128 v[192:195], v176 offset:39936
	v_mfma_f32_16x16x32_bf16 v[104:107], v[144:147], v[196:199], v[104:107]
	s_add_u32 m0, s2, 0x18000
	v_mfma_f32_16x16x32_bf16 v[72:75], v[148:151], v[196:199], v[72:75]
	v_mfma_f32_16x16x32_bf16 v[40:43], v[152:155], v[196:199], v[40:43]
	global_load_lds_dwordx4 v128, vcc
	v_mfma_f32_16x16x32_bf16 v[8:11], v[156:159], v[196:199], v[8:11]
	ds_read_b128 v[196:199], v176 offset:41984
	v_mfma_f32_16x16x32_bf16 v[108:111], v[144:147], v[200:203], v[108:111]
	v_mfma_f32_16x16x32_bf16 v[76:79], v[148:151], v[200:203], v[76:79]
	v_mfma_f32_16x16x32_bf16 v[44:47], v[152:155], v[200:203], v[44:47]
	v_mfma_f32_16x16x32_bf16 v[12:15], v[156:159], v[200:203], v[12:15]
	ds_read_b128 v[200:203], v176 offset:44032
	v_mfma_f32_16x16x32_bf16 v[96:99], v[144:147], v[204:207], v[96:99]
	s_add_u32 m0, s2, 0x1c000
	v_mfma_f32_16x16x32_bf16 v[64:67], v[148:151], v[204:207], v[64:67]
	v_mfma_f32_16x16x32_bf16 v[32:35], v[152:155], v[204:207], v[32:35]
	global_load_lds_dwordx4 v226, vcc
	v_mfma_f32_16x16x32_bf16 v[0:3], v[156:159], v[204:207], v[0:3]
	s_add_u32 vcc_lo, vcc_lo, 64
	s_addc_u32 vcc_hi, vcc_hi, 0
	v_mfma_f32_16x16x32_bf16 v[100:103], v[144:147], v[212:215], v[100:103]
	v_mfma_f32_16x16x32_bf16 v[68:71], v[148:151], v[212:215], v[68:71]
	v_mfma_f32_16x16x32_bf16 v[36:39], v[152:155], v[212:215], v[36:39]
	v_mfma_f32_16x16x32_bf16 v[4:7], v[156:159], v[212:215], v[4:7]
	s_waitcnt lgkmcnt(0)
	s_waitcnt vmcnt(8)
	s_barrier
	v_mfma_f32_16x16x32_bf16 v[120:123], v[160:163], v[178:181], v[120:123]
	ds_read_b128 v[144:147], v141
	s_add_u32 m0, s2, 0x10400
	v_mfma_f32_16x16x32_bf16 v[88:91], v[164:167], v[178:181], v[88:91]
	ds_read_b128 v[148:151], v141 offset:2048
	v_mfma_f32_16x16x32_bf16 v[56:59], v[168:171], v[178:181], v[56:59]
	ds_read_b128 v[152:155], v141 offset:4096
	global_load_lds_dwordx4 v130, s[8:9]
	v_mfma_f32_16x16x32_bf16 v[24:27], v[172:175], v[178:181], v[24:27]
	ds_read_b128 v[156:159], v141 offset:6144
	v_mfma_f32_16x16x32_bf16 v[124:127], v[160:163], v[184:187], v[124:127]
	ds_read_b128 v[204:207], v142 offset:45056
	v_mfma_f32_16x16x32_bf16 v[92:95], v[164:167], v[184:187], v[92:95]
	ds_read_b128 v[212:215], v142 offset:47104
	v_mfma_f32_16x16x32_bf16 v[60:63], v[168:171], v[184:187], v[60:63]
	ds_read_b128 v[178:181], v142 offset:32768
	v_mfma_f32_16x16x32_bf16 v[28:31], v[172:175], v[184:187], v[28:31]
	ds_read_b128 v[184:187], v142 offset:34816
	v_mfma_f32_16x16x32_bf16 v[112:115], v[160:163], v[188:191], v[112:115]
	s_add_u32 m0, s2, 0x14400
	v_mfma_f32_16x16x32_bf16 v[80:83], v[164:167], v[188:191], v[80:83]
	v_mfma_f32_16x16x32_bf16 v[48:51], v[168:171], v[188:191], v[48:51]
	global_load_lds_dwordx4 v224, s[8:9]
	v_mfma_f32_16x16x32_bf16 v[16:19], v[172:175], v[188:191], v[16:19]
	ds_read_b128 v[188:191], v142 offset:36864
	s_add_u32 s8, s8, 64
	s_addc_u32 s9, s9, 0
	v_mfma_f32_16x16x32_bf16 v[116:119], v[160:163], v[192:195], v[116:119]
	v_mfma_f32_16x16x32_bf16 v[84:87], v[164:167], v[192:195], v[84:87]
	v_mfma_f32_16x16x32_bf16 v[52:55], v[168:171], v[192:195], v[52:55]
	v_mfma_f32_16x16x32_bf16 v[20:23], v[172:175], v[192:195], v[20:23]
	ds_read_b128 v[192:195], v142 offset:38912
	v_mfma_f32_16x16x32_bf16 v[104:107], v[160:163], v[196:199], v[104:107]
	s_add_u32 m0, s2, 0x18400
	v_mfma_f32_16x16x32_bf16 v[72:75], v[164:167], v[196:199], v[72:75]
	v_mfma_f32_16x16x32_bf16 v[40:43], v[168:171], v[196:199], v[40:43]
	global_load_lds_dwordx4 v128, vcc
	v_mfma_f32_16x16x32_bf16 v[8:11], v[172:175], v[196:199], v[8:11]
	ds_read_b128 v[196:199], v142 offset:40960
	v_mfma_f32_16x16x32_bf16 v[108:111], v[160:163], v[200:203], v[108:111]
	v_mfma_f32_16x16x32_bf16 v[76:79], v[164:167], v[200:203], v[76:79]
	v_mfma_f32_16x16x32_bf16 v[44:47], v[168:171], v[200:203], v[44:47]
	v_mfma_f32_16x16x32_bf16 v[12:15], v[172:175], v[200:203], v[12:15]
	ds_read_b128 v[200:203], v142 offset:43008
	v_mfma_f32_16x16x32_bf16 v[96:99], v[160:163], v[208:211], v[96:99]
	s_add_u32 m0, s2, 0x1c400
	v_mfma_f32_16x16x32_bf16 v[64:67], v[164:167], v[208:211], v[64:67]
	v_mfma_f32_16x16x32_bf16 v[32:35], v[168:171], v[208:211], v[32:35]
	global_load_lds_dwordx4 v226, vcc
	v_mfma_f32_16x16x32_bf16 v[0:3], v[172:175], v[208:211], v[0:3]
	s_add_u32 vcc_lo, vcc_lo, 64
	s_addc_u32 vcc_hi, vcc_hi, 0
	v_mfma_f32_16x16x32_bf16 v[100:103], v[160:163], v[218:221], v[100:103]
	v_mfma_f32_16x16x32_bf16 v[68:71], v[164:167], v[218:221], v[68:71]
	v_mfma_f32_16x16x32_bf16 v[36:39], v[168:171], v[218:221], v[36:39]
	v_mfma_f32_16x16x32_bf16 v[4:7], v[172:175], v[218:221], v[4:7]
	s_sub_u32 s3, s3, 1
	s_cmp_lg_u32 s3, 0
	s_cbranch_scc1 .LgkK_loop
; #define SBAR() __builtin_amdgcn_sched_barrier(0)
; #define WAIT_V0() asm volatile("s_waitcnt vmcnt(0)" ::: "memory")
; #define GLDS_STAGE(buf, kt) gemm_stage(t, (buf), (kt), shm, wid, lane)
; template <class Epi>
; DEVFI void gemm_main(const TileSrc t, const int K, char* shm, const bool pf, const TileSrc nx, const int wv, Epi epi) {
;     ...
;   for (int t_ = 0; t_ < nt; ++t_) { const int cur = t_ & 1;
;     if (t_ + 1 < nt) GLDS_STAGE(cur ^ 1, t_ + 1);
; #pragma unroll
;     for (int ks = 0; ks < G_KS; ++ks) {
;       bf16x8 At[4], Bf[8];
; #pragma unroll
;       for (int n = 0; n < 8; ++n) Bf[n] = *(const bf16x8*)(bBase + cur * G_STAGE_B + (n * 2048 + ks * 1024));
;       SBAR();
;       At[0] = *(const bf16x8*)(aBase + cur * G_STAGE_B + (0 * 2048 + ks * 1024)); SBAR();
;       At[1] = *(const bf16x8*)(aBase + cur * G_STAGE_B + (1 * 2048 + ks * 1024)); SBAR();
;       At[2] = *(const bf16x8*)(aBase + cur * G_STAGE_B + (2 * 2048 + ks * 1024)); SBAR();
;       At[3] = *(const bf16x8*)(aBase + cur * G_STAGE_B + (3 * 2048 + ks * 1024));
;       SBAR();
;       __builtin_amdgcn_s_setprio(1);
; #pragma unroll
;       for (int m = 0; m < 4; ++m)
; #pragma unroll
;         for (int n = 0; n < 8; ++n) acc[m][n] = __builtin_amdgcn_mfma_f32_16x16x32_bf16(At[m], Bf[n], acc[m][n], 0, 0, 0);
;       __builtin_amdgcn_s_setprio(0);
;       SBAR();
;     }
;     WAIT_V0(); __syncthreads();
;   }
	s_waitcnt lgkmcnt(0)
	s_waitcnt vmcnt(8)
	s_barrier
	v_mfma_f32_16x16x32_bf16 v[120:123], v[144:147], v[178:181], v[120:123]
	ds_read_b128 v[160:163], v141 offset:1024
	v_mfma_f32_16x16x32_bf16 v[88:91], v[148:151], v[178:181], v[88:91]
	ds_read_b128 v[164:167], v141 offset:3072
	v_mfma_f32_16x16x32_bf16 v[56:59], v[152:155], v[178:181], v[56:59]
	ds_read_b128 v[168:171], v141 offset:5120
	v_mfma_f32_16x16x32_bf16 v[24:27], v[156:159], v[178:181], v[24:27]
	ds_read_b128 v[172:175], v141 offset:7168
	v_mfma_f32_16x16x32_bf16 v[124:127], v[144:147], v[184:187], v[124:127]
	ds_read_b128 v[208:211], v142 offset:46080
	v_mfma_f32_16x16x32_bf16 v[92:95], v[148:151], v[184:187], v[92:95]
	ds_read_b128 v[218:221], v142 offset:48128
	v_mfma_f32_16x16x32_bf16 v[60:63], v[152:155], v[184:187], v[60:63]
	ds_read_b128 v[178:181], v142 offset:33792
	v_mfma_f32_16x16x32_bf16 v[28:31], v[156:159], v[184:187], v[28:31]
	ds_read_b128 v[184:187], v142 offset:35840
	v_mfma_f32_16x16x32_bf16 v[112:115], v[144:147], v[188:191], v[112:115]
	v_mfma_f32_16x16x32_bf16 v[80:83], v[148:151], v[188:191], v[80:83]
	v_mfma_f32_16x16x32_bf16 v[48:51], v[152:155], v[188:191], v[48:51]
	v_mfma_f32_16x16x32_bf16 v[16:19], v[156:159], v[188:191], v[16:19]
	ds_read_b128 v[188:191], v142 offset:37888
	v_mfma_f32_16x16x32_bf16 v[116:119], v[144:147], v[192:195], v[116:119]
	v_mfma_f32_16x16x32_bf16 v[84:87], v[148:151], v[192:195], v[84:87]
	v_mfma_f32_16x16x32_bf16 v[52:55], v[152:155], v[192:195], v[52:55]
	v_mfma_f32_16x16x32_bf16 v[20:23], v[156:159], v[192:195], v[20:23]
	ds_read_b128 v[192:195], v142 offset:39936
	v_mfma_f32_16x16x32_bf16 v[104:107], v[144:147], v[196:199], v[104:107]
	v_mfma_f32_16x16x32_bf16 v[72:75], v[148:151], v[196:199], v[72:75]
	v_mfma_f32_16x16x32_bf16 v[40:43], v[152:155], v[196:199], v[40:43]
	v_mfma_f32_16x16x32_bf16 v[8:11], v[156:159], v[196:199], v[8:11]
	ds_read_b128 v[196:199], v142 offset:41984
	v_mfma_f32_16x16x32_bf16 v[108:111], v[144:147], v[200:203], v[108:111]
	v_mfma_f32_16x16x32_bf16 v[76:79], v[148:151], v[200:203], v[76:79]
	v_mfma_f32_16x16x32_bf16 v[44:47], v[152:155], v[200:203], v[44:47]
	v_mfma_f32_16x16x32_bf16 v[12:15], v[156:159], v[200:203], v[12:15]
	ds_read_b128 v[200:203], v142 offset:44032
	v_mfma_f32_16x16x32_bf16 v[96:99], v[144:147], v[204:207], v[96:99]
	v_mfma_f32_16x16x32_bf16 v[64:67], v[148:151], v[204:207], v[64:67]
	v_mfma_f32_16x16x32_bf16 v[32:35], v[152:155], v[204:207], v[32:35]
	v_mfma_f32_16x16x32_bf16 v[0:3], v[156:159], v[204:207], v[0:3]
	v_mfma_f32_16x16x32_bf16 v[100:103], v[144:147], v[212:215], v[100:103]
	v_mfma_f32_16x16x32_bf16 v[68:71], v[148:151], v[212:215], v[68:71]
	v_mfma_f32_16x16x32_bf16 v[36:39], v[152:155], v[212:215], v[36:39]
	v_mfma_f32_16x16x32_bf16 v[4:7], v[156:159], v[212:215], v[4:7]
	s_waitcnt lgkmcnt(0)
	s_waitcnt vmcnt(4)
	s_barrier
	v_mfma_f32_16x16x32_bf16 v[120:123], v[160:163], v[178:181], v[120:123]
	ds_read_b128 v[144:147], v143
	v_mfma_f32_16x16x32_bf16 v[88:91], v[164:167], v[178:181], v[88:91]
	ds_read_b128 v[148:151], v143 offset:2048
	v_mfma_f32_16x16x32_bf16 v[56:59], v[168:171], v[178:181], v[56:59]
	ds_read_b128 v[152:155], v143 offset:4096
	v_mfma_f32_16x16x32_bf16 v[24:27], v[172:175], v[178:181], v[24:27]
	ds_read_b128 v[156:159], v143 offset:6144
	v_mfma_f32_16x16x32_bf16 v[124:127], v[160:163], v[184:187], v[124:127]
	ds_read_b128 v[204:207], v176 offset:45056
	v_mfma_f32_16x16x32_bf16 v[92:95], v[164:167], v[184:187], v[92:95]
	ds_read_b128 v[212:215], v176 offset:47104
	v_mfma_f32_16x16x32_bf16 v[60:63], v[168:171], v[184:187], v[60:63]
	ds_read_b128 v[178:181], v176 offset:32768
	v_mfma_f32_16x16x32_bf16 v[28:31], v[172:175], v[184:187], v[28:31]
	ds_read_b128 v[184:187], v176 offset:34816
	v_mfma_f32_16x16x32_bf16 v[112:115], v[160:163], v[188:191], v[112:115]
	v_mfma_f32_16x16x32_bf16 v[80:83], v[164:167], v[188:191], v[80:83]
	v_mfma_f32_16x16x32_bf16 v[48:51], v[168:171], v[188:191], v[48:51]
	v_mfma_f32_16x16x32_bf16 v[16:19], v[172:175], v[188:191], v[16:19]
	ds_read_b128 v[188:191], v176 offset:36864
	v_mfma_f32_16x16x32_bf16 v[116:119], v[160:163], v[192:195], v[116:119]
	v_mfma_f32_16x16x32_bf16 v[84:87], v[164:167], v[192:195], v[84:87]
	v_mfma_f32_16x16x32_bf16 v[52:55], v[168:171], v[192:195], v[52:55]
	v_mfma_f32_16x16x32_bf16 v[20:23], v[172:175], v[192:195], v[20:23]
	ds_read_b128 v[192:195], v176 offset:38912
	v_mfma_f32_16x16x32_bf16 v[104:107], v[160:163], v[196:199], v[104:107]
	v_mfma_f32_16x16x32_bf16 v[72:75], v[164:167], v[196:199], v[72:75]
	v_mfma_f32_16x16x32_bf16 v[40:43], v[168:171], v[196:199], v[40:43]
	v_mfma_f32_16x16x32_bf16 v[8:11], v[172:175], v[196:199], v[8:11]
	ds_read_b128 v[196:199], v176 offset:40960
	v_mfma_f32_16x16x32_bf16 v[108:111], v[160:163], v[200:203], v[108:111]
	v_mfma_f32_16x16x32_bf16 v[76:79], v[164:167], v[200:203], v[76:79]
	v_mfma_f32_16x16x32_bf16 v[44:47], v[168:171], v[200:203], v[44:47]
	v_mfma_f32_16x16x32_bf16 v[12:15], v[172:175], v[200:203], v[12:15]
	ds_read_b128 v[200:203], v176 offset:43008
	v_mfma_f32_16x16x32_bf16 v[96:99], v[160:163], v[208:211], v[96:99]
	v_mfma_f32_16x16x32_bf16 v[64:67], v[164:167], v[208:211], v[64:67]
	v_mfma_f32_16x16x32_bf16 v[32:35], v[168:171], v[208:211], v[32:35]
	v_mfma_f32_16x16x32_bf16 v[0:3], v[172:175], v[208:211], v[0:3]
	v_mfma_f32_16x16x32_bf16 v[100:103], v[160:163], v[218:221], v[100:103]
	v_mfma_f32_16x16x32_bf16 v[68:71], v[164:167], v[218:221], v[68:71]
	v_mfma_f32_16x16x32_bf16 v[36:39], v[168:171], v[218:221], v[36:39]
	v_mfma_f32_16x16x32_bf16 v[4:7], v[172:175], v[218:221], v[4:7]
	s_waitcnt lgkmcnt(0)
	s_waitcnt vmcnt(0)
	s_barrier
; #define SBAR() __builtin_amdgcn_sched_barrier(0)
; #define WAIT_V0() asm volatile("s_waitcnt vmcnt(0)" ::: "memory")
; #define GLDS_STAGE(buf, kt) gemm_stage(t, (buf), (kt), shm, wid, lane)
; template <class Epi>
; DEVFI void gemm_main(const TileSrc t, const int K, char* shm, const bool pf, const TileSrc nx, const int wv, Epi epi) {
;     ...
;   for (int t_ = 0; t_ < nt; ++t_) { const int cur = t_ & 1;
;     if (t_ + 1 < nt) GLDS_STAGE(cur ^ 1, t_ + 1);
; #pragma unroll
;     for (int ks = 0; ks < G_KS; ++ks) {
;       bf16x8 At[4], Bf[8];
; #pragma unroll
;       for (int n = 0; n < 8; ++n) Bf[n] = *(const bf16x8*)(bBase + cur * G_STAGE_B + (n * 2048 + ks * 1024));
;       SBAR();
;       At[0] = *(const bf16x8*)(aBase + cur * G_STAGE_B + (0 * 2048 + ks * 1024)); SBAR();
;       At[1] = *(const bf16x8*)(aBase + cur * G_STAGE_B + (1 * 2048 + ks * 1024)); SBAR();
;       At[2] = *(const bf16x8*)(aBase + cur * G_STAGE_B + (2 * 2048 + ks * 1024)); SBAR();
;       At[3] = *(const bf16x8*)(aBase + cur * G_STAGE_B + (3 * 2048 + ks * 1024));
;       SBAR();
;       __builtin_amdgcn_s_setprio(1);
; #pragma unroll
;       for (int m = 0; m < 4; ++m)
; #pragma unroll
;         for (int n = 0; n < 8; ++n) acc[m][n] = __builtin_amdgcn_mfma_f32_16x16x32_bf16(At[m], Bf[n], acc[m][n], 0, 0, 0);
;       __builtin_amdgcn_s_setprio(0);
;       SBAR();
;     }
;     WAIT_V0(); __syncthreads();
;   }
;     ...
;   if (pf) gemm_stage(nx, 0, 0, shm, wid, lane);
	v_mfma_f32_16x16x32_bf16 v[120:123], v[144:147], v[178:181], v[120:123]
	ds_read_b128 v[160:163], v143 offset:1024
	v_mfma_f32_16x16x32_bf16 v[88:91], v[148:151], v[178:181], v[88:91]
	ds_read_b128 v[164:167], v143 offset:3072
	v_mfma_f32_16x16x32_bf16 v[56:59], v[152:155], v[178:181], v[56:59]
	ds_read_b128 v[168:171], v143 offset:5120
	v_mfma_f32_16x16x32_bf16 v[24:27], v[156:159], v[178:181], v[24:27]
	ds_read_b128 v[172:175], v143 offset:7168
	v_mfma_f32_16x16x32_bf16 v[124:127], v[144:147], v[184:187], v[124:127]
	ds_read_b128 v[208:211], v176 offset:46080
	v_mfma_f32_16x16x32_bf16 v[92:95], v[148:151], v[184:187], v[92:95]
	ds_read_b128 v[218:221], v176 offset:48128
	v_mfma_f32_16x16x32_bf16 v[60:63], v[152:155], v[184:187], v[60:63]
	ds_read_b128 v[178:181], v176 offset:33792
	v_mfma_f32_16x16x32_bf16 v[28:31], v[156:159], v[184:187], v[28:31]
	ds_read_b128 v[184:187], v176 offset:35840
	v_mfma_f32_16x16x32_bf16 v[112:115], v[144:147], v[188:191], v[112:115]
	v_mfma_f32_16x16x32_bf16 v[80:83], v[148:151], v[188:191], v[80:83]
	v_mfma_f32_16x16x32_bf16 v[48:51], v[152:155], v[188:191], v[48:51]
	v_mfma_f32_16x16x32_bf16 v[16:19], v[156:159], v[188:191], v[16:19]
	ds_read_b128 v[188:191], v176 offset:37888
	v_mfma_f32_16x16x32_bf16 v[116:119], v[144:147], v[192:195], v[116:119]
	v_mfma_f32_16x16x32_bf16 v[84:87], v[148:151], v[192:195], v[84:87]
	v_mfma_f32_16x16x32_bf16 v[52:55], v[152:155], v[192:195], v[52:55]
	v_mfma_f32_16x16x32_bf16 v[20:23], v[156:159], v[192:195], v[20:23]
	ds_read_b128 v[192:195], v176 offset:39936
	v_mfma_f32_16x16x32_bf16 v[104:107], v[144:147], v[196:199], v[104:107]
	v_mfma_f32_16x16x32_bf16 v[72:75], v[148:151], v[196:199], v[72:75]
	v_mfma_f32_16x16x32_bf16 v[40:43], v[152:155], v[196:199], v[40:43]
	v_mfma_f32_16x16x32_bf16 v[8:11], v[156:159], v[196:199], v[8:11]
	ds_read_b128 v[196:199], v176 offset:41984
	v_mfma_f32_16x16x32_bf16 v[108:111], v[144:147], v[200:203], v[108:111]
	v_mfma_f32_16x16x32_bf16 v[76:79], v[148:151], v[200:203], v[76:79]
	v_mfma_f32_16x16x32_bf16 v[44:47], v[152:155], v[200:203], v[44:47]
	v_mfma_f32_16x16x32_bf16 v[12:15], v[156:159], v[200:203], v[12:15]
	ds_read_b128 v[200:203], v176 offset:44032
	v_mfma_f32_16x16x32_bf16 v[96:99], v[144:147], v[204:207], v[96:99]
	v_mfma_f32_16x16x32_bf16 v[64:67], v[148:151], v[204:207], v[64:67]
	v_mfma_f32_16x16x32_bf16 v[32:35], v[152:155], v[204:207], v[32:35]
	v_mfma_f32_16x16x32_bf16 v[0:3], v[156:159], v[204:207], v[0:3]
	v_mfma_f32_16x16x32_bf16 v[100:103], v[144:147], v[212:215], v[100:103]
	v_mfma_f32_16x16x32_bf16 v[68:71], v[148:151], v[212:215], v[68:71]
	v_mfma_f32_16x16x32_bf16 v[36:39], v[152:155], v[212:215], v[36:39]
	v_mfma_f32_16x16x32_bf16 v[4:7], v[156:159], v[212:215], v[4:7]
	s_waitcnt lgkmcnt(0)
	s_barrier
	v_mfma_f32_16x16x32_bf16 v[120:123], v[160:163], v[178:181], v[120:123]
	v_mfma_f32_16x16x32_bf16 v[88:91], v[164:167], v[178:181], v[88:91]
	v_mfma_f32_16x16x32_bf16 v[56:59], v[168:171], v[178:181], v[56:59]
	v_mfma_f32_16x16x32_bf16 v[24:27], v[172:175], v[178:181], v[24:27]
	v_mfma_f32_16x16x32_bf16 v[124:127], v[160:163], v[184:187], v[124:127]
	v_mfma_f32_16x16x32_bf16 v[92:95], v[164:167], v[184:187], v[92:95]
	v_mfma_f32_16x16x32_bf16 v[60:63], v[168:171], v[184:187], v[60:63]
	v_mfma_f32_16x16x32_bf16 v[28:31], v[172:175], v[184:187], v[28:31]
	v_mfma_f32_16x16x32_bf16 v[112:115], v[160:163], v[188:191], v[112:115]
	v_mfma_f32_16x16x32_bf16 v[80:83], v[164:167], v[188:191], v[80:83]
	v_mfma_f32_16x16x32_bf16 v[48:51], v[168:171], v[188:191], v[48:51]
	v_mfma_f32_16x16x32_bf16 v[16:19], v[172:175], v[188:191], v[16:19]
	v_mfma_f32_16x16x32_bf16 v[116:119], v[160:163], v[192:195], v[116:119]
	v_mfma_f32_16x16x32_bf16 v[84:87], v[164:167], v[192:195], v[84:87]
	v_mfma_f32_16x16x32_bf16 v[52:55], v[168:171], v[192:195], v[52:55]
	v_mfma_f32_16x16x32_bf16 v[20:23], v[172:175], v[192:195], v[20:23]
	v_mfma_f32_16x16x32_bf16 v[104:107], v[160:163], v[196:199], v[104:107]
	v_mfma_f32_16x16x32_bf16 v[72:75], v[164:167], v[196:199], v[72:75]
	v_mfma_f32_16x16x32_bf16 v[40:43], v[168:171], v[196:199], v[40:43]
	v_mfma_f32_16x16x32_bf16 v[8:11], v[172:175], v[196:199], v[8:11]
	v_mfma_f32_16x16x32_bf16 v[108:111], v[160:163], v[200:203], v[108:111]
	v_mfma_f32_16x16x32_bf16 v[76:79], v[164:167], v[200:203], v[76:79]
	v_mfma_f32_16x16x32_bf16 v[44:47], v[168:171], v[200:203], v[44:47]
	v_mfma_f32_16x16x32_bf16 v[12:15], v[172:175], v[200:203], v[12:15]
	v_mfma_f32_16x16x32_bf16 v[96:99], v[160:163], v[208:211], v[96:99]
	v_mfma_f32_16x16x32_bf16 v[64:67], v[164:167], v[208:211], v[64:67]
	v_mfma_f32_16x16x32_bf16 v[32:35], v[168:171], v[208:211], v[32:35]
	v_mfma_f32_16x16x32_bf16 v[0:3], v[172:175], v[208:211], v[0:3]
	v_mfma_f32_16x16x32_bf16 v[100:103], v[160:163], v[218:221], v[100:103]
	v_mfma_f32_16x16x32_bf16 v[68:71], v[164:167], v[218:221], v[68:71]
	v_mfma_f32_16x16x32_bf16 v[36:39], v[168:171], v[218:221], v[36:39]
	v_mfma_f32_16x16x32_bf16 v[4:7], v[172:175], v[218:221], v[4:7]
	s_nop 7
	s_nop 3
	s_mov_b64 s[8:9], 0x780
	s_mov_b32 s18, 0xf0000
	s_and_b64 vcc, exec, s[6:7]
	s_cbranch_vccz .LBB0_4072
	v_lshlrev_b32_e32 v128, 1, v138
	v_sub_u32_e32 v128, v137, v128
	v_lshl_or_b32 v129, v138, 14, v140
	v_lshl_add_u32 v128, v128, 5, v129
	v_or_b32_e32 v128, v128, v139
	v_ashrrev_i32_e32 v129, 31, v128
	v_add_u32_e32 v137, 0x8000, v136
	v_lshlrev_b64 v[128:129], 1, v[128:129]
	v_readfirstlane_b32 s2, v136
	v_lshl_add_u64 v[130:131], s[14:15], 0, v[128:129]
	s_mov_b32 m0, s2
	v_readfirstlane_b32 s2, v137
	v_add_u32_e32 v137, 0x2000, v136
	global_load_lds_dwordx4 v[130:131], off
	v_lshl_add_u64 v[128:129], s[16:17], 0, v[128:129]
	s_mov_b32 m0, s2
	v_readfirstlane_b32 s2, v137
	v_add_u32_e32 v137, 0xa000, v136
	global_load_lds_dwordx4 v[128:129], off
	v_lshl_add_u64 v[138:139], v[130:131], 0, s[86:87]
	s_mov_b32 m0, s2
	v_readfirstlane_b32 s2, v137
	v_add_u32_e32 v137, 0x4000, v136
	global_load_lds_dwordx4 v[138:139], off
	v_lshl_add_u64 v[138:139], v[128:129], 0, s[86:87]
	s_mov_b32 m0, s2
	v_readfirstlane_b32 s2, v137
	v_add_u32_e32 v137, 0xc000, v136
	global_load_lds_dwordx4 v[138:139], off
	v_lshl_add_u64 v[138:139], v[130:131], 0, s[88:89]
	s_mov_b32 m0, s2
	v_readfirstlane_b32 s2, v137
	v_add_u32_e32 v137, 0x6000, v136
	global_load_lds_dwordx4 v[138:139], off
	v_lshl_add_u64 v[138:139], v[128:129], 0, s[88:89]
	s_mov_b32 m0, s2
	v_readfirstlane_b32 s2, v137
	global_load_lds_dwordx4 v[138:139], off
	v_lshl_add_u64 v[130:131], v[130:131], 0, s[90:91]
	s_mov_b32 m0, s2
	v_lshl_add_u64 v[128:129], v[128:129], 0, s[90:91]
	global_load_lds_dwordx4 v[130:131], off
	v_add_u32_e32 v130, 0xe000, v136
	s_nop 0
	v_readfirstlane_b32 s2, v130
	s_mov_b32 m0, s2
	s_nop 0
	global_load_lds_dwordx4 v[128:129], off
; #define SBAR() __builtin_amdgcn_sched_barrier(0)
; DEVFI float dpp_xor1(float x) { return __int_as_float(__builtin_amdgcn_update_dpp(0, __float_as_int(x), 0xB1, 0xF, 0xF, true)); }
; DEVFI void store_nat_m(bfraw* base, long ld, f32x4 (&a)[8], int fr) {
;   const bool odd = fr & 1;
;   bfraw* p0 = base + (odd ? 15 + fr : fr);
; #pragma unroll
;   for (int j = 0; j < 4; ++j)
; #pragma unroll
;     for (int n0 = 0; n0 < 8; n0 += 2) { const float own0 = a[n0][j], own1 = a[n0 + 1][j];
;       const float recv = dpp_xor1(odd ? own0 : own1);
;       const unsigned pk = odd ? cvtpk(recv, own1) : cvtpk(own0, recv);
;       *reinterpret_cast<unsigned*>(p0 + (long)j * ld + n0 * 16) = pk; }
; }
; DEVFI void store_nat(bfraw* dst, long ld, f32x4 (&acc)[4][8], int fr, int fq) {
;   store_nat_m(dst + (long)(0 * 16 + fq * 4) * ld, ld, acc[0], fr); SBAR();
;   store_nat_m(dst + (long)(1 * 16 + fq * 4) * ld, ld, acc[1], fr); SBAR();
;   store_nat_m(dst + (long)(2 * 16 + fq * 4) * ld, ld, acc[2], fr); SBAR();
;   store_nat_m(dst + (long)(3 * 16 + fq * 4) * ld, ld, acc[3], fr); SBAR();
; }
.LBB0_4072:
	s_mov_b64 s[2:3], s[0:1]
	s_load_dwordx2 s[2:3], s[2:3], 0xe8
	v_and_b32_e32 v128, 1, v135
	v_cmp_eq_u32_e64 s[8:9], 0, v128
	v_cmp_eq_u32_e64 s[6:7], 1, v128
	s_nop 0
	v_cndmask_b32_e64 v128, v120, v124, s[8:9]
	s_nop 1
	v_mov_b32_dpp v128, v128 quad_perm:[1,0,3,2] row_mask:0xf bank_mask:0xf bound_ctrl:1
	v_cndmask_b32_e64 v135, v120, v128, s[6:7]
	v_cndmask_b32_e64 v128, v128, v124, s[6:7]
	v_cvt_pk_bf16_f32 v135, v135, v128
	s_lshr_b32 s18, s12, 2
	s_and_b32 s18, s18, 0xfffff8
	s_and_b32 s19, s12, 7
	s_or_b32 s18, s18, s19
	s_lshl_b32 s18, s18, 8
	v_mov_b32_e32 v120, s18
	v_lshl_add_u32 v128, s21, 6, v120
	v_ashrrev_i32_e32 v129, 31, v128
	v_lshlrev_b64 v[128:129], 11, v[128:129]
	s_waitcnt lgkmcnt(0)
	v_lshl_add_u64 v[128:129], s[2:3], 0, v[128:129]
	s_lshl_b32 s2, s12, 6
	s_and_b32 s12, s2, 0x600
	v_lshl_add_u64 v[128:129], v[128:129], 0, s[12:13]
	v_lshlrev_b32_e32 v176, 8, v134
	v_lshlrev_b32_e32 v120, 9, v133
	v_lshl_add_u64 v[128:129], v[128:129], 0, v[176:177]
	v_and_b32_e32 v176, 0x6000, v120
	v_add_u32_e32 v120, 15, v132
	v_lshl_add_u64 v[128:129], v[128:129], 0, v[176:177]
	s_mov_b64 s[2:3], 0x7720000
	v_cndmask_b32_e64 v120, v120, v132, s[8:9]
	v_lshl_add_u64 v[128:129], v[128:129], 0, s[2:3]
	v_lshlrev_b32_e32 v176, 1, v120
	v_cndmask_b32_e64 v120, v112, v116, s[8:9]
	v_lshl_add_u64 v[130:131], v[128:129], 0, v[176:177]
	global_store_dword v[130:131], v135, off
	v_mov_b32_dpp v124, v120 quad_perm:[1,0,3,2] row_mask:0xf bank_mask:0xf bound_ctrl:1
	v_cndmask_b32_e64 v120, v112, v124, s[6:7]
	v_cndmask_b32_e64 v124, v124, v116, s[6:7]
	v_cvt_pk_bf16_f32 v120, v120, v124
	v_cndmask_b32_e64 v112, v104, v108, s[8:9]
	global_store_dword v[130:131], v120, off offset:64
	s_nop 0
	v_mov_b32_dpp v116, v112 quad_perm:[1,0,3,2] row_mask:0xf bank_mask:0xf bound_ctrl:1
	v_cndmask_b32_e64 v112, v104, v116, s[6:7]
	v_cndmask_b32_e64 v116, v116, v108, s[6:7]
	v_cvt_pk_bf16_f32 v112, v112, v116
	v_cndmask_b32_e64 v104, v96, v100, s[8:9]
	global_store_dword v[130:131], v112, off offset:128
	s_nop 0
	v_mov_b32_dpp v108, v104 quad_perm:[1,0,3,2] row_mask:0xf bank_mask:0xf bound_ctrl:1
	v_cndmask_b32_e64 v104, v96, v108, s[6:7]
	v_cndmask_b32_e64 v108, v108, v100, s[6:7]
	v_cvt_pk_bf16_f32 v104, v104, v108
	v_cndmask_b32_e64 v96, v121, v125, s[8:9]
	global_store_dword v[130:131], v104, off offset:192
	s_nop 0
	v_mov_b32_dpp v100, v96 quad_perm:[1,0,3,2] row_mask:0xf bank_mask:0xf bound_ctrl:1
	v_cndmask_b32_e64 v96, v121, v100, s[6:7]
	v_cndmask_b32_e64 v100, v100, v125, s[6:7]
	v_cvt_pk_bf16_f32 v96, v96, v100
	global_store_dword v[130:131], v96, off offset:2048
	v_cndmask_b32_e64 v96, v113, v117, s[8:9]
	s_nop 1
	v_mov_b32_dpp v100, v96 quad_perm:[1,0,3,2] row_mask:0xf bank_mask:0xf bound_ctrl:1
	v_cndmask_b32_e64 v96, v113, v100, s[6:7]
	v_cndmask_b32_e64 v100, v100, v117, s[6:7]
	v_cvt_pk_bf16_f32 v96, v96, v100
	global_store_dword v[130:131], v96, off offset:2112
	v_cndmask_b32_e64 v96, v105, v109, s[8:9]
	s_nop 1
	v_mov_b32_dpp v100, v96 quad_perm:[1,0,3,2] row_mask:0xf bank_mask:0xf bound_ctrl:1
	v_cndmask_b32_e64 v96, v105, v100, s[6:7]
	v_cndmask_b32_e64 v100, v100, v109, s[6:7]
	v_cvt_pk_bf16_f32 v96, v96, v100
	global_store_dword v[130:131], v96, off offset:2176
	v_cndmask_b32_e64 v96, v97, v101, s[8:9]
	s_nop 1
	v_mov_b32_dpp v100, v96 quad_perm:[1,0,3,2] row_mask:0xf bank_mask:0xf bound_ctrl:1
	v_cndmask_b32_e64 v96, v97, v100, s[6:7]
	v_cndmask_b32_e64 v100, v100, v101, s[6:7]
	v_cvt_pk_bf16_f32 v96, v96, v100
	global_store_dword v[130:131], v96, off offset:2240
	v_cndmask_b32_e64 v96, v122, v126, s[8:9]
	s_nop 1
	v_mov_b32_dpp v97, v96 quad_perm:[1,0,3,2] row_mask:0xf bank_mask:0xf bound_ctrl:1
	v_cndmask_b32_e64 v96, v122, v97, s[6:7]
	v_cndmask_b32_e64 v97, v97, v126, s[6:7]
	v_cvt_pk_bf16_f32 v96, v96, v97
	v_add_co_u32_e32 v100, vcc, 0x1000, v130
	s_nop 1
	v_addc_co_u32_e32 v101, vcc, 0, v131, vcc
	global_store_dword v[100:101], v96, off
	v_cndmask_b32_e64 v96, v114, v118, s[8:9]
	s_nop 1
	v_mov_b32_dpp v97, v96 quad_perm:[1,0,3,2] row_mask:0xf bank_mask:0xf bound_ctrl:1
	v_cndmask_b32_e64 v96, v114, v97, s[6:7]
	v_cndmask_b32_e64 v97, v97, v118, s[6:7]
	v_cvt_pk_bf16_f32 v96, v96, v97
	v_add_co_u32_e32 v100, vcc, 0x1000, v130
	s_nop 1
	v_addc_co_u32_e32 v101, vcc, 0, v131, vcc
	global_store_dword v[100:101], v96, off offset:64
	v_cndmask_b32_e64 v96, v106, v110, s[8:9]
	s_nop 1
	v_mov_b32_dpp v97, v96 quad_perm:[1,0,3,2] row_mask:0xf bank_mask:0xf bound_ctrl:1
	v_cndmask_b32_e64 v96, v106, v97, s[6:7]
	v_cndmask_b32_e64 v97, v97, v110, s[6:7]
	v_cvt_pk_bf16_f32 v96, v96, v97
	v_add_co_u32_e32 v100, vcc, 0x1000, v130
	s_nop 1
	v_addc_co_u32_e32 v101, vcc, 0, v131, vcc
	global_store_dword v[100:101], v96, off offset:128
	v_cndmask_b32_e64 v96, v98, v102, s[8:9]
	s_nop 1
	v_mov_b32_dpp v97, v96 quad_perm:[1,0,3,2] row_mask:0xf bank_mask:0xf bound_ctrl:1
	v_cndmask_b32_e64 v96, v98, v97, s[6:7]
	v_cndmask_b32_e64 v97, v97, v102, s[6:7]
	v_cvt_pk_bf16_f32 v96, v96, v97
	v_add_co_u32_e32 v100, vcc, 0x1000, v130
	s_nop 1
	v_addc_co_u32_e32 v101, vcc, 0, v131, vcc
	global_store_dword v[100:101], v96, off offset:192
	v_cndmask_b32_e64 v96, v123, v127, s[8:9]
	s_nop 1
	v_mov_b32_dpp v97, v96 quad_perm:[1,0,3,2] row_mask:0xf bank_mask:0xf bound_ctrl:1
	v_cndmask_b32_e64 v96, v123, v97, s[6:7]
	v_cndmask_b32_e64 v97, v97, v127, s[6:7]
	v_cvt_pk_bf16_f32 v96, v96, v97
	v_add_co_u32_e32 v100, vcc, 0x1000, v130
	s_nop 1
	v_addc_co_u32_e32 v101, vcc, 0, v131, vcc
	global_store_dword v[100:101], v96, off offset:2048
	v_cndmask_b32_e64 v96, v115, v119, s[8:9]
	s_nop 1
	v_mov_b32_dpp v97, v96 quad_perm:[1,0,3,2] row_mask:0xf bank_mask:0xf bound_ctrl:1
; #define SBAR() __builtin_amdgcn_sched_barrier(0)
; DEVFI float dpp_xor1(float x) { return __int_as_float(__builtin_amdgcn_update_dpp(0, __float_as_int(x), 0xB1, 0xF, 0xF, true)); }
; DEVFI void store_nat_m(bfraw* base, long ld, f32x4 (&a)[8], int fr) {
;   const bool odd = fr & 1;
;   bfraw* p0 = base + (odd ? 15 + fr : fr);
; #pragma unroll
;   for (int j = 0; j < 4; ++j)
; #pragma unroll
;     for (int n0 = 0; n0 < 8; n0 += 2) { const float own0 = a[n0][j], own1 = a[n0 + 1][j];
;       const float recv = dpp_xor1(odd ? own0 : own1);
;       const unsigned pk = odd ? cvtpk(recv, own1) : cvtpk(own0, recv);
;       *reinterpret_cast<unsigned*>(p0 + (long)j * ld + n0 * 16) = pk; }
; }
; DEVFI void store_nat(bfraw* dst, long ld, f32x4 (&acc)[4][8], int fr, int fq) {
;   store_nat_m(dst + (long)(0 * 16 + fq * 4) * ld, ld, acc[0], fr); SBAR();
;   store_nat_m(dst + (long)(1 * 16 + fq * 4) * ld, ld, acc[1], fr); SBAR();
;   store_nat_m(dst + (long)(2 * 16 + fq * 4) * ld, ld, acc[2], fr); SBAR();
;   store_nat_m(dst + (long)(3 * 16 + fq * 4) * ld, ld, acc[3], fr); SBAR();
; }
	v_cndmask_b32_e64 v96, v115, v97, s[6:7]
	v_cndmask_b32_e64 v97, v97, v119, s[6:7]
	v_cvt_pk_bf16_f32 v96, v96, v97
	v_add_co_u32_e32 v100, vcc, 0x1000, v130
	s_nop 1
	v_addc_co_u32_e32 v101, vcc, 0, v131, vcc
	global_store_dword v[100:101], v96, off offset:2112
	v_cndmask_b32_e64 v96, v107, v111, s[8:9]
	s_nop 1
	v_mov_b32_dpp v97, v96 quad_perm:[1,0,3,2] row_mask:0xf bank_mask:0xf bound_ctrl:1
	v_cndmask_b32_e64 v96, v107, v97, s[6:7]
	v_cndmask_b32_e64 v97, v97, v111, s[6:7]
	v_cvt_pk_bf16_f32 v96, v96, v97
	v_add_co_u32_e32 v100, vcc, 0x1000, v130
	s_nop 1
	v_addc_co_u32_e32 v101, vcc, 0, v131, vcc
	global_store_dword v[100:101], v96, off offset:2176
	v_cndmask_b32_e64 v96, v99, v103, s[8:9]
	s_nop 1
	v_mov_b32_dpp v96, v96 quad_perm:[1,0,3,2] row_mask:0xf bank_mask:0xf bound_ctrl:1
	v_cndmask_b32_e64 v100, v99, v96, s[6:7]
	v_cndmask_b32_e64 v96, v96, v103, s[6:7]
	v_cvt_pk_bf16_f32 v100, v100, v96
	v_add_co_u32_e32 v96, vcc, 0x1000, v130
	s_nop 1
	v_addc_co_u32_e32 v97, vcc, 0, v131, vcc
	global_store_dword v[96:97], v100, off offset:2240
	v_cndmask_b32_e64 v96, v88, v92, s[8:9]
	s_nop 1
	v_mov_b32_dpp v96, v96 quad_perm:[1,0,3,2] row_mask:0xf bank_mask:0xf bound_ctrl:1
	v_cndmask_b32_e64 v98, v88, v96, s[6:7]
	v_cndmask_b32_e64 v96, v96, v92, s[6:7]
	v_cvt_pk_bf16_f32 v98, v98, v96
	v_lshl_add_u64 v[96:97], v[128:129], 0, v[176:177]
	v_add_co_u32_e32 v100, vcc, 0x8000, v96
	v_cndmask_b32_e64 v88, v80, v84, s[8:9]
	s_nop 0
	v_addc_co_u32_e32 v101, vcc, 0, v97, vcc
	v_mov_b32_dpp v92, v88 quad_perm:[1,0,3,2] row_mask:0xf bank_mask:0xf bound_ctrl:1
	global_store_dword v[100:101], v98, off
	v_cndmask_b32_e64 v88, v80, v92, s[6:7]
	v_cndmask_b32_e64 v92, v92, v84, s[6:7]
	v_cvt_pk_bf16_f32 v88, v88, v92
	s_mov_b64 s[2:3], 0x8000
	v_cndmask_b32_e64 v80, v72, v76, s[8:9]
	v_lshl_add_u64 v[96:97], v[96:97], 0, s[2:3]
	global_store_dword v[96:97], v88, off offset:64
	v_mov_b32_dpp v84, v80 quad_perm:[1,0,3,2] row_mask:0xf bank_mask:0xf bound_ctrl:1
	v_cndmask_b32_e64 v80, v72, v84, s[6:7]
	v_cndmask_b32_e64 v84, v84, v76, s[6:7]
	v_cvt_pk_bf16_f32 v80, v80, v84
	v_cndmask_b32_e64 v72, v64, v68, s[8:9]
	global_store_dword v[96:97], v80, off offset:128
	s_nop 0
	v_mov_b32_dpp v76, v72 quad_perm:[1,0,3,2] row_mask:0xf bank_mask:0xf bound_ctrl:1
	v_cndmask_b32_e64 v72, v64, v76, s[6:7]
	v_cndmask_b32_e64 v76, v76, v68, s[6:7]
	v_cvt_pk_bf16_f32 v72, v72, v76
	v_cndmask_b32_e64 v64, v89, v93, s[8:9]
	global_store_dword v[96:97], v72, off offset:192
	s_nop 0
	v_mov_b32_dpp v68, v64 quad_perm:[1,0,3,2] row_mask:0xf bank_mask:0xf bound_ctrl:1
	v_cndmask_b32_e64 v64, v89, v68, s[6:7]
	v_cndmask_b32_e64 v68, v68, v93, s[6:7]
	v_cvt_pk_bf16_f32 v64, v64, v68
	global_store_dword v[96:97], v64, off offset:2048
	v_cndmask_b32_e64 v64, v81, v85, s[8:9]
	s_nop 1
	v_mov_b32_dpp v68, v64 quad_perm:[1,0,3,2] row_mask:0xf bank_mask:0xf bound_ctrl:1
	v_cndmask_b32_e64 v64, v81, v68, s[6:7]
	v_cndmask_b32_e64 v68, v68, v85, s[6:7]
	v_cvt_pk_bf16_f32 v64, v64, v68
	global_store_dword v[96:97], v64, off offset:2112
	v_cndmask_b32_e64 v64, v73, v77, s[8:9]
	s_nop 1
	v_mov_b32_dpp v68, v64 quad_perm:[1,0,3,2] row_mask:0xf bank_mask:0xf bound_ctrl:1
	v_cndmask_b32_e64 v64, v73, v68, s[6:7]
	v_cndmask_b32_e64 v68, v68, v77, s[6:7]
	v_cvt_pk_bf16_f32 v64, v64, v68
	global_store_dword v[96:97], v64, off offset:2176
	v_cndmask_b32_e64 v64, v65, v69, s[8:9]
	s_nop 1
	v_mov_b32_dpp v68, v64 quad_perm:[1,0,3,2] row_mask:0xf bank_mask:0xf bound_ctrl:1
	v_cndmask_b32_e64 v64, v65, v68, s[6:7]
	v_cndmask_b32_e64 v68, v68, v69, s[6:7]
	v_cvt_pk_bf16_f32 v64, v64, v68
	global_store_dword v[96:97], v64, off offset:2240
	v_cndmask_b32_e64 v64, v90, v94, s[8:9]
	s_nop 1
	v_mov_b32_dpp v65, v64 quad_perm:[1,0,3,2] row_mask:0xf bank_mask:0xf bound_ctrl:1
	v_cndmask_b32_e64 v64, v90, v65, s[6:7]
	v_cndmask_b32_e64 v65, v65, v94, s[6:7]
	v_cvt_pk_bf16_f32 v64, v64, v65
	v_add_co_u32_e32 v68, vcc, 0x1000, v96
	s_nop 1
	v_addc_co_u32_e32 v69, vcc, 0, v97, vcc
	global_store_dword v[68:69], v64, off
	v_cndmask_b32_e64 v64, v82, v86, s[8:9]
	s_nop 1
	v_mov_b32_dpp v65, v64 quad_perm:[1,0,3,2] row_mask:0xf bank_mask:0xf bound_ctrl:1
	v_cndmask_b32_e64 v64, v82, v65, s[6:7]
	v_cndmask_b32_e64 v65, v65, v86, s[6:7]
	v_cvt_pk_bf16_f32 v64, v64, v65
	v_add_co_u32_e32 v68, vcc, 0x1000, v96
	s_nop 1
	v_addc_co_u32_e32 v69, vcc, 0, v97, vcc
	global_store_dword v[68:69], v64, off offset:64
	v_cndmask_b32_e64 v64, v74, v78, s[8:9]
	s_nop 1
	v_mov_b32_dpp v65, v64 quad_perm:[1,0,3,2] row_mask:0xf bank_mask:0xf bound_ctrl:1
	v_cndmask_b32_e64 v64, v74, v65, s[6:7]
	v_cndmask_b32_e64 v65, v65, v78, s[6:7]
	v_cvt_pk_bf16_f32 v64, v64, v65
	v_add_co_u32_e32 v68, vcc, 0x1000, v96
	s_nop 1
	v_addc_co_u32_e32 v69, vcc, 0, v97, vcc
	global_store_dword v[68:69], v64, off offset:128
	v_cndmask_b32_e64 v64, v66, v70, s[8:9]
	s_nop 1
	v_mov_b32_dpp v65, v64 quad_perm:[1,0,3,2] row_mask:0xf bank_mask:0xf bound_ctrl:1
	v_cndmask_b32_e64 v64, v66, v65, s[6:7]
	v_cndmask_b32_e64 v65, v65, v70, s[6:7]
	v_cvt_pk_bf16_f32 v64, v64, v65
	v_add_co_u32_e32 v68, vcc, 0x1000, v96
	s_nop 1
	v_addc_co_u32_e32 v69, vcc, 0, v97, vcc
	global_store_dword v[68:69], v64, off offset:192
	v_cndmask_b32_e64 v64, v91, v95, s[8:9]
	s_nop 1
	v_mov_b32_dpp v65, v64 quad_perm:[1,0,3,2] row_mask:0xf bank_mask:0xf bound_ctrl:1
	v_cndmask_b32_e64 v64, v91, v65, s[6:7]
	v_cndmask_b32_e64 v65, v65, v95, s[6:7]
	v_cvt_pk_bf16_f32 v64, v64, v65
	v_add_co_u32_e32 v68, vcc, 0x1000, v96
	s_nop 1
	v_addc_co_u32_e32 v69, vcc, 0, v97, vcc
	global_store_dword v[68:69], v64, off offset:2048
	v_cndmask_b32_e64 v64, v83, v87, s[8:9]
	s_nop 1
; #define SBAR() __builtin_amdgcn_sched_barrier(0)
; DEVFI float dpp_xor1(float x) { return __int_as_float(__builtin_amdgcn_update_dpp(0, __float_as_int(x), 0xB1, 0xF, 0xF, true)); }
; DEVFI void store_nat_m(bfraw* base, long ld, f32x4 (&a)[8], int fr) {
;   const bool odd = fr & 1;
;   bfraw* p0 = base + (odd ? 15 + fr : fr);
; #pragma unroll
;   for (int j = 0; j < 4; ++j)
; #pragma unroll
;     for (int n0 = 0; n0 < 8; n0 += 2) { const float own0 = a[n0][j], own1 = a[n0 + 1][j];
;       const float recv = dpp_xor1(odd ? own0 : own1);
;       const unsigned pk = odd ? cvtpk(recv, own1) : cvtpk(own0, recv);
;       *reinterpret_cast<unsigned*>(p0 + (long)j * ld + n0 * 16) = pk; }
; }
; DEVFI void store_nat(bfraw* dst, long ld, f32x4 (&acc)[4][8], int fr, int fq) {
;   store_nat_m(dst + (long)(0 * 16 + fq * 4) * ld, ld, acc[0], fr); SBAR();
;   store_nat_m(dst + (long)(1 * 16 + fq * 4) * ld, ld, acc[1], fr); SBAR();
;   store_nat_m(dst + (long)(2 * 16 + fq * 4) * ld, ld, acc[2], fr); SBAR();
;   store_nat_m(dst + (long)(3 * 16 + fq * 4) * ld, ld, acc[3], fr); SBAR();
; }
	v_mov_b32_dpp v65, v64 quad_perm:[1,0,3,2] row_mask:0xf bank_mask:0xf bound_ctrl:1
	v_cndmask_b32_e64 v64, v83, v65, s[6:7]
	v_cndmask_b32_e64 v65, v65, v87, s[6:7]
	v_cvt_pk_bf16_f32 v64, v64, v65
	v_add_co_u32_e32 v68, vcc, 0x1000, v96
	s_nop 1
	v_addc_co_u32_e32 v69, vcc, 0, v97, vcc
	global_store_dword v[68:69], v64, off offset:2112
	v_cndmask_b32_e64 v64, v75, v79, s[8:9]
	s_nop 1
	v_mov_b32_dpp v65, v64 quad_perm:[1,0,3,2] row_mask:0xf bank_mask:0xf bound_ctrl:1
	v_cndmask_b32_e64 v64, v75, v65, s[6:7]
	v_cndmask_b32_e64 v65, v65, v79, s[6:7]
	v_cvt_pk_bf16_f32 v64, v64, v65
	v_add_co_u32_e32 v68, vcc, 0x1000, v96
	s_nop 1
	v_addc_co_u32_e32 v69, vcc, 0, v97, vcc
	global_store_dword v[68:69], v64, off offset:2176
	v_cndmask_b32_e64 v64, v67, v71, s[8:9]
	s_nop 1
	v_mov_b32_dpp v64, v64 quad_perm:[1,0,3,2] row_mask:0xf bank_mask:0xf bound_ctrl:1
	v_cndmask_b32_e64 v68, v67, v64, s[6:7]
	v_cndmask_b32_e64 v64, v64, v71, s[6:7]
	v_cvt_pk_bf16_f32 v68, v68, v64
	v_add_co_u32_e32 v64, vcc, 0x1000, v96
	s_nop 1
	v_addc_co_u32_e32 v65, vcc, 0, v97, vcc
	global_store_dword v[64:65], v68, off offset:2240
	v_cndmask_b32_e64 v64, v56, v60, s[8:9]
	s_nop 1
	v_mov_b32_dpp v64, v64 quad_perm:[1,0,3,2] row_mask:0xf bank_mask:0xf bound_ctrl:1
	v_cndmask_b32_e64 v66, v56, v64, s[6:7]
	v_cndmask_b32_e64 v64, v64, v60, s[6:7]
	v_cvt_pk_bf16_f32 v66, v66, v64
	v_lshl_add_u64 v[64:65], v[128:129], 0, v[176:177]
	v_add_co_u32_e32 v68, vcc, 0x10000, v64
	v_cndmask_b32_e64 v56, v48, v52, s[8:9]
	s_nop 0
	v_addc_co_u32_e32 v69, vcc, 0, v65, vcc
	v_mov_b32_dpp v60, v56 quad_perm:[1,0,3,2] row_mask:0xf bank_mask:0xf bound_ctrl:1
	global_store_dword v[68:69], v66, off
	v_cndmask_b32_e64 v56, v48, v60, s[6:7]
	v_cndmask_b32_e64 v60, v60, v52, s[6:7]
	v_cvt_pk_bf16_f32 v56, v56, v60
	v_cndmask_b32_e64 v48, v40, v44, s[8:9]
	v_lshl_add_u64 v[64:65], v[64:65], 0, s[48:49]
	global_store_dword v[64:65], v56, off offset:64
	v_mov_b32_dpp v52, v48 quad_perm:[1,0,3,2] row_mask:0xf bank_mask:0xf bound_ctrl:1
	v_cndmask_b32_e64 v48, v40, v52, s[6:7]
	v_cndmask_b32_e64 v52, v52, v44, s[6:7]
	v_cvt_pk_bf16_f32 v48, v48, v52
	v_cndmask_b32_e64 v40, v32, v36, s[8:9]
	global_store_dword v[64:65], v48, off offset:128
	s_nop 0
	v_mov_b32_dpp v44, v40 quad_perm:[1,0,3,2] row_mask:0xf bank_mask:0xf bound_ctrl:1
	v_cndmask_b32_e64 v40, v32, v44, s[6:7]
	v_cndmask_b32_e64 v44, v44, v36, s[6:7]
	v_cvt_pk_bf16_f32 v40, v40, v44
	v_cndmask_b32_e64 v32, v57, v61, s[8:9]
	global_store_dword v[64:65], v40, off offset:192
	s_nop 0
	v_mov_b32_dpp v36, v32 quad_perm:[1,0,3,2] row_mask:0xf bank_mask:0xf bound_ctrl:1
	v_cndmask_b32_e64 v32, v57, v36, s[6:7]
	v_cndmask_b32_e64 v36, v36, v61, s[6:7]
	v_cvt_pk_bf16_f32 v32, v32, v36
	global_store_dword v[64:65], v32, off offset:2048
	v_cndmask_b32_e64 v32, v49, v53, s[8:9]
	s_nop 1
	v_mov_b32_dpp v36, v32 quad_perm:[1,0,3,2] row_mask:0xf bank_mask:0xf bound_ctrl:1
	v_cndmask_b32_e64 v32, v49, v36, s[6:7]
	v_cndmask_b32_e64 v36, v36, v53, s[6:7]
	v_cvt_pk_bf16_f32 v32, v32, v36
	global_store_dword v[64:65], v32, off offset:2112
	v_cndmask_b32_e64 v32, v41, v45, s[8:9]
	s_nop 1
	v_mov_b32_dpp v36, v32 quad_perm:[1,0,3,2] row_mask:0xf bank_mask:0xf bound_ctrl:1
	v_cndmask_b32_e64 v32, v41, v36, s[6:7]
	v_cndmask_b32_e64 v36, v36, v45, s[6:7]
	v_cvt_pk_bf16_f32 v32, v32, v36
	global_store_dword v[64:65], v32, off offset:2176
	v_cndmask_b32_e64 v32, v33, v37, s[8:9]
	s_nop 1
	v_mov_b32_dpp v36, v32 quad_perm:[1,0,3,2] row_mask:0xf bank_mask:0xf bound_ctrl:1
	v_cndmask_b32_e64 v32, v33, v36, s[6:7]
	v_cndmask_b32_e64 v36, v36, v37, s[6:7]
	v_cvt_pk_bf16_f32 v32, v32, v36
	global_store_dword v[64:65], v32, off offset:2240
	v_cndmask_b32_e64 v32, v58, v62, s[8:9]
	s_nop 1
	v_mov_b32_dpp v33, v32 quad_perm:[1,0,3,2] row_mask:0xf bank_mask:0xf bound_ctrl:1
	v_cndmask_b32_e64 v32, v58, v33, s[6:7]
	v_cndmask_b32_e64 v33, v33, v62, s[6:7]
	v_cvt_pk_bf16_f32 v32, v32, v33
	v_add_co_u32_e32 v36, vcc, 0x1000, v64
	s_nop 1
	v_addc_co_u32_e32 v37, vcc, 0, v65, vcc
	global_store_dword v[36:37], v32, off
	v_cndmask_b32_e64 v32, v50, v54, s[8:9]
	s_nop 1
	v_mov_b32_dpp v33, v32 quad_perm:[1,0,3,2] row_mask:0xf bank_mask:0xf bound_ctrl:1
	v_cndmask_b32_e64 v32, v50, v33, s[6:7]
	v_cndmask_b32_e64 v33, v33, v54, s[6:7]
	v_cvt_pk_bf16_f32 v32, v32, v33
	v_add_co_u32_e32 v36, vcc, 0x1000, v64
	s_nop 1
	v_addc_co_u32_e32 v37, vcc, 0, v65, vcc
	global_store_dword v[36:37], v32, off offset:64
	v_cndmask_b32_e64 v32, v42, v46, s[8:9]
	s_nop 1
	v_mov_b32_dpp v33, v32 quad_perm:[1,0,3,2] row_mask:0xf bank_mask:0xf bound_ctrl:1
	v_cndmask_b32_e64 v32, v42, v33, s[6:7]
	v_cndmask_b32_e64 v33, v33, v46, s[6:7]
	v_cvt_pk_bf16_f32 v32, v32, v33
	v_add_co_u32_e32 v36, vcc, 0x1000, v64
	s_nop 1
	v_addc_co_u32_e32 v37, vcc, 0, v65, vcc
	global_store_dword v[36:37], v32, off offset:128
	v_cndmask_b32_e64 v32, v34, v38, s[8:9]
	s_nop 1
	v_mov_b32_dpp v33, v32 quad_perm:[1,0,3,2] row_mask:0xf bank_mask:0xf bound_ctrl:1
	v_cndmask_b32_e64 v32, v34, v33, s[6:7]
	v_cndmask_b32_e64 v33, v33, v38, s[6:7]
	v_cvt_pk_bf16_f32 v32, v32, v33
	v_add_co_u32_e32 v36, vcc, 0x1000, v64
	s_nop 1
	v_addc_co_u32_e32 v37, vcc, 0, v65, vcc
	global_store_dword v[36:37], v32, off offset:192
	v_cndmask_b32_e64 v32, v59, v63, s[8:9]
	s_nop 1
	v_mov_b32_dpp v33, v32 quad_perm:[1,0,3,2] row_mask:0xf bank_mask:0xf bound_ctrl:1
	v_cndmask_b32_e64 v32, v59, v33, s[6:7]
	v_cndmask_b32_e64 v33, v33, v63, s[6:7]
	v_cvt_pk_bf16_f32 v32, v32, v33
	v_add_co_u32_e32 v36, vcc, 0x1000, v64
	s_nop 1
	v_addc_co_u32_e32 v37, vcc, 0, v65, vcc
	global_store_dword v[36:37], v32, off offset:2048
	v_cndmask_b32_e64 v32, v51, v55, s[8:9]
; #define SBAR() __builtin_amdgcn_sched_barrier(0)
; DEVFI float dpp_xor1(float x) { return __int_as_float(__builtin_amdgcn_update_dpp(0, __float_as_int(x), 0xB1, 0xF, 0xF, true)); }
; DEVFI void store_nat_m(bfraw* base, long ld, f32x4 (&a)[8], int fr) {
;   const bool odd = fr & 1;
;   bfraw* p0 = base + (odd ? 15 + fr : fr);
; #pragma unroll
;   for (int j = 0; j < 4; ++j)
; #pragma unroll
;     for (int n0 = 0; n0 < 8; n0 += 2) { const float own0 = a[n0][j], own1 = a[n0 + 1][j];
;       const float recv = dpp_xor1(odd ? own0 : own1);
;       const unsigned pk = odd ? cvtpk(recv, own1) : cvtpk(own0, recv);
;       *reinterpret_cast<unsigned*>(p0 + (long)j * ld + n0 * 16) = pk; }
; }
; DEVFI void store_nat(bfraw* dst, long ld, f32x4 (&acc)[4][8], int fr, int fq) {
;   store_nat_m(dst + (long)(0 * 16 + fq * 4) * ld, ld, acc[0], fr); SBAR();
;   store_nat_m(dst + (long)(1 * 16 + fq * 4) * ld, ld, acc[1], fr); SBAR();
;   store_nat_m(dst + (long)(2 * 16 + fq * 4) * ld, ld, acc[2], fr); SBAR();
;   store_nat_m(dst + (long)(3 * 16 + fq * 4) * ld, ld, acc[3], fr); SBAR();
; }
	s_nop 1
	v_mov_b32_dpp v33, v32 quad_perm:[1,0,3,2] row_mask:0xf bank_mask:0xf bound_ctrl:1
	v_cndmask_b32_e64 v32, v51, v33, s[6:7]
	v_cndmask_b32_e64 v33, v33, v55, s[6:7]
	v_cvt_pk_bf16_f32 v32, v32, v33
	v_add_co_u32_e32 v36, vcc, 0x1000, v64
	s_nop 1
	v_addc_co_u32_e32 v37, vcc, 0, v65, vcc
	global_store_dword v[36:37], v32, off offset:2112
	v_cndmask_b32_e64 v32, v43, v47, s[8:9]
	s_nop 1
	v_mov_b32_dpp v33, v32 quad_perm:[1,0,3,2] row_mask:0xf bank_mask:0xf bound_ctrl:1
	v_cndmask_b32_e64 v32, v43, v33, s[6:7]
	v_cndmask_b32_e64 v33, v33, v47, s[6:7]
	v_cvt_pk_bf16_f32 v32, v32, v33
	v_add_co_u32_e32 v36, vcc, 0x1000, v64
	s_nop 1
	v_addc_co_u32_e32 v37, vcc, 0, v65, vcc
	global_store_dword v[36:37], v32, off offset:2176
	v_cndmask_b32_e64 v32, v35, v39, s[8:9]
	s_nop 1
	v_mov_b32_dpp v32, v32 quad_perm:[1,0,3,2] row_mask:0xf bank_mask:0xf bound_ctrl:1
	v_cndmask_b32_e64 v36, v35, v32, s[6:7]
	v_cndmask_b32_e64 v32, v32, v39, s[6:7]
	v_cvt_pk_bf16_f32 v36, v36, v32
	v_add_co_u32_e32 v32, vcc, 0x1000, v64
	s_nop 1
	v_addc_co_u32_e32 v33, vcc, 0, v65, vcc
	global_store_dword v[32:33], v36, off offset:2240
	v_cndmask_b32_e64 v32, v24, v28, s[8:9]
	s_nop 1
	v_mov_b32_dpp v32, v32 quad_perm:[1,0,3,2] row_mask:0xf bank_mask:0xf bound_ctrl:1
	v_cndmask_b32_e64 v34, v24, v32, s[6:7]
	v_cndmask_b32_e64 v32, v32, v28, s[6:7]
	v_cvt_pk_bf16_f32 v34, v34, v32
	v_lshl_add_u64 v[32:33], v[128:129], 0, v[176:177]
	v_add_co_u32_e32 v36, vcc, 0x18000, v32
	v_cndmask_b32_e64 v24, v16, v20, s[8:9]
	s_nop 0
	v_addc_co_u32_e32 v37, vcc, 0, v33, vcc
	v_mov_b32_dpp v28, v24 quad_perm:[1,0,3,2] row_mask:0xf bank_mask:0xf bound_ctrl:1
	global_store_dword v[36:37], v34, off
	v_cndmask_b32_e64 v24, v16, v28, s[6:7]
	v_cndmask_b32_e64 v28, v28, v20, s[6:7]
	v_cvt_pk_bf16_f32 v24, v24, v28
	s_mov_b64 s[2:3], 0x18000
	v_cndmask_b32_e64 v16, v8, v12, s[8:9]
	v_lshl_add_u64 v[32:33], v[32:33], 0, s[2:3]
	global_store_dword v[32:33], v24, off offset:64
	v_mov_b32_dpp v20, v16 quad_perm:[1,0,3,2] row_mask:0xf bank_mask:0xf bound_ctrl:1
	v_cndmask_b32_e64 v16, v8, v20, s[6:7]
	v_cndmask_b32_e64 v20, v20, v12, s[6:7]
	v_cvt_pk_bf16_f32 v16, v16, v20
	v_cndmask_b32_e64 v8, v0, v4, s[8:9]
	global_store_dword v[32:33], v16, off offset:128
	s_nop 0
	v_mov_b32_dpp v12, v8 quad_perm:[1,0,3,2] row_mask:0xf bank_mask:0xf bound_ctrl:1
	v_cndmask_b32_e64 v8, v0, v12, s[6:7]
	v_cndmask_b32_e64 v12, v12, v4, s[6:7]
	v_cvt_pk_bf16_f32 v8, v8, v12
	v_cndmask_b32_e64 v0, v25, v29, s[8:9]
	global_store_dword v[32:33], v8, off offset:192
	s_nop 0
	v_mov_b32_dpp v4, v0 quad_perm:[1,0,3,2] row_mask:0xf bank_mask:0xf bound_ctrl:1
	v_cndmask_b32_e64 v0, v25, v4, s[6:7]
	v_cndmask_b32_e64 v4, v4, v29, s[6:7]
	v_cvt_pk_bf16_f32 v0, v0, v4
	global_store_dword v[32:33], v0, off offset:2048
	v_cndmask_b32_e64 v0, v17, v21, s[8:9]
	s_nop 1
	v_mov_b32_dpp v4, v0 quad_perm:[1,0,3,2] row_mask:0xf bank_mask:0xf bound_ctrl:1
	v_cndmask_b32_e64 v0, v17, v4, s[6:7]
	v_cndmask_b32_e64 v4, v4, v21, s[6:7]
	v_cvt_pk_bf16_f32 v0, v0, v4
	global_store_dword v[32:33], v0, off offset:2112
	v_cndmask_b32_e64 v0, v9, v13, s[8:9]
	s_nop 1
	v_mov_b32_dpp v4, v0 quad_perm:[1,0,3,2] row_mask:0xf bank_mask:0xf bound_ctrl:1
	v_cndmask_b32_e64 v0, v9, v4, s[6:7]
	v_cndmask_b32_e64 v4, v4, v13, s[6:7]
	v_cvt_pk_bf16_f32 v0, v0, v4
	global_store_dword v[32:33], v0, off offset:2176
	v_cndmask_b32_e64 v0, v1, v5, s[8:9]
	s_nop 1
	v_mov_b32_dpp v4, v0 quad_perm:[1,0,3,2] row_mask:0xf bank_mask:0xf bound_ctrl:1
	v_cndmask_b32_e64 v0, v1, v4, s[6:7]
	v_cndmask_b32_e64 v4, v4, v5, s[6:7]
	v_cvt_pk_bf16_f32 v0, v0, v4
	global_store_dword v[32:33], v0, off offset:2240
	v_cndmask_b32_e64 v0, v26, v30, s[8:9]
	s_nop 1
	v_mov_b32_dpp v1, v0 quad_perm:[1,0,3,2] row_mask:0xf bank_mask:0xf bound_ctrl:1
	v_cndmask_b32_e64 v0, v26, v1, s[6:7]
	v_cndmask_b32_e64 v1, v1, v30, s[6:7]
	v_cvt_pk_bf16_f32 v0, v0, v1
	v_add_co_u32_e32 v4, vcc, 0x1000, v32
	s_nop 1
	v_addc_co_u32_e32 v5, vcc, 0, v33, vcc
	global_store_dword v[4:5], v0, off
	v_cndmask_b32_e64 v0, v18, v22, s[8:9]
	s_nop 1
	v_mov_b32_dpp v1, v0 quad_perm:[1,0,3,2] row_mask:0xf bank_mask:0xf bound_ctrl:1
	v_cndmask_b32_e64 v0, v18, v1, s[6:7]
	v_cndmask_b32_e64 v1, v1, v22, s[6:7]
	v_cvt_pk_bf16_f32 v0, v0, v1
	v_add_co_u32_e32 v4, vcc, 0x1000, v32
	s_nop 1
	v_addc_co_u32_e32 v5, vcc, 0, v33, vcc
	global_store_dword v[4:5], v0, off offset:64
	v_cndmask_b32_e64 v0, v10, v14, s[8:9]
	s_nop 1
	v_mov_b32_dpp v1, v0 quad_perm:[1,0,3,2] row_mask:0xf bank_mask:0xf bound_ctrl:1
	v_cndmask_b32_e64 v0, v10, v1, s[6:7]
	v_cndmask_b32_e64 v1, v1, v14, s[6:7]
	v_cvt_pk_bf16_f32 v0, v0, v1
	v_add_co_u32_e32 v4, vcc, 0x1000, v32
	s_nop 1
	v_addc_co_u32_e32 v5, vcc, 0, v33, vcc
	global_store_dword v[4:5], v0, off offset:128
	v_cndmask_b32_e64 v0, v2, v6, s[8:9]
	s_nop 1
	v_mov_b32_dpp v1, v0 quad_perm:[1,0,3,2] row_mask:0xf bank_mask:0xf bound_ctrl:1
	v_cndmask_b32_e64 v0, v2, v1, s[6:7]
	v_cndmask_b32_e64 v1, v1, v6, s[6:7]
	v_cvt_pk_bf16_f32 v0, v0, v1
	v_add_co_u32_e32 v4, vcc, 0x1000, v32
	s_nop 1
	v_addc_co_u32_e32 v5, vcc, 0, v33, vcc
	global_store_dword v[4:5], v0, off offset:192
	v_cndmask_b32_e64 v0, v27, v31, s[8:9]
	s_nop 1
	v_mov_b32_dpp v1, v0 quad_perm:[1,0,3,2] row_mask:0xf bank_mask:0xf bound_ctrl:1
	v_cndmask_b32_e64 v0, v27, v1, s[6:7]
	v_cndmask_b32_e64 v1, v1, v31, s[6:7]
	v_cvt_pk_bf16_f32 v0, v0, v1
	v_add_co_u32_e32 v4, vcc, 0x1000, v32
	s_nop 1
	v_addc_co_u32_e32 v5, vcc, 0, v33, vcc
	global_store_dword v[4:5], v0, off offset:2048
	v_cndmask_b32_e64 v0, v19, v23, s[8:9]
	s_nop 1
	v_mov_b32_dpp v1, v0 quad_perm:[1,0,3,2] row_mask:0xf bank_mask:0xf bound_ctrl:1
	v_cndmask_b32_e64 v0, v19, v1, s[6:7]
	v_cndmask_b32_e64 v1, v1, v23, s[6:7]
	v_cvt_pk_bf16_f32 v0, v0, v1
	v_add_co_u32_e32 v4, vcc, 0x1000, v32
	s_nop 1
	v_addc_co_u32_e32 v5, vcc, 0, v33, vcc
	global_store_dword v[4:5], v0, off offset:2112
	v_cndmask_b32_e64 v0, v11, v15, s[8:9]
	s_nop 1
	v_mov_b32_dpp v1, v0 quad_perm:[1,0,3,2] row_mask:0xf bank_mask:0xf bound_ctrl:1
	v_cndmask_b32_e64 v0, v11, v1, s[6:7]
	v_cndmask_b32_e64 v1, v1, v15, s[6:7]
	v_cvt_pk_bf16_f32 v0, v0, v1
	v_add_co_u32_e32 v4, vcc, 0x1000, v32
	s_nop 1
	v_addc_co_u32_e32 v5, vcc, 0, v33, vcc
	global_store_dword v[4:5], v0, off offset:2176
	v_cndmask_b32_e64 v0, v3, v7, s[8:9]
	s_nop 1
	v_mov_b32_dpp v0, v0 quad_perm:[1,0,3,2] row_mask:0xf bank_mask:0xf bound_ctrl:1
	s_and_saveexec_b64 s[2:3], s[6:7]
	s_xor_b64 s[2:3], exec, s[2:3]
	s_cbranch_execz .LBB0_4326
	v_cvt_pk_bf16_f32 v4, v0, v7

; DEVFI int opaque_tid(const int wv) { return (wv << 6) | lane_opaque(); }
; #define WAIT_V0() asm volatile("s_waitcnt vmcnt(0)" ::: "memory")
; DEVFI void gemm_stage(const TileSrc& t, const int buf, const int kt, char* shm, const int wid, const int lane) {
;   int R, C; stage_rc<G_KS>(wid * 1024 + lane * 16, R, C);
;   const int oa = R * t.lda + C, ob = R * t.ldb + C;
; #pragma unroll
;   for (int i = 0; i < G_GL; ++i) {
;     __builtin_amdgcn_global_load_lds((const unsigned*)(t.A + (i * 64 * t.lda + kt * G_BK) + oa), (unsigned*)(shm + buf * G_STAGE_B + wid * 1024 + i * 8192), 16, 0, 0);
;     __builtin_amdgcn_global_load_lds((const unsigned*)(t.B + (i * 64 * t.ldb + kt * G_BK) + ob), (unsigned*)(shm + buf * G_STAGE_B + G_TILE_B + wid * 1024 + i * 8192), 16, 0, 0); }
; }
; DEVFI void gemm_issue0(const TileSrc& t, char* shm, const int wv) { const int tid = opaque_tid(wv); gemm_stage(t, 0, 0, shm, tid >> 6, tid & 63); }
; template <class Epi>
; DEVFI void gemm_main(const TileSrc t, const int K, char* shm, const bool pf, const TileSrc nx, const int wv, Epi epi) {
;   const int tid = opaque_tid(wv), wid = tid >> 6, lane = tid & 63, wr = wid >> 1, wc = wid & 1, fr = lane & 15, fq = lane >> 4;
;     ...
;   f32x4 acc[4][8] = {};
;   const int nt = K / G_BK;
;   const int sw = (fr * 64 + fq * 16) ^ ((fr >> 3) << 5);
;   const char* aBase = shm + wr * 8192 + sw;
;   const char* bBase = shm + G_TILE_B + wc * 16384 + sw;
;   WAIT_V0(); __syncthreads();
.LBB0_4362:
	s_mov_b32 s21, -1
	s_ashr_i32 s23, s33, 7
	v_mbcnt_lo_u32_b32 v0, s21, 0
	v_mbcnt_hi_u32_b32 v133, s21, v0
	v_or_b32_e32 v0, s33, v133
	v_ashrrev_i32_e32 v136, 6, v0
	v_and_b32_e32 v134, 1, v136
	v_and_b32_e32 v132, 15, v133
	v_and_b32_e32 v0, 48, v133
	v_lshlrev_b32_e32 v1, 2, v133
	v_lshl_or_b32 v0, v132, 6, v0
	v_and_b32_e32 v1, 32, v1
	s_lshl_b32 s21, s23, 13
	v_lshlrev_b32_e32 v2, 14, v134
	v_bitop3_b32 v140, s21, v0, v1 bitop3:0xf6
	v_bitop3_b32 v141, v2, v0, v1 bitop3:0xf6
	v_lshlrev_b32_e32 v0, 4, v133
	v_and_b32_e32 v1, 32, v133
	v_lshrrev_b32_e32 v2, 31, v136
	v_add_u32_e32 v2, v136, v2
	v_bitop3_b32 v0, v0, v1, 48 bitop3:0x6c
	v_ashrrev_i32_e32 v137, 1, v2
	v_lshrrev_b32_e32 v138, 1, v0
	v_lshlrev_b32_e32 v0, 8, v133
	v_and_b32_e32 v139, 0x3c00, v0
	v_mul_lo_u32 v0, v137, s66
	v_or_b32_e32 v0, v138, v0
	v_lshlrev_b32_e32 v1, 5, v136
	v_add3_u32 v0, v0, v139, v1
	v_ashrrev_i32_e32 v1, 31, v0
	s_waitcnt vmcnt(0)
	v_lshlrev_b64 v[0:1], 1, v[0:1]
	v_lshl_add_u64 v[128:129], s[18:19], 0, v[0:1]
	v_lshl_add_u64 v[130:131], s[2:3], 0, v[0:1]
	v_mov_b32_e32 v0, 0
	s_mov_b32 s20, 0
	v_lshlrev_b32_e32 v135, 10, v136
	s_mov_b64 s[18:19], 0
	v_mov_b32_e32 v1, v0
	v_mov_b32_e32 v2, v0
	v_mov_b32_e32 v3, v0
	v_mov_b32_e32 v4, v0
	v_mov_b32_e32 v5, v0
	v_mov_b32_e32 v6, v0
	v_mov_b32_e32 v7, v0
	v_mov_b32_e32 v8, v0
	v_mov_b32_e32 v9, v0
	v_mov_b32_e32 v10, v0
	v_mov_b32_e32 v11, v0
	v_mov_b32_e32 v12, v0
	v_mov_b32_e32 v13, v0
	v_mov_b32_e32 v14, v0
	v_mov_b32_e32 v15, v0
	v_mov_b32_e32 v16, v0
	v_mov_b32_e32 v17, v0
	v_mov_b32_e32 v18, v0
	v_mov_b32_e32 v19, v0
	v_mov_b32_e32 v20, v0
	v_mov_b32_e32 v21, v0
	v_mov_b32_e32 v22, v0
	v_mov_b32_e32 v23, v0
	v_mov_b32_e32 v24, v0
	v_mov_b32_e32 v25, v0
	v_mov_b32_e32 v26, v0
	v_mov_b32_e32 v27, v0
	v_mov_b32_e32 v28, v0
	v_mov_b32_e32 v29, v0
	v_mov_b32_e32 v30, v0
	v_mov_b32_e32 v31, v0
	v_mov_b32_e32 v32, v0
	v_mov_b32_e32 v33, v0
	v_mov_b32_e32 v34, v0
	v_mov_b32_e32 v35, v0
	v_mov_b32_e32 v36, v0
	v_mov_b32_e32 v37, v0
	v_mov_b32_e32 v38, v0
	v_mov_b32_e32 v39, v0
	v_mov_b32_e32 v40, v0
	v_mov_b32_e32 v41, v0
	v_mov_b32_e32 v42, v0
	v_mov_b32_e32 v43, v0
	v_mov_b32_e32 v44, v0
	v_mov_b32_e32 v45, v0
	v_mov_b32_e32 v46, v0
	v_mov_b32_e32 v47, v0
	v_mov_b32_e32 v48, v0
	v_mov_b32_e32 v49, v0
	v_mov_b32_e32 v50, v0
	v_mov_b32_e32 v51, v0
	v_mov_b32_e32 v52, v0
	v_mov_b32_e32 v53, v0
	v_mov_b32_e32 v54, v0
	v_mov_b32_e32 v55, v0
	v_mov_b32_e32 v56, v0
	v_mov_b32_e32 v57, v0
	v_mov_b32_e32 v58, v0
	v_mov_b32_e32 v59, v0
	v_mov_b32_e32 v60, v0
	v_mov_b32_e32 v61, v0
	v_mov_b32_e32 v62, v0
	v_mov_b32_e32 v63, v0
	v_mov_b32_e32 v64, v0
	v_mov_b32_e32 v65, v0
	v_mov_b32_e32 v66, v0
	v_mov_b32_e32 v67, v0
	v_mov_b32_e32 v68, v0
	v_mov_b32_e32 v69, v0
	v_mov_b32_e32 v70, v0
	v_mov_b32_e32 v71, v0
	v_mov_b32_e32 v72, v0
	v_mov_b32_e32 v73, v0
	v_mov_b32_e32 v74, v0
	v_mov_b32_e32 v75, v0
	v_mov_b32_e32 v76, v0
	v_mov_b32_e32 v77, v0
	v_mov_b32_e32 v78, v0
	v_mov_b32_e32 v79, v0
	v_mov_b32_e32 v80, v0
	v_mov_b32_e32 v81, v0
	v_mov_b32_e32 v82, v0
	v_mov_b32_e32 v83, v0
	v_mov_b32_e32 v84, v0
	v_mov_b32_e32 v85, v0
	v_mov_b32_e32 v86, v0
	v_mov_b32_e32 v87, v0
	v_mov_b32_e32 v88, v0
	v_mov_b32_e32 v89, v0
	v_mov_b32_e32 v90, v0
	v_mov_b32_e32 v91, v0
	v_mov_b32_e32 v92, v0
	v_mov_b32_e32 v93, v0
	v_mov_b32_e32 v94, v0
	v_mov_b32_e32 v95, v0
	v_mov_b32_e32 v96, v0
	v_mov_b32_e32 v97, v0
	v_mov_b32_e32 v98, v0
	v_mov_b32_e32 v99, v0
	v_mov_b32_e32 v100, v0
	v_mov_b32_e32 v101, v0
	v_mov_b32_e32 v102, v0
	v_mov_b32_e32 v103, v0
	v_mov_b32_e32 v104, v0
	v_mov_b32_e32 v105, v0
	v_mov_b32_e32 v106, v0
	v_mov_b32_e32 v107, v0
	v_mov_b32_e32 v108, v0
	v_mov_b32_e32 v109, v0
	v_mov_b32_e32 v110, v0
	v_mov_b32_e32 v111, v0
	v_mov_b32_e32 v112, v0
	v_mov_b32_e32 v113, v0
	v_mov_b32_e32 v114, v0
	v_mov_b32_e32 v115, v0
	v_mov_b32_e32 v116, v0
	v_mov_b32_e32 v117, v0
	v_mov_b32_e32 v118, v0
	v_mov_b32_e32 v119, v0
	v_mov_b32_e32 v120, v0
	v_mov_b32_e32 v121, v0
	v_mov_b32_e32 v122, v0
	v_mov_b32_e32 v123, v0
	v_mov_b32_e32 v124, v0
	v_mov_b32_e32 v125, v0
	v_mov_b32_e32 v126, v0
	v_mov_b32_e32 v127, v0
	s_waitcnt lgkmcnt(0)
	s_lshr_b32 s2, s33, 6
	s_lshr_b32 s3, s2, 1
	s_sub_u32 s3, s2, s3
	s_mov_b32 s18, 0x20000
	s_lshr_b32 s19, s18, 2
	s_mul_i32 s3, s3, s19
	s_and_b32 s19, s2, 1
	s_lshl_b32 s19, s19, 6
	s_sub_u32 s3, s3, s19
	s_add_u32 s3, s3, 0x80
	s_lshl_b32 s20, s18, 1
	s_lshl_b32 s2, s2, 11
	s_mov_b32 vcc_hi, 0
	s_mov_b32 vcc_lo, s3
	v_lshl_add_u64 v[130:131], v[130:131], 0, vcc
	v_lshl_add_u64 v[128:129], v[128:129], 0, vcc
	s_mov_b32 vcc_lo, s20
	v_lshl_add_u64 v[174:175], v[130:131], 0, vcc
	v_lshl_add_u64 v[224:225], v[128:129], 0, vcc
	v_add_u32_e32 v176, 0x10000, v140
	v_add_u32_e32 v223, 0x10000, v141
	s_nop 0
	v_readfirstlane_b32 s18, v130
	v_readfirstlane_b32 s19, v131
	v_readfirstlane_b32 vcc_lo, v128
	v_readfirstlane_b32 vcc_hi, v129
	s_nop 1
	v_subrev_u32_e32 v130, s18, v130
	v_subrev_u32_e32 v128, vcc_lo, v128
	v_add_u32_e32 v174, s20, v130
	v_add_u32_e32 v224, s20, v128
	s_nop 4
	s_add_u32 m0, s2, 0x10000
	s_nop 0
	global_load_lds_dwordx4 v130, s[18:19]
	s_add_u32 m0, s2, 0x14000
	s_nop 0
	global_load_lds_dwordx4 v174, s[18:19]
	s_add_u32 s18, s18, 64
	s_addc_u32 s19, s19, 0
	s_add_u32 m0, s2, 0x18000
	s_nop 0
	global_load_lds_dwordx4 v128, vcc
	s_add_u32 m0, s2, 0x1c000
	s_nop 0
	global_load_lds_dwordx4 v224, vcc
	s_add_u32 vcc_lo, vcc_lo, 64
	s_addc_u32 vcc_hi, vcc_hi, 0
	s_add_u32 m0, s2, 0x10400
	s_nop 0
	global_load_lds_dwordx4 v130, s[18:19]
	s_add_u32 m0, s2, 0x14400
	s_nop 0
	global_load_lds_dwordx4 v174, s[18:19]
	s_add_u32 s18, s18, 64
	s_addc_u32 s19, s19, 0
	s_add_u32 m0, s2, 0x18400
	s_nop 0
	global_load_lds_dwordx4 v128, vcc
	s_add_u32 m0, s2, 0x1c400
	s_nop 0
	global_load_lds_dwordx4 v224, vcc
	s_add_u32 vcc_lo, vcc_lo, 64
	s_addc_u32 vcc_hi, vcc_hi, 0
	s_waitcnt vmcnt(8)
	s_barrier
	ds_read_b128 v[142:145], v140
	ds_read_b128 v[146:149], v140 offset:2048
	ds_read_b128 v[150:153], v140 offset:4096
	ds_read_b128 v[154:157], v140 offset:6144
	ds_read_b128 v[178:181], v141 offset:32768
	ds_read_b128 v[184:187], v141 offset:34816
	ds_read_b128 v[188:191], v141 offset:36864
	ds_read_b128 v[192:195], v141 offset:38912
	ds_read_b128 v[196:199], v141 offset:40960
	ds_read_b128 v[200:203], v141 offset:43008
	ds_read_b128 v[204:207], v141 offset:45056
	ds_read_b128 v[212:215], v141 offset:47104
	s_mov_b32 s3, 7
; #define SBAR() __builtin_amdgcn_sched_barrier(0)
; #define WAIT_V0() asm volatile("s_waitcnt vmcnt(0)" ::: "memory")
; #define GLDS_STAGE(buf, kt) gemm_stage(t, (buf), (kt), shm, wid, lane)
; template <class Epi>
; DEVFI void gemm_main(const TileSrc t, const int K, char* shm, const bool pf, const TileSrc nx, const int wv, Epi epi) {
;     ...
;   for (int t_ = 0; t_ < nt; ++t_) { const int cur = t_ & 1;
;     if (t_ + 1 < nt) GLDS_STAGE(cur ^ 1, t_ + 1);
; #pragma unroll
;     for (int ks = 0; ks < G_KS; ++ks) {
;       bf16x8 At[4], Bf[8];
; #pragma unroll
;       for (int n = 0; n < 8; ++n) Bf[n] = *(const bf16x8*)(bBase + cur * G_STAGE_B + (n * 2048 + ks * 1024));
;       SBAR();
;       At[0] = *(const bf16x8*)(aBase + cur * G_STAGE_B + (0 * 2048 + ks * 1024)); SBAR();
;       At[1] = *(const bf16x8*)(aBase + cur * G_STAGE_B + (1 * 2048 + ks * 1024)); SBAR();
;       At[2] = *(const bf16x8*)(aBase + cur * G_STAGE_B + (2 * 2048 + ks * 1024)); SBAR();
;       At[3] = *(const bf16x8*)(aBase + cur * G_STAGE_B + (3 * 2048 + ks * 1024));
;       SBAR();
;       __builtin_amdgcn_s_setprio(1);
; #pragma unroll
;       for (int m = 0; m < 4; ++m)
; #pragma unroll
;         for (int n = 0; n < 8; ++n) acc[m][n] = __builtin_amdgcn_mfma_f32_16x16x32_bf16(At[m], Bf[n], acc[m][n], 0, 0, 0);
;       __builtin_amdgcn_s_setprio(0);
;       SBAR();
;     }
;     WAIT_V0(); __syncthreads();
;   }
.LgkM_loop:
	s_waitcnt lgkmcnt(0)
	s_waitcnt vmcnt(8)
	s_barrier
	v_mfma_f32_16x16x32_bf16 v[120:123], v[142:145], v[178:181], v[120:123]
	ds_read_b128 v[158:161], v140 offset:1024
	s_add_u32 m0, s2, 0x0
	v_mfma_f32_16x16x32_bf16 v[88:91], v[146:149], v[178:181], v[88:91]
	ds_read_b128 v[162:165], v140 offset:3072
	v_mfma_f32_16x16x32_bf16 v[56:59], v[150:153], v[178:181], v[56:59]
	ds_read_b128 v[166:169], v140 offset:5120
	global_load_lds_dwordx4 v130, s[18:19]
	v_mfma_f32_16x16x32_bf16 v[24:27], v[154:157], v[178:181], v[24:27]
	ds_read_b128 v[170:173], v140 offset:7168
	v_mfma_f32_16x16x32_bf16 v[112:115], v[142:145], v[184:187], v[112:115]
	ds_read_b128 v[208:211], v141 offset:46080
	v_mfma_f32_16x16x32_bf16 v[80:83], v[146:149], v[184:187], v[80:83]
	ds_read_b128 v[218:221], v141 offset:48128
	v_mfma_f32_16x16x32_bf16 v[48:51], v[150:153], v[184:187], v[48:51]
	ds_read_b128 v[178:181], v141 offset:33792
	v_mfma_f32_16x16x32_bf16 v[16:19], v[154:157], v[184:187], v[16:19]
	ds_read_b128 v[184:187], v141 offset:35840
	v_mfma_f32_16x16x32_bf16 v[104:107], v[142:145], v[188:191], v[104:107]
	s_add_u32 m0, s2, 0x4000
	v_mfma_f32_16x16x32_bf16 v[72:75], v[146:149], v[188:191], v[72:75]
	v_mfma_f32_16x16x32_bf16 v[40:43], v[150:153], v[188:191], v[40:43]
	global_load_lds_dwordx4 v174, s[18:19]
	v_mfma_f32_16x16x32_bf16 v[8:11], v[154:157], v[188:191], v[8:11]
	ds_read_b128 v[188:191], v141 offset:37888
	s_add_u32 s18, s18, 64
	s_addc_u32 s19, s19, 0
	v_mfma_f32_16x16x32_bf16 v[96:99], v[142:145], v[192:195], v[96:99]
	v_mfma_f32_16x16x32_bf16 v[64:67], v[146:149], v[192:195], v[64:67]
	v_mfma_f32_16x16x32_bf16 v[32:35], v[150:153], v[192:195], v[32:35]
	v_mfma_f32_16x16x32_bf16 v[0:3], v[154:157], v[192:195], v[0:3]
	ds_read_b128 v[192:195], v141 offset:39936
	v_mfma_f32_16x16x32_bf16 v[124:127], v[142:145], v[196:199], v[124:127]
	s_add_u32 m0, s2, 0x8000
	v_mfma_f32_16x16x32_bf16 v[92:95], v[146:149], v[196:199], v[92:95]
	v_mfma_f32_16x16x32_bf16 v[60:63], v[150:153], v[196:199], v[60:63]
	global_load_lds_dwordx4 v128, vcc
	v_mfma_f32_16x16x32_bf16 v[28:31], v[154:157], v[196:199], v[28:31]
	ds_read_b128 v[196:199], v141 offset:41984
	v_mfma_f32_16x16x32_bf16 v[116:119], v[142:145], v[200:203], v[116:119]
	v_mfma_f32_16x16x32_bf16 v[84:87], v[146:149], v[200:203], v[84:87]
	v_mfma_f32_16x16x32_bf16 v[52:55], v[150:153], v[200:203], v[52:55]
	v_mfma_f32_16x16x32_bf16 v[20:23], v[154:157], v[200:203], v[20:23]
	ds_read_b128 v[200:203], v141 offset:44032
	v_mfma_f32_16x16x32_bf16 v[108:111], v[142:145], v[204:207], v[108:111]
	s_add_u32 m0, s2, 0xc000
	v_mfma_f32_16x16x32_bf16 v[76:79], v[146:149], v[204:207], v[76:79]
	v_mfma_f32_16x16x32_bf16 v[44:47], v[150:153], v[204:207], v[44:47]
	global_load_lds_dwordx4 v224, vcc
	v_mfma_f32_16x16x32_bf16 v[12:15], v[154:157], v[204:207], v[12:15]
	s_add_u32 vcc_lo, vcc_lo, 64
	s_addc_u32 vcc_hi, vcc_hi, 0
	v_mfma_f32_16x16x32_bf16 v[100:103], v[142:145], v[212:215], v[100:103]
	v_mfma_f32_16x16x32_bf16 v[68:71], v[146:149], v[212:215], v[68:71]
	v_mfma_f32_16x16x32_bf16 v[36:39], v[150:153], v[212:215], v[36:39]
	v_mfma_f32_16x16x32_bf16 v[4:7], v[154:157], v[212:215], v[4:7]
	s_waitcnt lgkmcnt(0)
	s_waitcnt vmcnt(8)
	s_barrier
	v_mfma_f32_16x16x32_bf16 v[120:123], v[158:161], v[178:181], v[120:123]
	ds_read_b128 v[142:145], v176
	s_add_u32 m0, s2, 0x400
	v_mfma_f32_16x16x32_bf16 v[88:91], v[162:165], v[178:181], v[88:91]
	ds_read_b128 v[146:149], v176 offset:2048
	v_mfma_f32_16x16x32_bf16 v[56:59], v[166:169], v[178:181], v[56:59]
	ds_read_b128 v[150:153], v176 offset:4096
	global_load_lds_dwordx4 v130, s[18:19]
	v_mfma_f32_16x16x32_bf16 v[24:27], v[170:173], v[178:181], v[24:27]
	ds_read_b128 v[154:157], v176 offset:6144
	v_mfma_f32_16x16x32_bf16 v[112:115], v[158:161], v[184:187], v[112:115]
	ds_read_b128 v[204:207], v223 offset:45056
	v_mfma_f32_16x16x32_bf16 v[80:83], v[162:165], v[184:187], v[80:83]
	ds_read_b128 v[212:215], v223 offset:47104
	v_mfma_f32_16x16x32_bf16 v[48:51], v[166:169], v[184:187], v[48:51]
	ds_read_b128 v[178:181], v223 offset:32768
	v_mfma_f32_16x16x32_bf16 v[16:19], v[170:173], v[184:187], v[16:19]
	ds_read_b128 v[184:187], v223 offset:34816
	v_mfma_f32_16x16x32_bf16 v[104:107], v[158:161], v[188:191], v[104:107]
	s_add_u32 m0, s2, 0x4400
	v_mfma_f32_16x16x32_bf16 v[72:75], v[162:165], v[188:191], v[72:75]
	v_mfma_f32_16x16x32_bf16 v[40:43], v[166:169], v[188:191], v[40:43]
	global_load_lds_dwordx4 v174, s[18:19]
	v_mfma_f32_16x16x32_bf16 v[8:11], v[170:173], v[188:191], v[8:11]
	ds_read_b128 v[188:191], v223 offset:36864
	s_add_u32 s18, s18, 64
	s_addc_u32 s19, s19, 0
	v_mfma_f32_16x16x32_bf16 v[96:99], v[158:161], v[192:195], v[96:99]
	v_mfma_f32_16x16x32_bf16 v[64:67], v[162:165], v[192:195], v[64:67]
	v_mfma_f32_16x16x32_bf16 v[32:35], v[166:169], v[192:195], v[32:35]
	v_mfma_f32_16x16x32_bf16 v[0:3], v[170:173], v[192:195], v[0:3]
	ds_read_b128 v[192:195], v223 offset:38912
	v_mfma_f32_16x16x32_bf16 v[124:127], v[158:161], v[196:199], v[124:127]
	s_add_u32 m0, s2, 0x8400
	v_mfma_f32_16x16x32_bf16 v[92:95], v[162:165], v[196:199], v[92:95]
	v_mfma_f32_16x16x32_bf16 v[60:63], v[166:169], v[196:199], v[60:63]
	global_load_lds_dwordx4 v128, vcc
	v_mfma_f32_16x16x32_bf16 v[28:31], v[170:173], v[196:199], v[28:31]
	ds_read_b128 v[196:199], v223 offset:40960
	v_mfma_f32_16x16x32_bf16 v[116:119], v[158:161], v[200:203], v[116:119]
	v_mfma_f32_16x16x32_bf16 v[84:87], v[162:165], v[200:203], v[84:87]
	v_mfma_f32_16x16x32_bf16 v[52:55], v[166:169], v[200:203], v[52:55]
	v_mfma_f32_16x16x32_bf16 v[20:23], v[170:173], v[200:203], v[20:23]
	ds_read_b128 v[200:203], v223 offset:43008
	v_mfma_f32_16x16x32_bf16 v[108:111], v[158:161], v[208:211], v[108:111]
	s_add_u32 m0, s2, 0xc400
	v_mfma_f32_16x16x32_bf16 v[76:79], v[162:165], v[208:211], v[76:79]
	v_mfma_f32_16x16x32_bf16 v[44:47], v[166:169], v[208:211], v[44:47]
	global_load_lds_dwordx4 v224, vcc
	v_mfma_f32_16x16x32_bf16 v[12:15], v[170:173], v[208:211], v[12:15]
	s_add_u32 vcc_lo, vcc_lo, 64
	s_addc_u32 vcc_hi, vcc_hi, 0
	v_mfma_f32_16x16x32_bf16 v[100:103], v[158:161], v[218:221], v[100:103]
	v_mfma_f32_16x16x32_bf16 v[68:71], v[162:165], v[218:221], v[68:71]
	v_mfma_f32_16x16x32_bf16 v[36:39], v[166:169], v[218:221], v[36:39]
	v_mfma_f32_16x16x32_bf16 v[4:7], v[170:173], v[218:221], v[4:7]
	s_waitcnt lgkmcnt(0)
	s_waitcnt vmcnt(8)
	s_barrier
; #define SBAR() __builtin_amdgcn_sched_barrier(0)
; #define WAIT_V0() asm volatile("s_waitcnt vmcnt(0)" ::: "memory")
; #define GLDS_STAGE(buf, kt) gemm_stage(t, (buf), (kt), shm, wid, lane)
; template <class Epi>
; DEVFI void gemm_main(const TileSrc t, const int K, char* shm, const bool pf, const TileSrc nx, const int wv, Epi epi) {
;     ...
;   for (int t_ = 0; t_ < nt; ++t_) { const int cur = t_ & 1;
;     if (t_ + 1 < nt) GLDS_STAGE(cur ^ 1, t_ + 1);
; #pragma unroll
;     for (int ks = 0; ks < G_KS; ++ks) {
;       bf16x8 At[4], Bf[8];
; #pragma unroll
;       for (int n = 0; n < 8; ++n) Bf[n] = *(const bf16x8*)(bBase + cur * G_STAGE_B + (n * 2048 + ks * 1024));
;       SBAR();
;       At[0] = *(const bf16x8*)(aBase + cur * G_STAGE_B + (0 * 2048 + ks * 1024)); SBAR();
;       At[1] = *(const bf16x8*)(aBase + cur * G_STAGE_B + (1 * 2048 + ks * 1024)); SBAR();
;       At[2] = *(const bf16x8*)(aBase + cur * G_STAGE_B + (2 * 2048 + ks * 1024)); SBAR();
;       At[3] = *(const bf16x8*)(aBase + cur * G_STAGE_B + (3 * 2048 + ks * 1024));
;       SBAR();
;       __builtin_amdgcn_s_setprio(1);
; #pragma unroll
;       for (int m = 0; m < 4; ++m)
; #pragma unroll
;         for (int n = 0; n < 8; ++n) acc[m][n] = __builtin_amdgcn_mfma_f32_16x16x32_bf16(At[m], Bf[n], acc[m][n], 0, 0, 0);
;       __builtin_amdgcn_s_setprio(0);
;       SBAR();
;     }
;     WAIT_V0(); __syncthreads();
;   }
	v_mfma_f32_16x16x32_bf16 v[120:123], v[142:145], v[178:181], v[120:123]
	ds_read_b128 v[158:161], v176 offset:1024
	s_add_u32 m0, s2, 0x10000
	v_mfma_f32_16x16x32_bf16 v[88:91], v[146:149], v[178:181], v[88:91]
	ds_read_b128 v[162:165], v176 offset:3072
	v_mfma_f32_16x16x32_bf16 v[56:59], v[150:153], v[178:181], v[56:59]
	ds_read_b128 v[166:169], v176 offset:5120
	global_load_lds_dwordx4 v130, s[18:19]
	v_mfma_f32_16x16x32_bf16 v[24:27], v[154:157], v[178:181], v[24:27]
	ds_read_b128 v[170:173], v176 offset:7168
	v_mfma_f32_16x16x32_bf16 v[112:115], v[142:145], v[184:187], v[112:115]
	ds_read_b128 v[208:211], v223 offset:46080
	v_mfma_f32_16x16x32_bf16 v[80:83], v[146:149], v[184:187], v[80:83]
	ds_read_b128 v[218:221], v223 offset:48128
	v_mfma_f32_16x16x32_bf16 v[48:51], v[150:153], v[184:187], v[48:51]
	ds_read_b128 v[178:181], v223 offset:33792
	v_mfma_f32_16x16x32_bf16 v[16:19], v[154:157], v[184:187], v[16:19]
	ds_read_b128 v[184:187], v223 offset:35840
	v_mfma_f32_16x16x32_bf16 v[104:107], v[142:145], v[188:191], v[104:107]
	s_add_u32 m0, s2, 0x14000
	v_mfma_f32_16x16x32_bf16 v[72:75], v[146:149], v[188:191], v[72:75]
	v_mfma_f32_16x16x32_bf16 v[40:43], v[150:153], v[188:191], v[40:43]
	global_load_lds_dwordx4 v174, s[18:19]
	v_mfma_f32_16x16x32_bf16 v[8:11], v[154:157], v[188:191], v[8:11]
	ds_read_b128 v[188:191], v223 offset:37888
	s_add_u32 s18, s18, 64
	s_addc_u32 s19, s19, 0
	v_mfma_f32_16x16x32_bf16 v[96:99], v[142:145], v[192:195], v[96:99]
	v_mfma_f32_16x16x32_bf16 v[64:67], v[146:149], v[192:195], v[64:67]
	v_mfma_f32_16x16x32_bf16 v[32:35], v[150:153], v[192:195], v[32:35]
	v_mfma_f32_16x16x32_bf16 v[0:3], v[154:157], v[192:195], v[0:3]
	ds_read_b128 v[192:195], v223 offset:39936
	v_mfma_f32_16x16x32_bf16 v[124:127], v[142:145], v[196:199], v[124:127]
	s_add_u32 m0, s2, 0x18000
	v_mfma_f32_16x16x32_bf16 v[92:95], v[146:149], v[196:199], v[92:95]
	v_mfma_f32_16x16x32_bf16 v[60:63], v[150:153], v[196:199], v[60:63]
	global_load_lds_dwordx4 v128, vcc
	v_mfma_f32_16x16x32_bf16 v[28:31], v[154:157], v[196:199], v[28:31]
	ds_read_b128 v[196:199], v223 offset:41984
	v_mfma_f32_16x16x32_bf16 v[116:119], v[142:145], v[200:203], v[116:119]
	v_mfma_f32_16x16x32_bf16 v[84:87], v[146:149], v[200:203], v[84:87]
	v_mfma_f32_16x16x32_bf16 v[52:55], v[150:153], v[200:203], v[52:55]
	v_mfma_f32_16x16x32_bf16 v[20:23], v[154:157], v[200:203], v[20:23]
	ds_read_b128 v[200:203], v223 offset:44032
	v_mfma_f32_16x16x32_bf16 v[108:111], v[142:145], v[204:207], v[108:111]
	s_add_u32 m0, s2, 0x1c000
	v_mfma_f32_16x16x32_bf16 v[76:79], v[146:149], v[204:207], v[76:79]
	v_mfma_f32_16x16x32_bf16 v[44:47], v[150:153], v[204:207], v[44:47]
	global_load_lds_dwordx4 v224, vcc
	v_mfma_f32_16x16x32_bf16 v[12:15], v[154:157], v[204:207], v[12:15]
	s_add_u32 vcc_lo, vcc_lo, 64
	s_addc_u32 vcc_hi, vcc_hi, 0
	v_mfma_f32_16x16x32_bf16 v[100:103], v[142:145], v[212:215], v[100:103]
	v_mfma_f32_16x16x32_bf16 v[68:71], v[146:149], v[212:215], v[68:71]
	v_mfma_f32_16x16x32_bf16 v[36:39], v[150:153], v[212:215], v[36:39]
	v_mfma_f32_16x16x32_bf16 v[4:7], v[154:157], v[212:215], v[4:7]
	s_waitcnt lgkmcnt(0)
	s_waitcnt vmcnt(8)
	s_barrier
	v_mfma_f32_16x16x32_bf16 v[120:123], v[158:161], v[178:181], v[120:123]
	ds_read_b128 v[142:145], v140
	s_add_u32 m0, s2, 0x10400
	v_mfma_f32_16x16x32_bf16 v[88:91], v[162:165], v[178:181], v[88:91]
	ds_read_b128 v[146:149], v140 offset:2048
	v_mfma_f32_16x16x32_bf16 v[56:59], v[166:169], v[178:181], v[56:59]
	ds_read_b128 v[150:153], v140 offset:4096
	global_load_lds_dwordx4 v130, s[18:19]
	v_mfma_f32_16x16x32_bf16 v[24:27], v[170:173], v[178:181], v[24:27]
	ds_read_b128 v[154:157], v140 offset:6144
	v_mfma_f32_16x16x32_bf16 v[112:115], v[158:161], v[184:187], v[112:115]
	ds_read_b128 v[204:207], v141 offset:45056
	v_mfma_f32_16x16x32_bf16 v[80:83], v[162:165], v[184:187], v[80:83]
	ds_read_b128 v[212:215], v141 offset:47104
	v_mfma_f32_16x16x32_bf16 v[48:51], v[166:169], v[184:187], v[48:51]
	ds_read_b128 v[178:181], v141 offset:32768
	v_mfma_f32_16x16x32_bf16 v[16:19], v[170:173], v[184:187], v[16:19]
	ds_read_b128 v[184:187], v141 offset:34816
	v_mfma_f32_16x16x32_bf16 v[104:107], v[158:161], v[188:191], v[104:107]
	s_add_u32 m0, s2, 0x14400
	v_mfma_f32_16x16x32_bf16 v[72:75], v[162:165], v[188:191], v[72:75]
	v_mfma_f32_16x16x32_bf16 v[40:43], v[166:169], v[188:191], v[40:43]
	global_load_lds_dwordx4 v174, s[18:19]
	v_mfma_f32_16x16x32_bf16 v[8:11], v[170:173], v[188:191], v[8:11]
	ds_read_b128 v[188:191], v141 offset:36864
	s_add_u32 s18, s18, 64
	s_addc_u32 s19, s19, 0
	v_mfma_f32_16x16x32_bf16 v[96:99], v[158:161], v[192:195], v[96:99]
	v_mfma_f32_16x16x32_bf16 v[64:67], v[162:165], v[192:195], v[64:67]
	v_mfma_f32_16x16x32_bf16 v[32:35], v[166:169], v[192:195], v[32:35]
	v_mfma_f32_16x16x32_bf16 v[0:3], v[170:173], v[192:195], v[0:3]
	ds_read_b128 v[192:195], v141 offset:38912
	v_mfma_f32_16x16x32_bf16 v[124:127], v[158:161], v[196:199], v[124:127]
	s_add_u32 m0, s2, 0x18400
	v_mfma_f32_16x16x32_bf16 v[92:95], v[162:165], v[196:199], v[92:95]
	v_mfma_f32_16x16x32_bf16 v[60:63], v[166:169], v[196:199], v[60:63]
	global_load_lds_dwordx4 v128, vcc
	v_mfma_f32_16x16x32_bf16 v[28:31], v[170:173], v[196:199], v[28:31]
	ds_read_b128 v[196:199], v141 offset:40960
	v_mfma_f32_16x16x32_bf16 v[116:119], v[158:161], v[200:203], v[116:119]
	v_mfma_f32_16x16x32_bf16 v[84:87], v[162:165], v[200:203], v[84:87]
	v_mfma_f32_16x16x32_bf16 v[52:55], v[166:169], v[200:203], v[52:55]
	v_mfma_f32_16x16x32_bf16 v[20:23], v[170:173], v[200:203], v[20:23]
	ds_read_b128 v[200:203], v141 offset:43008
	v_mfma_f32_16x16x32_bf16 v[108:111], v[158:161], v[208:211], v[108:111]
	s_add_u32 m0, s2, 0x1c400
	v_mfma_f32_16x16x32_bf16 v[76:79], v[162:165], v[208:211], v[76:79]
	v_mfma_f32_16x16x32_bf16 v[44:47], v[166:169], v[208:211], v[44:47]
	global_load_lds_dwordx4 v224, vcc
	v_mfma_f32_16x16x32_bf16 v[12:15], v[170:173], v[208:211], v[12:15]
	s_add_u32 vcc_lo, vcc_lo, 64
	s_addc_u32 vcc_hi, vcc_hi, 0
	v_mfma_f32_16x16x32_bf16 v[100:103], v[158:161], v[218:221], v[100:103]
	v_mfma_f32_16x16x32_bf16 v[68:71], v[162:165], v[218:221], v[68:71]
	v_mfma_f32_16x16x32_bf16 v[36:39], v[166:169], v[218:221], v[36:39]
	v_mfma_f32_16x16x32_bf16 v[4:7], v[170:173], v[218:221], v[4:7]
	s_sub_u32 s3, s3, 1
	s_cmp_lg_u32 s3, 0
	s_cbranch_scc1 .LgkM_loop
; #define SBAR() __builtin_amdgcn_sched_barrier(0)
; #define WAIT_V0() asm volatile("s_waitcnt vmcnt(0)" ::: "memory")
; #define GLDS_STAGE(buf, kt) gemm_stage(t, (buf), (kt), shm, wid, lane)
; template <class Epi>
; DEVFI void gemm_main(const TileSrc t, const int K, char* shm, const bool pf, const TileSrc nx, const int wv, Epi epi) {
;     ...
;   for (int t_ = 0; t_ < nt; ++t_) { const int cur = t_ & 1;
;     if (t_ + 1 < nt) GLDS_STAGE(cur ^ 1, t_ + 1);
; #pragma unroll
;     for (int ks = 0; ks < G_KS; ++ks) {
;       bf16x8 At[4], Bf[8];
; #pragma unroll
;       for (int n = 0; n < 8; ++n) Bf[n] = *(const bf16x8*)(bBase + cur * G_STAGE_B + (n * 2048 + ks * 1024));
;       SBAR();
;       At[0] = *(const bf16x8*)(aBase + cur * G_STAGE_B + (0 * 2048 + ks * 1024)); SBAR();
;       At[1] = *(const bf16x8*)(aBase + cur * G_STAGE_B + (1 * 2048 + ks * 1024)); SBAR();
;       At[2] = *(const bf16x8*)(aBase + cur * G_STAGE_B + (2 * 2048 + ks * 1024)); SBAR();
;       At[3] = *(const bf16x8*)(aBase + cur * G_STAGE_B + (3 * 2048 + ks * 1024));
;       SBAR();
;       __builtin_amdgcn_s_setprio(1);
; #pragma unroll
;       for (int m = 0; m < 4; ++m)
; #pragma unroll
;         for (int n = 0; n < 8; ++n) acc[m][n] = __builtin_amdgcn_mfma_f32_16x16x32_bf16(At[m], Bf[n], acc[m][n], 0, 0, 0);
;       __builtin_amdgcn_s_setprio(0);
;       SBAR();
;     }
;     WAIT_V0(); __syncthreads();
;   }
	s_waitcnt lgkmcnt(0)
	s_waitcnt vmcnt(8)
	s_barrier
	v_mfma_f32_16x16x32_bf16 v[120:123], v[142:145], v[178:181], v[120:123]
	ds_read_b128 v[158:161], v140 offset:1024
	v_mfma_f32_16x16x32_bf16 v[88:91], v[146:149], v[178:181], v[88:91]
	ds_read_b128 v[162:165], v140 offset:3072
	v_mfma_f32_16x16x32_bf16 v[56:59], v[150:153], v[178:181], v[56:59]
	ds_read_b128 v[166:169], v140 offset:5120
	v_mfma_f32_16x16x32_bf16 v[24:27], v[154:157], v[178:181], v[24:27]
	ds_read_b128 v[170:173], v140 offset:7168
	v_mfma_f32_16x16x32_bf16 v[112:115], v[142:145], v[184:187], v[112:115]
	ds_read_b128 v[208:211], v141 offset:46080
	v_mfma_f32_16x16x32_bf16 v[80:83], v[146:149], v[184:187], v[80:83]
	ds_read_b128 v[218:221], v141 offset:48128
	v_mfma_f32_16x16x32_bf16 v[48:51], v[150:153], v[184:187], v[48:51]
	ds_read_b128 v[178:181], v141 offset:33792
	v_mfma_f32_16x16x32_bf16 v[16:19], v[154:157], v[184:187], v[16:19]
	ds_read_b128 v[184:187], v141 offset:35840
	v_mfma_f32_16x16x32_bf16 v[104:107], v[142:145], v[188:191], v[104:107]
	v_mfma_f32_16x16x32_bf16 v[72:75], v[146:149], v[188:191], v[72:75]
	v_mfma_f32_16x16x32_bf16 v[40:43], v[150:153], v[188:191], v[40:43]
	v_mfma_f32_16x16x32_bf16 v[8:11], v[154:157], v[188:191], v[8:11]
	ds_read_b128 v[188:191], v141 offset:37888
	v_mfma_f32_16x16x32_bf16 v[96:99], v[142:145], v[192:195], v[96:99]
	v_mfma_f32_16x16x32_bf16 v[64:67], v[146:149], v[192:195], v[64:67]
	v_mfma_f32_16x16x32_bf16 v[32:35], v[150:153], v[192:195], v[32:35]
	v_mfma_f32_16x16x32_bf16 v[0:3], v[154:157], v[192:195], v[0:3]
	ds_read_b128 v[192:195], v141 offset:39936
	v_mfma_f32_16x16x32_bf16 v[124:127], v[142:145], v[196:199], v[124:127]
	v_mfma_f32_16x16x32_bf16 v[92:95], v[146:149], v[196:199], v[92:95]
	v_mfma_f32_16x16x32_bf16 v[60:63], v[150:153], v[196:199], v[60:63]
	v_mfma_f32_16x16x32_bf16 v[28:31], v[154:157], v[196:199], v[28:31]
	ds_read_b128 v[196:199], v141 offset:41984
	v_mfma_f32_16x16x32_bf16 v[116:119], v[142:145], v[200:203], v[116:119]
	v_mfma_f32_16x16x32_bf16 v[84:87], v[146:149], v[200:203], v[84:87]
	v_mfma_f32_16x16x32_bf16 v[52:55], v[150:153], v[200:203], v[52:55]
	v_mfma_f32_16x16x32_bf16 v[20:23], v[154:157], v[200:203], v[20:23]
	ds_read_b128 v[200:203], v141 offset:44032
	v_mfma_f32_16x16x32_bf16 v[108:111], v[142:145], v[204:207], v[108:111]
	v_mfma_f32_16x16x32_bf16 v[76:79], v[146:149], v[204:207], v[76:79]
	v_mfma_f32_16x16x32_bf16 v[44:47], v[150:153], v[204:207], v[44:47]
	v_mfma_f32_16x16x32_bf16 v[12:15], v[154:157], v[204:207], v[12:15]
	v_mfma_f32_16x16x32_bf16 v[100:103], v[142:145], v[212:215], v[100:103]
	v_mfma_f32_16x16x32_bf16 v[68:71], v[146:149], v[212:215], v[68:71]
	v_mfma_f32_16x16x32_bf16 v[36:39], v[150:153], v[212:215], v[36:39]
	v_mfma_f32_16x16x32_bf16 v[4:7], v[154:157], v[212:215], v[4:7]
	s_waitcnt lgkmcnt(0)
	s_waitcnt vmcnt(4)
	s_barrier
	v_mfma_f32_16x16x32_bf16 v[120:123], v[158:161], v[178:181], v[120:123]
	ds_read_b128 v[142:145], v176
	v_mfma_f32_16x16x32_bf16 v[88:91], v[162:165], v[178:181], v[88:91]
	ds_read_b128 v[146:149], v176 offset:2048
	v_mfma_f32_16x16x32_bf16 v[56:59], v[166:169], v[178:181], v[56:59]
	ds_read_b128 v[150:153], v176 offset:4096
	v_mfma_f32_16x16x32_bf16 v[24:27], v[170:173], v[178:181], v[24:27]
	ds_read_b128 v[154:157], v176 offset:6144
	v_mfma_f32_16x16x32_bf16 v[112:115], v[158:161], v[184:187], v[112:115]
	ds_read_b128 v[204:207], v223 offset:45056
	v_mfma_f32_16x16x32_bf16 v[80:83], v[162:165], v[184:187], v[80:83]
	ds_read_b128 v[212:215], v223 offset:47104
	v_mfma_f32_16x16x32_bf16 v[48:51], v[166:169], v[184:187], v[48:51]
	ds_read_b128 v[178:181], v223 offset:32768
	v_mfma_f32_16x16x32_bf16 v[16:19], v[170:173], v[184:187], v[16:19]
	ds_read_b128 v[184:187], v223 offset:34816
	v_mfma_f32_16x16x32_bf16 v[104:107], v[158:161], v[188:191], v[104:107]
	v_mfma_f32_16x16x32_bf16 v[72:75], v[162:165], v[188:191], v[72:75]
	v_mfma_f32_16x16x32_bf16 v[40:43], v[166:169], v[188:191], v[40:43]
	v_mfma_f32_16x16x32_bf16 v[8:11], v[170:173], v[188:191], v[8:11]
	ds_read_b128 v[188:191], v223 offset:36864
	v_mfma_f32_16x16x32_bf16 v[96:99], v[158:161], v[192:195], v[96:99]
	v_mfma_f32_16x16x32_bf16 v[64:67], v[162:165], v[192:195], v[64:67]
	v_mfma_f32_16x16x32_bf16 v[32:35], v[166:169], v[192:195], v[32:35]
	v_mfma_f32_16x16x32_bf16 v[0:3], v[170:173], v[192:195], v[0:3]
	ds_read_b128 v[192:195], v223 offset:38912
	v_mfma_f32_16x16x32_bf16 v[124:127], v[158:161], v[196:199], v[124:127]
	v_mfma_f32_16x16x32_bf16 v[92:95], v[162:165], v[196:199], v[92:95]
	v_mfma_f32_16x16x32_bf16 v[60:63], v[166:169], v[196:199], v[60:63]
	v_mfma_f32_16x16x32_bf16 v[28:31], v[170:173], v[196:199], v[28:31]
	ds_read_b128 v[196:199], v223 offset:40960
	v_mfma_f32_16x16x32_bf16 v[116:119], v[158:161], v[200:203], v[116:119]
	v_mfma_f32_16x16x32_bf16 v[84:87], v[162:165], v[200:203], v[84:87]
	v_mfma_f32_16x16x32_bf16 v[52:55], v[166:169], v[200:203], v[52:55]
	v_mfma_f32_16x16x32_bf16 v[20:23], v[170:173], v[200:203], v[20:23]
	ds_read_b128 v[200:203], v223 offset:43008
	v_mfma_f32_16x16x32_bf16 v[108:111], v[158:161], v[208:211], v[108:111]
	v_mfma_f32_16x16x32_bf16 v[76:79], v[162:165], v[208:211], v[76:79]
	v_mfma_f32_16x16x32_bf16 v[44:47], v[166:169], v[208:211], v[44:47]
	v_mfma_f32_16x16x32_bf16 v[12:15], v[170:173], v[208:211], v[12:15]
	v_mfma_f32_16x16x32_bf16 v[100:103], v[158:161], v[218:221], v[100:103]
	v_mfma_f32_16x16x32_bf16 v[68:71], v[162:165], v[218:221], v[68:71]
	v_mfma_f32_16x16x32_bf16 v[36:39], v[166:169], v[218:221], v[36:39]
	v_mfma_f32_16x16x32_bf16 v[4:7], v[170:173], v[218:221], v[4:7]
	s_waitcnt lgkmcnt(0)
	s_waitcnt vmcnt(0)
	s_barrier
; #define SBAR() __builtin_amdgcn_sched_barrier(0)
; #define WAIT_V0() asm volatile("s_waitcnt vmcnt(0)" ::: "memory")
; #define GLDS_STAGE(buf, kt) gemm_stage(t, (buf), (kt), shm, wid, lane)
; template <class Epi>
; DEVFI void gemm_main(const TileSrc t, const int K, char* shm, const bool pf, const TileSrc nx, const int wv, Epi epi) {
;     ...
;   for (int t_ = 0; t_ < nt; ++t_) { const int cur = t_ & 1;
;     if (t_ + 1 < nt) GLDS_STAGE(cur ^ 1, t_ + 1);
; #pragma unroll
;     for (int ks = 0; ks < G_KS; ++ks) {
;       bf16x8 At[4], Bf[8];
; #pragma unroll
;       for (int n = 0; n < 8; ++n) Bf[n] = *(const bf16x8*)(bBase + cur * G_STAGE_B + (n * 2048 + ks * 1024));
;       SBAR();
;       At[0] = *(const bf16x8*)(aBase + cur * G_STAGE_B + (0 * 2048 + ks * 1024)); SBAR();
;       At[1] = *(const bf16x8*)(aBase + cur * G_STAGE_B + (1 * 2048 + ks * 1024)); SBAR();
;       At[2] = *(const bf16x8*)(aBase + cur * G_STAGE_B + (2 * 2048 + ks * 1024)); SBAR();
;       At[3] = *(const bf16x8*)(aBase + cur * G_STAGE_B + (3 * 2048 + ks * 1024));
;       SBAR();
;       __builtin_amdgcn_s_setprio(1);
; #pragma unroll
;       for (int m = 0; m < 4; ++m)
; #pragma unroll
;         for (int n = 0; n < 8; ++n) acc[m][n] = __builtin_amdgcn_mfma_f32_16x16x32_bf16(At[m], Bf[n], acc[m][n], 0, 0, 0);
;       __builtin_amdgcn_s_setprio(0);
;       SBAR();
;     }
;     WAIT_V0(); __syncthreads();
;   }
;     ...
;   if (pf) gemm_stage(nx, 0, 0, shm, wid, lane);
	v_mfma_f32_16x16x32_bf16 v[120:123], v[142:145], v[178:181], v[120:123]
	ds_read_b128 v[158:161], v176 offset:1024
	v_mfma_f32_16x16x32_bf16 v[88:91], v[146:149], v[178:181], v[88:91]
	ds_read_b128 v[162:165], v176 offset:3072
	v_mfma_f32_16x16x32_bf16 v[56:59], v[150:153], v[178:181], v[56:59]
	ds_read_b128 v[166:169], v176 offset:5120
	v_mfma_f32_16x16x32_bf16 v[24:27], v[154:157], v[178:181], v[24:27]
	ds_read_b128 v[170:173], v176 offset:7168
	v_mfma_f32_16x16x32_bf16 v[112:115], v[142:145], v[184:187], v[112:115]
	ds_read_b128 v[208:211], v223 offset:46080
	v_mfma_f32_16x16x32_bf16 v[80:83], v[146:149], v[184:187], v[80:83]
	ds_read_b128 v[218:221], v223 offset:48128
	v_mfma_f32_16x16x32_bf16 v[48:51], v[150:153], v[184:187], v[48:51]
	ds_read_b128 v[178:181], v223 offset:33792
	v_mfma_f32_16x16x32_bf16 v[16:19], v[154:157], v[184:187], v[16:19]
	ds_read_b128 v[184:187], v223 offset:35840
	v_mfma_f32_16x16x32_bf16 v[104:107], v[142:145], v[188:191], v[104:107]
	v_mfma_f32_16x16x32_bf16 v[72:75], v[146:149], v[188:191], v[72:75]
	v_mfma_f32_16x16x32_bf16 v[40:43], v[150:153], v[188:191], v[40:43]
	v_mfma_f32_16x16x32_bf16 v[8:11], v[154:157], v[188:191], v[8:11]
	ds_read_b128 v[188:191], v223 offset:37888
	v_mfma_f32_16x16x32_bf16 v[96:99], v[142:145], v[192:195], v[96:99]
	v_mfma_f32_16x16x32_bf16 v[64:67], v[146:149], v[192:195], v[64:67]
	v_mfma_f32_16x16x32_bf16 v[32:35], v[150:153], v[192:195], v[32:35]
	v_mfma_f32_16x16x32_bf16 v[0:3], v[154:157], v[192:195], v[0:3]
	ds_read_b128 v[192:195], v223 offset:39936
	v_mfma_f32_16x16x32_bf16 v[124:127], v[142:145], v[196:199], v[124:127]
	v_mfma_f32_16x16x32_bf16 v[92:95], v[146:149], v[196:199], v[92:95]
	v_mfma_f32_16x16x32_bf16 v[60:63], v[150:153], v[196:199], v[60:63]
	v_mfma_f32_16x16x32_bf16 v[28:31], v[154:157], v[196:199], v[28:31]
	ds_read_b128 v[196:199], v223 offset:41984
	v_mfma_f32_16x16x32_bf16 v[116:119], v[142:145], v[200:203], v[116:119]
	v_mfma_f32_16x16x32_bf16 v[84:87], v[146:149], v[200:203], v[84:87]
	v_mfma_f32_16x16x32_bf16 v[52:55], v[150:153], v[200:203], v[52:55]
	v_mfma_f32_16x16x32_bf16 v[20:23], v[154:157], v[200:203], v[20:23]
	ds_read_b128 v[200:203], v223 offset:44032
	v_mfma_f32_16x16x32_bf16 v[108:111], v[142:145], v[204:207], v[108:111]
	v_mfma_f32_16x16x32_bf16 v[76:79], v[146:149], v[204:207], v[76:79]
	v_mfma_f32_16x16x32_bf16 v[44:47], v[150:153], v[204:207], v[44:47]
	v_mfma_f32_16x16x32_bf16 v[12:15], v[154:157], v[204:207], v[12:15]
	v_mfma_f32_16x16x32_bf16 v[100:103], v[142:145], v[212:215], v[100:103]
	v_mfma_f32_16x16x32_bf16 v[68:71], v[146:149], v[212:215], v[68:71]
	v_mfma_f32_16x16x32_bf16 v[36:39], v[150:153], v[212:215], v[36:39]
	v_mfma_f32_16x16x32_bf16 v[4:7], v[154:157], v[212:215], v[4:7]
	s_waitcnt lgkmcnt(0)
	s_barrier
	v_mfma_f32_16x16x32_bf16 v[120:123], v[158:161], v[178:181], v[120:123]
	v_mfma_f32_16x16x32_bf16 v[88:91], v[162:165], v[178:181], v[88:91]
	v_mfma_f32_16x16x32_bf16 v[56:59], v[166:169], v[178:181], v[56:59]
	v_mfma_f32_16x16x32_bf16 v[24:27], v[170:173], v[178:181], v[24:27]
	v_mfma_f32_16x16x32_bf16 v[112:115], v[158:161], v[184:187], v[112:115]
	v_mfma_f32_16x16x32_bf16 v[80:83], v[162:165], v[184:187], v[80:83]
	v_mfma_f32_16x16x32_bf16 v[48:51], v[166:169], v[184:187], v[48:51]
	v_mfma_f32_16x16x32_bf16 v[16:19], v[170:173], v[184:187], v[16:19]
	v_mfma_f32_16x16x32_bf16 v[104:107], v[158:161], v[188:191], v[104:107]
	v_mfma_f32_16x16x32_bf16 v[72:75], v[162:165], v[188:191], v[72:75]
	v_mfma_f32_16x16x32_bf16 v[40:43], v[166:169], v[188:191], v[40:43]
	v_mfma_f32_16x16x32_bf16 v[8:11], v[170:173], v[188:191], v[8:11]
	v_mfma_f32_16x16x32_bf16 v[96:99], v[158:161], v[192:195], v[96:99]
	v_mfma_f32_16x16x32_bf16 v[64:67], v[162:165], v[192:195], v[64:67]
	v_mfma_f32_16x16x32_bf16 v[32:35], v[166:169], v[192:195], v[32:35]
	v_mfma_f32_16x16x32_bf16 v[0:3], v[170:173], v[192:195], v[0:3]
	v_mfma_f32_16x16x32_bf16 v[124:127], v[158:161], v[196:199], v[124:127]
	v_mfma_f32_16x16x32_bf16 v[92:95], v[162:165], v[196:199], v[92:95]
	v_mfma_f32_16x16x32_bf16 v[60:63], v[166:169], v[196:199], v[60:63]
	v_mfma_f32_16x16x32_bf16 v[28:31], v[170:173], v[196:199], v[28:31]
	v_mfma_f32_16x16x32_bf16 v[116:119], v[158:161], v[200:203], v[116:119]
	v_mfma_f32_16x16x32_bf16 v[84:87], v[162:165], v[200:203], v[84:87]
	v_mfma_f32_16x16x32_bf16 v[52:55], v[166:169], v[200:203], v[52:55]
	v_mfma_f32_16x16x32_bf16 v[20:23], v[170:173], v[200:203], v[20:23]
	v_mfma_f32_16x16x32_bf16 v[108:111], v[158:161], v[208:211], v[108:111]
	v_mfma_f32_16x16x32_bf16 v[76:79], v[162:165], v[208:211], v[76:79]
	v_mfma_f32_16x16x32_bf16 v[44:47], v[166:169], v[208:211], v[44:47]
	v_mfma_f32_16x16x32_bf16 v[12:15], v[170:173], v[208:211], v[12:15]
	v_mfma_f32_16x16x32_bf16 v[100:103], v[158:161], v[218:221], v[100:103]
	v_mfma_f32_16x16x32_bf16 v[68:71], v[162:165], v[218:221], v[68:71]
	v_mfma_f32_16x16x32_bf16 v[36:39], v[166:169], v[218:221], v[36:39]
	v_mfma_f32_16x16x32_bf16 v[4:7], v[170:173], v[218:221], v[4:7]
	s_nop 7
	s_nop 3
	s_mov_b64 s[18:19], 0x780
	s_mov_b32 s20, 0xf0000
	s_and_b64 vcc, exec, s[6:7]
	s_cbranch_vccz .LBB0_4366
	v_lshlrev_b32_e32 v128, 1, v137
	v_sub_u32_e32 v128, v136, v128
	v_lshl_or_b32 v129, v137, 14, v139
	v_lshl_add_u32 v128, v128, 5, v129
	v_or_b32_e32 v128, v128, v138
	v_ashrrev_i32_e32 v129, 31, v128
	v_add_u32_e32 v136, 0x8000, v135
	v_lshlrev_b64 v[128:129], 1, v[128:129]
	v_readfirstlane_b32 s2, v135
	v_lshl_add_u64 v[130:131], s[14:15], 0, v[128:129]
	s_mov_b32 m0, s2
	v_readfirstlane_b32 s2, v136
	v_add_u32_e32 v138, 0x2000, v135
	global_load_lds_dwordx4 v[130:131], off
	v_lshl_add_u64 v[128:129], s[16:17], 0, v[128:129]
	s_mov_b32 m0, s2
	v_readfirstlane_b32 s2, v138
	v_add_u32_e32 v138, 0xa000, v135
	global_load_lds_dwordx4 v[128:129], off
	v_lshl_add_u64 v[136:137], v[130:131], 0, s[86:87]
	s_mov_b32 m0, s2
	v_readfirstlane_b32 s2, v138
	v_add_u32_e32 v138, 0x4000, v135
	global_load_lds_dwordx4 v[136:137], off
	v_lshl_add_u64 v[136:137], v[128:129], 0, s[86:87]
	s_mov_b32 m0, s2
	v_readfirstlane_b32 s2, v138
	v_add_u32_e32 v138, 0xc000, v135
	global_load_lds_dwordx4 v[136:137], off
	v_lshl_add_u64 v[136:137], v[130:131], 0, s[88:89]
	s_mov_b32 m0, s2
	v_readfirstlane_b32 s2, v138
	global_load_lds_dwordx4 v[136:137], off
	v_lshl_add_u64 v[136:137], v[128:129], 0, s[88:89]
	s_mov_b32 m0, s2
	v_lshl_add_u64 v[130:131], v[130:131], 0, s[90:91]
	global_load_lds_dwordx4 v[136:137], off
	v_add_u32_e32 v136, 0x6000, v135
	v_lshl_add_u64 v[128:129], v[128:129], 0, s[90:91]
	v_readfirstlane_b32 s2, v136
	s_mov_b32 m0, s2
	s_nop 0
	global_load_lds_dwordx4 v[130:131], off
	v_add_u32_e32 v130, 0xe000, v135
	s_nop 0
	v_readfirstlane_b32 s2, v130
	s_mov_b32 m0, s2
	s_nop 0
	global_load_lds_dwordx4 v[128:129], off

; DEVFI int opaque_tid(const int wv) { return (wv << 6) | lane_opaque(); }
; #define WAIT_V0() asm volatile("s_waitcnt vmcnt(0)" ::: "memory")
; #define GLDS_STAGE(buf, kt) gemm_stage(t, (buf), (kt), shm, wid, lane)
; DEVFI void gemm_stage(const TileSrc& t, const int buf, const int kt, char* shm, const int wid, const int lane) {
;   int R, C; stage_rc<G_KS>(wid * 1024 + lane * 16, R, C);
;   const int oa = R * t.lda + C, ob = R * t.ldb + C;
; #pragma unroll
;   for (int i = 0; i < G_GL; ++i) {
;     __builtin_amdgcn_global_load_lds((const unsigned*)(t.A + (i * 64 * t.lda + kt * G_BK) + oa), (unsigned*)(shm + buf * G_STAGE_B + wid * 1024 + i * 8192), 16, 0, 0);
;     __builtin_amdgcn_global_load_lds((const unsigned*)(t.B + (i * 64 * t.ldb + kt * G_BK) + ob), (unsigned*)(shm + buf * G_STAGE_B + G_TILE_B + wid * 1024 + i * 8192), 16, 0, 0); }
; }
; DEVFI void gemm_issue0(const TileSrc& t, char* shm, const int wv) { const int tid = opaque_tid(wv); gemm_stage(t, 0, 0, shm, tid >> 6, tid & 63); }
; template <class Epi>
; DEVFI void gemm_main(const TileSrc t, const int K, char* shm, const bool pf, const TileSrc nx, const int wv, Epi epi) {
;   const int tid = opaque_tid(wv), wid = tid >> 6, lane = tid & 63, wr = wid >> 1, wc = wid & 1, fr = lane & 15, fq = lane >> 4;
;     ...
;   f32x4 acc[4][8] = {};
;   const int nt = K / G_BK;
;   const int sw = (fr * 64 + fq * 16) ^ ((fr >> 3) << 5);
;   const char* aBase = shm + wr * 8192 + sw;
;   const char* bBase = shm + G_TILE_B + wc * 16384 + sw;
;   WAIT_V0(); __syncthreads();
;   for (int t_ = 0; t_ < nt; ++t_) { const int cur = t_ & 1;
;     if (t_ + 1 < nt) GLDS_STAGE(cur ^ 1, t_ + 1);
.LBB0_4508:
	s_mov_b32 s19, -1
	s_ashr_i32 s21, s33, 7
	v_mbcnt_lo_u32_b32 v0, s19, 0
	v_mbcnt_hi_u32_b32 v135, s19, v0
	v_or_b32_e32 v0, s33, v135
	v_ashrrev_i32_e32 v137, 6, v0
	v_and_b32_e32 v134, 1, v137
	v_and_b32_e32 v132, 15, v135
	v_and_b32_e32 v0, 48, v135
	v_lshlrev_b32_e32 v1, 2, v135
	v_lshl_or_b32 v0, v132, 6, v0
	v_and_b32_e32 v1, 32, v1
	v_lshlrev_b32_e32 v2, 14, v134
	s_lshl_b32 s19, s21, 13
	v_bitop3_b32 v142, v2, v0, v1 bitop3:0xf6
	v_lshrrev_b32_e32 v2, 31, v137
	v_bitop3_b32 v141, s19, v0, v1 bitop3:0xf6
	v_lshlrev_b32_e32 v0, 4, v135
	v_and_b32_e32 v1, 32, v135
	v_add_u32_e32 v2, v137, v2
	v_ashrrev_i32_e32 v138, 1, v2
	v_bitop3_b32 v0, v0, v1, 48 bitop3:0x6c
	s_mov_b32 s19, 0xafc0
	v_bfe_u32 v140, v135, 2, 4
	v_lshrrev_b32_e32 v139, 1, v0
	v_mul_lo_u32 v0, v138, s19
	v_or_b32_e32 v0, v139, v0
	v_mul_u32_u24_e32 v1, 0xb00, v140
	v_lshlrev_b32_e32 v2, 5, v137
	v_add3_u32 v0, v0, v1, v2
	v_ashrrev_i32_e32 v1, 31, v0
	s_waitcnt vmcnt(0)
	v_lshlrev_b64 v[0:1], 1, v[0:1]
	v_lshl_add_u64 v[128:129], s[6:7], 0, v[0:1]
	v_lshl_add_u64 v[130:131], s[2:3], 0, v[0:1]
	v_mov_b32_e32 v0, 0
	s_mov_b32 s18, 0
	v_and_b32_e32 v133, 63, v135
	v_lshlrev_b32_e32 v136, 10, v137
	s_mov_b64 s[6:7], 0
	v_mov_b32_e32 v1, v0
	v_mov_b32_e32 v2, v0
	v_mov_b32_e32 v3, v0
	v_mov_b32_e32 v4, v0
	v_mov_b32_e32 v5, v0
	v_mov_b32_e32 v6, v0
	v_mov_b32_e32 v7, v0
	v_mov_b32_e32 v8, v0
	v_mov_b32_e32 v9, v0
	v_mov_b32_e32 v10, v0
	v_mov_b32_e32 v11, v0
	v_mov_b32_e32 v12, v0
	v_mov_b32_e32 v13, v0
	v_mov_b32_e32 v14, v0
	v_mov_b32_e32 v15, v0
	v_mov_b32_e32 v16, v0
	v_mov_b32_e32 v17, v0
	v_mov_b32_e32 v18, v0
	v_mov_b32_e32 v19, v0
	v_mov_b32_e32 v20, v0
	v_mov_b32_e32 v21, v0
	v_mov_b32_e32 v22, v0
	v_mov_b32_e32 v23, v0
	v_mov_b32_e32 v24, v0
	v_mov_b32_e32 v25, v0
	v_mov_b32_e32 v26, v0
	v_mov_b32_e32 v27, v0
	v_mov_b32_e32 v28, v0
	v_mov_b32_e32 v29, v0
	v_mov_b32_e32 v30, v0
	v_mov_b32_e32 v31, v0
	v_mov_b32_e32 v32, v0
	v_mov_b32_e32 v33, v0
	v_mov_b32_e32 v34, v0
	v_mov_b32_e32 v35, v0
	v_mov_b32_e32 v36, v0
	v_mov_b32_e32 v37, v0
	v_mov_b32_e32 v38, v0
	v_mov_b32_e32 v39, v0
	v_mov_b32_e32 v40, v0
	v_mov_b32_e32 v41, v0
	v_mov_b32_e32 v42, v0
	v_mov_b32_e32 v43, v0
	v_mov_b32_e32 v44, v0
	v_mov_b32_e32 v45, v0
	v_mov_b32_e32 v46, v0
	v_mov_b32_e32 v47, v0
	v_mov_b32_e32 v48, v0
	v_mov_b32_e32 v49, v0
	v_mov_b32_e32 v50, v0
	v_mov_b32_e32 v51, v0
	v_mov_b32_e32 v52, v0
	v_mov_b32_e32 v53, v0
	v_mov_b32_e32 v54, v0
	v_mov_b32_e32 v55, v0
	v_mov_b32_e32 v56, v0
	v_mov_b32_e32 v57, v0
	v_mov_b32_e32 v58, v0
	v_mov_b32_e32 v59, v0
	v_mov_b32_e32 v60, v0
	v_mov_b32_e32 v61, v0
	v_mov_b32_e32 v62, v0
	v_mov_b32_e32 v63, v0
	v_mov_b32_e32 v64, v0
	v_mov_b32_e32 v65, v0
	v_mov_b32_e32 v66, v0
	v_mov_b32_e32 v67, v0
	v_mov_b32_e32 v68, v0
	v_mov_b32_e32 v69, v0
	v_mov_b32_e32 v70, v0
	v_mov_b32_e32 v71, v0
	v_mov_b32_e32 v72, v0
	v_mov_b32_e32 v73, v0
	v_mov_b32_e32 v74, v0
	v_mov_b32_e32 v75, v0
	v_mov_b32_e32 v76, v0
	v_mov_b32_e32 v77, v0
	v_mov_b32_e32 v78, v0
	v_mov_b32_e32 v79, v0
	v_mov_b32_e32 v80, v0
	v_mov_b32_e32 v81, v0
	v_mov_b32_e32 v82, v0
	v_mov_b32_e32 v83, v0
	v_mov_b32_e32 v84, v0
	v_mov_b32_e32 v85, v0
	v_mov_b32_e32 v86, v0
	v_mov_b32_e32 v87, v0
	v_mov_b32_e32 v88, v0
	v_mov_b32_e32 v89, v0
	v_mov_b32_e32 v90, v0
	v_mov_b32_e32 v91, v0
	v_mov_b32_e32 v92, v0
	v_mov_b32_e32 v93, v0
	v_mov_b32_e32 v94, v0
	v_mov_b32_e32 v95, v0
	v_mov_b32_e32 v96, v0
	v_mov_b32_e32 v97, v0
	v_mov_b32_e32 v98, v0
	v_mov_b32_e32 v99, v0
	v_mov_b32_e32 v100, v0
	v_mov_b32_e32 v101, v0
	v_mov_b32_e32 v102, v0
	v_mov_b32_e32 v103, v0
	v_mov_b32_e32 v104, v0
	v_mov_b32_e32 v105, v0
	v_mov_b32_e32 v106, v0
	v_mov_b32_e32 v107, v0
	v_mov_b32_e32 v108, v0
	v_mov_b32_e32 v109, v0
	v_mov_b32_e32 v110, v0
	v_mov_b32_e32 v111, v0
	v_mov_b32_e32 v112, v0
	v_mov_b32_e32 v113, v0
	v_mov_b32_e32 v114, v0
	v_mov_b32_e32 v115, v0
	v_mov_b32_e32 v116, v0
	v_mov_b32_e32 v117, v0
	v_mov_b32_e32 v118, v0
	v_mov_b32_e32 v119, v0
	v_mov_b32_e32 v120, v0
	v_mov_b32_e32 v121, v0
	v_mov_b32_e32 v122, v0
	v_mov_b32_e32 v123, v0
	v_mov_b32_e32 v124, v0
	v_mov_b32_e32 v125, v0
	v_mov_b32_e32 v126, v0
	v_mov_b32_e32 v127, v0
	s_mov_b64 s[24:25], 0xb0080
	s_mov_b64 s[26:27], 0x108080
	s_waitcnt lgkmcnt(0)
	s_lshr_b32 s2, s33, 6
	s_lshr_b32 s3, s2, 1
	s_sub_u32 s3, s2, s3
	s_mov_b32 s6, 0x58000
	s_lshr_b32 s7, s6, 2
	s_mul_i32 s3, s3, s7
	s_and_b32 s7, s2, 1
	s_lshl_b32 s7, s7, 6
	s_sub_u32 s3, s3, s7
	s_add_u32 s3, s3, 0x80
	s_lshl_b32 s18, s6, 1
	s_lshl_b32 s2, s2, 11
	s_mov_b32 vcc_hi, 0
	s_mov_b32 vcc_lo, s3
	v_lshl_add_u64 v[130:131], v[130:131], 0, vcc
	v_lshl_add_u64 v[128:129], v[128:129], 0, vcc
	s_mov_b32 vcc_lo, s18
	v_lshl_add_u64 v[224:225], v[130:131], 0, vcc
	v_lshl_add_u64 v[226:227], v[128:129], 0, vcc
	v_add_u32_e32 v143, 0x10000, v141
	v_add_u32_e32 v176, 0x10000, v142
	s_nop 0
	v_readfirstlane_b32 s6, v130
	v_readfirstlane_b32 s7, v131
	v_readfirstlane_b32 vcc_lo, v128
	v_readfirstlane_b32 vcc_hi, v129
	s_nop 1
	v_subrev_u32_e32 v130, s6, v130
	v_subrev_u32_e32 v128, vcc_lo, v128
	v_add_u32_e32 v224, s18, v130
	v_add_u32_e32 v226, s18, v128
	s_nop 4
	s_add_u32 m0, s2, 0x10000
	s_nop 0
	global_load_lds_dwordx4 v130, s[6:7]
	s_add_u32 m0, s2, 0x14000
	s_nop 0
	global_load_lds_dwordx4 v224, s[6:7]
	s_add_u32 s6, s6, 64
	s_addc_u32 s7, s7, 0
	s_add_u32 m0, s2, 0x18000
	s_nop 0
	global_load_lds_dwordx4 v128, vcc
	s_add_u32 m0, s2, 0x1c000
	s_nop 0
	global_load_lds_dwordx4 v226, vcc
	s_add_u32 vcc_lo, vcc_lo, 64
	s_addc_u32 vcc_hi, vcc_hi, 0
	s_add_u32 m0, s2, 0x10400
	s_nop 0
	global_load_lds_dwordx4 v130, s[6:7]
	s_add_u32 m0, s2, 0x14400
	s_nop 0
	global_load_lds_dwordx4 v224, s[6:7]
	s_add_u32 s6, s6, 64
	s_addc_u32 s7, s7, 0
	s_add_u32 m0, s2, 0x18400
	s_nop 0
	global_load_lds_dwordx4 v128, vcc
	s_add_u32 m0, s2, 0x1c400
	s_nop 0
	global_load_lds_dwordx4 v226, vcc
	s_add_u32 vcc_lo, vcc_lo, 64
	s_addc_u32 vcc_hi, vcc_hi, 0
	s_waitcnt vmcnt(8)
	s_barrier
	ds_read_b128 v[144:147], v141
	ds_read_b128 v[148:151], v141 offset:2048
	ds_read_b128 v[152:155], v141 offset:4096
	ds_read_b128 v[156:159], v141 offset:6144
	ds_read_b128 v[178:181], v142 offset:32768
	ds_read_b128 v[184:187], v142 offset:34816
	ds_read_b128 v[188:191], v142 offset:36864
	ds_read_b128 v[192:195], v142 offset:38912
	ds_read_b128 v[196:199], v142 offset:40960
	ds_read_b128 v[200:203], v142 offset:43008
	ds_read_b128 v[204:207], v142 offset:45056
	ds_read_b128 v[212:215], v142 offset:47104
	s_mov_b32 s3, 21
; #define SBAR() __builtin_amdgcn_sched_barrier(0)
; #define WAIT_V0() asm volatile("s_waitcnt vmcnt(0)" ::: "memory")
; #define GLDS_STAGE(buf, kt) gemm_stage(t, (buf), (kt), shm, wid, lane)
; template <class Epi>
; DEVFI void gemm_main(const TileSrc t, const int K, char* shm, const bool pf, const TileSrc nx, const int wv, Epi epi) {
;     ...
;   for (int t_ = 0; t_ < nt; ++t_) { const int cur = t_ & 1;
;     if (t_ + 1 < nt) GLDS_STAGE(cur ^ 1, t_ + 1);
; #pragma unroll
;     for (int ks = 0; ks < G_KS; ++ks) {
;       bf16x8 At[4], Bf[8];
; #pragma unroll
;       for (int n = 0; n < 8; ++n) Bf[n] = *(const bf16x8*)(bBase + cur * G_STAGE_B + (n * 2048 + ks * 1024));
;       SBAR();
;       At[0] = *(const bf16x8*)(aBase + cur * G_STAGE_B + (0 * 2048 + ks * 1024)); SBAR();
;       At[1] = *(const bf16x8*)(aBase + cur * G_STAGE_B + (1 * 2048 + ks * 1024)); SBAR();
;       At[2] = *(const bf16x8*)(aBase + cur * G_STAGE_B + (2 * 2048 + ks * 1024)); SBAR();
;       At[3] = *(const bf16x8*)(aBase + cur * G_STAGE_B + (3 * 2048 + ks * 1024));
;       SBAR();
;       __builtin_amdgcn_s_setprio(1);
; #pragma unroll
;       for (int m = 0; m < 4; ++m)
; #pragma unroll
;         for (int n = 0; n < 8; ++n) acc[m][n] = __builtin_amdgcn_mfma_f32_16x16x32_bf16(At[m], Bf[n], acc[m][n], 0, 0, 0);
;       __builtin_amdgcn_s_setprio(0);
;       SBAR();
;     }
;     WAIT_V0(); __syncthreads();
.LgkN_loop:
	s_waitcnt lgkmcnt(0)
	s_waitcnt vmcnt(8)
	s_barrier
	v_mfma_f32_16x16x32_bf16 v[120:123], v[144:147], v[178:181], v[120:123]
	ds_read_b128 v[160:163], v141 offset:1024
	s_add_u32 m0, s2, 0x0
	v_mfma_f32_16x16x32_bf16 v[88:91], v[148:151], v[178:181], v[88:91]
	ds_read_b128 v[164:167], v141 offset:3072
	v_mfma_f32_16x16x32_bf16 v[56:59], v[152:155], v[178:181], v[56:59]
	ds_read_b128 v[168:171], v141 offset:5120
	global_load_lds_dwordx4 v130, s[6:7]
	v_mfma_f32_16x16x32_bf16 v[24:27], v[156:159], v[178:181], v[24:27]
	ds_read_b128 v[172:175], v141 offset:7168
	v_mfma_f32_16x16x32_bf16 v[124:127], v[144:147], v[184:187], v[124:127]
	ds_read_b128 v[208:211], v142 offset:46080
	v_mfma_f32_16x16x32_bf16 v[92:95], v[148:151], v[184:187], v[92:95]
	ds_read_b128 v[218:221], v142 offset:48128
	v_mfma_f32_16x16x32_bf16 v[60:63], v[152:155], v[184:187], v[60:63]
	ds_read_b128 v[178:181], v142 offset:33792
	v_mfma_f32_16x16x32_bf16 v[28:31], v[156:159], v[184:187], v[28:31]
	ds_read_b128 v[184:187], v142 offset:35840
	v_mfma_f32_16x16x32_bf16 v[112:115], v[144:147], v[188:191], v[112:115]
	s_add_u32 m0, s2, 0x4000
	v_mfma_f32_16x16x32_bf16 v[80:83], v[148:151], v[188:191], v[80:83]
	v_mfma_f32_16x16x32_bf16 v[48:51], v[152:155], v[188:191], v[48:51]
	global_load_lds_dwordx4 v224, s[6:7]
	v_mfma_f32_16x16x32_bf16 v[16:19], v[156:159], v[188:191], v[16:19]
	ds_read_b128 v[188:191], v142 offset:37888
	s_add_u32 s6, s6, 64
	s_addc_u32 s7, s7, 0
	v_mfma_f32_16x16x32_bf16 v[116:119], v[144:147], v[192:195], v[116:119]
	v_mfma_f32_16x16x32_bf16 v[84:87], v[148:151], v[192:195], v[84:87]
	v_mfma_f32_16x16x32_bf16 v[52:55], v[152:155], v[192:195], v[52:55]
	v_mfma_f32_16x16x32_bf16 v[20:23], v[156:159], v[192:195], v[20:23]
	ds_read_b128 v[192:195], v142 offset:39936
	v_mfma_f32_16x16x32_bf16 v[104:107], v[144:147], v[196:199], v[104:107]
	s_add_u32 m0, s2, 0x8000
	v_mfma_f32_16x16x32_bf16 v[72:75], v[148:151], v[196:199], v[72:75]
	v_mfma_f32_16x16x32_bf16 v[40:43], v[152:155], v[196:199], v[40:43]
	global_load_lds_dwordx4 v128, vcc
	v_mfma_f32_16x16x32_bf16 v[8:11], v[156:159], v[196:199], v[8:11]
	ds_read_b128 v[196:199], v142 offset:41984
	v_mfma_f32_16x16x32_bf16 v[108:111], v[144:147], v[200:203], v[108:111]
	v_mfma_f32_16x16x32_bf16 v[76:79], v[148:151], v[200:203], v[76:79]
	v_mfma_f32_16x16x32_bf16 v[44:47], v[152:155], v[200:203], v[44:47]
	v_mfma_f32_16x16x32_bf16 v[12:15], v[156:159], v[200:203], v[12:15]
	ds_read_b128 v[200:203], v142 offset:44032
	v_mfma_f32_16x16x32_bf16 v[96:99], v[144:147], v[204:207], v[96:99]
	s_add_u32 m0, s2, 0xc000
	v_mfma_f32_16x16x32_bf16 v[64:67], v[148:151], v[204:207], v[64:67]
	v_mfma_f32_16x16x32_bf16 v[32:35], v[152:155], v[204:207], v[32:35]
	global_load_lds_dwordx4 v226, vcc
	v_mfma_f32_16x16x32_bf16 v[0:3], v[156:159], v[204:207], v[0:3]
	s_add_u32 vcc_lo, vcc_lo, 64
	s_addc_u32 vcc_hi, vcc_hi, 0
	v_mfma_f32_16x16x32_bf16 v[100:103], v[144:147], v[212:215], v[100:103]
	v_mfma_f32_16x16x32_bf16 v[68:71], v[148:151], v[212:215], v[68:71]
	v_mfma_f32_16x16x32_bf16 v[36:39], v[152:155], v[212:215], v[36:39]
	v_mfma_f32_16x16x32_bf16 v[4:7], v[156:159], v[212:215], v[4:7]
	s_waitcnt lgkmcnt(0)
	s_waitcnt vmcnt(8)
	s_barrier
	v_mfma_f32_16x16x32_bf16 v[120:123], v[160:163], v[178:181], v[120:123]
	ds_read_b128 v[144:147], v143
	s_add_u32 m0, s2, 0x400
	v_mfma_f32_16x16x32_bf16 v[88:91], v[164:167], v[178:181], v[88:91]
	ds_read_b128 v[148:151], v143 offset:2048
	v_mfma_f32_16x16x32_bf16 v[56:59], v[168:171], v[178:181], v[56:59]
	ds_read_b128 v[152:155], v143 offset:4096
	global_load_lds_dwordx4 v130, s[6:7]
	v_mfma_f32_16x16x32_bf16 v[24:27], v[172:175], v[178:181], v[24:27]
	ds_read_b128 v[156:159], v143 offset:6144
	v_mfma_f32_16x16x32_bf16 v[124:127], v[160:163], v[184:187], v[124:127]
	ds_read_b128 v[204:207], v176 offset:45056
	v_mfma_f32_16x16x32_bf16 v[92:95], v[164:167], v[184:187], v[92:95]
	ds_read_b128 v[212:215], v176 offset:47104
	v_mfma_f32_16x16x32_bf16 v[60:63], v[168:171], v[184:187], v[60:63]
	ds_read_b128 v[178:181], v176 offset:32768
	v_mfma_f32_16x16x32_bf16 v[28:31], v[172:175], v[184:187], v[28:31]
	ds_read_b128 v[184:187], v176 offset:34816
	v_mfma_f32_16x16x32_bf16 v[112:115], v[160:163], v[188:191], v[112:115]
	s_add_u32 m0, s2, 0x4400
	v_mfma_f32_16x16x32_bf16 v[80:83], v[164:167], v[188:191], v[80:83]
	v_mfma_f32_16x16x32_bf16 v[48:51], v[168:171], v[188:191], v[48:51]
	global_load_lds_dwordx4 v224, s[6:7]
	v_mfma_f32_16x16x32_bf16 v[16:19], v[172:175], v[188:191], v[16:19]
	ds_read_b128 v[188:191], v176 offset:36864
	s_add_u32 s6, s6, 64
	s_addc_u32 s7, s7, 0
	v_mfma_f32_16x16x32_bf16 v[116:119], v[160:163], v[192:195], v[116:119]
	v_mfma_f32_16x16x32_bf16 v[84:87], v[164:167], v[192:195], v[84:87]
	v_mfma_f32_16x16x32_bf16 v[52:55], v[168:171], v[192:195], v[52:55]
	v_mfma_f32_16x16x32_bf16 v[20:23], v[172:175], v[192:195], v[20:23]
	ds_read_b128 v[192:195], v176 offset:38912
	v_mfma_f32_16x16x32_bf16 v[104:107], v[160:163], v[196:199], v[104:107]
	s_add_u32 m0, s2, 0x8400
	v_mfma_f32_16x16x32_bf16 v[72:75], v[164:167], v[196:199], v[72:75]
	v_mfma_f32_16x16x32_bf16 v[40:43], v[168:171], v[196:199], v[40:43]
	global_load_lds_dwordx4 v128, vcc
	v_mfma_f32_16x16x32_bf16 v[8:11], v[172:175], v[196:199], v[8:11]
	ds_read_b128 v[196:199], v176 offset:40960
	v_mfma_f32_16x16x32_bf16 v[108:111], v[160:163], v[200:203], v[108:111]
	v_mfma_f32_16x16x32_bf16 v[76:79], v[164:167], v[200:203], v[76:79]
	v_mfma_f32_16x16x32_bf16 v[44:47], v[168:171], v[200:203], v[44:47]
	v_mfma_f32_16x16x32_bf16 v[12:15], v[172:175], v[200:203], v[12:15]
	ds_read_b128 v[200:203], v176 offset:43008
	v_mfma_f32_16x16x32_bf16 v[96:99], v[160:163], v[208:211], v[96:99]
	s_add_u32 m0, s2, 0xc400
	v_mfma_f32_16x16x32_bf16 v[64:67], v[164:167], v[208:211], v[64:67]
	v_mfma_f32_16x16x32_bf16 v[32:35], v[168:171], v[208:211], v[32:35]
	global_load_lds_dwordx4 v226, vcc
	v_mfma_f32_16x16x32_bf16 v[0:3], v[172:175], v[208:211], v[0:3]
	s_add_u32 vcc_lo, vcc_lo, 64
	s_addc_u32 vcc_hi, vcc_hi, 0
	v_mfma_f32_16x16x32_bf16 v[100:103], v[160:163], v[218:221], v[100:103]
	v_mfma_f32_16x16x32_bf16 v[68:71], v[164:167], v[218:221], v[68:71]
	v_mfma_f32_16x16x32_bf16 v[36:39], v[168:171], v[218:221], v[36:39]
	v_mfma_f32_16x16x32_bf16 v[4:7], v[172:175], v[218:221], v[4:7]
	s_waitcnt lgkmcnt(0)
	s_waitcnt vmcnt(8)
	s_barrier
; #define SBAR() __builtin_amdgcn_sched_barrier(0)
; #define WAIT_V0() asm volatile("s_waitcnt vmcnt(0)" ::: "memory")
; #define GLDS_STAGE(buf, kt) gemm_stage(t, (buf), (kt), shm, wid, lane)
; template <class Epi>
; DEVFI void gemm_main(const TileSrc t, const int K, char* shm, const bool pf, const TileSrc nx, const int wv, Epi epi) {
;     ...
;   for (int t_ = 0; t_ < nt; ++t_) { const int cur = t_ & 1;
;     if (t_ + 1 < nt) GLDS_STAGE(cur ^ 1, t_ + 1);
; #pragma unroll
;     for (int ks = 0; ks < G_KS; ++ks) {
;       bf16x8 At[4], Bf[8];
; #pragma unroll
;       for (int n = 0; n < 8; ++n) Bf[n] = *(const bf16x8*)(bBase + cur * G_STAGE_B + (n * 2048 + ks * 1024));
;       SBAR();
;       At[0] = *(const bf16x8*)(aBase + cur * G_STAGE_B + (0 * 2048 + ks * 1024)); SBAR();
;       At[1] = *(const bf16x8*)(aBase + cur * G_STAGE_B + (1 * 2048 + ks * 1024)); SBAR();
;       At[2] = *(const bf16x8*)(aBase + cur * G_STAGE_B + (2 * 2048 + ks * 1024)); SBAR();
;       At[3] = *(const bf16x8*)(aBase + cur * G_STAGE_B + (3 * 2048 + ks * 1024));
;       SBAR();
;       __builtin_amdgcn_s_setprio(1);
; #pragma unroll
;       for (int m = 0; m < 4; ++m)
; #pragma unroll
;         for (int n = 0; n < 8; ++n) acc[m][n] = __builtin_amdgcn_mfma_f32_16x16x32_bf16(At[m], Bf[n], acc[m][n], 0, 0, 0);
;       __builtin_amdgcn_s_setprio(0);
;       SBAR();
;     }
;     WAIT_V0(); __syncthreads();
	v_mfma_f32_16x16x32_bf16 v[120:123], v[144:147], v[178:181], v[120:123]
	ds_read_b128 v[160:163], v143 offset:1024
	s_add_u32 m0, s2, 0x10000
	v_mfma_f32_16x16x32_bf16 v[88:91], v[148:151], v[178:181], v[88:91]
	ds_read_b128 v[164:167], v143 offset:3072
	v_mfma_f32_16x16x32_bf16 v[56:59], v[152:155], v[178:181], v[56:59]
	ds_read_b128 v[168:171], v143 offset:5120
	global_load_lds_dwordx4 v130, s[6:7]
	v_mfma_f32_16x16x32_bf16 v[24:27], v[156:159], v[178:181], v[24:27]
	ds_read_b128 v[172:175], v143 offset:7168
	v_mfma_f32_16x16x32_bf16 v[124:127], v[144:147], v[184:187], v[124:127]
	ds_read_b128 v[208:211], v176 offset:46080
	v_mfma_f32_16x16x32_bf16 v[92:95], v[148:151], v[184:187], v[92:95]
	ds_read_b128 v[218:221], v176 offset:48128
	v_mfma_f32_16x16x32_bf16 v[60:63], v[152:155], v[184:187], v[60:63]
	ds_read_b128 v[178:181], v176 offset:33792
	v_mfma_f32_16x16x32_bf16 v[28:31], v[156:159], v[184:187], v[28:31]
	ds_read_b128 v[184:187], v176 offset:35840
	v_mfma_f32_16x16x32_bf16 v[112:115], v[144:147], v[188:191], v[112:115]
	s_add_u32 m0, s2, 0x14000
	v_mfma_f32_16x16x32_bf16 v[80:83], v[148:151], v[188:191], v[80:83]
	v_mfma_f32_16x16x32_bf16 v[48:51], v[152:155], v[188:191], v[48:51]
	global_load_lds_dwordx4 v224, s[6:7]
	v_mfma_f32_16x16x32_bf16 v[16:19], v[156:159], v[188:191], v[16:19]
	ds_read_b128 v[188:191], v176 offset:37888
	s_add_u32 s6, s6, 64
	s_addc_u32 s7, s7, 0
	v_mfma_f32_16x16x32_bf16 v[116:119], v[144:147], v[192:195], v[116:119]
	v_mfma_f32_16x16x32_bf16 v[84:87], v[148:151], v[192:195], v[84:87]
	v_mfma_f32_16x16x32_bf16 v[52:55], v[152:155], v[192:195], v[52:55]
	v_mfma_f32_16x16x32_bf16 v[20:23], v[156:159], v[192:195], v[20:23]
	ds_read_b128 v[192:195], v176 offset:39936
	v_mfma_f32_16x16x32_bf16 v[104:107], v[144:147], v[196:199], v[104:107]
	s_add_u32 m0, s2, 0x18000
	v_mfma_f32_16x16x32_bf16 v[72:75], v[148:151], v[196:199], v[72:75]
	v_mfma_f32_16x16x32_bf16 v[40:43], v[152:155], v[196:199], v[40:43]
	global_load_lds_dwordx4 v128, vcc
	v_mfma_f32_16x16x32_bf16 v[8:11], v[156:159], v[196:199], v[8:11]
	ds_read_b128 v[196:199], v176 offset:41984
	v_mfma_f32_16x16x32_bf16 v[108:111], v[144:147], v[200:203], v[108:111]
	v_mfma_f32_16x16x32_bf16 v[76:79], v[148:151], v[200:203], v[76:79]
	v_mfma_f32_16x16x32_bf16 v[44:47], v[152:155], v[200:203], v[44:47]
	v_mfma_f32_16x16x32_bf16 v[12:15], v[156:159], v[200:203], v[12:15]
	ds_read_b128 v[200:203], v176 offset:44032
	v_mfma_f32_16x16x32_bf16 v[96:99], v[144:147], v[204:207], v[96:99]
	s_add_u32 m0, s2, 0x1c000
	v_mfma_f32_16x16x32_bf16 v[64:67], v[148:151], v[204:207], v[64:67]
	v_mfma_f32_16x16x32_bf16 v[32:35], v[152:155], v[204:207], v[32:35]
	global_load_lds_dwordx4 v226, vcc
	v_mfma_f32_16x16x32_bf16 v[0:3], v[156:159], v[204:207], v[0:3]
	s_add_u32 vcc_lo, vcc_lo, 64
	s_addc_u32 vcc_hi, vcc_hi, 0
	v_mfma_f32_16x16x32_bf16 v[100:103], v[144:147], v[212:215], v[100:103]
	v_mfma_f32_16x16x32_bf16 v[68:71], v[148:151], v[212:215], v[68:71]
	v_mfma_f32_16x16x32_bf16 v[36:39], v[152:155], v[212:215], v[36:39]
	v_mfma_f32_16x16x32_bf16 v[4:7], v[156:159], v[212:215], v[4:7]
	s_waitcnt lgkmcnt(0)
	s_waitcnt vmcnt(8)
	s_barrier
	v_mfma_f32_16x16x32_bf16 v[120:123], v[160:163], v[178:181], v[120:123]
	ds_read_b128 v[144:147], v141
	s_add_u32 m0, s2, 0x10400
	v_mfma_f32_16x16x32_bf16 v[88:91], v[164:167], v[178:181], v[88:91]
	ds_read_b128 v[148:151], v141 offset:2048
	v_mfma_f32_16x16x32_bf16 v[56:59], v[168:171], v[178:181], v[56:59]
	ds_read_b128 v[152:155], v141 offset:4096
	global_load_lds_dwordx4 v130, s[6:7]
	v_mfma_f32_16x16x32_bf16 v[24:27], v[172:175], v[178:181], v[24:27]
	ds_read_b128 v[156:159], v141 offset:6144
	v_mfma_f32_16x16x32_bf16 v[124:127], v[160:163], v[184:187], v[124:127]
	ds_read_b128 v[204:207], v142 offset:45056
	v_mfma_f32_16x16x32_bf16 v[92:95], v[164:167], v[184:187], v[92:95]
	ds_read_b128 v[212:215], v142 offset:47104
	v_mfma_f32_16x16x32_bf16 v[60:63], v[168:171], v[184:187], v[60:63]
	ds_read_b128 v[178:181], v142 offset:32768
	v_mfma_f32_16x16x32_bf16 v[28:31], v[172:175], v[184:187], v[28:31]
	ds_read_b128 v[184:187], v142 offset:34816
	v_mfma_f32_16x16x32_bf16 v[112:115], v[160:163], v[188:191], v[112:115]
	s_add_u32 m0, s2, 0x14400
	v_mfma_f32_16x16x32_bf16 v[80:83], v[164:167], v[188:191], v[80:83]
	v_mfma_f32_16x16x32_bf16 v[48:51], v[168:171], v[188:191], v[48:51]
	global_load_lds_dwordx4 v224, s[6:7]
	v_mfma_f32_16x16x32_bf16 v[16:19], v[172:175], v[188:191], v[16:19]
	ds_read_b128 v[188:191], v142 offset:36864
	s_add_u32 s6, s6, 64
	s_addc_u32 s7, s7, 0
	v_mfma_f32_16x16x32_bf16 v[116:119], v[160:163], v[192:195], v[116:119]
	v_mfma_f32_16x16x32_bf16 v[84:87], v[164:167], v[192:195], v[84:87]
	v_mfma_f32_16x16x32_bf16 v[52:55], v[168:171], v[192:195], v[52:55]
	v_mfma_f32_16x16x32_bf16 v[20:23], v[172:175], v[192:195], v[20:23]
	ds_read_b128 v[192:195], v142 offset:38912
	v_mfma_f32_16x16x32_bf16 v[104:107], v[160:163], v[196:199], v[104:107]
	s_add_u32 m0, s2, 0x18400
	v_mfma_f32_16x16x32_bf16 v[72:75], v[164:167], v[196:199], v[72:75]
	v_mfma_f32_16x16x32_bf16 v[40:43], v[168:171], v[196:199], v[40:43]
	global_load_lds_dwordx4 v128, vcc
	v_mfma_f32_16x16x32_bf16 v[8:11], v[172:175], v[196:199], v[8:11]
	ds_read_b128 v[196:199], v142 offset:40960
	v_mfma_f32_16x16x32_bf16 v[108:111], v[160:163], v[200:203], v[108:111]
	v_mfma_f32_16x16x32_bf16 v[76:79], v[164:167], v[200:203], v[76:79]
	v_mfma_f32_16x16x32_bf16 v[44:47], v[168:171], v[200:203], v[44:47]
	v_mfma_f32_16x16x32_bf16 v[12:15], v[172:175], v[200:203], v[12:15]
	ds_read_b128 v[200:203], v142 offset:43008
	v_mfma_f32_16x16x32_bf16 v[96:99], v[160:163], v[208:211], v[96:99]
	s_add_u32 m0, s2, 0x1c400
	v_mfma_f32_16x16x32_bf16 v[64:67], v[164:167], v[208:211], v[64:67]
	v_mfma_f32_16x16x32_bf16 v[32:35], v[168:171], v[208:211], v[32:35]
	global_load_lds_dwordx4 v226, vcc
	v_mfma_f32_16x16x32_bf16 v[0:3], v[172:175], v[208:211], v[0:3]
	s_add_u32 vcc_lo, vcc_lo, 64
	s_addc_u32 vcc_hi, vcc_hi, 0
	v_mfma_f32_16x16x32_bf16 v[100:103], v[160:163], v[218:221], v[100:103]
	v_mfma_f32_16x16x32_bf16 v[68:71], v[164:167], v[218:221], v[68:71]
	v_mfma_f32_16x16x32_bf16 v[36:39], v[168:171], v[218:221], v[36:39]
	v_mfma_f32_16x16x32_bf16 v[4:7], v[172:175], v[218:221], v[4:7]
	s_sub_u32 s3, s3, 1
	s_cmp_lg_u32 s3, 0
	s_cbranch_scc1 .LgkN_loop
; #define SBAR() __builtin_amdgcn_sched_barrier(0)
; #define WAIT_V0() asm volatile("s_waitcnt vmcnt(0)" ::: "memory")
; #define GLDS_STAGE(buf, kt) gemm_stage(t, (buf), (kt), shm, wid, lane)
; template <class Epi>
; DEVFI void gemm_main(const TileSrc t, const int K, char* shm, const bool pf, const TileSrc nx, const int wv, Epi epi) {
;     ...
;   for (int t_ = 0; t_ < nt; ++t_) { const int cur = t_ & 1;
;     if (t_ + 1 < nt) GLDS_STAGE(cur ^ 1, t_ + 1);
; #pragma unroll
;     for (int ks = 0; ks < G_KS; ++ks) {
;       bf16x8 At[4], Bf[8];
; #pragma unroll
;       for (int n = 0; n < 8; ++n) Bf[n] = *(const bf16x8*)(bBase + cur * G_STAGE_B + (n * 2048 + ks * 1024));
;       SBAR();
;       At[0] = *(const bf16x8*)(aBase + cur * G_STAGE_B + (0 * 2048 + ks * 1024)); SBAR();
;       At[1] = *(const bf16x8*)(aBase + cur * G_STAGE_B + (1 * 2048 + ks * 1024)); SBAR();
;       At[2] = *(const bf16x8*)(aBase + cur * G_STAGE_B + (2 * 2048 + ks * 1024)); SBAR();
;       At[3] = *(const bf16x8*)(aBase + cur * G_STAGE_B + (3 * 2048 + ks * 1024));
;       SBAR();
;       __builtin_amdgcn_s_setprio(1);
; #pragma unroll
;       for (int m = 0; m < 4; ++m)
; #pragma unroll
;         for (int n = 0; n < 8; ++n) acc[m][n] = __builtin_amdgcn_mfma_f32_16x16x32_bf16(At[m], Bf[n], acc[m][n], 0, 0, 0);
;       __builtin_amdgcn_s_setprio(0);
;       SBAR();
;     }
;     WAIT_V0(); __syncthreads();
	s_waitcnt lgkmcnt(0)
	s_waitcnt vmcnt(8)
	s_barrier
	v_mfma_f32_16x16x32_bf16 v[120:123], v[144:147], v[178:181], v[120:123]
	ds_read_b128 v[160:163], v141 offset:1024
	v_mfma_f32_16x16x32_bf16 v[88:91], v[148:151], v[178:181], v[88:91]
	ds_read_b128 v[164:167], v141 offset:3072
	v_mfma_f32_16x16x32_bf16 v[56:59], v[152:155], v[178:181], v[56:59]
	ds_read_b128 v[168:171], v141 offset:5120
	v_mfma_f32_16x16x32_bf16 v[24:27], v[156:159], v[178:181], v[24:27]
	ds_read_b128 v[172:175], v141 offset:7168
	v_mfma_f32_16x16x32_bf16 v[124:127], v[144:147], v[184:187], v[124:127]
	ds_read_b128 v[208:211], v142 offset:46080
	v_mfma_f32_16x16x32_bf16 v[92:95], v[148:151], v[184:187], v[92:95]
	ds_read_b128 v[218:221], v142 offset:48128
	v_mfma_f32_16x16x32_bf16 v[60:63], v[152:155], v[184:187], v[60:63]
	ds_read_b128 v[178:181], v142 offset:33792
	v_mfma_f32_16x16x32_bf16 v[28:31], v[156:159], v[184:187], v[28:31]
	ds_read_b128 v[184:187], v142 offset:35840
	v_mfma_f32_16x16x32_bf16 v[112:115], v[144:147], v[188:191], v[112:115]
	v_mfma_f32_16x16x32_bf16 v[80:83], v[148:151], v[188:191], v[80:83]
	v_mfma_f32_16x16x32_bf16 v[48:51], v[152:155], v[188:191], v[48:51]
	v_mfma_f32_16x16x32_bf16 v[16:19], v[156:159], v[188:191], v[16:19]
	ds_read_b128 v[188:191], v142 offset:37888
	v_mfma_f32_16x16x32_bf16 v[116:119], v[144:147], v[192:195], v[116:119]
	v_mfma_f32_16x16x32_bf16 v[84:87], v[148:151], v[192:195], v[84:87]
	v_mfma_f32_16x16x32_bf16 v[52:55], v[152:155], v[192:195], v[52:55]
	v_mfma_f32_16x16x32_bf16 v[20:23], v[156:159], v[192:195], v[20:23]
	ds_read_b128 v[192:195], v142 offset:39936
	v_mfma_f32_16x16x32_bf16 v[104:107], v[144:147], v[196:199], v[104:107]
	v_mfma_f32_16x16x32_bf16 v[72:75], v[148:151], v[196:199], v[72:75]
	v_mfma_f32_16x16x32_bf16 v[40:43], v[152:155], v[196:199], v[40:43]
	v_mfma_f32_16x16x32_bf16 v[8:11], v[156:159], v[196:199], v[8:11]
	ds_read_b128 v[196:199], v142 offset:41984
	v_mfma_f32_16x16x32_bf16 v[108:111], v[144:147], v[200:203], v[108:111]
	v_mfma_f32_16x16x32_bf16 v[76:79], v[148:151], v[200:203], v[76:79]
	v_mfma_f32_16x16x32_bf16 v[44:47], v[152:155], v[200:203], v[44:47]
	v_mfma_f32_16x16x32_bf16 v[12:15], v[156:159], v[200:203], v[12:15]
	ds_read_b128 v[200:203], v142 offset:44032
	v_mfma_f32_16x16x32_bf16 v[96:99], v[144:147], v[204:207], v[96:99]
	v_mfma_f32_16x16x32_bf16 v[64:67], v[148:151], v[204:207], v[64:67]
	v_mfma_f32_16x16x32_bf16 v[32:35], v[152:155], v[204:207], v[32:35]
	v_mfma_f32_16x16x32_bf16 v[0:3], v[156:159], v[204:207], v[0:3]
	v_mfma_f32_16x16x32_bf16 v[100:103], v[144:147], v[212:215], v[100:103]
	v_mfma_f32_16x16x32_bf16 v[68:71], v[148:151], v[212:215], v[68:71]
	v_mfma_f32_16x16x32_bf16 v[36:39], v[152:155], v[212:215], v[36:39]
	v_mfma_f32_16x16x32_bf16 v[4:7], v[156:159], v[212:215], v[4:7]
	s_waitcnt lgkmcnt(0)
	s_waitcnt vmcnt(4)
	s_barrier
	v_mfma_f32_16x16x32_bf16 v[120:123], v[160:163], v[178:181], v[120:123]
	ds_read_b128 v[144:147], v143
	v_mfma_f32_16x16x32_bf16 v[88:91], v[164:167], v[178:181], v[88:91]
	ds_read_b128 v[148:151], v143 offset:2048
	v_mfma_f32_16x16x32_bf16 v[56:59], v[168:171], v[178:181], v[56:59]
	ds_read_b128 v[152:155], v143 offset:4096
	v_mfma_f32_16x16x32_bf16 v[24:27], v[172:175], v[178:181], v[24:27]
	ds_read_b128 v[156:159], v143 offset:6144
	v_mfma_f32_16x16x32_bf16 v[124:127], v[160:163], v[184:187], v[124:127]
	ds_read_b128 v[204:207], v176 offset:45056
	v_mfma_f32_16x16x32_bf16 v[92:95], v[164:167], v[184:187], v[92:95]
	ds_read_b128 v[212:215], v176 offset:47104
	v_mfma_f32_16x16x32_bf16 v[60:63], v[168:171], v[184:187], v[60:63]
	ds_read_b128 v[178:181], v176 offset:32768
	v_mfma_f32_16x16x32_bf16 v[28:31], v[172:175], v[184:187], v[28:31]
	ds_read_b128 v[184:187], v176 offset:34816
	v_mfma_f32_16x16x32_bf16 v[112:115], v[160:163], v[188:191], v[112:115]
	v_mfma_f32_16x16x32_bf16 v[80:83], v[164:167], v[188:191], v[80:83]
	v_mfma_f32_16x16x32_bf16 v[48:51], v[168:171], v[188:191], v[48:51]
	v_mfma_f32_16x16x32_bf16 v[16:19], v[172:175], v[188:191], v[16:19]
	ds_read_b128 v[188:191], v176 offset:36864
	v_mfma_f32_16x16x32_bf16 v[116:119], v[160:163], v[192:195], v[116:119]
	v_mfma_f32_16x16x32_bf16 v[84:87], v[164:167], v[192:195], v[84:87]
	v_mfma_f32_16x16x32_bf16 v[52:55], v[168:171], v[192:195], v[52:55]
	v_mfma_f32_16x16x32_bf16 v[20:23], v[172:175], v[192:195], v[20:23]
	ds_read_b128 v[192:195], v176 offset:38912
	v_mfma_f32_16x16x32_bf16 v[104:107], v[160:163], v[196:199], v[104:107]
	v_mfma_f32_16x16x32_bf16 v[72:75], v[164:167], v[196:199], v[72:75]
	v_mfma_f32_16x16x32_bf16 v[40:43], v[168:171], v[196:199], v[40:43]
	v_mfma_f32_16x16x32_bf16 v[8:11], v[172:175], v[196:199], v[8:11]
	ds_read_b128 v[196:199], v176 offset:40960
	v_mfma_f32_16x16x32_bf16 v[108:111], v[160:163], v[200:203], v[108:111]
	v_mfma_f32_16x16x32_bf16 v[76:79], v[164:167], v[200:203], v[76:79]
	v_mfma_f32_16x16x32_bf16 v[44:47], v[168:171], v[200:203], v[44:47]
	v_mfma_f32_16x16x32_bf16 v[12:15], v[172:175], v[200:203], v[12:15]
	ds_read_b128 v[200:203], v176 offset:43008
	v_mfma_f32_16x16x32_bf16 v[96:99], v[160:163], v[208:211], v[96:99]
	v_mfma_f32_16x16x32_bf16 v[64:67], v[164:167], v[208:211], v[64:67]
	v_mfma_f32_16x16x32_bf16 v[32:35], v[168:171], v[208:211], v[32:35]
	v_mfma_f32_16x16x32_bf16 v[0:3], v[172:175], v[208:211], v[0:3]
	v_mfma_f32_16x16x32_bf16 v[100:103], v[160:163], v[218:221], v[100:103]
	v_mfma_f32_16x16x32_bf16 v[68:71], v[164:167], v[218:221], v[68:71]
	v_mfma_f32_16x16x32_bf16 v[36:39], v[168:171], v[218:221], v[36:39]
	v_mfma_f32_16x16x32_bf16 v[4:7], v[172:175], v[218:221], v[4:7]
	s_waitcnt lgkmcnt(0)
	s_waitcnt vmcnt(0)
	s_barrier
; #define SBAR() __builtin_amdgcn_sched_barrier(0)
; #define WAIT_V0() asm volatile("s_waitcnt vmcnt(0)" ::: "memory")
; template <class Epi>
; DEVFI void gemm_main(const TileSrc t, const int K, char* shm, const bool pf, const TileSrc nx, const int wv, Epi epi) {
;     ...
;       for (int m = 0; m < 4; ++m)
; #pragma unroll
;         for (int n = 0; n < 8; ++n) acc[m][n] = __builtin_amdgcn_mfma_f32_16x16x32_bf16(At[m], Bf[n], acc[m][n], 0, 0, 0);
;       __builtin_amdgcn_s_setprio(0);
;       SBAR();
;     }
;     WAIT_V0(); __syncthreads();
;   }
;     ...
;   if (pf) gemm_stage(nx, 0, 0, shm, wid, lane);
	v_mfma_f32_16x16x32_bf16 v[120:123], v[144:147], v[178:181], v[120:123]
	ds_read_b128 v[160:163], v143 offset:1024
	v_mfma_f32_16x16x32_bf16 v[88:91], v[148:151], v[178:181], v[88:91]
	ds_read_b128 v[164:167], v143 offset:3072
	v_mfma_f32_16x16x32_bf16 v[56:59], v[152:155], v[178:181], v[56:59]
	ds_read_b128 v[168:171], v143 offset:5120
	v_mfma_f32_16x16x32_bf16 v[24:27], v[156:159], v[178:181], v[24:27]
	ds_read_b128 v[172:175], v143 offset:7168
	v_mfma_f32_16x16x32_bf16 v[124:127], v[144:147], v[184:187], v[124:127]
	ds_read_b128 v[208:211], v176 offset:46080
	v_mfma_f32_16x16x32_bf16 v[92:95], v[148:151], v[184:187], v[92:95]
	ds_read_b128 v[218:221], v176 offset:48128
	v_mfma_f32_16x16x32_bf16 v[60:63], v[152:155], v[184:187], v[60:63]
	ds_read_b128 v[178:181], v176 offset:33792
	v_mfma_f32_16x16x32_bf16 v[28:31], v[156:159], v[184:187], v[28:31]
	ds_read_b128 v[184:187], v176 offset:35840
	v_mfma_f32_16x16x32_bf16 v[112:115], v[144:147], v[188:191], v[112:115]
	v_mfma_f32_16x16x32_bf16 v[80:83], v[148:151], v[188:191], v[80:83]
	v_mfma_f32_16x16x32_bf16 v[48:51], v[152:155], v[188:191], v[48:51]
	v_mfma_f32_16x16x32_bf16 v[16:19], v[156:159], v[188:191], v[16:19]
	ds_read_b128 v[188:191], v176 offset:37888
	v_mfma_f32_16x16x32_bf16 v[116:119], v[144:147], v[192:195], v[116:119]
	v_mfma_f32_16x16x32_bf16 v[84:87], v[148:151], v[192:195], v[84:87]
	v_mfma_f32_16x16x32_bf16 v[52:55], v[152:155], v[192:195], v[52:55]
	v_mfma_f32_16x16x32_bf16 v[20:23], v[156:159], v[192:195], v[20:23]
	ds_read_b128 v[192:195], v176 offset:39936
	v_mfma_f32_16x16x32_bf16 v[104:107], v[144:147], v[196:199], v[104:107]
	v_mfma_f32_16x16x32_bf16 v[72:75], v[148:151], v[196:199], v[72:75]
	v_mfma_f32_16x16x32_bf16 v[40:43], v[152:155], v[196:199], v[40:43]
	v_mfma_f32_16x16x32_bf16 v[8:11], v[156:159], v[196:199], v[8:11]
	ds_read_b128 v[196:199], v176 offset:41984
	v_mfma_f32_16x16x32_bf16 v[108:111], v[144:147], v[200:203], v[108:111]
	v_mfma_f32_16x16x32_bf16 v[76:79], v[148:151], v[200:203], v[76:79]
	v_mfma_f32_16x16x32_bf16 v[44:47], v[152:155], v[200:203], v[44:47]
	v_mfma_f32_16x16x32_bf16 v[12:15], v[156:159], v[200:203], v[12:15]
	ds_read_b128 v[200:203], v176 offset:44032
	v_mfma_f32_16x16x32_bf16 v[96:99], v[144:147], v[204:207], v[96:99]
	v_mfma_f32_16x16x32_bf16 v[64:67], v[148:151], v[204:207], v[64:67]
	v_mfma_f32_16x16x32_bf16 v[32:35], v[152:155], v[204:207], v[32:35]
	v_mfma_f32_16x16x32_bf16 v[0:3], v[156:159], v[204:207], v[0:3]
	v_mfma_f32_16x16x32_bf16 v[100:103], v[144:147], v[212:215], v[100:103]
	v_mfma_f32_16x16x32_bf16 v[68:71], v[148:151], v[212:215], v[68:71]
	v_mfma_f32_16x16x32_bf16 v[36:39], v[152:155], v[212:215], v[36:39]
	v_mfma_f32_16x16x32_bf16 v[4:7], v[156:159], v[212:215], v[4:7]
	s_waitcnt lgkmcnt(0)
	s_barrier
	v_mfma_f32_16x16x32_bf16 v[120:123], v[160:163], v[178:181], v[120:123]
	v_mfma_f32_16x16x32_bf16 v[88:91], v[164:167], v[178:181], v[88:91]
	v_mfma_f32_16x16x32_bf16 v[56:59], v[168:171], v[178:181], v[56:59]
	v_mfma_f32_16x16x32_bf16 v[24:27], v[172:175], v[178:181], v[24:27]
	v_mfma_f32_16x16x32_bf16 v[124:127], v[160:163], v[184:187], v[124:127]
	v_mfma_f32_16x16x32_bf16 v[92:95], v[164:167], v[184:187], v[92:95]
	v_mfma_f32_16x16x32_bf16 v[60:63], v[168:171], v[184:187], v[60:63]
	v_mfma_f32_16x16x32_bf16 v[28:31], v[172:175], v[184:187], v[28:31]
	v_mfma_f32_16x16x32_bf16 v[112:115], v[160:163], v[188:191], v[112:115]
	v_mfma_f32_16x16x32_bf16 v[80:83], v[164:167], v[188:191], v[80:83]
	v_mfma_f32_16x16x32_bf16 v[48:51], v[168:171], v[188:191], v[48:51]
	v_mfma_f32_16x16x32_bf16 v[16:19], v[172:175], v[188:191], v[16:19]
	v_mfma_f32_16x16x32_bf16 v[116:119], v[160:163], v[192:195], v[116:119]
	v_mfma_f32_16x16x32_bf16 v[84:87], v[164:167], v[192:195], v[84:87]
	v_mfma_f32_16x16x32_bf16 v[52:55], v[168:171], v[192:195], v[52:55]
	v_mfma_f32_16x16x32_bf16 v[20:23], v[172:175], v[192:195], v[20:23]
	v_mfma_f32_16x16x32_bf16 v[104:107], v[160:163], v[196:199], v[104:107]
	v_mfma_f32_16x16x32_bf16 v[72:75], v[164:167], v[196:199], v[72:75]
	v_mfma_f32_16x16x32_bf16 v[40:43], v[168:171], v[196:199], v[40:43]
	v_mfma_f32_16x16x32_bf16 v[8:11], v[172:175], v[196:199], v[8:11]
	v_mfma_f32_16x16x32_bf16 v[108:111], v[160:163], v[200:203], v[108:111]
	v_mfma_f32_16x16x32_bf16 v[76:79], v[164:167], v[200:203], v[76:79]
	v_mfma_f32_16x16x32_bf16 v[44:47], v[168:171], v[200:203], v[44:47]
	v_mfma_f32_16x16x32_bf16 v[12:15], v[172:175], v[200:203], v[12:15]
	v_mfma_f32_16x16x32_bf16 v[96:99], v[160:163], v[208:211], v[96:99]
	v_mfma_f32_16x16x32_bf16 v[64:67], v[164:167], v[208:211], v[64:67]
	v_mfma_f32_16x16x32_bf16 v[32:35], v[168:171], v[208:211], v[32:35]
	v_mfma_f32_16x16x32_bf16 v[0:3], v[172:175], v[208:211], v[0:3]
	v_mfma_f32_16x16x32_bf16 v[100:103], v[160:163], v[218:221], v[100:103]
	v_mfma_f32_16x16x32_bf16 v[68:71], v[164:167], v[218:221], v[68:71]
	v_mfma_f32_16x16x32_bf16 v[36:39], v[168:171], v[218:221], v[36:39]
	v_mfma_f32_16x16x32_bf16 v[4:7], v[172:175], v[218:221], v[4:7]
	s_nop 7
	s_nop 3
	s_mov_b64 s[6:7], 0x1580
	s_mov_b32 s18, 0x2b0000
	s_and_b64 vcc, exec, s[4:5]
	s_cbranch_vccz .LBB0_4512
	v_lshlrev_b32_e32 v128, 1, v138
	v_sub_u32_e32 v128, v137, v128
	v_lshl_or_b32 v129, v138, 4, v140
	v_lshl_or_b32 v128, v128, 5, v139
	v_mad_u64_u32 v[128:129], s[2:3], v129, s39, v[128:129]
	v_ashrrev_i32_e32 v129, 31, v128
	v_add_u32_e32 v137, 0x8000, v136
	v_lshlrev_b64 v[128:129], 1, v[128:129]
	v_readfirstlane_b32 s2, v136
	v_lshl_add_u64 v[130:131], s[14:15], 0, v[128:129]
	s_mov_b32 m0, s2
	v_readfirstlane_b32 s2, v137
	v_add_u32_e32 v137, 0x2000, v136
	global_load_lds_dwordx4 v[130:131], off
	v_lshl_add_u64 v[128:129], s[16:17], 0, v[128:129]
	s_mov_b32 m0, s2
	s_mov_b64 s[4:5], 0x58000
	v_readfirstlane_b32 s2, v137
	v_add_u32_e32 v137, 0xa000, v136
	global_load_lds_dwordx4 v[128:129], off
	v_lshl_add_u64 v[138:139], v[130:131], 0, s[4:5]
	s_mov_b32 m0, s2
	v_readfirstlane_b32 s2, v137
	v_add_u32_e32 v137, 0x4000, v136
	global_load_lds_dwordx4 v[138:139], off
	v_lshl_add_u64 v[138:139], v[128:129], 0, s[4:5]
	s_mov_b32 m0, s2
	s_mov_b64 s[4:5], 0xb0000
	v_readfirstlane_b32 s2, v137
	v_add_u32_e32 v137, 0xc000, v136
	global_load_lds_dwordx4 v[138:139], off
	v_lshl_add_u64 v[138:139], v[130:131], 0, s[4:5]
	s_mov_b32 m0, s2
	v_readfirstlane_b32 s2, v137
	v_add_u32_e32 v137, 0x6000, v136
	global_load_lds_dwordx4 v[138:139], off
	v_lshl_add_u64 v[138:139], v[128:129], 0, s[4:5]
	s_mov_b32 m0, s2
	s_mov_b64 s[4:5], 0x108000
	v_readfirstlane_b32 s2, v137
	global_load_lds_dwordx4 v[138:139], off
	v_lshl_add_u64 v[130:131], v[130:131], 0, s[4:5]
	s_mov_b32 m0, s2
	v_lshl_add_u64 v[128:129], v[128:129], 0, s[4:5]
	global_load_lds_dwordx4 v[130:131], off
	v_add_u32_e32 v130, 0xe000, v136
	s_nop 0
	v_readfirstlane_b32 s2, v130
	s_mov_b32 m0, s2
	s_nop 0
	global_load_lds_dwordx4 v[128:129], off
; #define SBAR() __builtin_amdgcn_sched_barrier(0)
; DEVFI float dpp_xor1(float x) { return __int_as_float(__builtin_amdgcn_update_dpp(0, __float_as_int(x), 0xB1, 0xF, 0xF, true)); }
; #define XBF ((bfraw*)(kargs()->ws + O_XBF))
; DEVFI void store_nat_m(bfraw* base, long ld, f32x4 (&a)[8], int fr) {
;   const bool odd = fr & 1;
;   bfraw* p0 = base + (odd ? 15 + fr : fr);
; #pragma unroll
;   for (int j = 0; j < 4; ++j)
; #pragma unroll
;     for (int n0 = 0; n0 < 8; n0 += 2) { const float own0 = a[n0][j], own1 = a[n0 + 1][j];
;       const float recv = dpp_xor1(odd ? own0 : own1);
;       const unsigned pk = odd ? cvtpk(recv, own1) : cvtpk(own0, recv);
;       *reinterpret_cast<unsigned*>(p0 + (long)j * ld + n0 * 16) = pk; }
; }
; DEVFI void store_nat(bfraw* dst, long ld, f32x4 (&acc)[4][8], int fr, int fq) {
;   store_nat_m(dst + (long)(0 * 16 + fq * 4) * ld, ld, acc[0], fr); SBAR();
;   store_nat_m(dst + (long)(1 * 16 + fq * 4) * ld, ld, acc[1], fr); SBAR();
;   store_nat_m(dst + (long)(2 * 16 + fq * 4) * ld, ld, acc[2], fr); SBAR();
;   store_nat_m(dst + (long)(3 * 16 + fq * 4) * ld, ld, acc[3], fr); SBAR();
; }
; __global__ void __launch_bounds__(512) mega(Params p) {
;     ...
;         [&](const int u, f32x4 (&acc)[4][8], int wr0, int wc0, int fr, int fq) { TILE256(u); store_nat(XBF + (long)(brow + wr0) * 1024 + bcol + wc0, 1024, acc, fr, fq); });
.LBB0_4512:
	s_mov_b64 s[2:3], s[0:1]
	s_load_dwordx2 s[2:3], s[2:3], 0xe8
	v_and_b32_e32 v128, 1, v135
	v_cmp_eq_u32_e64 s[6:7], 0, v128
	v_cmp_eq_u32_e64 s[4:5], 1, v128
	s_nop 0
	v_cndmask_b32_e64 v128, v120, v124, s[6:7]
	s_nop 1
	v_mov_b32_dpp v128, v128 quad_perm:[1,0,3,2] row_mask:0xf bank_mask:0xf bound_ctrl:1
	v_cndmask_b32_e64 v135, v120, v128, s[4:5]
	v_cndmask_b32_e64 v128, v128, v124, s[4:5]
	v_cvt_pk_bf16_f32 v135, v135, v128
	s_lshr_b32 s18, s12, 2
	s_and_b32 s18, s18, 0xfffff8
	s_and_b32 s19, s12, 7
	s_or_b32 s18, s18, s19
	s_lshl_b32 s18, s18, 8
	v_mov_b32_e32 v120, s18
	v_lshl_add_u32 v128, s21, 6, v120
	v_ashrrev_i32_e32 v129, 31, v128
	v_lshlrev_b64 v[128:129], 11, v[128:129]
	s_waitcnt lgkmcnt(0)
	v_lshl_add_u64 v[128:129], s[2:3], 0, v[128:129]
	s_lshl_b32 s2, s12, 6
	s_and_b32 s12, s2, 0x600
	v_lshl_add_u64 v[128:129], v[128:129], 0, s[12:13]
	v_lshlrev_b32_e32 v176, 8, v134
	v_lshlrev_b32_e32 v120, 9, v133
	v_lshl_add_u64 v[128:129], v[128:129], 0, v[176:177]
	v_and_b32_e32 v176, 0x6000, v120
	v_add_u32_e32 v120, 15, v132
	v_lshl_add_u64 v[128:129], v[128:129], 0, v[176:177]
	s_mov_b64 s[2:3], 0x7720000
	v_cndmask_b32_e64 v120, v120, v132, s[6:7]
	v_lshl_add_u64 v[128:129], v[128:129], 0, s[2:3]
	v_lshlrev_b32_e32 v176, 1, v120
	v_cndmask_b32_e64 v120, v112, v116, s[6:7]
	v_lshl_add_u64 v[130:131], v[128:129], 0, v[176:177]
	global_store_dword v[130:131], v135, off
	v_mov_b32_dpp v124, v120 quad_perm:[1,0,3,2] row_mask:0xf bank_mask:0xf bound_ctrl:1
	s_and_saveexec_b64 s[2:3], s[4:5]
	s_xor_b64 s[2:3], exec, s[2:3]
	s_mov_b64 s[22:23], 0x58080
	s_cbranch_execz .LBB0_4518
	v_cvt_pk_bf16_f32 v120, v124, v116

; DEVFI float dpp_xor1(float x) { return __int_as_float(__builtin_amdgcn_update_dpp(0, __float_as_int(x), 0xB1, 0xF, 0xF, true)); }
; DEVFI void store_nat_m(bfraw* base, long ld, f32x4 (&a)[8], int fr) {
;   const bool odd = fr & 1;
;   bfraw* p0 = base + (odd ? 15 + fr : fr);
; #pragma unroll
;   for (int j = 0; j < 4; ++j)
; #pragma unroll
;     for (int n0 = 0; n0 < 8; n0 += 2) { const float own0 = a[n0][j], own1 = a[n0 + 1][j];
;       const float recv = dpp_xor1(odd ? own0 : own1);
;       const unsigned pk = odd ? cvtpk(recv, own1) : cvtpk(own0, recv);
;       *reinterpret_cast<unsigned*>(p0 + (long)j * ld + n0 * 16) = pk; }
; }
.LBB0_4520:
	s_or_b64 exec, exec, s[2:3]
	v_cndmask_b32_e64 v112, v104, v108, s[6:7]
	global_store_dword v[130:131], v120, off offset:64
	s_nop 0
	v_mov_b32_dpp v116, v112 quad_perm:[1,0,3,2] row_mask:0xf bank_mask:0xf bound_ctrl:1
	v_cndmask_b32_e64 v112, v104, v116, s[4:5]
	v_cndmask_b32_e64 v116, v116, v108, s[4:5]
	v_cvt_pk_bf16_f32 v112, v112, v116
	v_cndmask_b32_e64 v104, v96, v100, s[6:7]
	global_store_dword v[130:131], v112, off offset:128
	s_nop 0
	v_mov_b32_dpp v108, v104 quad_perm:[1,0,3,2] row_mask:0xf bank_mask:0xf bound_ctrl:1
	v_cndmask_b32_e64 v104, v96, v108, s[4:5]
	v_cndmask_b32_e64 v108, v108, v100, s[4:5]
	v_cvt_pk_bf16_f32 v104, v104, v108
	v_cndmask_b32_e64 v96, v121, v125, s[6:7]
	global_store_dword v[130:131], v104, off offset:192
	s_nop 0
	v_mov_b32_dpp v100, v96 quad_perm:[1,0,3,2] row_mask:0xf bank_mask:0xf bound_ctrl:1
	v_cndmask_b32_e64 v96, v121, v100, s[4:5]
	v_cndmask_b32_e64 v100, v100, v125, s[4:5]
	v_cvt_pk_bf16_f32 v96, v96, v100
	global_store_dword v[130:131], v96, off offset:2048
	v_cndmask_b32_e64 v96, v113, v117, s[6:7]
	s_nop 1
	v_mov_b32_dpp v100, v96 quad_perm:[1,0,3,2] row_mask:0xf bank_mask:0xf bound_ctrl:1
	v_cndmask_b32_e64 v96, v113, v100, s[4:5]
	v_cndmask_b32_e64 v100, v100, v117, s[4:5]
	v_cvt_pk_bf16_f32 v96, v96, v100
	global_store_dword v[130:131], v96, off offset:2112
	v_cndmask_b32_e64 v96, v105, v109, s[6:7]
	s_nop 1
	v_mov_b32_dpp v100, v96 quad_perm:[1,0,3,2] row_mask:0xf bank_mask:0xf bound_ctrl:1
	v_cndmask_b32_e64 v96, v105, v100, s[4:5]
	v_cndmask_b32_e64 v100, v100, v109, s[4:5]
	v_cvt_pk_bf16_f32 v96, v96, v100
	global_store_dword v[130:131], v96, off offset:2176
	v_cndmask_b32_e64 v96, v97, v101, s[6:7]
	s_nop 1
	v_mov_b32_dpp v100, v96 quad_perm:[1,0,3,2] row_mask:0xf bank_mask:0xf bound_ctrl:1
	v_cndmask_b32_e64 v96, v97, v100, s[4:5]
	v_cndmask_b32_e64 v100, v100, v101, s[4:5]
	v_cvt_pk_bf16_f32 v96, v96, v100
	global_store_dword v[130:131], v96, off offset:2240
	v_cndmask_b32_e64 v96, v122, v126, s[6:7]
	s_nop 1
	v_mov_b32_dpp v97, v96 quad_perm:[1,0,3,2] row_mask:0xf bank_mask:0xf bound_ctrl:1
	v_cndmask_b32_e64 v96, v122, v97, s[4:5]
	v_cndmask_b32_e64 v97, v97, v126, s[4:5]
	v_cvt_pk_bf16_f32 v96, v96, v97
	v_add_co_u32_e32 v100, vcc, 0x1000, v130
	s_nop 1
	v_addc_co_u32_e32 v101, vcc, 0, v131, vcc
	global_store_dword v[100:101], v96, off
	v_cndmask_b32_e64 v96, v114, v118, s[6:7]
	s_nop 1
	v_mov_b32_dpp v97, v96 quad_perm:[1,0,3,2] row_mask:0xf bank_mask:0xf bound_ctrl:1
	v_cndmask_b32_e64 v96, v114, v97, s[4:5]
	v_cndmask_b32_e64 v97, v97, v118, s[4:5]
	v_cvt_pk_bf16_f32 v96, v96, v97
	v_add_co_u32_e32 v100, vcc, 0x1000, v130
	s_nop 1
	v_addc_co_u32_e32 v101, vcc, 0, v131, vcc
	global_store_dword v[100:101], v96, off offset:64
	v_cndmask_b32_e64 v96, v106, v110, s[6:7]
	s_nop 1
	v_mov_b32_dpp v97, v96 quad_perm:[1,0,3,2] row_mask:0xf bank_mask:0xf bound_ctrl:1
	v_cndmask_b32_e64 v96, v106, v97, s[4:5]
	v_cndmask_b32_e64 v97, v97, v110, s[4:5]
	v_cvt_pk_bf16_f32 v96, v96, v97
	v_add_co_u32_e32 v100, vcc, 0x1000, v130
	s_nop 1
	v_addc_co_u32_e32 v101, vcc, 0, v131, vcc
	global_store_dword v[100:101], v96, off offset:128
	v_cndmask_b32_e64 v96, v98, v102, s[6:7]
	s_nop 1
	v_mov_b32_dpp v97, v96 quad_perm:[1,0,3,2] row_mask:0xf bank_mask:0xf bound_ctrl:1
	v_cndmask_b32_e64 v96, v98, v97, s[4:5]
	v_cndmask_b32_e64 v97, v97, v102, s[4:5]
	v_cvt_pk_bf16_f32 v96, v96, v97
	v_add_co_u32_e32 v100, vcc, 0x1000, v130
	s_nop 1
	v_addc_co_u32_e32 v101, vcc, 0, v131, vcc
	global_store_dword v[100:101], v96, off offset:192
	v_cndmask_b32_e64 v96, v123, v127, s[6:7]
	s_nop 1
	v_mov_b32_dpp v97, v96 quad_perm:[1,0,3,2] row_mask:0xf bank_mask:0xf bound_ctrl:1
	v_cndmask_b32_e64 v96, v123, v97, s[4:5]
	v_cndmask_b32_e64 v97, v97, v127, s[4:5]
	v_cvt_pk_bf16_f32 v96, v96, v97
	v_add_co_u32_e32 v100, vcc, 0x1000, v130
	s_nop 1
	v_addc_co_u32_e32 v101, vcc, 0, v131, vcc
	global_store_dword v[100:101], v96, off offset:2048
	v_cndmask_b32_e64 v96, v115, v119, s[6:7]
	s_nop 1
	v_mov_b32_dpp v97, v96 quad_perm:[1,0,3,2] row_mask:0xf bank_mask:0xf bound_ctrl:1
	v_cndmask_b32_e64 v96, v115, v97, s[4:5]
	v_cndmask_b32_e64 v97, v97, v119, s[4:5]
	v_cvt_pk_bf16_f32 v96, v96, v97
	v_add_co_u32_e32 v100, vcc, 0x1000, v130
	s_nop 1
	v_addc_co_u32_e32 v101, vcc, 0, v131, vcc
	global_store_dword v[100:101], v96, off offset:2112
	v_cndmask_b32_e64 v96, v107, v111, s[6:7]
	s_nop 1
	v_mov_b32_dpp v97, v96 quad_perm:[1,0,3,2] row_mask:0xf bank_mask:0xf bound_ctrl:1
	v_cndmask_b32_e64 v96, v107, v97, s[4:5]
	v_cndmask_b32_e64 v97, v97, v111, s[4:5]
	v_cvt_pk_bf16_f32 v96, v96, v97
	v_add_co_u32_e32 v100, vcc, 0x1000, v130
	s_nop 1
	v_addc_co_u32_e32 v101, vcc, 0, v131, vcc
	global_store_dword v[100:101], v96, off offset:2176
	v_cndmask_b32_e64 v96, v99, v103, s[6:7]
	s_nop 1
	v_mov_b32_dpp v96, v96 quad_perm:[1,0,3,2] row_mask:0xf bank_mask:0xf bound_ctrl:1
	v_cndmask_b32_e64 v100, v99, v96, s[4:5]
	v_cndmask_b32_e64 v96, v96, v103, s[4:5]
	v_cvt_pk_bf16_f32 v100, v100, v96
	v_add_co_u32_e32 v96, vcc, 0x1000, v130
	s_nop 1
	v_addc_co_u32_e32 v97, vcc, 0, v131, vcc
	global_store_dword v[96:97], v100, off offset:2240
	v_cndmask_b32_e64 v96, v88, v92, s[6:7]
	s_nop 1
	v_mov_b32_dpp v96, v96 quad_perm:[1,0,3,2] row_mask:0xf bank_mask:0xf bound_ctrl:1
	v_cndmask_b32_e64 v98, v88, v96, s[4:5]
	v_cndmask_b32_e64 v96, v96, v92, s[4:5]
	v_cvt_pk_bf16_f32 v98, v98, v96
	v_lshl_add_u64 v[96:97], v[128:129], 0, v[176:177]
	v_add_co_u32_e32 v100, vcc, 0x8000, v96
	v_cndmask_b32_e64 v88, v80, v84, s[6:7]
	s_nop 0
	v_addc_co_u32_e32 v101, vcc, 0, v97, vcc
	v_mov_b32_dpp v92, v88 quad_perm:[1,0,3,2] row_mask:0xf bank_mask:0xf bound_ctrl:1
; DEVFI float dpp_xor1(float x) { return __int_as_float(__builtin_amdgcn_update_dpp(0, __float_as_int(x), 0xB1, 0xF, 0xF, true)); }
; DEVFI void store_nat_m(bfraw* base, long ld, f32x4 (&a)[8], int fr) {
;   const bool odd = fr & 1;
;   bfraw* p0 = base + (odd ? 15 + fr : fr);
; #pragma unroll
;   for (int j = 0; j < 4; ++j)
; #pragma unroll
;     for (int n0 = 0; n0 < 8; n0 += 2) { const float own0 = a[n0][j], own1 = a[n0 + 1][j];
;       const float recv = dpp_xor1(odd ? own0 : own1);
;       const unsigned pk = odd ? cvtpk(recv, own1) : cvtpk(own0, recv);
;       *reinterpret_cast<unsigned*>(p0 + (long)j * ld + n0 * 16) = pk; }
; }
	global_store_dword v[100:101], v98, off
	v_cndmask_b32_e64 v88, v80, v92, s[4:5]
	v_cndmask_b32_e64 v92, v92, v84, s[4:5]
	v_cvt_pk_bf16_f32 v88, v88, v92
	s_mov_b64 s[2:3], 0x8000
	v_cndmask_b32_e64 v80, v72, v76, s[6:7]
	v_lshl_add_u64 v[96:97], v[96:97], 0, s[2:3]
	global_store_dword v[96:97], v88, off offset:64
	v_mov_b32_dpp v84, v80 quad_perm:[1,0,3,2] row_mask:0xf bank_mask:0xf bound_ctrl:1
	v_cndmask_b32_e64 v80, v72, v84, s[4:5]
	v_cndmask_b32_e64 v84, v84, v76, s[4:5]
	v_cvt_pk_bf16_f32 v80, v80, v84
	v_cndmask_b32_e64 v72, v64, v68, s[6:7]
	global_store_dword v[96:97], v80, off offset:128
	s_nop 0
	v_mov_b32_dpp v76, v72 quad_perm:[1,0,3,2] row_mask:0xf bank_mask:0xf bound_ctrl:1
	v_cndmask_b32_e64 v72, v64, v76, s[4:5]
	v_cndmask_b32_e64 v76, v76, v68, s[4:5]
	v_cvt_pk_bf16_f32 v72, v72, v76
	v_cndmask_b32_e64 v64, v89, v93, s[6:7]
	global_store_dword v[96:97], v72, off offset:192
	s_nop 0
	v_mov_b32_dpp v68, v64 quad_perm:[1,0,3,2] row_mask:0xf bank_mask:0xf bound_ctrl:1
	v_cndmask_b32_e64 v64, v89, v68, s[4:5]
	v_cndmask_b32_e64 v68, v68, v93, s[4:5]
	v_cvt_pk_bf16_f32 v64, v64, v68
	global_store_dword v[96:97], v64, off offset:2048
	v_cndmask_b32_e64 v64, v81, v85, s[6:7]
	s_nop 1
	v_mov_b32_dpp v68, v64 quad_perm:[1,0,3,2] row_mask:0xf bank_mask:0xf bound_ctrl:1
	v_cndmask_b32_e64 v64, v81, v68, s[4:5]
	v_cndmask_b32_e64 v68, v68, v85, s[4:5]
	v_cvt_pk_bf16_f32 v64, v64, v68
	global_store_dword v[96:97], v64, off offset:2112
	v_cndmask_b32_e64 v64, v73, v77, s[6:7]
	s_nop 1
	v_mov_b32_dpp v68, v64 quad_perm:[1,0,3,2] row_mask:0xf bank_mask:0xf bound_ctrl:1
	v_cndmask_b32_e64 v64, v73, v68, s[4:5]
	v_cndmask_b32_e64 v68, v68, v77, s[4:5]
	v_cvt_pk_bf16_f32 v64, v64, v68
	global_store_dword v[96:97], v64, off offset:2176
	v_cndmask_b32_e64 v64, v65, v69, s[6:7]
	s_nop 1
	v_mov_b32_dpp v68, v64 quad_perm:[1,0,3,2] row_mask:0xf bank_mask:0xf bound_ctrl:1
	v_cndmask_b32_e64 v64, v65, v68, s[4:5]
	v_cndmask_b32_e64 v68, v68, v69, s[4:5]
	v_cvt_pk_bf16_f32 v64, v64, v68
	global_store_dword v[96:97], v64, off offset:2240
	v_cndmask_b32_e64 v64, v90, v94, s[6:7]
	s_nop 1
	v_mov_b32_dpp v65, v64 quad_perm:[1,0,3,2] row_mask:0xf bank_mask:0xf bound_ctrl:1
	v_cndmask_b32_e64 v64, v90, v65, s[4:5]
	v_cndmask_b32_e64 v65, v65, v94, s[4:5]
	v_cvt_pk_bf16_f32 v64, v64, v65
	v_add_co_u32_e32 v68, vcc, 0x1000, v96
	s_nop 1
	v_addc_co_u32_e32 v69, vcc, 0, v97, vcc
	global_store_dword v[68:69], v64, off
	v_cndmask_b32_e64 v64, v82, v86, s[6:7]
	s_nop 1
	v_mov_b32_dpp v65, v64 quad_perm:[1,0,3,2] row_mask:0xf bank_mask:0xf bound_ctrl:1
	v_cndmask_b32_e64 v64, v82, v65, s[4:5]
	v_cndmask_b32_e64 v65, v65, v86, s[4:5]
	v_cvt_pk_bf16_f32 v64, v64, v65
	v_add_co_u32_e32 v68, vcc, 0x1000, v96
	s_nop 1
	v_addc_co_u32_e32 v69, vcc, 0, v97, vcc
	global_store_dword v[68:69], v64, off offset:64
	v_cndmask_b32_e64 v64, v74, v78, s[6:7]
	s_nop 1
	v_mov_b32_dpp v65, v64 quad_perm:[1,0,3,2] row_mask:0xf bank_mask:0xf bound_ctrl:1
	v_cndmask_b32_e64 v64, v74, v65, s[4:5]
	v_cndmask_b32_e64 v65, v65, v78, s[4:5]
	v_cvt_pk_bf16_f32 v64, v64, v65
	v_add_co_u32_e32 v68, vcc, 0x1000, v96
	s_nop 1
	v_addc_co_u32_e32 v69, vcc, 0, v97, vcc
	global_store_dword v[68:69], v64, off offset:128
	v_cndmask_b32_e64 v64, v66, v70, s[6:7]
	s_nop 1
	v_mov_b32_dpp v65, v64 quad_perm:[1,0,3,2] row_mask:0xf bank_mask:0xf bound_ctrl:1
	v_cndmask_b32_e64 v64, v66, v65, s[4:5]
	v_cndmask_b32_e64 v65, v65, v70, s[4:5]
	v_cvt_pk_bf16_f32 v64, v64, v65
	v_add_co_u32_e32 v68, vcc, 0x1000, v96
	s_nop 1
	v_addc_co_u32_e32 v69, vcc, 0, v97, vcc
	global_store_dword v[68:69], v64, off offset:192
	v_cndmask_b32_e64 v64, v91, v95, s[6:7]
	s_nop 1
	v_mov_b32_dpp v65, v64 quad_perm:[1,0,3,2] row_mask:0xf bank_mask:0xf bound_ctrl:1
	v_cndmask_b32_e64 v64, v91, v65, s[4:5]
	v_cndmask_b32_e64 v65, v65, v95, s[4:5]
	v_cvt_pk_bf16_f32 v64, v64, v65
	v_add_co_u32_e32 v68, vcc, 0x1000, v96
	s_nop 1
	v_addc_co_u32_e32 v69, vcc, 0, v97, vcc
	global_store_dword v[68:69], v64, off offset:2048
	v_cndmask_b32_e64 v64, v83, v87, s[6:7]
	s_nop 1
	v_mov_b32_dpp v65, v64 quad_perm:[1,0,3,2] row_mask:0xf bank_mask:0xf bound_ctrl:1
	v_cndmask_b32_e64 v64, v83, v65, s[4:5]
	v_cndmask_b32_e64 v65, v65, v87, s[4:5]
	v_cvt_pk_bf16_f32 v64, v64, v65
	v_add_co_u32_e32 v68, vcc, 0x1000, v96
	s_nop 1
	v_addc_co_u32_e32 v69, vcc, 0, v97, vcc
	global_store_dword v[68:69], v64, off offset:2112
	v_cndmask_b32_e64 v64, v75, v79, s[6:7]
	s_nop 1
	v_mov_b32_dpp v65, v64 quad_perm:[1,0,3,2] row_mask:0xf bank_mask:0xf bound_ctrl:1
	v_cndmask_b32_e64 v64, v75, v65, s[4:5]
	v_cndmask_b32_e64 v65, v65, v79, s[4:5]
	v_cvt_pk_bf16_f32 v64, v64, v65
	v_add_co_u32_e32 v68, vcc, 0x1000, v96
	s_nop 1
	v_addc_co_u32_e32 v69, vcc, 0, v97, vcc
	global_store_dword v[68:69], v64, off offset:2176
	v_cndmask_b32_e64 v64, v67, v71, s[6:7]
	s_nop 1
	v_mov_b32_dpp v64, v64 quad_perm:[1,0,3,2] row_mask:0xf bank_mask:0xf bound_ctrl:1
	v_cndmask_b32_e64 v68, v67, v64, s[4:5]
	v_cndmask_b32_e64 v64, v64, v71, s[4:5]
	v_cvt_pk_bf16_f32 v68, v68, v64
	v_add_co_u32_e32 v64, vcc, 0x1000, v96
	s_nop 1
	v_addc_co_u32_e32 v65, vcc, 0, v97, vcc
	global_store_dword v[64:65], v68, off offset:2240
	v_cndmask_b32_e64 v64, v56, v60, s[6:7]
	s_nop 1
	v_mov_b32_dpp v64, v64 quad_perm:[1,0,3,2] row_mask:0xf bank_mask:0xf bound_ctrl:1
	v_cndmask_b32_e64 v66, v56, v64, s[4:5]
	v_cndmask_b32_e64 v64, v64, v60, s[4:5]
	v_cvt_pk_bf16_f32 v66, v66, v64
	v_lshl_add_u64 v[64:65], v[128:129], 0, v[176:177]
	v_add_co_u32_e32 v68, vcc, 0x10000, v64
	v_cndmask_b32_e64 v56, v48, v52, s[6:7]
	s_nop 0
	v_addc_co_u32_e32 v69, vcc, 0, v65, vcc
; DEVFI float dpp_xor1(float x) { return __int_as_float(__builtin_amdgcn_update_dpp(0, __float_as_int(x), 0xB1, 0xF, 0xF, true)); }
; DEVFI void store_nat_m(bfraw* base, long ld, f32x4 (&a)[8], int fr) {
;   const bool odd = fr & 1;
;   bfraw* p0 = base + (odd ? 15 + fr : fr);
; #pragma unroll
;   for (int j = 0; j < 4; ++j)
; #pragma unroll
;     for (int n0 = 0; n0 < 8; n0 += 2) { const float own0 = a[n0][j], own1 = a[n0 + 1][j];
;       const float recv = dpp_xor1(odd ? own0 : own1);
;       const unsigned pk = odd ? cvtpk(recv, own1) : cvtpk(own0, recv);
;       *reinterpret_cast<unsigned*>(p0 + (long)j * ld + n0 * 16) = pk; }
; }
	v_mov_b32_dpp v60, v56 quad_perm:[1,0,3,2] row_mask:0xf bank_mask:0xf bound_ctrl:1
	global_store_dword v[68:69], v66, off
	v_cndmask_b32_e64 v56, v48, v60, s[4:5]
	v_cndmask_b32_e64 v60, v60, v52, s[4:5]
	v_cvt_pk_bf16_f32 v56, v56, v60
	v_cndmask_b32_e64 v48, v40, v44, s[6:7]
	v_lshl_add_u64 v[64:65], v[64:65], 0, s[48:49]
	global_store_dword v[64:65], v56, off offset:64
	v_mov_b32_dpp v52, v48 quad_perm:[1,0,3,2] row_mask:0xf bank_mask:0xf bound_ctrl:1
	v_cndmask_b32_e64 v48, v40, v52, s[4:5]
	v_cndmask_b32_e64 v52, v52, v44, s[4:5]
	v_cvt_pk_bf16_f32 v48, v48, v52
	v_cndmask_b32_e64 v40, v32, v36, s[6:7]
	global_store_dword v[64:65], v48, off offset:128
	s_nop 0
	v_mov_b32_dpp v44, v40 quad_perm:[1,0,3,2] row_mask:0xf bank_mask:0xf bound_ctrl:1
	v_cndmask_b32_e64 v40, v32, v44, s[4:5]
	v_cndmask_b32_e64 v44, v44, v36, s[4:5]
	v_cvt_pk_bf16_f32 v40, v40, v44
	v_cndmask_b32_e64 v32, v57, v61, s[6:7]
	global_store_dword v[64:65], v40, off offset:192
	s_nop 0
	v_mov_b32_dpp v36, v32 quad_perm:[1,0,3,2] row_mask:0xf bank_mask:0xf bound_ctrl:1
	v_cndmask_b32_e64 v32, v57, v36, s[4:5]
	v_cndmask_b32_e64 v36, v36, v61, s[4:5]
	v_cvt_pk_bf16_f32 v32, v32, v36
	global_store_dword v[64:65], v32, off offset:2048
	v_cndmask_b32_e64 v32, v49, v53, s[6:7]
	s_nop 1
	v_mov_b32_dpp v36, v32 quad_perm:[1,0,3,2] row_mask:0xf bank_mask:0xf bound_ctrl:1
	v_cndmask_b32_e64 v32, v49, v36, s[4:5]
	v_cndmask_b32_e64 v36, v36, v53, s[4:5]
	v_cvt_pk_bf16_f32 v32, v32, v36
	global_store_dword v[64:65], v32, off offset:2112
	v_cndmask_b32_e64 v32, v41, v45, s[6:7]
	s_nop 1
	v_mov_b32_dpp v36, v32 quad_perm:[1,0,3,2] row_mask:0xf bank_mask:0xf bound_ctrl:1
	v_cndmask_b32_e64 v32, v41, v36, s[4:5]
	v_cndmask_b32_e64 v36, v36, v45, s[4:5]
	v_cvt_pk_bf16_f32 v32, v32, v36
	global_store_dword v[64:65], v32, off offset:2176
	v_cndmask_b32_e64 v32, v33, v37, s[6:7]
	s_nop 1
	v_mov_b32_dpp v36, v32 quad_perm:[1,0,3,2] row_mask:0xf bank_mask:0xf bound_ctrl:1
	v_cndmask_b32_e64 v32, v33, v36, s[4:5]
	v_cndmask_b32_e64 v36, v36, v37, s[4:5]
	v_cvt_pk_bf16_f32 v32, v32, v36
	global_store_dword v[64:65], v32, off offset:2240
	v_cndmask_b32_e64 v32, v58, v62, s[6:7]
	s_nop 1
	v_mov_b32_dpp v33, v32 quad_perm:[1,0,3,2] row_mask:0xf bank_mask:0xf bound_ctrl:1
	v_cndmask_b32_e64 v32, v58, v33, s[4:5]
	v_cndmask_b32_e64 v33, v33, v62, s[4:5]
	v_cvt_pk_bf16_f32 v32, v32, v33
	v_add_co_u32_e32 v36, vcc, 0x1000, v64
	s_nop 1
	v_addc_co_u32_e32 v37, vcc, 0, v65, vcc
	global_store_dword v[36:37], v32, off
	v_cndmask_b32_e64 v32, v50, v54, s[6:7]
	s_nop 1
	v_mov_b32_dpp v33, v32 quad_perm:[1,0,3,2] row_mask:0xf bank_mask:0xf bound_ctrl:1
	v_cndmask_b32_e64 v32, v50, v33, s[4:5]
	v_cndmask_b32_e64 v33, v33, v54, s[4:5]
	v_cvt_pk_bf16_f32 v32, v32, v33
	v_add_co_u32_e32 v36, vcc, 0x1000, v64
	s_nop 1
	v_addc_co_u32_e32 v37, vcc, 0, v65, vcc
	global_store_dword v[36:37], v32, off offset:64
	v_cndmask_b32_e64 v32, v42, v46, s[6:7]
	s_nop 1
	v_mov_b32_dpp v33, v32 quad_perm:[1,0,3,2] row_mask:0xf bank_mask:0xf bound_ctrl:1
	v_cndmask_b32_e64 v32, v42, v33, s[4:5]
	v_cndmask_b32_e64 v33, v33, v46, s[4:5]
	v_cvt_pk_bf16_f32 v32, v32, v33
	v_add_co_u32_e32 v36, vcc, 0x1000, v64
	s_nop 1
	v_addc_co_u32_e32 v37, vcc, 0, v65, vcc
	global_store_dword v[36:37], v32, off offset:128
	v_cndmask_b32_e64 v32, v34, v38, s[6:7]
	s_nop 1
	v_mov_b32_dpp v33, v32 quad_perm:[1,0,3,2] row_mask:0xf bank_mask:0xf bound_ctrl:1
	v_cndmask_b32_e64 v32, v34, v33, s[4:5]
	v_cndmask_b32_e64 v33, v33, v38, s[4:5]
	v_cvt_pk_bf16_f32 v32, v32, v33
	v_add_co_u32_e32 v36, vcc, 0x1000, v64
	s_nop 1
	v_addc_co_u32_e32 v37, vcc, 0, v65, vcc
	global_store_dword v[36:37], v32, off offset:192
	v_cndmask_b32_e64 v32, v59, v63, s[6:7]
	s_nop 1
	v_mov_b32_dpp v33, v32 quad_perm:[1,0,3,2] row_mask:0xf bank_mask:0xf bound_ctrl:1
	v_cndmask_b32_e64 v32, v59, v33, s[4:5]
	v_cndmask_b32_e64 v33, v33, v63, s[4:5]
	v_cvt_pk_bf16_f32 v32, v32, v33
	v_add_co_u32_e32 v36, vcc, 0x1000, v64
	s_nop 1
	v_addc_co_u32_e32 v37, vcc, 0, v65, vcc
	global_store_dword v[36:37], v32, off offset:2048
	v_cndmask_b32_e64 v32, v51, v55, s[6:7]
	s_nop 1
	v_mov_b32_dpp v33, v32 quad_perm:[1,0,3,2] row_mask:0xf bank_mask:0xf bound_ctrl:1
	v_cndmask_b32_e64 v32, v51, v33, s[4:5]
	v_cndmask_b32_e64 v33, v33, v55, s[4:5]
	v_cvt_pk_bf16_f32 v32, v32, v33
	v_add_co_u32_e32 v36, vcc, 0x1000, v64
	s_nop 1
	v_addc_co_u32_e32 v37, vcc, 0, v65, vcc
	global_store_dword v[36:37], v32, off offset:2112
	v_cndmask_b32_e64 v32, v43, v47, s[6:7]
	s_nop 1
	v_mov_b32_dpp v33, v32 quad_perm:[1,0,3,2] row_mask:0xf bank_mask:0xf bound_ctrl:1
	v_cndmask_b32_e64 v32, v43, v33, s[4:5]
	v_cndmask_b32_e64 v33, v33, v47, s[4:5]
	v_cvt_pk_bf16_f32 v32, v32, v33
	v_add_co_u32_e32 v36, vcc, 0x1000, v64
	s_nop 1
	v_addc_co_u32_e32 v37, vcc, 0, v65, vcc
	global_store_dword v[36:37], v32, off offset:2176
	v_cndmask_b32_e64 v32, v35, v39, s[6:7]
	s_nop 1
	v_mov_b32_dpp v32, v32 quad_perm:[1,0,3,2] row_mask:0xf bank_mask:0xf bound_ctrl:1
	v_cndmask_b32_e64 v36, v35, v32, s[4:5]
	v_cndmask_b32_e64 v32, v32, v39, s[4:5]
	v_cvt_pk_bf16_f32 v36, v36, v32
	v_add_co_u32_e32 v32, vcc, 0x1000, v64
	s_nop 1
	v_addc_co_u32_e32 v33, vcc, 0, v65, vcc
	global_store_dword v[32:33], v36, off offset:2240
	v_cndmask_b32_e64 v32, v24, v28, s[6:7]
	s_nop 1
; #define SBAR() __builtin_amdgcn_sched_barrier(0)
; DEVFI float dpp_xor1(float x) { return __int_as_float(__builtin_amdgcn_update_dpp(0, __float_as_int(x), 0xB1, 0xF, 0xF, true)); }
; DEVFI void store_nat_m(bfraw* base, long ld, f32x4 (&a)[8], int fr) {
;   const bool odd = fr & 1;
;   bfraw* p0 = base + (odd ? 15 + fr : fr);
; #pragma unroll
;   for (int j = 0; j < 4; ++j)
; #pragma unroll
;     for (int n0 = 0; n0 < 8; n0 += 2) { const float own0 = a[n0][j], own1 = a[n0 + 1][j];
;       const float recv = dpp_xor1(odd ? own0 : own1);
;       const unsigned pk = odd ? cvtpk(recv, own1) : cvtpk(own0, recv);
;       *reinterpret_cast<unsigned*>(p0 + (long)j * ld + n0 * 16) = pk; }
; }
; DEVFI void store_nat(bfraw* dst, long ld, f32x4 (&acc)[4][8], int fr, int fq) {
;   store_nat_m(dst + (long)(0 * 16 + fq * 4) * ld, ld, acc[0], fr); SBAR();
;   store_nat_m(dst + (long)(1 * 16 + fq * 4) * ld, ld, acc[1], fr); SBAR();
;   store_nat_m(dst + (long)(2 * 16 + fq * 4) * ld, ld, acc[2], fr); SBAR();
;   store_nat_m(dst + (long)(3 * 16 + fq * 4) * ld, ld, acc[3], fr); SBAR();
; }
	v_mov_b32_dpp v32, v32 quad_perm:[1,0,3,2] row_mask:0xf bank_mask:0xf bound_ctrl:1
	v_cndmask_b32_e64 v34, v24, v32, s[4:5]
	v_cndmask_b32_e64 v32, v32, v28, s[4:5]
	v_cvt_pk_bf16_f32 v34, v34, v32
	v_lshl_add_u64 v[32:33], v[128:129], 0, v[176:177]
	v_add_co_u32_e32 v36, vcc, 0x18000, v32
	v_cndmask_b32_e64 v24, v16, v20, s[6:7]
	s_nop 0
	v_addc_co_u32_e32 v37, vcc, 0, v33, vcc
	v_mov_b32_dpp v28, v24 quad_perm:[1,0,3,2] row_mask:0xf bank_mask:0xf bound_ctrl:1
	global_store_dword v[36:37], v34, off
	v_cndmask_b32_e64 v24, v16, v28, s[4:5]
	v_cndmask_b32_e64 v28, v28, v20, s[4:5]
	v_cvt_pk_bf16_f32 v24, v24, v28
	s_mov_b64 s[2:3], 0x18000
	v_cndmask_b32_e64 v16, v8, v12, s[6:7]
	v_lshl_add_u64 v[32:33], v[32:33], 0, s[2:3]
	global_store_dword v[32:33], v24, off offset:64
	v_mov_b32_dpp v20, v16 quad_perm:[1,0,3,2] row_mask:0xf bank_mask:0xf bound_ctrl:1
	v_cndmask_b32_e64 v16, v8, v20, s[4:5]
	v_cndmask_b32_e64 v20, v20, v12, s[4:5]
	v_cvt_pk_bf16_f32 v16, v16, v20
	v_cndmask_b32_e64 v8, v0, v4, s[6:7]
	global_store_dword v[32:33], v16, off offset:128
	s_nop 0
	v_mov_b32_dpp v12, v8 quad_perm:[1,0,3,2] row_mask:0xf bank_mask:0xf bound_ctrl:1
	v_cndmask_b32_e64 v8, v0, v12, s[4:5]
	v_cndmask_b32_e64 v12, v12, v4, s[4:5]
	v_cvt_pk_bf16_f32 v8, v8, v12
	v_cndmask_b32_e64 v0, v25, v29, s[6:7]
	global_store_dword v[32:33], v8, off offset:192
	s_nop 0
	v_mov_b32_dpp v4, v0 quad_perm:[1,0,3,2] row_mask:0xf bank_mask:0xf bound_ctrl:1
	v_cndmask_b32_e64 v0, v25, v4, s[4:5]
	v_cndmask_b32_e64 v4, v4, v29, s[4:5]
	v_cvt_pk_bf16_f32 v0, v0, v4
	global_store_dword v[32:33], v0, off offset:2048
	v_cndmask_b32_e64 v0, v17, v21, s[6:7]
	s_nop 1
	v_mov_b32_dpp v4, v0 quad_perm:[1,0,3,2] row_mask:0xf bank_mask:0xf bound_ctrl:1
	v_cndmask_b32_e64 v0, v17, v4, s[4:5]
	v_cndmask_b32_e64 v4, v4, v21, s[4:5]
	v_cvt_pk_bf16_f32 v0, v0, v4
	global_store_dword v[32:33], v0, off offset:2112
	v_cndmask_b32_e64 v0, v9, v13, s[6:7]
	s_nop 1
	v_mov_b32_dpp v4, v0 quad_perm:[1,0,3,2] row_mask:0xf bank_mask:0xf bound_ctrl:1
	v_cndmask_b32_e64 v0, v9, v4, s[4:5]
	v_cndmask_b32_e64 v4, v4, v13, s[4:5]
	v_cvt_pk_bf16_f32 v0, v0, v4
	global_store_dword v[32:33], v0, off offset:2176
	v_cndmask_b32_e64 v0, v1, v5, s[6:7]
	s_nop 1
	v_mov_b32_dpp v4, v0 quad_perm:[1,0,3,2] row_mask:0xf bank_mask:0xf bound_ctrl:1
	v_cndmask_b32_e64 v0, v1, v4, s[4:5]
	v_cndmask_b32_e64 v4, v4, v5, s[4:5]
	v_cvt_pk_bf16_f32 v0, v0, v4
	global_store_dword v[32:33], v0, off offset:2240
	v_cndmask_b32_e64 v0, v26, v30, s[6:7]
	s_nop 1
	v_mov_b32_dpp v1, v0 quad_perm:[1,0,3,2] row_mask:0xf bank_mask:0xf bound_ctrl:1
	v_cndmask_b32_e64 v0, v26, v1, s[4:5]
	v_cndmask_b32_e64 v1, v1, v30, s[4:5]
	v_cvt_pk_bf16_f32 v0, v0, v1
	v_add_co_u32_e32 v4, vcc, 0x1000, v32
	s_nop 1
	v_addc_co_u32_e32 v5, vcc, 0, v33, vcc
	global_store_dword v[4:5], v0, off
	v_cndmask_b32_e64 v0, v18, v22, s[6:7]
	s_nop 1
	v_mov_b32_dpp v1, v0 quad_perm:[1,0,3,2] row_mask:0xf bank_mask:0xf bound_ctrl:1
	v_cndmask_b32_e64 v0, v18, v1, s[4:5]
	v_cndmask_b32_e64 v1, v1, v22, s[4:5]
	v_cvt_pk_bf16_f32 v0, v0, v1
	v_add_co_u32_e32 v4, vcc, 0x1000, v32
	s_nop 1
	v_addc_co_u32_e32 v5, vcc, 0, v33, vcc
	global_store_dword v[4:5], v0, off offset:64
	v_cndmask_b32_e64 v0, v10, v14, s[6:7]
	s_nop 1
	v_mov_b32_dpp v1, v0 quad_perm:[1,0,3,2] row_mask:0xf bank_mask:0xf bound_ctrl:1
	v_cndmask_b32_e64 v0, v10, v1, s[4:5]
	v_cndmask_b32_e64 v1, v1, v14, s[4:5]
	v_cvt_pk_bf16_f32 v0, v0, v1
	v_add_co_u32_e32 v4, vcc, 0x1000, v32
	s_nop 1
	v_addc_co_u32_e32 v5, vcc, 0, v33, vcc
	global_store_dword v[4:5], v0, off offset:128
	v_cndmask_b32_e64 v0, v2, v6, s[6:7]
	s_nop 1
	v_mov_b32_dpp v1, v0 quad_perm:[1,0,3,2] row_mask:0xf bank_mask:0xf bound_ctrl:1
	v_cndmask_b32_e64 v0, v2, v1, s[4:5]
	v_cndmask_b32_e64 v1, v1, v6, s[4:5]
	v_cvt_pk_bf16_f32 v0, v0, v1
	v_add_co_u32_e32 v4, vcc, 0x1000, v32
	s_nop 1
	v_addc_co_u32_e32 v5, vcc, 0, v33, vcc
	global_store_dword v[4:5], v0, off offset:192
	v_cndmask_b32_e64 v0, v27, v31, s[6:7]
	s_nop 1
	v_mov_b32_dpp v1, v0 quad_perm:[1,0,3,2] row_mask:0xf bank_mask:0xf bound_ctrl:1
	v_cndmask_b32_e64 v0, v27, v1, s[4:5]
	v_cndmask_b32_e64 v1, v1, v31, s[4:5]
	v_cvt_pk_bf16_f32 v0, v0, v1
	v_add_co_u32_e32 v4, vcc, 0x1000, v32
	s_nop 1
	v_addc_co_u32_e32 v5, vcc, 0, v33, vcc
	global_store_dword v[4:5], v0, off offset:2048
	v_cndmask_b32_e64 v0, v19, v23, s[6:7]
	s_nop 1
	v_mov_b32_dpp v1, v0 quad_perm:[1,0,3,2] row_mask:0xf bank_mask:0xf bound_ctrl:1
	v_cndmask_b32_e64 v0, v19, v1, s[4:5]
	v_cndmask_b32_e64 v1, v1, v23, s[4:5]
	v_cvt_pk_bf16_f32 v0, v0, v1
	v_add_co_u32_e32 v4, vcc, 0x1000, v32
	s_nop 1
	v_addc_co_u32_e32 v5, vcc, 0, v33, vcc
	global_store_dword v[4:5], v0, off offset:2112
	v_cndmask_b32_e64 v0, v11, v15, s[6:7]
	s_nop 1
	v_mov_b32_dpp v1, v0 quad_perm:[1,0,3,2] row_mask:0xf bank_mask:0xf bound_ctrl:1
	v_cndmask_b32_e64 v0, v11, v1, s[4:5]
	v_cndmask_b32_e64 v1, v1, v15, s[4:5]
	v_cvt_pk_bf16_f32 v0, v0, v1
	v_add_co_u32_e32 v4, vcc, 0x1000, v32
	s_nop 1
	v_addc_co_u32_e32 v5, vcc, 0, v33, vcc
	global_store_dword v[4:5], v0, off offset:2176
	v_cndmask_b32_e64 v0, v3, v7, s[6:7]
	s_nop 1
	v_mov_b32_dpp v0, v0 quad_perm:[1,0,3,2] row_mask:0xf bank_mask:0xf bound_ctrl:1
	s_and_saveexec_b64 s[2:3], s[4:5]
	s_xor_b64 s[2:3], exec, s[2:3]
	s_cbranch_execz .LBB0_4766
	v_cvt_pk_bf16_f32 v4, v0, v7
